# in-proj GEMM epilogue: the 74 flat_store instructions become global_store (same addresses; no LDS-queue slot / lgkmcnt traffic)
# baseline (speedup 1.0000x reference)
; #define LAS __attribute__((address_space(3)))
;     __device__ __forceinline__ void operator()(f32x4 (&acc)[2][2][4][2], const pg8::Unit& u, int wr, int wc, int fr, int fq) const {
;     ...
;         const int tile = u.pm * 37 + u.pn;
;         if (prompt) {
;             if (fr >= 13) {
; #pragma unroll
;                 for (int ai = 0; ai < 2; ++ai)
; #pragma unroll
;                     for (int bj = 0; bj < 2; ++bj)
; #pragma unroll
;                         for (int n = 0; n < 2; ++n) *(LAS f32x4*)(H + ((2 * ai + wr) * 3 + (fr - 13)) * 256 + bj * 128 + cl0 + 4 * n) = acc[ai][bj][3][n];
;                 if (wr == 1 && (u.pm & 7) != 7) { unsigned long long* hp = HALO + ((size_t)tile * 3 + (fr - 13)) * 128 + (cl0 >> 1);
; #pragma unroll
;                     for (int bj = 0; bj < 2; ++bj)
; #pragma unroll
;                         for (int n = 0; n < 2; ++n) { const f32x4 g = acc[1][bj][3][n];
;                             __hip_atomic_store(hp + bj * 64 + 2 * n, ((unsigned long long)__float_as_uint(g[1]) << 32) | __float_as_uint(g[0]), __ATOMIC_RELAXED, __HIP_MEMORY_SCOPE_AGENT);
;                             __hip_atomic_store(hp + bj * 64 + 2 * n + 1, ((unsigned long long)__float_as_uint(g[3]) << 32) | __float_as_uint(g[2]), __ATOMIC_RELAXED, __HIP_MEMORY_SCOPE_AGENT); } }
.LBB0_237:
	s_add_u32 s13, s74, 0x28600
	s_addc_u32 s14, s75, 0
	s_add_u32 s8, s74, 0x1915f800
	s_mul_i32 s0, s2, 37
	v_cndmask_b32_e64 v130, 0, 1, s[76:77]
	s_addc_u32 s9, s75, 0
	s_add_i32 s2, s0, s72
	v_cmp_ne_u32_e64 s[20:21], 1, v130
	s_andn2_b64 vcc, exec, s[76:77]
	v_cmp_lt_i32_e64 s[0:1], 12, v207
	s_cbranch_vccnz .LBB0_249
	s_mov_b64 s[10:11], -1
	s_and_saveexec_b64 s[6:7], s[0:1]
	s_cbranch_execz .LBB0_244
	v_add_u32_e32 v182, -13, v207
	v_readlane_b32 s0, v255, 5
	v_lshlrev_b32_e32 v131, 2, v206
	v_readlane_b32 s1, v255, 19
	v_add_lshl_u32 v130, v182, s0, 10
	v_readlane_b32 s0, v255, 7
	v_add3_u32 v130, s1, v130, v131
	ds_write_b128 v130, v[78:81]
	ds_write_b128 v130, v[74:77] offset:16
	ds_write_b128 v130, v[70:73] offset:512
	ds_write_b128 v130, v[66:69] offset:528
	v_add_lshl_u32 v130, v182, s0, 10
	v_add3_u32 v130, s1, v130, v131
	s_mov_b64 s[0:1], 0
	s_and_b64 vcc, exec, s[78:79]
	ds_write_b128 v130, v[14:17]
	ds_write_b128 v130, v[10:13] offset:16
	ds_write_b128 v130, v[6:9] offset:512
	ds_write_b128 v130, v[2:5] offset:528
	s_cbranch_vccz .LBB0_243
	s_cmp_eq_u32 s12, 7
	s_cbranch_scc1 .LBB0_242
	v_mad_i64_i32 v[130:131], s[0:1], s2, 3, v[182:183]
	v_lshlrev_b64 v[130:131], 10, v[130:131]
	v_ashrrev_i32_e32 v132, 1, v206
	v_lshl_add_u64 v[130:131], s[8:9], 0, v[130:131]
	v_ashrrev_i32_e32 v133, 31, v132
	v_lshl_add_u64 v[130:131], v[132:133], 3, v[130:131]
	global_store_dwordx2 v[130:131], v[14:15], off sc1
	global_store_dwordx2 v[130:131], v[16:17], off offset:8 sc1
	global_store_dwordx2 v[130:131], v[10:11], off offset:16 sc1
	global_store_dwordx2 v[130:131], v[12:13], off offset:24 sc1
	global_store_dwordx2 v[130:131], v[6:7], off offset:512 sc1
	global_store_dwordx2 v[130:131], v[8:9], off offset:520 sc1
	global_store_dwordx2 v[130:131], v[2:3], off offset:528 sc1
	global_store_dwordx2 v[130:131], v[4:5], off offset:536 sc1

;     __device__ __forceinline__ void operator()(f32x4 (&acc)[2][2][4][2], const pg8::Unit& u, int wr, int wc, int fr, int fq) const {
;     ...
;                     else if ((u.pm & 7) != 0) { unsigned* fl = HFLAG + (tile - 37); unsigned sp = 0;
;                         while ((unsigned)__builtin_amdgcn_readfirstlane(__hip_atomic_load(fl, __ATOMIC_RELAXED, __HIP_MEMORY_SCOPE_AGENT)) < 4u) { __builtin_amdgcn_s_sleep(2);
;                             if ((++sp & 1023u) == 0u) { if (__hip_atomic_load(tmo, __ATOMIC_RELAXED, __HIP_MEMORY_SCOPE_AGENT) != 0u) break; if (sp > (1u << 22)) { __hip_atomic_store(tmo, 1u, __ATOMIC_RELAXED, __HIP_MEMORY_SCOPE_AGENT); break; } } }
.LBB0_281:
	s_or_b64 exec, exec, s[2:3]
	s_xor_b64 s[2:3], s[8:9], -1
	s_and_saveexec_b64 s[8:9], s[2:3]
	s_xor_b64 s[2:3], exec, s[8:9]
	s_cbranch_execz .LBB0_283
	v_mov_b64_e32 v[130:131], s[74:75]
	v_mov_b32_e32 v132, 1
	global_store_dword v[130:131], v132, off offset:64 sc1

; __device__ __forceinline__ unsigned cvt_pk_bf16(float lo, float hi) { unsigned r; asm("v_cvt_pk_bf16_f32 %0, %1, %2" : "=v"(r) : "v"(lo), "v"(hi)); return r; }
; __device__ __forceinline__ float siluf_(float x) { return x * sigmoidf_(x); }
; __device__ __forceinline__ float dpp_ror1(float v) { return __builtin_bit_cast(float, __builtin_amdgcn_update_dpp(0, __builtin_bit_cast(int, v), 0x121, 0xf, 0xf, false)); }
;     __device__ __forceinline__ void operator()(f32x4 (&acc)[2][2][4][2], const pg8::Unit& u, int wr, int wc, int fr, int fq) const {
;     ...
;                 for (int n = 0; n < 2; ++n) { const int ch = ch0 + bj * 128 + 4 * n;
;                     const f32x4 w0 = *(const f32x4*)(cw + ch), w1 = *(const f32x4*)(cw + CW + ch), w2 = *(const f32x4*)(cw + 2 * CW + ch), w3 = *(const f32x4*)(cw + 3 * CW + ch), bb = *(const f32x4*)(cb + ch);
; #pragma unroll
;                     for (int m = 0; m < 4; ++m) { const int row = row0 + ai * 128 + m * 16; const f32x4 g = acc[ai][bj][m][n]; f32x4 p1, p2, p3;
;                         if (prompt) { const f32x4 gp = (m == 0) ? hal[n] : acc[ai][bj][m > 0 ? m - 1 : 0][n];
; #pragma unroll
;                             for (int j = 0; j < 4; ++j) { p1[j] = dpp_ror1(fr == 15 ? gp[j] : g[j]); p2[j] = dpp_ror2(fr >= 14 ? gp[j] : g[j]); p3[j] = dpp_ror3(fr >= 13 ? gp[j] : g[j]); } }
;                         else { const int t = fr & 3; const float* sp = stp + (size_t)((row - MP) >> 2) * 3 * CW + ch;
;                             const f32x4 b0 = *(const f32x4*)sp, b1 = *(const f32x4*)(sp + CW), b2 = *(const f32x4*)(sp + 2 * CW);
; #pragma unroll
;                             for (int j = 0; j < 4; ++j) { const float r1 = dpp_ror1(g[j]), r2 = dpp_ror2(g[j]), r3 = dpp_ror3(g[j]);
;                                 p1[j] = t >= 1 ? r1 : b2[j]; p2[j] = t >= 2 ? r2 : (t == 1 ? b2[j] : b1[j]); p3[j] = t >= 3 ? r3 : (t == 2 ? b2[j] : (t == 1 ? b1[j] : b0[j])); } }
;                         float o[4];
; #pragma unroll
;                         for (int j = 0; j < 4; ++j) { const float y = bb[j] + w0[j] * p3[j] + w1[j] * p2[j] + w2[j] * p1[j] + w3[j] * g[j]; o[j] = is_rg ? y : siluf_(y); }
;                         u32x2 w; w.x = cvt_pk_bf16(o[0], o[1]); w.y = cvt_pk_bf16(o[2], o[3]);
;                         *(u32x2*)(dst + (size_t)row * ld + bj * 128 + 4 * n) = w; }
.LBB0_331:
	s_movk_i32 s2, 0x800
	v_cmp_gt_i32_e32 vcc, s2, v220
	s_waitcnt vmcnt(0) lgkmcnt(0)
	v_add_u32_e32 v148, 0xfffff800, v220
	v_mov_b32_e32 v166, v154
	v_cndmask_b32_e32 v146, v249, v250, vcc
	v_cndmask_b32_e64 v182, v146, v251, s[4:5]
	v_lshl_add_u64 v[146:147], s[74:75], 0, v[182:183]
	v_cndmask_b32_e32 v182, v148, v220, vcc
	v_mov_b32_e32 v167, v134
	v_mov_b32_e32 v148, v162
	v_mov_b32_e32 v149, v158
	v_pk_mul_f32 v[148:149], v[166:167], v[148:149]
	v_mov_b32_e32 v168, v150
	v_add_f32_e32 v134, v142, v149
	v_mov_b32_e32 v169, v138
	v_mov_b32_e32 v229, v170
	v_add_f32_e32 v134, v148, v134
	v_pk_mul_f32 v[148:149], v[168:169], v[228:229]
	v_mov_b32_e32 v158, v163
	v_add_f32_e32 v134, v149, v134
	v_add_f32_e32 v150, v148, v134
	v_mul_f32_e32 v134, 0xbfb8aa3b, v150
	v_exp_f32_e32 v134, v134
	v_cndmask_b32_e64 v148, v182, v204, s[4:5]
	v_ashrrev_i32_e32 v149, 31, v148
	v_lshl_add_u64 v[220:221], v[148:149], 1, v[146:147]
	v_add_f32_e32 v134, 1.0, v134
	v_rcp_f32_e32 v148, v134
	v_mov_b32_e32 v134, v155
	v_pk_mul_f32 v[146:147], v[134:135], v[158:159]
	v_mov_b32_e32 v227, v171
	v_add_f32_e32 v138, v143, v147
	v_add_f32_e32 v149, v146, v138
	v_mov_b32_e32 v138, v151
	v_pk_mul_f32 v[146:147], v[138:139], v[226:227]
	v_mov_b32_e32 v162, v156
	v_add_f32_e32 v147, v147, v149
	v_add_f32_e32 v149, v146, v147
	v_mul_f32_e32 v146, 0xbfb8aa3b, v149
	v_exp_f32_e32 v146, v146
	v_mul_f32_e32 v147, v150, v148
	v_cndmask_b32_e64 v148, v147, v150, s[4:5]
	v_mov_b32_e32 v163, v136
	v_add_f32_e32 v146, 1.0, v146
	v_rcp_f32_e32 v150, v146
	v_mov_b32_e32 v146, v164
	v_mov_b32_e32 v147, v160
	v_pk_mul_f32 v[146:147], v[162:163], v[146:147]
	v_mov_b32_e32 v170, v152
	v_add_f32_e32 v136, v144, v147
	v_mov_b32_e32 v171, v140
	v_mov_b32_e32 v225, v172
	v_add_f32_e32 v136, v146, v136
	v_pk_mul_f32 v[146:147], v[170:171], v[224:225]
	v_mov_b32_e32 v160, v165
	v_add_f32_e32 v136, v147, v136
	v_add_f32_e32 v151, v146, v136
	v_mul_f32_e32 v136, 0xbfb8aa3b, v151
	v_exp_f32_e32 v152, v136
	v_mov_b32_e32 v136, v157
	v_pk_mul_f32 v[146:147], v[136:137], v[160:161]
	v_mov_b32_e32 v223, v173
	v_add_f32_e32 v140, v145, v147
	v_add_f32_e32 v154, v146, v140
	v_mov_b32_e32 v140, v153
	v_pk_mul_f32 v[146:147], v[140:141], v[222:223]
	v_add_f32_e32 v152, 1.0, v152
	v_add_f32_e32 v147, v147, v154
	v_add_f32_e32 v146, v146, v147
	v_mul_f32_e32 v147, 0xbfb8aa3b, v146
	v_exp_f32_e32 v147, v147
	v_rcp_f32_e32 v152, v152
	s_or_b64 s[2:3], s[4:5], vcc
	v_mul_f32_e32 v150, v149, v150
	v_add_f32_e32 v147, 1.0, v147
	v_rcp_f32_e32 v147, v147
	v_cndmask_b32_e64 v182, 10, 11, s[2:3]
	v_cndmask_b32_e64 v149, v150, v149, s[4:5]
	v_mul_f32_e32 v150, v151, v152
	v_mul_f32_e32 v147, v146, v147
	v_cndmask_b32_e64 v147, v147, v146, s[4:5]
	v_cvt_pk_bf16_f32 v146, v148, v149
	v_lshlrev_b64 v[148:149], v182, v[202:203]
	v_lshl_add_u64 v[222:223], v[148:149], 1, v[220:221]
	v_cndmask_b32_e64 v150, v150, v151, s[4:5]
	v_cvt_pk_bf16_f32 v147, v150, v147
	global_store_dwordx2 v[222:223], v[146:147], off
	v_cndmask_b32_e64 v146, 0, 1, s[80:81]
	s_mov_b64 s[2:3], -1
	v_cmp_ne_u32_e64 s[18:19], 1, v146
	s_andn2_b64 vcc, exec, s[80:81]
	v_mov_b32_e32 v172, v110
	v_mov_b32_e32 v164, v111
	v_mov_b32_e32 v156, v112
	v_mov_b32_e32 v154, v113
	s_cbranch_vccnz .LBB0_373
	v_add_u32_e32 v147, 0xffffe010, v202
	v_ashrrev_i32_e32 v147, 2, v147
	v_lshl_add_u32 v147, v147, 1, v147
	v_mad_i64_i32 v[148:149], s[2:3], v147, s47, 0
	v_lshl_add_u64 v[148:149], v[148:149], 2, v[208:209]
	v_lshl_add_u64 v[150:151], v[148:149], 0, s[24:25]
	s_lshl_b32 s2, s27, 2
	s_mov_b32 s3, s25
	global_load_dwordx4 v[158:161], v[148:149], off
	s_nop 0
	global_load_dwordx4 v[150:153], v[150:151], off
	v_lshl_add_u64 v[148:149], v[148:149], 0, s[2:3]
	global_load_dwordx4 v[154:157], v[148:149], off
	v_mov_b32_e32 v164, 0
	v_mov_b32_e32 v165, 0
	v_mov_b32_e32 v146, 0
	v_mov_b32_dpp v164, v110 row_ror:1 row_mask:0xf bank_mask:0xf
	v_mov_b32_dpp v165, v110 row_ror:2 row_mask:0xf bank_mask:0xf
	v_mov_b32_dpp v146, v110 row_ror:3 row_mask:0xf bank_mask:0xf
	v_cmp_lt_i32_e32 vcc, 1, v205
	s_and_saveexec_b64 s[2:3], vcc
	s_xor_b64 s[2:3], exec, s[2:3]
	s_cbranch_execz .LBB0_336
	v_cmp_gt_i32_e32 vcc, 3, v205
	s_and_saveexec_b64 s[80:81], vcc
	s_cbranch_execz .LBB0_335
	s_waitcnt vmcnt(0)
	v_mov_b32_e32 v146, v154

; __device__ __forceinline__ unsigned cvt_pk_bf16(float lo, float hi) { unsigned r; asm("v_cvt_pk_bf16_f32 %0, %1, %2" : "=v"(r) : "v"(lo), "v"(hi)); return r; }
; __device__ __forceinline__ float siluf_(float x) { return x * sigmoidf_(x); }
; __device__ __forceinline__ float dpp_ror1(float v) { return __builtin_bit_cast(float, __builtin_amdgcn_update_dpp(0, __builtin_bit_cast(int, v), 0x121, 0xf, 0xf, false)); }
;     __device__ __forceinline__ void operator()(f32x4 (&acc)[2][2][4][2], const pg8::Unit& u, int wr, int wc, int fr, int fq) const {
;     ...
;                 for (int n = 0; n < 2; ++n) { const int ch = ch0 + bj * 128 + 4 * n;
;                     const f32x4 w0 = *(const f32x4*)(cw + ch), w1 = *(const f32x4*)(cw + CW + ch), w2 = *(const f32x4*)(cw + 2 * CW + ch), w3 = *(const f32x4*)(cw + 3 * CW + ch), bb = *(const f32x4*)(cb + ch);
; #pragma unroll
;                     for (int m = 0; m < 4; ++m) { const int row = row0 + ai * 128 + m * 16; const f32x4 g = acc[ai][bj][m][n]; f32x4 p1, p2, p3;
;                         if (prompt) { const f32x4 gp = (m == 0) ? hal[n] : acc[ai][bj][m > 0 ? m - 1 : 0][n];
; #pragma unroll
;                             for (int j = 0; j < 4; ++j) { p1[j] = dpp_ror1(fr == 15 ? gp[j] : g[j]); p2[j] = dpp_ror2(fr >= 14 ? gp[j] : g[j]); p3[j] = dpp_ror3(fr >= 13 ? gp[j] : g[j]); } }
;                         else { const int t = fr & 3; const float* sp = stp + (size_t)((row - MP) >> 2) * 3 * CW + ch;
;                             const f32x4 b0 = *(const f32x4*)sp, b1 = *(const f32x4*)(sp + CW), b2 = *(const f32x4*)(sp + 2 * CW);
; #pragma unroll
;                             for (int j = 0; j < 4; ++j) { const float r1 = dpp_ror1(g[j]), r2 = dpp_ror2(g[j]), r3 = dpp_ror3(g[j]);
;                                 p1[j] = t >= 1 ? r1 : b2[j]; p2[j] = t >= 2 ? r2 : (t == 1 ? b2[j] : b1[j]); p3[j] = t >= 3 ? r3 : (t == 2 ? b2[j] : (t == 1 ? b1[j] : b0[j])); } }
;                         float o[4];
; #pragma unroll
;                         for (int j = 0; j < 4; ++j) { const float y = bb[j] + w0[j] * p3[j] + w1[j] * p2[j] + w2[j] * p1[j] + w3[j] * g[j]; o[j] = is_rg ? y : siluf_(y); }
;                         u32x2 w; w.x = cvt_pk_bf16(o[0], o[1]); w.y = cvt_pk_bf16(o[2], o[3]);
;                         *(u32x2*)(dst + (size_t)row * ld + bj * 128 + 4 * n) = w; }
.LBB0_375:
	v_mov_b32_e32 v224, v150
	v_mov_b32_e32 v225, v146
	v_pk_mul_f32 v[224:225], v[166:167], v[224:225]
	v_mov_b32_e32 v173, v158
	v_add_f32_e32 v146, v142, v225
	v_add_f32_e32 v146, v224, v146
	v_pk_mul_f32 v[172:173], v[168:169], v[172:173]
	v_mov_b32_e32 v165, v159
	v_add_f32_e32 v146, v173, v146
	v_add_f32_e32 v150, v172, v146
	v_mul_f32_e32 v146, 0xbfb8aa3b, v150
	v_exp_f32_e32 v146, v146
	v_mov_b32_e32 v157, v160
	s_mov_b64 s[2:3], -1
	s_and_b64 vcc, exec, s[18:19]
	v_add_f32_e32 v146, 1.0, v146
	v_rcp_f32_e32 v155, v146
	v_mov_b32_e32 v146, v151
	v_pk_mul_f32 v[146:147], v[134:135], v[146:147]
	v_mov_b32_e32 v172, v94
	v_add_f32_e32 v147, v143, v147
	v_add_f32_e32 v151, v146, v147
	v_pk_mul_f32 v[146:147], v[138:139], v[164:165]
	v_mov_b32_e32 v164, v95
	v_add_f32_e32 v147, v147, v151
	v_add_f32_e32 v151, v146, v147
	v_mul_f32_e32 v146, 0xbfb8aa3b, v151
	v_exp_f32_e32 v146, v146
	v_mul_f32_e32 v147, v150, v155
	v_cndmask_b32_e64 v150, v147, v150, s[4:5]
	v_mov_b32_e32 v147, v148
	v_add_f32_e32 v146, 1.0, v146
	v_rcp_f32_e32 v158, v146
	v_mov_b32_e32 v146, v152
	v_pk_mul_f32 v[146:147], v[162:163], v[146:147]
	v_mov_b32_e32 v155, v161
	v_add_f32_e32 v147, v144, v147
	v_add_f32_e32 v148, v146, v147
	v_pk_mul_f32 v[146:147], v[170:171], v[156:157]
	s_nop 0
	v_add_f32_e32 v147, v147, v148
	v_add_f32_e32 v152, v146, v147
	v_mul_f32_e32 v146, 0xbfb8aa3b, v152
	v_mov_b32_e32 v148, v153
	v_exp_f32_e32 v156, v146
	v_pk_mul_f32 v[146:147], v[136:137], v[148:149]
	v_add_f32_e32 v149, 1.0, v156
	v_add_f32_e32 v147, v145, v147
	v_add_f32_e32 v148, v146, v147
	v_pk_mul_f32 v[146:147], v[140:141], v[154:155]
	v_rcp_f32_e32 v149, v149
	v_add_f32_e32 v147, v147, v148
	v_add_f32_e32 v146, v146, v147
	v_mul_f32_e32 v147, 0xbfb8aa3b, v146
	v_exp_f32_e32 v147, v147
	v_mul_f32_e32 v148, v151, v158
	v_mul_f32_e32 v149, v152, v149
	v_cndmask_b32_e64 v148, v148, v151, s[4:5]
	v_add_f32_e32 v147, 1.0, v147
	v_rcp_f32_e32 v147, v147
	v_cndmask_b32_e64 v149, v149, v152, s[4:5]
	v_mov_b32_e32 v156, v96
	v_mov_b32_e32 v154, v97
	v_mul_f32_e32 v147, v146, v147
	v_cndmask_b32_e64 v147, v147, v146, s[4:5]
	v_cvt_pk_bf16_f32 v146, v150, v148
	v_cvt_pk_bf16_f32 v147, v149, v147
	v_lshlrev_b64 v[148:149], v182, v[200:201]
	v_lshl_add_u64 v[224:225], v[148:149], 1, v[220:221]
	global_store_dwordx2 v[224:225], v[146:147], off
	s_cbranch_vccnz .LBB0_417
	v_add_u32_e32 v147, 0xffffe020, v202
	v_ashrrev_i32_e32 v147, 2, v147
	v_lshl_add_u32 v147, v147, 1, v147
	v_mad_i64_i32 v[148:149], s[2:3], v147, s47, 0
	v_lshl_add_u64 v[148:149], v[148:149], 2, v[208:209]
	v_lshl_add_u64 v[150:151], v[148:149], 0, s[24:25]
	s_lshl_b32 s2, s27, 2
	s_mov_b32 s3, s25
	global_load_dwordx4 v[158:161], v[148:149], off
	s_nop 0
	global_load_dwordx4 v[150:153], v[150:151], off
	v_lshl_add_u64 v[148:149], v[148:149], 0, s[2:3]
	global_load_dwordx4 v[154:157], v[148:149], off
	v_mov_b32_e32 v164, 0
	v_mov_b32_e32 v165, 0
	v_mov_b32_e32 v146, 0
	v_mov_b32_dpp v164, v94 row_ror:1 row_mask:0xf bank_mask:0xf
	v_mov_b32_dpp v165, v94 row_ror:2 row_mask:0xf bank_mask:0xf
	v_mov_b32_dpp v146, v94 row_ror:3 row_mask:0xf bank_mask:0xf
	v_cmp_lt_i32_e32 vcc, 1, v205
	s_and_saveexec_b64 s[2:3], vcc
	s_xor_b64 s[2:3], exec, s[2:3]
	s_cbranch_execz .LBB0_380
	v_cmp_gt_i32_e32 vcc, 3, v205
	s_and_saveexec_b64 s[80:81], vcc
	s_cbranch_execz .LBB0_379
	s_waitcnt vmcnt(0)
	v_mov_b32_e32 v146, v154

; __device__ __forceinline__ unsigned cvt_pk_bf16(float lo, float hi) { unsigned r; asm("v_cvt_pk_bf16_f32 %0, %1, %2" : "=v"(r) : "v"(lo), "v"(hi)); return r; }
; __device__ __forceinline__ float siluf_(float x) { return x * sigmoidf_(x); }
; __device__ __forceinline__ float dpp_ror1(float v) { return __builtin_bit_cast(float, __builtin_amdgcn_update_dpp(0, __builtin_bit_cast(int, v), 0x121, 0xf, 0xf, false)); }
;     __device__ __forceinline__ void operator()(f32x4 (&acc)[2][2][4][2], const pg8::Unit& u, int wr, int wc, int fr, int fq) const {
;     ...
;                 for (int n = 0; n < 2; ++n) { const int ch = ch0 + bj * 128 + 4 * n;
;                     const f32x4 w0 = *(const f32x4*)(cw + ch), w1 = *(const f32x4*)(cw + CW + ch), w2 = *(const f32x4*)(cw + 2 * CW + ch), w3 = *(const f32x4*)(cw + 3 * CW + ch), bb = *(const f32x4*)(cb + ch);
; #pragma unroll
;                     for (int m = 0; m < 4; ++m) { const int row = row0 + ai * 128 + m * 16; const f32x4 g = acc[ai][bj][m][n]; f32x4 p1, p2, p3;
;                         if (prompt) { const f32x4 gp = (m == 0) ? hal[n] : acc[ai][bj][m > 0 ? m - 1 : 0][n];
; #pragma unroll
;                             for (int j = 0; j < 4; ++j) { p1[j] = dpp_ror1(fr == 15 ? gp[j] : g[j]); p2[j] = dpp_ror2(fr >= 14 ? gp[j] : g[j]); p3[j] = dpp_ror3(fr >= 13 ? gp[j] : g[j]); } }
;                         else { const int t = fr & 3; const float* sp = stp + (size_t)((row - MP) >> 2) * 3 * CW + ch;
;                             const f32x4 b0 = *(const f32x4*)sp, b1 = *(const f32x4*)(sp + CW), b2 = *(const f32x4*)(sp + 2 * CW);
; #pragma unroll
;                             for (int j = 0; j < 4; ++j) { const float r1 = dpp_ror1(g[j]), r2 = dpp_ror2(g[j]), r3 = dpp_ror3(g[j]);
;                                 p1[j] = t >= 1 ? r1 : b2[j]; p2[j] = t >= 2 ? r2 : (t == 1 ? b2[j] : b1[j]); p3[j] = t >= 3 ? r3 : (t == 2 ? b2[j] : (t == 1 ? b1[j] : b0[j])); } }
;                         float o[4];
; #pragma unroll
;                         for (int j = 0; j < 4; ++j) { const float y = bb[j] + w0[j] * p3[j] + w1[j] * p2[j] + w2[j] * p1[j] + w3[j] * g[j]; o[j] = is_rg ? y : siluf_(y); }
;                         u32x2 w; w.x = cvt_pk_bf16(o[0], o[1]); w.y = cvt_pk_bf16(o[2], o[3]);
;                         *(u32x2*)(dst + (size_t)row * ld + bj * 128 + 4 * n) = w; }
.LBB0_419:
	v_mov_b32_e32 v226, v150
	v_mov_b32_e32 v227, v146
	v_pk_mul_f32 v[226:227], v[166:167], v[226:227]
	v_mov_b32_e32 v173, v158
	v_add_f32_e32 v146, v142, v227
	v_add_f32_e32 v146, v226, v146
	v_pk_mul_f32 v[172:173], v[168:169], v[172:173]
	v_mov_b32_e32 v165, v159
	v_add_f32_e32 v146, v173, v146
	v_add_f32_e32 v150, v172, v146
	v_mul_f32_e32 v146, 0xbfb8aa3b, v150
	v_exp_f32_e32 v146, v146
	v_mov_b32_e32 v157, v160
	s_mov_b64 s[2:3], -1
	s_and_b64 vcc, exec, s[18:19]
	v_add_f32_e32 v146, 1.0, v146
	v_rcp_f32_e32 v155, v146
	v_mov_b32_e32 v146, v151
	v_pk_mul_f32 v[146:147], v[134:135], v[146:147]
	v_mov_b32_e32 v172, v78
	v_add_f32_e32 v147, v143, v147
	v_add_f32_e32 v151, v146, v147
	v_pk_mul_f32 v[146:147], v[138:139], v[164:165]
	v_mov_b32_e32 v164, v79
	v_add_f32_e32 v147, v147, v151
	v_add_f32_e32 v151, v146, v147
	v_mul_f32_e32 v146, 0xbfb8aa3b, v151
	v_exp_f32_e32 v146, v146
	v_mul_f32_e32 v147, v150, v155
	v_cndmask_b32_e64 v150, v147, v150, s[4:5]
	v_mov_b32_e32 v147, v148
	v_add_f32_e32 v146, 1.0, v146
	v_rcp_f32_e32 v158, v146
	v_mov_b32_e32 v146, v152
	v_pk_mul_f32 v[146:147], v[162:163], v[146:147]
	v_mov_b32_e32 v155, v161
	v_add_f32_e32 v147, v144, v147
	v_add_f32_e32 v148, v146, v147
	v_pk_mul_f32 v[146:147], v[170:171], v[156:157]
	s_nop 0
	v_add_f32_e32 v147, v147, v148
	v_add_f32_e32 v152, v146, v147
	v_mul_f32_e32 v146, 0xbfb8aa3b, v152
	v_mov_b32_e32 v148, v153
	v_exp_f32_e32 v156, v146
	v_pk_mul_f32 v[146:147], v[136:137], v[148:149]
	v_add_f32_e32 v149, 1.0, v156
	v_add_f32_e32 v147, v145, v147
	v_add_f32_e32 v148, v146, v147
	v_pk_mul_f32 v[146:147], v[140:141], v[154:155]
	v_rcp_f32_e32 v149, v149
	v_add_f32_e32 v147, v147, v148
	v_add_f32_e32 v146, v146, v147
	v_mul_f32_e32 v147, 0xbfb8aa3b, v146
	v_exp_f32_e32 v147, v147
	v_mul_f32_e32 v148, v151, v158
	v_mul_f32_e32 v149, v152, v149
	v_cndmask_b32_e64 v148, v148, v151, s[4:5]
	v_add_f32_e32 v147, 1.0, v147
	v_rcp_f32_e32 v147, v147
	v_cndmask_b32_e64 v149, v149, v152, s[4:5]
	v_mov_b32_e32 v156, v80
	v_mov_b32_e32 v154, v81
	v_mul_f32_e32 v147, v146, v147
	v_cndmask_b32_e64 v147, v147, v146, s[4:5]
	v_cvt_pk_bf16_f32 v146, v150, v148
	v_cvt_pk_bf16_f32 v147, v149, v147
	v_lshlrev_b64 v[148:149], v182, v[198:199]
	v_lshl_add_u64 v[226:227], v[148:149], 1, v[220:221]
	global_store_dwordx2 v[226:227], v[146:147], off
	s_cbranch_vccnz .LBB0_461
	v_add_u32_e32 v147, 0xffffe030, v202
	v_ashrrev_i32_e32 v147, 2, v147
	v_lshl_add_u32 v147, v147, 1, v147
	v_mad_i64_i32 v[148:149], s[2:3], v147, s47, 0
	v_lshl_add_u64 v[148:149], v[148:149], 2, v[208:209]
	v_lshl_add_u64 v[150:151], v[148:149], 0, s[24:25]
	s_lshl_b32 s2, s27, 2
	s_mov_b32 s3, s25
	global_load_dwordx4 v[158:161], v[148:149], off
	s_nop 0
	global_load_dwordx4 v[150:153], v[150:151], off
	v_lshl_add_u64 v[148:149], v[148:149], 0, s[2:3]
	global_load_dwordx4 v[154:157], v[148:149], off
	v_mov_b32_e32 v164, 0
	v_mov_b32_e32 v165, 0
	v_mov_b32_e32 v146, 0
	v_mov_b32_dpp v164, v78 row_ror:1 row_mask:0xf bank_mask:0xf
	v_mov_b32_dpp v165, v78 row_ror:2 row_mask:0xf bank_mask:0xf
	v_mov_b32_dpp v146, v78 row_ror:3 row_mask:0xf bank_mask:0xf
	v_cmp_lt_i32_e32 vcc, 1, v205
	s_and_saveexec_b64 s[2:3], vcc
	s_xor_b64 s[2:3], exec, s[2:3]
	s_cbranch_execz .LBB0_424
	v_cmp_gt_i32_e32 vcc, 3, v205
	s_and_saveexec_b64 s[80:81], vcc
	s_cbranch_execz .LBB0_423
	s_waitcnt vmcnt(0)
	v_mov_b32_e32 v146, v154

; __device__ __forceinline__ unsigned cvt_pk_bf16(float lo, float hi) { unsigned r; asm("v_cvt_pk_bf16_f32 %0, %1, %2" : "=v"(r) : "v"(lo), "v"(hi)); return r; }
; __device__ __forceinline__ float siluf_(float x) { return x * sigmoidf_(x); }
; __device__ __forceinline__ float dpp_ror1(float v) { return __builtin_bit_cast(float, __builtin_amdgcn_update_dpp(0, __builtin_bit_cast(int, v), 0x121, 0xf, 0xf, false)); }
;     __device__ __forceinline__ void operator()(f32x4 (&acc)[2][2][4][2], const pg8::Unit& u, int wr, int wc, int fr, int fq) const {
;     ...
;                 for (int n = 0; n < 2; ++n) { const int ch = ch0 + bj * 128 + 4 * n;
;                     const f32x4 w0 = *(const f32x4*)(cw + ch), w1 = *(const f32x4*)(cw + CW + ch), w2 = *(const f32x4*)(cw + 2 * CW + ch), w3 = *(const f32x4*)(cw + 3 * CW + ch), bb = *(const f32x4*)(cb + ch);
; #pragma unroll
;                     for (int m = 0; m < 4; ++m) { const int row = row0 + ai * 128 + m * 16; const f32x4 g = acc[ai][bj][m][n]; f32x4 p1, p2, p3;
;                         if (prompt) { const f32x4 gp = (m == 0) ? hal[n] : acc[ai][bj][m > 0 ? m - 1 : 0][n];
; #pragma unroll
;                             for (int j = 0; j < 4; ++j) { p1[j] = dpp_ror1(fr == 15 ? gp[j] : g[j]); p2[j] = dpp_ror2(fr >= 14 ? gp[j] : g[j]); p3[j] = dpp_ror3(fr >= 13 ? gp[j] : g[j]); } }
;                         else { const int t = fr & 3; const float* sp = stp + (size_t)((row - MP) >> 2) * 3 * CW + ch;
;                             const f32x4 b0 = *(const f32x4*)sp, b1 = *(const f32x4*)(sp + CW), b2 = *(const f32x4*)(sp + 2 * CW);
; #pragma unroll
;                             for (int j = 0; j < 4; ++j) { const float r1 = dpp_ror1(g[j]), r2 = dpp_ror2(g[j]), r3 = dpp_ror3(g[j]);
;                                 p1[j] = t >= 1 ? r1 : b2[j]; p2[j] = t >= 2 ? r2 : (t == 1 ? b2[j] : b1[j]); p3[j] = t >= 3 ? r3 : (t == 2 ? b2[j] : (t == 1 ? b1[j] : b0[j])); } }
;                         float o[4];
; #pragma unroll
;                         for (int j = 0; j < 4; ++j) { const float y = bb[j] + w0[j] * p3[j] + w1[j] * p2[j] + w2[j] * p1[j] + w3[j] * g[j]; o[j] = is_rg ? y : siluf_(y); }
;                         u32x2 w; w.x = cvt_pk_bf16(o[0], o[1]); w.y = cvt_pk_bf16(o[2], o[3]);
;                         *(u32x2*)(dst + (size_t)row * ld + bj * 128 + 4 * n) = w; }
.LBB0_463:
	v_mov_b32_e32 v228, v150
	v_mov_b32_e32 v229, v146
	v_pk_mul_f32 v[166:167], v[166:167], v[228:229]
	v_mov_b32_e32 v173, v158
	v_add_f32_e32 v142, v142, v167
	v_add_f32_e32 v142, v166, v142
	v_pk_mul_f32 v[166:167], v[168:169], v[172:173]
	v_mov_b32_e32 v165, v159
	v_add_f32_e32 v142, v167, v142
	v_add_f32_e32 v142, v166, v142
	v_mul_f32_e32 v146, 0xbfb8aa3b, v142
	v_exp_f32_e32 v146, v146
	v_mov_b32_e32 v157, v160
	v_mov_b32_e32 v155, v161
	s_mov_b64 s[2:3], -1
	v_add_f32_e32 v146, 1.0, v146
	v_rcp_f32_e32 v150, v146
	v_mov_b32_e32 v146, v151
	v_pk_mul_f32 v[134:135], v[134:135], v[146:147]
	s_and_b64 vcc, exec, s[18:19]
	v_add_f32_e32 v135, v143, v135
	v_add_f32_e32 v143, v134, v135
	v_pk_mul_f32 v[134:135], v[138:139], v[164:165]
	v_mov_b32_e32 v234, v126
	v_add_f32_e32 v135, v135, v143
	v_add_f32_e32 v138, v134, v135
	v_mul_f32_e32 v134, 0xbfb8aa3b, v138
	v_exp_f32_e32 v134, v134
	v_mul_f32_e32 v135, v142, v150
	v_cndmask_b32_e64 v139, v135, v142, s[4:5]
	v_mov_b32_e32 v135, v148
	v_add_f32_e32 v134, 1.0, v134
	v_rcp_f32_e32 v142, v134
	v_mov_b32_e32 v134, v152
	v_pk_mul_f32 v[134:135], v[162:163], v[134:135]
	v_mov_b32_e32 v148, v153
	v_add_f32_e32 v135, v144, v135
	v_add_f32_e32 v143, v134, v135
	v_pk_mul_f32 v[134:135], v[170:171], v[156:157]
	v_mov_b32_e32 v232, v127
	v_add_f32_e32 v135, v135, v143
	v_add_f32_e32 v143, v134, v135
	v_mul_f32_e32 v134, 0xbfb8aa3b, v143
	v_exp_f32_e32 v144, v134
	v_pk_mul_f32 v[134:135], v[136:137], v[148:149]
	v_mov_b32_e32 v172, v128
	v_add_f32_e32 v135, v145, v135
	v_add_f32_e32 v136, v134, v135
	v_pk_mul_f32 v[134:135], v[140:141], v[154:155]
	v_add_f32_e32 v137, 1.0, v144
	v_add_f32_e32 v135, v135, v136
	v_add_f32_e32 v134, v134, v135
	v_mul_f32_e32 v135, 0xbfb8aa3b, v134
	v_exp_f32_e32 v135, v135
	v_rcp_f32_e32 v137, v137
	v_mul_f32_e32 v136, v138, v142
	v_cndmask_b32_e64 v136, v136, v138, s[4:5]
	v_add_f32_e32 v135, 1.0, v135
	v_rcp_f32_e32 v135, v135
	v_mul_f32_e32 v137, v143, v137
	v_cndmask_b32_e64 v137, v137, v143, s[4:5]
	v_mov_b32_e32 v170, v129
	v_mul_f32_e32 v135, v134, v135
	v_cndmask_b32_e64 v135, v135, v134, s[4:5]
	v_cvt_pk_bf16_f32 v134, v139, v136
	v_cvt_pk_bf16_f32 v135, v137, v135
	v_lshlrev_b64 v[136:137], v182, v[196:197]
	v_lshl_add_u64 v[228:229], v[136:137], 1, v[220:221]
	global_store_dwordx2 v[228:229], v[134:135], off
	global_load_dwordx4 v[138:141], v[210:211], off offset:16
	global_load_dwordx4 v[150:153], v[212:213], off offset:16
	global_load_dwordx4 v[134:137], v[214:215], off offset:16
	global_load_dwordx4 v[146:149], v[216:217], off offset:16
	global_load_dwordx4 v[142:145], v[218:219], off offset:16
	s_cbranch_vccnz .LBB0_505
	v_add_u32_e32 v155, 0xffffe000, v202
	v_ashrrev_i32_e32 v155, 2, v155
	v_lshl_add_u32 v155, v155, 1, v155
	v_mad_i64_i32 v[156:157], s[2:3], v155, s47, 0
	v_lshl_add_u64 v[156:157], v[156:157], 2, v[208:209]
	v_lshl_add_u64 v[158:159], v[156:157], 0, s[24:25]
	s_lshl_b32 s2, s27, 2
	s_mov_b32 s3, s25
	global_load_dwordx4 v[166:169], v[156:157], off offset:16
	s_nop 0
	global_load_dwordx4 v[158:161], v[158:159], off offset:16
	v_lshl_add_u64 v[156:157], v[156:157], 0, s[2:3]
	global_load_dwordx4 v[162:165], v[156:157], off offset:16
	v_mov_b32_e32 v170, 0
	v_mov_b32_e32 v171, 0
	v_mov_b32_e32 v154, 0
	v_mov_b32_dpp v170, v126 row_ror:1 row_mask:0xf bank_mask:0xf
	v_mov_b32_dpp v171, v126 row_ror:2 row_mask:0xf bank_mask:0xf
	v_mov_b32_dpp v154, v126 row_ror:3 row_mask:0xf bank_mask:0xf
	v_cmp_lt_i32_e32 vcc, 1, v205
	s_and_saveexec_b64 s[2:3], vcc
	s_xor_b64 s[2:3], exec, s[2:3]
	s_cbranch_execz .LBB0_468
	v_cmp_gt_i32_e32 vcc, 3, v205
	s_and_saveexec_b64 s[80:81], vcc
	s_cbranch_execz .LBB0_467
	s_waitcnt vmcnt(0)
	v_mov_b32_e32 v154, v162

; __device__ __forceinline__ unsigned cvt_pk_bf16(float lo, float hi) { unsigned r; asm("v_cvt_pk_bf16_f32 %0, %1, %2" : "=v"(r) : "v"(lo), "v"(hi)); return r; }
; __device__ __forceinline__ float siluf_(float x) { return x * sigmoidf_(x); }
; __device__ __forceinline__ float dpp_ror1(float v) { return __builtin_bit_cast(float, __builtin_amdgcn_update_dpp(0, __builtin_bit_cast(int, v), 0x121, 0xf, 0xf, false)); }
;     __device__ __forceinline__ void operator()(f32x4 (&acc)[2][2][4][2], const pg8::Unit& u, int wr, int wc, int fr, int fq) const {
;     ...
;                 for (int n = 0; n < 2; ++n) { const int ch = ch0 + bj * 128 + 4 * n;
;                     const f32x4 w0 = *(const f32x4*)(cw + ch), w1 = *(const f32x4*)(cw + CW + ch), w2 = *(const f32x4*)(cw + 2 * CW + ch), w3 = *(const f32x4*)(cw + 3 * CW + ch), bb = *(const f32x4*)(cb + ch);
; #pragma unroll
;                     for (int m = 0; m < 4; ++m) { const int row = row0 + ai * 128 + m * 16; const f32x4 g = acc[ai][bj][m][n]; f32x4 p1, p2, p3;
;                         if (prompt) { const f32x4 gp = (m == 0) ? hal[n] : acc[ai][bj][m > 0 ? m - 1 : 0][n];
; #pragma unroll
;                             for (int j = 0; j < 4; ++j) { p1[j] = dpp_ror1(fr == 15 ? gp[j] : g[j]); p2[j] = dpp_ror2(fr >= 14 ? gp[j] : g[j]); p3[j] = dpp_ror3(fr >= 13 ? gp[j] : g[j]); } }
;                         else { const int t = fr & 3; const float* sp = stp + (size_t)((row - MP) >> 2) * 3 * CW + ch;
;                             const f32x4 b0 = *(const f32x4*)sp, b1 = *(const f32x4*)(sp + CW), b2 = *(const f32x4*)(sp + 2 * CW);
; #pragma unroll
;                             for (int j = 0; j < 4; ++j) { const float r1 = dpp_ror1(g[j]), r2 = dpp_ror2(g[j]), r3 = dpp_ror3(g[j]);
;                                 p1[j] = t >= 1 ? r1 : b2[j]; p2[j] = t >= 2 ? r2 : (t == 1 ? b2[j] : b1[j]); p3[j] = t >= 3 ? r3 : (t == 2 ? b2[j] : (t == 1 ? b1[j] : b0[j])); } }
;                         float o[4];
; #pragma unroll
;                         for (int j = 0; j < 4; ++j) { const float y = bb[j] + w0[j] * p3[j] + w1[j] * p2[j] + w2[j] * p1[j] + w3[j] * g[j]; o[j] = is_rg ? y : siluf_(y); }
;                         u32x2 w; w.x = cvt_pk_bf16(o[0], o[1]); w.y = cvt_pk_bf16(o[2], o[3]);
;                         *(u32x2*)(dst + (size_t)row * ld + bj * 128 + 4 * n) = w; }
.LBB0_507:
	s_waitcnt vmcnt(0)
	v_mov_b32_e32 v162, v150
	v_mov_b32_e32 v163, v138
	v_mov_b32_e32 v130, v158
	v_mov_b32_e32 v131, v154
	v_pk_mul_f32 v[130:131], v[162:163], v[130:131]
	v_mov_b32_e32 v164, v146
	v_add_f32_e32 v131, v142, v131
	v_mov_b32_e32 v165, v134
	v_mov_b32_e32 v235, v166
	v_add_f32_e32 v132, v130, v131
	v_pk_mul_f32 v[130:131], v[164:165], v[234:235]
	v_mov_b32_e32 v138, v151
	v_add_f32_e32 v131, v131, v132
	v_add_f32_e32 v132, v130, v131
	v_mul_f32_e32 v130, 0xbfb8aa3b, v132
	v_exp_f32_e32 v130, v130
	v_mov_b32_e32 v154, v159
	v_mov_b32_e32 v134, v147
	v_mov_b32_e32 v233, v167
	v_add_f32_e32 v130, 1.0, v130
	v_rcp_f32_e32 v133, v130
	v_pk_mul_f32 v[130:131], v[138:139], v[154:155]
	v_mov_b32_e32 v158, v152
	v_add_f32_e32 v131, v143, v131
	v_add_f32_e32 v146, v130, v131
	v_pk_mul_f32 v[130:131], v[134:135], v[232:233]
	v_mov_b32_e32 v159, v140
	v_add_f32_e32 v131, v131, v146
	v_add_f32_e32 v146, v130, v131
	v_mul_f32_e32 v130, 0xbfb8aa3b, v146
	v_exp_f32_e32 v130, v130
	v_mul_f32_e32 v131, v132, v133
	v_cndmask_b32_e64 v132, v131, v132, s[4:5]
	v_mov_b32_e32 v131, v156
	v_add_f32_e32 v130, 1.0, v130
	v_rcp_f32_e32 v133, v130
	v_mov_b32_e32 v130, v160
	v_pk_mul_f32 v[130:131], v[158:159], v[130:131]
	v_mov_b32_e32 v166, v148
	v_add_f32_e32 v131, v144, v131
	v_mov_b32_e32 v167, v136
	v_mov_b32_e32 v173, v168
	v_add_f32_e32 v140, v130, v131
	v_pk_mul_f32 v[130:131], v[166:167], v[172:173]
	v_mov_b32_e32 v156, v161
	v_add_f32_e32 v131, v131, v140
	v_add_f32_e32 v147, v130, v131
	v_mul_f32_e32 v130, 0xbfb8aa3b, v147
	v_mov_b32_e32 v140, v153
	v_exp_f32_e32 v148, v130
	v_pk_mul_f32 v[130:131], v[140:141], v[156:157]
	v_mov_b32_e32 v136, v149
	v_add_f32_e32 v131, v145, v131
	v_mov_b32_e32 v171, v169
	v_add_f32_e32 v150, v130, v131
	v_pk_mul_f32 v[130:131], v[136:137], v[170:171]
	v_add_f32_e32 v148, 1.0, v148
	v_add_f32_e32 v131, v131, v150
	v_add_f32_e32 v130, v130, v131
	v_mul_f32_e32 v131, 0xbfb8aa3b, v130
	v_exp_f32_e32 v131, v131
	v_rcp_f32_e32 v148, v148
	v_mul_f32_e32 v133, v146, v133
	v_cndmask_b32_e64 v133, v133, v146, s[4:5]
	v_add_f32_e32 v131, 1.0, v131
	v_rcp_f32_e32 v131, v131
	v_mul_f32_e32 v146, v147, v148
	v_cndmask_b32_e64 v146, v146, v147, s[4:5]
	s_mov_b64 s[2:3], -1
	v_mul_f32_e32 v131, v130, v131
	v_cndmask_b32_e64 v131, v131, v130, s[4:5]
	v_cvt_pk_bf16_f32 v130, v132, v133
	v_cvt_pk_bf16_f32 v131, v146, v131
	s_and_b64 vcc, exec, s[18:19]
	v_mov_b32_e32 v168, v106
	v_mov_b32_e32 v160, v107
	v_mov_b32_e32 v152, v108
	v_mov_b32_e32 v150, v109
	global_store_dwordx2 v[222:223], v[130:131], off offset:8
	s_cbranch_vccnz .LBB0_549
	v_add_u32_e32 v131, 0xffffe010, v202
	v_ashrrev_i32_e32 v131, 2, v131
	v_lshl_add_u32 v131, v131, 1, v131
	v_mad_i64_i32 v[132:133], s[2:3], v131, s47, 0
	v_lshl_add_u64 v[132:133], v[132:133], 2, v[208:209]
	v_lshl_add_u64 v[146:147], v[132:133], 0, s[24:25]
	s_lshl_b32 s2, s27, 2
	s_mov_b32 s3, s25
	global_load_dwordx4 v[154:157], v[132:133], off offset:16
	s_nop 0
	global_load_dwordx4 v[146:149], v[146:147], off offset:16
	v_lshl_add_u64 v[132:133], v[132:133], 0, s[2:3]
	global_load_dwordx4 v[150:153], v[132:133], off offset:16
	v_mov_b32_e32 v160, 0
	v_mov_b32_e32 v161, 0
	v_mov_b32_e32 v130, 0
	v_mov_b32_dpp v160, v106 row_ror:1 row_mask:0xf bank_mask:0xf
	v_mov_b32_dpp v161, v106 row_ror:2 row_mask:0xf bank_mask:0xf
	v_mov_b32_dpp v130, v106 row_ror:3 row_mask:0xf bank_mask:0xf
	v_cmp_lt_i32_e32 vcc, 1, v205
	s_and_saveexec_b64 s[2:3], vcc
	s_xor_b64 s[2:3], exec, s[2:3]
	s_cbranch_execz .LBB0_512
	v_cmp_gt_i32_e32 vcc, 3, v205
	s_and_saveexec_b64 s[80:81], vcc
	s_cbranch_execz .LBB0_511
	s_waitcnt vmcnt(0)
	v_mov_b32_e32 v130, v150

; __device__ __forceinline__ unsigned cvt_pk_bf16(float lo, float hi) { unsigned r; asm("v_cvt_pk_bf16_f32 %0, %1, %2" : "=v"(r) : "v"(lo), "v"(hi)); return r; }
; __device__ __forceinline__ float siluf_(float x) { return x * sigmoidf_(x); }
; __device__ __forceinline__ float dpp_ror1(float v) { return __builtin_bit_cast(float, __builtin_amdgcn_update_dpp(0, __builtin_bit_cast(int, v), 0x121, 0xf, 0xf, false)); }
;     __device__ __forceinline__ void operator()(f32x4 (&acc)[2][2][4][2], const pg8::Unit& u, int wr, int wc, int fr, int fq) const {
;     ...
;                 for (int n = 0; n < 2; ++n) { const int ch = ch0 + bj * 128 + 4 * n;
;                     const f32x4 w0 = *(const f32x4*)(cw + ch), w1 = *(const f32x4*)(cw + CW + ch), w2 = *(const f32x4*)(cw + 2 * CW + ch), w3 = *(const f32x4*)(cw + 3 * CW + ch), bb = *(const f32x4*)(cb + ch);
; #pragma unroll
;                     for (int m = 0; m < 4; ++m) { const int row = row0 + ai * 128 + m * 16; const f32x4 g = acc[ai][bj][m][n]; f32x4 p1, p2, p3;
;                         if (prompt) { const f32x4 gp = (m == 0) ? hal[n] : acc[ai][bj][m > 0 ? m - 1 : 0][n];
; #pragma unroll
;                             for (int j = 0; j < 4; ++j) { p1[j] = dpp_ror1(fr == 15 ? gp[j] : g[j]); p2[j] = dpp_ror2(fr >= 14 ? gp[j] : g[j]); p3[j] = dpp_ror3(fr >= 13 ? gp[j] : g[j]); } }
;                         else { const int t = fr & 3; const float* sp = stp + (size_t)((row - MP) >> 2) * 3 * CW + ch;
;                             const f32x4 b0 = *(const f32x4*)sp, b1 = *(const f32x4*)(sp + CW), b2 = *(const f32x4*)(sp + 2 * CW);
; #pragma unroll
;                             for (int j = 0; j < 4; ++j) { const float r1 = dpp_ror1(g[j]), r2 = dpp_ror2(g[j]), r3 = dpp_ror3(g[j]);
;                                 p1[j] = t >= 1 ? r1 : b2[j]; p2[j] = t >= 2 ? r2 : (t == 1 ? b2[j] : b1[j]); p3[j] = t >= 3 ? r3 : (t == 2 ? b2[j] : (t == 1 ? b1[j] : b0[j])); } }
;                         float o[4];
; #pragma unroll
;                         for (int j = 0; j < 4; ++j) { const float y = bb[j] + w0[j] * p3[j] + w1[j] * p2[j] + w2[j] * p1[j] + w3[j] * g[j]; o[j] = is_rg ? y : siluf_(y); }
;                         u32x2 w; w.x = cvt_pk_bf16(o[0], o[1]); w.y = cvt_pk_bf16(o[2], o[3]);
;                         *(u32x2*)(dst + (size_t)row * ld + bj * 128 + 4 * n) = w; }
.LBB0_551:
	v_mov_b32_e32 v170, v146
	v_mov_b32_e32 v171, v130
	v_pk_mul_f32 v[170:171], v[162:163], v[170:171]
	v_mov_b32_e32 v169, v154
	v_add_f32_e32 v130, v142, v171
	v_add_f32_e32 v130, v170, v130
	v_pk_mul_f32 v[168:169], v[164:165], v[168:169]
	v_mov_b32_e32 v161, v155
	v_add_f32_e32 v130, v169, v130
	v_add_f32_e32 v146, v168, v130
	v_mul_f32_e32 v130, 0xbfb8aa3b, v146
	v_exp_f32_e32 v130, v130
	v_mov_b32_e32 v153, v156
	s_mov_b64 s[2:3], -1
	s_and_b64 vcc, exec, s[18:19]
	v_add_f32_e32 v130, 1.0, v130
	v_rcp_f32_e32 v151, v130
	v_mov_b32_e32 v130, v147
	v_pk_mul_f32 v[130:131], v[138:139], v[130:131]
	v_mov_b32_e32 v168, v90
	v_add_f32_e32 v131, v143, v131
	v_add_f32_e32 v147, v130, v131
	v_pk_mul_f32 v[130:131], v[134:135], v[160:161]
	v_mov_b32_e32 v160, v91
	v_add_f32_e32 v131, v131, v147
	v_add_f32_e32 v147, v130, v131
	v_mul_f32_e32 v130, 0xbfb8aa3b, v147
	v_exp_f32_e32 v130, v130
	v_mul_f32_e32 v131, v146, v151
	v_cndmask_b32_e64 v146, v131, v146, s[4:5]
	v_mov_b32_e32 v131, v132
	v_add_f32_e32 v130, 1.0, v130
	v_rcp_f32_e32 v154, v130
	v_mov_b32_e32 v130, v148
	v_pk_mul_f32 v[130:131], v[158:159], v[130:131]
	v_mov_b32_e32 v151, v157
	v_add_f32_e32 v131, v144, v131
	v_add_f32_e32 v132, v130, v131
	v_pk_mul_f32 v[130:131], v[166:167], v[152:153]
	s_nop 0
	v_add_f32_e32 v131, v131, v132
	v_add_f32_e32 v148, v130, v131
	v_mul_f32_e32 v130, 0xbfb8aa3b, v148
	v_mov_b32_e32 v132, v149
	v_exp_f32_e32 v152, v130
	v_pk_mul_f32 v[130:131], v[140:141], v[132:133]
	v_add_f32_e32 v133, 1.0, v152
	v_add_f32_e32 v131, v145, v131
	v_add_f32_e32 v132, v130, v131
	v_pk_mul_f32 v[130:131], v[136:137], v[150:151]
	v_rcp_f32_e32 v133, v133
	v_add_f32_e32 v131, v131, v132
	v_add_f32_e32 v130, v130, v131
	v_mul_f32_e32 v131, 0xbfb8aa3b, v130
	v_exp_f32_e32 v131, v131
	v_mul_f32_e32 v132, v147, v154
	v_mul_f32_e32 v133, v148, v133
	v_cndmask_b32_e64 v132, v132, v147, s[4:5]
	v_add_f32_e32 v131, 1.0, v131
	v_rcp_f32_e32 v131, v131
	v_cndmask_b32_e64 v133, v133, v148, s[4:5]
	v_mov_b32_e32 v152, v92
	v_mov_b32_e32 v150, v93
	v_mul_f32_e32 v131, v130, v131
	v_cndmask_b32_e64 v131, v131, v130, s[4:5]
	v_cvt_pk_bf16_f32 v130, v146, v132
	v_cvt_pk_bf16_f32 v131, v133, v131
	global_store_dwordx2 v[224:225], v[130:131], off offset:8
	s_cbranch_vccnz .LBB0_593
	v_add_u32_e32 v131, 0xffffe020, v202
	v_ashrrev_i32_e32 v131, 2, v131
	v_lshl_add_u32 v131, v131, 1, v131
	v_mad_i64_i32 v[132:133], s[2:3], v131, s47, 0
	v_lshl_add_u64 v[132:133], v[132:133], 2, v[208:209]
	v_lshl_add_u64 v[146:147], v[132:133], 0, s[24:25]
	s_lshl_b32 s2, s27, 2
	s_mov_b32 s3, s25
	global_load_dwordx4 v[154:157], v[132:133], off offset:16
	s_nop 0
	global_load_dwordx4 v[146:149], v[146:147], off offset:16
	v_lshl_add_u64 v[132:133], v[132:133], 0, s[2:3]
	global_load_dwordx4 v[150:153], v[132:133], off offset:16
	v_mov_b32_e32 v160, 0
	v_mov_b32_e32 v161, 0
	v_mov_b32_e32 v130, 0
	v_mov_b32_dpp v160, v90 row_ror:1 row_mask:0xf bank_mask:0xf
	v_mov_b32_dpp v161, v90 row_ror:2 row_mask:0xf bank_mask:0xf
	v_mov_b32_dpp v130, v90 row_ror:3 row_mask:0xf bank_mask:0xf
	v_cmp_lt_i32_e32 vcc, 1, v205
	s_and_saveexec_b64 s[2:3], vcc
	s_xor_b64 s[2:3], exec, s[2:3]
	s_cbranch_execz .LBB0_556
	v_cmp_gt_i32_e32 vcc, 3, v205
	s_and_saveexec_b64 s[80:81], vcc
	s_cbranch_execz .LBB0_555
	s_waitcnt vmcnt(0)
	v_mov_b32_e32 v130, v150

; __device__ __forceinline__ unsigned cvt_pk_bf16(float lo, float hi) { unsigned r; asm("v_cvt_pk_bf16_f32 %0, %1, %2" : "=v"(r) : "v"(lo), "v"(hi)); return r; }
; __device__ __forceinline__ float siluf_(float x) { return x * sigmoidf_(x); }
; __device__ __forceinline__ float dpp_ror1(float v) { return __builtin_bit_cast(float, __builtin_amdgcn_update_dpp(0, __builtin_bit_cast(int, v), 0x121, 0xf, 0xf, false)); }
;     __device__ __forceinline__ void operator()(f32x4 (&acc)[2][2][4][2], const pg8::Unit& u, int wr, int wc, int fr, int fq) const {
;     ...
;                 for (int n = 0; n < 2; ++n) { const int ch = ch0 + bj * 128 + 4 * n;
;                     const f32x4 w0 = *(const f32x4*)(cw + ch), w1 = *(const f32x4*)(cw + CW + ch), w2 = *(const f32x4*)(cw + 2 * CW + ch), w3 = *(const f32x4*)(cw + 3 * CW + ch), bb = *(const f32x4*)(cb + ch);
; #pragma unroll
;                     for (int m = 0; m < 4; ++m) { const int row = row0 + ai * 128 + m * 16; const f32x4 g = acc[ai][bj][m][n]; f32x4 p1, p2, p3;
;                         if (prompt) { const f32x4 gp = (m == 0) ? hal[n] : acc[ai][bj][m > 0 ? m - 1 : 0][n];
; #pragma unroll
;                             for (int j = 0; j < 4; ++j) { p1[j] = dpp_ror1(fr == 15 ? gp[j] : g[j]); p2[j] = dpp_ror2(fr >= 14 ? gp[j] : g[j]); p3[j] = dpp_ror3(fr >= 13 ? gp[j] : g[j]); } }
;                         else { const int t = fr & 3; const float* sp = stp + (size_t)((row - MP) >> 2) * 3 * CW + ch;
;                             const f32x4 b0 = *(const f32x4*)sp, b1 = *(const f32x4*)(sp + CW), b2 = *(const f32x4*)(sp + 2 * CW);
; #pragma unroll
;                             for (int j = 0; j < 4; ++j) { const float r1 = dpp_ror1(g[j]), r2 = dpp_ror2(g[j]), r3 = dpp_ror3(g[j]);
;                                 p1[j] = t >= 1 ? r1 : b2[j]; p2[j] = t >= 2 ? r2 : (t == 1 ? b2[j] : b1[j]); p3[j] = t >= 3 ? r3 : (t == 2 ? b2[j] : (t == 1 ? b1[j] : b0[j])); } }
;                         float o[4];
; #pragma unroll
;                         for (int j = 0; j < 4; ++j) { const float y = bb[j] + w0[j] * p3[j] + w1[j] * p2[j] + w2[j] * p1[j] + w3[j] * g[j]; o[j] = is_rg ? y : siluf_(y); }
;                         u32x2 w; w.x = cvt_pk_bf16(o[0], o[1]); w.y = cvt_pk_bf16(o[2], o[3]);
;                         *(u32x2*)(dst + (size_t)row * ld + bj * 128 + 4 * n) = w; }
.LBB0_595:
	v_mov_b32_e32 v170, v146
	v_mov_b32_e32 v171, v130
	v_pk_mul_f32 v[170:171], v[162:163], v[170:171]
	v_mov_b32_e32 v169, v154
	v_add_f32_e32 v130, v142, v171
	v_add_f32_e32 v130, v170, v130
	v_pk_mul_f32 v[168:169], v[164:165], v[168:169]
	v_mov_b32_e32 v161, v155
	v_add_f32_e32 v130, v169, v130
	v_add_f32_e32 v146, v168, v130
	v_mul_f32_e32 v130, 0xbfb8aa3b, v146
	v_exp_f32_e32 v130, v130
	v_mov_b32_e32 v153, v156
	s_mov_b64 s[2:3], -1
	s_and_b64 vcc, exec, s[18:19]
	v_add_f32_e32 v130, 1.0, v130
	v_rcp_f32_e32 v151, v130
	v_mov_b32_e32 v130, v147
	v_pk_mul_f32 v[130:131], v[138:139], v[130:131]
	v_mov_b32_e32 v168, v74
	v_add_f32_e32 v131, v143, v131
	v_add_f32_e32 v147, v130, v131
	v_pk_mul_f32 v[130:131], v[134:135], v[160:161]
	v_mov_b32_e32 v160, v75
	v_add_f32_e32 v131, v131, v147
	v_add_f32_e32 v147, v130, v131
	v_mul_f32_e32 v130, 0xbfb8aa3b, v147
	v_exp_f32_e32 v130, v130
	v_mul_f32_e32 v131, v146, v151
	v_cndmask_b32_e64 v146, v131, v146, s[4:5]
	v_mov_b32_e32 v131, v132
	v_add_f32_e32 v130, 1.0, v130
	v_rcp_f32_e32 v154, v130
	v_mov_b32_e32 v130, v148
	v_pk_mul_f32 v[130:131], v[158:159], v[130:131]
	v_mov_b32_e32 v151, v157
	v_add_f32_e32 v131, v144, v131
	v_add_f32_e32 v132, v130, v131
	v_pk_mul_f32 v[130:131], v[166:167], v[152:153]
	s_nop 0
	v_add_f32_e32 v131, v131, v132
	v_add_f32_e32 v148, v130, v131
	v_mul_f32_e32 v130, 0xbfb8aa3b, v148
	v_mov_b32_e32 v132, v149
	v_exp_f32_e32 v152, v130
	v_pk_mul_f32 v[130:131], v[140:141], v[132:133]
	v_add_f32_e32 v133, 1.0, v152
	v_add_f32_e32 v131, v145, v131
	v_add_f32_e32 v132, v130, v131
	v_pk_mul_f32 v[130:131], v[136:137], v[150:151]
	v_rcp_f32_e32 v133, v133
	v_add_f32_e32 v131, v131, v132
	v_add_f32_e32 v130, v130, v131
	v_mul_f32_e32 v131, 0xbfb8aa3b, v130
	v_exp_f32_e32 v131, v131
	v_mul_f32_e32 v132, v147, v154
	v_mul_f32_e32 v133, v148, v133
	v_cndmask_b32_e64 v132, v132, v147, s[4:5]
	v_add_f32_e32 v131, 1.0, v131
	v_rcp_f32_e32 v131, v131
	v_cndmask_b32_e64 v133, v133, v148, s[4:5]
	v_mov_b32_e32 v152, v76
	v_mov_b32_e32 v150, v77
	v_mul_f32_e32 v131, v130, v131
	v_cndmask_b32_e64 v131, v131, v130, s[4:5]
	v_cvt_pk_bf16_f32 v130, v146, v132
	v_cvt_pk_bf16_f32 v131, v133, v131
	global_store_dwordx2 v[226:227], v[130:131], off offset:8
	s_cbranch_vccnz .LBB0_637
	v_add_u32_e32 v131, 0xffffe030, v202
	v_ashrrev_i32_e32 v131, 2, v131
	v_lshl_add_u32 v131, v131, 1, v131
	v_mad_i64_i32 v[132:133], s[2:3], v131, s47, 0
	v_lshl_add_u64 v[132:133], v[132:133], 2, v[208:209]
	v_lshl_add_u64 v[146:147], v[132:133], 0, s[24:25]
	s_lshl_b32 s2, s27, 2
	s_mov_b32 s3, s25
	global_load_dwordx4 v[154:157], v[132:133], off offset:16
	s_nop 0
	global_load_dwordx4 v[146:149], v[146:147], off offset:16
	v_lshl_add_u64 v[132:133], v[132:133], 0, s[2:3]
	global_load_dwordx4 v[150:153], v[132:133], off offset:16
	v_mov_b32_e32 v160, 0
	v_mov_b32_e32 v161, 0
	v_mov_b32_e32 v130, 0
	v_mov_b32_dpp v160, v74 row_ror:1 row_mask:0xf bank_mask:0xf
	v_mov_b32_dpp v161, v74 row_ror:2 row_mask:0xf bank_mask:0xf
	v_mov_b32_dpp v130, v74 row_ror:3 row_mask:0xf bank_mask:0xf
	v_cmp_lt_i32_e32 vcc, 1, v205
	s_and_saveexec_b64 s[2:3], vcc
	s_xor_b64 s[2:3], exec, s[2:3]
	s_cbranch_execz .LBB0_600
	v_cmp_gt_i32_e32 vcc, 3, v205
	s_and_saveexec_b64 s[80:81], vcc
	s_cbranch_execz .LBB0_599
	s_waitcnt vmcnt(0)
	v_mov_b32_e32 v130, v150

; #define LAS __attribute__((address_space(3)))
;     __device__ __forceinline__ void operator()(f32x4 (&acc)[2][2][4][2], const pg8::Unit& u, int wr, int wc, int fr, int fq) const {
;     ...
;                 f32x4 hal[2];
;                 hal[0] = hal[1] = (f32x4){0.f, 0.f, 0.f, 0.f};
;                 if (prompt) { const int b = 2 * ai + wr;
;                     if (b >= 1) { if (fr >= 13) {
; #pragma unroll
;                             for (int n = 0; n < 2; ++n) hal[n] = *(const LAS f32x4*)(H + ((b - 1) * 3 + (fr - 13)) * 256 + bj * 128 + cl0 + 4 * n); } }
;                     else if ((u.pm & 7) != 0) { unsigned* fl = HFLAG + (tile - 37); unsigned sp = 0;
;                         while ((unsigned)__builtin_amdgcn_readfirstlane(__hip_atomic_load(fl, __ATOMIC_RELAXED, __HIP_MEMORY_SCOPE_AGENT)) < 4u) { __builtin_amdgcn_s_sleep(2);
;                             if ((++sp & 1023u) == 0u) { if (__hip_atomic_load(tmo, __ATOMIC_RELAXED, __HIP_MEMORY_SCOPE_AGENT) != 0u) break; if (sp > (1u << 22)) { __hip_atomic_store(tmo, 1u, __ATOMIC_RELAXED, __HIP_MEMORY_SCOPE_AGENT); break; } } }
;                         if (fr >= 13) { const unsigned long long* hp = HALO + ((size_t)(tile - 37) * 3 + (fr - 13)) * 128 + (cl0 >> 1) + bj * 64;
; #pragma unroll
;                             for (int n = 0; n < 2; ++n) { const unsigned long long a2 = __hip_atomic_load(hp + 2 * n, __ATOMIC_RELAXED, __HIP_MEMORY_SCOPE_AGENT), b2 = __hip_atomic_load(hp + 2 * n + 1, __ATOMIC_RELAXED, __HIP_MEMORY_SCOPE_AGENT);
;                                 hal[n] = (f32x4){__uint_as_float((unsigned)a2), __uint_as_float((unsigned)(a2 >> 32)), __uint_as_float((unsigned)b2), __uint_as_float((unsigned)(b2 >> 32))}; } } } }
; #pragma unroll
;                 for (int n = 0; n < 2; ++n) { const int ch = ch0 + bj * 128 + 4 * n;
;                     const f32x4 w0 = *(const f32x4*)(cw + ch), w1 = *(const f32x4*)(cw + CW + ch), w2 = *(const f32x4*)(cw + 2 * CW + ch), w3 = *(const f32x4*)(cw + 3 * CW + ch), bb = *(const f32x4*)(cb + ch);
; #pragma unroll
;                     for (int m = 0; m < 4; ++m) { const int row = row0 + ai * 128 + m * 16; const f32x4 g = acc[ai][bj][m][n]; f32x4 p1, p2, p3;
;                         if (prompt) { const f32x4 gp = (m == 0) ? hal[n] : acc[ai][bj][m > 0 ? m - 1 : 0][n];
; #pragma unroll
.LBB0_639:
	v_mov_b32_e32 v170, v146
	v_mov_b32_e32 v171, v130
	v_pk_mul_f32 v[162:163], v[162:163], v[170:171]
	v_mov_b32_e32 v169, v154
	v_add_f32_e32 v130, v142, v163
	v_add_f32_e32 v130, v162, v130
	v_pk_mul_f32 v[162:163], v[164:165], v[168:169]
	v_mov_b32_e32 v161, v155
	v_add_f32_e32 v130, v163, v130
	v_add_f32_e32 v142, v162, v130
	v_mul_f32_e32 v130, 0xbfb8aa3b, v142
	v_exp_f32_e32 v130, v130
	v_mov_b32_e32 v153, v156
	v_mov_b32_e32 v151, v157
	s_and_b64 vcc, exec, s[20:21]
	v_add_f32_e32 v130, 1.0, v130
	v_rcp_f32_e32 v146, v130
	v_mov_b32_e32 v130, v147
	v_pk_mul_f32 v[130:131], v[138:139], v[130:131]
	v_mov_b32_e32 v147, 0
	v_add_f32_e32 v131, v143, v131
	v_add_f32_e32 v138, v130, v131
	v_pk_mul_f32 v[130:131], v[134:135], v[160:161]
	s_nop 0
	v_add_f32_e32 v131, v131, v138
	v_add_f32_e32 v134, v130, v131
	v_mul_f32_e32 v130, 0xbfb8aa3b, v134
	v_exp_f32_e32 v130, v130
	v_mul_f32_e32 v131, v142, v146
	v_cndmask_b32_e64 v135, v131, v142, s[4:5]
	v_mov_b32_e32 v131, v132
	v_add_f32_e32 v130, 1.0, v130
	v_rcp_f32_e32 v138, v130
	v_mov_b32_e32 v130, v148
	v_pk_mul_f32 v[130:131], v[158:159], v[130:131]
	v_mov_b32_e32 v146, 0
	v_add_f32_e32 v131, v144, v131
	v_add_f32_e32 v132, v130, v131
	v_pk_mul_f32 v[130:131], v[166:167], v[152:153]
	v_mov_b32_e32 v148, 0
	v_add_f32_e32 v131, v131, v132
	v_add_f32_e32 v139, v130, v131
	v_mul_f32_e32 v130, 0xbfb8aa3b, v139
	v_mov_b32_e32 v132, v149
	v_exp_f32_e32 v142, v130
	v_pk_mul_f32 v[130:131], v[140:141], v[132:133]
	v_mov_b32_e32 v149, 0
	v_add_f32_e32 v131, v145, v131
	v_add_f32_e32 v132, v130, v131
	v_pk_mul_f32 v[130:131], v[136:137], v[150:151]
	v_add_f32_e32 v133, 1.0, v142
	v_add_f32_e32 v131, v131, v132
	v_add_f32_e32 v130, v130, v131
	v_mul_f32_e32 v131, 0xbfb8aa3b, v130
	v_exp_f32_e32 v131, v131
	v_rcp_f32_e32 v133, v133
	v_mul_f32_e32 v132, v134, v138
	v_cndmask_b32_e64 v132, v132, v134, s[4:5]
	v_add_f32_e32 v131, 1.0, v131
	v_rcp_f32_e32 v131, v131
	v_mul_f32_e32 v133, v139, v133
	v_cndmask_b32_e64 v133, v133, v139, s[4:5]
	v_mul_f32_e32 v131, v130, v131
	v_cndmask_b32_e64 v131, v131, v130, s[4:5]
	v_cvt_pk_bf16_f32 v130, v135, v132
	v_cvt_pk_bf16_f32 v131, v133, v131
	global_store_dwordx2 v[228:229], v[130:131], off offset:8
	v_mov_b32_e32 v130, 0
	v_mov_b32_e32 v131, 0
	v_mov_b32_e32 v132, 0
	v_mov_b32_e32 v133, 0
	s_cbranch_vccnz .LBB0_663
	v_readlane_b32 s20, v255, 3
	v_readlane_b32 s21, v255, 4
	s_mov_b64 s[2:3], -1
	s_and_b64 vcc, exec, s[20:21]
	s_cbranch_vccz .LBB0_644
	v_mov_b32_e32 v149, 0
	v_mov_b32_e32 v148, 0
	v_mov_b32_e32 v147, 0
	v_mov_b32_e32 v146, 0
	v_mov_b32_e32 v133, 0
	v_mov_b32_e32 v132, 0
	v_mov_b32_e32 v131, 0
	v_mov_b32_e32 v130, 0
	s_and_saveexec_b64 s[2:3], s[6:7]
	s_cbranch_execz .LBB0_643
	v_readlane_b32 s20, v255, 19
	v_lshlrev_b32_e32 v131, 2, v206
	s_nop 0
	v_add_u32_e32 v130, s20, v236
	s_movk_i32 s20, 0xc200
	v_add3_u32 v130, v130, v131, s20
	ds_read_b128 v[146:149], v130
	ds_read_b128 v[130:133], v130 offset:16

;     __device__ __forceinline__ void operator()(f32x4 (&acc)[2][2][4][2], const pg8::Unit& u, int wr, int wc, int fr, int fq) const {
;     ...
;                     else if ((u.pm & 7) != 0) { unsigned* fl = HFLAG + (tile - 37); unsigned sp = 0;
;                         while ((unsigned)__builtin_amdgcn_readfirstlane(__hip_atomic_load(fl, __ATOMIC_RELAXED, __HIP_MEMORY_SCOPE_AGENT)) < 4u) { __builtin_amdgcn_s_sleep(2);
;                             if ((++sp & 1023u) == 0u) { if (__hip_atomic_load(tmo, __ATOMIC_RELAXED, __HIP_MEMORY_SCOPE_AGENT) != 0u) break; if (sp > (1u << 22)) { __hip_atomic_store(tmo, 1u, __ATOMIC_RELAXED, __HIP_MEMORY_SCOPE_AGENT); break; } } }
.LBB0_657:
	s_or_b64 exec, exec, s[2:3]
	s_xor_b64 s[0:1], s[20:21], -1
	s_and_saveexec_b64 s[2:3], s[0:1]
	s_xor_b64 s[0:1], exec, s[2:3]
	s_cbranch_execz .LBB0_659
	v_mov_b64_e32 v[130:131], s[74:75]
	v_mov_b32_e32 v132, 1
	global_store_dword v[130:131], v132, off offset:64 sc1

; __device__ __forceinline__ unsigned cvt_pk_bf16(float lo, float hi) { unsigned r; asm("v_cvt_pk_bf16_f32 %0, %1, %2" : "=v"(r) : "v"(lo), "v"(hi)); return r; }
; __device__ __forceinline__ float siluf_(float x) { return x * sigmoidf_(x); }
; __device__ __forceinline__ float dpp_ror1(float v) { return __builtin_bit_cast(float, __builtin_amdgcn_update_dpp(0, __builtin_bit_cast(int, v), 0x121, 0xf, 0xf, false)); }
;     __device__ __forceinline__ void operator()(f32x4 (&acc)[2][2][4][2], const pg8::Unit& u, int wr, int wc, int fr, int fq) const {
;     ...
;                 for (int n = 0; n < 2; ++n) { const int ch = ch0 + bj * 128 + 4 * n;
;                     const f32x4 w0 = *(const f32x4*)(cw + ch), w1 = *(const f32x4*)(cw + CW + ch), w2 = *(const f32x4*)(cw + 2 * CW + ch), w3 = *(const f32x4*)(cw + 3 * CW + ch), bb = *(const f32x4*)(cb + ch);
; #pragma unroll
;                     for (int m = 0; m < 4; ++m) { const int row = row0 + ai * 128 + m * 16; const f32x4 g = acc[ai][bj][m][n]; f32x4 p1, p2, p3;
;                         if (prompt) { const f32x4 gp = (m == 0) ? hal[n] : acc[ai][bj][m > 0 ? m - 1 : 0][n];
; #pragma unroll
;                             for (int j = 0; j < 4; ++j) { p1[j] = dpp_ror1(fr == 15 ? gp[j] : g[j]); p2[j] = dpp_ror2(fr >= 14 ? gp[j] : g[j]); p3[j] = dpp_ror3(fr >= 13 ? gp[j] : g[j]); } }
;                         else { const int t = fr & 3; const float* sp = stp + (size_t)((row - MP) >> 2) * 3 * CW + ch;
;                             const f32x4 b0 = *(const f32x4*)sp, b1 = *(const f32x4*)(sp + CW), b2 = *(const f32x4*)(sp + 2 * CW);
; #pragma unroll
;                             for (int j = 0; j < 4; ++j) { const float r1 = dpp_ror1(g[j]), r2 = dpp_ror2(g[j]), r3 = dpp_ror3(g[j]);
;                                 p1[j] = t >= 1 ? r1 : b2[j]; p2[j] = t >= 2 ? r2 : (t == 1 ? b2[j] : b1[j]); p3[j] = t >= 3 ? r3 : (t == 2 ? b2[j] : (t == 1 ? b1[j] : b0[j])); } }
;                         float o[4];
; #pragma unroll
;                         for (int j = 0; j < 4; ++j) { const float y = bb[j] + w0[j] * p3[j] + w1[j] * p2[j] + w2[j] * p1[j] + w3[j] * g[j]; o[j] = is_rg ? y : siluf_(y); }
;                         u32x2 w; w.x = cvt_pk_bf16(o[0], o[1]); w.y = cvt_pk_bf16(o[2], o[3]);
;                         *(u32x2*)(dst + (size_t)row * ld + bj * 128 + 4 * n) = w; }
.LBB0_707:
	s_waitcnt vmcnt(0)
	v_mov_b32_e32 v166, v154
	v_mov_b32_e32 v167, v138
	s_waitcnt lgkmcnt(0)
	v_mov_b32_e32 v146, v162
	v_mov_b32_e32 v147, v158
	v_pk_mul_f32 v[146:147], v[166:167], v[146:147]
	v_mov_b32_e32 v168, v150
	v_add_f32_e32 v138, v142, v147
	v_mov_b32_e32 v169, v134
	v_mov_b32_e32 v237, v170
	v_add_f32_e32 v138, v146, v138
	v_pk_mul_f32 v[146:147], v[168:169], v[236:237]
	v_mov_b32_e32 v158, v163
	v_add_f32_e32 v134, v147, v138
	v_add_f32_e32 v148, v146, v134
	v_mul_f32_e32 v134, 0xbfb8aa3b, v148
	v_exp_f32_e32 v134, v134
	v_mov_b32_e32 v138, v155
	v_pk_mul_f32 v[146:147], v[138:139], v[158:159]
	v_mov_b32_e32 v235, v171
	v_add_f32_e32 v134, 1.0, v134
	v_rcp_f32_e32 v149, v134
	v_add_f32_e32 v134, v143, v147
	v_add_f32_e32 v150, v146, v134
	v_mov_b32_e32 v134, v151
	v_pk_mul_f32 v[146:147], v[134:135], v[234:235]
	v_mov_b32_e32 v162, v156
	v_add_f32_e32 v147, v147, v150
	v_add_f32_e32 v150, v146, v147
	v_mul_f32_e32 v146, 0xbfb8aa3b, v150
	v_exp_f32_e32 v146, v146
	v_mul_f32_e32 v147, v148, v149
	v_cndmask_b32_e64 v148, v147, v148, s[4:5]
	v_mov_b32_e32 v163, v140
	v_add_f32_e32 v146, 1.0, v146
	v_rcp_f32_e32 v149, v146
	v_mov_b32_e32 v146, v164
	v_mov_b32_e32 v147, v160
	v_pk_mul_f32 v[146:147], v[162:163], v[146:147]
	v_mov_b32_e32 v170, v152
	v_add_f32_e32 v140, v144, v147
	v_mov_b32_e32 v171, v136
	v_mov_b32_e32 v233, v172
	v_add_f32_e32 v140, v146, v140
	v_pk_mul_f32 v[146:147], v[170:171], v[232:233]
	v_mov_b32_e32 v160, v165
	v_add_f32_e32 v136, v147, v140
	v_add_f32_e32 v151, v146, v136
	v_mov_b32_e32 v140, v157
	v_mul_f32_e32 v136, 0xbfb8aa3b, v151
	v_pk_mul_f32 v[146:147], v[140:141], v[160:161]
	v_exp_f32_e32 v152, v136
	v_add_f32_e32 v136, v145, v147
	v_add_f32_e32 v154, v146, v136
	v_mov_b32_e32 v136, v153
	v_mov_b32_e32 v231, v173
	v_pk_mul_f32 v[146:147], v[136:137], v[230:231]
	v_add_f32_e32 v152, 1.0, v152
	v_add_f32_e32 v147, v147, v154
	v_add_f32_e32 v146, v146, v147
	v_mul_f32_e32 v147, 0xbfb8aa3b, v146
	v_exp_f32_e32 v147, v147
	v_rcp_f32_e32 v152, v152
	v_mul_f32_e32 v149, v150, v149
	v_cndmask_b32_e64 v149, v149, v150, s[4:5]
	v_add_f32_e32 v147, 1.0, v147
	v_rcp_f32_e32 v147, v147
	v_mul_f32_e32 v150, v151, v152
	v_cndmask_b32_e64 v150, v150, v151, s[4:5]
	s_mov_b64 s[0:1], -1
	v_mul_f32_e32 v147, v146, v147
	v_cndmask_b32_e64 v147, v147, v146, s[4:5]
	v_cvt_pk_bf16_f32 v146, v148, v149
	v_cvt_pk_bf16_f32 v147, v150, v147
	s_and_b64 vcc, exec, s[18:19]
	v_mov_b32_e32 v172, v102
	v_mov_b32_e32 v164, v103
	v_mov_b32_e32 v156, v104
	v_mov_b32_e32 v154, v105
	global_store_dwordx2 v[222:223], v[146:147], off offset:256
	s_cbranch_vccnz .LBB0_749
	v_add_u32_e32 v147, 0xffffe010, v202
	v_ashrrev_i32_e32 v147, 2, v147
	v_lshl_add_u32 v147, v147, 1, v147
	v_mad_i64_i32 v[148:149], s[0:1], v147, s47, 0
	v_lshl_add_u64 v[148:149], v[148:149], 2, v[208:209]
	v_lshl_add_u64 v[150:151], v[148:149], 0, s[24:25]
	s_lshl_b32 s0, s27, 2
	s_mov_b32 s1, s25
	global_load_dwordx4 v[158:161], v[148:149], off offset:512
	s_nop 0
	global_load_dwordx4 v[150:153], v[150:151], off offset:512
	v_lshl_add_u64 v[148:149], v[148:149], 0, s[0:1]
	global_load_dwordx4 v[154:157], v[148:149], off offset:512
	v_mov_b32_e32 v164, 0
	v_mov_b32_e32 v165, 0
	v_mov_b32_e32 v146, 0
	v_mov_b32_dpp v164, v102 row_ror:1 row_mask:0xf bank_mask:0xf
	v_mov_b32_dpp v165, v102 row_ror:2 row_mask:0xf bank_mask:0xf
	v_mov_b32_dpp v146, v102 row_ror:3 row_mask:0xf bank_mask:0xf
	v_cmp_lt_i32_e32 vcc, 1, v205
	s_and_saveexec_b64 s[0:1], vcc
	s_xor_b64 s[0:1], exec, s[0:1]
	s_cbranch_execz .LBB0_712
	v_cmp_gt_i32_e32 vcc, 3, v205
	s_and_saveexec_b64 s[2:3], vcc
	s_cbranch_execz .LBB0_711
	s_waitcnt vmcnt(0)
	v_mov_b32_e32 v146, v154

; __device__ __forceinline__ unsigned cvt_pk_bf16(float lo, float hi) { unsigned r; asm("v_cvt_pk_bf16_f32 %0, %1, %2" : "=v"(r) : "v"(lo), "v"(hi)); return r; }
; __device__ __forceinline__ float siluf_(float x) { return x * sigmoidf_(x); }
; __device__ __forceinline__ float dpp_ror1(float v) { return __builtin_bit_cast(float, __builtin_amdgcn_update_dpp(0, __builtin_bit_cast(int, v), 0x121, 0xf, 0xf, false)); }
;     __device__ __forceinline__ void operator()(f32x4 (&acc)[2][2][4][2], const pg8::Unit& u, int wr, int wc, int fr, int fq) const {
;     ...
;                 for (int n = 0; n < 2; ++n) { const int ch = ch0 + bj * 128 + 4 * n;
;                     const f32x4 w0 = *(const f32x4*)(cw + ch), w1 = *(const f32x4*)(cw + CW + ch), w2 = *(const f32x4*)(cw + 2 * CW + ch), w3 = *(const f32x4*)(cw + 3 * CW + ch), bb = *(const f32x4*)(cb + ch);
; #pragma unroll
;                     for (int m = 0; m < 4; ++m) { const int row = row0 + ai * 128 + m * 16; const f32x4 g = acc[ai][bj][m][n]; f32x4 p1, p2, p3;
;                         if (prompt) { const f32x4 gp = (m == 0) ? hal[n] : acc[ai][bj][m > 0 ? m - 1 : 0][n];
; #pragma unroll
;                             for (int j = 0; j < 4; ++j) { p1[j] = dpp_ror1(fr == 15 ? gp[j] : g[j]); p2[j] = dpp_ror2(fr >= 14 ? gp[j] : g[j]); p3[j] = dpp_ror3(fr >= 13 ? gp[j] : g[j]); } }
;                         else { const int t = fr & 3; const float* sp = stp + (size_t)((row - MP) >> 2) * 3 * CW + ch;
;                             const f32x4 b0 = *(const f32x4*)sp, b1 = *(const f32x4*)(sp + CW), b2 = *(const f32x4*)(sp + 2 * CW);
; #pragma unroll
;                             for (int j = 0; j < 4; ++j) { const float r1 = dpp_ror1(g[j]), r2 = dpp_ror2(g[j]), r3 = dpp_ror3(g[j]);
;                                 p1[j] = t >= 1 ? r1 : b2[j]; p2[j] = t >= 2 ? r2 : (t == 1 ? b2[j] : b1[j]); p3[j] = t >= 3 ? r3 : (t == 2 ? b2[j] : (t == 1 ? b1[j] : b0[j])); } }
;                         float o[4];
; #pragma unroll
;                         for (int j = 0; j < 4; ++j) { const float y = bb[j] + w0[j] * p3[j] + w1[j] * p2[j] + w2[j] * p1[j] + w3[j] * g[j]; o[j] = is_rg ? y : siluf_(y); }
;                         u32x2 w; w.x = cvt_pk_bf16(o[0], o[1]); w.y = cvt_pk_bf16(o[2], o[3]);
;                         *(u32x2*)(dst + (size_t)row * ld + bj * 128 + 4 * n) = w; }
.LBB0_751:
	v_mov_b32_e32 v230, v150
	v_mov_b32_e32 v231, v146
	v_pk_mul_f32 v[230:231], v[166:167], v[230:231]
	v_mov_b32_e32 v173, v158
	v_add_f32_e32 v146, v142, v231
	v_add_f32_e32 v146, v230, v146
	v_pk_mul_f32 v[172:173], v[168:169], v[172:173]
	v_mov_b32_e32 v165, v159
	v_add_f32_e32 v146, v173, v146
	v_add_f32_e32 v150, v172, v146
	v_mul_f32_e32 v146, 0xbfb8aa3b, v150
	v_exp_f32_e32 v146, v146
	v_mov_b32_e32 v157, v160
	s_mov_b64 s[0:1], -1
	s_and_b64 vcc, exec, s[18:19]
	v_add_f32_e32 v146, 1.0, v146
	v_rcp_f32_e32 v155, v146
	v_mov_b32_e32 v146, v151
	v_pk_mul_f32 v[146:147], v[138:139], v[146:147]
	v_mov_b32_e32 v172, v86
	v_add_f32_e32 v147, v143, v147
	v_add_f32_e32 v151, v146, v147
	v_pk_mul_f32 v[146:147], v[134:135], v[164:165]
	v_mov_b32_e32 v164, v87
	v_add_f32_e32 v147, v147, v151
	v_add_f32_e32 v151, v146, v147
	v_mul_f32_e32 v146, 0xbfb8aa3b, v151
	v_exp_f32_e32 v146, v146
	v_mul_f32_e32 v147, v150, v155
	v_cndmask_b32_e64 v150, v147, v150, s[4:5]
	v_mov_b32_e32 v147, v148
	v_add_f32_e32 v146, 1.0, v146
	v_rcp_f32_e32 v158, v146
	v_mov_b32_e32 v146, v152
	v_pk_mul_f32 v[146:147], v[162:163], v[146:147]
	v_mov_b32_e32 v155, v161
	v_add_f32_e32 v147, v144, v147
	v_add_f32_e32 v148, v146, v147
	v_pk_mul_f32 v[146:147], v[170:171], v[156:157]
	s_nop 0
	v_add_f32_e32 v147, v147, v148
	v_add_f32_e32 v152, v146, v147
	v_mul_f32_e32 v146, 0xbfb8aa3b, v152
	v_mov_b32_e32 v148, v153
	v_exp_f32_e32 v156, v146
	v_pk_mul_f32 v[146:147], v[140:141], v[148:149]
	v_add_f32_e32 v149, 1.0, v156
	v_add_f32_e32 v147, v145, v147
	v_add_f32_e32 v148, v146, v147
	v_pk_mul_f32 v[146:147], v[136:137], v[154:155]
	v_rcp_f32_e32 v149, v149
	v_add_f32_e32 v147, v147, v148
	v_add_f32_e32 v146, v146, v147
	v_mul_f32_e32 v147, 0xbfb8aa3b, v146
	v_exp_f32_e32 v147, v147
	v_mul_f32_e32 v148, v151, v158
	v_mul_f32_e32 v149, v152, v149
	v_cndmask_b32_e64 v148, v148, v151, s[4:5]
	v_add_f32_e32 v147, 1.0, v147
	v_rcp_f32_e32 v147, v147
	v_cndmask_b32_e64 v149, v149, v152, s[4:5]
	v_mov_b32_e32 v156, v88
	v_mov_b32_e32 v154, v89
	v_mul_f32_e32 v147, v146, v147
	v_cndmask_b32_e64 v147, v147, v146, s[4:5]
	v_cvt_pk_bf16_f32 v146, v150, v148
	v_cvt_pk_bf16_f32 v147, v149, v147
	global_store_dwordx2 v[224:225], v[146:147], off offset:256
	s_cbranch_vccnz .LBB0_793
	v_add_u32_e32 v147, 0xffffe020, v202
	v_ashrrev_i32_e32 v147, 2, v147
	v_lshl_add_u32 v147, v147, 1, v147
	v_mad_i64_i32 v[148:149], s[0:1], v147, s47, 0
	v_lshl_add_u64 v[148:149], v[148:149], 2, v[208:209]
	v_lshl_add_u64 v[150:151], v[148:149], 0, s[24:25]
	s_lshl_b32 s0, s27, 2
	s_mov_b32 s1, s25
	global_load_dwordx4 v[158:161], v[148:149], off offset:512
	s_nop 0
	global_load_dwordx4 v[150:153], v[150:151], off offset:512
	v_lshl_add_u64 v[148:149], v[148:149], 0, s[0:1]
	global_load_dwordx4 v[154:157], v[148:149], off offset:512
	v_mov_b32_e32 v164, 0
	v_mov_b32_e32 v165, 0
	v_mov_b32_e32 v146, 0
	v_mov_b32_dpp v164, v86 row_ror:1 row_mask:0xf bank_mask:0xf
	v_mov_b32_dpp v165, v86 row_ror:2 row_mask:0xf bank_mask:0xf
	v_mov_b32_dpp v146, v86 row_ror:3 row_mask:0xf bank_mask:0xf
	v_cmp_lt_i32_e32 vcc, 1, v205
	s_and_saveexec_b64 s[0:1], vcc
	s_xor_b64 s[0:1], exec, s[0:1]
	s_cbranch_execz .LBB0_756
	v_cmp_gt_i32_e32 vcc, 3, v205
	s_and_saveexec_b64 s[2:3], vcc
	s_cbranch_execz .LBB0_755
	s_waitcnt vmcnt(0)
	v_mov_b32_e32 v146, v154

; __device__ __forceinline__ unsigned cvt_pk_bf16(float lo, float hi) { unsigned r; asm("v_cvt_pk_bf16_f32 %0, %1, %2" : "=v"(r) : "v"(lo), "v"(hi)); return r; }
; __device__ __forceinline__ float siluf_(float x) { return x * sigmoidf_(x); }
; __device__ __forceinline__ float dpp_ror1(float v) { return __builtin_bit_cast(float, __builtin_amdgcn_update_dpp(0, __builtin_bit_cast(int, v), 0x121, 0xf, 0xf, false)); }
;     __device__ __forceinline__ void operator()(f32x4 (&acc)[2][2][4][2], const pg8::Unit& u, int wr, int wc, int fr, int fq) const {
;     ...
;                 for (int n = 0; n < 2; ++n) { const int ch = ch0 + bj * 128 + 4 * n;
;                     const f32x4 w0 = *(const f32x4*)(cw + ch), w1 = *(const f32x4*)(cw + CW + ch), w2 = *(const f32x4*)(cw + 2 * CW + ch), w3 = *(const f32x4*)(cw + 3 * CW + ch), bb = *(const f32x4*)(cb + ch);
; #pragma unroll
;                     for (int m = 0; m < 4; ++m) { const int row = row0 + ai * 128 + m * 16; const f32x4 g = acc[ai][bj][m][n]; f32x4 p1, p2, p3;
;                         if (prompt) { const f32x4 gp = (m == 0) ? hal[n] : acc[ai][bj][m > 0 ? m - 1 : 0][n];
; #pragma unroll
;                             for (int j = 0; j < 4; ++j) { p1[j] = dpp_ror1(fr == 15 ? gp[j] : g[j]); p2[j] = dpp_ror2(fr >= 14 ? gp[j] : g[j]); p3[j] = dpp_ror3(fr >= 13 ? gp[j] : g[j]); } }
;                         else { const int t = fr & 3; const float* sp = stp + (size_t)((row - MP) >> 2) * 3 * CW + ch;
;                             const f32x4 b0 = *(const f32x4*)sp, b1 = *(const f32x4*)(sp + CW), b2 = *(const f32x4*)(sp + 2 * CW);
; #pragma unroll
;                             for (int j = 0; j < 4; ++j) { const float r1 = dpp_ror1(g[j]), r2 = dpp_ror2(g[j]), r3 = dpp_ror3(g[j]);
;                                 p1[j] = t >= 1 ? r1 : b2[j]; p2[j] = t >= 2 ? r2 : (t == 1 ? b2[j] : b1[j]); p3[j] = t >= 3 ? r3 : (t == 2 ? b2[j] : (t == 1 ? b1[j] : b0[j])); } }
;                         float o[4];
; #pragma unroll
;                         for (int j = 0; j < 4; ++j) { const float y = bb[j] + w0[j] * p3[j] + w1[j] * p2[j] + w2[j] * p1[j] + w3[j] * g[j]; o[j] = is_rg ? y : siluf_(y); }
;                         u32x2 w; w.x = cvt_pk_bf16(o[0], o[1]); w.y = cvt_pk_bf16(o[2], o[3]);
;                         *(u32x2*)(dst + (size_t)row * ld + bj * 128 + 4 * n) = w; }
.LBB0_795:
	v_mov_b32_e32 v230, v150
	v_mov_b32_e32 v231, v146
	v_pk_mul_f32 v[230:231], v[166:167], v[230:231]
	v_mov_b32_e32 v173, v158
	v_add_f32_e32 v146, v142, v231
	v_add_f32_e32 v146, v230, v146
	v_pk_mul_f32 v[172:173], v[168:169], v[172:173]
	v_mov_b32_e32 v165, v159
	v_add_f32_e32 v146, v173, v146
	v_add_f32_e32 v150, v172, v146
	v_mul_f32_e32 v146, 0xbfb8aa3b, v150
	v_exp_f32_e32 v146, v146
	v_mov_b32_e32 v157, v160
	s_mov_b64 s[0:1], -1
	s_and_b64 vcc, exec, s[18:19]
	v_add_f32_e32 v146, 1.0, v146
	v_rcp_f32_e32 v155, v146
	v_mov_b32_e32 v146, v151
	v_pk_mul_f32 v[146:147], v[138:139], v[146:147]
	v_mov_b32_e32 v172, v70
	v_add_f32_e32 v147, v143, v147
	v_add_f32_e32 v151, v146, v147
	v_pk_mul_f32 v[146:147], v[134:135], v[164:165]
	v_mov_b32_e32 v164, v71
	v_add_f32_e32 v147, v147, v151
	v_add_f32_e32 v151, v146, v147
	v_mul_f32_e32 v146, 0xbfb8aa3b, v151
	v_exp_f32_e32 v146, v146
	v_mul_f32_e32 v147, v150, v155
	v_cndmask_b32_e64 v150, v147, v150, s[4:5]
	v_mov_b32_e32 v147, v148
	v_add_f32_e32 v146, 1.0, v146
	v_rcp_f32_e32 v158, v146
	v_mov_b32_e32 v146, v152
	v_pk_mul_f32 v[146:147], v[162:163], v[146:147]
	v_mov_b32_e32 v155, v161
	v_add_f32_e32 v147, v144, v147
	v_add_f32_e32 v148, v146, v147
	v_pk_mul_f32 v[146:147], v[170:171], v[156:157]
	s_nop 0
	v_add_f32_e32 v147, v147, v148
	v_add_f32_e32 v152, v146, v147
	v_mul_f32_e32 v146, 0xbfb8aa3b, v152
	v_mov_b32_e32 v148, v153
	v_exp_f32_e32 v156, v146
	v_pk_mul_f32 v[146:147], v[140:141], v[148:149]
	v_add_f32_e32 v149, 1.0, v156
	v_add_f32_e32 v147, v145, v147
	v_add_f32_e32 v148, v146, v147
	v_pk_mul_f32 v[146:147], v[136:137], v[154:155]
	v_rcp_f32_e32 v149, v149
	v_add_f32_e32 v147, v147, v148
	v_add_f32_e32 v146, v146, v147
	v_mul_f32_e32 v147, 0xbfb8aa3b, v146
	v_exp_f32_e32 v147, v147
	v_mul_f32_e32 v148, v151, v158
	v_mul_f32_e32 v149, v152, v149
	v_cndmask_b32_e64 v148, v148, v151, s[4:5]
	v_add_f32_e32 v147, 1.0, v147
	v_rcp_f32_e32 v147, v147
	v_cndmask_b32_e64 v149, v149, v152, s[4:5]
	v_mov_b32_e32 v156, v72
	v_mov_b32_e32 v154, v73
	v_mul_f32_e32 v147, v146, v147
	v_cndmask_b32_e64 v147, v147, v146, s[4:5]
	v_cvt_pk_bf16_f32 v146, v150, v148
	v_cvt_pk_bf16_f32 v147, v149, v147
	global_store_dwordx2 v[226:227], v[146:147], off offset:256
	s_cbranch_vccnz .LBB0_837
	v_add_u32_e32 v147, 0xffffe030, v202
	v_ashrrev_i32_e32 v147, 2, v147
	v_lshl_add_u32 v147, v147, 1, v147
	v_mad_i64_i32 v[148:149], s[0:1], v147, s47, 0
	v_lshl_add_u64 v[148:149], v[148:149], 2, v[208:209]
	v_lshl_add_u64 v[150:151], v[148:149], 0, s[24:25]
	s_lshl_b32 s0, s27, 2
	s_mov_b32 s1, s25
	global_load_dwordx4 v[158:161], v[148:149], off offset:512
	s_nop 0
	global_load_dwordx4 v[150:153], v[150:151], off offset:512
	v_lshl_add_u64 v[148:149], v[148:149], 0, s[0:1]
	global_load_dwordx4 v[154:157], v[148:149], off offset:512
	v_mov_b32_e32 v164, 0
	v_mov_b32_e32 v165, 0
	v_mov_b32_e32 v146, 0
	v_mov_b32_dpp v164, v70 row_ror:1 row_mask:0xf bank_mask:0xf
	v_mov_b32_dpp v165, v70 row_ror:2 row_mask:0xf bank_mask:0xf
	v_mov_b32_dpp v146, v70 row_ror:3 row_mask:0xf bank_mask:0xf
	v_cmp_lt_i32_e32 vcc, 1, v205
	s_and_saveexec_b64 s[0:1], vcc
	s_xor_b64 s[0:1], exec, s[0:1]
	s_cbranch_execz .LBB0_800
	v_cmp_gt_i32_e32 vcc, 3, v205
	s_and_saveexec_b64 s[2:3], vcc
	s_cbranch_execz .LBB0_799
	s_waitcnt vmcnt(0)
	v_mov_b32_e32 v146, v154

; __device__ __forceinline__ unsigned cvt_pk_bf16(float lo, float hi) { unsigned r; asm("v_cvt_pk_bf16_f32 %0, %1, %2" : "=v"(r) : "v"(lo), "v"(hi)); return r; }
; __device__ __forceinline__ float siluf_(float x) { return x * sigmoidf_(x); }
; __device__ __forceinline__ float dpp_ror1(float v) { return __builtin_bit_cast(float, __builtin_amdgcn_update_dpp(0, __builtin_bit_cast(int, v), 0x121, 0xf, 0xf, false)); }
;     __device__ __forceinline__ void operator()(f32x4 (&acc)[2][2][4][2], const pg8::Unit& u, int wr, int wc, int fr, int fq) const {
;     ...
;                 for (int n = 0; n < 2; ++n) { const int ch = ch0 + bj * 128 + 4 * n;
;                     const f32x4 w0 = *(const f32x4*)(cw + ch), w1 = *(const f32x4*)(cw + CW + ch), w2 = *(const f32x4*)(cw + 2 * CW + ch), w3 = *(const f32x4*)(cw + 3 * CW + ch), bb = *(const f32x4*)(cb + ch);
; #pragma unroll
;                     for (int m = 0; m < 4; ++m) { const int row = row0 + ai * 128 + m * 16; const f32x4 g = acc[ai][bj][m][n]; f32x4 p1, p2, p3;
;                         if (prompt) { const f32x4 gp = (m == 0) ? hal[n] : acc[ai][bj][m > 0 ? m - 1 : 0][n];
; #pragma unroll
;                             for (int j = 0; j < 4; ++j) { p1[j] = dpp_ror1(fr == 15 ? gp[j] : g[j]); p2[j] = dpp_ror2(fr >= 14 ? gp[j] : g[j]); p3[j] = dpp_ror3(fr >= 13 ? gp[j] : g[j]); } }
;                         else { const int t = fr & 3; const float* sp = stp + (size_t)((row - MP) >> 2) * 3 * CW + ch;
;                             const f32x4 b0 = *(const f32x4*)sp, b1 = *(const f32x4*)(sp + CW), b2 = *(const f32x4*)(sp + 2 * CW);
; #pragma unroll
;                             for (int j = 0; j < 4; ++j) { const float r1 = dpp_ror1(g[j]), r2 = dpp_ror2(g[j]), r3 = dpp_ror3(g[j]);
;                                 p1[j] = t >= 1 ? r1 : b2[j]; p2[j] = t >= 2 ? r2 : (t == 1 ? b2[j] : b1[j]); p3[j] = t >= 3 ? r3 : (t == 2 ? b2[j] : (t == 1 ? b1[j] : b0[j])); } }
;                         float o[4];
; #pragma unroll
;                         for (int j = 0; j < 4; ++j) { const float y = bb[j] + w0[j] * p3[j] + w1[j] * p2[j] + w2[j] * p1[j] + w3[j] * g[j]; o[j] = is_rg ? y : siluf_(y); }
;                         u32x2 w; w.x = cvt_pk_bf16(o[0], o[1]); w.y = cvt_pk_bf16(o[2], o[3]);
;                         *(u32x2*)(dst + (size_t)row * ld + bj * 128 + 4 * n) = w; }
.LBB0_839:
	v_mov_b32_e32 v230, v150
	v_mov_b32_e32 v231, v146
	v_pk_mul_f32 v[166:167], v[166:167], v[230:231]
	v_mov_b32_e32 v173, v158
	v_add_f32_e32 v142, v142, v167
	v_add_f32_e32 v142, v166, v142
	v_pk_mul_f32 v[166:167], v[168:169], v[172:173]
	v_mov_b32_e32 v165, v159
	v_add_f32_e32 v142, v167, v142
	v_add_f32_e32 v142, v166, v142
	v_mul_f32_e32 v146, 0xbfb8aa3b, v142
	v_exp_f32_e32 v146, v146
	v_pk_mul_f32 v[134:135], v[134:135], v[164:165]
	v_mov_b32_e32 v157, v160
	v_mov_b32_e32 v155, v161
	v_add_f32_e32 v146, 1.0, v146
	v_rcp_f32_e32 v150, v146
	v_mov_b32_e32 v146, v151
	v_pk_mul_f32 v[138:139], v[138:139], v[146:147]
	s_mov_b64 s[0:1], -1
	v_add_f32_e32 v139, v143, v139
	v_add_f32_e32 v138, v138, v139
	v_add_f32_e32 v135, v135, v138
	v_add_f32_e32 v138, v134, v135
	v_mul_f32_e32 v134, 0xbfb8aa3b, v138
	v_exp_f32_e32 v134, v134
	v_mul_f32_e32 v135, v142, v150
	v_cndmask_b32_e64 v139, v135, v142, s[4:5]
	v_mov_b32_e32 v135, v148
	v_add_f32_e32 v134, 1.0, v134
	v_rcp_f32_e32 v142, v134
	v_mov_b32_e32 v134, v152
	v_pk_mul_f32 v[134:135], v[162:163], v[134:135]
	v_mov_b32_e32 v148, v153
	v_add_f32_e32 v135, v144, v135
	v_add_f32_e32 v143, v134, v135
	v_pk_mul_f32 v[134:135], v[170:171], v[156:157]
	s_and_b64 vcc, exec, s[18:19]
	v_add_f32_e32 v135, v135, v143
	v_add_f32_e32 v143, v134, v135
	v_mul_f32_e32 v134, 0xbfb8aa3b, v143
	v_exp_f32_e32 v144, v134
	v_pk_mul_f32 v[134:135], v[140:141], v[148:149]
	v_mov_b32_e32 v232, v114
	v_add_f32_e32 v135, v145, v135
	v_add_f32_e32 v140, v134, v135
	v_pk_mul_f32 v[134:135], v[136:137], v[154:155]
	v_add_f32_e32 v137, 1.0, v144
	v_add_f32_e32 v135, v135, v140
	v_add_f32_e32 v134, v134, v135
	v_mul_f32_e32 v135, 0xbfb8aa3b, v134
	v_exp_f32_e32 v135, v135
	v_rcp_f32_e32 v137, v137
	v_mul_f32_e32 v136, v138, v142
	v_cndmask_b32_e64 v136, v136, v138, s[4:5]
	v_add_f32_e32 v135, 1.0, v135
	v_rcp_f32_e32 v135, v135
	v_mul_f32_e32 v137, v143, v137
	v_cndmask_b32_e64 v137, v137, v143, s[4:5]
	v_mov_b32_e32 v230, v115
	v_mul_f32_e32 v135, v134, v135
	v_cndmask_b32_e64 v135, v135, v134, s[4:5]
	v_cvt_pk_bf16_f32 v134, v139, v136
	v_cvt_pk_bf16_f32 v135, v137, v135
	global_store_dwordx2 v[228:229], v[134:135], off offset:256
	global_load_dwordx4 v[138:141], v[210:211], off offset:528
	global_load_dwordx4 v[150:153], v[212:213], off offset:528
	global_load_dwordx4 v[134:137], v[214:215], off offset:528
	global_load_dwordx4 v[146:149], v[216:217], off offset:528
	global_load_dwordx4 v[142:145], v[218:219], off offset:528
	v_mov_b32_e32 v172, v116
	v_mov_b32_e32 v170, v117
	s_cbranch_vccnz .LBB0_881
	v_add_u32_e32 v155, 0xffffe000, v202
	v_ashrrev_i32_e32 v155, 2, v155
	v_lshl_add_u32 v155, v155, 1, v155
	v_mad_i64_i32 v[156:157], s[0:1], v155, s47, 0
	v_lshl_add_u64 v[156:157], v[156:157], 2, v[208:209]
	v_lshl_add_u64 v[158:159], v[156:157], 0, s[24:25]
	s_lshl_b32 s0, s27, 2
	s_mov_b32 s1, s25
	global_load_dwordx4 v[166:169], v[156:157], off offset:528
	s_nop 0
	global_load_dwordx4 v[158:161], v[158:159], off offset:528
	v_lshl_add_u64 v[156:157], v[156:157], 0, s[0:1]
	global_load_dwordx4 v[162:165], v[156:157], off offset:528
	v_mov_b32_e32 v170, 0
	v_mov_b32_e32 v171, 0
	v_mov_b32_e32 v154, 0
	v_mov_b32_dpp v170, v114 row_ror:1 row_mask:0xf bank_mask:0xf
	v_mov_b32_dpp v171, v114 row_ror:2 row_mask:0xf bank_mask:0xf
	v_mov_b32_dpp v154, v114 row_ror:3 row_mask:0xf bank_mask:0xf
	v_cmp_lt_i32_e32 vcc, 1, v205
	s_and_saveexec_b64 s[0:1], vcc
	s_xor_b64 s[0:1], exec, s[0:1]
	s_cbranch_execz .LBB0_844
	v_cmp_gt_i32_e32 vcc, 3, v205
	s_and_saveexec_b64 s[2:3], vcc
	s_cbranch_execz .LBB0_843
	s_waitcnt vmcnt(0)
	v_mov_b32_e32 v154, v162

; __device__ __forceinline__ unsigned cvt_pk_bf16(float lo, float hi) { unsigned r; asm("v_cvt_pk_bf16_f32 %0, %1, %2" : "=v"(r) : "v"(lo), "v"(hi)); return r; }
; __device__ __forceinline__ float siluf_(float x) { return x * sigmoidf_(x); }
; __device__ __forceinline__ float dpp_ror1(float v) { return __builtin_bit_cast(float, __builtin_amdgcn_update_dpp(0, __builtin_bit_cast(int, v), 0x121, 0xf, 0xf, false)); }
;     __device__ __forceinline__ void operator()(f32x4 (&acc)[2][2][4][2], const pg8::Unit& u, int wr, int wc, int fr, int fq) const {
;     ...
;                 for (int n = 0; n < 2; ++n) { const int ch = ch0 + bj * 128 + 4 * n;
;                     const f32x4 w0 = *(const f32x4*)(cw + ch), w1 = *(const f32x4*)(cw + CW + ch), w2 = *(const f32x4*)(cw + 2 * CW + ch), w3 = *(const f32x4*)(cw + 3 * CW + ch), bb = *(const f32x4*)(cb + ch);
; #pragma unroll
;                     for (int m = 0; m < 4; ++m) { const int row = row0 + ai * 128 + m * 16; const f32x4 g = acc[ai][bj][m][n]; f32x4 p1, p2, p3;
;                         if (prompt) { const f32x4 gp = (m == 0) ? hal[n] : acc[ai][bj][m > 0 ? m - 1 : 0][n];
; #pragma unroll
;                             for (int j = 0; j < 4; ++j) { p1[j] = dpp_ror1(fr == 15 ? gp[j] : g[j]); p2[j] = dpp_ror2(fr >= 14 ? gp[j] : g[j]); p3[j] = dpp_ror3(fr >= 13 ? gp[j] : g[j]); } }
;                         else { const int t = fr & 3; const float* sp = stp + (size_t)((row - MP) >> 2) * 3 * CW + ch;
;                             const f32x4 b0 = *(const f32x4*)sp, b1 = *(const f32x4*)(sp + CW), b2 = *(const f32x4*)(sp + 2 * CW);
; #pragma unroll
;                             for (int j = 0; j < 4; ++j) { const float r1 = dpp_ror1(g[j]), r2 = dpp_ror2(g[j]), r3 = dpp_ror3(g[j]);
;                                 p1[j] = t >= 1 ? r1 : b2[j]; p2[j] = t >= 2 ? r2 : (t == 1 ? b2[j] : b1[j]); p3[j] = t >= 3 ? r3 : (t == 2 ? b2[j] : (t == 1 ? b1[j] : b0[j])); } }
;                         float o[4];
; #pragma unroll
;                         for (int j = 0; j < 4; ++j) { const float y = bb[j] + w0[j] * p3[j] + w1[j] * p2[j] + w2[j] * p1[j] + w3[j] * g[j]; o[j] = is_rg ? y : siluf_(y); }
;                         u32x2 w; w.x = cvt_pk_bf16(o[0], o[1]); w.y = cvt_pk_bf16(o[2], o[3]);
;                         *(u32x2*)(dst + (size_t)row * ld + bj * 128 + 4 * n) = w; }
.LBB0_883:
	s_waitcnt vmcnt(0)
	v_mov_b32_e32 v162, v150
	v_mov_b32_e32 v163, v138
	v_mov_b32_e32 v130, v158
	v_mov_b32_e32 v131, v154
	v_pk_mul_f32 v[130:131], v[162:163], v[130:131]
	v_mov_b32_e32 v164, v146
	v_add_f32_e32 v131, v142, v131
	v_mov_b32_e32 v165, v134
	v_mov_b32_e32 v233, v166
	v_add_f32_e32 v132, v130, v131
	v_pk_mul_f32 v[130:131], v[164:165], v[232:233]
	v_mov_b32_e32 v138, v151
	v_add_f32_e32 v131, v131, v132
	v_add_f32_e32 v132, v130, v131
	v_mul_f32_e32 v130, 0xbfb8aa3b, v132
	v_exp_f32_e32 v130, v130
	v_mov_b32_e32 v154, v159
	v_mov_b32_e32 v134, v147
	v_mov_b32_e32 v231, v167
	v_add_f32_e32 v130, 1.0, v130
	v_rcp_f32_e32 v133, v130
	v_pk_mul_f32 v[130:131], v[138:139], v[154:155]
	v_mov_b32_e32 v158, v152
	v_add_f32_e32 v131, v143, v131
	v_add_f32_e32 v146, v130, v131
	v_pk_mul_f32 v[130:131], v[134:135], v[230:231]
	v_mov_b32_e32 v159, v140
	v_add_f32_e32 v131, v131, v146
	v_add_f32_e32 v146, v130, v131
	v_mul_f32_e32 v130, 0xbfb8aa3b, v146
	v_exp_f32_e32 v130, v130
	v_mul_f32_e32 v131, v132, v133
	v_cndmask_b32_e64 v132, v131, v132, s[4:5]
	v_mov_b32_e32 v131, v156
	v_add_f32_e32 v130, 1.0, v130
	v_rcp_f32_e32 v133, v130
	v_mov_b32_e32 v130, v160
	v_pk_mul_f32 v[130:131], v[158:159], v[130:131]
	v_mov_b32_e32 v166, v148
	v_add_f32_e32 v131, v144, v131
	v_mov_b32_e32 v167, v136
	v_mov_b32_e32 v173, v168
	v_add_f32_e32 v140, v130, v131
	v_pk_mul_f32 v[130:131], v[166:167], v[172:173]
	v_mov_b32_e32 v156, v161
	v_add_f32_e32 v131, v131, v140
	v_add_f32_e32 v147, v130, v131
	v_mul_f32_e32 v130, 0xbfb8aa3b, v147
	v_mov_b32_e32 v140, v153
	v_exp_f32_e32 v148, v130
	v_pk_mul_f32 v[130:131], v[140:141], v[156:157]
	v_mov_b32_e32 v136, v149
	v_add_f32_e32 v131, v145, v131
	v_mov_b32_e32 v171, v169
	v_add_f32_e32 v150, v130, v131
	v_pk_mul_f32 v[130:131], v[136:137], v[170:171]
	v_add_f32_e32 v148, 1.0, v148
	v_add_f32_e32 v131, v131, v150
	v_add_f32_e32 v130, v130, v131
	v_mul_f32_e32 v131, 0xbfb8aa3b, v130
	v_exp_f32_e32 v131, v131
	v_rcp_f32_e32 v148, v148
	v_mul_f32_e32 v133, v146, v133
	v_cndmask_b32_e64 v133, v133, v146, s[4:5]
	v_add_f32_e32 v131, 1.0, v131
	v_rcp_f32_e32 v131, v131
	v_mul_f32_e32 v146, v147, v148
	v_cndmask_b32_e64 v146, v146, v147, s[4:5]
	s_mov_b64 s[0:1], -1
	v_mul_f32_e32 v131, v130, v131
	v_cndmask_b32_e64 v131, v131, v130, s[4:5]
	v_cvt_pk_bf16_f32 v130, v132, v133
	v_cvt_pk_bf16_f32 v131, v146, v131
	s_and_b64 vcc, exec, s[18:19]
	v_mov_b32_e32 v168, v98
	v_mov_b32_e32 v160, v99
	v_mov_b32_e32 v152, v100
	v_mov_b32_e32 v150, v101
	global_store_dwordx2 v[222:223], v[130:131], off offset:264
	s_cbranch_vccnz .LBB0_925
	v_add_u32_e32 v131, 0xffffe010, v202
	v_ashrrev_i32_e32 v131, 2, v131
	v_lshl_add_u32 v131, v131, 1, v131
	v_mad_i64_i32 v[132:133], s[0:1], v131, s47, 0
	v_lshl_add_u64 v[132:133], v[132:133], 2, v[208:209]
	v_lshl_add_u64 v[146:147], v[132:133], 0, s[24:25]
	s_lshl_b32 s0, s27, 2
	s_mov_b32 s1, s25
	global_load_dwordx4 v[154:157], v[132:133], off offset:528
	s_nop 0
	global_load_dwordx4 v[146:149], v[146:147], off offset:528
	v_lshl_add_u64 v[132:133], v[132:133], 0, s[0:1]
	global_load_dwordx4 v[150:153], v[132:133], off offset:528
	v_mov_b32_e32 v160, 0
	v_mov_b32_e32 v161, 0
	v_mov_b32_e32 v130, 0
	v_mov_b32_dpp v160, v98 row_ror:1 row_mask:0xf bank_mask:0xf
	v_mov_b32_dpp v161, v98 row_ror:2 row_mask:0xf bank_mask:0xf
	v_mov_b32_dpp v130, v98 row_ror:3 row_mask:0xf bank_mask:0xf
	v_cmp_lt_i32_e32 vcc, 1, v205
	s_and_saveexec_b64 s[0:1], vcc
	s_xor_b64 s[0:1], exec, s[0:1]
	s_cbranch_execz .LBB0_888
	v_cmp_gt_i32_e32 vcc, 3, v205
	s_and_saveexec_b64 s[2:3], vcc
	s_cbranch_execz .LBB0_887
	s_waitcnt vmcnt(0)
	v_mov_b32_e32 v130, v150

; __device__ __forceinline__ unsigned cvt_pk_bf16(float lo, float hi) { unsigned r; asm("v_cvt_pk_bf16_f32 %0, %1, %2" : "=v"(r) : "v"(lo), "v"(hi)); return r; }
; __device__ __forceinline__ float siluf_(float x) { return x * sigmoidf_(x); }
; __device__ __forceinline__ float dpp_ror1(float v) { return __builtin_bit_cast(float, __builtin_amdgcn_update_dpp(0, __builtin_bit_cast(int, v), 0x121, 0xf, 0xf, false)); }
;     __device__ __forceinline__ void operator()(f32x4 (&acc)[2][2][4][2], const pg8::Unit& u, int wr, int wc, int fr, int fq) const {
;     ...
;                 for (int n = 0; n < 2; ++n) { const int ch = ch0 + bj * 128 + 4 * n;
;                     const f32x4 w0 = *(const f32x4*)(cw + ch), w1 = *(const f32x4*)(cw + CW + ch), w2 = *(const f32x4*)(cw + 2 * CW + ch), w3 = *(const f32x4*)(cw + 3 * CW + ch), bb = *(const f32x4*)(cb + ch);
; #pragma unroll
;                     for (int m = 0; m < 4; ++m) { const int row = row0 + ai * 128 + m * 16; const f32x4 g = acc[ai][bj][m][n]; f32x4 p1, p2, p3;
;                         if (prompt) { const f32x4 gp = (m == 0) ? hal[n] : acc[ai][bj][m > 0 ? m - 1 : 0][n];
; #pragma unroll
;                             for (int j = 0; j < 4; ++j) { p1[j] = dpp_ror1(fr == 15 ? gp[j] : g[j]); p2[j] = dpp_ror2(fr >= 14 ? gp[j] : g[j]); p3[j] = dpp_ror3(fr >= 13 ? gp[j] : g[j]); } }
;                         else { const int t = fr & 3; const float* sp = stp + (size_t)((row - MP) >> 2) * 3 * CW + ch;
;                             const f32x4 b0 = *(const f32x4*)sp, b1 = *(const f32x4*)(sp + CW), b2 = *(const f32x4*)(sp + 2 * CW);
; #pragma unroll
;                             for (int j = 0; j < 4; ++j) { const float r1 = dpp_ror1(g[j]), r2 = dpp_ror2(g[j]), r3 = dpp_ror3(g[j]);
;                                 p1[j] = t >= 1 ? r1 : b2[j]; p2[j] = t >= 2 ? r2 : (t == 1 ? b2[j] : b1[j]); p3[j] = t >= 3 ? r3 : (t == 2 ? b2[j] : (t == 1 ? b1[j] : b0[j])); } }
;                         float o[4];
; #pragma unroll
;                         for (int j = 0; j < 4; ++j) { const float y = bb[j] + w0[j] * p3[j] + w1[j] * p2[j] + w2[j] * p1[j] + w3[j] * g[j]; o[j] = is_rg ? y : siluf_(y); }
;                         u32x2 w; w.x = cvt_pk_bf16(o[0], o[1]); w.y = cvt_pk_bf16(o[2], o[3]);
;                         *(u32x2*)(dst + (size_t)row * ld + bj * 128 + 4 * n) = w; }
.LBB0_927:
	v_mov_b32_e32 v170, v146
	v_mov_b32_e32 v171, v130
	v_pk_mul_f32 v[170:171], v[162:163], v[170:171]
	v_mov_b32_e32 v169, v154
	v_add_f32_e32 v130, v142, v171
	v_add_f32_e32 v130, v170, v130
	v_pk_mul_f32 v[168:169], v[164:165], v[168:169]
	v_mov_b32_e32 v161, v155
	v_add_f32_e32 v130, v169, v130
	v_add_f32_e32 v146, v168, v130
	v_mul_f32_e32 v130, 0xbfb8aa3b, v146
	v_exp_f32_e32 v130, v130
	v_mov_b32_e32 v153, v156
	s_mov_b64 s[0:1], -1
	s_and_b64 vcc, exec, s[18:19]
	v_add_f32_e32 v130, 1.0, v130
	v_rcp_f32_e32 v151, v130
	v_mov_b32_e32 v130, v147
	v_pk_mul_f32 v[130:131], v[138:139], v[130:131]
	v_mov_b32_e32 v168, v82
	v_add_f32_e32 v131, v143, v131
	v_add_f32_e32 v147, v130, v131
	v_pk_mul_f32 v[130:131], v[134:135], v[160:161]
	v_mov_b32_e32 v160, v83
	v_add_f32_e32 v131, v131, v147
	v_add_f32_e32 v147, v130, v131
	v_mul_f32_e32 v130, 0xbfb8aa3b, v147
	v_exp_f32_e32 v130, v130
	v_mul_f32_e32 v131, v146, v151
	v_cndmask_b32_e64 v146, v131, v146, s[4:5]
	v_mov_b32_e32 v131, v132
	v_add_f32_e32 v130, 1.0, v130
	v_rcp_f32_e32 v154, v130
	v_mov_b32_e32 v130, v148
	v_pk_mul_f32 v[130:131], v[158:159], v[130:131]
	v_mov_b32_e32 v151, v157
	v_add_f32_e32 v131, v144, v131
	v_add_f32_e32 v132, v130, v131
	v_pk_mul_f32 v[130:131], v[166:167], v[152:153]
	s_nop 0
	v_add_f32_e32 v131, v131, v132
	v_add_f32_e32 v148, v130, v131
	v_mul_f32_e32 v130, 0xbfb8aa3b, v148
	v_mov_b32_e32 v132, v149
	v_exp_f32_e32 v152, v130
	v_pk_mul_f32 v[130:131], v[140:141], v[132:133]
	v_add_f32_e32 v133, 1.0, v152
	v_add_f32_e32 v131, v145, v131
	v_add_f32_e32 v132, v130, v131
	v_pk_mul_f32 v[130:131], v[136:137], v[150:151]
	v_rcp_f32_e32 v133, v133
	v_add_f32_e32 v131, v131, v132
	v_add_f32_e32 v130, v130, v131
	v_mul_f32_e32 v131, 0xbfb8aa3b, v130
	v_exp_f32_e32 v131, v131
	v_mul_f32_e32 v132, v147, v154
	v_mul_f32_e32 v133, v148, v133
	v_cndmask_b32_e64 v132, v132, v147, s[4:5]
	v_add_f32_e32 v131, 1.0, v131
	v_rcp_f32_e32 v131, v131
	v_cndmask_b32_e64 v133, v133, v148, s[4:5]
	v_mov_b32_e32 v152, v84
	v_mov_b32_e32 v150, v85
	v_mul_f32_e32 v131, v130, v131
	v_cndmask_b32_e64 v131, v131, v130, s[4:5]
	v_cvt_pk_bf16_f32 v130, v146, v132
	v_cvt_pk_bf16_f32 v131, v133, v131
	global_store_dwordx2 v[224:225], v[130:131], off offset:264
	s_cbranch_vccnz .LBB0_969
	v_add_u32_e32 v131, 0xffffe020, v202
	v_ashrrev_i32_e32 v131, 2, v131
	v_lshl_add_u32 v131, v131, 1, v131
	v_mad_i64_i32 v[132:133], s[0:1], v131, s47, 0
	v_lshl_add_u64 v[132:133], v[132:133], 2, v[208:209]
	v_lshl_add_u64 v[146:147], v[132:133], 0, s[24:25]
	s_lshl_b32 s0, s27, 2
	s_mov_b32 s1, s25
	global_load_dwordx4 v[154:157], v[132:133], off offset:528
	s_nop 0
	global_load_dwordx4 v[146:149], v[146:147], off offset:528
	v_lshl_add_u64 v[132:133], v[132:133], 0, s[0:1]
	global_load_dwordx4 v[150:153], v[132:133], off offset:528
	v_mov_b32_e32 v160, 0
	v_mov_b32_e32 v161, 0
	v_mov_b32_e32 v130, 0
	v_mov_b32_dpp v160, v82 row_ror:1 row_mask:0xf bank_mask:0xf
	v_mov_b32_dpp v161, v82 row_ror:2 row_mask:0xf bank_mask:0xf
	v_mov_b32_dpp v130, v82 row_ror:3 row_mask:0xf bank_mask:0xf
	v_cmp_lt_i32_e32 vcc, 1, v205
	s_and_saveexec_b64 s[0:1], vcc
	s_xor_b64 s[0:1], exec, s[0:1]
	s_cbranch_execz .LBB0_932
	v_cmp_gt_i32_e32 vcc, 3, v205
	s_and_saveexec_b64 s[2:3], vcc
	s_cbranch_execz .LBB0_931
	s_waitcnt vmcnt(0)
	v_mov_b32_e32 v130, v150

; __device__ __forceinline__ unsigned cvt_pk_bf16(float lo, float hi) { unsigned r; asm("v_cvt_pk_bf16_f32 %0, %1, %2" : "=v"(r) : "v"(lo), "v"(hi)); return r; }
; __device__ __forceinline__ float siluf_(float x) { return x * sigmoidf_(x); }
; __device__ __forceinline__ float dpp_ror1(float v) { return __builtin_bit_cast(float, __builtin_amdgcn_update_dpp(0, __builtin_bit_cast(int, v), 0x121, 0xf, 0xf, false)); }
;     __device__ __forceinline__ void operator()(f32x4 (&acc)[2][2][4][2], const pg8::Unit& u, int wr, int wc, int fr, int fq) const {
;     ...
;                 for (int n = 0; n < 2; ++n) { const int ch = ch0 + bj * 128 + 4 * n;
;                     const f32x4 w0 = *(const f32x4*)(cw + ch), w1 = *(const f32x4*)(cw + CW + ch), w2 = *(const f32x4*)(cw + 2 * CW + ch), w3 = *(const f32x4*)(cw + 3 * CW + ch), bb = *(const f32x4*)(cb + ch);
; #pragma unroll
;                     for (int m = 0; m < 4; ++m) { const int row = row0 + ai * 128 + m * 16; const f32x4 g = acc[ai][bj][m][n]; f32x4 p1, p2, p3;
;                         if (prompt) { const f32x4 gp = (m == 0) ? hal[n] : acc[ai][bj][m > 0 ? m - 1 : 0][n];
; #pragma unroll
;                             for (int j = 0; j < 4; ++j) { p1[j] = dpp_ror1(fr == 15 ? gp[j] : g[j]); p2[j] = dpp_ror2(fr >= 14 ? gp[j] : g[j]); p3[j] = dpp_ror3(fr >= 13 ? gp[j] : g[j]); } }
;                         else { const int t = fr & 3; const float* sp = stp + (size_t)((row - MP) >> 2) * 3 * CW + ch;
;                             const f32x4 b0 = *(const f32x4*)sp, b1 = *(const f32x4*)(sp + CW), b2 = *(const f32x4*)(sp + 2 * CW);
; #pragma unroll
;                             for (int j = 0; j < 4; ++j) { const float r1 = dpp_ror1(g[j]), r2 = dpp_ror2(g[j]), r3 = dpp_ror3(g[j]);
;                                 p1[j] = t >= 1 ? r1 : b2[j]; p2[j] = t >= 2 ? r2 : (t == 1 ? b2[j] : b1[j]); p3[j] = t >= 3 ? r3 : (t == 2 ? b2[j] : (t == 1 ? b1[j] : b0[j])); } }
;                         float o[4];
; #pragma unroll
;                         for (int j = 0; j < 4; ++j) { const float y = bb[j] + w0[j] * p3[j] + w1[j] * p2[j] + w2[j] * p1[j] + w3[j] * g[j]; o[j] = is_rg ? y : siluf_(y); }
;                         u32x2 w; w.x = cvt_pk_bf16(o[0], o[1]); w.y = cvt_pk_bf16(o[2], o[3]);
;                         *(u32x2*)(dst + (size_t)row * ld + bj * 128 + 4 * n) = w; }
.LBB0_971:
	v_mov_b32_e32 v170, v146
	v_mov_b32_e32 v171, v130
	v_pk_mul_f32 v[170:171], v[162:163], v[170:171]
	v_mov_b32_e32 v169, v154
	v_add_f32_e32 v130, v142, v171
	v_add_f32_e32 v130, v170, v130
	v_pk_mul_f32 v[168:169], v[164:165], v[168:169]
	v_mov_b32_e32 v161, v155
	v_add_f32_e32 v130, v169, v130
	v_add_f32_e32 v146, v168, v130
	v_mul_f32_e32 v130, 0xbfb8aa3b, v146
	v_exp_f32_e32 v130, v130
	v_mov_b32_e32 v153, v156
	s_mov_b64 s[0:1], -1
	s_and_b64 vcc, exec, s[18:19]
	v_add_f32_e32 v130, 1.0, v130
	v_rcp_f32_e32 v151, v130
	v_mov_b32_e32 v130, v147
	v_pk_mul_f32 v[130:131], v[138:139], v[130:131]
	v_mov_b32_e32 v168, v66
	v_add_f32_e32 v131, v143, v131
	v_add_f32_e32 v147, v130, v131
	v_pk_mul_f32 v[130:131], v[134:135], v[160:161]
	v_mov_b32_e32 v160, v67
	v_add_f32_e32 v131, v131, v147
	v_add_f32_e32 v147, v130, v131
	v_mul_f32_e32 v130, 0xbfb8aa3b, v147
	v_exp_f32_e32 v130, v130
	v_mul_f32_e32 v131, v146, v151
	v_cndmask_b32_e64 v146, v131, v146, s[4:5]
	v_mov_b32_e32 v131, v132
	v_add_f32_e32 v130, 1.0, v130
	v_rcp_f32_e32 v154, v130
	v_mov_b32_e32 v130, v148
	v_pk_mul_f32 v[130:131], v[158:159], v[130:131]
	v_mov_b32_e32 v151, v157
	v_add_f32_e32 v131, v144, v131
	v_add_f32_e32 v132, v130, v131
	v_pk_mul_f32 v[130:131], v[166:167], v[152:153]
	s_nop 0
	v_add_f32_e32 v131, v131, v132
	v_add_f32_e32 v148, v130, v131
	v_mul_f32_e32 v130, 0xbfb8aa3b, v148
	v_mov_b32_e32 v132, v149
	v_exp_f32_e32 v152, v130
	v_pk_mul_f32 v[130:131], v[140:141], v[132:133]
	v_add_f32_e32 v133, 1.0, v152
	v_add_f32_e32 v131, v145, v131
	v_add_f32_e32 v132, v130, v131
	v_pk_mul_f32 v[130:131], v[136:137], v[150:151]
	v_rcp_f32_e32 v133, v133
	v_add_f32_e32 v131, v131, v132
	v_add_f32_e32 v130, v130, v131
	v_mul_f32_e32 v131, 0xbfb8aa3b, v130
	v_exp_f32_e32 v131, v131
	v_mul_f32_e32 v132, v147, v154
	v_mul_f32_e32 v133, v148, v133
	v_cndmask_b32_e64 v132, v132, v147, s[4:5]
	v_add_f32_e32 v131, 1.0, v131
	v_rcp_f32_e32 v131, v131
	v_cndmask_b32_e64 v133, v133, v148, s[4:5]
	v_mov_b32_e32 v152, v68
	v_mov_b32_e32 v150, v69
	v_mul_f32_e32 v131, v130, v131
	v_cndmask_b32_e64 v131, v131, v130, s[4:5]
	v_cvt_pk_bf16_f32 v130, v146, v132
	v_cvt_pk_bf16_f32 v131, v133, v131
	global_store_dwordx2 v[226:227], v[130:131], off offset:264
	s_cbranch_vccnz .LBB0_1013
	v_add_u32_e32 v131, 0xffffe030, v202
	v_ashrrev_i32_e32 v131, 2, v131
	v_lshl_add_u32 v131, v131, 1, v131
	v_mad_i64_i32 v[132:133], s[0:1], v131, s47, 0
	v_lshl_add_u64 v[132:133], v[132:133], 2, v[208:209]
	v_lshl_add_u64 v[146:147], v[132:133], 0, s[24:25]
	s_lshl_b32 s0, s27, 2
	s_mov_b32 s1, s25
	global_load_dwordx4 v[154:157], v[132:133], off offset:528
	s_nop 0
	global_load_dwordx4 v[146:149], v[146:147], off offset:528
	v_lshl_add_u64 v[132:133], v[132:133], 0, s[0:1]
	global_load_dwordx4 v[150:153], v[132:133], off offset:528
	v_mov_b32_e32 v160, 0
	v_mov_b32_e32 v161, 0
	v_mov_b32_e32 v130, 0
	v_mov_b32_dpp v160, v66 row_ror:1 row_mask:0xf bank_mask:0xf
	v_mov_b32_dpp v161, v66 row_ror:2 row_mask:0xf bank_mask:0xf
	v_mov_b32_dpp v130, v66 row_ror:3 row_mask:0xf bank_mask:0xf
	v_cmp_lt_i32_e32 vcc, 1, v205
	s_and_saveexec_b64 s[0:1], vcc
	s_xor_b64 s[0:1], exec, s[0:1]
	s_cbranch_execz .LBB0_976
	v_cmp_gt_i32_e32 vcc, 3, v205
	s_and_saveexec_b64 s[2:3], vcc
	s_cbranch_execz .LBB0_975
	s_waitcnt vmcnt(0)
	v_mov_b32_e32 v130, v150

; #define LAS __attribute__((address_space(3)))
;     __device__ __forceinline__ void operator()(f32x4 (&acc)[2][2][4][2], const pg8::Unit& u, int wr, int wc, int fr, int fq) const {
;     ...
;                 f32x4 hal[2];
;                 hal[0] = hal[1] = (f32x4){0.f, 0.f, 0.f, 0.f};
;                 if (prompt) { const int b = 2 * ai + wr;
;                     if (b >= 1) { if (fr >= 13) {
; #pragma unroll
;                             for (int n = 0; n < 2; ++n) hal[n] = *(const LAS f32x4*)(H + ((b - 1) * 3 + (fr - 13)) * 256 + bj * 128 + cl0 + 4 * n); } }
;                     else if ((u.pm & 7) != 0) { unsigned* fl = HFLAG + (tile - 37); unsigned sp = 0;
;                         while ((unsigned)__builtin_amdgcn_readfirstlane(__hip_atomic_load(fl, __ATOMIC_RELAXED, __HIP_MEMORY_SCOPE_AGENT)) < 4u) { __builtin_amdgcn_s_sleep(2);
;                             if ((++sp & 1023u) == 0u) { if (__hip_atomic_load(tmo, __ATOMIC_RELAXED, __HIP_MEMORY_SCOPE_AGENT) != 0u) break; if (sp > (1u << 22)) { __hip_atomic_store(tmo, 1u, __ATOMIC_RELAXED, __HIP_MEMORY_SCOPE_AGENT); break; } } }
;                         if (fr >= 13) { const unsigned long long* hp = HALO + ((size_t)(tile - 37) * 3 + (fr - 13)) * 128 + (cl0 >> 1) + bj * 64;
; #pragma unroll
;                             for (int n = 0; n < 2; ++n) { const unsigned long long a2 = __hip_atomic_load(hp + 2 * n, __ATOMIC_RELAXED, __HIP_MEMORY_SCOPE_AGENT), b2 = __hip_atomic_load(hp + 2 * n + 1, __ATOMIC_RELAXED, __HIP_MEMORY_SCOPE_AGENT);
;                                 hal[n] = (f32x4){__uint_as_float((unsigned)a2), __uint_as_float((unsigned)(a2 >> 32)), __uint_as_float((unsigned)b2), __uint_as_float((unsigned)(b2 >> 32))}; } } } }
; #pragma unroll
;                 for (int n = 0; n < 2; ++n) { const int ch = ch0 + bj * 128 + 4 * n;
;                     const f32x4 w0 = *(const f32x4*)(cw + ch), w1 = *(const f32x4*)(cw + CW + ch), w2 = *(const f32x4*)(cw + 2 * CW + ch), w3 = *(const f32x4*)(cw + 3 * CW + ch), bb = *(const f32x4*)(cb + ch);
; #pragma unroll
;                     for (int m = 0; m < 4; ++m) { const int row = row0 + ai * 128 + m * 16; const f32x4 g = acc[ai][bj][m][n]; f32x4 p1, p2, p3;
;                         if (prompt) { const f32x4 gp = (m == 0) ? hal[n] : acc[ai][bj][m > 0 ? m - 1 : 0][n];
; #pragma unroll
.LBB0_1015:
	v_mov_b32_e32 v170, v146
	v_mov_b32_e32 v171, v130
	v_pk_mul_f32 v[162:163], v[162:163], v[170:171]
	v_mov_b32_e32 v169, v154
	v_add_f32_e32 v130, v142, v163
	v_add_f32_e32 v130, v162, v130
	v_pk_mul_f32 v[162:163], v[164:165], v[168:169]
	v_mov_b32_e32 v161, v155
	v_add_f32_e32 v130, v163, v130
	v_add_f32_e32 v142, v162, v130
	v_mul_f32_e32 v130, 0xbfb8aa3b, v142
	v_exp_f32_e32 v130, v130
	v_mov_b32_e32 v153, v156
	v_mov_b32_e32 v151, v157
	v_readlane_b32 s0, v255, 7
	v_add_f32_e32 v130, 1.0, v130
	v_rcp_f32_e32 v146, v130
	v_mov_b32_e32 v130, v147
	v_pk_mul_f32 v[130:131], v[138:139], v[130:131]
	v_readlane_b32 s2, v255, 19
	v_add_f32_e32 v131, v143, v131
	v_add_f32_e32 v138, v130, v131
	v_pk_mul_f32 v[130:131], v[134:135], v[160:161]
	v_mov_b32_e32 v160, 0
	v_add_f32_e32 v131, v131, v138
	v_add_f32_e32 v134, v130, v131
	v_mul_f32_e32 v130, 0xbfb8aa3b, v134
	v_exp_f32_e32 v130, v130
	v_mul_f32_e32 v131, v142, v146
	v_cndmask_b32_e64 v135, v131, v142, s[4:5]
	v_mov_b32_e32 v131, v132
	v_add_f32_e32 v130, 1.0, v130
	v_rcp_f32_e32 v138, v130
	v_mov_b32_e32 v130, v148
	v_pk_mul_f32 v[130:131], v[158:159], v[130:131]
	v_mov_b32_e32 v158, 0
	v_add_f32_e32 v131, v144, v131
	v_add_f32_e32 v132, v130, v131
	v_pk_mul_f32 v[130:131], v[166:167], v[152:153]
	v_mov_b32_e32 v159, 0
	v_add_f32_e32 v131, v131, v132
	v_add_f32_e32 v139, v130, v131
	v_mul_f32_e32 v130, 0xbfb8aa3b, v139
	v_mov_b32_e32 v132, v149
	v_exp_f32_e32 v142, v130
	v_pk_mul_f32 v[130:131], v[140:141], v[132:133]
	v_mov_b32_e32 v161, 0
	v_add_f32_e32 v131, v145, v131
	v_add_f32_e32 v132, v130, v131
	v_pk_mul_f32 v[130:131], v[136:137], v[150:151]
	v_add_f32_e32 v133, 1.0, v142
	v_add_f32_e32 v131, v131, v132
	v_add_f32_e32 v130, v130, v131
	v_mul_f32_e32 v131, 0xbfb8aa3b, v130
	v_exp_f32_e32 v131, v131
	v_rcp_f32_e32 v133, v133
	v_mul_f32_e32 v132, v134, v138
	v_cndmask_b32_e64 v132, v132, v134, s[4:5]
	v_add_f32_e32 v131, 1.0, v131
	v_rcp_f32_e32 v131, v131
	v_mul_f32_e32 v133, v139, v133
	v_cndmask_b32_e64 v133, v133, v139, s[4:5]
	v_mul_f32_e32 v131, v130, v131
	v_cndmask_b32_e64 v131, v131, v130, s[4:5]
	v_cvt_pk_bf16_f32 v130, v135, v132
	v_cvt_pk_bf16_f32 v131, v133, v131
	global_store_dwordx2 v[228:229], v[130:131], off offset:264
	v_add_lshl_u32 v131, v207, s0, 10
	s_and_b64 s[0:1], s[76:77], s[6:7]
	v_mov_b32_e32 v130, 0
	v_lshlrev_b32_e32 v207, 2, v206
	v_add_u32_e32 v232, s2, v131
	v_mov_b32_e32 v131, 0
	v_mov_b32_e32 v132, 0
	v_mov_b32_e32 v133, 0
	s_and_saveexec_b64 s[2:3], s[0:1]
	s_cbranch_execz .LBB0_1017
	s_movk_i32 s20, 0xc000
	v_add3_u32 v130, v232, v207, s20
	ds_read_b128 v[158:161], v130
	ds_read_b128 v[130:133], v130 offset:16

; __device__ __forceinline__ unsigned cvt_pk_bf16(float lo, float hi) { unsigned r; asm("v_cvt_pk_bf16_f32 %0, %1, %2" : "=v"(r) : "v"(lo), "v"(hi)); return r; }
; __device__ __forceinline__ float siluf_(float x) { return x * sigmoidf_(x); }
; __device__ __forceinline__ float dpp_ror1(float v) { return __builtin_bit_cast(float, __builtin_amdgcn_update_dpp(0, __builtin_bit_cast(int, v), 0x121, 0xf, 0xf, false)); }
;     __device__ __forceinline__ void operator()(f32x4 (&acc)[2][2][4][2], const pg8::Unit& u, int wr, int wc, int fr, int fq) const {
;     ...
;                 for (int n = 0; n < 2; ++n) { const int ch = ch0 + bj * 128 + 4 * n;
;                     const f32x4 w0 = *(const f32x4*)(cw + ch), w1 = *(const f32x4*)(cw + CW + ch), w2 = *(const f32x4*)(cw + 2 * CW + ch), w3 = *(const f32x4*)(cw + 3 * CW + ch), bb = *(const f32x4*)(cb + ch);
; #pragma unroll
;                     for (int m = 0; m < 4; ++m) { const int row = row0 + ai * 128 + m * 16; const f32x4 g = acc[ai][bj][m][n]; f32x4 p1, p2, p3;
;                         if (prompt) { const f32x4 gp = (m == 0) ? hal[n] : acc[ai][bj][m > 0 ? m - 1 : 0][n];
; #pragma unroll
;                             for (int j = 0; j < 4; ++j) { p1[j] = dpp_ror1(fr == 15 ? gp[j] : g[j]); p2[j] = dpp_ror2(fr >= 14 ? gp[j] : g[j]); p3[j] = dpp_ror3(fr >= 13 ? gp[j] : g[j]); } }
;                         else { const int t = fr & 3; const float* sp = stp + (size_t)((row - MP) >> 2) * 3 * CW + ch;
;                             const f32x4 b0 = *(const f32x4*)sp, b1 = *(const f32x4*)(sp + CW), b2 = *(const f32x4*)(sp + 2 * CW);
; #pragma unroll
;                             for (int j = 0; j < 4; ++j) { const float r1 = dpp_ror1(g[j]), r2 = dpp_ror2(g[j]), r3 = dpp_ror3(g[j]);
;                                 p1[j] = t >= 1 ? r1 : b2[j]; p2[j] = t >= 2 ? r2 : (t == 1 ? b2[j] : b1[j]); p3[j] = t >= 3 ? r3 : (t == 2 ? b2[j] : (t == 1 ? b1[j] : b0[j])); } }
;                         float o[4];
; #pragma unroll
;                         for (int j = 0; j < 4; ++j) { const float y = bb[j] + w0[j] * p3[j] + w1[j] * p2[j] + w2[j] * p1[j] + w3[j] * g[j]; o[j] = is_rg ? y : siluf_(y); }
;                         u32x2 w; w.x = cvt_pk_bf16(o[0], o[1]); w.y = cvt_pk_bf16(o[2], o[3]);
;                         *(u32x2*)(dst + (size_t)row * ld + bj * 128 + 4 * n) = w; }
.LBB0_1061:
	s_waitcnt vmcnt(0)
	v_mov_b32_e32 v166, v150
	v_mov_b32_e32 v167, v138
	s_waitcnt lgkmcnt(0)
	v_mov_b32_e32 v158, v162
	v_mov_b32_e32 v159, v154
	v_pk_mul_f32 v[158:159], v[166:167], v[158:159]
	v_mov_b32_e32 v168, v146
	v_add_f32_e32 v138, v142, v159
	v_mov_b32_e32 v169, v134
	v_mov_b32_e32 v229, v170
	v_add_f32_e32 v138, v158, v138
	v_pk_mul_f32 v[158:159], v[168:169], v[228:229]
	v_mov_b32_e32 v154, v163
	v_add_f32_e32 v134, v159, v138
	v_add_f32_e32 v158, v158, v134
	v_mul_f32_e32 v134, 0xbfb8aa3b, v158
	v_exp_f32_e32 v134, v134
	v_mov_b32_e32 v138, v151
	v_pk_mul_f32 v[150:151], v[138:139], v[154:155]
	v_mov_b32_e32 v227, v171
	v_add_f32_e32 v134, 1.0, v134
	v_rcp_f32_e32 v159, v134
	v_add_f32_e32 v134, v143, v151
	v_add_f32_e32 v150, v150, v134
	v_mov_b32_e32 v134, v147
	v_pk_mul_f32 v[146:147], v[134:135], v[226:227]
	v_mov_b32_e32 v162, v152
	v_add_f32_e32 v147, v147, v150
	v_add_f32_e32 v150, v146, v147
	v_mul_f32_e32 v146, 0xbfb8aa3b, v150
	v_exp_f32_e32 v146, v146
	v_mul_f32_e32 v147, v158, v159
	v_cndmask_b32_e64 v151, v147, v158, s[4:5]
	v_mov_b32_e32 v163, v140
	v_add_f32_e32 v146, 1.0, v146
	v_rcp_f32_e32 v154, v146
	v_mov_b32_e32 v146, v164
	v_mov_b32_e32 v147, v156
	v_pk_mul_f32 v[146:147], v[162:163], v[146:147]
	v_mov_b32_e32 v170, v148
	v_add_f32_e32 v140, v144, v147
	v_mov_b32_e32 v171, v136
	v_mov_b32_e32 v225, v172
	v_add_f32_e32 v140, v146, v140
	v_pk_mul_f32 v[146:147], v[170:171], v[224:225]
	v_mov_b32_e32 v156, v165
	v_add_f32_e32 v136, v147, v140
	v_add_f32_e32 v148, v146, v136
	v_mov_b32_e32 v140, v153
	v_mul_f32_e32 v136, 0xbfb8aa3b, v148
	v_pk_mul_f32 v[146:147], v[140:141], v[156:157]
	v_exp_f32_e32 v152, v136
	v_add_f32_e32 v136, v145, v147
	v_add_f32_e32 v153, v146, v136
	v_mov_b32_e32 v136, v149
	v_mov_b32_e32 v223, v173
	v_pk_mul_f32 v[146:147], v[136:137], v[222:223]
	v_add_f32_e32 v152, 1.0, v152
	v_add_f32_e32 v147, v147, v153
	v_add_f32_e32 v146, v146, v147
	v_mul_f32_e32 v147, 0xbfb8aa3b, v146
	v_exp_f32_e32 v147, v147
	v_rcp_f32_e32 v152, v152
	v_mul_f32_e32 v149, v150, v154
	v_cndmask_b32_e64 v149, v149, v150, s[4:5]
	v_add_f32_e32 v147, 1.0, v147
	v_rcp_f32_e32 v147, v147
	v_mul_f32_e32 v150, v148, v152
	v_cndmask_b32_e64 v148, v150, v148, s[4:5]
	s_mov_b64 s[2:3], -1
	v_mul_f32_e32 v147, v146, v147
	v_cndmask_b32_e64 v147, v147, v146, s[4:5]
	v_cvt_pk_bf16_f32 v146, v151, v149
	v_cvt_pk_bf16_f32 v147, v148, v147
	v_lshlrev_b64 v[148:149], v182, v[194:195]
	v_lshl_add_u64 v[222:223], v[148:149], 1, v[220:221]
	s_and_b64 vcc, exec, s[18:19]
	v_mov_b32_e32 v172, v46
	v_mov_b32_e32 v164, v47
	v_mov_b32_e32 v156, v48
	v_mov_b32_e32 v154, v49
	global_store_dwordx2 v[222:223], v[146:147], off
	s_cbranch_vccnz .LBB0_1103
	v_add_u32_e32 v147, 0xffffe090, v202
	v_ashrrev_i32_e32 v147, 2, v147
	v_lshl_add_u32 v147, v147, 1, v147
	v_mad_i64_i32 v[148:149], s[2:3], v147, s47, 0
	v_lshl_add_u64 v[148:149], v[148:149], 2, v[208:209]
	v_lshl_add_u64 v[150:151], v[148:149], 0, s[24:25]
	s_lshl_b32 s2, s27, 2
	s_mov_b32 s3, s25
	global_load_dwordx4 v[158:161], v[148:149], off
	s_nop 0
	global_load_dwordx4 v[150:153], v[150:151], off
	v_lshl_add_u64 v[148:149], v[148:149], 0, s[2:3]
	global_load_dwordx4 v[154:157], v[148:149], off
	v_mov_b32_e32 v164, 0
	v_mov_b32_e32 v165, 0
	v_mov_b32_e32 v146, 0
	v_mov_b32_dpp v164, v46 row_ror:1 row_mask:0xf bank_mask:0xf
	v_mov_b32_dpp v165, v46 row_ror:2 row_mask:0xf bank_mask:0xf
	v_mov_b32_dpp v146, v46 row_ror:3 row_mask:0xf bank_mask:0xf
	v_cmp_lt_i32_e32 vcc, 1, v205
	s_and_saveexec_b64 s[2:3], vcc
	s_xor_b64 s[2:3], exec, s[2:3]
	s_cbranch_execz .LBB0_1066
	v_cmp_gt_i32_e32 vcc, 3, v205
	s_and_saveexec_b64 s[20:21], vcc
	s_cbranch_execz .LBB0_1065
	s_waitcnt vmcnt(0)
	v_mov_b32_e32 v146, v154

; __device__ __forceinline__ unsigned cvt_pk_bf16(float lo, float hi) { unsigned r; asm("v_cvt_pk_bf16_f32 %0, %1, %2" : "=v"(r) : "v"(lo), "v"(hi)); return r; }
; __device__ __forceinline__ float siluf_(float x) { return x * sigmoidf_(x); }
; __device__ __forceinline__ float dpp_ror1(float v) { return __builtin_bit_cast(float, __builtin_amdgcn_update_dpp(0, __builtin_bit_cast(int, v), 0x121, 0xf, 0xf, false)); }
;     __device__ __forceinline__ void operator()(f32x4 (&acc)[2][2][4][2], const pg8::Unit& u, int wr, int wc, int fr, int fq) const {
;     ...
;                 for (int n = 0; n < 2; ++n) { const int ch = ch0 + bj * 128 + 4 * n;
;                     const f32x4 w0 = *(const f32x4*)(cw + ch), w1 = *(const f32x4*)(cw + CW + ch), w2 = *(const f32x4*)(cw + 2 * CW + ch), w3 = *(const f32x4*)(cw + 3 * CW + ch), bb = *(const f32x4*)(cb + ch);
; #pragma unroll
;                     for (int m = 0; m < 4; ++m) { const int row = row0 + ai * 128 + m * 16; const f32x4 g = acc[ai][bj][m][n]; f32x4 p1, p2, p3;
;                         if (prompt) { const f32x4 gp = (m == 0) ? hal[n] : acc[ai][bj][m > 0 ? m - 1 : 0][n];
; #pragma unroll
;                             for (int j = 0; j < 4; ++j) { p1[j] = dpp_ror1(fr == 15 ? gp[j] : g[j]); p2[j] = dpp_ror2(fr >= 14 ? gp[j] : g[j]); p3[j] = dpp_ror3(fr >= 13 ? gp[j] : g[j]); } }
;                         else { const int t = fr & 3; const float* sp = stp + (size_t)((row - MP) >> 2) * 3 * CW + ch;
;                             const f32x4 b0 = *(const f32x4*)sp, b1 = *(const f32x4*)(sp + CW), b2 = *(const f32x4*)(sp + 2 * CW);
; #pragma unroll
;                             for (int j = 0; j < 4; ++j) { const float r1 = dpp_ror1(g[j]), r2 = dpp_ror2(g[j]), r3 = dpp_ror3(g[j]);
;                                 p1[j] = t >= 1 ? r1 : b2[j]; p2[j] = t >= 2 ? r2 : (t == 1 ? b2[j] : b1[j]); p3[j] = t >= 3 ? r3 : (t == 2 ? b2[j] : (t == 1 ? b1[j] : b0[j])); } }
;                         float o[4];
; #pragma unroll
;                         for (int j = 0; j < 4; ++j) { const float y = bb[j] + w0[j] * p3[j] + w1[j] * p2[j] + w2[j] * p1[j] + w3[j] * g[j]; o[j] = is_rg ? y : siluf_(y); }
;                         u32x2 w; w.x = cvt_pk_bf16(o[0], o[1]); w.y = cvt_pk_bf16(o[2], o[3]);
;                         *(u32x2*)(dst + (size_t)row * ld + bj * 128 + 4 * n) = w; }
.LBB0_1105:
	v_mov_b32_e32 v224, v150
	v_mov_b32_e32 v225, v146
	v_pk_mul_f32 v[224:225], v[166:167], v[224:225]
	v_mov_b32_e32 v173, v158
	v_add_f32_e32 v146, v142, v225
	v_add_f32_e32 v146, v224, v146
	v_pk_mul_f32 v[172:173], v[168:169], v[172:173]
	v_mov_b32_e32 v165, v159
	v_add_f32_e32 v146, v173, v146
	v_add_f32_e32 v150, v172, v146
	v_mul_f32_e32 v146, 0xbfb8aa3b, v150
	v_exp_f32_e32 v146, v146
	v_mov_b32_e32 v157, v160
	s_mov_b64 s[2:3], -1
	s_and_b64 vcc, exec, s[18:19]
	v_add_f32_e32 v146, 1.0, v146
	v_rcp_f32_e32 v155, v146
	v_mov_b32_e32 v146, v151
	v_pk_mul_f32 v[146:147], v[138:139], v[146:147]
	v_mov_b32_e32 v172, v26
	v_add_f32_e32 v147, v143, v147
	v_add_f32_e32 v151, v146, v147
	v_pk_mul_f32 v[146:147], v[134:135], v[164:165]
	v_mov_b32_e32 v164, v27
	v_add_f32_e32 v147, v147, v151
	v_add_f32_e32 v151, v146, v147
	v_mul_f32_e32 v146, 0xbfb8aa3b, v151
	v_exp_f32_e32 v146, v146
	v_mul_f32_e32 v147, v150, v155
	v_cndmask_b32_e64 v150, v147, v150, s[4:5]
	v_mov_b32_e32 v147, v148
	v_add_f32_e32 v146, 1.0, v146
	v_rcp_f32_e32 v158, v146
	v_mov_b32_e32 v146, v152
	v_pk_mul_f32 v[146:147], v[162:163], v[146:147]
	v_mov_b32_e32 v155, v161
	v_add_f32_e32 v147, v144, v147
	v_add_f32_e32 v148, v146, v147
	v_pk_mul_f32 v[146:147], v[170:171], v[156:157]
	s_nop 0
	v_add_f32_e32 v147, v147, v148
	v_add_f32_e32 v152, v146, v147
	v_mul_f32_e32 v146, 0xbfb8aa3b, v152
	v_mov_b32_e32 v148, v153
	v_exp_f32_e32 v156, v146
	v_pk_mul_f32 v[146:147], v[140:141], v[148:149]
	v_add_f32_e32 v149, 1.0, v156
	v_add_f32_e32 v147, v145, v147
	v_add_f32_e32 v148, v146, v147
	v_pk_mul_f32 v[146:147], v[136:137], v[154:155]
	v_rcp_f32_e32 v149, v149
	v_add_f32_e32 v147, v147, v148
	v_add_f32_e32 v146, v146, v147
	v_mul_f32_e32 v147, 0xbfb8aa3b, v146
	v_exp_f32_e32 v147, v147
	v_mul_f32_e32 v148, v151, v158
	v_mul_f32_e32 v149, v152, v149
	v_cndmask_b32_e64 v148, v148, v151, s[4:5]
	v_add_f32_e32 v147, 1.0, v147
	v_rcp_f32_e32 v147, v147
	v_cndmask_b32_e64 v149, v149, v152, s[4:5]
	v_mov_b32_e32 v156, v28
	v_mov_b32_e32 v154, v29
	v_mul_f32_e32 v147, v146, v147
	v_cndmask_b32_e64 v147, v147, v146, s[4:5]
	v_cvt_pk_bf16_f32 v146, v150, v148
	v_cvt_pk_bf16_f32 v147, v149, v147
	v_lshlrev_b64 v[148:149], v182, v[192:193]
	v_lshl_add_u64 v[224:225], v[148:149], 1, v[220:221]
	global_store_dwordx2 v[224:225], v[146:147], off
	s_cbranch_vccnz .LBB0_1147
	v_add_u32_e32 v147, 0xffffe0a0, v202
	v_ashrrev_i32_e32 v147, 2, v147
	v_lshl_add_u32 v147, v147, 1, v147
	v_mad_i64_i32 v[148:149], s[2:3], v147, s47, 0
	v_lshl_add_u64 v[148:149], v[148:149], 2, v[208:209]
	v_lshl_add_u64 v[150:151], v[148:149], 0, s[24:25]
	s_lshl_b32 s2, s27, 2
	s_mov_b32 s3, s25
	global_load_dwordx4 v[158:161], v[148:149], off
	s_nop 0
	global_load_dwordx4 v[150:153], v[150:151], off
	v_lshl_add_u64 v[148:149], v[148:149], 0, s[2:3]
	global_load_dwordx4 v[154:157], v[148:149], off
	v_mov_b32_e32 v164, 0
	v_mov_b32_e32 v165, 0
	v_mov_b32_e32 v146, 0
	v_mov_b32_dpp v164, v26 row_ror:1 row_mask:0xf bank_mask:0xf
	v_mov_b32_dpp v165, v26 row_ror:2 row_mask:0xf bank_mask:0xf
	v_mov_b32_dpp v146, v26 row_ror:3 row_mask:0xf bank_mask:0xf
	v_cmp_lt_i32_e32 vcc, 1, v205
	s_and_saveexec_b64 s[2:3], vcc
	s_xor_b64 s[2:3], exec, s[2:3]
	s_cbranch_execz .LBB0_1110
	v_cmp_gt_i32_e32 vcc, 3, v205
	s_and_saveexec_b64 s[20:21], vcc
	s_cbranch_execz .LBB0_1109
	s_waitcnt vmcnt(0)
	v_mov_b32_e32 v146, v154

; __device__ __forceinline__ unsigned cvt_pk_bf16(float lo, float hi) { unsigned r; asm("v_cvt_pk_bf16_f32 %0, %1, %2" : "=v"(r) : "v"(lo), "v"(hi)); return r; }
; __device__ __forceinline__ float siluf_(float x) { return x * sigmoidf_(x); }
; __device__ __forceinline__ float dpp_ror1(float v) { return __builtin_bit_cast(float, __builtin_amdgcn_update_dpp(0, __builtin_bit_cast(int, v), 0x121, 0xf, 0xf, false)); }
;     __device__ __forceinline__ void operator()(f32x4 (&acc)[2][2][4][2], const pg8::Unit& u, int wr, int wc, int fr, int fq) const {
;     ...
;                 for (int n = 0; n < 2; ++n) { const int ch = ch0 + bj * 128 + 4 * n;
;                     const f32x4 w0 = *(const f32x4*)(cw + ch), w1 = *(const f32x4*)(cw + CW + ch), w2 = *(const f32x4*)(cw + 2 * CW + ch), w3 = *(const f32x4*)(cw + 3 * CW + ch), bb = *(const f32x4*)(cb + ch);
; #pragma unroll
;                     for (int m = 0; m < 4; ++m) { const int row = row0 + ai * 128 + m * 16; const f32x4 g = acc[ai][bj][m][n]; f32x4 p1, p2, p3;
;                         if (prompt) { const f32x4 gp = (m == 0) ? hal[n] : acc[ai][bj][m > 0 ? m - 1 : 0][n];
; #pragma unroll
;                             for (int j = 0; j < 4; ++j) { p1[j] = dpp_ror1(fr == 15 ? gp[j] : g[j]); p2[j] = dpp_ror2(fr >= 14 ? gp[j] : g[j]); p3[j] = dpp_ror3(fr >= 13 ? gp[j] : g[j]); } }
;                         else { const int t = fr & 3; const float* sp = stp + (size_t)((row - MP) >> 2) * 3 * CW + ch;
;                             const f32x4 b0 = *(const f32x4*)sp, b1 = *(const f32x4*)(sp + CW), b2 = *(const f32x4*)(sp + 2 * CW);
; #pragma unroll
;                             for (int j = 0; j < 4; ++j) { const float r1 = dpp_ror1(g[j]), r2 = dpp_ror2(g[j]), r3 = dpp_ror3(g[j]);
;                                 p1[j] = t >= 1 ? r1 : b2[j]; p2[j] = t >= 2 ? r2 : (t == 1 ? b2[j] : b1[j]); p3[j] = t >= 3 ? r3 : (t == 2 ? b2[j] : (t == 1 ? b1[j] : b0[j])); } }
;                         float o[4];
; #pragma unroll
;                         for (int j = 0; j < 4; ++j) { const float y = bb[j] + w0[j] * p3[j] + w1[j] * p2[j] + w2[j] * p1[j] + w3[j] * g[j]; o[j] = is_rg ? y : siluf_(y); }
;                         u32x2 w; w.x = cvt_pk_bf16(o[0], o[1]); w.y = cvt_pk_bf16(o[2], o[3]);
;                         *(u32x2*)(dst + (size_t)row * ld + bj * 128 + 4 * n) = w; }
.LBB0_1149:
	v_mov_b32_e32 v226, v150
	v_mov_b32_e32 v227, v146
	v_pk_mul_f32 v[226:227], v[166:167], v[226:227]
	v_mov_b32_e32 v173, v158
	v_add_f32_e32 v146, v142, v227
	v_add_f32_e32 v146, v226, v146
	v_pk_mul_f32 v[172:173], v[168:169], v[172:173]
	v_mov_b32_e32 v165, v159
	v_add_f32_e32 v146, v173, v146
	v_add_f32_e32 v150, v172, v146
	v_mul_f32_e32 v146, 0xbfb8aa3b, v150
	v_exp_f32_e32 v146, v146
	v_mov_b32_e32 v157, v160
	s_mov_b64 s[2:3], -1
	s_and_b64 vcc, exec, s[18:19]
	v_add_f32_e32 v146, 1.0, v146
	v_rcp_f32_e32 v155, v146
	v_mov_b32_e32 v146, v151
	v_pk_mul_f32 v[146:147], v[138:139], v[146:147]
	v_mov_b32_e32 v172, v14
	v_add_f32_e32 v147, v143, v147
	v_add_f32_e32 v151, v146, v147
	v_pk_mul_f32 v[146:147], v[134:135], v[164:165]
	v_mov_b32_e32 v164, v15
	v_add_f32_e32 v147, v147, v151
	v_add_f32_e32 v151, v146, v147
	v_mul_f32_e32 v146, 0xbfb8aa3b, v151
	v_exp_f32_e32 v146, v146
	v_mul_f32_e32 v147, v150, v155
	v_cndmask_b32_e64 v150, v147, v150, s[4:5]
	v_mov_b32_e32 v147, v148
	v_add_f32_e32 v146, 1.0, v146
	v_rcp_f32_e32 v158, v146
	v_mov_b32_e32 v146, v152
	v_pk_mul_f32 v[146:147], v[162:163], v[146:147]
	v_mov_b32_e32 v155, v161
	v_add_f32_e32 v147, v144, v147
	v_add_f32_e32 v148, v146, v147
	v_pk_mul_f32 v[146:147], v[170:171], v[156:157]
	s_nop 0
	v_add_f32_e32 v147, v147, v148
	v_add_f32_e32 v152, v146, v147
	v_mul_f32_e32 v146, 0xbfb8aa3b, v152
	v_mov_b32_e32 v148, v153
	v_exp_f32_e32 v156, v146
	v_pk_mul_f32 v[146:147], v[140:141], v[148:149]
	v_add_f32_e32 v149, 1.0, v156
	v_add_f32_e32 v147, v145, v147
	v_add_f32_e32 v148, v146, v147
	v_pk_mul_f32 v[146:147], v[136:137], v[154:155]
	v_rcp_f32_e32 v149, v149
	v_add_f32_e32 v147, v147, v148
	v_add_f32_e32 v146, v146, v147
	v_mul_f32_e32 v147, 0xbfb8aa3b, v146
	v_exp_f32_e32 v147, v147
	v_mul_f32_e32 v148, v151, v158
	v_mul_f32_e32 v149, v152, v149
	v_cndmask_b32_e64 v148, v148, v151, s[4:5]
	v_add_f32_e32 v147, 1.0, v147
	v_rcp_f32_e32 v147, v147
	v_cndmask_b32_e64 v149, v149, v152, s[4:5]
	v_mov_b32_e32 v156, v16
	v_mov_b32_e32 v154, v17
	v_mul_f32_e32 v147, v146, v147
	v_cndmask_b32_e64 v147, v147, v146, s[4:5]
	v_cvt_pk_bf16_f32 v146, v150, v148
	v_cvt_pk_bf16_f32 v147, v149, v147
	v_lshlrev_b64 v[148:149], v182, v[190:191]
	v_lshl_add_u64 v[226:227], v[148:149], 1, v[220:221]
	global_store_dwordx2 v[226:227], v[146:147], off
	s_cbranch_vccnz .LBB0_1191
	v_add_u32_e32 v147, 0xffffe0b0, v202
	v_ashrrev_i32_e32 v147, 2, v147
	v_lshl_add_u32 v147, v147, 1, v147
	v_mad_i64_i32 v[148:149], s[2:3], v147, s47, 0
	v_lshl_add_u64 v[148:149], v[148:149], 2, v[208:209]
	v_lshl_add_u64 v[150:151], v[148:149], 0, s[24:25]
	s_lshl_b32 s2, s27, 2
	s_mov_b32 s3, s25
	global_load_dwordx4 v[158:161], v[148:149], off
	s_nop 0
	global_load_dwordx4 v[150:153], v[150:151], off
	v_lshl_add_u64 v[148:149], v[148:149], 0, s[2:3]
	global_load_dwordx4 v[154:157], v[148:149], off
	v_mov_b32_e32 v164, 0
	v_mov_b32_e32 v165, 0
	v_mov_b32_e32 v146, 0
	v_mov_b32_dpp v164, v14 row_ror:1 row_mask:0xf bank_mask:0xf
	v_mov_b32_dpp v165, v14 row_ror:2 row_mask:0xf bank_mask:0xf
	v_mov_b32_dpp v146, v14 row_ror:3 row_mask:0xf bank_mask:0xf
	v_cmp_lt_i32_e32 vcc, 1, v205
	s_and_saveexec_b64 s[2:3], vcc
	s_xor_b64 s[2:3], exec, s[2:3]
	s_cbranch_execz .LBB0_1154
	v_cmp_gt_i32_e32 vcc, 3, v205
	s_and_saveexec_b64 s[20:21], vcc
	s_cbranch_execz .LBB0_1153
	s_waitcnt vmcnt(0)
	v_mov_b32_e32 v146, v154

; __device__ __forceinline__ unsigned cvt_pk_bf16(float lo, float hi) { unsigned r; asm("v_cvt_pk_bf16_f32 %0, %1, %2" : "=v"(r) : "v"(lo), "v"(hi)); return r; }
; __device__ __forceinline__ float siluf_(float x) { return x * sigmoidf_(x); }
; __device__ __forceinline__ float dpp_ror1(float v) { return __builtin_bit_cast(float, __builtin_amdgcn_update_dpp(0, __builtin_bit_cast(int, v), 0x121, 0xf, 0xf, false)); }
;     __device__ __forceinline__ void operator()(f32x4 (&acc)[2][2][4][2], const pg8::Unit& u, int wr, int wc, int fr, int fq) const {
;     ...
;                 for (int n = 0; n < 2; ++n) { const int ch = ch0 + bj * 128 + 4 * n;
;                     const f32x4 w0 = *(const f32x4*)(cw + ch), w1 = *(const f32x4*)(cw + CW + ch), w2 = *(const f32x4*)(cw + 2 * CW + ch), w3 = *(const f32x4*)(cw + 3 * CW + ch), bb = *(const f32x4*)(cb + ch);
; #pragma unroll
;                     for (int m = 0; m < 4; ++m) { const int row = row0 + ai * 128 + m * 16; const f32x4 g = acc[ai][bj][m][n]; f32x4 p1, p2, p3;
;                         if (prompt) { const f32x4 gp = (m == 0) ? hal[n] : acc[ai][bj][m > 0 ? m - 1 : 0][n];
; #pragma unroll
;                             for (int j = 0; j < 4; ++j) { p1[j] = dpp_ror1(fr == 15 ? gp[j] : g[j]); p2[j] = dpp_ror2(fr >= 14 ? gp[j] : g[j]); p3[j] = dpp_ror3(fr >= 13 ? gp[j] : g[j]); } }
;                         else { const int t = fr & 3; const float* sp = stp + (size_t)((row - MP) >> 2) * 3 * CW + ch;
;                             const f32x4 b0 = *(const f32x4*)sp, b1 = *(const f32x4*)(sp + CW), b2 = *(const f32x4*)(sp + 2 * CW);
; #pragma unroll
;                             for (int j = 0; j < 4; ++j) { const float r1 = dpp_ror1(g[j]), r2 = dpp_ror2(g[j]), r3 = dpp_ror3(g[j]);
;                                 p1[j] = t >= 1 ? r1 : b2[j]; p2[j] = t >= 2 ? r2 : (t == 1 ? b2[j] : b1[j]); p3[j] = t >= 3 ? r3 : (t == 2 ? b2[j] : (t == 1 ? b1[j] : b0[j])); } }
;                         float o[4];
; #pragma unroll
;                         for (int j = 0; j < 4; ++j) { const float y = bb[j] + w0[j] * p3[j] + w1[j] * p2[j] + w2[j] * p1[j] + w3[j] * g[j]; o[j] = is_rg ? y : siluf_(y); }
;                         u32x2 w; w.x = cvt_pk_bf16(o[0], o[1]); w.y = cvt_pk_bf16(o[2], o[3]);
;                         *(u32x2*)(dst + (size_t)row * ld + bj * 128 + 4 * n) = w; }
.LBB0_1193:
	v_mov_b32_e32 v228, v150
	v_mov_b32_e32 v229, v146
	v_pk_mul_f32 v[166:167], v[166:167], v[228:229]
	v_mov_b32_e32 v173, v158
	v_add_f32_e32 v142, v142, v167
	v_add_f32_e32 v142, v166, v142
	v_pk_mul_f32 v[166:167], v[168:169], v[172:173]
	v_mov_b32_e32 v165, v159
	v_add_f32_e32 v142, v167, v142
	v_add_f32_e32 v142, v166, v142
	v_mul_f32_e32 v146, 0xbfb8aa3b, v142
	v_exp_f32_e32 v146, v146
	v_pk_mul_f32 v[134:135], v[134:135], v[164:165]
	v_mov_b32_e32 v157, v160
	v_mov_b32_e32 v155, v161
	v_add_f32_e32 v146, 1.0, v146
	v_rcp_f32_e32 v150, v146
	v_mov_b32_e32 v146, v151
	v_pk_mul_f32 v[138:139], v[138:139], v[146:147]
	s_mov_b64 s[2:3], -1
	v_add_f32_e32 v139, v143, v139
	v_add_f32_e32 v138, v138, v139
	v_add_f32_e32 v135, v135, v138
	v_add_f32_e32 v138, v134, v135
	v_mul_f32_e32 v134, 0xbfb8aa3b, v138
	v_exp_f32_e32 v134, v134
	v_mul_f32_e32 v135, v142, v150
	v_cndmask_b32_e64 v139, v135, v142, s[4:5]
	v_mov_b32_e32 v135, v148
	v_add_f32_e32 v134, 1.0, v134
	v_rcp_f32_e32 v142, v134
	v_mov_b32_e32 v134, v152
	v_pk_mul_f32 v[134:135], v[162:163], v[134:135]
	v_mov_b32_e32 v148, v153
	v_add_f32_e32 v135, v144, v135
	v_add_f32_e32 v143, v134, v135
	v_pk_mul_f32 v[134:135], v[170:171], v[156:157]
	s_and_b64 vcc, exec, s[18:19]
	v_add_f32_e32 v135, v135, v143
	v_add_f32_e32 v143, v134, v135
	v_mul_f32_e32 v134, 0xbfb8aa3b, v143
	v_exp_f32_e32 v144, v134
	v_pk_mul_f32 v[134:135], v[140:141], v[148:149]
	v_mov_b32_e32 v230, v58
	v_add_f32_e32 v135, v145, v135
	v_add_f32_e32 v140, v134, v135
	v_pk_mul_f32 v[134:135], v[136:137], v[154:155]
	v_add_f32_e32 v137, 1.0, v144
	v_add_f32_e32 v135, v135, v140
	v_add_f32_e32 v134, v134, v135
	v_mul_f32_e32 v135, 0xbfb8aa3b, v134
	v_exp_f32_e32 v135, v135
	v_rcp_f32_e32 v137, v137
	v_mul_f32_e32 v136, v138, v142
	v_cndmask_b32_e64 v136, v136, v138, s[4:5]
	v_add_f32_e32 v135, 1.0, v135
	v_rcp_f32_e32 v135, v135
	v_mul_f32_e32 v137, v143, v137
	v_cndmask_b32_e64 v137, v137, v143, s[4:5]
	v_mov_b32_e32 v228, v59
	v_mul_f32_e32 v135, v134, v135
	v_cndmask_b32_e64 v135, v135, v134, s[4:5]
	v_cvt_pk_bf16_f32 v134, v139, v136
	v_cvt_pk_bf16_f32 v135, v137, v135
	v_lshlrev_b64 v[136:137], v182, v[188:189]
	v_lshl_add_u64 v[220:221], v[136:137], 1, v[220:221]
	global_store_dwordx2 v[220:221], v[134:135], off
	global_load_dwordx4 v[138:141], v[210:211], off offset:16
	global_load_dwordx4 v[150:153], v[212:213], off offset:16
	global_load_dwordx4 v[134:137], v[214:215], off offset:16
	global_load_dwordx4 v[146:149], v[216:217], off offset:16
	global_load_dwordx4 v[142:145], v[218:219], off offset:16
	v_mov_b32_e32 v172, v60
	v_mov_b32_e32 v170, v61
	s_cbranch_vccnz .LBB0_1235
	v_add_u32_e32 v155, 0xffffe080, v202
	v_ashrrev_i32_e32 v155, 2, v155
	v_lshl_add_u32 v155, v155, 1, v155
	v_mad_i64_i32 v[156:157], s[2:3], v155, s47, 0
	v_lshl_add_u64 v[156:157], v[156:157], 2, v[208:209]
	v_lshl_add_u64 v[158:159], v[156:157], 0, s[24:25]
	s_lshl_b32 s2, s27, 2
	s_mov_b32 s3, s25
	global_load_dwordx4 v[166:169], v[156:157], off offset:16
	s_nop 0
	global_load_dwordx4 v[158:161], v[158:159], off offset:16
	v_lshl_add_u64 v[156:157], v[156:157], 0, s[2:3]
	global_load_dwordx4 v[162:165], v[156:157], off offset:16
	v_mov_b32_e32 v170, 0
	v_mov_b32_e32 v171, 0
	v_mov_b32_e32 v154, 0
	v_mov_b32_dpp v170, v58 row_ror:1 row_mask:0xf bank_mask:0xf
	v_mov_b32_dpp v171, v58 row_ror:2 row_mask:0xf bank_mask:0xf
	v_mov_b32_dpp v154, v58 row_ror:3 row_mask:0xf bank_mask:0xf
	v_cmp_lt_i32_e32 vcc, 1, v205
	s_and_saveexec_b64 s[2:3], vcc
	s_xor_b64 s[2:3], exec, s[2:3]
	s_cbranch_execz .LBB0_1198
	v_cmp_gt_i32_e32 vcc, 3, v205
	s_and_saveexec_b64 s[20:21], vcc
	s_cbranch_execz .LBB0_1197
	s_waitcnt vmcnt(0)
	v_mov_b32_e32 v154, v162

; __device__ __forceinline__ unsigned cvt_pk_bf16(float lo, float hi) { unsigned r; asm("v_cvt_pk_bf16_f32 %0, %1, %2" : "=v"(r) : "v"(lo), "v"(hi)); return r; }
; __device__ __forceinline__ float siluf_(float x) { return x * sigmoidf_(x); }
; __device__ __forceinline__ float dpp_ror1(float v) { return __builtin_bit_cast(float, __builtin_amdgcn_update_dpp(0, __builtin_bit_cast(int, v), 0x121, 0xf, 0xf, false)); }
;     __device__ __forceinline__ void operator()(f32x4 (&acc)[2][2][4][2], const pg8::Unit& u, int wr, int wc, int fr, int fq) const {
;     ...
;                 for (int n = 0; n < 2; ++n) { const int ch = ch0 + bj * 128 + 4 * n;
;                     const f32x4 w0 = *(const f32x4*)(cw + ch), w1 = *(const f32x4*)(cw + CW + ch), w2 = *(const f32x4*)(cw + 2 * CW + ch), w3 = *(const f32x4*)(cw + 3 * CW + ch), bb = *(const f32x4*)(cb + ch);
; #pragma unroll
;                     for (int m = 0; m < 4; ++m) { const int row = row0 + ai * 128 + m * 16; const f32x4 g = acc[ai][bj][m][n]; f32x4 p1, p2, p3;
;                         if (prompt) { const f32x4 gp = (m == 0) ? hal[n] : acc[ai][bj][m > 0 ? m - 1 : 0][n];
; #pragma unroll
;                             for (int j = 0; j < 4; ++j) { p1[j] = dpp_ror1(fr == 15 ? gp[j] : g[j]); p2[j] = dpp_ror2(fr >= 14 ? gp[j] : g[j]); p3[j] = dpp_ror3(fr >= 13 ? gp[j] : g[j]); } }
;                         else { const int t = fr & 3; const float* sp = stp + (size_t)((row - MP) >> 2) * 3 * CW + ch;
;                             const f32x4 b0 = *(const f32x4*)sp, b1 = *(const f32x4*)(sp + CW), b2 = *(const f32x4*)(sp + 2 * CW);
; #pragma unroll
;                             for (int j = 0; j < 4; ++j) { const float r1 = dpp_ror1(g[j]), r2 = dpp_ror2(g[j]), r3 = dpp_ror3(g[j]);
;                                 p1[j] = t >= 1 ? r1 : b2[j]; p2[j] = t >= 2 ? r2 : (t == 1 ? b2[j] : b1[j]); p3[j] = t >= 3 ? r3 : (t == 2 ? b2[j] : (t == 1 ? b1[j] : b0[j])); } }
;                         float o[4];
; #pragma unroll
;                         for (int j = 0; j < 4; ++j) { const float y = bb[j] + w0[j] * p3[j] + w1[j] * p2[j] + w2[j] * p1[j] + w3[j] * g[j]; o[j] = is_rg ? y : siluf_(y); }
;                         u32x2 w; w.x = cvt_pk_bf16(o[0], o[1]); w.y = cvt_pk_bf16(o[2], o[3]);
;                         *(u32x2*)(dst + (size_t)row * ld + bj * 128 + 4 * n) = w; }
.LBB0_1237:
	s_waitcnt vmcnt(0)
	v_mov_b32_e32 v162, v150
	v_mov_b32_e32 v163, v138
	v_mov_b32_e32 v130, v158
	v_mov_b32_e32 v131, v154
	v_pk_mul_f32 v[130:131], v[162:163], v[130:131]
	v_mov_b32_e32 v164, v146
	v_add_f32_e32 v131, v142, v131
	v_mov_b32_e32 v165, v134
	v_mov_b32_e32 v231, v166
	v_add_f32_e32 v132, v130, v131
	v_pk_mul_f32 v[130:131], v[164:165], v[230:231]
	v_mov_b32_e32 v138, v151
	v_add_f32_e32 v131, v131, v132
	v_add_f32_e32 v132, v130, v131
	v_mul_f32_e32 v130, 0xbfb8aa3b, v132
	v_exp_f32_e32 v130, v130
	v_mov_b32_e32 v154, v159
	v_mov_b32_e32 v134, v147
	v_mov_b32_e32 v229, v167
	v_add_f32_e32 v130, 1.0, v130
	v_rcp_f32_e32 v133, v130
	v_pk_mul_f32 v[130:131], v[138:139], v[154:155]
	v_mov_b32_e32 v158, v152
	v_add_f32_e32 v131, v143, v131
	v_add_f32_e32 v146, v130, v131
	v_pk_mul_f32 v[130:131], v[134:135], v[228:229]
	v_mov_b32_e32 v159, v140
	v_add_f32_e32 v131, v131, v146
	v_add_f32_e32 v146, v130, v131
	v_mul_f32_e32 v130, 0xbfb8aa3b, v146
	v_exp_f32_e32 v130, v130
	v_mul_f32_e32 v131, v132, v133
	v_cndmask_b32_e64 v132, v131, v132, s[4:5]
	v_mov_b32_e32 v131, v156
	v_add_f32_e32 v130, 1.0, v130
	v_rcp_f32_e32 v133, v130
	v_mov_b32_e32 v130, v160
	v_pk_mul_f32 v[130:131], v[158:159], v[130:131]
	v_mov_b32_e32 v166, v148
	v_add_f32_e32 v131, v144, v131
	v_mov_b32_e32 v167, v136
	v_mov_b32_e32 v173, v168
	v_add_f32_e32 v140, v130, v131
	v_pk_mul_f32 v[130:131], v[166:167], v[172:173]
	v_mov_b32_e32 v156, v161
	v_add_f32_e32 v131, v131, v140
	v_add_f32_e32 v147, v130, v131
	v_mul_f32_e32 v130, 0xbfb8aa3b, v147
	v_mov_b32_e32 v140, v153
	v_exp_f32_e32 v148, v130
	v_pk_mul_f32 v[130:131], v[140:141], v[156:157]
	v_mov_b32_e32 v136, v149
	v_add_f32_e32 v131, v145, v131
	v_mov_b32_e32 v171, v169
	v_add_f32_e32 v150, v130, v131
	v_pk_mul_f32 v[130:131], v[136:137], v[170:171]
	v_add_f32_e32 v148, 1.0, v148
	v_add_f32_e32 v131, v131, v150
	v_add_f32_e32 v130, v130, v131
	v_mul_f32_e32 v131, 0xbfb8aa3b, v130
	v_exp_f32_e32 v131, v131
	v_rcp_f32_e32 v148, v148
	v_mul_f32_e32 v133, v146, v133
	v_cndmask_b32_e64 v133, v133, v146, s[4:5]
	v_add_f32_e32 v131, 1.0, v131
	v_rcp_f32_e32 v131, v131
	v_mul_f32_e32 v146, v147, v148
	v_cndmask_b32_e64 v146, v146, v147, s[4:5]
	s_mov_b64 s[2:3], -1
	v_mul_f32_e32 v131, v130, v131
	v_cndmask_b32_e64 v131, v131, v130, s[4:5]
	v_cvt_pk_bf16_f32 v130, v132, v133
	v_cvt_pk_bf16_f32 v131, v146, v131
	s_and_b64 vcc, exec, s[18:19]
	v_mov_b32_e32 v168, v42
	v_mov_b32_e32 v160, v43
	v_mov_b32_e32 v152, v44
	v_mov_b32_e32 v150, v45
	global_store_dwordx2 v[222:223], v[130:131], off offset:8
	s_cbranch_vccnz .LBB0_1279
	v_add_u32_e32 v131, 0xffffe090, v202
	v_ashrrev_i32_e32 v131, 2, v131
	v_lshl_add_u32 v131, v131, 1, v131
	v_mad_i64_i32 v[132:133], s[2:3], v131, s47, 0
	v_lshl_add_u64 v[132:133], v[132:133], 2, v[208:209]
	v_lshl_add_u64 v[146:147], v[132:133], 0, s[24:25]
	s_lshl_b32 s2, s27, 2
	s_mov_b32 s3, s25
	global_load_dwordx4 v[154:157], v[132:133], off offset:16
	s_nop 0
	global_load_dwordx4 v[146:149], v[146:147], off offset:16
	v_lshl_add_u64 v[132:133], v[132:133], 0, s[2:3]
	global_load_dwordx4 v[150:153], v[132:133], off offset:16
	v_mov_b32_e32 v160, 0
	v_mov_b32_e32 v161, 0
	v_mov_b32_e32 v130, 0
	v_mov_b32_dpp v160, v42 row_ror:1 row_mask:0xf bank_mask:0xf
	v_mov_b32_dpp v161, v42 row_ror:2 row_mask:0xf bank_mask:0xf
	v_mov_b32_dpp v130, v42 row_ror:3 row_mask:0xf bank_mask:0xf
	v_cmp_lt_i32_e32 vcc, 1, v205
	s_and_saveexec_b64 s[2:3], vcc
	s_xor_b64 s[2:3], exec, s[2:3]
	s_cbranch_execz .LBB0_1242
	v_cmp_gt_i32_e32 vcc, 3, v205
	s_and_saveexec_b64 s[20:21], vcc
	s_cbranch_execz .LBB0_1241
	s_waitcnt vmcnt(0)
	v_mov_b32_e32 v130, v150

; __device__ __forceinline__ unsigned cvt_pk_bf16(float lo, float hi) { unsigned r; asm("v_cvt_pk_bf16_f32 %0, %1, %2" : "=v"(r) : "v"(lo), "v"(hi)); return r; }
; __device__ __forceinline__ float siluf_(float x) { return x * sigmoidf_(x); }
; __device__ __forceinline__ float dpp_ror1(float v) { return __builtin_bit_cast(float, __builtin_amdgcn_update_dpp(0, __builtin_bit_cast(int, v), 0x121, 0xf, 0xf, false)); }
;     __device__ __forceinline__ void operator()(f32x4 (&acc)[2][2][4][2], const pg8::Unit& u, int wr, int wc, int fr, int fq) const {
;     ...
;                 for (int n = 0; n < 2; ++n) { const int ch = ch0 + bj * 128 + 4 * n;
;                     const f32x4 w0 = *(const f32x4*)(cw + ch), w1 = *(const f32x4*)(cw + CW + ch), w2 = *(const f32x4*)(cw + 2 * CW + ch), w3 = *(const f32x4*)(cw + 3 * CW + ch), bb = *(const f32x4*)(cb + ch);
; #pragma unroll
;                     for (int m = 0; m < 4; ++m) { const int row = row0 + ai * 128 + m * 16; const f32x4 g = acc[ai][bj][m][n]; f32x4 p1, p2, p3;
;                         if (prompt) { const f32x4 gp = (m == 0) ? hal[n] : acc[ai][bj][m > 0 ? m - 1 : 0][n];
; #pragma unroll
;                             for (int j = 0; j < 4; ++j) { p1[j] = dpp_ror1(fr == 15 ? gp[j] : g[j]); p2[j] = dpp_ror2(fr >= 14 ? gp[j] : g[j]); p3[j] = dpp_ror3(fr >= 13 ? gp[j] : g[j]); } }
;                         else { const int t = fr & 3; const float* sp = stp + (size_t)((row - MP) >> 2) * 3 * CW + ch;
;                             const f32x4 b0 = *(const f32x4*)sp, b1 = *(const f32x4*)(sp + CW), b2 = *(const f32x4*)(sp + 2 * CW);
; #pragma unroll
;                             for (int j = 0; j < 4; ++j) { const float r1 = dpp_ror1(g[j]), r2 = dpp_ror2(g[j]), r3 = dpp_ror3(g[j]);
;                                 p1[j] = t >= 1 ? r1 : b2[j]; p2[j] = t >= 2 ? r2 : (t == 1 ? b2[j] : b1[j]); p3[j] = t >= 3 ? r3 : (t == 2 ? b2[j] : (t == 1 ? b1[j] : b0[j])); } }
;                         float o[4];
; #pragma unroll
;                         for (int j = 0; j < 4; ++j) { const float y = bb[j] + w0[j] * p3[j] + w1[j] * p2[j] + w2[j] * p1[j] + w3[j] * g[j]; o[j] = is_rg ? y : siluf_(y); }
;                         u32x2 w; w.x = cvt_pk_bf16(o[0], o[1]); w.y = cvt_pk_bf16(o[2], o[3]);
;                         *(u32x2*)(dst + (size_t)row * ld + bj * 128 + 4 * n) = w; }
.LBB0_1281:
	v_mov_b32_e32 v170, v146
	v_mov_b32_e32 v171, v130
	v_pk_mul_f32 v[170:171], v[162:163], v[170:171]
	v_mov_b32_e32 v169, v154
	v_add_f32_e32 v130, v142, v171
	v_add_f32_e32 v130, v170, v130
	v_pk_mul_f32 v[168:169], v[164:165], v[168:169]
	v_mov_b32_e32 v161, v155
	v_add_f32_e32 v130, v169, v130
	v_add_f32_e32 v146, v168, v130
	v_mul_f32_e32 v130, 0xbfb8aa3b, v146
	v_exp_f32_e32 v130, v130
	v_mov_b32_e32 v153, v156
	s_mov_b64 s[2:3], -1
	s_and_b64 vcc, exec, s[18:19]
	v_add_f32_e32 v130, 1.0, v130
	v_rcp_f32_e32 v151, v130
	v_mov_b32_e32 v130, v147
	v_pk_mul_f32 v[130:131], v[138:139], v[130:131]
	v_mov_b32_e32 v168, v30
	v_add_f32_e32 v131, v143, v131
	v_add_f32_e32 v147, v130, v131
	v_pk_mul_f32 v[130:131], v[134:135], v[160:161]
	v_mov_b32_e32 v160, v31
	v_add_f32_e32 v131, v131, v147
	v_add_f32_e32 v147, v130, v131
	v_mul_f32_e32 v130, 0xbfb8aa3b, v147
	v_exp_f32_e32 v130, v130
	v_mul_f32_e32 v131, v146, v151
	v_cndmask_b32_e64 v146, v131, v146, s[4:5]
	v_mov_b32_e32 v131, v132
	v_add_f32_e32 v130, 1.0, v130
	v_rcp_f32_e32 v154, v130
	v_mov_b32_e32 v130, v148
	v_pk_mul_f32 v[130:131], v[158:159], v[130:131]
	v_mov_b32_e32 v151, v157
	v_add_f32_e32 v131, v144, v131
	v_add_f32_e32 v132, v130, v131
	v_pk_mul_f32 v[130:131], v[166:167], v[152:153]
	s_nop 0
	v_add_f32_e32 v131, v131, v132
	v_add_f32_e32 v148, v130, v131
	v_mul_f32_e32 v130, 0xbfb8aa3b, v148
	v_mov_b32_e32 v132, v149
	v_exp_f32_e32 v152, v130
	v_pk_mul_f32 v[130:131], v[140:141], v[132:133]
	v_add_f32_e32 v133, 1.0, v152
	v_add_f32_e32 v131, v145, v131
	v_add_f32_e32 v132, v130, v131
	v_pk_mul_f32 v[130:131], v[136:137], v[150:151]
	v_rcp_f32_e32 v133, v133
	v_add_f32_e32 v131, v131, v132
	v_add_f32_e32 v130, v130, v131
	v_mul_f32_e32 v131, 0xbfb8aa3b, v130
	v_exp_f32_e32 v131, v131
	v_mul_f32_e32 v132, v147, v154
	v_mul_f32_e32 v133, v148, v133
	v_cndmask_b32_e64 v132, v132, v147, s[4:5]
	v_add_f32_e32 v131, 1.0, v131
	v_rcp_f32_e32 v131, v131
	v_cndmask_b32_e64 v133, v133, v148, s[4:5]
	v_mov_b32_e32 v152, v32
	v_mov_b32_e32 v150, v33
	v_mul_f32_e32 v131, v130, v131
	v_cndmask_b32_e64 v131, v131, v130, s[4:5]
	v_cvt_pk_bf16_f32 v130, v146, v132
	v_cvt_pk_bf16_f32 v131, v133, v131
	global_store_dwordx2 v[224:225], v[130:131], off offset:8
	s_cbranch_vccnz .LBB0_1323
	v_add_u32_e32 v131, 0xffffe0a0, v202
	v_ashrrev_i32_e32 v131, 2, v131
	v_lshl_add_u32 v131, v131, 1, v131
	v_mad_i64_i32 v[132:133], s[2:3], v131, s47, 0
	v_lshl_add_u64 v[132:133], v[132:133], 2, v[208:209]
	v_lshl_add_u64 v[146:147], v[132:133], 0, s[24:25]
	s_lshl_b32 s2, s27, 2
	s_mov_b32 s3, s25
	global_load_dwordx4 v[154:157], v[132:133], off offset:16
	s_nop 0
	global_load_dwordx4 v[146:149], v[146:147], off offset:16
	v_lshl_add_u64 v[132:133], v[132:133], 0, s[2:3]
	global_load_dwordx4 v[150:153], v[132:133], off offset:16
	v_mov_b32_e32 v160, 0
	v_mov_b32_e32 v161, 0
	v_mov_b32_e32 v130, 0
	v_mov_b32_dpp v160, v30 row_ror:1 row_mask:0xf bank_mask:0xf
	v_mov_b32_dpp v161, v30 row_ror:2 row_mask:0xf bank_mask:0xf
	v_mov_b32_dpp v130, v30 row_ror:3 row_mask:0xf bank_mask:0xf
	v_cmp_lt_i32_e32 vcc, 1, v205
	s_and_saveexec_b64 s[2:3], vcc
	s_xor_b64 s[2:3], exec, s[2:3]
	s_cbranch_execz .LBB0_1286
	v_cmp_gt_i32_e32 vcc, 3, v205
	s_and_saveexec_b64 s[20:21], vcc
	s_cbranch_execz .LBB0_1285
	s_waitcnt vmcnt(0)
	v_mov_b32_e32 v130, v150

; __device__ __forceinline__ unsigned cvt_pk_bf16(float lo, float hi) { unsigned r; asm("v_cvt_pk_bf16_f32 %0, %1, %2" : "=v"(r) : "v"(lo), "v"(hi)); return r; }
; __device__ __forceinline__ float siluf_(float x) { return x * sigmoidf_(x); }
; __device__ __forceinline__ float dpp_ror1(float v) { return __builtin_bit_cast(float, __builtin_amdgcn_update_dpp(0, __builtin_bit_cast(int, v), 0x121, 0xf, 0xf, false)); }
;     __device__ __forceinline__ void operator()(f32x4 (&acc)[2][2][4][2], const pg8::Unit& u, int wr, int wc, int fr, int fq) const {
;     ...
;                 for (int n = 0; n < 2; ++n) { const int ch = ch0 + bj * 128 + 4 * n;
;                     const f32x4 w0 = *(const f32x4*)(cw + ch), w1 = *(const f32x4*)(cw + CW + ch), w2 = *(const f32x4*)(cw + 2 * CW + ch), w3 = *(const f32x4*)(cw + 3 * CW + ch), bb = *(const f32x4*)(cb + ch);
; #pragma unroll
;                     for (int m = 0; m < 4; ++m) { const int row = row0 + ai * 128 + m * 16; const f32x4 g = acc[ai][bj][m][n]; f32x4 p1, p2, p3;
;                         if (prompt) { const f32x4 gp = (m == 0) ? hal[n] : acc[ai][bj][m > 0 ? m - 1 : 0][n];
; #pragma unroll
;                             for (int j = 0; j < 4; ++j) { p1[j] = dpp_ror1(fr == 15 ? gp[j] : g[j]); p2[j] = dpp_ror2(fr >= 14 ? gp[j] : g[j]); p3[j] = dpp_ror3(fr >= 13 ? gp[j] : g[j]); } }
;                         else { const int t = fr & 3; const float* sp = stp + (size_t)((row - MP) >> 2) * 3 * CW + ch;
;                             const f32x4 b0 = *(const f32x4*)sp, b1 = *(const f32x4*)(sp + CW), b2 = *(const f32x4*)(sp + 2 * CW);
; #pragma unroll
;                             for (int j = 0; j < 4; ++j) { const float r1 = dpp_ror1(g[j]), r2 = dpp_ror2(g[j]), r3 = dpp_ror3(g[j]);
;                                 p1[j] = t >= 1 ? r1 : b2[j]; p2[j] = t >= 2 ? r2 : (t == 1 ? b2[j] : b1[j]); p3[j] = t >= 3 ? r3 : (t == 2 ? b2[j] : (t == 1 ? b1[j] : b0[j])); } }
;                         float o[4];
; #pragma unroll
;                         for (int j = 0; j < 4; ++j) { const float y = bb[j] + w0[j] * p3[j] + w1[j] * p2[j] + w2[j] * p1[j] + w3[j] * g[j]; o[j] = is_rg ? y : siluf_(y); }
;                         u32x2 w; w.x = cvt_pk_bf16(o[0], o[1]); w.y = cvt_pk_bf16(o[2], o[3]);
;                         *(u32x2*)(dst + (size_t)row * ld + bj * 128 + 4 * n) = w; }
.LBB0_1325:
	v_mov_b32_e32 v170, v146
	v_mov_b32_e32 v171, v130
	v_pk_mul_f32 v[170:171], v[162:163], v[170:171]
	v_mov_b32_e32 v169, v154
	v_add_f32_e32 v130, v142, v171
	v_add_f32_e32 v130, v170, v130
	v_pk_mul_f32 v[168:169], v[164:165], v[168:169]
	v_mov_b32_e32 v161, v155
	v_add_f32_e32 v130, v169, v130
	v_add_f32_e32 v146, v168, v130
	v_mul_f32_e32 v130, 0xbfb8aa3b, v146
	v_exp_f32_e32 v130, v130
	v_mov_b32_e32 v153, v156
	s_mov_b64 s[2:3], -1
	s_and_b64 vcc, exec, s[18:19]
	v_add_f32_e32 v130, 1.0, v130
	v_rcp_f32_e32 v151, v130
	v_mov_b32_e32 v130, v147
	v_pk_mul_f32 v[130:131], v[138:139], v[130:131]
	v_mov_b32_e32 v168, v10
	v_add_f32_e32 v131, v143, v131
	v_add_f32_e32 v147, v130, v131
	v_pk_mul_f32 v[130:131], v[134:135], v[160:161]
	v_mov_b32_e32 v160, v11
	v_add_f32_e32 v131, v131, v147
	v_add_f32_e32 v147, v130, v131
	v_mul_f32_e32 v130, 0xbfb8aa3b, v147
	v_exp_f32_e32 v130, v130
	v_mul_f32_e32 v131, v146, v151
	v_cndmask_b32_e64 v146, v131, v146, s[4:5]
	v_mov_b32_e32 v131, v132
	v_add_f32_e32 v130, 1.0, v130
	v_rcp_f32_e32 v154, v130
	v_mov_b32_e32 v130, v148
	v_pk_mul_f32 v[130:131], v[158:159], v[130:131]
	v_mov_b32_e32 v151, v157
	v_add_f32_e32 v131, v144, v131
	v_add_f32_e32 v132, v130, v131
	v_pk_mul_f32 v[130:131], v[166:167], v[152:153]
	s_nop 0
	v_add_f32_e32 v131, v131, v132
	v_add_f32_e32 v148, v130, v131
	v_mul_f32_e32 v130, 0xbfb8aa3b, v148
	v_mov_b32_e32 v132, v149
	v_exp_f32_e32 v152, v130
	v_pk_mul_f32 v[130:131], v[140:141], v[132:133]
	v_add_f32_e32 v133, 1.0, v152
	v_add_f32_e32 v131, v145, v131
	v_add_f32_e32 v132, v130, v131
	v_pk_mul_f32 v[130:131], v[136:137], v[150:151]
	v_rcp_f32_e32 v133, v133
	v_add_f32_e32 v131, v131, v132
	v_add_f32_e32 v130, v130, v131
	v_mul_f32_e32 v131, 0xbfb8aa3b, v130
	v_exp_f32_e32 v131, v131
	v_mul_f32_e32 v132, v147, v154
	v_mul_f32_e32 v133, v148, v133
	v_cndmask_b32_e64 v132, v132, v147, s[4:5]
	v_add_f32_e32 v131, 1.0, v131
	v_rcp_f32_e32 v131, v131
	v_cndmask_b32_e64 v133, v133, v148, s[4:5]
	v_mov_b32_e32 v152, v12
	v_mov_b32_e32 v150, v13
	v_mul_f32_e32 v131, v130, v131
	v_cndmask_b32_e64 v131, v131, v130, s[4:5]
	v_cvt_pk_bf16_f32 v130, v146, v132
	v_cvt_pk_bf16_f32 v131, v133, v131
	global_store_dwordx2 v[226:227], v[130:131], off offset:8
	s_cbranch_vccnz .LBB0_1367
	v_add_u32_e32 v131, 0xffffe0b0, v202
	v_ashrrev_i32_e32 v131, 2, v131
	v_lshl_add_u32 v131, v131, 1, v131
	v_mad_i64_i32 v[132:133], s[2:3], v131, s47, 0
	v_lshl_add_u64 v[132:133], v[132:133], 2, v[208:209]
	v_lshl_add_u64 v[146:147], v[132:133], 0, s[24:25]
	s_lshl_b32 s2, s27, 2
	s_mov_b32 s3, s25
	global_load_dwordx4 v[154:157], v[132:133], off offset:16
	s_nop 0
	global_load_dwordx4 v[146:149], v[146:147], off offset:16
	v_lshl_add_u64 v[132:133], v[132:133], 0, s[2:3]
	global_load_dwordx4 v[150:153], v[132:133], off offset:16
	v_mov_b32_e32 v160, 0
	v_mov_b32_e32 v161, 0
	v_mov_b32_e32 v130, 0
	v_mov_b32_dpp v160, v10 row_ror:1 row_mask:0xf bank_mask:0xf
	v_mov_b32_dpp v161, v10 row_ror:2 row_mask:0xf bank_mask:0xf
	v_mov_b32_dpp v130, v10 row_ror:3 row_mask:0xf bank_mask:0xf
	v_cmp_lt_i32_e32 vcc, 1, v205
	s_and_saveexec_b64 s[2:3], vcc
	s_xor_b64 s[2:3], exec, s[2:3]
	s_cbranch_execz .LBB0_1330
	v_cmp_gt_i32_e32 vcc, 3, v205
	s_and_saveexec_b64 s[20:21], vcc
	s_cbranch_execz .LBB0_1329
	s_waitcnt vmcnt(0)
	v_mov_b32_e32 v130, v150

; #define LAS __attribute__((address_space(3)))
;     __device__ __forceinline__ void operator()(f32x4 (&acc)[2][2][4][2], const pg8::Unit& u, int wr, int wc, int fr, int fq) const {
;     ...
;                 f32x4 hal[2];
;                 hal[0] = hal[1] = (f32x4){0.f, 0.f, 0.f, 0.f};
;                 if (prompt) { const int b = 2 * ai + wr;
;                     if (b >= 1) { if (fr >= 13) {
; #pragma unroll
;                             for (int n = 0; n < 2; ++n) hal[n] = *(const LAS f32x4*)(H + ((b - 1) * 3 + (fr - 13)) * 256 + bj * 128 + cl0 + 4 * n); } }
;                     else if ((u.pm & 7) != 0) { unsigned* fl = HFLAG + (tile - 37); unsigned sp = 0;
;                         while ((unsigned)__builtin_amdgcn_readfirstlane(__hip_atomic_load(fl, __ATOMIC_RELAXED, __HIP_MEMORY_SCOPE_AGENT)) < 4u) { __builtin_amdgcn_s_sleep(2);
;                             if ((++sp & 1023u) == 0u) { if (__hip_atomic_load(tmo, __ATOMIC_RELAXED, __HIP_MEMORY_SCOPE_AGENT) != 0u) break; if (sp > (1u << 22)) { __hip_atomic_store(tmo, 1u, __ATOMIC_RELAXED, __HIP_MEMORY_SCOPE_AGENT); break; } } }
;                         if (fr >= 13) { const unsigned long long* hp = HALO + ((size_t)(tile - 37) * 3 + (fr - 13)) * 128 + (cl0 >> 1) + bj * 64;
; #pragma unroll
;                             for (int n = 0; n < 2; ++n) { const unsigned long long a2 = __hip_atomic_load(hp + 2 * n, __ATOMIC_RELAXED, __HIP_MEMORY_SCOPE_AGENT), b2 = __hip_atomic_load(hp + 2 * n + 1, __ATOMIC_RELAXED, __HIP_MEMORY_SCOPE_AGENT);
;                                 hal[n] = (f32x4){__uint_as_float((unsigned)a2), __uint_as_float((unsigned)(a2 >> 32)), __uint_as_float((unsigned)b2), __uint_as_float((unsigned)(b2 >> 32))}; } } } }
; #pragma unroll
;                 for (int n = 0; n < 2; ++n) { const int ch = ch0 + bj * 128 + 4 * n;
;                     const f32x4 w0 = *(const f32x4*)(cw + ch), w1 = *(const f32x4*)(cw + CW + ch), w2 = *(const f32x4*)(cw + 2 * CW + ch), w3 = *(const f32x4*)(cw + 3 * CW + ch), bb = *(const f32x4*)(cb + ch);
; #pragma unroll
;                     for (int m = 0; m < 4; ++m) { const int row = row0 + ai * 128 + m * 16; const f32x4 g = acc[ai][bj][m][n]; f32x4 p1, p2, p3;
;                         if (prompt) { const f32x4 gp = (m == 0) ? hal[n] : acc[ai][bj][m > 0 ? m - 1 : 0][n];
; #pragma unroll
.LBB0_1369:
	v_mov_b32_e32 v170, v146
	v_mov_b32_e32 v171, v130
	v_pk_mul_f32 v[162:163], v[162:163], v[170:171]
	v_mov_b32_e32 v169, v154
	v_add_f32_e32 v130, v142, v163
	v_add_f32_e32 v130, v162, v130
	v_pk_mul_f32 v[162:163], v[164:165], v[168:169]
	v_mov_b32_e32 v161, v155
	v_add_f32_e32 v130, v163, v130
	v_add_f32_e32 v142, v162, v130
	v_mul_f32_e32 v130, 0xbfb8aa3b, v142
	v_exp_f32_e32 v130, v130
	v_mov_b32_e32 v153, v156
	v_mov_b32_e32 v151, v157
	v_add_f32_e32 v130, 1.0, v130
	v_rcp_f32_e32 v146, v130
	v_mov_b32_e32 v130, v147
	v_pk_mul_f32 v[130:131], v[138:139], v[130:131]
	s_nop 0
	v_add_f32_e32 v131, v143, v131
	v_add_f32_e32 v138, v130, v131
	v_pk_mul_f32 v[130:131], v[134:135], v[160:161]
	v_mov_b32_e32 v160, 0
	v_add_f32_e32 v131, v131, v138
	v_add_f32_e32 v134, v130, v131
	v_mul_f32_e32 v130, 0xbfb8aa3b, v134
	v_exp_f32_e32 v130, v130
	v_mul_f32_e32 v131, v142, v146
	v_cndmask_b32_e64 v135, v131, v142, s[4:5]
	v_mov_b32_e32 v131, v132
	v_add_f32_e32 v130, 1.0, v130
	v_rcp_f32_e32 v138, v130
	v_mov_b32_e32 v130, v148
	v_pk_mul_f32 v[130:131], v[158:159], v[130:131]
	v_mov_b32_e32 v158, 0
	v_add_f32_e32 v131, v144, v131
	v_add_f32_e32 v132, v130, v131
	v_pk_mul_f32 v[130:131], v[166:167], v[152:153]
	v_mov_b32_e32 v159, 0
	v_add_f32_e32 v131, v131, v132
	v_add_f32_e32 v139, v130, v131
	v_mul_f32_e32 v130, 0xbfb8aa3b, v139
	v_mov_b32_e32 v132, v149
	v_exp_f32_e32 v142, v130
	v_pk_mul_f32 v[130:131], v[140:141], v[132:133]
	v_mov_b32_e32 v161, 0
	v_add_f32_e32 v131, v145, v131
	v_add_f32_e32 v132, v130, v131
	v_pk_mul_f32 v[130:131], v[136:137], v[150:151]
	v_add_f32_e32 v133, 1.0, v142
	v_add_f32_e32 v131, v131, v132
	v_add_f32_e32 v130, v130, v131
	v_mul_f32_e32 v131, 0xbfb8aa3b, v130
	v_exp_f32_e32 v131, v131
	v_rcp_f32_e32 v133, v133
	v_mul_f32_e32 v132, v134, v138
	v_cndmask_b32_e64 v132, v132, v134, s[4:5]
	v_add_f32_e32 v131, 1.0, v131
	v_rcp_f32_e32 v131, v131
	v_mul_f32_e32 v133, v139, v133
	v_cndmask_b32_e64 v133, v133, v139, s[4:5]
	v_mul_f32_e32 v131, v130, v131
	v_cndmask_b32_e64 v131, v131, v130, s[4:5]
	v_cvt_pk_bf16_f32 v130, v135, v132
	v_cvt_pk_bf16_f32 v131, v133, v131
	global_store_dwordx2 v[220:221], v[130:131], off offset:8
	v_mov_b32_e32 v130, 0
	v_mov_b32_e32 v131, 0
	v_mov_b32_e32 v132, 0
	v_mov_b32_e32 v133, 0
	s_and_saveexec_b64 s[2:3], s[0:1]
	s_cbranch_execz .LBB0_1371
	s_movk_i32 s0, 0xc200
	v_add3_u32 v130, v232, v207, s0
	ds_read_b128 v[158:161], v130
	ds_read_b128 v[130:133], v130 offset:16

; __device__ __forceinline__ unsigned cvt_pk_bf16(float lo, float hi) { unsigned r; asm("v_cvt_pk_bf16_f32 %0, %1, %2" : "=v"(r) : "v"(lo), "v"(hi)); return r; }
; __device__ __forceinline__ float siluf_(float x) { return x * sigmoidf_(x); }
; __device__ __forceinline__ float dpp_ror1(float v) { return __builtin_bit_cast(float, __builtin_amdgcn_update_dpp(0, __builtin_bit_cast(int, v), 0x121, 0xf, 0xf, false)); }
;     __device__ __forceinline__ void operator()(f32x4 (&acc)[2][2][4][2], const pg8::Unit& u, int wr, int wc, int fr, int fq) const {
;     ...
;                 for (int n = 0; n < 2; ++n) { const int ch = ch0 + bj * 128 + 4 * n;
;                     const f32x4 w0 = *(const f32x4*)(cw + ch), w1 = *(const f32x4*)(cw + CW + ch), w2 = *(const f32x4*)(cw + 2 * CW + ch), w3 = *(const f32x4*)(cw + 3 * CW + ch), bb = *(const f32x4*)(cb + ch);
; #pragma unroll
;                     for (int m = 0; m < 4; ++m) { const int row = row0 + ai * 128 + m * 16; const f32x4 g = acc[ai][bj][m][n]; f32x4 p1, p2, p3;
;                         if (prompt) { const f32x4 gp = (m == 0) ? hal[n] : acc[ai][bj][m > 0 ? m - 1 : 0][n];
; #pragma unroll
;                             for (int j = 0; j < 4; ++j) { p1[j] = dpp_ror1(fr == 15 ? gp[j] : g[j]); p2[j] = dpp_ror2(fr >= 14 ? gp[j] : g[j]); p3[j] = dpp_ror3(fr >= 13 ? gp[j] : g[j]); } }
;                         else { const int t = fr & 3; const float* sp = stp + (size_t)((row - MP) >> 2) * 3 * CW + ch;
;                             const f32x4 b0 = *(const f32x4*)sp, b1 = *(const f32x4*)(sp + CW), b2 = *(const f32x4*)(sp + 2 * CW);
; #pragma unroll
;                             for (int j = 0; j < 4; ++j) { const float r1 = dpp_ror1(g[j]), r2 = dpp_ror2(g[j]), r3 = dpp_ror3(g[j]);
;                                 p1[j] = t >= 1 ? r1 : b2[j]; p2[j] = t >= 2 ? r2 : (t == 1 ? b2[j] : b1[j]); p3[j] = t >= 3 ? r3 : (t == 2 ? b2[j] : (t == 1 ? b1[j] : b0[j])); } }
;                         float o[4];
; #pragma unroll
;                         for (int j = 0; j < 4; ++j) { const float y = bb[j] + w0[j] * p3[j] + w1[j] * p2[j] + w2[j] * p1[j] + w3[j] * g[j]; o[j] = is_rg ? y : siluf_(y); }
;                         u32x2 w; w.x = cvt_pk_bf16(o[0], o[1]); w.y = cvt_pk_bf16(o[2], o[3]);
;                         *(u32x2*)(dst + (size_t)row * ld + bj * 128 + 4 * n) = w; }
.LBB0_1415:
	s_waitcnt vmcnt(0)
	v_mov_b32_e32 v166, v150
	v_mov_b32_e32 v167, v138
	s_waitcnt lgkmcnt(0)
	v_mov_b32_e32 v158, v162
	v_mov_b32_e32 v159, v154
	v_pk_mul_f32 v[158:159], v[166:167], v[158:159]
	v_mov_b32_e32 v168, v146
	v_add_f32_e32 v138, v142, v159
	v_mov_b32_e32 v169, v134
	v_mov_b32_e32 v235, v170
	v_add_f32_e32 v138, v158, v138
	v_pk_mul_f32 v[158:159], v[168:169], v[234:235]
	v_mov_b32_e32 v154, v163
	v_add_f32_e32 v134, v159, v138
	v_add_f32_e32 v158, v158, v134
	v_mul_f32_e32 v134, 0xbfb8aa3b, v158
	v_exp_f32_e32 v134, v134
	v_mov_b32_e32 v138, v151
	v_pk_mul_f32 v[150:151], v[138:139], v[154:155]
	v_mov_b32_e32 v233, v171
	v_add_f32_e32 v134, 1.0, v134
	v_rcp_f32_e32 v159, v134
	v_add_f32_e32 v134, v143, v151
	v_add_f32_e32 v150, v150, v134
	v_mov_b32_e32 v134, v147
	v_pk_mul_f32 v[146:147], v[134:135], v[232:233]
	v_mov_b32_e32 v162, v152
	v_add_f32_e32 v147, v147, v150
	v_add_f32_e32 v150, v146, v147
	v_mul_f32_e32 v146, 0xbfb8aa3b, v150
	v_exp_f32_e32 v146, v146
	v_mul_f32_e32 v147, v158, v159
	v_cndmask_b32_e64 v151, v147, v158, s[4:5]
	v_mov_b32_e32 v163, v140
	v_add_f32_e32 v146, 1.0, v146
	v_rcp_f32_e32 v154, v146
	v_mov_b32_e32 v146, v164
	v_mov_b32_e32 v147, v156
	v_pk_mul_f32 v[146:147], v[162:163], v[146:147]
	v_mov_b32_e32 v170, v148
	v_add_f32_e32 v140, v144, v147
	v_mov_b32_e32 v171, v136
	v_mov_b32_e32 v231, v172
	v_add_f32_e32 v140, v146, v140
	v_pk_mul_f32 v[146:147], v[170:171], v[230:231]
	v_mov_b32_e32 v156, v165
	v_add_f32_e32 v136, v147, v140
	v_add_f32_e32 v148, v146, v136
	v_mov_b32_e32 v140, v153
	v_mul_f32_e32 v136, 0xbfb8aa3b, v148
	v_pk_mul_f32 v[146:147], v[140:141], v[156:157]
	v_exp_f32_e32 v152, v136
	v_add_f32_e32 v136, v145, v147
	v_add_f32_e32 v153, v146, v136
	v_mov_b32_e32 v136, v149
	v_mov_b32_e32 v229, v173
	v_pk_mul_f32 v[146:147], v[136:137], v[228:229]
	v_add_f32_e32 v152, 1.0, v152
	v_add_f32_e32 v147, v147, v153
	v_add_f32_e32 v146, v146, v147
	v_mul_f32_e32 v147, 0xbfb8aa3b, v146
	v_exp_f32_e32 v147, v147
	v_rcp_f32_e32 v152, v152
	v_mul_f32_e32 v149, v150, v154
	v_cndmask_b32_e64 v149, v149, v150, s[4:5]
	v_add_f32_e32 v147, 1.0, v147
	v_rcp_f32_e32 v147, v147
	v_mul_f32_e32 v150, v148, v152
	v_cndmask_b32_e64 v148, v150, v148, s[4:5]
	s_mov_b64 s[0:1], -1
	v_mul_f32_e32 v147, v146, v147
	v_cndmask_b32_e64 v147, v147, v146, s[4:5]
	v_cvt_pk_bf16_f32 v146, v151, v149
	v_cvt_pk_bf16_f32 v147, v148, v147
	s_and_b64 vcc, exec, s[18:19]
	v_mov_b32_e32 v172, v38
	v_mov_b32_e32 v164, v39
	v_mov_b32_e32 v156, v40
	v_mov_b32_e32 v154, v41
	global_store_dwordx2 v[222:223], v[146:147], off offset:256
	s_cbranch_vccnz .LBB0_1457
	v_add_u32_e32 v147, 0xffffe090, v202
	v_ashrrev_i32_e32 v147, 2, v147
	v_lshl_add_u32 v147, v147, 1, v147
	v_mad_i64_i32 v[148:149], s[0:1], v147, s47, 0
	v_lshl_add_u64 v[148:149], v[148:149], 2, v[208:209]
	v_lshl_add_u64 v[150:151], v[148:149], 0, s[24:25]
	s_lshl_b32 s0, s27, 2
	s_mov_b32 s1, s25
	global_load_dwordx4 v[158:161], v[148:149], off offset:512
	s_nop 0
	global_load_dwordx4 v[150:153], v[150:151], off offset:512
	v_lshl_add_u64 v[148:149], v[148:149], 0, s[0:1]
	global_load_dwordx4 v[154:157], v[148:149], off offset:512
	v_mov_b32_e32 v164, 0
	v_mov_b32_e32 v165, 0
	v_mov_b32_e32 v146, 0
	v_mov_b32_dpp v164, v38 row_ror:1 row_mask:0xf bank_mask:0xf
	v_mov_b32_dpp v165, v38 row_ror:2 row_mask:0xf bank_mask:0xf
	v_mov_b32_dpp v146, v38 row_ror:3 row_mask:0xf bank_mask:0xf
	v_cmp_lt_i32_e32 vcc, 1, v205
	s_and_saveexec_b64 s[0:1], vcc
	s_xor_b64 s[0:1], exec, s[0:1]
	s_cbranch_execz .LBB0_1420
	v_cmp_gt_i32_e32 vcc, 3, v205
	s_and_saveexec_b64 s[2:3], vcc
	s_cbranch_execz .LBB0_1419
	s_waitcnt vmcnt(0)
	v_mov_b32_e32 v146, v154

; __device__ __forceinline__ unsigned cvt_pk_bf16(float lo, float hi) { unsigned r; asm("v_cvt_pk_bf16_f32 %0, %1, %2" : "=v"(r) : "v"(lo), "v"(hi)); return r; }
; __device__ __forceinline__ float siluf_(float x) { return x * sigmoidf_(x); }
; __device__ __forceinline__ float dpp_ror1(float v) { return __builtin_bit_cast(float, __builtin_amdgcn_update_dpp(0, __builtin_bit_cast(int, v), 0x121, 0xf, 0xf, false)); }
;     __device__ __forceinline__ void operator()(f32x4 (&acc)[2][2][4][2], const pg8::Unit& u, int wr, int wc, int fr, int fq) const {
;     ...
;                 for (int n = 0; n < 2; ++n) { const int ch = ch0 + bj * 128 + 4 * n;
;                     const f32x4 w0 = *(const f32x4*)(cw + ch), w1 = *(const f32x4*)(cw + CW + ch), w2 = *(const f32x4*)(cw + 2 * CW + ch), w3 = *(const f32x4*)(cw + 3 * CW + ch), bb = *(const f32x4*)(cb + ch);
; #pragma unroll
;                     for (int m = 0; m < 4; ++m) { const int row = row0 + ai * 128 + m * 16; const f32x4 g = acc[ai][bj][m][n]; f32x4 p1, p2, p3;
;                         if (prompt) { const f32x4 gp = (m == 0) ? hal[n] : acc[ai][bj][m > 0 ? m - 1 : 0][n];
; #pragma unroll
;                             for (int j = 0; j < 4; ++j) { p1[j] = dpp_ror1(fr == 15 ? gp[j] : g[j]); p2[j] = dpp_ror2(fr >= 14 ? gp[j] : g[j]); p3[j] = dpp_ror3(fr >= 13 ? gp[j] : g[j]); } }
;                         else { const int t = fr & 3; const float* sp = stp + (size_t)((row - MP) >> 2) * 3 * CW + ch;
;                             const f32x4 b0 = *(const f32x4*)sp, b1 = *(const f32x4*)(sp + CW), b2 = *(const f32x4*)(sp + 2 * CW);
; #pragma unroll
;                             for (int j = 0; j < 4; ++j) { const float r1 = dpp_ror1(g[j]), r2 = dpp_ror2(g[j]), r3 = dpp_ror3(g[j]);
;                                 p1[j] = t >= 1 ? r1 : b2[j]; p2[j] = t >= 2 ? r2 : (t == 1 ? b2[j] : b1[j]); p3[j] = t >= 3 ? r3 : (t == 2 ? b2[j] : (t == 1 ? b1[j] : b0[j])); } }
;                         float o[4];
; #pragma unroll
;                         for (int j = 0; j < 4; ++j) { const float y = bb[j] + w0[j] * p3[j] + w1[j] * p2[j] + w2[j] * p1[j] + w3[j] * g[j]; o[j] = is_rg ? y : siluf_(y); }
;                         u32x2 w; w.x = cvt_pk_bf16(o[0], o[1]); w.y = cvt_pk_bf16(o[2], o[3]);
;                         *(u32x2*)(dst + (size_t)row * ld + bj * 128 + 4 * n) = w; }
.LBB0_1459:
	v_mov_b32_e32 v228, v150
	v_mov_b32_e32 v229, v146
	v_pk_mul_f32 v[228:229], v[166:167], v[228:229]
	v_mov_b32_e32 v173, v158
	v_add_f32_e32 v146, v142, v229
	v_add_f32_e32 v146, v228, v146
	v_pk_mul_f32 v[172:173], v[168:169], v[172:173]
	v_mov_b32_e32 v165, v159
	v_add_f32_e32 v146, v173, v146
	v_add_f32_e32 v150, v172, v146
	v_mul_f32_e32 v146, 0xbfb8aa3b, v150
	v_exp_f32_e32 v146, v146
	v_mov_b32_e32 v157, v160
	s_mov_b64 s[0:1], -1
	s_and_b64 vcc, exec, s[18:19]
	v_add_f32_e32 v146, 1.0, v146
	v_rcp_f32_e32 v155, v146
	v_mov_b32_e32 v146, v151
	v_pk_mul_f32 v[146:147], v[138:139], v[146:147]
	v_mov_b32_e32 v172, v22
	v_add_f32_e32 v147, v143, v147
	v_add_f32_e32 v151, v146, v147
	v_pk_mul_f32 v[146:147], v[134:135], v[164:165]
	v_mov_b32_e32 v164, v23
	v_add_f32_e32 v147, v147, v151
	v_add_f32_e32 v151, v146, v147
	v_mul_f32_e32 v146, 0xbfb8aa3b, v151
	v_exp_f32_e32 v146, v146
	v_mul_f32_e32 v147, v150, v155
	v_cndmask_b32_e64 v150, v147, v150, s[4:5]
	v_mov_b32_e32 v147, v148
	v_add_f32_e32 v146, 1.0, v146
	v_rcp_f32_e32 v158, v146
	v_mov_b32_e32 v146, v152
	v_pk_mul_f32 v[146:147], v[162:163], v[146:147]
	v_mov_b32_e32 v155, v161
	v_add_f32_e32 v147, v144, v147
	v_add_f32_e32 v148, v146, v147
	v_pk_mul_f32 v[146:147], v[170:171], v[156:157]
	s_nop 0
	v_add_f32_e32 v147, v147, v148
	v_add_f32_e32 v152, v146, v147
	v_mul_f32_e32 v146, 0xbfb8aa3b, v152
	v_mov_b32_e32 v148, v153
	v_exp_f32_e32 v156, v146
	v_pk_mul_f32 v[146:147], v[140:141], v[148:149]
	v_add_f32_e32 v149, 1.0, v156
	v_add_f32_e32 v147, v145, v147
	v_add_f32_e32 v148, v146, v147
	v_pk_mul_f32 v[146:147], v[136:137], v[154:155]
	v_rcp_f32_e32 v149, v149
	v_add_f32_e32 v147, v147, v148
	v_add_f32_e32 v146, v146, v147
	v_mul_f32_e32 v147, 0xbfb8aa3b, v146
	v_exp_f32_e32 v147, v147
	v_mul_f32_e32 v148, v151, v158
	v_mul_f32_e32 v149, v152, v149
	v_cndmask_b32_e64 v148, v148, v151, s[4:5]
	v_add_f32_e32 v147, 1.0, v147
	v_rcp_f32_e32 v147, v147
	v_cndmask_b32_e64 v149, v149, v152, s[4:5]
	v_mov_b32_e32 v156, v24
	v_mov_b32_e32 v154, v25
	v_mul_f32_e32 v147, v146, v147
	v_cndmask_b32_e64 v147, v147, v146, s[4:5]
	v_cvt_pk_bf16_f32 v146, v150, v148
	v_cvt_pk_bf16_f32 v147, v149, v147
	global_store_dwordx2 v[224:225], v[146:147], off offset:256
	s_cbranch_vccnz .LBB0_1501
	v_add_u32_e32 v147, 0xffffe0a0, v202
	v_ashrrev_i32_e32 v147, 2, v147
	v_lshl_add_u32 v147, v147, 1, v147
	v_mad_i64_i32 v[148:149], s[0:1], v147, s47, 0
	v_lshl_add_u64 v[148:149], v[148:149], 2, v[208:209]
	v_lshl_add_u64 v[150:151], v[148:149], 0, s[24:25]
	s_lshl_b32 s0, s27, 2
	s_mov_b32 s1, s25
	global_load_dwordx4 v[158:161], v[148:149], off offset:512
	s_nop 0
	global_load_dwordx4 v[150:153], v[150:151], off offset:512
	v_lshl_add_u64 v[148:149], v[148:149], 0, s[0:1]
	global_load_dwordx4 v[154:157], v[148:149], off offset:512
	v_mov_b32_e32 v164, 0
	v_mov_b32_e32 v165, 0
	v_mov_b32_e32 v146, 0
	v_mov_b32_dpp v164, v22 row_ror:1 row_mask:0xf bank_mask:0xf
	v_mov_b32_dpp v165, v22 row_ror:2 row_mask:0xf bank_mask:0xf
	v_mov_b32_dpp v146, v22 row_ror:3 row_mask:0xf bank_mask:0xf
	v_cmp_lt_i32_e32 vcc, 1, v205
	s_and_saveexec_b64 s[0:1], vcc
	s_xor_b64 s[0:1], exec, s[0:1]
	s_cbranch_execz .LBB0_1464
	v_cmp_gt_i32_e32 vcc, 3, v205
	s_and_saveexec_b64 s[2:3], vcc
	s_cbranch_execz .LBB0_1463
	s_waitcnt vmcnt(0)
	v_mov_b32_e32 v146, v154

; __device__ __forceinline__ unsigned cvt_pk_bf16(float lo, float hi) { unsigned r; asm("v_cvt_pk_bf16_f32 %0, %1, %2" : "=v"(r) : "v"(lo), "v"(hi)); return r; }
; __device__ __forceinline__ float siluf_(float x) { return x * sigmoidf_(x); }
; __device__ __forceinline__ float dpp_ror1(float v) { return __builtin_bit_cast(float, __builtin_amdgcn_update_dpp(0, __builtin_bit_cast(int, v), 0x121, 0xf, 0xf, false)); }
; __device__ __forceinline__ float dpp_ror2(float v) { return __builtin_bit_cast(float, __builtin_amdgcn_update_dpp(0, __builtin_bit_cast(int, v), 0x122, 0xf, 0xf, false)); }
; __device__ __forceinline__ float dpp_ror3(float v) { return __builtin_bit_cast(float, __builtin_amdgcn_update_dpp(0, __builtin_bit_cast(int, v), 0x123, 0xf, 0xf, false)); }
;     __device__ __forceinline__ void operator()(f32x4 (&acc)[2][2][4][2], const pg8::Unit& u, int wr, int wc, int fr, int fq) const {
;     ...
;                     for (int m = 0; m < 4; ++m) { const int row = row0 + ai * 128 + m * 16; const f32x4 g = acc[ai][bj][m][n]; f32x4 p1, p2, p3;
;                         if (prompt) { const f32x4 gp = (m == 0) ? hal[n] : acc[ai][bj][m > 0 ? m - 1 : 0][n];
; #pragma unroll
;                             for (int j = 0; j < 4; ++j) { p1[j] = dpp_ror1(fr == 15 ? gp[j] : g[j]); p2[j] = dpp_ror2(fr >= 14 ? gp[j] : g[j]); p3[j] = dpp_ror3(fr >= 13 ? gp[j] : g[j]); } }
;                         else { const int t = fr & 3; const float* sp = stp + (size_t)((row - MP) >> 2) * 3 * CW + ch;
;                             const f32x4 b0 = *(const f32x4*)sp, b1 = *(const f32x4*)(sp + CW), b2 = *(const f32x4*)(sp + 2 * CW);
; #pragma unroll
;                             for (int j = 0; j < 4; ++j) { const float r1 = dpp_ror1(g[j]), r2 = dpp_ror2(g[j]), r3 = dpp_ror3(g[j]);
;                                 p1[j] = t >= 1 ? r1 : b2[j]; p2[j] = t >= 2 ? r2 : (t == 1 ? b2[j] : b1[j]); p3[j] = t >= 3 ? r3 : (t == 2 ? b2[j] : (t == 1 ? b1[j] : b0[j])); } }
;                         float o[4];
; #pragma unroll
;                         for (int j = 0; j < 4; ++j) { const float y = bb[j] + w0[j] * p3[j] + w1[j] * p2[j] + w2[j] * p1[j] + w3[j] * g[j]; o[j] = is_rg ? y : siluf_(y); }
;                         u32x2 w; w.x = cvt_pk_bf16(o[0], o[1]); w.y = cvt_pk_bf16(o[2], o[3]);
;                         *(u32x2*)(dst + (size_t)row * ld + bj * 128 + 4 * n) = w; }
.LBB0_1503:
	v_mov_b32_e32 v228, v150
	v_mov_b32_e32 v229, v146
	v_pk_mul_f32 v[228:229], v[166:167], v[228:229]
	v_mov_b32_e32 v173, v158
	v_add_f32_e32 v146, v142, v229
	v_add_f32_e32 v146, v228, v146
	v_pk_mul_f32 v[172:173], v[168:169], v[172:173]
	v_mov_b32_e32 v165, v159
	v_add_f32_e32 v146, v173, v146
	v_add_f32_e32 v150, v172, v146
	v_mul_f32_e32 v146, 0xbfb8aa3b, v150
	v_exp_f32_e32 v146, v146
	v_mov_b32_e32 v157, v160
	s_mov_b64 s[0:1], -1
	s_and_b64 vcc, exec, s[18:19]
	v_add_f32_e32 v146, 1.0, v146
	v_rcp_f32_e32 v155, v146
	v_mov_b32_e32 v146, v151
	v_pk_mul_f32 v[146:147], v[138:139], v[146:147]
	v_mov_b32_e32 v172, v6
	v_add_f32_e32 v147, v143, v147
	v_add_f32_e32 v151, v146, v147
	v_pk_mul_f32 v[146:147], v[134:135], v[164:165]
	v_mov_b32_e32 v164, v7
	v_add_f32_e32 v147, v147, v151
	v_add_f32_e32 v151, v146, v147
	v_mul_f32_e32 v146, 0xbfb8aa3b, v151
	v_exp_f32_e32 v146, v146
	v_mul_f32_e32 v147, v150, v155
	v_cndmask_b32_e64 v150, v147, v150, s[4:5]
	v_mov_b32_e32 v147, v148
	v_add_f32_e32 v146, 1.0, v146
	v_rcp_f32_e32 v158, v146
	v_mov_b32_e32 v146, v152
	v_pk_mul_f32 v[146:147], v[162:163], v[146:147]
	v_mov_b32_e32 v155, v161
	v_add_f32_e32 v147, v144, v147
	v_add_f32_e32 v148, v146, v147
	v_pk_mul_f32 v[146:147], v[170:171], v[156:157]
	s_nop 0
	v_add_f32_e32 v147, v147, v148
	v_add_f32_e32 v152, v146, v147
	v_mul_f32_e32 v146, 0xbfb8aa3b, v152
	v_mov_b32_e32 v148, v153
	v_exp_f32_e32 v156, v146
	v_pk_mul_f32 v[146:147], v[140:141], v[148:149]
	v_add_f32_e32 v149, 1.0, v156
	v_add_f32_e32 v147, v145, v147
	v_add_f32_e32 v148, v146, v147
	v_pk_mul_f32 v[146:147], v[136:137], v[154:155]
	v_rcp_f32_e32 v149, v149
	v_add_f32_e32 v147, v147, v148
	v_add_f32_e32 v146, v146, v147
	v_mul_f32_e32 v147, 0xbfb8aa3b, v146
	v_exp_f32_e32 v147, v147
	v_mul_f32_e32 v148, v151, v158
	v_mul_f32_e32 v149, v152, v149
	v_cndmask_b32_e64 v148, v148, v151, s[4:5]
	v_add_f32_e32 v147, 1.0, v147
	v_rcp_f32_e32 v147, v147
	v_cndmask_b32_e64 v149, v149, v152, s[4:5]
	v_mov_b32_e32 v156, v8
	v_mov_b32_e32 v154, v9
	v_mul_f32_e32 v147, v146, v147
	v_cndmask_b32_e64 v147, v147, v146, s[4:5]
	v_cvt_pk_bf16_f32 v146, v150, v148
	v_cvt_pk_bf16_f32 v147, v149, v147
	global_store_dwordx2 v[226:227], v[146:147], off offset:256
	s_cbranch_vccnz .LBB0_1545
	v_add_u32_e32 v147, 0xffffe0b0, v202
	v_ashrrev_i32_e32 v147, 2, v147
	v_lshl_add_u32 v147, v147, 1, v147
	v_mad_i64_i32 v[148:149], s[0:1], v147, s47, 0
	v_lshl_add_u64 v[148:149], v[148:149], 2, v[208:209]
	v_lshl_add_u64 v[150:151], v[148:149], 0, s[24:25]
	s_lshl_b32 s0, s27, 2
	s_mov_b32 s1, s25
	global_load_dwordx4 v[158:161], v[148:149], off offset:512
	s_nop 0
	global_load_dwordx4 v[150:153], v[150:151], off offset:512
	v_lshl_add_u64 v[148:149], v[148:149], 0, s[0:1]
	global_load_dwordx4 v[154:157], v[148:149], off offset:512
	v_mov_b32_e32 v164, 0
	v_mov_b32_e32 v165, 0
	v_mov_b32_e32 v146, 0
	v_mov_b32_dpp v164, v6 row_ror:1 row_mask:0xf bank_mask:0xf
	v_mov_b32_dpp v165, v6 row_ror:2 row_mask:0xf bank_mask:0xf
	v_mov_b32_dpp v146, v6 row_ror:3 row_mask:0xf bank_mask:0xf
	v_cmp_lt_i32_e32 vcc, 1, v205
	s_and_saveexec_b64 s[0:1], vcc
	s_xor_b64 s[0:1], exec, s[0:1]
	s_cbranch_execz .LBB0_1508
	v_cmp_gt_i32_e32 vcc, 3, v205
	s_and_saveexec_b64 s[2:3], vcc
	s_cbranch_execz .LBB0_1507
	s_waitcnt vmcnt(0)
	v_mov_b32_e32 v146, v154

; __device__ __forceinline__ unsigned cvt_pk_bf16(float lo, float hi) { unsigned r; asm("v_cvt_pk_bf16_f32 %0, %1, %2" : "=v"(r) : "v"(lo), "v"(hi)); return r; }
; __device__ __forceinline__ float siluf_(float x) { return x * sigmoidf_(x); }
; __device__ __forceinline__ float dpp_ror1(float v) { return __builtin_bit_cast(float, __builtin_amdgcn_update_dpp(0, __builtin_bit_cast(int, v), 0x121, 0xf, 0xf, false)); }
;     __device__ __forceinline__ void operator()(f32x4 (&acc)[2][2][4][2], const pg8::Unit& u, int wr, int wc, int fr, int fq) const {
;     ...
;                 for (int n = 0; n < 2; ++n) { const int ch = ch0 + bj * 128 + 4 * n;
;                     const f32x4 w0 = *(const f32x4*)(cw + ch), w1 = *(const f32x4*)(cw + CW + ch), w2 = *(const f32x4*)(cw + 2 * CW + ch), w3 = *(const f32x4*)(cw + 3 * CW + ch), bb = *(const f32x4*)(cb + ch);
; #pragma unroll
;                     for (int m = 0; m < 4; ++m) { const int row = row0 + ai * 128 + m * 16; const f32x4 g = acc[ai][bj][m][n]; f32x4 p1, p2, p3;
;                         if (prompt) { const f32x4 gp = (m == 0) ? hal[n] : acc[ai][bj][m > 0 ? m - 1 : 0][n];
; #pragma unroll
;                             for (int j = 0; j < 4; ++j) { p1[j] = dpp_ror1(fr == 15 ? gp[j] : g[j]); p2[j] = dpp_ror2(fr >= 14 ? gp[j] : g[j]); p3[j] = dpp_ror3(fr >= 13 ? gp[j] : g[j]); } }
;                         else { const int t = fr & 3; const float* sp = stp + (size_t)((row - MP) >> 2) * 3 * CW + ch;
;                             const f32x4 b0 = *(const f32x4*)sp, b1 = *(const f32x4*)(sp + CW), b2 = *(const f32x4*)(sp + 2 * CW);
; #pragma unroll
;                             for (int j = 0; j < 4; ++j) { const float r1 = dpp_ror1(g[j]), r2 = dpp_ror2(g[j]), r3 = dpp_ror3(g[j]);
;                                 p1[j] = t >= 1 ? r1 : b2[j]; p2[j] = t >= 2 ? r2 : (t == 1 ? b2[j] : b1[j]); p3[j] = t >= 3 ? r3 : (t == 2 ? b2[j] : (t == 1 ? b1[j] : b0[j])); } }
;                         float o[4];
; #pragma unroll
;                         for (int j = 0; j < 4; ++j) { const float y = bb[j] + w0[j] * p3[j] + w1[j] * p2[j] + w2[j] * p1[j] + w3[j] * g[j]; o[j] = is_rg ? y : siluf_(y); }
;                         u32x2 w; w.x = cvt_pk_bf16(o[0], o[1]); w.y = cvt_pk_bf16(o[2], o[3]);
;                         *(u32x2*)(dst + (size_t)row * ld + bj * 128 + 4 * n) = w; }
.LBB0_1547:
	v_mov_b32_e32 v228, v150
	v_mov_b32_e32 v229, v146
	v_pk_mul_f32 v[166:167], v[166:167], v[228:229]
	v_mov_b32_e32 v173, v158
	v_add_f32_e32 v142, v142, v167
	v_add_f32_e32 v142, v166, v142
	v_pk_mul_f32 v[166:167], v[168:169], v[172:173]
	v_mov_b32_e32 v165, v159
	v_add_f32_e32 v142, v167, v142
	v_add_f32_e32 v142, v166, v142
	v_mul_f32_e32 v146, 0xbfb8aa3b, v142
	v_exp_f32_e32 v146, v146
	v_pk_mul_f32 v[134:135], v[134:135], v[164:165]
	v_mov_b32_e32 v157, v160
	v_mov_b32_e32 v155, v161
	v_add_f32_e32 v146, 1.0, v146
	v_rcp_f32_e32 v150, v146
	v_mov_b32_e32 v146, v151
	v_pk_mul_f32 v[138:139], v[138:139], v[146:147]
	s_mov_b64 s[0:1], -1
	v_add_f32_e32 v139, v143, v139
	v_add_f32_e32 v138, v138, v139
	v_add_f32_e32 v135, v135, v138
	v_add_f32_e32 v138, v134, v135
	v_mul_f32_e32 v134, 0xbfb8aa3b, v138
	v_exp_f32_e32 v134, v134
	v_mul_f32_e32 v135, v142, v150
	v_cndmask_b32_e64 v139, v135, v142, s[4:5]
	v_mov_b32_e32 v135, v148
	v_add_f32_e32 v134, 1.0, v134
	v_rcp_f32_e32 v142, v134
	v_mov_b32_e32 v134, v152
	v_pk_mul_f32 v[134:135], v[162:163], v[134:135]
	v_mov_b32_e32 v148, v153
	v_add_f32_e32 v135, v144, v135
	v_add_f32_e32 v143, v134, v135
	v_pk_mul_f32 v[134:135], v[170:171], v[156:157]
	s_and_b64 vcc, exec, s[18:19]
	v_add_f32_e32 v135, v135, v143
	v_add_f32_e32 v143, v134, v135
	v_mul_f32_e32 v134, 0xbfb8aa3b, v143
	v_exp_f32_e32 v144, v134
	v_pk_mul_f32 v[134:135], v[140:141], v[148:149]
	v_mov_b32_e32 v172, v52
	v_add_f32_e32 v135, v145, v135
	v_add_f32_e32 v140, v134, v135
	v_pk_mul_f32 v[134:135], v[136:137], v[154:155]
	v_add_f32_e32 v137, 1.0, v144
	v_add_f32_e32 v135, v135, v140
	v_add_f32_e32 v134, v134, v135
	v_mul_f32_e32 v135, 0xbfb8aa3b, v134
	v_exp_f32_e32 v135, v135
	v_rcp_f32_e32 v137, v137
	v_mul_f32_e32 v136, v138, v142
	v_cndmask_b32_e64 v136, v136, v138, s[4:5]
	v_add_f32_e32 v135, 1.0, v135
	v_rcp_f32_e32 v135, v135
	v_mul_f32_e32 v137, v143, v137
	v_cndmask_b32_e64 v137, v137, v143, s[4:5]
	v_mov_b32_e32 v170, v53
	v_mul_f32_e32 v135, v134, v135
	v_cndmask_b32_e64 v135, v135, v134, s[4:5]
	v_cvt_pk_bf16_f32 v134, v139, v136
	v_cvt_pk_bf16_f32 v135, v137, v135
	global_store_dwordx2 v[220:221], v[134:135], off offset:256
	global_load_dwordx4 v[138:141], v[210:211], off offset:528
	global_load_dwordx4 v[150:153], v[212:213], off offset:528
	global_load_dwordx4 v[134:137], v[214:215], off offset:528
	global_load_dwordx4 v[146:149], v[216:217], off offset:528
	global_load_dwordx4 v[142:145], v[218:219], off offset:528
	v_mov_b32_e32 v212, v50
	v_mov_b32_e32 v210, v51
	s_cbranch_vccnz .LBB0_1589
	v_add_u32_e32 v155, 0xffffe080, v202
	v_ashrrev_i32_e32 v155, 2, v155
	v_lshl_add_u32 v155, v155, 1, v155
	v_mad_i64_i32 v[156:157], s[0:1], v155, s47, 0
	v_lshl_add_u64 v[156:157], v[156:157], 2, v[208:209]
	v_lshl_add_u64 v[158:159], v[156:157], 0, s[24:25]
	s_lshl_b32 s0, s27, 2
	s_mov_b32 s1, s25
	global_load_dwordx4 v[166:169], v[156:157], off offset:528
	s_nop 0
	global_load_dwordx4 v[158:161], v[158:159], off offset:528
	v_lshl_add_u64 v[156:157], v[156:157], 0, s[0:1]
	global_load_dwordx4 v[162:165], v[156:157], off offset:528
	v_mov_b32_e32 v170, 0
	v_mov_b32_e32 v171, 0
	v_mov_b32_e32 v154, 0
	v_mov_b32_dpp v170, v50 row_ror:1 row_mask:0xf bank_mask:0xf
	v_mov_b32_dpp v171, v50 row_ror:2 row_mask:0xf bank_mask:0xf
	v_mov_b32_dpp v154, v50 row_ror:3 row_mask:0xf bank_mask:0xf
	v_cmp_lt_i32_e32 vcc, 1, v205
	s_and_saveexec_b64 s[0:1], vcc
	s_xor_b64 s[0:1], exec, s[0:1]
	s_cbranch_execz .LBB0_1552
	v_cmp_gt_i32_e32 vcc, 3, v205
	s_and_saveexec_b64 s[2:3], vcc
	s_cbranch_execz .LBB0_1551
	s_waitcnt vmcnt(0)
	v_mov_b32_e32 v154, v162

; __device__ __forceinline__ unsigned cvt_pk_bf16(float lo, float hi) { unsigned r; asm("v_cvt_pk_bf16_f32 %0, %1, %2" : "=v"(r) : "v"(lo), "v"(hi)); return r; }
; __device__ __forceinline__ float siluf_(float x) { return x * sigmoidf_(x); }
; __device__ __forceinline__ float dpp_ror1(float v) { return __builtin_bit_cast(float, __builtin_amdgcn_update_dpp(0, __builtin_bit_cast(int, v), 0x121, 0xf, 0xf, false)); }
; __device__ __forceinline__ float dpp_ror2(float v) { return __builtin_bit_cast(float, __builtin_amdgcn_update_dpp(0, __builtin_bit_cast(int, v), 0x122, 0xf, 0xf, false)); }
; __device__ __forceinline__ float dpp_ror3(float v) { return __builtin_bit_cast(float, __builtin_amdgcn_update_dpp(0, __builtin_bit_cast(int, v), 0x123, 0xf, 0xf, false)); }
;     __device__ __forceinline__ void operator()(f32x4 (&acc)[2][2][4][2], const pg8::Unit& u, int wr, int wc, int fr, int fq) const {
;     ...
;                     for (int m = 0; m < 4; ++m) { const int row = row0 + ai * 128 + m * 16; const f32x4 g = acc[ai][bj][m][n]; f32x4 p1, p2, p3;
;                         if (prompt) { const f32x4 gp = (m == 0) ? hal[n] : acc[ai][bj][m > 0 ? m - 1 : 0][n];
; #pragma unroll
;                             for (int j = 0; j < 4; ++j) { p1[j] = dpp_ror1(fr == 15 ? gp[j] : g[j]); p2[j] = dpp_ror2(fr >= 14 ? gp[j] : g[j]); p3[j] = dpp_ror3(fr >= 13 ? gp[j] : g[j]); } }
;                         else { const int t = fr & 3; const float* sp = stp + (size_t)((row - MP) >> 2) * 3 * CW + ch;
;                             const f32x4 b0 = *(const f32x4*)sp, b1 = *(const f32x4*)(sp + CW), b2 = *(const f32x4*)(sp + 2 * CW);
; #pragma unroll
;                             for (int j = 0; j < 4; ++j) { const float r1 = dpp_ror1(g[j]), r2 = dpp_ror2(g[j]), r3 = dpp_ror3(g[j]);
;                                 p1[j] = t >= 1 ? r1 : b2[j]; p2[j] = t >= 2 ? r2 : (t == 1 ? b2[j] : b1[j]); p3[j] = t >= 3 ? r3 : (t == 2 ? b2[j] : (t == 1 ? b1[j] : b0[j])); } }
;                         float o[4];
; #pragma unroll
;                         for (int j = 0; j < 4; ++j) { const float y = bb[j] + w0[j] * p3[j] + w1[j] * p2[j] + w2[j] * p1[j] + w3[j] * g[j]; o[j] = is_rg ? y : siluf_(y); }
;                         u32x2 w; w.x = cvt_pk_bf16(o[0], o[1]); w.y = cvt_pk_bf16(o[2], o[3]);
;                         *(u32x2*)(dst + (size_t)row * ld + bj * 128 + 4 * n) = w; }
.LBB0_1591:
	s_waitcnt vmcnt(0)
	v_mov_b32_e32 v162, v150
	v_mov_b32_e32 v163, v138
	v_mov_b32_e32 v130, v158
	v_mov_b32_e32 v131, v154
	v_pk_mul_f32 v[130:131], v[162:163], v[130:131]
	v_mov_b32_e32 v164, v146
	v_add_f32_e32 v131, v142, v131
	v_mov_b32_e32 v165, v134
	v_mov_b32_e32 v213, v166
	v_add_f32_e32 v132, v130, v131
	v_pk_mul_f32 v[130:131], v[164:165], v[212:213]
	v_mov_b32_e32 v138, v151
	v_add_f32_e32 v131, v131, v132
	v_add_f32_e32 v132, v130, v131
	v_mul_f32_e32 v130, 0xbfb8aa3b, v132
	v_exp_f32_e32 v130, v130
	v_mov_b32_e32 v154, v159
	v_mov_b32_e32 v134, v147
	v_mov_b32_e32 v211, v167
	v_add_f32_e32 v130, 1.0, v130
	v_rcp_f32_e32 v133, v130
	v_pk_mul_f32 v[130:131], v[138:139], v[154:155]
	v_mov_b32_e32 v158, v152
	v_add_f32_e32 v131, v143, v131
	v_add_f32_e32 v146, v130, v131
	v_pk_mul_f32 v[130:131], v[134:135], v[210:211]
	v_mov_b32_e32 v159, v140
	v_add_f32_e32 v131, v131, v146
	v_add_f32_e32 v146, v130, v131
	v_mul_f32_e32 v130, 0xbfb8aa3b, v146
	v_exp_f32_e32 v130, v130
	v_mul_f32_e32 v131, v132, v133
	v_cndmask_b32_e64 v132, v131, v132, s[4:5]
	v_mov_b32_e32 v131, v156
	v_add_f32_e32 v130, 1.0, v130
	v_rcp_f32_e32 v133, v130
	v_mov_b32_e32 v130, v160
	v_pk_mul_f32 v[130:131], v[158:159], v[130:131]
	v_mov_b32_e32 v166, v148
	v_add_f32_e32 v131, v144, v131
	v_mov_b32_e32 v167, v136
	v_mov_b32_e32 v173, v168
	v_add_f32_e32 v140, v130, v131
	v_pk_mul_f32 v[130:131], v[166:167], v[172:173]
	v_mov_b32_e32 v156, v161
	v_add_f32_e32 v131, v131, v140
	v_add_f32_e32 v147, v130, v131
	v_mul_f32_e32 v130, 0xbfb8aa3b, v147
	v_mov_b32_e32 v140, v153
	v_exp_f32_e32 v148, v130
	v_pk_mul_f32 v[130:131], v[140:141], v[156:157]
	v_mov_b32_e32 v136, v149
	v_add_f32_e32 v131, v145, v131
	v_mov_b32_e32 v171, v169
	v_add_f32_e32 v150, v130, v131
	v_pk_mul_f32 v[130:131], v[136:137], v[170:171]
	v_add_f32_e32 v148, 1.0, v148
	v_add_f32_e32 v131, v131, v150
	v_add_f32_e32 v130, v130, v131
	v_mul_f32_e32 v131, 0xbfb8aa3b, v130
	v_exp_f32_e32 v131, v131
	v_rcp_f32_e32 v148, v148
	v_mul_f32_e32 v133, v146, v133
	v_cndmask_b32_e64 v133, v133, v146, s[4:5]
	v_add_f32_e32 v131, 1.0, v131
	v_rcp_f32_e32 v131, v131
	v_mul_f32_e32 v146, v147, v148
	v_cndmask_b32_e64 v146, v146, v147, s[4:5]
	s_mov_b64 s[0:1], -1
	v_mul_f32_e32 v131, v130, v131
	v_cndmask_b32_e64 v131, v131, v130, s[4:5]
	v_cvt_pk_bf16_f32 v130, v132, v133
	v_cvt_pk_bf16_f32 v131, v146, v131
	s_and_b64 vcc, exec, s[18:19]
	v_mov_b32_e32 v168, v34
	v_mov_b32_e32 v160, v35
	v_mov_b32_e32 v152, v36
	v_mov_b32_e32 v150, v37
	global_store_dwordx2 v[222:223], v[130:131], off offset:264
	s_cbranch_vccnz .LBB0_1633
	v_add_u32_e32 v131, 0xffffe090, v202
	v_ashrrev_i32_e32 v131, 2, v131
	v_lshl_add_u32 v131, v131, 1, v131
	v_mad_i64_i32 v[132:133], s[0:1], v131, s47, 0
	v_lshl_add_u64 v[132:133], v[132:133], 2, v[208:209]
	v_lshl_add_u64 v[146:147], v[132:133], 0, s[24:25]
	s_lshl_b32 s0, s27, 2
	s_mov_b32 s1, s25
	global_load_dwordx4 v[154:157], v[132:133], off offset:528
	s_nop 0
	global_load_dwordx4 v[146:149], v[146:147], off offset:528
	v_lshl_add_u64 v[132:133], v[132:133], 0, s[0:1]
	global_load_dwordx4 v[150:153], v[132:133], off offset:528
	v_mov_b32_e32 v160, 0
	v_mov_b32_e32 v161, 0
	v_mov_b32_e32 v130, 0
	v_mov_b32_dpp v160, v34 row_ror:1 row_mask:0xf bank_mask:0xf
	v_mov_b32_dpp v161, v34 row_ror:2 row_mask:0xf bank_mask:0xf
	v_mov_b32_dpp v130, v34 row_ror:3 row_mask:0xf bank_mask:0xf
	v_cmp_lt_i32_e32 vcc, 1, v205
	s_and_saveexec_b64 s[0:1], vcc
	s_xor_b64 s[0:1], exec, s[0:1]
	s_cbranch_execz .LBB0_1596
	v_cmp_gt_i32_e32 vcc, 3, v205
	s_and_saveexec_b64 s[2:3], vcc
	s_cbranch_execz .LBB0_1595
	s_waitcnt vmcnt(0)
	v_mov_b32_e32 v130, v150

; __device__ __forceinline__ unsigned cvt_pk_bf16(float lo, float hi) { unsigned r; asm("v_cvt_pk_bf16_f32 %0, %1, %2" : "=v"(r) : "v"(lo), "v"(hi)); return r; }
; __device__ __forceinline__ float siluf_(float x) { return x * sigmoidf_(x); }
; __device__ __forceinline__ float dpp_ror1(float v) { return __builtin_bit_cast(float, __builtin_amdgcn_update_dpp(0, __builtin_bit_cast(int, v), 0x121, 0xf, 0xf, false)); }
; __device__ __forceinline__ float dpp_ror2(float v) { return __builtin_bit_cast(float, __builtin_amdgcn_update_dpp(0, __builtin_bit_cast(int, v), 0x122, 0xf, 0xf, false)); }
; __device__ __forceinline__ float dpp_ror3(float v) { return __builtin_bit_cast(float, __builtin_amdgcn_update_dpp(0, __builtin_bit_cast(int, v), 0x123, 0xf, 0xf, false)); }
;     __device__ __forceinline__ void operator()(f32x4 (&acc)[2][2][4][2], const pg8::Unit& u, int wr, int wc, int fr, int fq) const {
;     ...
;                     for (int m = 0; m < 4; ++m) { const int row = row0 + ai * 128 + m * 16; const f32x4 g = acc[ai][bj][m][n]; f32x4 p1, p2, p3;
;                         if (prompt) { const f32x4 gp = (m == 0) ? hal[n] : acc[ai][bj][m > 0 ? m - 1 : 0][n];
; #pragma unroll
;                             for (int j = 0; j < 4; ++j) { p1[j] = dpp_ror1(fr == 15 ? gp[j] : g[j]); p2[j] = dpp_ror2(fr >= 14 ? gp[j] : g[j]); p3[j] = dpp_ror3(fr >= 13 ? gp[j] : g[j]); } }
;                         else { const int t = fr & 3; const float* sp = stp + (size_t)((row - MP) >> 2) * 3 * CW + ch;
;                             const f32x4 b0 = *(const f32x4*)sp, b1 = *(const f32x4*)(sp + CW), b2 = *(const f32x4*)(sp + 2 * CW);
; #pragma unroll
;                             for (int j = 0; j < 4; ++j) { const float r1 = dpp_ror1(g[j]), r2 = dpp_ror2(g[j]), r3 = dpp_ror3(g[j]);
;                                 p1[j] = t >= 1 ? r1 : b2[j]; p2[j] = t >= 2 ? r2 : (t == 1 ? b2[j] : b1[j]); p3[j] = t >= 3 ? r3 : (t == 2 ? b2[j] : (t == 1 ? b1[j] : b0[j])); } }
;                         float o[4];
; #pragma unroll
;                         for (int j = 0; j < 4; ++j) { const float y = bb[j] + w0[j] * p3[j] + w1[j] * p2[j] + w2[j] * p1[j] + w3[j] * g[j]; o[j] = is_rg ? y : siluf_(y); }
;                         u32x2 w; w.x = cvt_pk_bf16(o[0], o[1]); w.y = cvt_pk_bf16(o[2], o[3]);
;                         *(u32x2*)(dst + (size_t)row * ld + bj * 128 + 4 * n) = w; }
.LBB0_1635:
	v_mov_b32_e32 v170, v146
	v_mov_b32_e32 v171, v130
	v_pk_mul_f32 v[170:171], v[162:163], v[170:171]
	v_mov_b32_e32 v169, v154
	v_add_f32_e32 v130, v142, v171
	v_add_f32_e32 v130, v170, v130
	v_pk_mul_f32 v[168:169], v[164:165], v[168:169]
	v_mov_b32_e32 v161, v155
	v_add_f32_e32 v130, v169, v130
	v_add_f32_e32 v146, v168, v130
	v_mul_f32_e32 v130, 0xbfb8aa3b, v146
	v_exp_f32_e32 v130, v130
	v_mov_b32_e32 v153, v156
	s_mov_b64 s[0:1], -1
	s_and_b64 vcc, exec, s[18:19]
	v_add_f32_e32 v130, 1.0, v130
	v_rcp_f32_e32 v151, v130
	v_mov_b32_e32 v130, v147
	v_pk_mul_f32 v[130:131], v[138:139], v[130:131]
	v_mov_b32_e32 v168, v18
	v_add_f32_e32 v131, v143, v131
	v_add_f32_e32 v147, v130, v131
	v_pk_mul_f32 v[130:131], v[134:135], v[160:161]
	v_mov_b32_e32 v160, v19
	v_add_f32_e32 v131, v131, v147
	v_add_f32_e32 v147, v130, v131
	v_mul_f32_e32 v130, 0xbfb8aa3b, v147
	v_exp_f32_e32 v130, v130
	v_mul_f32_e32 v131, v146, v151
	v_cndmask_b32_e64 v146, v131, v146, s[4:5]
	v_mov_b32_e32 v131, v132
	v_add_f32_e32 v130, 1.0, v130
	v_rcp_f32_e32 v154, v130
	v_mov_b32_e32 v130, v148
	v_pk_mul_f32 v[130:131], v[158:159], v[130:131]
	v_mov_b32_e32 v151, v157
	v_add_f32_e32 v131, v144, v131
	v_add_f32_e32 v132, v130, v131
	v_pk_mul_f32 v[130:131], v[166:167], v[152:153]
	s_nop 0
	v_add_f32_e32 v131, v131, v132
	v_add_f32_e32 v148, v130, v131
	v_mul_f32_e32 v130, 0xbfb8aa3b, v148
	v_mov_b32_e32 v132, v149
	v_exp_f32_e32 v152, v130
	v_pk_mul_f32 v[130:131], v[140:141], v[132:133]
	v_add_f32_e32 v133, 1.0, v152
	v_add_f32_e32 v131, v145, v131
	v_add_f32_e32 v132, v130, v131
	v_pk_mul_f32 v[130:131], v[136:137], v[150:151]
	v_rcp_f32_e32 v133, v133
	v_add_f32_e32 v131, v131, v132
	v_add_f32_e32 v130, v130, v131
	v_mul_f32_e32 v131, 0xbfb8aa3b, v130
	v_exp_f32_e32 v131, v131
	v_mul_f32_e32 v132, v147, v154
	v_mul_f32_e32 v133, v148, v133
	v_cndmask_b32_e64 v132, v132, v147, s[4:5]
	v_add_f32_e32 v131, 1.0, v131
	v_rcp_f32_e32 v131, v131
	v_cndmask_b32_e64 v133, v133, v148, s[4:5]
	v_mov_b32_e32 v152, v20
	v_mov_b32_e32 v150, v21
	v_mul_f32_e32 v131, v130, v131
	v_cndmask_b32_e64 v131, v131, v130, s[4:5]
	v_cvt_pk_bf16_f32 v130, v146, v132
	v_cvt_pk_bf16_f32 v131, v133, v131
	global_store_dwordx2 v[224:225], v[130:131], off offset:264
	s_cbranch_vccnz .LBB0_1677
	v_add_u32_e32 v131, 0xffffe0a0, v202
	v_ashrrev_i32_e32 v131, 2, v131
	v_lshl_add_u32 v131, v131, 1, v131
	v_mad_i64_i32 v[132:133], s[0:1], v131, s47, 0
	v_lshl_add_u64 v[132:133], v[132:133], 2, v[208:209]
	v_lshl_add_u64 v[146:147], v[132:133], 0, s[24:25]
	s_lshl_b32 s0, s27, 2
	s_mov_b32 s1, s25
	global_load_dwordx4 v[154:157], v[132:133], off offset:528
	s_nop 0
	global_load_dwordx4 v[146:149], v[146:147], off offset:528
	v_lshl_add_u64 v[132:133], v[132:133], 0, s[0:1]
	global_load_dwordx4 v[150:153], v[132:133], off offset:528
	v_mov_b32_e32 v160, 0
	v_mov_b32_e32 v161, 0
	v_mov_b32_e32 v130, 0
	v_mov_b32_dpp v160, v18 row_ror:1 row_mask:0xf bank_mask:0xf
	v_mov_b32_dpp v161, v18 row_ror:2 row_mask:0xf bank_mask:0xf
	v_mov_b32_dpp v130, v18 row_ror:3 row_mask:0xf bank_mask:0xf
	v_cmp_lt_i32_e32 vcc, 1, v205
	s_and_saveexec_b64 s[0:1], vcc
	s_xor_b64 s[0:1], exec, s[0:1]
	s_cbranch_execz .LBB0_1640
	v_cmp_gt_i32_e32 vcc, 3, v205
	s_and_saveexec_b64 s[2:3], vcc
	s_cbranch_execz .LBB0_1639
	s_waitcnt vmcnt(0)
	v_mov_b32_e32 v130, v150

; __device__ __forceinline__ unsigned cvt_pk_bf16(float lo, float hi) { unsigned r; asm("v_cvt_pk_bf16_f32 %0, %1, %2" : "=v"(r) : "v"(lo), "v"(hi)); return r; }
; __device__ __forceinline__ float siluf_(float x) { return x * sigmoidf_(x); }
; __device__ __forceinline__ float dpp_ror1(float v) { return __builtin_bit_cast(float, __builtin_amdgcn_update_dpp(0, __builtin_bit_cast(int, v), 0x121, 0xf, 0xf, false)); }
; __device__ __forceinline__ float dpp_ror2(float v) { return __builtin_bit_cast(float, __builtin_amdgcn_update_dpp(0, __builtin_bit_cast(int, v), 0x122, 0xf, 0xf, false)); }
; __device__ __forceinline__ float dpp_ror3(float v) { return __builtin_bit_cast(float, __builtin_amdgcn_update_dpp(0, __builtin_bit_cast(int, v), 0x123, 0xf, 0xf, false)); }
;     __device__ __forceinline__ void operator()(f32x4 (&acc)[2][2][4][2], const pg8::Unit& u, int wr, int wc, int fr, int fq) const {
;     ...
;                     for (int m = 0; m < 4; ++m) { const int row = row0 + ai * 128 + m * 16; const f32x4 g = acc[ai][bj][m][n]; f32x4 p1, p2, p3;
;                         if (prompt) { const f32x4 gp = (m == 0) ? hal[n] : acc[ai][bj][m > 0 ? m - 1 : 0][n];
; #pragma unroll
;                             for (int j = 0; j < 4; ++j) { p1[j] = dpp_ror1(fr == 15 ? gp[j] : g[j]); p2[j] = dpp_ror2(fr >= 14 ? gp[j] : g[j]); p3[j] = dpp_ror3(fr >= 13 ? gp[j] : g[j]); } }
;                         else { const int t = fr & 3; const float* sp = stp + (size_t)((row - MP) >> 2) * 3 * CW + ch;
;                             const f32x4 b0 = *(const f32x4*)sp, b1 = *(const f32x4*)(sp + CW), b2 = *(const f32x4*)(sp + 2 * CW);
; #pragma unroll
;                             for (int j = 0; j < 4; ++j) { const float r1 = dpp_ror1(g[j]), r2 = dpp_ror2(g[j]), r3 = dpp_ror3(g[j]);
;                                 p1[j] = t >= 1 ? r1 : b2[j]; p2[j] = t >= 2 ? r2 : (t == 1 ? b2[j] : b1[j]); p3[j] = t >= 3 ? r3 : (t == 2 ? b2[j] : (t == 1 ? b1[j] : b0[j])); } }
;                         float o[4];
; #pragma unroll
;                         for (int j = 0; j < 4; ++j) { const float y = bb[j] + w0[j] * p3[j] + w1[j] * p2[j] + w2[j] * p1[j] + w3[j] * g[j]; o[j] = is_rg ? y : siluf_(y); }
;                         u32x2 w; w.x = cvt_pk_bf16(o[0], o[1]); w.y = cvt_pk_bf16(o[2], o[3]);
;                         *(u32x2*)(dst + (size_t)row * ld + bj * 128 + 4 * n) = w; }
.LBB0_1679:
	v_mov_b32_e32 v170, v146
	v_mov_b32_e32 v171, v130
	v_pk_mul_f32 v[170:171], v[162:163], v[170:171]
	v_mov_b32_e32 v169, v154
	v_add_f32_e32 v130, v142, v171
	v_add_f32_e32 v130, v170, v130
	v_pk_mul_f32 v[168:169], v[164:165], v[168:169]
	v_mov_b32_e32 v161, v155
	v_add_f32_e32 v130, v169, v130
	v_add_f32_e32 v146, v168, v130
	v_mul_f32_e32 v130, 0xbfb8aa3b, v146
	v_exp_f32_e32 v130, v130
	v_mov_b32_e32 v153, v156
	s_and_b64 vcc, exec, s[18:19]
	s_mov_b64 s[0:1], -1
	v_add_f32_e32 v130, 1.0, v130
	v_rcp_f32_e32 v151, v130
	v_mov_b32_e32 v130, v147
	v_pk_mul_f32 v[130:131], v[138:139], v[130:131]
	s_nop 0
	v_add_f32_e32 v131, v143, v131
	v_add_f32_e32 v147, v130, v131
	v_pk_mul_f32 v[130:131], v[134:135], v[160:161]
	s_nop 0
	v_add_f32_e32 v131, v131, v147
	v_add_f32_e32 v147, v130, v131
	v_mul_f32_e32 v130, 0xbfb8aa3b, v147
	v_exp_f32_e32 v130, v130
	v_mul_f32_e32 v131, v146, v151
	v_cndmask_b32_e64 v146, v131, v146, s[4:5]
	v_mov_b32_e32 v131, v132
	v_add_f32_e32 v130, 1.0, v130
	v_rcp_f32_e32 v154, v130
	v_mov_b32_e32 v130, v148
	v_pk_mul_f32 v[130:131], v[158:159], v[130:131]
	v_mov_b32_e32 v151, v157
	v_add_f32_e32 v131, v144, v131
	v_add_f32_e32 v132, v130, v131
	v_pk_mul_f32 v[130:131], v[166:167], v[152:153]
	s_nop 0
	v_add_f32_e32 v131, v131, v132
	v_add_f32_e32 v148, v130, v131
	v_mul_f32_e32 v130, 0xbfb8aa3b, v148
	v_mov_b32_e32 v132, v149
	v_exp_f32_e32 v152, v130
	v_pk_mul_f32 v[130:131], v[140:141], v[132:133]
	v_add_f32_e32 v133, 1.0, v152
	v_add_f32_e32 v131, v145, v131
	v_add_f32_e32 v132, v130, v131
	v_pk_mul_f32 v[130:131], v[136:137], v[150:151]
	v_rcp_f32_e32 v133, v133
	v_add_f32_e32 v131, v131, v132
	v_add_f32_e32 v130, v130, v131
	v_mul_f32_e32 v131, 0xbfb8aa3b, v130
	v_exp_f32_e32 v131, v131
	v_mul_f32_e32 v132, v147, v154
	v_mul_f32_e32 v133, v148, v133
	v_cndmask_b32_e64 v132, v132, v147, s[4:5]
	v_add_f32_e32 v131, 1.0, v131
	v_rcp_f32_e32 v131, v131
	v_cndmask_b32_e64 v133, v133, v148, s[4:5]
	v_mul_f32_e32 v131, v130, v131
	v_cndmask_b32_e64 v131, v131, v130, s[4:5]
	v_cvt_pk_bf16_f32 v130, v146, v132
	v_cvt_pk_bf16_f32 v131, v133, v131
	global_store_dwordx2 v[226:227], v[130:131], off offset:264
	s_cbranch_vccnz .LBB0_1721
	v_add_u32_e32 v131, 0xffffe0b0, v202
	v_ashrrev_i32_e32 v131, 2, v131
	v_lshl_add_u32 v131, v131, 1, v131
	v_mad_i64_i32 v[132:133], s[0:1], v131, s47, 0
	v_lshl_add_u64 v[132:133], v[132:133], 2, v[208:209]
	v_lshl_add_u64 v[146:147], v[132:133], 0, s[24:25]
	s_lshl_b32 s24, s27, 2
	global_load_dwordx4 v[154:157], v[132:133], off offset:528
	s_nop 0
	global_load_dwordx4 v[146:149], v[146:147], off offset:528
	v_lshl_add_u64 v[132:133], v[132:133], 0, s[24:25]
	global_load_dwordx4 v[150:153], v[132:133], off offset:528
	v_mov_b32_e32 v160, 0
	v_mov_b32_e32 v161, 0
	v_mov_b32_e32 v130, 0
	v_mov_b32_dpp v160, v2 row_ror:1 row_mask:0xf bank_mask:0xf
	v_mov_b32_dpp v161, v2 row_ror:2 row_mask:0xf bank_mask:0xf
	v_mov_b32_dpp v130, v2 row_ror:3 row_mask:0xf bank_mask:0xf
	v_cmp_lt_i32_e32 vcc, 1, v205
	s_and_saveexec_b64 s[0:1], vcc
	s_xor_b64 s[0:1], exec, s[0:1]
	s_cbranch_execz .LBB0_1684
	v_cmp_gt_i32_e32 vcc, 3, v205
	s_and_saveexec_b64 s[2:3], vcc
	s_cbranch_execz .LBB0_1683
	s_waitcnt vmcnt(0)
	v_mov_b32_e32 v130, v150

; __device__ __forceinline__ unsigned cvt_pk_bf16(float lo, float hi) { unsigned r; asm("v_cvt_pk_bf16_f32 %0, %1, %2" : "=v"(r) : "v"(lo), "v"(hi)); return r; }
; __device__ __forceinline__ float siluf_(float x) { return x * sigmoidf_(x); }
; __device__ __forceinline__ float dpp_ror1(float v) { return __builtin_bit_cast(float, __builtin_amdgcn_update_dpp(0, __builtin_bit_cast(int, v), 0x121, 0xf, 0xf, false)); }
; __device__ __forceinline__ float dpp_ror2(float v) { return __builtin_bit_cast(float, __builtin_amdgcn_update_dpp(0, __builtin_bit_cast(int, v), 0x122, 0xf, 0xf, false)); }
; __device__ __forceinline__ float dpp_ror3(float v) { return __builtin_bit_cast(float, __builtin_amdgcn_update_dpp(0, __builtin_bit_cast(int, v), 0x123, 0xf, 0xf, false)); }
;     __device__ __forceinline__ void operator()(f32x4 (&acc)[2][2][4][2], const pg8::Unit& u, int wr, int wc, int fr, int fq) const {
;     ...
;                     for (int m = 0; m < 4; ++m) { const int row = row0 + ai * 128 + m * 16; const f32x4 g = acc[ai][bj][m][n]; f32x4 p1, p2, p3;
;                         if (prompt) { const f32x4 gp = (m == 0) ? hal[n] : acc[ai][bj][m > 0 ? m - 1 : 0][n];
; #pragma unroll
;                             for (int j = 0; j < 4; ++j) { p1[j] = dpp_ror1(fr == 15 ? gp[j] : g[j]); p2[j] = dpp_ror2(fr >= 14 ? gp[j] : g[j]); p3[j] = dpp_ror3(fr >= 13 ? gp[j] : g[j]); } }
;                         else { const int t = fr & 3; const float* sp = stp + (size_t)((row - MP) >> 2) * 3 * CW + ch;
;                             const f32x4 b0 = *(const f32x4*)sp, b1 = *(const f32x4*)(sp + CW), b2 = *(const f32x4*)(sp + 2 * CW);
; #pragma unroll
;                             for (int j = 0; j < 4; ++j) { const float r1 = dpp_ror1(g[j]), r2 = dpp_ror2(g[j]), r3 = dpp_ror3(g[j]);
;                                 p1[j] = t >= 1 ? r1 : b2[j]; p2[j] = t >= 2 ? r2 : (t == 1 ? b2[j] : b1[j]); p3[j] = t >= 3 ? r3 : (t == 2 ? b2[j] : (t == 1 ? b1[j] : b0[j])); } }
;                         float o[4];
; #pragma unroll
;                         for (int j = 0; j < 4; ++j) { const float y = bb[j] + w0[j] * p3[j] + w1[j] * p2[j] + w2[j] * p1[j] + w3[j] * g[j]; o[j] = is_rg ? y : siluf_(y); }
;                         u32x2 w; w.x = cvt_pk_bf16(o[0], o[1]); w.y = cvt_pk_bf16(o[2], o[3]);
.LBB0_1723:
	v_mov_b32_e32 v150, v146
	v_mov_b32_e32 v151, v130
	v_pk_mul_f32 v[150:151], v[162:163], v[150:151]
	s_mov_b64 s[0:1], 0
	v_add_f32_e32 v130, v142, v151
	v_add_f32_e32 v130, v150, v130
	v_mov_b32_e32 v150, v2
	v_mov_b32_e32 v151, v154
	v_pk_mul_f32 v[150:151], v[164:165], v[150:151]
	v_mov_b32_e32 v154, v3
	v_add_f32_e32 v130, v151, v130
	v_add_f32_e32 v142, v150, v130
	v_mul_f32_e32 v130, 0xbfb8aa3b, v142
	v_exp_f32_e32 v130, v130
	v_readlane_b32 s24, v255, 21
	v_add_f32_e32 v130, 1.0, v130
	v_rcp_f32_e32 v146, v130
	v_mov_b32_e32 v130, v147
	v_pk_mul_f32 v[130:131], v[138:139], v[130:131]
	s_nop 0
	v_add_f32_e32 v131, v143, v131
	v_add_f32_e32 v138, v130, v131
	v_pk_mul_f32 v[130:131], v[134:135], v[154:155]
	s_nop 0
	v_add_f32_e32 v131, v131, v138
	v_add_f32_e32 v134, v130, v131
	v_mul_f32_e32 v130, 0xbfb8aa3b, v134
	v_exp_f32_e32 v130, v130
	v_mul_f32_e32 v131, v142, v146
	v_cndmask_b32_e64 v135, v131, v142, s[4:5]
	v_mov_b32_e32 v131, v132
	v_add_f32_e32 v130, 1.0, v130
	v_rcp_f32_e32 v138, v130
	v_mov_b32_e32 v130, v148
	v_pk_mul_f32 v[130:131], v[158:159], v[130:131]
	s_nop 0
	v_add_f32_e32 v131, v144, v131
	v_add_f32_e32 v132, v130, v131
	v_mov_b32_e32 v130, v4
	v_mov_b32_e32 v131, v156
	v_pk_mul_f32 v[130:131], v[166:167], v[130:131]
	v_mov_b32_e32 v156, v5
	v_add_f32_e32 v131, v131, v132
	v_add_f32_e32 v139, v130, v131
	v_mul_f32_e32 v130, 0xbfb8aa3b, v139
	v_mov_b32_e32 v132, v149
	v_exp_f32_e32 v142, v130
	v_pk_mul_f32 v[130:131], v[140:141], v[132:133]
	v_add_f32_e32 v133, 1.0, v142
	v_add_f32_e32 v131, v145, v131
	v_add_f32_e32 v132, v130, v131
	v_pk_mul_f32 v[130:131], v[136:137], v[156:157]
	v_rcp_f32_e32 v133, v133
	v_add_f32_e32 v131, v131, v132
	v_add_f32_e32 v130, v130, v131
	v_mul_f32_e32 v131, 0xbfb8aa3b, v130
	v_exp_f32_e32 v131, v131
	v_mul_f32_e32 v132, v134, v138
	v_mul_f32_e32 v133, v139, v133
	v_cndmask_b32_e64 v132, v132, v134, s[4:5]
	v_add_f32_e32 v131, 1.0, v131
	v_rcp_f32_e32 v131, v131
	v_cndmask_b32_e64 v133, v133, v139, s[4:5]
	v_mul_f32_e32 v131, v130, v131
	v_cndmask_b32_e64 v131, v131, v130, s[4:5]
	v_cvt_pk_bf16_f32 v130, v135, v132
	v_cvt_pk_bf16_f32 v131, v133, v131
	global_store_dwordx2 v[220:221], v[130:131], off offset:264

; __device__ __forceinline__ unsigned cvt_pk_bf16(float lo, float hi) { unsigned r; asm("v_cvt_pk_bf16_f32 %0, %1, %2" : "=v"(r) : "v"(lo), "v"(hi)); return r; }
; __device__ __forceinline__ float siluf_(float x) { return x * sigmoidf_(x); }
; __device__ __forceinline__ float gelu_tanh(float x) { const float u = 0.7978845608028654f * (x + 0.044715f * x * x * x); return x * sigmoidf_(2.0f * u); }
;     __device__ __forceinline__ void operator()(f32x4 (&acc)[2][2][4][2], const pg8::Unit& u, int wr, int wc, int fr, int fq) const {
;     ...
;                 for (int m = 0; m < 4; ++m) { const int row = row0 + ai * 128 + m * 16;
; #pragma unroll
;                     for (int bj = 0; bj < 2; ++bj) { f32x4 v0 = acc[ai][bj][m][0], v1 = acc[ai][bj][m][1];
;                         if (pn < 16) { v0 = (f32x4){gelu_tanh(v0[0]), gelu_tanh(v0[1]), gelu_tanh(v0[2]), gelu_tanh(v0[3])}; v1 = (f32x4){gelu_tanh(v1[0]), gelu_tanh(v1[1]), gelu_tanh(v1[2]), gelu_tanh(v1[3])}; }
;                         else { v0 = (f32x4){siluf_(v0[0]), siluf_(v0[1]), siluf_(v0[2]), siluf_(v0[3])}; v1 = (f32x4){siluf_(v1[0]), siluf_(v1[1]), siluf_(v1[2]), siluf_(v1[3])}; }
;                         u32x4 w; w.x = cvt_pk_bf16(v0[0], v0[1]); w.y = cvt_pk_bf16(v0[2], v0[3]); w.z = cvt_pk_bf16(v1[0], v1[1]); w.w = cvt_pk_bf16(v1[2], v1[3]);
;                         *(u32x4*)(G2 + (size_t)row * 4096 + (c0 - C_RGG) + bj * 128) = w; } }
.LBB0_1731:
	v_mul_f32_e32 v126, 0xbfb8aa3b, v138
	v_exp_f32_e32 v138, v126
	v_ashrrev_i32_e32 v205, 31, v204
	v_pk_mul_f32 v[128:129], v[124:125], v[132:133]
	v_lshlrev_b64 v[126:127], 13, v[202:203]
	v_add_f32_e32 v124, 1.0, v138
	v_rcp_f32_e32 v132, v124
	v_pk_mul_f32 v[130:131], v[122:123], v[130:131]
	v_lshl_add_u64 v[122:123], v[204:205], 1, s[74:75]
	v_lshl_add_u64 v[124:125], v[122:123], 0, v[126:127]
	v_cvt_pk_bf16_f32 v126, v130, v131
	v_add_co_u32_e32 v130, vcc, 0x2e90e000, v124
	v_mul_f32_e32 v132, v136, v132
	s_nop 0
	v_addc_co_u32_e32 v131, vcc, 0, v125, vcc
	v_cvt_pk_bf16_f32 v127, v128, v129
	v_cvt_pk_bf16_f32 v128, v134, v135
	v_cvt_pk_bf16_f32 v129, v137, v132
	global_store_dwordx4 v[130:131], v[126:129], off
	s_andn2_b64 vcc, exec, s[0:1]
	s_nop 0
	v_cndmask_b32_e64 v126, 0, 1, s[0:1]
	v_cmp_ne_u32_e64 s[4:5], 1, v126
	s_mov_b64 s[0:1], -1
	s_cbranch_vccnz .LBB0_1733
	v_mul_f32_e32 v130, 0xbfb8aa3b, v114
	v_mul_f32_e32 v131, 0xbfb8aa3b, v115
	v_mul_f32_e32 v132, 0xbfb8aa3b, v116
	v_mul_f32_e32 v126, 0xbfb8aa3b, v118
	v_mul_f32_e32 v127, 0xbfb8aa3b, v119
	v_mul_f32_e32 v128, 0xbfb8aa3b, v120
	v_mul_f32_e32 v129, 0xbfb8aa3b, v121
	v_exp_f32_e32 v130, v130
	v_exp_f32_e32 v131, v131
	v_exp_f32_e32 v132, v132
	v_exp_f32_e32 v126, v126
	v_exp_f32_e32 v127, v127
	v_exp_f32_e32 v128, v128
	v_exp_f32_e32 v129, v129
	v_add_f32_e32 v130, 1.0, v130
	v_add_f32_e32 v131, 1.0, v131
	v_add_f32_e32 v132, 1.0, v132
	v_add_f32_e32 v126, 1.0, v126
	v_add_f32_e32 v127, 1.0, v127
	v_add_f32_e32 v128, 1.0, v128
	v_add_f32_e32 v129, 1.0, v129
	v_rcp_f32_e32 v130, v130
	v_rcp_f32_e32 v131, v131
	v_rcp_f32_e32 v132, v132
	v_rcp_f32_e32 v126, v126
	v_rcp_f32_e32 v127, v127
	v_rcp_f32_e32 v128, v128
	v_rcp_f32_e32 v129, v129
	v_pk_mul_f32 v[130:131], v[114:115], v[130:131]
	v_mul_f32_e32 v132, v116, v132
	s_mov_b64 s[0:1], 0

; __device__ __forceinline__ unsigned cvt_pk_bf16(float lo, float hi) { unsigned r; asm("v_cvt_pk_bf16_f32 %0, %1, %2" : "=v"(r) : "v"(lo), "v"(hi)); return r; }
; __device__ __forceinline__ float siluf_(float x) { return x * sigmoidf_(x); }
; __device__ __forceinline__ float gelu_tanh(float x) { const float u = 0.7978845608028654f * (x + 0.044715f * x * x * x); return x * sigmoidf_(2.0f * u); }
;     __device__ __forceinline__ void operator()(f32x4 (&acc)[2][2][4][2], const pg8::Unit& u, int wr, int wc, int fr, int fq) const {
;     ...
;                 for (int m = 0; m < 4; ++m) { const int row = row0 + ai * 128 + m * 16;
; #pragma unroll
;                     for (int bj = 0; bj < 2; ++bj) { f32x4 v0 = acc[ai][bj][m][0], v1 = acc[ai][bj][m][1];
;                         if (pn < 16) { v0 = (f32x4){gelu_tanh(v0[0]), gelu_tanh(v0[1]), gelu_tanh(v0[2]), gelu_tanh(v0[3])}; v1 = (f32x4){gelu_tanh(v1[0]), gelu_tanh(v1[1]), gelu_tanh(v1[2]), gelu_tanh(v1[3])}; }
;                         else { v0 = (f32x4){siluf_(v0[0]), siluf_(v0[1]), siluf_(v0[2]), siluf_(v0[3])}; v1 = (f32x4){siluf_(v1[0]), siluf_(v1[1]), siluf_(v1[2]), siluf_(v1[3])}; }
;                         u32x4 w; w.x = cvt_pk_bf16(v0[0], v0[1]); w.y = cvt_pk_bf16(v0[2], v0[3]); w.z = cvt_pk_bf16(v1[0], v1[1]); w.w = cvt_pk_bf16(v1[2], v1[3]);
;                         *(u32x4*)(G2 + (size_t)row * 4096 + (c0 - C_RGG) + bj * 128) = w; } }
.LBB0_1735:
	v_mul_f32_e32 v114, 0xbfb8aa3b, v133
	v_exp_f32_e32 v116, v114
	v_pk_mul_f32 v[114:115], v[118:119], v[126:127]
	v_pk_mul_f32 v[120:121], v[120:121], v[128:129]
	v_cvt_pk_bf16_f32 v114, v114, v115
	v_add_f32_e32 v116, 1.0, v116
	v_rcp_f32_e32 v118, v116
	v_cvt_pk_bf16_f32 v116, v130, v131
	v_cvt_pk_bf16_f32 v115, v120, v121
	s_mov_b64 s[0:1], -1
	v_mul_f32_e32 v117, v117, v118
	v_add_co_u32_e32 v118, vcc, 0x2e90e000, v124
	v_cvt_pk_bf16_f32 v117, v132, v117
	s_nop 1
	v_addc_co_u32_e32 v119, vcc, 0, v125, vcc
	s_and_b64 vcc, exec, s[4:5]
	global_store_dwordx4 v[118:119], v[114:117], off offset:256
	s_cbranch_vccnz .LBB0_1737
	v_mul_f32_e32 v118, 0xbfb8aa3b, v106
	v_mul_f32_e32 v119, 0xbfb8aa3b, v107
	v_mul_f32_e32 v120, 0xbfb8aa3b, v108
	v_mul_f32_e32 v114, 0xbfb8aa3b, v110
	v_mul_f32_e32 v115, 0xbfb8aa3b, v111
	v_mul_f32_e32 v116, 0xbfb8aa3b, v112
	v_mul_f32_e32 v117, 0xbfb8aa3b, v113
	v_exp_f32_e32 v118, v118
	v_exp_f32_e32 v119, v119
	v_exp_f32_e32 v120, v120
	v_exp_f32_e32 v114, v114
	v_exp_f32_e32 v115, v115
	v_exp_f32_e32 v116, v116
	v_exp_f32_e32 v117, v117
	v_add_f32_e32 v118, 1.0, v118
	v_add_f32_e32 v119, 1.0, v119
	v_add_f32_e32 v120, 1.0, v120
	v_add_f32_e32 v114, 1.0, v114
	v_add_f32_e32 v115, 1.0, v115
	v_add_f32_e32 v116, 1.0, v116
	v_add_f32_e32 v117, 1.0, v117
	v_rcp_f32_e32 v118, v118
	v_rcp_f32_e32 v119, v119
	v_rcp_f32_e32 v120, v120
	v_rcp_f32_e32 v114, v114
	v_rcp_f32_e32 v115, v115
	v_rcp_f32_e32 v116, v116
	v_rcp_f32_e32 v117, v117
	v_pk_mul_f32 v[118:119], v[106:107], v[118:119]
	v_mul_f32_e32 v120, v108, v120
	s_mov_b64 s[0:1], 0

; __device__ __forceinline__ unsigned cvt_pk_bf16(float lo, float hi) { unsigned r; asm("v_cvt_pk_bf16_f32 %0, %1, %2" : "=v"(r) : "v"(lo), "v"(hi)); return r; }
; __device__ __forceinline__ float siluf_(float x) { return x * sigmoidf_(x); }
; __device__ __forceinline__ float gelu_tanh(float x) { const float u = 0.7978845608028654f * (x + 0.044715f * x * x * x); return x * sigmoidf_(2.0f * u); }
;     __device__ __forceinline__ void operator()(f32x4 (&acc)[2][2][4][2], const pg8::Unit& u, int wr, int wc, int fr, int fq) const {
;     ...
;                 for (int m = 0; m < 4; ++m) { const int row = row0 + ai * 128 + m * 16;
; #pragma unroll
;                     for (int bj = 0; bj < 2; ++bj) { f32x4 v0 = acc[ai][bj][m][0], v1 = acc[ai][bj][m][1];
;                         if (pn < 16) { v0 = (f32x4){gelu_tanh(v0[0]), gelu_tanh(v0[1]), gelu_tanh(v0[2]), gelu_tanh(v0[3])}; v1 = (f32x4){gelu_tanh(v1[0]), gelu_tanh(v1[1]), gelu_tanh(v1[2]), gelu_tanh(v1[3])}; }
;                         else { v0 = (f32x4){siluf_(v0[0]), siluf_(v0[1]), siluf_(v0[2]), siluf_(v0[3])}; v1 = (f32x4){siluf_(v1[0]), siluf_(v1[1]), siluf_(v1[2]), siluf_(v1[3])}; }
;                         u32x4 w; w.x = cvt_pk_bf16(v0[0], v0[1]); w.y = cvt_pk_bf16(v0[2], v0[3]); w.z = cvt_pk_bf16(v1[0], v1[1]); w.w = cvt_pk_bf16(v1[2], v1[3]);
;                         *(u32x4*)(G2 + (size_t)row * 4096 + (c0 - C_RGG) + bj * 128) = w; } }
.LBB0_1739:
	v_mul_f32_e32 v106, 0xbfb8aa3b, v121
	v_exp_f32_e32 v108, v106
	v_lshlrev_b64 v[106:107], 13, v[200:201]
	v_pk_mul_f32 v[112:113], v[112:113], v[116:117]
	v_pk_mul_f32 v[110:111], v[110:111], v[114:115]
	v_add_f32_e32 v108, 1.0, v108
	v_rcp_f32_e32 v108, v108
	v_lshl_add_u64 v[106:107], v[122:123], 0, v[106:107]
	v_cvt_pk_bf16_f32 v110, v110, v111
	v_cvt_pk_bf16_f32 v111, v112, v113
	v_mul_f32_e32 v108, v109, v108
	v_cvt_pk_bf16_f32 v113, v120, v108
	v_add_co_u32_e32 v108, vcc, 0x2e90e000, v106
	v_cvt_pk_bf16_f32 v112, v118, v119
	s_mov_b64 s[0:1], -1
	s_nop 0
	v_addc_co_u32_e32 v109, vcc, 0, v107, vcc
	s_and_b64 vcc, exec, s[4:5]
	global_store_dwordx4 v[108:109], v[110:113], off
	s_cbranch_vccnz .LBB0_1741
	s_nop 0
	v_mul_f32_e32 v112, 0xbfb8aa3b, v98
	v_mul_f32_e32 v113, 0xbfb8aa3b, v99
	v_mul_f32_e32 v114, 0xbfb8aa3b, v100
	v_mul_f32_e32 v108, 0xbfb8aa3b, v102
	v_mul_f32_e32 v109, 0xbfb8aa3b, v103
	v_mul_f32_e32 v110, 0xbfb8aa3b, v104
	v_mul_f32_e32 v111, 0xbfb8aa3b, v105
	v_exp_f32_e32 v112, v112
	v_exp_f32_e32 v113, v113
	v_exp_f32_e32 v114, v114
	v_exp_f32_e32 v108, v108
	v_exp_f32_e32 v109, v109
	v_exp_f32_e32 v110, v110
	v_exp_f32_e32 v111, v111
	v_add_f32_e32 v112, 1.0, v112
	v_add_f32_e32 v113, 1.0, v113
	v_add_f32_e32 v114, 1.0, v114
	v_add_f32_e32 v108, 1.0, v108
	v_add_f32_e32 v109, 1.0, v109
	v_add_f32_e32 v110, 1.0, v110
	v_add_f32_e32 v111, 1.0, v111
	v_rcp_f32_e32 v112, v112
	v_rcp_f32_e32 v113, v113
	v_rcp_f32_e32 v114, v114
	v_rcp_f32_e32 v108, v108
	v_rcp_f32_e32 v109, v109
	v_rcp_f32_e32 v110, v110
	v_rcp_f32_e32 v111, v111
	v_pk_mul_f32 v[112:113], v[98:99], v[112:113]
	v_mul_f32_e32 v114, v100, v114
	s_mov_b64 s[0:1], 0

; __device__ __forceinline__ unsigned cvt_pk_bf16(float lo, float hi) { unsigned r; asm("v_cvt_pk_bf16_f32 %0, %1, %2" : "=v"(r) : "v"(lo), "v"(hi)); return r; }
; __device__ __forceinline__ float siluf_(float x) { return x * sigmoidf_(x); }
; __device__ __forceinline__ float gelu_tanh(float x) { const float u = 0.7978845608028654f * (x + 0.044715f * x * x * x); return x * sigmoidf_(2.0f * u); }
;     __device__ __forceinline__ void operator()(f32x4 (&acc)[2][2][4][2], const pg8::Unit& u, int wr, int wc, int fr, int fq) const {
;     ...
;                 for (int m = 0; m < 4; ++m) { const int row = row0 + ai * 128 + m * 16;
; #pragma unroll
;                     for (int bj = 0; bj < 2; ++bj) { f32x4 v0 = acc[ai][bj][m][0], v1 = acc[ai][bj][m][1];
;                         if (pn < 16) { v0 = (f32x4){gelu_tanh(v0[0]), gelu_tanh(v0[1]), gelu_tanh(v0[2]), gelu_tanh(v0[3])}; v1 = (f32x4){gelu_tanh(v1[0]), gelu_tanh(v1[1]), gelu_tanh(v1[2]), gelu_tanh(v1[3])}; }
;                         else { v0 = (f32x4){siluf_(v0[0]), siluf_(v0[1]), siluf_(v0[2]), siluf_(v0[3])}; v1 = (f32x4){siluf_(v1[0]), siluf_(v1[1]), siluf_(v1[2]), siluf_(v1[3])}; }
;                         u32x4 w; w.x = cvt_pk_bf16(v0[0], v0[1]); w.y = cvt_pk_bf16(v0[2], v0[3]); w.z = cvt_pk_bf16(v1[0], v1[1]); w.w = cvt_pk_bf16(v1[2], v1[3]);
;                         *(u32x4*)(G2 + (size_t)row * 4096 + (c0 - C_RGG) + bj * 128) = w; } }
.LBB0_1743:
	v_mul_f32_e32 v98, 0xbfb8aa3b, v115
	v_exp_f32_e32 v100, v98
	v_pk_mul_f32 v[98:99], v[102:103], v[108:109]
	v_pk_mul_f32 v[104:105], v[104:105], v[110:111]
	v_cvt_pk_bf16_f32 v98, v98, v99
	v_add_f32_e32 v100, 1.0, v100
	v_rcp_f32_e32 v102, v100
	v_cvt_pk_bf16_f32 v100, v112, v113
	v_cvt_pk_bf16_f32 v99, v104, v105
	s_mov_b64 s[0:1], -1
	v_mul_f32_e32 v101, v101, v102
	v_add_co_u32_e32 v102, vcc, 0x2e90e000, v106
	v_cvt_pk_bf16_f32 v101, v114, v101
	s_nop 1
	v_addc_co_u32_e32 v103, vcc, 0, v107, vcc
	s_and_b64 vcc, exec, s[4:5]
	global_store_dwordx4 v[102:103], v[98:101], off offset:256
	s_cbranch_vccnz .LBB0_1745
	v_mul_f32_e32 v102, 0xbfb8aa3b, v90
	v_mul_f32_e32 v103, 0xbfb8aa3b, v91
	v_mul_f32_e32 v104, 0xbfb8aa3b, v92
	v_mul_f32_e32 v98, 0xbfb8aa3b, v94
	v_mul_f32_e32 v99, 0xbfb8aa3b, v95
	v_mul_f32_e32 v100, 0xbfb8aa3b, v96
	v_mul_f32_e32 v101, 0xbfb8aa3b, v97
	v_exp_f32_e32 v102, v102
	v_exp_f32_e32 v103, v103
	v_exp_f32_e32 v104, v104
	v_exp_f32_e32 v98, v98
	v_exp_f32_e32 v99, v99
	v_exp_f32_e32 v100, v100
	v_exp_f32_e32 v101, v101
	v_add_f32_e32 v102, 1.0, v102
	v_add_f32_e32 v103, 1.0, v103
	v_add_f32_e32 v104, 1.0, v104
	v_add_f32_e32 v98, 1.0, v98
	v_add_f32_e32 v99, 1.0, v99
	v_add_f32_e32 v100, 1.0, v100
	v_add_f32_e32 v101, 1.0, v101
	v_rcp_f32_e32 v102, v102
	v_rcp_f32_e32 v103, v103
	v_rcp_f32_e32 v104, v104
	v_rcp_f32_e32 v98, v98
	v_rcp_f32_e32 v99, v99
	v_rcp_f32_e32 v100, v100
	v_rcp_f32_e32 v101, v101
	v_pk_mul_f32 v[102:103], v[90:91], v[102:103]
	v_mul_f32_e32 v104, v92, v104
	s_mov_b64 s[0:1], 0

; __device__ __forceinline__ unsigned cvt_pk_bf16(float lo, float hi) { unsigned r; asm("v_cvt_pk_bf16_f32 %0, %1, %2" : "=v"(r) : "v"(lo), "v"(hi)); return r; }
; __device__ __forceinline__ float siluf_(float x) { return x * sigmoidf_(x); }
; __device__ __forceinline__ float gelu_tanh(float x) { const float u = 0.7978845608028654f * (x + 0.044715f * x * x * x); return x * sigmoidf_(2.0f * u); }
;     __device__ __forceinline__ void operator()(f32x4 (&acc)[2][2][4][2], const pg8::Unit& u, int wr, int wc, int fr, int fq) const {
;     ...
;                 for (int m = 0; m < 4; ++m) { const int row = row0 + ai * 128 + m * 16;
; #pragma unroll
;                     for (int bj = 0; bj < 2; ++bj) { f32x4 v0 = acc[ai][bj][m][0], v1 = acc[ai][bj][m][1];
;                         if (pn < 16) { v0 = (f32x4){gelu_tanh(v0[0]), gelu_tanh(v0[1]), gelu_tanh(v0[2]), gelu_tanh(v0[3])}; v1 = (f32x4){gelu_tanh(v1[0]), gelu_tanh(v1[1]), gelu_tanh(v1[2]), gelu_tanh(v1[3])}; }
;                         else { v0 = (f32x4){siluf_(v0[0]), siluf_(v0[1]), siluf_(v0[2]), siluf_(v0[3])}; v1 = (f32x4){siluf_(v1[0]), siluf_(v1[1]), siluf_(v1[2]), siluf_(v1[3])}; }
;                         u32x4 w; w.x = cvt_pk_bf16(v0[0], v0[1]); w.y = cvt_pk_bf16(v0[2], v0[3]); w.z = cvt_pk_bf16(v1[0], v1[1]); w.w = cvt_pk_bf16(v1[2], v1[3]);
;                         *(u32x4*)(G2 + (size_t)row * 4096 + (c0 - C_RGG) + bj * 128) = w; } }
.LBB0_1747:
	v_mul_f32_e32 v90, 0xbfb8aa3b, v105
	v_exp_f32_e32 v92, v90
	v_lshlrev_b64 v[90:91], 13, v[198:199]
	v_pk_mul_f32 v[96:97], v[96:97], v[100:101]
	v_pk_mul_f32 v[94:95], v[94:95], v[98:99]
	v_add_f32_e32 v92, 1.0, v92
	v_rcp_f32_e32 v92, v92
	v_lshl_add_u64 v[90:91], v[122:123], 0, v[90:91]
	v_cvt_pk_bf16_f32 v94, v94, v95
	v_cvt_pk_bf16_f32 v95, v96, v97
	v_mul_f32_e32 v92, v93, v92
	v_cvt_pk_bf16_f32 v97, v104, v92
	v_add_co_u32_e32 v92, vcc, 0x2e90e000, v90
	v_cvt_pk_bf16_f32 v96, v102, v103
	s_mov_b64 s[0:1], -1
	s_nop 0
	v_addc_co_u32_e32 v93, vcc, 0, v91, vcc
	s_and_b64 vcc, exec, s[4:5]
	global_store_dwordx4 v[92:93], v[94:97], off
	s_cbranch_vccnz .LBB0_1749
	s_nop 0
	v_mul_f32_e32 v96, 0xbfb8aa3b, v82
	v_mul_f32_e32 v97, 0xbfb8aa3b, v83
	v_mul_f32_e32 v98, 0xbfb8aa3b, v84
	v_mul_f32_e32 v92, 0xbfb8aa3b, v86
	v_mul_f32_e32 v93, 0xbfb8aa3b, v87
	v_mul_f32_e32 v94, 0xbfb8aa3b, v88
	v_mul_f32_e32 v95, 0xbfb8aa3b, v89
	v_exp_f32_e32 v96, v96
	v_exp_f32_e32 v97, v97
	v_exp_f32_e32 v98, v98
	v_exp_f32_e32 v92, v92
	v_exp_f32_e32 v93, v93
	v_exp_f32_e32 v94, v94
	v_exp_f32_e32 v95, v95
	v_add_f32_e32 v96, 1.0, v96
	v_add_f32_e32 v97, 1.0, v97
	v_add_f32_e32 v98, 1.0, v98
	v_add_f32_e32 v92, 1.0, v92
	v_add_f32_e32 v93, 1.0, v93
	v_add_f32_e32 v94, 1.0, v94
	v_add_f32_e32 v95, 1.0, v95
	v_rcp_f32_e32 v96, v96
	v_rcp_f32_e32 v97, v97
	v_rcp_f32_e32 v98, v98
	v_rcp_f32_e32 v92, v92
	v_rcp_f32_e32 v93, v93
	v_rcp_f32_e32 v94, v94
	v_rcp_f32_e32 v95, v95
	v_pk_mul_f32 v[96:97], v[82:83], v[96:97]
	v_mul_f32_e32 v98, v84, v98
	s_mov_b64 s[0:1], 0

; __device__ __forceinline__ unsigned cvt_pk_bf16(float lo, float hi) { unsigned r; asm("v_cvt_pk_bf16_f32 %0, %1, %2" : "=v"(r) : "v"(lo), "v"(hi)); return r; }
; __device__ __forceinline__ float siluf_(float x) { return x * sigmoidf_(x); }
; __device__ __forceinline__ float gelu_tanh(float x) { const float u = 0.7978845608028654f * (x + 0.044715f * x * x * x); return x * sigmoidf_(2.0f * u); }
;     __device__ __forceinline__ void operator()(f32x4 (&acc)[2][2][4][2], const pg8::Unit& u, int wr, int wc, int fr, int fq) const {
;     ...
;                 for (int m = 0; m < 4; ++m) { const int row = row0 + ai * 128 + m * 16;
; #pragma unroll
;                     for (int bj = 0; bj < 2; ++bj) { f32x4 v0 = acc[ai][bj][m][0], v1 = acc[ai][bj][m][1];
;                         if (pn < 16) { v0 = (f32x4){gelu_tanh(v0[0]), gelu_tanh(v0[1]), gelu_tanh(v0[2]), gelu_tanh(v0[3])}; v1 = (f32x4){gelu_tanh(v1[0]), gelu_tanh(v1[1]), gelu_tanh(v1[2]), gelu_tanh(v1[3])}; }
;                         else { v0 = (f32x4){siluf_(v0[0]), siluf_(v0[1]), siluf_(v0[2]), siluf_(v0[3])}; v1 = (f32x4){siluf_(v1[0]), siluf_(v1[1]), siluf_(v1[2]), siluf_(v1[3])}; }
;                         u32x4 w; w.x = cvt_pk_bf16(v0[0], v0[1]); w.y = cvt_pk_bf16(v0[2], v0[3]); w.z = cvt_pk_bf16(v1[0], v1[1]); w.w = cvt_pk_bf16(v1[2], v1[3]);
;                         *(u32x4*)(G2 + (size_t)row * 4096 + (c0 - C_RGG) + bj * 128) = w; } }
.LBB0_1751:
	v_mul_f32_e32 v82, 0xbfb8aa3b, v99
	v_exp_f32_e32 v84, v82
	v_pk_mul_f32 v[82:83], v[86:87], v[92:93]
	v_pk_mul_f32 v[88:89], v[88:89], v[94:95]
	v_cvt_pk_bf16_f32 v82, v82, v83
	v_add_f32_e32 v84, 1.0, v84
	v_rcp_f32_e32 v86, v84
	v_cvt_pk_bf16_f32 v84, v96, v97
	v_cvt_pk_bf16_f32 v83, v88, v89
	s_mov_b64 s[0:1], -1
	v_mul_f32_e32 v85, v85, v86
	v_add_co_u32_e32 v86, vcc, 0x2e90e000, v90
	v_cvt_pk_bf16_f32 v85, v98, v85
	s_nop 1
	v_addc_co_u32_e32 v87, vcc, 0, v91, vcc
	s_and_b64 vcc, exec, s[4:5]
	global_store_dwordx4 v[86:87], v[82:85], off offset:256
	s_cbranch_vccnz .LBB0_1753
	v_mul_f32_e32 v86, 0xbfb8aa3b, v74
	v_mul_f32_e32 v87, 0xbfb8aa3b, v75
	v_mul_f32_e32 v88, 0xbfb8aa3b, v76
	v_mul_f32_e32 v82, 0xbfb8aa3b, v78
	v_mul_f32_e32 v83, 0xbfb8aa3b, v79
	v_mul_f32_e32 v84, 0xbfb8aa3b, v80
	v_mul_f32_e32 v85, 0xbfb8aa3b, v81
	v_exp_f32_e32 v86, v86
	v_exp_f32_e32 v87, v87
	v_exp_f32_e32 v88, v88
	v_exp_f32_e32 v82, v82
	v_exp_f32_e32 v83, v83
	v_exp_f32_e32 v84, v84
	v_exp_f32_e32 v85, v85
	v_add_f32_e32 v86, 1.0, v86
	v_add_f32_e32 v87, 1.0, v87
	v_add_f32_e32 v88, 1.0, v88
	v_add_f32_e32 v82, 1.0, v82
	v_add_f32_e32 v83, 1.0, v83
	v_add_f32_e32 v84, 1.0, v84
	v_add_f32_e32 v85, 1.0, v85
	v_rcp_f32_e32 v86, v86
	v_rcp_f32_e32 v87, v87
	v_rcp_f32_e32 v88, v88
	v_rcp_f32_e32 v82, v82
	v_rcp_f32_e32 v83, v83
	v_rcp_f32_e32 v84, v84
	v_rcp_f32_e32 v85, v85
	v_pk_mul_f32 v[86:87], v[74:75], v[86:87]
	v_mul_f32_e32 v88, v76, v88
	s_mov_b64 s[0:1], 0

; __device__ __forceinline__ unsigned cvt_pk_bf16(float lo, float hi) { unsigned r; asm("v_cvt_pk_bf16_f32 %0, %1, %2" : "=v"(r) : "v"(lo), "v"(hi)); return r; }
; __device__ __forceinline__ float siluf_(float x) { return x * sigmoidf_(x); }
; __device__ __forceinline__ float gelu_tanh(float x) { const float u = 0.7978845608028654f * (x + 0.044715f * x * x * x); return x * sigmoidf_(2.0f * u); }
;     __device__ __forceinline__ void operator()(f32x4 (&acc)[2][2][4][2], const pg8::Unit& u, int wr, int wc, int fr, int fq) const {
;     ...
;                 for (int m = 0; m < 4; ++m) { const int row = row0 + ai * 128 + m * 16;
; #pragma unroll
;                     for (int bj = 0; bj < 2; ++bj) { f32x4 v0 = acc[ai][bj][m][0], v1 = acc[ai][bj][m][1];
;                         if (pn < 16) { v0 = (f32x4){gelu_tanh(v0[0]), gelu_tanh(v0[1]), gelu_tanh(v0[2]), gelu_tanh(v0[3])}; v1 = (f32x4){gelu_tanh(v1[0]), gelu_tanh(v1[1]), gelu_tanh(v1[2]), gelu_tanh(v1[3])}; }
;                         else { v0 = (f32x4){siluf_(v0[0]), siluf_(v0[1]), siluf_(v0[2]), siluf_(v0[3])}; v1 = (f32x4){siluf_(v1[0]), siluf_(v1[1]), siluf_(v1[2]), siluf_(v1[3])}; }
;                         u32x4 w; w.x = cvt_pk_bf16(v0[0], v0[1]); w.y = cvt_pk_bf16(v0[2], v0[3]); w.z = cvt_pk_bf16(v1[0], v1[1]); w.w = cvt_pk_bf16(v1[2], v1[3]);
;                         *(u32x4*)(G2 + (size_t)row * 4096 + (c0 - C_RGG) + bj * 128) = w; } }
.LBB0_1755:
	v_mul_f32_e32 v74, 0xbfb8aa3b, v89
	v_exp_f32_e32 v76, v74
	v_lshlrev_b64 v[74:75], 13, v[196:197]
	v_pk_mul_f32 v[80:81], v[80:81], v[84:85]
	v_pk_mul_f32 v[78:79], v[78:79], v[82:83]
	v_add_f32_e32 v76, 1.0, v76
	v_rcp_f32_e32 v76, v76
	v_lshl_add_u64 v[74:75], v[122:123], 0, v[74:75]
	v_cvt_pk_bf16_f32 v78, v78, v79
	v_cvt_pk_bf16_f32 v79, v80, v81
	v_mul_f32_e32 v76, v77, v76
	v_cvt_pk_bf16_f32 v81, v88, v76
	v_add_co_u32_e32 v76, vcc, 0x2e90e000, v74
	v_cvt_pk_bf16_f32 v80, v86, v87
	s_mov_b64 s[0:1], -1
	s_nop 0
	v_addc_co_u32_e32 v77, vcc, 0, v75, vcc
	s_and_b64 vcc, exec, s[4:5]
	global_store_dwordx4 v[76:77], v[78:81], off
	s_cbranch_vccnz .LBB0_1757
	s_nop 0
	v_mul_f32_e32 v80, 0xbfb8aa3b, v66
	v_mul_f32_e32 v81, 0xbfb8aa3b, v67
	v_mul_f32_e32 v82, 0xbfb8aa3b, v68
	v_mul_f32_e32 v76, 0xbfb8aa3b, v70
	v_mul_f32_e32 v77, 0xbfb8aa3b, v71
	v_mul_f32_e32 v78, 0xbfb8aa3b, v72
	v_mul_f32_e32 v79, 0xbfb8aa3b, v73
	v_exp_f32_e32 v80, v80
	v_exp_f32_e32 v81, v81
	v_exp_f32_e32 v82, v82
	v_exp_f32_e32 v76, v76
	v_exp_f32_e32 v77, v77
	v_exp_f32_e32 v78, v78
	v_exp_f32_e32 v79, v79
	v_add_f32_e32 v80, 1.0, v80
	v_add_f32_e32 v81, 1.0, v81
	v_add_f32_e32 v82, 1.0, v82
	v_add_f32_e32 v76, 1.0, v76
	v_add_f32_e32 v77, 1.0, v77
	v_add_f32_e32 v78, 1.0, v78
	v_add_f32_e32 v79, 1.0, v79
	v_rcp_f32_e32 v80, v80
	v_rcp_f32_e32 v81, v81
	v_rcp_f32_e32 v82, v82
	v_rcp_f32_e32 v76, v76
	v_rcp_f32_e32 v77, v77
	v_rcp_f32_e32 v78, v78
	v_rcp_f32_e32 v79, v79
	v_pk_mul_f32 v[80:81], v[66:67], v[80:81]
	v_mul_f32_e32 v82, v68, v82
	s_mov_b64 s[0:1], 0

; __device__ __forceinline__ unsigned cvt_pk_bf16(float lo, float hi) { unsigned r; asm("v_cvt_pk_bf16_f32 %0, %1, %2" : "=v"(r) : "v"(lo), "v"(hi)); return r; }
; __device__ __forceinline__ float siluf_(float x) { return x * sigmoidf_(x); }
; __device__ __forceinline__ float gelu_tanh(float x) { const float u = 0.7978845608028654f * (x + 0.044715f * x * x * x); return x * sigmoidf_(2.0f * u); }
;     __device__ __forceinline__ void operator()(f32x4 (&acc)[2][2][4][2], const pg8::Unit& u, int wr, int wc, int fr, int fq) const {
;     ...
;                 for (int m = 0; m < 4; ++m) { const int row = row0 + ai * 128 + m * 16;
; #pragma unroll
;                     for (int bj = 0; bj < 2; ++bj) { f32x4 v0 = acc[ai][bj][m][0], v1 = acc[ai][bj][m][1];
;                         if (pn < 16) { v0 = (f32x4){gelu_tanh(v0[0]), gelu_tanh(v0[1]), gelu_tanh(v0[2]), gelu_tanh(v0[3])}; v1 = (f32x4){gelu_tanh(v1[0]), gelu_tanh(v1[1]), gelu_tanh(v1[2]), gelu_tanh(v1[3])}; }
;                         else { v0 = (f32x4){siluf_(v0[0]), siluf_(v0[1]), siluf_(v0[2]), siluf_(v0[3])}; v1 = (f32x4){siluf_(v1[0]), siluf_(v1[1]), siluf_(v1[2]), siluf_(v1[3])}; }
;                         u32x4 w; w.x = cvt_pk_bf16(v0[0], v0[1]); w.y = cvt_pk_bf16(v0[2], v0[3]); w.z = cvt_pk_bf16(v1[0], v1[1]); w.w = cvt_pk_bf16(v1[2], v1[3]);
;                         *(u32x4*)(G2 + (size_t)row * 4096 + (c0 - C_RGG) + bj * 128) = w; } }
.LBB0_1759:
	v_mul_f32_e32 v66, 0xbfb8aa3b, v83
	v_exp_f32_e32 v68, v66
	v_pk_mul_f32 v[66:67], v[70:71], v[76:77]
	v_pk_mul_f32 v[72:73], v[72:73], v[78:79]
	v_cvt_pk_bf16_f32 v66, v66, v67
	v_add_f32_e32 v68, 1.0, v68
	v_rcp_f32_e32 v70, v68
	v_cvt_pk_bf16_f32 v68, v80, v81
	v_cvt_pk_bf16_f32 v67, v72, v73
	s_mov_b64 s[0:1], -1
	v_mul_f32_e32 v69, v69, v70
	v_add_co_u32_e32 v70, vcc, 0x2e90e000, v74
	v_cvt_pk_bf16_f32 v69, v82, v69
	s_nop 1
	v_addc_co_u32_e32 v71, vcc, 0, v75, vcc
	s_and_b64 vcc, exec, s[4:5]
	global_store_dwordx4 v[70:71], v[66:69], off offset:256
	s_cbranch_vccnz .LBB0_1761
	v_mul_f32_e32 v70, 0xbfb8aa3b, v58
	v_mul_f32_e32 v71, 0xbfb8aa3b, v59
	v_mul_f32_e32 v72, 0xbfb8aa3b, v60
	v_mul_f32_e32 v66, 0xbfb8aa3b, v62
	v_mul_f32_e32 v67, 0xbfb8aa3b, v63
	v_mul_f32_e32 v68, 0xbfb8aa3b, v64
	v_mul_f32_e32 v69, 0xbfb8aa3b, v65
	v_exp_f32_e32 v70, v70
	v_exp_f32_e32 v71, v71
	v_exp_f32_e32 v72, v72
	v_exp_f32_e32 v66, v66
	v_exp_f32_e32 v67, v67
	v_exp_f32_e32 v68, v68
	v_exp_f32_e32 v69, v69
	v_add_f32_e32 v70, 1.0, v70
	v_add_f32_e32 v71, 1.0, v71
	v_add_f32_e32 v72, 1.0, v72
	v_add_f32_e32 v66, 1.0, v66
	v_add_f32_e32 v67, 1.0, v67
	v_add_f32_e32 v68, 1.0, v68
	v_add_f32_e32 v69, 1.0, v69
	v_rcp_f32_e32 v70, v70
	v_rcp_f32_e32 v71, v71
	v_rcp_f32_e32 v72, v72
	v_rcp_f32_e32 v66, v66
	v_rcp_f32_e32 v67, v67
	v_rcp_f32_e32 v68, v68
	v_rcp_f32_e32 v69, v69
	v_pk_mul_f32 v[70:71], v[58:59], v[70:71]
	v_mul_f32_e32 v72, v60, v72
	s_mov_b64 s[0:1], 0

; __device__ __forceinline__ unsigned cvt_pk_bf16(float lo, float hi) { unsigned r; asm("v_cvt_pk_bf16_f32 %0, %1, %2" : "=v"(r) : "v"(lo), "v"(hi)); return r; }
; __device__ __forceinline__ float siluf_(float x) { return x * sigmoidf_(x); }
; __device__ __forceinline__ float gelu_tanh(float x) { const float u = 0.7978845608028654f * (x + 0.044715f * x * x * x); return x * sigmoidf_(2.0f * u); }
;     __device__ __forceinline__ void operator()(f32x4 (&acc)[2][2][4][2], const pg8::Unit& u, int wr, int wc, int fr, int fq) const {
;     ...
;                 for (int m = 0; m < 4; ++m) { const int row = row0 + ai * 128 + m * 16;
; #pragma unroll
;                     for (int bj = 0; bj < 2; ++bj) { f32x4 v0 = acc[ai][bj][m][0], v1 = acc[ai][bj][m][1];
;                         if (pn < 16) { v0 = (f32x4){gelu_tanh(v0[0]), gelu_tanh(v0[1]), gelu_tanh(v0[2]), gelu_tanh(v0[3])}; v1 = (f32x4){gelu_tanh(v1[0]), gelu_tanh(v1[1]), gelu_tanh(v1[2]), gelu_tanh(v1[3])}; }
;                         else { v0 = (f32x4){siluf_(v0[0]), siluf_(v0[1]), siluf_(v0[2]), siluf_(v0[3])}; v1 = (f32x4){siluf_(v1[0]), siluf_(v1[1]), siluf_(v1[2]), siluf_(v1[3])}; }
;                         u32x4 w; w.x = cvt_pk_bf16(v0[0], v0[1]); w.y = cvt_pk_bf16(v0[2], v0[3]); w.z = cvt_pk_bf16(v1[0], v1[1]); w.w = cvt_pk_bf16(v1[2], v1[3]);
;                         *(u32x4*)(G2 + (size_t)row * 4096 + (c0 - C_RGG) + bj * 128) = w; } }
.LBB0_1763:
	v_mul_f32_e32 v58, 0xbfb8aa3b, v73
	v_exp_f32_e32 v60, v58
	v_lshlrev_b64 v[58:59], 13, v[194:195]
	v_pk_mul_f32 v[64:65], v[64:65], v[68:69]
	v_pk_mul_f32 v[62:63], v[62:63], v[66:67]
	v_add_f32_e32 v60, 1.0, v60
	v_rcp_f32_e32 v60, v60
	v_lshl_add_u64 v[58:59], v[122:123], 0, v[58:59]
	v_cvt_pk_bf16_f32 v62, v62, v63
	v_cvt_pk_bf16_f32 v63, v64, v65
	v_mul_f32_e32 v60, v61, v60
	v_cvt_pk_bf16_f32 v65, v72, v60
	v_add_co_u32_e32 v60, vcc, 0x2e90e000, v58
	v_cvt_pk_bf16_f32 v64, v70, v71
	s_mov_b64 s[0:1], -1
	s_nop 0
	v_addc_co_u32_e32 v61, vcc, 0, v59, vcc
	s_and_b64 vcc, exec, s[4:5]
	global_store_dwordx4 v[60:61], v[62:65], off
	s_cbranch_vccnz .LBB0_1765
	s_nop 0
	v_mul_f32_e32 v64, 0xbfb8aa3b, v50
	v_mul_f32_e32 v65, 0xbfb8aa3b, v51
	v_mul_f32_e32 v66, 0xbfb8aa3b, v52
	v_mul_f32_e32 v60, 0xbfb8aa3b, v54
	v_mul_f32_e32 v61, 0xbfb8aa3b, v55
	v_mul_f32_e32 v62, 0xbfb8aa3b, v56
	v_mul_f32_e32 v63, 0xbfb8aa3b, v57
	v_exp_f32_e32 v64, v64
	v_exp_f32_e32 v65, v65
	v_exp_f32_e32 v66, v66
	v_exp_f32_e32 v60, v60
	v_exp_f32_e32 v61, v61
	v_exp_f32_e32 v62, v62
	v_exp_f32_e32 v63, v63
	v_add_f32_e32 v64, 1.0, v64
	v_add_f32_e32 v65, 1.0, v65
	v_add_f32_e32 v66, 1.0, v66
	v_add_f32_e32 v60, 1.0, v60
	v_add_f32_e32 v61, 1.0, v61
	v_add_f32_e32 v62, 1.0, v62
	v_add_f32_e32 v63, 1.0, v63
	v_rcp_f32_e32 v64, v64
	v_rcp_f32_e32 v65, v65
	v_rcp_f32_e32 v66, v66
	v_rcp_f32_e32 v60, v60
	v_rcp_f32_e32 v61, v61
	v_rcp_f32_e32 v62, v62
	v_rcp_f32_e32 v63, v63
	v_pk_mul_f32 v[64:65], v[50:51], v[64:65]
	v_mul_f32_e32 v66, v52, v66
	s_mov_b64 s[0:1], 0

; __device__ __forceinline__ unsigned cvt_pk_bf16(float lo, float hi) { unsigned r; asm("v_cvt_pk_bf16_f32 %0, %1, %2" : "=v"(r) : "v"(lo), "v"(hi)); return r; }
; __device__ __forceinline__ float siluf_(float x) { return x * sigmoidf_(x); }
; __device__ __forceinline__ float gelu_tanh(float x) { const float u = 0.7978845608028654f * (x + 0.044715f * x * x * x); return x * sigmoidf_(2.0f * u); }
;     __device__ __forceinline__ void operator()(f32x4 (&acc)[2][2][4][2], const pg8::Unit& u, int wr, int wc, int fr, int fq) const {
;     ...
;                 for (int m = 0; m < 4; ++m) { const int row = row0 + ai * 128 + m * 16;
; #pragma unroll
;                     for (int bj = 0; bj < 2; ++bj) { f32x4 v0 = acc[ai][bj][m][0], v1 = acc[ai][bj][m][1];
;                         if (pn < 16) { v0 = (f32x4){gelu_tanh(v0[0]), gelu_tanh(v0[1]), gelu_tanh(v0[2]), gelu_tanh(v0[3])}; v1 = (f32x4){gelu_tanh(v1[0]), gelu_tanh(v1[1]), gelu_tanh(v1[2]), gelu_tanh(v1[3])}; }
;                         else { v0 = (f32x4){siluf_(v0[0]), siluf_(v0[1]), siluf_(v0[2]), siluf_(v0[3])}; v1 = (f32x4){siluf_(v1[0]), siluf_(v1[1]), siluf_(v1[2]), siluf_(v1[3])}; }
;                         u32x4 w; w.x = cvt_pk_bf16(v0[0], v0[1]); w.y = cvt_pk_bf16(v0[2], v0[3]); w.z = cvt_pk_bf16(v1[0], v1[1]); w.w = cvt_pk_bf16(v1[2], v1[3]);
;                         *(u32x4*)(G2 + (size_t)row * 4096 + (c0 - C_RGG) + bj * 128) = w; } }
.LBB0_1767:
	v_mul_f32_e32 v50, 0xbfb8aa3b, v67
	v_exp_f32_e32 v52, v50
	v_pk_mul_f32 v[50:51], v[54:55], v[60:61]
	v_pk_mul_f32 v[56:57], v[56:57], v[62:63]
	v_cvt_pk_bf16_f32 v50, v50, v51
	v_add_f32_e32 v52, 1.0, v52
	v_rcp_f32_e32 v54, v52
	v_cvt_pk_bf16_f32 v52, v64, v65
	v_cvt_pk_bf16_f32 v51, v56, v57
	s_mov_b64 s[0:1], -1
	v_mul_f32_e32 v53, v53, v54
	v_add_co_u32_e32 v54, vcc, 0x2e90e000, v58
	v_cvt_pk_bf16_f32 v53, v66, v53
	s_nop 1
	v_addc_co_u32_e32 v55, vcc, 0, v59, vcc
	s_and_b64 vcc, exec, s[4:5]
	global_store_dwordx4 v[54:55], v[50:53], off offset:256
	s_cbranch_vccnz .LBB0_1769
	v_mul_f32_e32 v54, 0xbfb8aa3b, v42
	v_mul_f32_e32 v55, 0xbfb8aa3b, v43
	v_mul_f32_e32 v56, 0xbfb8aa3b, v44
	v_mul_f32_e32 v50, 0xbfb8aa3b, v46
	v_mul_f32_e32 v51, 0xbfb8aa3b, v47
	v_mul_f32_e32 v52, 0xbfb8aa3b, v48
	v_mul_f32_e32 v53, 0xbfb8aa3b, v49
	v_exp_f32_e32 v54, v54
	v_exp_f32_e32 v55, v55
	v_exp_f32_e32 v56, v56
	v_exp_f32_e32 v50, v50
	v_exp_f32_e32 v51, v51
	v_exp_f32_e32 v52, v52
	v_exp_f32_e32 v53, v53
	v_add_f32_e32 v54, 1.0, v54
	v_add_f32_e32 v55, 1.0, v55
	v_add_f32_e32 v56, 1.0, v56
	v_add_f32_e32 v50, 1.0, v50
	v_add_f32_e32 v51, 1.0, v51
	v_add_f32_e32 v52, 1.0, v52
	v_add_f32_e32 v53, 1.0, v53
	v_rcp_f32_e32 v54, v54
	v_rcp_f32_e32 v55, v55
	v_rcp_f32_e32 v56, v56
	v_rcp_f32_e32 v50, v50
	v_rcp_f32_e32 v51, v51
	v_rcp_f32_e32 v52, v52
	v_rcp_f32_e32 v53, v53
	v_pk_mul_f32 v[54:55], v[42:43], v[54:55]
	v_mul_f32_e32 v56, v44, v56
	s_mov_b64 s[0:1], 0

; __device__ __forceinline__ unsigned cvt_pk_bf16(float lo, float hi) { unsigned r; asm("v_cvt_pk_bf16_f32 %0, %1, %2" : "=v"(r) : "v"(lo), "v"(hi)); return r; }
; __device__ __forceinline__ float siluf_(float x) { return x * sigmoidf_(x); }
; __device__ __forceinline__ float gelu_tanh(float x) { const float u = 0.7978845608028654f * (x + 0.044715f * x * x * x); return x * sigmoidf_(2.0f * u); }
;     __device__ __forceinline__ void operator()(f32x4 (&acc)[2][2][4][2], const pg8::Unit& u, int wr, int wc, int fr, int fq) const {
;     ...
;                 for (int m = 0; m < 4; ++m) { const int row = row0 + ai * 128 + m * 16;
; #pragma unroll
;                     for (int bj = 0; bj < 2; ++bj) { f32x4 v0 = acc[ai][bj][m][0], v1 = acc[ai][bj][m][1];
;                         if (pn < 16) { v0 = (f32x4){gelu_tanh(v0[0]), gelu_tanh(v0[1]), gelu_tanh(v0[2]), gelu_tanh(v0[3])}; v1 = (f32x4){gelu_tanh(v1[0]), gelu_tanh(v1[1]), gelu_tanh(v1[2]), gelu_tanh(v1[3])}; }
;                         else { v0 = (f32x4){siluf_(v0[0]), siluf_(v0[1]), siluf_(v0[2]), siluf_(v0[3])}; v1 = (f32x4){siluf_(v1[0]), siluf_(v1[1]), siluf_(v1[2]), siluf_(v1[3])}; }
;                         u32x4 w; w.x = cvt_pk_bf16(v0[0], v0[1]); w.y = cvt_pk_bf16(v0[2], v0[3]); w.z = cvt_pk_bf16(v1[0], v1[1]); w.w = cvt_pk_bf16(v1[2], v1[3]);
;                         *(u32x4*)(G2 + (size_t)row * 4096 + (c0 - C_RGG) + bj * 128) = w; } }
.LBB0_1771:
	v_mul_f32_e32 v42, 0xbfb8aa3b, v57
	v_exp_f32_e32 v44, v42
	v_lshlrev_b64 v[42:43], 13, v[192:193]
	v_pk_mul_f32 v[48:49], v[48:49], v[52:53]
	v_pk_mul_f32 v[46:47], v[46:47], v[50:51]
	v_add_f32_e32 v44, 1.0, v44
	v_rcp_f32_e32 v44, v44
	v_lshl_add_u64 v[42:43], v[122:123], 0, v[42:43]
	v_cvt_pk_bf16_f32 v46, v46, v47
	v_cvt_pk_bf16_f32 v47, v48, v49
	v_mul_f32_e32 v44, v45, v44
	v_cvt_pk_bf16_f32 v49, v56, v44
	v_add_co_u32_e32 v44, vcc, 0x2e90e000, v42
	v_cvt_pk_bf16_f32 v48, v54, v55
	s_mov_b64 s[0:1], -1
	s_nop 0
	v_addc_co_u32_e32 v45, vcc, 0, v43, vcc
	s_and_b64 vcc, exec, s[4:5]
	global_store_dwordx4 v[44:45], v[46:49], off
	s_cbranch_vccnz .LBB0_1773
	s_nop 0
	v_mul_f32_e32 v48, 0xbfb8aa3b, v34
	v_mul_f32_e32 v49, 0xbfb8aa3b, v35
	v_mul_f32_e32 v50, 0xbfb8aa3b, v36
	v_mul_f32_e32 v44, 0xbfb8aa3b, v38
	v_mul_f32_e32 v45, 0xbfb8aa3b, v39
	v_mul_f32_e32 v46, 0xbfb8aa3b, v40
	v_mul_f32_e32 v47, 0xbfb8aa3b, v41
	v_exp_f32_e32 v48, v48
	v_exp_f32_e32 v49, v49
	v_exp_f32_e32 v50, v50
	v_exp_f32_e32 v44, v44
	v_exp_f32_e32 v45, v45
	v_exp_f32_e32 v46, v46
	v_exp_f32_e32 v47, v47
	v_add_f32_e32 v48, 1.0, v48
	v_add_f32_e32 v49, 1.0, v49
	v_add_f32_e32 v50, 1.0, v50
	v_add_f32_e32 v44, 1.0, v44
	v_add_f32_e32 v45, 1.0, v45
	v_add_f32_e32 v46, 1.0, v46
	v_add_f32_e32 v47, 1.0, v47
	v_rcp_f32_e32 v48, v48
	v_rcp_f32_e32 v49, v49
	v_rcp_f32_e32 v50, v50
	v_rcp_f32_e32 v44, v44
	v_rcp_f32_e32 v45, v45
	v_rcp_f32_e32 v46, v46
	v_rcp_f32_e32 v47, v47
	v_pk_mul_f32 v[48:49], v[34:35], v[48:49]
	v_mul_f32_e32 v50, v36, v50
	s_mov_b64 s[0:1], 0

; __device__ __forceinline__ unsigned cvt_pk_bf16(float lo, float hi) { unsigned r; asm("v_cvt_pk_bf16_f32 %0, %1, %2" : "=v"(r) : "v"(lo), "v"(hi)); return r; }
; __device__ __forceinline__ float siluf_(float x) { return x * sigmoidf_(x); }
; __device__ __forceinline__ float gelu_tanh(float x) { const float u = 0.7978845608028654f * (x + 0.044715f * x * x * x); return x * sigmoidf_(2.0f * u); }
;     __device__ __forceinline__ void operator()(f32x4 (&acc)[2][2][4][2], const pg8::Unit& u, int wr, int wc, int fr, int fq) const {
;     ...
;                 for (int m = 0; m < 4; ++m) { const int row = row0 + ai * 128 + m * 16;
; #pragma unroll
;                     for (int bj = 0; bj < 2; ++bj) { f32x4 v0 = acc[ai][bj][m][0], v1 = acc[ai][bj][m][1];
;                         if (pn < 16) { v0 = (f32x4){gelu_tanh(v0[0]), gelu_tanh(v0[1]), gelu_tanh(v0[2]), gelu_tanh(v0[3])}; v1 = (f32x4){gelu_tanh(v1[0]), gelu_tanh(v1[1]), gelu_tanh(v1[2]), gelu_tanh(v1[3])}; }
;                         else { v0 = (f32x4){siluf_(v0[0]), siluf_(v0[1]), siluf_(v0[2]), siluf_(v0[3])}; v1 = (f32x4){siluf_(v1[0]), siluf_(v1[1]), siluf_(v1[2]), siluf_(v1[3])}; }
;                         u32x4 w; w.x = cvt_pk_bf16(v0[0], v0[1]); w.y = cvt_pk_bf16(v0[2], v0[3]); w.z = cvt_pk_bf16(v1[0], v1[1]); w.w = cvt_pk_bf16(v1[2], v1[3]);
;                         *(u32x4*)(G2 + (size_t)row * 4096 + (c0 - C_RGG) + bj * 128) = w; } }
.LBB0_1775:
	v_mul_f32_e32 v34, 0xbfb8aa3b, v51
	v_exp_f32_e32 v36, v34
	v_pk_mul_f32 v[34:35], v[38:39], v[44:45]
	v_pk_mul_f32 v[40:41], v[40:41], v[46:47]
	v_cvt_pk_bf16_f32 v34, v34, v35
	v_add_f32_e32 v36, 1.0, v36
	v_rcp_f32_e32 v38, v36
	v_cvt_pk_bf16_f32 v36, v48, v49
	v_cvt_pk_bf16_f32 v35, v40, v41
	s_mov_b64 s[0:1], -1
	v_mul_f32_e32 v37, v37, v38
	v_add_co_u32_e32 v38, vcc, 0x2e90e000, v42
	v_cvt_pk_bf16_f32 v37, v50, v37
	s_nop 1
	v_addc_co_u32_e32 v39, vcc, 0, v43, vcc
	s_and_b64 vcc, exec, s[4:5]
	global_store_dwordx4 v[38:39], v[34:37], off offset:256
	s_cbranch_vccnz .LBB0_1777
	v_mul_f32_e32 v38, 0xbfb8aa3b, v30
	v_mul_f32_e32 v39, 0xbfb8aa3b, v31
	v_mul_f32_e32 v40, 0xbfb8aa3b, v32
	v_mul_f32_e32 v34, 0xbfb8aa3b, v26
	v_mul_f32_e32 v35, 0xbfb8aa3b, v27
	v_mul_f32_e32 v36, 0xbfb8aa3b, v28
	v_mul_f32_e32 v37, 0xbfb8aa3b, v29
	v_exp_f32_e32 v38, v38
	v_exp_f32_e32 v39, v39
	v_exp_f32_e32 v40, v40
	v_exp_f32_e32 v34, v34
	v_exp_f32_e32 v35, v35
	v_exp_f32_e32 v36, v36
	v_exp_f32_e32 v37, v37
	v_add_f32_e32 v38, 1.0, v38
	v_add_f32_e32 v39, 1.0, v39
	v_add_f32_e32 v40, 1.0, v40
	v_add_f32_e32 v34, 1.0, v34
	v_add_f32_e32 v35, 1.0, v35
	v_add_f32_e32 v36, 1.0, v36
	v_add_f32_e32 v37, 1.0, v37
	v_rcp_f32_e32 v38, v38
	v_rcp_f32_e32 v39, v39
	v_rcp_f32_e32 v40, v40
	v_rcp_f32_e32 v34, v34
	v_rcp_f32_e32 v35, v35
	v_rcp_f32_e32 v36, v36
	v_rcp_f32_e32 v37, v37
	v_pk_mul_f32 v[38:39], v[30:31], v[38:39]
	v_mul_f32_e32 v40, v32, v40
	s_mov_b64 s[0:1], 0

; __device__ __forceinline__ unsigned cvt_pk_bf16(float lo, float hi) { unsigned r; asm("v_cvt_pk_bf16_f32 %0, %1, %2" : "=v"(r) : "v"(lo), "v"(hi)); return r; }
; __device__ __forceinline__ float siluf_(float x) { return x * sigmoidf_(x); }
; __device__ __forceinline__ float gelu_tanh(float x) { const float u = 0.7978845608028654f * (x + 0.044715f * x * x * x); return x * sigmoidf_(2.0f * u); }
;     __device__ __forceinline__ void operator()(f32x4 (&acc)[2][2][4][2], const pg8::Unit& u, int wr, int wc, int fr, int fq) const {
;     ...
;                 for (int m = 0; m < 4; ++m) { const int row = row0 + ai * 128 + m * 16;
; #pragma unroll
;                     for (int bj = 0; bj < 2; ++bj) { f32x4 v0 = acc[ai][bj][m][0], v1 = acc[ai][bj][m][1];
;                         if (pn < 16) { v0 = (f32x4){gelu_tanh(v0[0]), gelu_tanh(v0[1]), gelu_tanh(v0[2]), gelu_tanh(v0[3])}; v1 = (f32x4){gelu_tanh(v1[0]), gelu_tanh(v1[1]), gelu_tanh(v1[2]), gelu_tanh(v1[3])}; }
;                         else { v0 = (f32x4){siluf_(v0[0]), siluf_(v0[1]), siluf_(v0[2]), siluf_(v0[3])}; v1 = (f32x4){siluf_(v1[0]), siluf_(v1[1]), siluf_(v1[2]), siluf_(v1[3])}; }
;                         u32x4 w; w.x = cvt_pk_bf16(v0[0], v0[1]); w.y = cvt_pk_bf16(v0[2], v0[3]); w.z = cvt_pk_bf16(v1[0], v1[1]); w.w = cvt_pk_bf16(v1[2], v1[3]);
;                         *(u32x4*)(G2 + (size_t)row * 4096 + (c0 - C_RGG) + bj * 128) = w; } }
.LBB0_1779:
	v_mul_f32_e32 v30, 0xbfb8aa3b, v41
	v_exp_f32_e32 v32, v30
	v_pk_mul_f32 v[36:37], v[28:29], v[36:37]
	v_pk_mul_f32 v[28:29], v[26:27], v[34:35]
	v_lshlrev_b64 v[30:31], 13, v[190:191]
	v_add_f32_e32 v26, 1.0, v32
	v_rcp_f32_e32 v32, v26
	v_lshl_add_u64 v[26:27], v[122:123], 0, v[30:31]
	v_cvt_pk_bf16_f32 v28, v28, v29
	v_cvt_pk_bf16_f32 v29, v36, v37
	v_mul_f32_e32 v31, v33, v32
	v_add_co_u32_e32 v32, vcc, 0x2e90e000, v26
	v_cvt_pk_bf16_f32 v30, v38, v39
	v_cvt_pk_bf16_f32 v31, v40, v31
	s_mov_b64 s[0:1], -1
	s_nop 0
	v_addc_co_u32_e32 v33, vcc, 0, v27, vcc
	s_and_b64 vcc, exec, s[4:5]
	global_store_dwordx4 v[32:33], v[28:31], off
	s_cbranch_vccnz .LBB0_1781
	v_mul_f32_e32 v32, 0xbfb8aa3b, v18
	v_mul_f32_e32 v33, 0xbfb8aa3b, v19
	v_mul_f32_e32 v34, 0xbfb8aa3b, v20
	v_mul_f32_e32 v28, 0xbfb8aa3b, v22
	v_mul_f32_e32 v29, 0xbfb8aa3b, v23
	v_mul_f32_e32 v30, 0xbfb8aa3b, v24
	v_mul_f32_e32 v31, 0xbfb8aa3b, v25
	v_exp_f32_e32 v32, v32
	v_exp_f32_e32 v33, v33
	v_exp_f32_e32 v34, v34
	v_exp_f32_e32 v28, v28
	v_exp_f32_e32 v29, v29
	v_exp_f32_e32 v30, v30
	v_exp_f32_e32 v31, v31
	v_add_f32_e32 v32, 1.0, v32
	v_add_f32_e32 v33, 1.0, v33
	v_add_f32_e32 v34, 1.0, v34
	v_add_f32_e32 v28, 1.0, v28
	v_add_f32_e32 v29, 1.0, v29
	v_add_f32_e32 v30, 1.0, v30
	v_add_f32_e32 v31, 1.0, v31
	v_rcp_f32_e32 v32, v32
	v_rcp_f32_e32 v33, v33
	v_rcp_f32_e32 v34, v34
	v_rcp_f32_e32 v28, v28
	v_rcp_f32_e32 v29, v29
	v_rcp_f32_e32 v30, v30
	v_rcp_f32_e32 v31, v31
	v_pk_mul_f32 v[32:33], v[18:19], v[32:33]
	v_mul_f32_e32 v34, v20, v34
	s_mov_b64 s[0:1], 0

; __device__ __forceinline__ unsigned cvt_pk_bf16(float lo, float hi) { unsigned r; asm("v_cvt_pk_bf16_f32 %0, %1, %2" : "=v"(r) : "v"(lo), "v"(hi)); return r; }
; __device__ __forceinline__ float siluf_(float x) { return x * sigmoidf_(x); }
; __device__ __forceinline__ float gelu_tanh(float x) { const float u = 0.7978845608028654f * (x + 0.044715f * x * x * x); return x * sigmoidf_(2.0f * u); }
;     __device__ __forceinline__ void operator()(f32x4 (&acc)[2][2][4][2], const pg8::Unit& u, int wr, int wc, int fr, int fq) const {
;     ...
;                 for (int m = 0; m < 4; ++m) { const int row = row0 + ai * 128 + m * 16;
; #pragma unroll
;                     for (int bj = 0; bj < 2; ++bj) { f32x4 v0 = acc[ai][bj][m][0], v1 = acc[ai][bj][m][1];
;                         if (pn < 16) { v0 = (f32x4){gelu_tanh(v0[0]), gelu_tanh(v0[1]), gelu_tanh(v0[2]), gelu_tanh(v0[3])}; v1 = (f32x4){gelu_tanh(v1[0]), gelu_tanh(v1[1]), gelu_tanh(v1[2]), gelu_tanh(v1[3])}; }
;                         else { v0 = (f32x4){siluf_(v0[0]), siluf_(v0[1]), siluf_(v0[2]), siluf_(v0[3])}; v1 = (f32x4){siluf_(v1[0]), siluf_(v1[1]), siluf_(v1[2]), siluf_(v1[3])}; }
;                         u32x4 w; w.x = cvt_pk_bf16(v0[0], v0[1]); w.y = cvt_pk_bf16(v0[2], v0[3]); w.z = cvt_pk_bf16(v1[0], v1[1]); w.w = cvt_pk_bf16(v1[2], v1[3]);
;                         *(u32x4*)(G2 + (size_t)row * 4096 + (c0 - C_RGG) + bj * 128) = w; } }
.LBB0_1783:
	v_mul_f32_e32 v18, 0xbfb8aa3b, v35
	v_exp_f32_e32 v20, v18
	v_pk_mul_f32 v[18:19], v[22:23], v[28:29]
	v_pk_mul_f32 v[24:25], v[24:25], v[30:31]
	v_cvt_pk_bf16_f32 v18, v18, v19
	v_add_f32_e32 v20, 1.0, v20
	v_rcp_f32_e32 v22, v20
	v_cvt_pk_bf16_f32 v20, v32, v33
	v_cvt_pk_bf16_f32 v19, v24, v25
	s_mov_b64 s[0:1], -1
	v_mul_f32_e32 v21, v21, v22
	v_add_co_u32_e32 v22, vcc, 0x2e90e000, v26
	v_cvt_pk_bf16_f32 v21, v34, v21
	s_nop 1
	v_addc_co_u32_e32 v23, vcc, 0, v27, vcc
	s_and_b64 vcc, exec, s[4:5]
	global_store_dwordx4 v[22:23], v[18:21], off offset:256
	s_cbranch_vccnz .LBB0_1785
	v_mul_f32_e32 v22, 0xbfb8aa3b, v10
	v_mul_f32_e32 v23, 0xbfb8aa3b, v11
	v_mul_f32_e32 v24, 0xbfb8aa3b, v12
	v_mul_f32_e32 v18, 0xbfb8aa3b, v14
	v_mul_f32_e32 v19, 0xbfb8aa3b, v15
	v_mul_f32_e32 v20, 0xbfb8aa3b, v16
	v_mul_f32_e32 v21, 0xbfb8aa3b, v17
	v_exp_f32_e32 v22, v22
	v_exp_f32_e32 v23, v23
	v_exp_f32_e32 v24, v24
	v_exp_f32_e32 v18, v18
	v_exp_f32_e32 v19, v19
	v_exp_f32_e32 v20, v20
	v_exp_f32_e32 v21, v21
	v_add_f32_e32 v22, 1.0, v22
	v_add_f32_e32 v23, 1.0, v23
	v_add_f32_e32 v24, 1.0, v24
	v_add_f32_e32 v18, 1.0, v18
	v_add_f32_e32 v19, 1.0, v19
	v_add_f32_e32 v20, 1.0, v20
	v_add_f32_e32 v21, 1.0, v21
	v_rcp_f32_e32 v22, v22
	v_rcp_f32_e32 v23, v23
	v_rcp_f32_e32 v24, v24
	v_rcp_f32_e32 v18, v18
	v_rcp_f32_e32 v19, v19
	v_rcp_f32_e32 v20, v20
	v_rcp_f32_e32 v21, v21
	v_pk_mul_f32 v[22:23], v[10:11], v[22:23]
	v_mul_f32_e32 v24, v12, v24
	s_mov_b64 s[0:1], 0

; __device__ __forceinline__ unsigned cvt_pk_bf16(float lo, float hi) { unsigned r; asm("v_cvt_pk_bf16_f32 %0, %1, %2" : "=v"(r) : "v"(lo), "v"(hi)); return r; }
; __device__ __forceinline__ float siluf_(float x) { return x * sigmoidf_(x); }
; __device__ __forceinline__ float gelu_tanh(float x) { const float u = 0.7978845608028654f * (x + 0.044715f * x * x * x); return x * sigmoidf_(2.0f * u); }
;     __device__ __forceinline__ void operator()(f32x4 (&acc)[2][2][4][2], const pg8::Unit& u, int wr, int wc, int fr, int fq) const {
;     ...
;                 for (int m = 0; m < 4; ++m) { const int row = row0 + ai * 128 + m * 16;
; #pragma unroll
;                     for (int bj = 0; bj < 2; ++bj) { f32x4 v0 = acc[ai][bj][m][0], v1 = acc[ai][bj][m][1];
;                         if (pn < 16) { v0 = (f32x4){gelu_tanh(v0[0]), gelu_tanh(v0[1]), gelu_tanh(v0[2]), gelu_tanh(v0[3])}; v1 = (f32x4){gelu_tanh(v1[0]), gelu_tanh(v1[1]), gelu_tanh(v1[2]), gelu_tanh(v1[3])}; }
;                         else { v0 = (f32x4){siluf_(v0[0]), siluf_(v0[1]), siluf_(v0[2]), siluf_(v0[3])}; v1 = (f32x4){siluf_(v1[0]), siluf_(v1[1]), siluf_(v1[2]), siluf_(v1[3])}; }
;                         u32x4 w; w.x = cvt_pk_bf16(v0[0], v0[1]); w.y = cvt_pk_bf16(v0[2], v0[3]); w.z = cvt_pk_bf16(v1[0], v1[1]); w.w = cvt_pk_bf16(v1[2], v1[3]);
;                         *(u32x4*)(G2 + (size_t)row * 4096 + (c0 - C_RGG) + bj * 128) = w; } }
.LBB0_1787:
	v_mul_f32_e32 v10, 0xbfb8aa3b, v25
	v_exp_f32_e32 v12, v10
	v_lshlrev_b64 v[10:11], 13, v[188:189]
	v_pk_mul_f32 v[16:17], v[16:17], v[20:21]
	v_pk_mul_f32 v[14:15], v[14:15], v[18:19]
	v_add_f32_e32 v12, 1.0, v12
	v_rcp_f32_e32 v12, v12
	v_lshl_add_u64 v[10:11], v[122:123], 0, v[10:11]
	v_cvt_pk_bf16_f32 v14, v14, v15
	v_cvt_pk_bf16_f32 v15, v16, v17
	v_mul_f32_e32 v12, v13, v12
	v_cvt_pk_bf16_f32 v17, v24, v12
	v_add_co_u32_e32 v12, vcc, 0x2e90e000, v10
	v_cvt_pk_bf16_f32 v16, v22, v23
	s_mov_b64 s[0:1], -1
	s_nop 0
	v_addc_co_u32_e32 v13, vcc, 0, v11, vcc
	s_and_b64 vcc, exec, s[4:5]
	global_store_dwordx4 v[12:13], v[14:17], off
	s_cbranch_vccnz .LBB0_1789
	s_nop 0
	v_mul_f32_e32 v16, 0xbfb8aa3b, v2
	v_mul_f32_e32 v17, 0xbfb8aa3b, v3
	v_mul_f32_e32 v18, 0xbfb8aa3b, v4
	v_mul_f32_e32 v12, 0xbfb8aa3b, v6
	v_mul_f32_e32 v13, 0xbfb8aa3b, v7
	v_mul_f32_e32 v14, 0xbfb8aa3b, v8
	v_mul_f32_e32 v15, 0xbfb8aa3b, v9
	v_exp_f32_e32 v16, v16
	v_exp_f32_e32 v17, v17
	v_exp_f32_e32 v18, v18
	v_exp_f32_e32 v12, v12
	v_exp_f32_e32 v13, v13
	v_exp_f32_e32 v14, v14
	v_exp_f32_e32 v15, v15
	v_add_f32_e32 v16, 1.0, v16
	v_add_f32_e32 v17, 1.0, v17
	v_add_f32_e32 v18, 1.0, v18
	v_add_f32_e32 v12, 1.0, v12
	v_add_f32_e32 v13, 1.0, v13
	v_add_f32_e32 v14, 1.0, v14
	v_add_f32_e32 v15, 1.0, v15
	v_rcp_f32_e32 v16, v16
	v_rcp_f32_e32 v17, v17
	v_rcp_f32_e32 v18, v18
	v_rcp_f32_e32 v12, v12
	v_rcp_f32_e32 v13, v13
	v_rcp_f32_e32 v14, v14
	v_rcp_f32_e32 v15, v15
	v_pk_mul_f32 v[16:17], v[2:3], v[16:17]
	v_mul_f32_e32 v18, v4, v18
	s_mov_b64 s[0:1], 0

; __device__ __forceinline__ unsigned cvt_pk_bf16(float lo, float hi) { unsigned r; asm("v_cvt_pk_bf16_f32 %0, %1, %2" : "=v"(r) : "v"(lo), "v"(hi)); return r; }
; __device__ __forceinline__ float siluf_(float x) { return x * sigmoidf_(x); }
; __device__ __forceinline__ float gelu_tanh(float x) { const float u = 0.7978845608028654f * (x + 0.044715f * x * x * x); return x * sigmoidf_(2.0f * u); }
;     __device__ __forceinline__ void operator()(f32x4 (&acc)[2][2][4][2], const pg8::Unit& u, int wr, int wc, int fr, int fq) const {
;     ...
;                 for (int m = 0; m < 4; ++m) { const int row = row0 + ai * 128 + m * 16;
; #pragma unroll
;                     for (int bj = 0; bj < 2; ++bj) { f32x4 v0 = acc[ai][bj][m][0], v1 = acc[ai][bj][m][1];
;                         if (pn < 16) { v0 = (f32x4){gelu_tanh(v0[0]), gelu_tanh(v0[1]), gelu_tanh(v0[2]), gelu_tanh(v0[3])}; v1 = (f32x4){gelu_tanh(v1[0]), gelu_tanh(v1[1]), gelu_tanh(v1[2]), gelu_tanh(v1[3])}; }
;                         else { v0 = (f32x4){siluf_(v0[0]), siluf_(v0[1]), siluf_(v0[2]), siluf_(v0[3])}; v1 = (f32x4){siluf_(v1[0]), siluf_(v1[1]), siluf_(v1[2]), siluf_(v1[3])}; }
;                         u32x4 w; w.x = cvt_pk_bf16(v0[0], v0[1]); w.y = cvt_pk_bf16(v0[2], v0[3]); w.z = cvt_pk_bf16(v1[0], v1[1]); w.w = cvt_pk_bf16(v1[2], v1[3]);
;                         *(u32x4*)(G2 + (size_t)row * 4096 + (c0 - C_RGG) + bj * 128) = w; } }
.LBB0_1791:
	v_mul_f32_e32 v2, 0xbfb8aa3b, v19
	v_exp_f32_e32 v4, v2
	v_pk_mul_f32 v[2:3], v[6:7], v[12:13]
	v_pk_mul_f32 v[8:9], v[8:9], v[14:15]
	v_cvt_pk_bf16_f32 v2, v2, v3
	v_add_f32_e32 v4, 1.0, v4
	v_rcp_f32_e32 v6, v4
	v_cvt_pk_bf16_f32 v4, v16, v17
	v_cvt_pk_bf16_f32 v3, v8, v9
	s_nop 0
	v_mul_f32_e32 v5, v5, v6
	v_add_co_u32_e32 v6, vcc, 0x2e90e000, v10
	v_cvt_pk_bf16_f32 v5, v18, v5
	s_nop 1
	v_addc_co_u32_e32 v7, vcc, 0, v11, vcc
	global_store_dwordx4 v[6:7], v[2:5], off offset:256
	s_andn2_b64 vcc, exec, s[42:43]
	s_mov_b64 s[0:1], -1
	s_cbranch_vccnz .LBB0_190

; __device__ __forceinline__ float softplusf_(float x) { return fmaxf(x, 0.0f) + log1pf(__expf(-fabsf(x))); }
;     __device__ __forceinline__ void operator()(f32x4 (&acc)[2][2][4][2], const pg8::Unit& u, int wr, int wc, int fr, int fq) const {
;     ...
;             if (wc == 0) { const f32x4 b0 = *(const f32x4*)(dtb + cl0), b1 = *(const f32x4*)(dtb + cl0 + 4);
; #pragma unroll
;                 for (int ai = 0; ai < 2; ++ai)
; #pragma unroll
;                     for (int m = 0; m < 4; ++m) { const int row = row0 + ai * 128 + m * 16; const f32x4 v0 = acc[ai][0][m][0] + b0, v1 = acc[ai][0][m][1] + b1;
;                         float* d = DTA + (size_t)row * NH + cl0;
;                         *(f32x4*)d = (f32x4){softplusf_(v0[0]), softplusf_(v0[1]), softplusf_(v0[2]), softplusf_(v0[3])}; *(f32x4*)(d + 4) = (f32x4){softplusf_(v1[0]), softplusf_(v1[1]), softplusf_(v1[2]), softplusf_(v1[3])}; } }
.LBB0_1794:
	v_ashrrev_i32_e32 v207, 31, v206
	v_readlane_b32 s0, v254, 18
	v_lshlrev_b64 v[138:139], 2, v[206:207]
	v_readlane_b32 s6, v254, 24
	v_readlane_b32 s7, v254, 25
	v_readlane_b32 s1, v254, 19
	s_mov_b64 s[0:1], 0x48797000
	v_lshl_add_u64 v[134:135], s[6:7], 0, v[138:139]
	global_load_dwordx4 v[130:133], v[134:135], off offset:16
	s_nop 0
	global_load_dwordx4 v[134:137], v[134:135], off
	v_lshl_add_u64 v[138:139], s[74:75], 0, v[138:139]
	v_lshl_add_u64 v[144:145], v[138:139], 0, s[0:1]
	v_lshlrev_b64 v[138:139], 7, v[202:203]
	v_lshl_add_u64 v[146:147], v[144:145], 0, v[138:139]
	v_readlane_b32 s2, v254, 20
	s_mov_b32 s2, 0x3f2aaaab
	s_mov_b32 s0, 0x3ecc95a3
	v_readlane_b32 s8, v254, 26
	s_mov_b32 s6, 0x3e9b6dac
	v_readlane_b32 s9, v254, 27
	s_mov_b32 s8, 0x3f2aaada
	v_readlane_b32 s10, v254, 28
	v_readlane_b32 s11, v254, 29
	s_mov_b32 s10, 0xb102e308
	v_readlane_b32 s3, v254, 21
	s_mov_b32 s3, 0x7f800000
	v_readlane_b32 s4, v254, 22
	s_mov_b32 s4, 0x33800000
	v_readlane_b32 s5, v254, 23
	v_readlane_b32 s12, v254, 30
	v_readlane_b32 s13, v254, 31
	v_readlane_b32 s14, v254, 32
	v_readlane_b32 s15, v254, 33
	s_waitcnt vmcnt(0)
	v_pk_add_f32 v[150:151], v[126:127], v[130:131]
	v_pk_add_f32 v[142:143], v[122:123], v[134:135]
	v_pk_add_f32 v[140:141], v[124:125], v[136:137]
	v_mul_f32_e64 v139, |v142|, s88
	v_exp_f32_e32 v172, v139
	v_max_f32_e32 v138, 0, v142
	v_pk_add_f32 v[148:149], v[128:129], v[132:133]
	v_add_f32_e32 v139, 1.0, v172
	v_add_f32_e32 v142, -1.0, v139
	v_sub_f32_e32 v152, v142, v139
	v_add_f32_e32 v152, 1.0, v152
	v_sub_f32_e32 v142, v172, v142
	v_add_f32_e32 v154, v142, v152
	v_frexp_mant_f32_e32 v142, v139
	v_cvt_f64_f32_e32 v[152:153], v139
	v_cmp_gt_f32_e32 vcc, s2, v142
	v_frexp_exp_i32_f64_e32 v142, v[152:153]
	s_nop 0
	v_subbrev_co_u32_e32 v160, vcc, 0, v142, vcc
	v_sub_u32_e32 v152, 0, v160
	v_ldexp_f32 v142, v139, v152
	v_max_f32_e32 v139, 0, v143
	v_mul_f32_e64 v143, |v143|, s88
	v_exp_f32_e32 v173, v143
	v_ldexp_f32 v152, v154, v152
	v_cvt_f32_i32_e32 v160, v160
	v_add_f32_e32 v143, 1.0, v173
	v_add_f32_e32 v153, -1.0, v143
	v_sub_f32_e32 v154, v153, v143
	v_add_f32_e32 v154, 1.0, v154
	v_sub_f32_e32 v153, v173, v153
	v_add_f32_e32 v153, v153, v154
	v_frexp_mant_f32_e32 v154, v143
	v_cmp_gt_f32_e32 vcc, s2, v154
	v_cvt_f64_f32_e32 v[154:155], v143
	v_frexp_exp_i32_f64_e32 v154, v[154:155]
	v_subbrev_co_u32_e32 v161, vcc, 0, v154, vcc
	v_sub_u32_e32 v154, 0, v161
	v_ldexp_f32 v143, v143, v154
	v_ldexp_f32 v153, v153, v154
	v_pk_add_f32 v[154:155], v[142:143], 1.0 op_sel_hi:[1,0]
	v_pk_add_f32 v[164:165], v[142:143], -1.0 op_sel_hi:[1,0]
	v_pk_add_f32 v[156:157], v[154:155], -1.0 op_sel_hi:[1,0]
	v_pk_add_f32 v[166:167], v[164:165], 1.0 op_sel_hi:[1,0]
	v_pk_add_f32 v[156:157], v[142:143], v[156:157] neg_lo:[0,1] neg_hi:[0,1]
	v_pk_add_f32 v[142:143], v[142:143], v[166:167] neg_lo:[0,1] neg_hi:[0,1]
	v_pk_add_f32 v[156:157], v[152:153], v[156:157]
	v_pk_add_f32 v[142:143], v[152:153], v[142:143]
	v_pk_add_f32 v[158:159], v[154:155], v[156:157]
	v_pk_add_f32 v[152:153], v[164:165], v[142:143]
	v_rcp_f32_e32 v162, v158
	v_rcp_f32_e32 v163, v159
	v_pk_add_f32 v[154:155], v[158:159], v[154:155] neg_lo:[0,1] neg_hi:[0,1]
	v_pk_add_f32 v[164:165], v[152:153], v[164:165] neg_lo:[0,1] neg_hi:[0,1]
	v_pk_add_f32 v[154:155], v[156:157], v[154:155] neg_lo:[0,1] neg_hi:[0,1]
	v_pk_mul_f32 v[156:157], v[152:153], v[162:163]
	v_pk_add_f32 v[142:143], v[142:143], v[164:165] neg_lo:[0,1] neg_hi:[0,1]
	v_pk_mul_f32 v[164:165], v[158:159], v[156:157]
	v_cvt_f32_i32_e32 v161, v161
	v_pk_fma_f32 v[166:167], v[156:157], v[158:159], v[164:165] neg_lo:[0,0,1] neg_hi:[0,0,1]
	v_cmp_neq_f32_e32 vcc, s3, v172
	v_pk_fma_f32 v[166:167], v[156:157], v[154:155], v[166:167]
	s_nop 0
	v_pk_add_f32 v[168:169], v[164:165], v[166:167]
	s_nop 0
	v_pk_add_f32 v[170:171], v[152:153], v[168:169] neg_lo:[0,1] neg_hi:[0,1]
	v_pk_add_f32 v[164:165], v[168:169], v[164:165] neg_lo:[0,1] neg_hi:[0,1]
	v_pk_add_f32 v[152:153], v[152:153], v[170:171] neg_lo:[0,1] neg_hi:[0,1]
	s_nop 0
	v_pk_add_f32 v[152:153], v[152:153], v[168:169] neg_lo:[0,1] neg_hi:[0,1]
	s_nop 0
	v_pk_add_f32 v[142:143], v[142:143], v[152:153]
	v_pk_add_f32 v[152:153], v[164:165], v[166:167] neg_lo:[0,1] neg_hi:[0,1]
	s_nop 0
	v_pk_add_f32 v[142:143], v[152:153], v[142:143]
	s_nop 0
	v_pk_add_f32 v[152:153], v[170:171], v[142:143]
	s_nop 0
	v_pk_mul_f32 v[164:165], v[162:163], v[152:153]
	s_nop 0
	v_pk_mul_f32 v[166:167], v[158:159], v[164:165]
	s_nop 0
	v_pk_fma_f32 v[158:159], v[164:165], v[158:159], v[166:167] neg_lo:[0,0,1] neg_hi:[0,0,1]
	s_nop 0
	v_pk_fma_f32 v[154:155], v[164:165], v[154:155], v[158:159]
	v_pk_add_f32 v[158:159], v[170:171], v[152:153] neg_lo:[0,1] neg_hi:[0,1]
	s_nop 0
	v_pk_add_f32 v[142:143], v[142:143], v[158:159]
	v_pk_add_f32 v[158:159], v[166:167], v[154:155]
	s_nop 0
	v_pk_add_f32 v[168:169], v[152:153], v[158:159] neg_lo:[0,1] neg_hi:[0,1]
	v_pk_add_f32 v[166:167], v[158:159], v[166:167] neg_lo:[0,1] neg_hi:[0,1]
	v_pk_add_f32 v[152:153], v[152:153], v[168:169] neg_lo:[0,1] neg_hi:[0,1]
	s_nop 0
	v_pk_add_f32 v[152:153], v[152:153], v[158:159] neg_lo:[0,1] neg_hi:[0,1]
	s_nop 0
	v_pk_add_f32 v[142:143], v[142:143], v[152:153]
	v_pk_add_f32 v[152:153], v[166:167], v[154:155] neg_lo:[0,1] neg_hi:[0,1]
	s_nop 0
	v_pk_add_f32 v[142:143], v[152:153], v[142:143]
	v_pk_add_f32 v[152:153], v[156:157], v[164:165]
	v_pk_add_f32 v[142:143], v[168:169], v[142:143]
	v_pk_add_f32 v[154:155], v[152:153], v[156:157] neg_lo:[0,1] neg_hi:[0,1]
	v_pk_mul_f32 v[142:143], v[162:163], v[142:143]
	v_pk_add_f32 v[154:155], v[164:165], v[154:155] neg_lo:[0,1] neg_hi:[0,1]
; __device__ __forceinline__ float softplusf_(float x) { return fmaxf(x, 0.0f) + log1pf(__expf(-fabsf(x))); }
;     __device__ __forceinline__ void operator()(f32x4 (&acc)[2][2][4][2], const pg8::Unit& u, int wr, int wc, int fr, int fq) const {
;     ...
;             if (wc == 0) { const f32x4 b0 = *(const f32x4*)(dtb + cl0), b1 = *(const f32x4*)(dtb + cl0 + 4);
; #pragma unroll
;                 for (int ai = 0; ai < 2; ++ai)
; #pragma unroll
;                     for (int m = 0; m < 4; ++m) { const int row = row0 + ai * 128 + m * 16; const f32x4 v0 = acc[ai][0][m][0] + b0, v1 = acc[ai][0][m][1] + b1;
;                         float* d = DTA + (size_t)row * NH + cl0;
;                         *(f32x4*)d = (f32x4){softplusf_(v0[0]), softplusf_(v0[1]), softplusf_(v0[2]), softplusf_(v0[3])}; *(f32x4*)(d + 4) = (f32x4){softplusf_(v1[0]), softplusf_(v1[1]), softplusf_(v1[2]), softplusf_(v1[3])}; } }
	s_nop 0
	v_pk_add_f32 v[142:143], v[154:155], v[142:143]
	s_nop 0
	v_pk_add_f32 v[156:157], v[152:153], v[142:143]
	s_nop 0
	v_pk_add_f32 v[152:153], v[156:157], v[152:153] neg_lo:[0,1] neg_hi:[0,1]
	v_pk_mul_f32 v[158:159], v[156:157], v[156:157]
	v_pk_add_f32 v[152:153], v[142:143], v[152:153] neg_lo:[0,1] neg_hi:[0,1]
	v_mov_b64_e32 v[142:143], s[0:1]
	v_pk_fma_f32 v[162:163], v[158:159], s[6:7], v[142:143] op_sel_hi:[1,0,0]
	v_ldexp_f32 v154, v156, 1
	v_pk_fma_f32 v[162:163], v[158:159], v[162:163], s[8:9] op_sel_hi:[1,1,0]
	v_ldexp_f32 v155, v157, 1
	v_pk_mul_f32 v[156:157], v[156:157], v[158:159]
	v_ldexp_f32 v165, v153, 1
	v_pk_mul_f32 v[166:167], v[156:157], v[162:163]
	v_pk_mul_f32 v[158:159], v[160:161], s[36:37] op_sel_hi:[1,0]
	v_pk_add_f32 v[156:157], v[154:155], v[166:167]
	v_ldexp_f32 v152, v152, 1
	v_pk_add_f32 v[154:155], v[156:157], v[154:155] neg_lo:[0,1] neg_hi:[0,1]
	v_pk_fma_f32 v[162:163], v[160:161], s[36:37], v[158:159] op_sel_hi:[1,0,1] neg_lo:[0,0,1] neg_hi:[0,0,1]
	v_pk_add_f32 v[168:169], v[166:167], v[154:155] neg_lo:[0,1] neg_hi:[0,1]
	v_mov_b32_e32 v153, v165
	v_pk_fma_f32 v[160:161], v[160:161], s[10:11], v[162:163] op_sel_hi:[1,0,1]
	v_pk_add_f32 v[166:167], v[152:153], v[168:169]
	v_mov_b32_e32 v154, v158
	v_mov_b32_e32 v155, v169
	v_mov_b32_e32 v164, v160
	v_mov_b32_e32 v153, v167
	v_mov_b32_e32 v169, v157
	v_pk_add_f32 v[162:163], v[158:159], v[160:161]
	v_pk_add_f32 v[154:155], v[154:155], v[164:165]
	v_pk_add_f32 v[164:165], v[152:153], v[168:169]
	v_pk_add_f32 v[168:169], v[156:157], v[166:167]
	v_mov_b32_e32 v210, v156
	v_pk_add_f32 v[152:153], v[162:163], v[168:169]
	v_mov_b32_e32 v208, v168
	v_mov_b32_e32 v209, v153
	v_mov_b32_e32 v211, v163
	v_pk_add_f32 v[208:209], v[208:209], v[210:211] neg_lo:[0,1] neg_hi:[0,1]
	v_mov_b32_e32 v170, v152
	v_mov_b32_e32 v171, v163
	v_mov_b32_e32 v206, v162
	v_mov_b32_e32 v207, v159
	v_mov_b32_e32 v210, v162
	v_mov_b32_e32 v211, v153
	v_mov_b32_e32 v159, v209
	v_pk_add_f32 v[170:171], v[170:171], v[206:207] neg_lo:[0,1] neg_hi:[0,1]
	v_mov_b32_e32 v206, v168
	v_mov_b32_e32 v207, v161
	v_pk_add_f32 v[158:159], v[210:211], v[158:159] neg_lo:[0,1] neg_hi:[0,1]
	v_pk_add_f32 v[206:207], v[206:207], v[170:171] neg_lo:[0,1] neg_hi:[0,1]
	v_mov_b32_e32 v210, v158
	v_mov_b32_e32 v211, v171
	v_mov_b32_e32 v212, v152
	v_mov_b32_e32 v213, v169
	v_mov_b32_e32 v171, v157
	v_pk_add_f32 v[210:211], v[160:161], v[210:211] neg_lo:[0,1] neg_hi:[0,1]
	v_pk_add_f32 v[170:171], v[212:213], v[170:171] neg_lo:[0,1] neg_hi:[0,1]
	v_mov_b32_e32 v161, v163
	v_pk_add_f32 v[154:155], v[154:155], v[170:171] neg_lo:[0,1] neg_hi:[0,1]
	v_pk_add_f32 v[158:159], v[160:161], v[158:159] neg_lo:[0,1] neg_hi:[0,1]
	v_pk_add_f32 v[160:161], v[164:165], v[208:209] neg_lo:[0,1] neg_hi:[0,1]
	v_pk_add_f32 v[164:165], v[206:207], v[154:155]
	v_pk_add_f32 v[162:163], v[160:161], v[158:159]
	v_mov_b32_e32 v159, v207
	v_mov_b32_e32 v161, v155
	v_pk_add_f32 v[154:155], v[158:159], v[160:161]
	v_pk_add_f32 v[156:157], v[168:169], v[156:157] neg_lo:[0,1] neg_hi:[0,1]
	v_pk_add_f32 v[154:155], v[154:155], v[210:211] neg_lo:[0,1] neg_hi:[0,1]
	v_mov_b32_e32 v160, v162
	v_mov_b32_e32 v161, v165
	v_pk_add_f32 v[156:157], v[166:167], v[156:157] neg_lo:[0,1] neg_hi:[0,1]
	v_pk_add_f32 v[160:161], v[160:161], v[154:155] neg_lo:[0,1] neg_hi:[0,1]
	v_pk_add_f32 v[154:155], v[156:157], v[154:155] neg_lo:[0,1] neg_hi:[0,1]
	v_pk_add_f32 v[158:159], v[158:159], v[160:161] neg_lo:[0,1] neg_hi:[0,1]
	v_pk_add_f32 v[156:157], v[164:165], v[162:163]
	v_pk_add_f32 v[154:155], v[154:155], v[158:159]
	v_pk_add_f32 v[158:159], v[152:153], v[156:157]
	v_cmp_lt_f32_e64 s[0:1], |v173|, s4
	v_pk_add_f32 v[152:153], v[158:159], v[152:153] neg_lo:[0,1] neg_hi:[0,1]
	s_nop 0
	v_pk_add_f32 v[152:153], v[156:157], v[152:153] neg_lo:[0,1] neg_hi:[0,1]
	s_nop 0
	v_pk_add_f32 v[152:153], v[154:155], v[152:153]
	s_nop 0
	v_pk_add_f32 v[152:153], v[158:159], v[152:153]
	s_nop 0
	v_cndmask_b32_e32 v152, v252, v152, vcc
	v_cmp_neq_f32_e32 vcc, s3, v173
	s_nop 1
	v_cndmask_b32_e32 v153, v252, v153, vcc
	v_cmp_ngt_f32_e32 vcc, -1.0, v173
	s_nop 1
	v_cndmask_b32_e32 v153, v253, v153, vcc
	v_cmp_ngt_f32_e32 vcc, -1.0, v172
	s_nop 1
	v_cndmask_b32_e32 v152, v253, v152, vcc
	v_cmp_neq_f32_e32 vcc, -1.0, v172
	s_nop 1
	v_cndmask_b32_e32 v152, v244, v152, vcc
	v_cmp_neq_f32_e32 vcc, -1.0, v173
	s_nop 1
	v_cndmask_b32_e32 v153, v244, v153, vcc
	v_cmp_lt_f32_e64 vcc, |v172|, s4
	v_cndmask_b32_e64 v153, v153, v173, s[0:1]
	s_nop 0
	v_cndmask_b32_e32 v152, v152, v172, vcc
	v_pk_add_f32 v[138:139], v[138:139], v[152:153]
	v_max_f32_e32 v152, 0, v140
	v_mul_f32_e64 v140, |v140|, s88
	v_exp_f32_e32 v182, v140
	s_nop 0
	v_add_f32_e32 v140, 1.0, v182
	v_add_f32_e32 v153, -1.0, v140
	v_sub_f32_e32 v154, v153, v140
	v_add_f32_e32 v154, 1.0, v154
	v_sub_f32_e32 v153, v182, v153
	v_add_f32_e32 v153, v153, v154
	v_frexp_mant_f32_e32 v154, v140
	v_cmp_gt_f32_e32 vcc, s2, v154
	v_cvt_f64_f32_e32 v[154:155], v140
	v_frexp_exp_i32_f64_e32 v154, v[154:155]
	v_subbrev_co_u32_e32 v172, vcc, 0, v154, vcc
	v_sub_u32_e32 v154, 0, v172
	v_ldexp_f32 v140, v140, v154
	v_ldexp_f32 v154, v153, v154
	v_max_f32_e32 v153, 0, v141
	v_mul_f32_e64 v141, |v141|, s88
	v_exp_f32_e32 v205, v141
	s_nop 0
	v_add_f32_e32 v141, 1.0, v205
	v_add_f32_e32 v155, -1.0, v141
	v_sub_f32_e32 v156, v155, v141
	v_add_f32_e32 v156, 1.0, v156
	v_sub_f32_e32 v155, v205, v155
	v_add_f32_e32 v155, v155, v156
	v_frexp_mant_f32_e32 v156, v141
	v_cmp_gt_f32_e32 vcc, s2, v156
	v_cvt_f64_f32_e32 v[156:157], v141
	v_frexp_exp_i32_f64_e32 v156, v[156:157]
	v_subbrev_co_u32_e32 v173, vcc, 0, v156, vcc
; __device__ __forceinline__ float softplusf_(float x) { return fmaxf(x, 0.0f) + log1pf(__expf(-fabsf(x))); }
;     __device__ __forceinline__ void operator()(f32x4 (&acc)[2][2][4][2], const pg8::Unit& u, int wr, int wc, int fr, int fq) const {
;     ...
;             if (wc == 0) { const f32x4 b0 = *(const f32x4*)(dtb + cl0), b1 = *(const f32x4*)(dtb + cl0 + 4);
; #pragma unroll
;                 for (int ai = 0; ai < 2; ++ai)
; #pragma unroll
;                     for (int m = 0; m < 4; ++m) { const int row = row0 + ai * 128 + m * 16; const f32x4 v0 = acc[ai][0][m][0] + b0, v1 = acc[ai][0][m][1] + b1;
;                         float* d = DTA + (size_t)row * NH + cl0;
;                         *(f32x4*)d = (f32x4){softplusf_(v0[0]), softplusf_(v0[1]), softplusf_(v0[2]), softplusf_(v0[3])}; *(f32x4*)(d + 4) = (f32x4){softplusf_(v1[0]), softplusf_(v1[1]), softplusf_(v1[2]), softplusf_(v1[3])}; } }
	v_sub_u32_e32 v156, 0, v173
	v_ldexp_f32 v141, v141, v156
	v_ldexp_f32 v155, v155, v156
	v_pk_add_f32 v[156:157], v[140:141], 1.0 op_sel_hi:[1,0]
	v_pk_add_f32 v[164:165], v[140:141], -1.0 op_sel_hi:[1,0]
	v_pk_add_f32 v[158:159], v[156:157], -1.0 op_sel_hi:[1,0]
	v_pk_add_f32 v[166:167], v[164:165], 1.0 op_sel_hi:[1,0]
	v_pk_add_f32 v[158:159], v[140:141], v[158:159] neg_lo:[0,1] neg_hi:[0,1]
	v_pk_add_f32 v[140:141], v[140:141], v[166:167] neg_lo:[0,1] neg_hi:[0,1]
	v_pk_add_f32 v[158:159], v[154:155], v[158:159]
	v_pk_add_f32 v[140:141], v[154:155], v[140:141]
	v_pk_add_f32 v[160:161], v[156:157], v[158:159]
	v_pk_add_f32 v[154:155], v[164:165], v[140:141]
	v_rcp_f32_e32 v162, v160
	v_rcp_f32_e32 v163, v161
	v_pk_add_f32 v[156:157], v[160:161], v[156:157] neg_lo:[0,1] neg_hi:[0,1]
	v_pk_add_f32 v[164:165], v[154:155], v[164:165] neg_lo:[0,1] neg_hi:[0,1]
	v_pk_add_f32 v[156:157], v[158:159], v[156:157] neg_lo:[0,1] neg_hi:[0,1]
	v_pk_mul_f32 v[158:159], v[154:155], v[162:163]
	v_pk_add_f32 v[140:141], v[140:141], v[164:165] neg_lo:[0,1] neg_hi:[0,1]
	v_pk_mul_f32 v[164:165], v[160:161], v[158:159]
	v_cmp_neq_f32_e32 vcc, s3, v182
	v_pk_fma_f32 v[166:167], v[158:159], v[160:161], v[164:165] neg_lo:[0,0,1] neg_hi:[0,0,1]
	v_cmp_lt_f32_e64 s[0:1], |v205|, s4
	v_pk_fma_f32 v[166:167], v[158:159], v[156:157], v[166:167]
	s_nop 0
	v_pk_add_f32 v[168:169], v[164:165], v[166:167]
	s_nop 0
	v_pk_add_f32 v[170:171], v[154:155], v[168:169] neg_lo:[0,1] neg_hi:[0,1]
	v_pk_add_f32 v[164:165], v[168:169], v[164:165] neg_lo:[0,1] neg_hi:[0,1]
	v_pk_add_f32 v[154:155], v[154:155], v[170:171] neg_lo:[0,1] neg_hi:[0,1]
	s_nop 0
	v_pk_add_f32 v[154:155], v[154:155], v[168:169] neg_lo:[0,1] neg_hi:[0,1]
	s_nop 0
	v_pk_add_f32 v[140:141], v[140:141], v[154:155]
	v_pk_add_f32 v[154:155], v[164:165], v[166:167] neg_lo:[0,1] neg_hi:[0,1]
	s_nop 0
	v_pk_add_f32 v[140:141], v[154:155], v[140:141]
	s_nop 0
	v_pk_add_f32 v[154:155], v[170:171], v[140:141]
	s_nop 0
	v_pk_mul_f32 v[164:165], v[162:163], v[154:155]
	s_nop 0
	v_pk_mul_f32 v[166:167], v[160:161], v[164:165]
	s_nop 0
	v_pk_fma_f32 v[160:161], v[164:165], v[160:161], v[166:167] neg_lo:[0,0,1] neg_hi:[0,0,1]
	s_nop 0
	v_pk_fma_f32 v[156:157], v[164:165], v[156:157], v[160:161]
	v_pk_add_f32 v[160:161], v[170:171], v[154:155] neg_lo:[0,1] neg_hi:[0,1]
	s_nop 0
	v_pk_add_f32 v[140:141], v[140:141], v[160:161]
	v_pk_add_f32 v[160:161], v[166:167], v[156:157]
	s_nop 0
	v_pk_add_f32 v[168:169], v[154:155], v[160:161] neg_lo:[0,1] neg_hi:[0,1]
	v_pk_add_f32 v[166:167], v[160:161], v[166:167] neg_lo:[0,1] neg_hi:[0,1]
	v_pk_add_f32 v[154:155], v[154:155], v[168:169] neg_lo:[0,1] neg_hi:[0,1]
	s_nop 0
	v_pk_add_f32 v[154:155], v[154:155], v[160:161] neg_lo:[0,1] neg_hi:[0,1]
	s_nop 0
	v_pk_add_f32 v[140:141], v[140:141], v[154:155]
	v_pk_add_f32 v[154:155], v[166:167], v[156:157] neg_lo:[0,1] neg_hi:[0,1]
	s_nop 0
	v_pk_add_f32 v[140:141], v[154:155], v[140:141]
	v_pk_add_f32 v[154:155], v[158:159], v[164:165]
	v_pk_add_f32 v[140:141], v[168:169], v[140:141]
	v_pk_add_f32 v[156:157], v[154:155], v[158:159] neg_lo:[0,1] neg_hi:[0,1]
	v_pk_mul_f32 v[140:141], v[162:163], v[140:141]
	v_pk_add_f32 v[156:157], v[164:165], v[156:157] neg_lo:[0,1] neg_hi:[0,1]
	s_nop 0
	v_pk_add_f32 v[140:141], v[156:157], v[140:141]
	s_nop 0
	v_pk_add_f32 v[156:157], v[154:155], v[140:141]
	s_nop 0
	v_pk_mul_f32 v[158:159], v[156:157], v[156:157]
	v_pk_add_f32 v[154:155], v[156:157], v[154:155] neg_lo:[0,1] neg_hi:[0,1]
	v_pk_fma_f32 v[160:161], v[158:159], s[6:7], v[142:143] op_sel_hi:[1,0,0]
	v_pk_add_f32 v[140:141], v[140:141], v[154:155] neg_lo:[0,1] neg_hi:[0,1]
	v_ldexp_f32 v154, v156, 1
	v_pk_fma_f32 v[160:161], v[158:159], v[160:161], s[8:9] op_sel_hi:[1,1,0]
	v_ldexp_f32 v155, v157, 1
	v_pk_mul_f32 v[156:157], v[156:157], v[158:159]
	v_cvt_f32_i32_e32 v159, v173
	v_cvt_f32_i32_e32 v158, v172
	v_pk_mul_f32 v[156:157], v[156:157], v[160:161]
	v_ldexp_f32 v163, v141, 1
	v_pk_add_f32 v[160:161], v[154:155], v[156:157]
	v_pk_mul_f32 v[164:165], v[158:159], s[36:37] op_sel_hi:[1,0]
	v_pk_add_f32 v[154:155], v[160:161], v[154:155] neg_lo:[0,1] neg_hi:[0,1]
	v_pk_fma_f32 v[166:167], v[158:159], s[36:37], v[164:165] op_sel_hi:[1,0,1] neg_lo:[0,0,1] neg_hi:[0,0,1]
	v_pk_add_f32 v[154:155], v[156:157], v[154:155] neg_lo:[0,1] neg_hi:[0,1]
	v_pk_fma_f32 v[158:159], v[158:159], s[10:11], v[166:167] op_sel_hi:[1,0,1]
	v_ldexp_f32 v140, v140, 1
	v_mov_b32_e32 v156, v164
	v_mov_b32_e32 v157, v155
	v_mov_b32_e32 v162, v158
	v_mov_b32_e32 v141, v163
	v_pk_add_f32 v[156:157], v[156:157], v[162:163]
	v_pk_add_f32 v[162:163], v[140:141], v[154:155]
	v_mov_b32_e32 v155, v161
	v_mov_b32_e32 v141, v163
	v_pk_add_f32 v[166:167], v[164:165], v[158:159]
	v_pk_add_f32 v[140:141], v[140:141], v[154:155]
	v_pk_add_f32 v[154:155], v[160:161], v[162:163]
	v_mov_b32_e32 v208, v160
	v_pk_add_f32 v[168:169], v[166:167], v[154:155]
	v_mov_b32_e32 v206, v154
	v_mov_b32_e32 v207, v169
	v_mov_b32_e32 v209, v167
	v_pk_add_f32 v[206:207], v[206:207], v[208:209] neg_lo:[0,1] neg_hi:[0,1]
	v_mov_b32_e32 v170, v168
	v_mov_b32_e32 v171, v167
	v_mov_b32_e32 v172, v166
	v_mov_b32_e32 v173, v165
	v_mov_b32_e32 v208, v166
	v_mov_b32_e32 v209, v169
	v_mov_b32_e32 v165, v207
	v_pk_add_f32 v[170:171], v[170:171], v[172:173] neg_lo:[0,1] neg_hi:[0,1]
	v_mov_b32_e32 v172, v154
	v_mov_b32_e32 v173, v159
	v_pk_add_f32 v[164:165], v[208:209], v[164:165] neg_lo:[0,1] neg_hi:[0,1]
	v_pk_add_f32 v[172:173], v[172:173], v[170:171] neg_lo:[0,1] neg_hi:[0,1]
	v_mov_b32_e32 v208, v164
	v_mov_b32_e32 v209, v171
	v_mov_b32_e32 v210, v168
	v_mov_b32_e32 v211, v155
	v_mov_b32_e32 v171, v161
; __device__ __forceinline__ float softplusf_(float x) { return fmaxf(x, 0.0f) + log1pf(__expf(-fabsf(x))); }
;     __device__ __forceinline__ void operator()(f32x4 (&acc)[2][2][4][2], const pg8::Unit& u, int wr, int wc, int fr, int fq) const {
;     ...
;             if (wc == 0) { const f32x4 b0 = *(const f32x4*)(dtb + cl0), b1 = *(const f32x4*)(dtb + cl0 + 4);
; #pragma unroll
;                 for (int ai = 0; ai < 2; ++ai)
; #pragma unroll
;                     for (int m = 0; m < 4; ++m) { const int row = row0 + ai * 128 + m * 16; const f32x4 v0 = acc[ai][0][m][0] + b0, v1 = acc[ai][0][m][1] + b1;
;                         float* d = DTA + (size_t)row * NH + cl0;
;                         *(f32x4*)d = (f32x4){softplusf_(v0[0]), softplusf_(v0[1]), softplusf_(v0[2]), softplusf_(v0[3])}; *(f32x4*)(d + 4) = (f32x4){softplusf_(v1[0]), softplusf_(v1[1]), softplusf_(v1[2]), softplusf_(v1[3])}; } }
	v_pk_add_f32 v[208:209], v[158:159], v[208:209] neg_lo:[0,1] neg_hi:[0,1]
	v_pk_add_f32 v[170:171], v[210:211], v[170:171] neg_lo:[0,1] neg_hi:[0,1]
	v_mov_b32_e32 v159, v167
	v_pk_add_f32 v[156:157], v[156:157], v[170:171] neg_lo:[0,1] neg_hi:[0,1]
	v_pk_add_f32 v[158:159], v[158:159], v[164:165] neg_lo:[0,1] neg_hi:[0,1]
	v_pk_add_f32 v[140:141], v[140:141], v[206:207] neg_lo:[0,1] neg_hi:[0,1]
	v_pk_add_f32 v[154:155], v[154:155], v[160:161] neg_lo:[0,1] neg_hi:[0,1]
	v_pk_add_f32 v[160:161], v[140:141], v[158:159]
	v_mov_b32_e32 v159, v173
	v_mov_b32_e32 v141, v157
	v_pk_add_f32 v[154:155], v[162:163], v[154:155] neg_lo:[0,1] neg_hi:[0,1]
	v_pk_add_f32 v[162:163], v[172:173], v[156:157]
	v_pk_add_f32 v[140:141], v[158:159], v[140:141]
	v_mov_b32_e32 v156, v160
	v_pk_add_f32 v[140:141], v[140:141], v[208:209] neg_lo:[0,1] neg_hi:[0,1]
	v_mov_b32_e32 v157, v163
	v_pk_add_f32 v[156:157], v[156:157], v[140:141] neg_lo:[0,1] neg_hi:[0,1]
	v_pk_add_f32 v[140:141], v[154:155], v[140:141] neg_lo:[0,1] neg_hi:[0,1]
	v_pk_add_f32 v[156:157], v[158:159], v[156:157] neg_lo:[0,1] neg_hi:[0,1]
	v_pk_add_f32 v[154:155], v[162:163], v[160:161]
	v_pk_add_f32 v[140:141], v[140:141], v[156:157]
	v_pk_add_f32 v[156:157], v[168:169], v[154:155]
	s_nop 0
	v_pk_add_f32 v[158:159], v[156:157], v[168:169] neg_lo:[0,1] neg_hi:[0,1]
	s_nop 0
	v_pk_add_f32 v[154:155], v[154:155], v[158:159] neg_lo:[0,1] neg_hi:[0,1]
	s_nop 0
	v_pk_add_f32 v[140:141], v[140:141], v[154:155]
	s_nop 0
	v_pk_add_f32 v[140:141], v[156:157], v[140:141]
	s_nop 0
	v_cndmask_b32_e32 v140, v252, v140, vcc
	v_cmp_neq_f32_e32 vcc, s3, v205
	s_nop 1
	v_cndmask_b32_e32 v141, v252, v141, vcc
	v_cmp_ngt_f32_e32 vcc, -1.0, v205
	s_nop 1
	v_cndmask_b32_e32 v141, v253, v141, vcc
	v_cmp_ngt_f32_e32 vcc, -1.0, v182
	s_nop 1
	v_cndmask_b32_e32 v140, v253, v140, vcc
	v_cmp_neq_f32_e32 vcc, -1.0, v182
	s_nop 1
	v_cndmask_b32_e32 v140, v244, v140, vcc
	v_cmp_neq_f32_e32 vcc, -1.0, v205
	s_nop 1
	v_cndmask_b32_e32 v141, v244, v141, vcc
	v_cmp_lt_f32_e64 vcc, |v182|, s4
	v_cndmask_b32_e64 v141, v141, v205, s[0:1]
	s_nop 0
	v_cndmask_b32_e32 v140, v140, v182, vcc
	v_pk_add_f32 v[140:141], v[152:153], v[140:141]
	global_store_dwordx4 v[146:147], v[138:141], off
	s_nop 1
	v_mul_f32_e64 v139, |v150|, s88
	v_exp_f32_e32 v182, v139
	v_max_f32_e32 v138, 0, v150
	v_add_f32_e32 v139, 1.0, v182
	v_add_f32_e32 v140, -1.0, v139
	v_sub_f32_e32 v141, v140, v139
	v_add_f32_e32 v141, 1.0, v141
	v_sub_f32_e32 v140, v182, v140
	v_add_f32_e32 v150, v140, v141
	v_frexp_mant_f32_e32 v140, v139
	v_cmp_gt_f32_e32 vcc, s2, v140
	v_cvt_f64_f32_e32 v[140:141], v139
	v_frexp_exp_i32_f64_e32 v140, v[140:141]
	v_subbrev_co_u32_e32 v168, vcc, 0, v140, vcc
	v_sub_u32_e32 v141, 0, v168
	v_ldexp_f32 v140, v139, v141
	v_ldexp_f32 v150, v150, v141
	v_mul_f32_e64 v141, |v151|, s88
	v_exp_f32_e32 v205, v141
	v_max_f32_e32 v139, 0, v151
	v_add_f32_e32 v141, 1.0, v205
	v_add_f32_e32 v151, -1.0, v141
	v_sub_f32_e32 v152, v151, v141
	v_add_f32_e32 v152, 1.0, v152
	v_sub_f32_e32 v151, v205, v151
	v_add_f32_e32 v151, v151, v152
	v_frexp_mant_f32_e32 v152, v141
	v_cmp_gt_f32_e32 vcc, s2, v152
	v_cvt_f64_f32_e32 v[152:153], v141
	v_frexp_exp_i32_f64_e32 v152, v[152:153]
	v_subbrev_co_u32_e32 v169, vcc, 0, v152, vcc
	v_sub_u32_e32 v152, 0, v169
	v_ldexp_f32 v141, v141, v152
	v_ldexp_f32 v151, v151, v152
	v_pk_add_f32 v[152:153], v[140:141], 1.0 op_sel_hi:[1,0]
	v_pk_add_f32 v[160:161], v[140:141], -1.0 op_sel_hi:[1,0]
	v_pk_add_f32 v[154:155], v[152:153], -1.0 op_sel_hi:[1,0]
	v_pk_add_f32 v[162:163], v[160:161], 1.0 op_sel_hi:[1,0]
	v_pk_add_f32 v[154:155], v[140:141], v[154:155] neg_lo:[0,1] neg_hi:[0,1]
	v_pk_add_f32 v[140:141], v[140:141], v[162:163] neg_lo:[0,1] neg_hi:[0,1]
	v_pk_add_f32 v[154:155], v[150:151], v[154:155]
	v_pk_add_f32 v[140:141], v[150:151], v[140:141]
	v_pk_add_f32 v[156:157], v[152:153], v[154:155]
	v_pk_add_f32 v[150:151], v[160:161], v[140:141]
	v_rcp_f32_e32 v158, v156
	v_rcp_f32_e32 v159, v157
	v_pk_add_f32 v[152:153], v[156:157], v[152:153] neg_lo:[0,1] neg_hi:[0,1]
	v_pk_add_f32 v[160:161], v[150:151], v[160:161] neg_lo:[0,1] neg_hi:[0,1]
	v_pk_add_f32 v[152:153], v[154:155], v[152:153] neg_lo:[0,1] neg_hi:[0,1]
	v_pk_mul_f32 v[154:155], v[150:151], v[158:159]
	v_pk_add_f32 v[140:141], v[140:141], v[160:161] neg_lo:[0,1] neg_hi:[0,1]
	v_pk_mul_f32 v[160:161], v[156:157], v[154:155]
	v_cmp_neq_f32_e32 vcc, s3, v182
	v_pk_fma_f32 v[162:163], v[154:155], v[156:157], v[160:161] neg_lo:[0,0,1] neg_hi:[0,0,1]
	v_cmp_lt_f32_e64 s[0:1], |v205|, s4
	v_pk_fma_f32 v[162:163], v[154:155], v[152:153], v[162:163]
	s_nop 0
	v_pk_add_f32 v[164:165], v[160:161], v[162:163]
	s_nop 0
	v_pk_add_f32 v[166:167], v[150:151], v[164:165] neg_lo:[0,1] neg_hi:[0,1]
	v_pk_add_f32 v[160:161], v[164:165], v[160:161] neg_lo:[0,1] neg_hi:[0,1]
	v_pk_add_f32 v[150:151], v[150:151], v[166:167] neg_lo:[0,1] neg_hi:[0,1]
	s_nop 0
	v_pk_add_f32 v[150:151], v[150:151], v[164:165] neg_lo:[0,1] neg_hi:[0,1]
	s_nop 0
	v_pk_add_f32 v[140:141], v[140:141], v[150:151]
	v_pk_add_f32 v[150:151], v[160:161], v[162:163] neg_lo:[0,1] neg_hi:[0,1]
	s_nop 0
	v_pk_add_f32 v[140:141], v[150:151], v[140:141]
	s_nop 0
	v_pk_add_f32 v[150:151], v[166:167], v[140:141]
	s_nop 0
	v_pk_mul_f32 v[160:161], v[158:159], v[150:151]
	s_nop 0
	v_pk_mul_f32 v[162:163], v[156:157], v[160:161]
	s_nop 0
	v_pk_fma_f32 v[156:157], v[160:161], v[156:157], v[162:163] neg_lo:[0,0,1] neg_hi:[0,0,1]
	s_nop 0
	v_pk_fma_f32 v[152:153], v[160:161], v[152:153], v[156:157]
	v_pk_add_f32 v[156:157], v[166:167], v[150:151] neg_lo:[0,1] neg_hi:[0,1]
	s_nop 0
	v_pk_add_f32 v[140:141], v[140:141], v[156:157]
; __device__ __forceinline__ float softplusf_(float x) { return fmaxf(x, 0.0f) + log1pf(__expf(-fabsf(x))); }
;     __device__ __forceinline__ void operator()(f32x4 (&acc)[2][2][4][2], const pg8::Unit& u, int wr, int wc, int fr, int fq) const {
;     ...
;             if (wc == 0) { const f32x4 b0 = *(const f32x4*)(dtb + cl0), b1 = *(const f32x4*)(dtb + cl0 + 4);
; #pragma unroll
;                 for (int ai = 0; ai < 2; ++ai)
; #pragma unroll
;                     for (int m = 0; m < 4; ++m) { const int row = row0 + ai * 128 + m * 16; const f32x4 v0 = acc[ai][0][m][0] + b0, v1 = acc[ai][0][m][1] + b1;
;                         float* d = DTA + (size_t)row * NH + cl0;
;                         *(f32x4*)d = (f32x4){softplusf_(v0[0]), softplusf_(v0[1]), softplusf_(v0[2]), softplusf_(v0[3])}; *(f32x4*)(d + 4) = (f32x4){softplusf_(v1[0]), softplusf_(v1[1]), softplusf_(v1[2]), softplusf_(v1[3])}; } }
	v_pk_add_f32 v[156:157], v[162:163], v[152:153]
	s_nop 0
	v_pk_add_f32 v[164:165], v[150:151], v[156:157] neg_lo:[0,1] neg_hi:[0,1]
	v_pk_add_f32 v[162:163], v[156:157], v[162:163] neg_lo:[0,1] neg_hi:[0,1]
	v_pk_add_f32 v[150:151], v[150:151], v[164:165] neg_lo:[0,1] neg_hi:[0,1]
	s_nop 0
	v_pk_add_f32 v[150:151], v[150:151], v[156:157] neg_lo:[0,1] neg_hi:[0,1]
	s_nop 0
	v_pk_add_f32 v[140:141], v[140:141], v[150:151]
	v_pk_add_f32 v[150:151], v[162:163], v[152:153] neg_lo:[0,1] neg_hi:[0,1]
	s_nop 0
	v_pk_add_f32 v[140:141], v[150:151], v[140:141]
	v_pk_add_f32 v[150:151], v[154:155], v[160:161]
	v_pk_add_f32 v[140:141], v[164:165], v[140:141]
	v_pk_add_f32 v[152:153], v[150:151], v[154:155] neg_lo:[0,1] neg_hi:[0,1]
	v_pk_mul_f32 v[140:141], v[158:159], v[140:141]
	v_pk_add_f32 v[152:153], v[160:161], v[152:153] neg_lo:[0,1] neg_hi:[0,1]
	s_nop 0
	v_pk_add_f32 v[140:141], v[152:153], v[140:141]
	s_nop 0
	v_pk_add_f32 v[152:153], v[150:151], v[140:141]
	s_nop 0
	v_pk_mul_f32 v[154:155], v[152:153], v[152:153]
	v_pk_add_f32 v[150:151], v[152:153], v[150:151] neg_lo:[0,1] neg_hi:[0,1]
	v_pk_fma_f32 v[156:157], v[154:155], s[6:7], v[142:143] op_sel_hi:[1,0,0]
	v_pk_add_f32 v[140:141], v[140:141], v[150:151] neg_lo:[0,1] neg_hi:[0,1]
	v_ldexp_f32 v150, v152, 1
	v_pk_fma_f32 v[156:157], v[154:155], v[156:157], s[8:9] op_sel_hi:[1,1,0]
	v_ldexp_f32 v151, v153, 1
	v_pk_mul_f32 v[152:153], v[152:153], v[154:155]
	v_cvt_f32_i32_e32 v155, v169
	v_cvt_f32_i32_e32 v154, v168
	v_pk_mul_f32 v[152:153], v[152:153], v[156:157]
	v_ldexp_f32 v159, v141, 1
	v_pk_add_f32 v[156:157], v[150:151], v[152:153]
	v_pk_mul_f32 v[160:161], v[154:155], s[36:37] op_sel_hi:[1,0]
	v_pk_add_f32 v[150:151], v[156:157], v[150:151] neg_lo:[0,1] neg_hi:[0,1]
	v_pk_fma_f32 v[162:163], v[154:155], s[36:37], v[160:161] op_sel_hi:[1,0,1] neg_lo:[0,0,1] neg_hi:[0,0,1]
	v_pk_add_f32 v[150:151], v[152:153], v[150:151] neg_lo:[0,1] neg_hi:[0,1]
	v_pk_fma_f32 v[154:155], v[154:155], s[10:11], v[162:163] op_sel_hi:[1,0,1]
	v_ldexp_f32 v140, v140, 1
	v_mov_b32_e32 v152, v160
	v_mov_b32_e32 v153, v151
	v_mov_b32_e32 v158, v154
	v_mov_b32_e32 v141, v159
	v_pk_add_f32 v[152:153], v[152:153], v[158:159]
	v_pk_add_f32 v[158:159], v[140:141], v[150:151]
	v_mov_b32_e32 v151, v157
	v_mov_b32_e32 v141, v159
	v_pk_add_f32 v[162:163], v[160:161], v[154:155]
	v_pk_add_f32 v[140:141], v[140:141], v[150:151]
	v_pk_add_f32 v[150:151], v[156:157], v[158:159]
	v_mov_b32_e32 v172, v156
	v_pk_add_f32 v[164:165], v[162:163], v[150:151]
	v_mov_b32_e32 v170, v150
	v_mov_b32_e32 v171, v165
	v_mov_b32_e32 v173, v163
	v_pk_add_f32 v[170:171], v[170:171], v[172:173] neg_lo:[0,1] neg_hi:[0,1]
	v_mov_b32_e32 v166, v164
	v_mov_b32_e32 v167, v163
	v_mov_b32_e32 v168, v162
	v_mov_b32_e32 v169, v161
	v_mov_b32_e32 v172, v162
	v_mov_b32_e32 v173, v165
	v_mov_b32_e32 v161, v171
	v_pk_add_f32 v[166:167], v[166:167], v[168:169] neg_lo:[0,1] neg_hi:[0,1]
	v_mov_b32_e32 v168, v150
	v_mov_b32_e32 v169, v155
	v_pk_add_f32 v[160:161], v[172:173], v[160:161] neg_lo:[0,1] neg_hi:[0,1]
	v_pk_add_f32 v[168:169], v[168:169], v[166:167] neg_lo:[0,1] neg_hi:[0,1]
	v_mov_b32_e32 v172, v160
	v_mov_b32_e32 v173, v167
	v_mov_b32_e32 v206, v164
	v_mov_b32_e32 v207, v151
	v_mov_b32_e32 v167, v157
	v_pk_add_f32 v[172:173], v[154:155], v[172:173] neg_lo:[0,1] neg_hi:[0,1]
	v_pk_add_f32 v[166:167], v[206:207], v[166:167] neg_lo:[0,1] neg_hi:[0,1]
	v_mov_b32_e32 v155, v163
	v_pk_add_f32 v[152:153], v[152:153], v[166:167] neg_lo:[0,1] neg_hi:[0,1]
	v_pk_add_f32 v[154:155], v[154:155], v[160:161] neg_lo:[0,1] neg_hi:[0,1]
	v_pk_add_f32 v[140:141], v[140:141], v[170:171] neg_lo:[0,1] neg_hi:[0,1]
	v_pk_add_f32 v[150:151], v[150:151], v[156:157] neg_lo:[0,1] neg_hi:[0,1]
	v_pk_add_f32 v[156:157], v[140:141], v[154:155]
	v_mov_b32_e32 v155, v169
	v_mov_b32_e32 v141, v153
	v_pk_add_f32 v[150:151], v[158:159], v[150:151] neg_lo:[0,1] neg_hi:[0,1]
	v_pk_add_f32 v[158:159], v[168:169], v[152:153]
	v_pk_add_f32 v[140:141], v[154:155], v[140:141]
	v_mov_b32_e32 v152, v156
	v_pk_add_f32 v[140:141], v[140:141], v[172:173] neg_lo:[0,1] neg_hi:[0,1]
	v_mov_b32_e32 v153, v159
	v_pk_add_f32 v[152:153], v[152:153], v[140:141] neg_lo:[0,1] neg_hi:[0,1]
	v_pk_add_f32 v[140:141], v[150:151], v[140:141] neg_lo:[0,1] neg_hi:[0,1]
	v_pk_add_f32 v[152:153], v[154:155], v[152:153] neg_lo:[0,1] neg_hi:[0,1]
	v_pk_add_f32 v[150:151], v[158:159], v[156:157]
	v_pk_add_f32 v[140:141], v[140:141], v[152:153]
	v_pk_add_f32 v[152:153], v[164:165], v[150:151]
	s_nop 0
	v_pk_add_f32 v[154:155], v[152:153], v[164:165] neg_lo:[0,1] neg_hi:[0,1]
	s_nop 0
	v_pk_add_f32 v[150:151], v[150:151], v[154:155] neg_lo:[0,1] neg_hi:[0,1]
	s_nop 0
	v_pk_add_f32 v[140:141], v[140:141], v[150:151]
	s_nop 0
	v_pk_add_f32 v[140:141], v[152:153], v[140:141]
	s_nop 0
	v_cndmask_b32_e32 v140, v252, v140, vcc
	v_cmp_neq_f32_e32 vcc, s3, v205
	s_nop 1
	v_cndmask_b32_e32 v141, v252, v141, vcc
	v_cmp_ngt_f32_e32 vcc, -1.0, v205
	s_nop 1
	v_cndmask_b32_e32 v141, v253, v141, vcc
	v_cmp_ngt_f32_e32 vcc, -1.0, v182
	s_nop 1
	v_cndmask_b32_e32 v140, v253, v140, vcc
	v_cmp_neq_f32_e32 vcc, -1.0, v182
	s_nop 1
	v_cndmask_b32_e32 v140, v244, v140, vcc
	v_cmp_neq_f32_e32 vcc, -1.0, v205
	s_nop 1
	v_cndmask_b32_e32 v141, v244, v141, vcc
	v_cmp_lt_f32_e64 vcc, |v182|, s4
	v_cndmask_b32_e64 v141, v141, v205, s[0:1]
	s_nop 0
	v_cndmask_b32_e32 v140, v140, v182, vcc
	v_pk_add_f32 v[138:139], v[138:139], v[140:141]
	v_mul_f32_e64 v141, |v148|, s88
	v_exp_f32_e32 v182, v141
	v_max_f32_e32 v140, 0, v148
	v_add_f32_e32 v141, 1.0, v182
	v_add_f32_e32 v148, -1.0, v141
	v_sub_f32_e32 v150, v148, v141
; __device__ __forceinline__ float softplusf_(float x) { return fmaxf(x, 0.0f) + log1pf(__expf(-fabsf(x))); }
;     __device__ __forceinline__ void operator()(f32x4 (&acc)[2][2][4][2], const pg8::Unit& u, int wr, int wc, int fr, int fq) const {
;     ...
;             if (wc == 0) { const f32x4 b0 = *(const f32x4*)(dtb + cl0), b1 = *(const f32x4*)(dtb + cl0 + 4);
; #pragma unroll
;                 for (int ai = 0; ai < 2; ++ai)
; #pragma unroll
;                     for (int m = 0; m < 4; ++m) { const int row = row0 + ai * 128 + m * 16; const f32x4 v0 = acc[ai][0][m][0] + b0, v1 = acc[ai][0][m][1] + b1;
;                         float* d = DTA + (size_t)row * NH + cl0;
;                         *(f32x4*)d = (f32x4){softplusf_(v0[0]), softplusf_(v0[1]), softplusf_(v0[2]), softplusf_(v0[3])}; *(f32x4*)(d + 4) = (f32x4){softplusf_(v1[0]), softplusf_(v1[1]), softplusf_(v1[2]), softplusf_(v1[3])}; } }
	v_add_f32_e32 v150, 1.0, v150
	v_sub_f32_e32 v148, v182, v148
	v_add_f32_e32 v152, v148, v150
	v_frexp_mant_f32_e32 v148, v141
	v_cvt_f64_f32_e32 v[150:151], v141
	v_cmp_gt_f32_e32 vcc, s2, v148
	v_frexp_exp_i32_f64_e32 v148, v[150:151]
	s_nop 0
	v_subbrev_co_u32_e32 v168, vcc, 0, v148, vcc
	v_sub_u32_e32 v150, 0, v168
	v_ldexp_f32 v148, v141, v150
	v_max_f32_e32 v141, 0, v149
	v_mul_f32_e64 v149, |v149|, s88
	v_exp_f32_e32 v205, v149
	v_ldexp_f32 v150, v152, v150
	v_add_f32_e32 v149, 1.0, v205
	v_add_f32_e32 v151, -1.0, v149
	v_sub_f32_e32 v152, v151, v149
	v_add_f32_e32 v152, 1.0, v152
	v_sub_f32_e32 v151, v205, v151
	v_add_f32_e32 v151, v151, v152
	v_frexp_mant_f32_e32 v152, v149
	v_cmp_gt_f32_e32 vcc, s2, v152
	v_cvt_f64_f32_e32 v[152:153], v149
	v_frexp_exp_i32_f64_e32 v152, v[152:153]
	v_subbrev_co_u32_e32 v169, vcc, 0, v152, vcc
	v_sub_u32_e32 v152, 0, v169
	v_ldexp_f32 v149, v149, v152
	v_ldexp_f32 v151, v151, v152
	v_pk_add_f32 v[152:153], v[148:149], 1.0 op_sel_hi:[1,0]
	v_pk_add_f32 v[160:161], v[148:149], -1.0 op_sel_hi:[1,0]
	v_pk_add_f32 v[154:155], v[152:153], -1.0 op_sel_hi:[1,0]
	v_pk_add_f32 v[162:163], v[160:161], 1.0 op_sel_hi:[1,0]
	v_pk_add_f32 v[154:155], v[148:149], v[154:155] neg_lo:[0,1] neg_hi:[0,1]
	v_pk_add_f32 v[148:149], v[148:149], v[162:163] neg_lo:[0,1] neg_hi:[0,1]
	v_pk_add_f32 v[154:155], v[150:151], v[154:155]
	v_pk_add_f32 v[148:149], v[150:151], v[148:149]
	v_pk_add_f32 v[156:157], v[152:153], v[154:155]
	v_pk_add_f32 v[150:151], v[160:161], v[148:149]
	v_rcp_f32_e32 v158, v156
	v_rcp_f32_e32 v159, v157
	v_pk_add_f32 v[152:153], v[156:157], v[152:153] neg_lo:[0,1] neg_hi:[0,1]
	v_pk_add_f32 v[160:161], v[150:151], v[160:161] neg_lo:[0,1] neg_hi:[0,1]
	v_pk_add_f32 v[152:153], v[154:155], v[152:153] neg_lo:[0,1] neg_hi:[0,1]
	v_pk_mul_f32 v[154:155], v[150:151], v[158:159]
	v_pk_add_f32 v[148:149], v[148:149], v[160:161] neg_lo:[0,1] neg_hi:[0,1]
	v_pk_mul_f32 v[160:161], v[156:157], v[154:155]
	v_cmp_neq_f32_e32 vcc, s3, v182
	v_pk_fma_f32 v[162:163], v[154:155], v[156:157], v[160:161] neg_lo:[0,0,1] neg_hi:[0,0,1]
	v_cmp_lt_f32_e64 s[0:1], |v205|, s4
	v_pk_fma_f32 v[162:163], v[154:155], v[152:153], v[162:163]
	s_nop 0
	v_pk_add_f32 v[164:165], v[160:161], v[162:163]
	s_nop 0
	v_pk_add_f32 v[166:167], v[150:151], v[164:165] neg_lo:[0,1] neg_hi:[0,1]
	v_pk_add_f32 v[160:161], v[164:165], v[160:161] neg_lo:[0,1] neg_hi:[0,1]
	v_pk_add_f32 v[150:151], v[150:151], v[166:167] neg_lo:[0,1] neg_hi:[0,1]
	s_nop 0
	v_pk_add_f32 v[150:151], v[150:151], v[164:165] neg_lo:[0,1] neg_hi:[0,1]
	s_nop 0
	v_pk_add_f32 v[148:149], v[148:149], v[150:151]
	v_pk_add_f32 v[150:151], v[160:161], v[162:163] neg_lo:[0,1] neg_hi:[0,1]
	s_nop 0
	v_pk_add_f32 v[148:149], v[150:151], v[148:149]
	s_nop 0
	v_pk_add_f32 v[150:151], v[166:167], v[148:149]
	s_nop 0
	v_pk_mul_f32 v[160:161], v[158:159], v[150:151]
	s_nop 0
	v_pk_mul_f32 v[162:163], v[156:157], v[160:161]
	s_nop 0
	v_pk_fma_f32 v[156:157], v[160:161], v[156:157], v[162:163] neg_lo:[0,0,1] neg_hi:[0,0,1]
	s_nop 0
	v_pk_fma_f32 v[152:153], v[160:161], v[152:153], v[156:157]
	v_pk_add_f32 v[156:157], v[166:167], v[150:151] neg_lo:[0,1] neg_hi:[0,1]
	s_nop 0
	v_pk_add_f32 v[148:149], v[148:149], v[156:157]
	v_pk_add_f32 v[156:157], v[162:163], v[152:153]
	s_nop 0
	v_pk_add_f32 v[164:165], v[150:151], v[156:157] neg_lo:[0,1] neg_hi:[0,1]
	v_pk_add_f32 v[162:163], v[156:157], v[162:163] neg_lo:[0,1] neg_hi:[0,1]
	v_pk_add_f32 v[150:151], v[150:151], v[164:165] neg_lo:[0,1] neg_hi:[0,1]
	s_nop 0
	v_pk_add_f32 v[150:151], v[150:151], v[156:157] neg_lo:[0,1] neg_hi:[0,1]
	s_nop 0
	v_pk_add_f32 v[148:149], v[148:149], v[150:151]
	v_pk_add_f32 v[150:151], v[162:163], v[152:153] neg_lo:[0,1] neg_hi:[0,1]
	s_nop 0
	v_pk_add_f32 v[148:149], v[150:151], v[148:149]
	v_pk_add_f32 v[150:151], v[154:155], v[160:161]
	v_pk_add_f32 v[148:149], v[164:165], v[148:149]
	v_pk_add_f32 v[152:153], v[150:151], v[154:155] neg_lo:[0,1] neg_hi:[0,1]
	v_pk_mul_f32 v[148:149], v[158:159], v[148:149]
	v_pk_add_f32 v[152:153], v[160:161], v[152:153] neg_lo:[0,1] neg_hi:[0,1]
	s_nop 0
	v_pk_add_f32 v[148:149], v[152:153], v[148:149]
	s_nop 0
	v_pk_add_f32 v[152:153], v[150:151], v[148:149]
	s_nop 0
	v_pk_mul_f32 v[154:155], v[152:153], v[152:153]
	v_pk_add_f32 v[150:151], v[152:153], v[150:151] neg_lo:[0,1] neg_hi:[0,1]
	v_pk_fma_f32 v[156:157], v[154:155], s[6:7], v[142:143] op_sel_hi:[1,0,0]
	v_pk_add_f32 v[148:149], v[148:149], v[150:151] neg_lo:[0,1] neg_hi:[0,1]
	v_ldexp_f32 v150, v152, 1
	v_pk_fma_f32 v[156:157], v[154:155], v[156:157], s[8:9] op_sel_hi:[1,1,0]
	v_ldexp_f32 v151, v153, 1
	v_pk_mul_f32 v[152:153], v[152:153], v[154:155]
	v_cvt_f32_i32_e32 v155, v169
	v_cvt_f32_i32_e32 v154, v168
	v_pk_mul_f32 v[152:153], v[152:153], v[156:157]
	v_ldexp_f32 v159, v149, 1
	v_pk_add_f32 v[156:157], v[150:151], v[152:153]
	v_pk_mul_f32 v[160:161], v[154:155], s[36:37] op_sel_hi:[1,0]
	v_pk_add_f32 v[150:151], v[156:157], v[150:151] neg_lo:[0,1] neg_hi:[0,1]
	v_pk_fma_f32 v[162:163], v[154:155], s[36:37], v[160:161] op_sel_hi:[1,0,1] neg_lo:[0,0,1] neg_hi:[0,0,1]
	v_pk_add_f32 v[150:151], v[152:153], v[150:151] neg_lo:[0,1] neg_hi:[0,1]
	v_pk_fma_f32 v[154:155], v[154:155], s[10:11], v[162:163] op_sel_hi:[1,0,1]
	v_ldexp_f32 v148, v148, 1
	v_mov_b32_e32 v152, v160
	v_mov_b32_e32 v153, v151
	v_mov_b32_e32 v158, v154
	v_mov_b32_e32 v149, v159
	v_pk_add_f32 v[152:153], v[152:153], v[158:159]
	v_pk_add_f32 v[158:159], v[148:149], v[150:151]
	v_mov_b32_e32 v151, v157
	v_mov_b32_e32 v149, v159
	v_pk_add_f32 v[162:163], v[160:161], v[154:155]
	v_pk_add_f32 v[148:149], v[148:149], v[150:151]
; __device__ __forceinline__ float softplusf_(float x) { return fmaxf(x, 0.0f) + log1pf(__expf(-fabsf(x))); }
;     __device__ __forceinline__ void operator()(f32x4 (&acc)[2][2][4][2], const pg8::Unit& u, int wr, int wc, int fr, int fq) const {
;     ...
;             if (wc == 0) { const f32x4 b0 = *(const f32x4*)(dtb + cl0), b1 = *(const f32x4*)(dtb + cl0 + 4);
; #pragma unroll
;                 for (int ai = 0; ai < 2; ++ai)
; #pragma unroll
;                     for (int m = 0; m < 4; ++m) { const int row = row0 + ai * 128 + m * 16; const f32x4 v0 = acc[ai][0][m][0] + b0, v1 = acc[ai][0][m][1] + b1;
;                         float* d = DTA + (size_t)row * NH + cl0;
;                         *(f32x4*)d = (f32x4){softplusf_(v0[0]), softplusf_(v0[1]), softplusf_(v0[2]), softplusf_(v0[3])}; *(f32x4*)(d + 4) = (f32x4){softplusf_(v1[0]), softplusf_(v1[1]), softplusf_(v1[2]), softplusf_(v1[3])}; } }
	v_pk_add_f32 v[150:151], v[156:157], v[158:159]
	v_mov_b32_e32 v172, v156
	v_pk_add_f32 v[164:165], v[162:163], v[150:151]
	v_mov_b32_e32 v170, v150
	v_mov_b32_e32 v171, v165
	v_mov_b32_e32 v173, v163
	v_pk_add_f32 v[170:171], v[170:171], v[172:173] neg_lo:[0,1] neg_hi:[0,1]
	v_mov_b32_e32 v166, v164
	v_mov_b32_e32 v167, v163
	v_mov_b32_e32 v168, v162
	v_mov_b32_e32 v169, v161
	v_mov_b32_e32 v172, v162
	v_mov_b32_e32 v173, v165
	v_mov_b32_e32 v161, v171
	v_pk_add_f32 v[166:167], v[166:167], v[168:169] neg_lo:[0,1] neg_hi:[0,1]
	v_mov_b32_e32 v168, v150
	v_mov_b32_e32 v169, v155
	v_pk_add_f32 v[160:161], v[172:173], v[160:161] neg_lo:[0,1] neg_hi:[0,1]
	v_pk_add_f32 v[168:169], v[168:169], v[166:167] neg_lo:[0,1] neg_hi:[0,1]
	v_mov_b32_e32 v172, v160
	v_mov_b32_e32 v173, v167
	v_mov_b32_e32 v206, v164
	v_mov_b32_e32 v207, v151
	v_mov_b32_e32 v167, v157
	v_pk_add_f32 v[172:173], v[154:155], v[172:173] neg_lo:[0,1] neg_hi:[0,1]
	v_pk_add_f32 v[166:167], v[206:207], v[166:167] neg_lo:[0,1] neg_hi:[0,1]
	v_mov_b32_e32 v155, v163
	v_pk_add_f32 v[152:153], v[152:153], v[166:167] neg_lo:[0,1] neg_hi:[0,1]
	v_pk_add_f32 v[154:155], v[154:155], v[160:161] neg_lo:[0,1] neg_hi:[0,1]
	v_pk_add_f32 v[148:149], v[148:149], v[170:171] neg_lo:[0,1] neg_hi:[0,1]
	v_pk_add_f32 v[150:151], v[150:151], v[156:157] neg_lo:[0,1] neg_hi:[0,1]
	v_pk_add_f32 v[156:157], v[148:149], v[154:155]
	v_mov_b32_e32 v155, v169
	v_mov_b32_e32 v149, v153
	v_pk_add_f32 v[150:151], v[158:159], v[150:151] neg_lo:[0,1] neg_hi:[0,1]
	v_pk_add_f32 v[158:159], v[168:169], v[152:153]
	v_pk_add_f32 v[148:149], v[154:155], v[148:149]
	v_mov_b32_e32 v152, v156
	v_pk_add_f32 v[148:149], v[148:149], v[172:173] neg_lo:[0,1] neg_hi:[0,1]
	v_mov_b32_e32 v153, v159
	v_pk_add_f32 v[152:153], v[152:153], v[148:149] neg_lo:[0,1] neg_hi:[0,1]
	v_pk_add_f32 v[148:149], v[150:151], v[148:149] neg_lo:[0,1] neg_hi:[0,1]
	v_pk_add_f32 v[152:153], v[154:155], v[152:153] neg_lo:[0,1] neg_hi:[0,1]
	v_pk_add_f32 v[150:151], v[158:159], v[156:157]
	v_pk_add_f32 v[148:149], v[148:149], v[152:153]
	v_pk_add_f32 v[152:153], v[164:165], v[150:151]
	s_nop 0
	v_pk_add_f32 v[154:155], v[152:153], v[164:165] neg_lo:[0,1] neg_hi:[0,1]
	s_nop 0
	v_pk_add_f32 v[150:151], v[150:151], v[154:155] neg_lo:[0,1] neg_hi:[0,1]
	s_nop 0
	v_pk_add_f32 v[148:149], v[148:149], v[150:151]
	v_pk_add_f32 v[150:151], v[106:107], v[130:131]
	v_pk_add_f32 v[148:149], v[152:153], v[148:149]
	v_pk_add_f32 v[152:153], v[110:111], v[134:135]
	v_cndmask_b32_e32 v148, v252, v148, vcc
	v_cmp_neq_f32_e32 vcc, s3, v205
	s_nop 1
	v_cndmask_b32_e32 v149, v252, v149, vcc
	v_cmp_ngt_f32_e32 vcc, -1.0, v205
	s_nop 1
	v_cndmask_b32_e32 v149, v253, v149, vcc
	v_cmp_ngt_f32_e32 vcc, -1.0, v182
	s_nop 1
	v_cndmask_b32_e32 v148, v253, v148, vcc
	v_cmp_neq_f32_e32 vcc, -1.0, v182
	s_nop 1
	v_cndmask_b32_e32 v148, v244, v148, vcc
	v_cmp_neq_f32_e32 vcc, -1.0, v205
	s_nop 1
	v_cndmask_b32_e32 v149, v244, v149, vcc
	v_cmp_lt_f32_e64 vcc, |v182|, s4
	v_cndmask_b32_e64 v149, v149, v205, s[0:1]
	s_nop 0
	v_cndmask_b32_e32 v148, v148, v182, vcc
	v_pk_add_f32 v[140:141], v[140:141], v[148:149]
	global_store_dwordx4 v[146:147], v[138:141], off offset:16
	v_pk_add_f32 v[148:149], v[108:109], v[132:133]
	s_nop 0
	v_lshlrev_b64 v[138:139], 7, v[200:201]
	v_lshl_add_u64 v[146:147], v[144:145], 0, v[138:139]
	v_mul_f32_e64 v139, |v152|, s88
	v_exp_f32_e32 v182, v139
	v_max_f32_e32 v138, 0, v152
	v_pk_add_f32 v[140:141], v[112:113], v[136:137]
	v_add_f32_e32 v139, 1.0, v182
	v_add_f32_e32 v152, -1.0, v139
	v_sub_f32_e32 v154, v152, v139
	v_add_f32_e32 v154, 1.0, v154
	v_sub_f32_e32 v152, v182, v152
	v_add_f32_e32 v156, v152, v154
	v_frexp_mant_f32_e32 v152, v139
	v_cvt_f64_f32_e32 v[154:155], v139
	v_cmp_gt_f32_e32 vcc, s2, v152
	v_frexp_exp_i32_f64_e32 v152, v[154:155]
	s_nop 0
	v_subbrev_co_u32_e32 v172, vcc, 0, v152, vcc
	v_sub_u32_e32 v154, 0, v172
	v_ldexp_f32 v152, v139, v154
	v_max_f32_e32 v139, 0, v153
	v_mul_f32_e64 v153, |v153|, s88
	v_exp_f32_e32 v205, v153
	v_ldexp_f32 v154, v156, v154
	v_add_f32_e32 v153, 1.0, v205
	v_add_f32_e32 v155, -1.0, v153
	v_sub_f32_e32 v156, v155, v153
	v_add_f32_e32 v156, 1.0, v156
	v_sub_f32_e32 v155, v205, v155
	v_add_f32_e32 v155, v155, v156
	v_frexp_mant_f32_e32 v156, v153
	v_cmp_gt_f32_e32 vcc, s2, v156
	v_cvt_f64_f32_e32 v[156:157], v153
	v_frexp_exp_i32_f64_e32 v156, v[156:157]
	v_subbrev_co_u32_e32 v173, vcc, 0, v156, vcc
	v_sub_u32_e32 v156, 0, v173
	v_ldexp_f32 v153, v153, v156
	v_ldexp_f32 v155, v155, v156
	v_pk_add_f32 v[156:157], v[152:153], 1.0 op_sel_hi:[1,0]
	v_pk_add_f32 v[164:165], v[152:153], -1.0 op_sel_hi:[1,0]
	v_pk_add_f32 v[158:159], v[156:157], -1.0 op_sel_hi:[1,0]
	v_pk_add_f32 v[166:167], v[164:165], 1.0 op_sel_hi:[1,0]
	v_pk_add_f32 v[158:159], v[152:153], v[158:159] neg_lo:[0,1] neg_hi:[0,1]
	v_pk_add_f32 v[152:153], v[152:153], v[166:167] neg_lo:[0,1] neg_hi:[0,1]
	v_pk_add_f32 v[158:159], v[154:155], v[158:159]
	v_pk_add_f32 v[152:153], v[154:155], v[152:153]
	v_pk_add_f32 v[160:161], v[156:157], v[158:159]
	v_pk_add_f32 v[154:155], v[164:165], v[152:153]
	v_rcp_f32_e32 v162, v160
	v_rcp_f32_e32 v163, v161
	v_pk_add_f32 v[156:157], v[160:161], v[156:157] neg_lo:[0,1] neg_hi:[0,1]
	v_pk_add_f32 v[164:165], v[154:155], v[164:165] neg_lo:[0,1] neg_hi:[0,1]
	v_pk_add_f32 v[156:157], v[158:159], v[156:157] neg_lo:[0,1] neg_hi:[0,1]
	v_pk_mul_f32 v[158:159], v[154:155], v[162:163]
	v_pk_add_f32 v[152:153], v[152:153], v[164:165] neg_lo:[0,1] neg_hi:[0,1]
	v_pk_mul_f32 v[164:165], v[160:161], v[158:159]
	v_cmp_neq_f32_e32 vcc, s3, v182
	v_pk_fma_f32 v[166:167], v[158:159], v[160:161], v[164:165] neg_lo:[0,0,1] neg_hi:[0,0,1]
; __device__ __forceinline__ float softplusf_(float x) { return fmaxf(x, 0.0f) + log1pf(__expf(-fabsf(x))); }
;     __device__ __forceinline__ void operator()(f32x4 (&acc)[2][2][4][2], const pg8::Unit& u, int wr, int wc, int fr, int fq) const {
;     ...
;             if (wc == 0) { const f32x4 b0 = *(const f32x4*)(dtb + cl0), b1 = *(const f32x4*)(dtb + cl0 + 4);
; #pragma unroll
;                 for (int ai = 0; ai < 2; ++ai)
; #pragma unroll
;                     for (int m = 0; m < 4; ++m) { const int row = row0 + ai * 128 + m * 16; const f32x4 v0 = acc[ai][0][m][0] + b0, v1 = acc[ai][0][m][1] + b1;
;                         float* d = DTA + (size_t)row * NH + cl0;
;                         *(f32x4*)d = (f32x4){softplusf_(v0[0]), softplusf_(v0[1]), softplusf_(v0[2]), softplusf_(v0[3])}; *(f32x4*)(d + 4) = (f32x4){softplusf_(v1[0]), softplusf_(v1[1]), softplusf_(v1[2]), softplusf_(v1[3])}; } }
	v_cmp_lt_f32_e64 s[0:1], |v205|, s4
	v_pk_fma_f32 v[166:167], v[158:159], v[156:157], v[166:167]
	s_nop 0
	v_pk_add_f32 v[168:169], v[164:165], v[166:167]
	s_nop 0
	v_pk_add_f32 v[170:171], v[154:155], v[168:169] neg_lo:[0,1] neg_hi:[0,1]
	v_pk_add_f32 v[164:165], v[168:169], v[164:165] neg_lo:[0,1] neg_hi:[0,1]
	v_pk_add_f32 v[154:155], v[154:155], v[170:171] neg_lo:[0,1] neg_hi:[0,1]
	s_nop 0
	v_pk_add_f32 v[154:155], v[154:155], v[168:169] neg_lo:[0,1] neg_hi:[0,1]
	s_nop 0
	v_pk_add_f32 v[152:153], v[152:153], v[154:155]
	v_pk_add_f32 v[154:155], v[164:165], v[166:167] neg_lo:[0,1] neg_hi:[0,1]
	s_nop 0
	v_pk_add_f32 v[152:153], v[154:155], v[152:153]
	s_nop 0
	v_pk_add_f32 v[154:155], v[170:171], v[152:153]
	s_nop 0
	v_pk_mul_f32 v[164:165], v[162:163], v[154:155]
	s_nop 0
	v_pk_mul_f32 v[166:167], v[160:161], v[164:165]
	s_nop 0
	v_pk_fma_f32 v[160:161], v[164:165], v[160:161], v[166:167] neg_lo:[0,0,1] neg_hi:[0,0,1]
	s_nop 0
	v_pk_fma_f32 v[156:157], v[164:165], v[156:157], v[160:161]
	v_pk_add_f32 v[160:161], v[170:171], v[154:155] neg_lo:[0,1] neg_hi:[0,1]
	s_nop 0
	v_pk_add_f32 v[152:153], v[152:153], v[160:161]
	v_pk_add_f32 v[160:161], v[166:167], v[156:157]
	s_nop 0
	v_pk_add_f32 v[168:169], v[154:155], v[160:161] neg_lo:[0,1] neg_hi:[0,1]
	v_pk_add_f32 v[166:167], v[160:161], v[166:167] neg_lo:[0,1] neg_hi:[0,1]
	v_pk_add_f32 v[154:155], v[154:155], v[168:169] neg_lo:[0,1] neg_hi:[0,1]
	s_nop 0
	v_pk_add_f32 v[154:155], v[154:155], v[160:161] neg_lo:[0,1] neg_hi:[0,1]
	s_nop 0
	v_pk_add_f32 v[152:153], v[152:153], v[154:155]
	v_pk_add_f32 v[154:155], v[166:167], v[156:157] neg_lo:[0,1] neg_hi:[0,1]
	s_nop 0
	v_pk_add_f32 v[152:153], v[154:155], v[152:153]
	v_pk_add_f32 v[154:155], v[158:159], v[164:165]
	v_pk_add_f32 v[152:153], v[168:169], v[152:153]
	v_pk_add_f32 v[156:157], v[154:155], v[158:159] neg_lo:[0,1] neg_hi:[0,1]
	v_pk_mul_f32 v[152:153], v[162:163], v[152:153]
	v_pk_add_f32 v[156:157], v[164:165], v[156:157] neg_lo:[0,1] neg_hi:[0,1]
	s_nop 0
	v_pk_add_f32 v[152:153], v[156:157], v[152:153]
	s_nop 0
	v_pk_add_f32 v[156:157], v[154:155], v[152:153]
	s_nop 0
	v_pk_mul_f32 v[158:159], v[156:157], v[156:157]
	v_pk_add_f32 v[154:155], v[156:157], v[154:155] neg_lo:[0,1] neg_hi:[0,1]
	v_pk_fma_f32 v[160:161], v[158:159], s[6:7], v[142:143] op_sel_hi:[1,0,0]
	v_pk_add_f32 v[152:153], v[152:153], v[154:155] neg_lo:[0,1] neg_hi:[0,1]
	v_ldexp_f32 v154, v156, 1
	v_pk_fma_f32 v[160:161], v[158:159], v[160:161], s[8:9] op_sel_hi:[1,1,0]
	v_ldexp_f32 v155, v157, 1
	v_pk_mul_f32 v[156:157], v[156:157], v[158:159]
	v_cvt_f32_i32_e32 v159, v173
	v_cvt_f32_i32_e32 v158, v172
	v_pk_mul_f32 v[156:157], v[156:157], v[160:161]
	v_ldexp_f32 v163, v153, 1
	v_pk_add_f32 v[160:161], v[154:155], v[156:157]
	v_pk_mul_f32 v[164:165], v[158:159], s[36:37] op_sel_hi:[1,0]
	v_pk_add_f32 v[154:155], v[160:161], v[154:155] neg_lo:[0,1] neg_hi:[0,1]
	v_pk_fma_f32 v[166:167], v[158:159], s[36:37], v[164:165] op_sel_hi:[1,0,1] neg_lo:[0,0,1] neg_hi:[0,0,1]
	v_pk_add_f32 v[154:155], v[156:157], v[154:155] neg_lo:[0,1] neg_hi:[0,1]
	v_pk_fma_f32 v[158:159], v[158:159], s[10:11], v[166:167] op_sel_hi:[1,0,1]
	v_ldexp_f32 v152, v152, 1
	v_mov_b32_e32 v156, v164
	v_mov_b32_e32 v157, v155
	v_mov_b32_e32 v162, v158
	v_mov_b32_e32 v153, v163
	v_pk_add_f32 v[156:157], v[156:157], v[162:163]
	v_pk_add_f32 v[162:163], v[152:153], v[154:155]
	v_mov_b32_e32 v155, v161
	v_mov_b32_e32 v153, v163
	v_pk_add_f32 v[166:167], v[164:165], v[158:159]
	v_pk_add_f32 v[152:153], v[152:153], v[154:155]
	v_pk_add_f32 v[154:155], v[160:161], v[162:163]
	v_mov_b32_e32 v208, v160
	v_pk_add_f32 v[168:169], v[166:167], v[154:155]
	v_mov_b32_e32 v206, v154
	v_mov_b32_e32 v207, v169
	v_mov_b32_e32 v209, v167
	v_pk_add_f32 v[206:207], v[206:207], v[208:209] neg_lo:[0,1] neg_hi:[0,1]
	v_mov_b32_e32 v170, v168
	v_mov_b32_e32 v171, v167
	v_mov_b32_e32 v172, v166
	v_mov_b32_e32 v173, v165
	v_mov_b32_e32 v208, v166
	v_mov_b32_e32 v209, v169
	v_mov_b32_e32 v165, v207
	v_pk_add_f32 v[170:171], v[170:171], v[172:173] neg_lo:[0,1] neg_hi:[0,1]
	v_mov_b32_e32 v172, v154
	v_mov_b32_e32 v173, v159
	v_pk_add_f32 v[164:165], v[208:209], v[164:165] neg_lo:[0,1] neg_hi:[0,1]
	v_pk_add_f32 v[172:173], v[172:173], v[170:171] neg_lo:[0,1] neg_hi:[0,1]
	v_mov_b32_e32 v208, v164
	v_mov_b32_e32 v209, v171
	v_mov_b32_e32 v210, v168
	v_mov_b32_e32 v211, v155
	v_mov_b32_e32 v171, v161
	v_pk_add_f32 v[208:209], v[158:159], v[208:209] neg_lo:[0,1] neg_hi:[0,1]
	v_pk_add_f32 v[170:171], v[210:211], v[170:171] neg_lo:[0,1] neg_hi:[0,1]
	v_mov_b32_e32 v159, v167
	v_pk_add_f32 v[156:157], v[156:157], v[170:171] neg_lo:[0,1] neg_hi:[0,1]
	v_pk_add_f32 v[158:159], v[158:159], v[164:165] neg_lo:[0,1] neg_hi:[0,1]
	v_pk_add_f32 v[152:153], v[152:153], v[206:207] neg_lo:[0,1] neg_hi:[0,1]
	v_pk_add_f32 v[154:155], v[154:155], v[160:161] neg_lo:[0,1] neg_hi:[0,1]
	v_pk_add_f32 v[160:161], v[152:153], v[158:159]
	v_mov_b32_e32 v159, v173
	v_mov_b32_e32 v153, v157
	v_pk_add_f32 v[154:155], v[162:163], v[154:155] neg_lo:[0,1] neg_hi:[0,1]
	v_pk_add_f32 v[162:163], v[172:173], v[156:157]
	v_pk_add_f32 v[152:153], v[158:159], v[152:153]
	v_mov_b32_e32 v156, v160
	v_pk_add_f32 v[152:153], v[152:153], v[208:209] neg_lo:[0,1] neg_hi:[0,1]
	v_mov_b32_e32 v157, v163
	v_pk_add_f32 v[156:157], v[156:157], v[152:153] neg_lo:[0,1] neg_hi:[0,1]
	v_pk_add_f32 v[152:153], v[154:155], v[152:153] neg_lo:[0,1] neg_hi:[0,1]
	v_pk_add_f32 v[156:157], v[158:159], v[156:157] neg_lo:[0,1] neg_hi:[0,1]
	v_pk_add_f32 v[154:155], v[162:163], v[160:161]
	v_pk_add_f32 v[152:153], v[152:153], v[156:157]
	v_pk_add_f32 v[156:157], v[168:169], v[154:155]
; __device__ __forceinline__ float softplusf_(float x) { return fmaxf(x, 0.0f) + log1pf(__expf(-fabsf(x))); }
;     __device__ __forceinline__ void operator()(f32x4 (&acc)[2][2][4][2], const pg8::Unit& u, int wr, int wc, int fr, int fq) const {
;     ...
;             if (wc == 0) { const f32x4 b0 = *(const f32x4*)(dtb + cl0), b1 = *(const f32x4*)(dtb + cl0 + 4);
; #pragma unroll
;                 for (int ai = 0; ai < 2; ++ai)
; #pragma unroll
;                     for (int m = 0; m < 4; ++m) { const int row = row0 + ai * 128 + m * 16; const f32x4 v0 = acc[ai][0][m][0] + b0, v1 = acc[ai][0][m][1] + b1;
;                         float* d = DTA + (size_t)row * NH + cl0;
;                         *(f32x4*)d = (f32x4){softplusf_(v0[0]), softplusf_(v0[1]), softplusf_(v0[2]), softplusf_(v0[3])}; *(f32x4*)(d + 4) = (f32x4){softplusf_(v1[0]), softplusf_(v1[1]), softplusf_(v1[2]), softplusf_(v1[3])}; } }
	s_nop 0
	v_pk_add_f32 v[158:159], v[156:157], v[168:169] neg_lo:[0,1] neg_hi:[0,1]
	s_nop 0
	v_pk_add_f32 v[154:155], v[154:155], v[158:159] neg_lo:[0,1] neg_hi:[0,1]
	s_nop 0
	v_pk_add_f32 v[152:153], v[152:153], v[154:155]
	s_nop 0
	v_pk_add_f32 v[152:153], v[156:157], v[152:153]
	s_nop 0
	v_cndmask_b32_e32 v152, v252, v152, vcc
	v_cmp_neq_f32_e32 vcc, s3, v205
	s_nop 1
	v_cndmask_b32_e32 v153, v252, v153, vcc
	v_cmp_ngt_f32_e32 vcc, -1.0, v205
	s_nop 1
	v_cndmask_b32_e32 v153, v253, v153, vcc
	v_cmp_ngt_f32_e32 vcc, -1.0, v182
	s_nop 1
	v_cndmask_b32_e32 v152, v253, v152, vcc
	v_cmp_neq_f32_e32 vcc, -1.0, v182
	s_nop 1
	v_cndmask_b32_e32 v152, v244, v152, vcc
	v_cmp_neq_f32_e32 vcc, -1.0, v205
	s_nop 1
	v_cndmask_b32_e32 v153, v244, v153, vcc
	v_cmp_lt_f32_e64 vcc, |v182|, s4
	v_cndmask_b32_e64 v153, v153, v205, s[0:1]
	s_nop 0
	v_cndmask_b32_e32 v152, v152, v182, vcc
	v_pk_add_f32 v[138:139], v[138:139], v[152:153]
	v_max_f32_e32 v152, 0, v140
	v_mul_f32_e64 v140, |v140|, s88
	v_exp_f32_e32 v182, v140
	s_nop 0
	v_add_f32_e32 v140, 1.0, v182
	v_add_f32_e32 v153, -1.0, v140
	v_sub_f32_e32 v154, v153, v140
	v_add_f32_e32 v154, 1.0, v154
	v_sub_f32_e32 v153, v182, v153
	v_add_f32_e32 v153, v153, v154
	v_frexp_mant_f32_e32 v154, v140
	v_cmp_gt_f32_e32 vcc, s2, v154
	v_cvt_f64_f32_e32 v[154:155], v140
	v_frexp_exp_i32_f64_e32 v154, v[154:155]
	v_subbrev_co_u32_e32 v172, vcc, 0, v154, vcc
	v_sub_u32_e32 v154, 0, v172
	v_ldexp_f32 v140, v140, v154
	v_ldexp_f32 v154, v153, v154
	v_max_f32_e32 v153, 0, v141
	v_mul_f32_e64 v141, |v141|, s88
	v_exp_f32_e32 v205, v141
	s_nop 0
	v_add_f32_e32 v141, 1.0, v205
	v_add_f32_e32 v155, -1.0, v141
	v_sub_f32_e32 v156, v155, v141
	v_add_f32_e32 v156, 1.0, v156
	v_sub_f32_e32 v155, v205, v155
	v_add_f32_e32 v155, v155, v156
	v_frexp_mant_f32_e32 v156, v141
	v_cmp_gt_f32_e32 vcc, s2, v156
	v_cvt_f64_f32_e32 v[156:157], v141
	v_frexp_exp_i32_f64_e32 v156, v[156:157]
	v_subbrev_co_u32_e32 v173, vcc, 0, v156, vcc
	v_sub_u32_e32 v156, 0, v173
	v_ldexp_f32 v141, v141, v156
	v_ldexp_f32 v155, v155, v156
	v_pk_add_f32 v[156:157], v[140:141], 1.0 op_sel_hi:[1,0]
	v_pk_add_f32 v[164:165], v[140:141], -1.0 op_sel_hi:[1,0]
	v_pk_add_f32 v[158:159], v[156:157], -1.0 op_sel_hi:[1,0]
	v_pk_add_f32 v[166:167], v[164:165], 1.0 op_sel_hi:[1,0]
	v_pk_add_f32 v[158:159], v[140:141], v[158:159] neg_lo:[0,1] neg_hi:[0,1]
	v_pk_add_f32 v[140:141], v[140:141], v[166:167] neg_lo:[0,1] neg_hi:[0,1]
	v_pk_add_f32 v[158:159], v[154:155], v[158:159]
	v_pk_add_f32 v[140:141], v[154:155], v[140:141]
	v_pk_add_f32 v[160:161], v[156:157], v[158:159]
	v_pk_add_f32 v[154:155], v[164:165], v[140:141]
	v_rcp_f32_e32 v162, v160
	v_rcp_f32_e32 v163, v161
	v_pk_add_f32 v[156:157], v[160:161], v[156:157] neg_lo:[0,1] neg_hi:[0,1]
	v_pk_add_f32 v[164:165], v[154:155], v[164:165] neg_lo:[0,1] neg_hi:[0,1]
	v_pk_add_f32 v[156:157], v[158:159], v[156:157] neg_lo:[0,1] neg_hi:[0,1]
	v_pk_mul_f32 v[158:159], v[154:155], v[162:163]
	v_pk_add_f32 v[140:141], v[140:141], v[164:165] neg_lo:[0,1] neg_hi:[0,1]
	v_pk_mul_f32 v[164:165], v[160:161], v[158:159]
	v_cmp_neq_f32_e32 vcc, s3, v182
	v_pk_fma_f32 v[166:167], v[158:159], v[160:161], v[164:165] neg_lo:[0,0,1] neg_hi:[0,0,1]
	v_cmp_lt_f32_e64 s[0:1], |v205|, s4
	v_pk_fma_f32 v[166:167], v[158:159], v[156:157], v[166:167]
	s_nop 0
	v_pk_add_f32 v[168:169], v[164:165], v[166:167]
	s_nop 0
	v_pk_add_f32 v[170:171], v[154:155], v[168:169] neg_lo:[0,1] neg_hi:[0,1]
	v_pk_add_f32 v[164:165], v[168:169], v[164:165] neg_lo:[0,1] neg_hi:[0,1]
	v_pk_add_f32 v[154:155], v[154:155], v[170:171] neg_lo:[0,1] neg_hi:[0,1]
	s_nop 0
	v_pk_add_f32 v[154:155], v[154:155], v[168:169] neg_lo:[0,1] neg_hi:[0,1]
	s_nop 0
	v_pk_add_f32 v[140:141], v[140:141], v[154:155]
	v_pk_add_f32 v[154:155], v[164:165], v[166:167] neg_lo:[0,1] neg_hi:[0,1]
	s_nop 0
	v_pk_add_f32 v[140:141], v[154:155], v[140:141]
	s_nop 0
	v_pk_add_f32 v[154:155], v[170:171], v[140:141]
	s_nop 0
	v_pk_mul_f32 v[164:165], v[162:163], v[154:155]
	s_nop 0
	v_pk_mul_f32 v[166:167], v[160:161], v[164:165]
	s_nop 0
	v_pk_fma_f32 v[160:161], v[164:165], v[160:161], v[166:167] neg_lo:[0,0,1] neg_hi:[0,0,1]
	s_nop 0
	v_pk_fma_f32 v[156:157], v[164:165], v[156:157], v[160:161]
	v_pk_add_f32 v[160:161], v[170:171], v[154:155] neg_lo:[0,1] neg_hi:[0,1]
	s_nop 0
	v_pk_add_f32 v[140:141], v[140:141], v[160:161]
	v_pk_add_f32 v[160:161], v[166:167], v[156:157]
	s_nop 0
	v_pk_add_f32 v[168:169], v[154:155], v[160:161] neg_lo:[0,1] neg_hi:[0,1]
	v_pk_add_f32 v[166:167], v[160:161], v[166:167] neg_lo:[0,1] neg_hi:[0,1]
	v_pk_add_f32 v[154:155], v[154:155], v[168:169] neg_lo:[0,1] neg_hi:[0,1]
	s_nop 0
	v_pk_add_f32 v[154:155], v[154:155], v[160:161] neg_lo:[0,1] neg_hi:[0,1]
	s_nop 0
	v_pk_add_f32 v[140:141], v[140:141], v[154:155]
	v_pk_add_f32 v[154:155], v[166:167], v[156:157] neg_lo:[0,1] neg_hi:[0,1]
	s_nop 0
	v_pk_add_f32 v[140:141], v[154:155], v[140:141]
	v_pk_add_f32 v[154:155], v[158:159], v[164:165]
	v_pk_add_f32 v[140:141], v[168:169], v[140:141]
	v_pk_add_f32 v[156:157], v[154:155], v[158:159] neg_lo:[0,1] neg_hi:[0,1]
	v_pk_mul_f32 v[140:141], v[162:163], v[140:141]
	v_pk_add_f32 v[156:157], v[164:165], v[156:157] neg_lo:[0,1] neg_hi:[0,1]
	s_nop 0
	v_pk_add_f32 v[140:141], v[156:157], v[140:141]
	s_nop 0
	v_pk_add_f32 v[156:157], v[154:155], v[140:141]
	s_nop 0
	v_pk_mul_f32 v[158:159], v[156:157], v[156:157]
	v_pk_add_f32 v[154:155], v[156:157], v[154:155] neg_lo:[0,1] neg_hi:[0,1]
	v_pk_fma_f32 v[160:161], v[158:159], s[6:7], v[142:143] op_sel_hi:[1,0,0]
	v_pk_add_f32 v[140:141], v[140:141], v[154:155] neg_lo:[0,1] neg_hi:[0,1]
	v_ldexp_f32 v154, v156, 1
; __device__ __forceinline__ float softplusf_(float x) { return fmaxf(x, 0.0f) + log1pf(__expf(-fabsf(x))); }
;     __device__ __forceinline__ void operator()(f32x4 (&acc)[2][2][4][2], const pg8::Unit& u, int wr, int wc, int fr, int fq) const {
;     ...
;             if (wc == 0) { const f32x4 b0 = *(const f32x4*)(dtb + cl0), b1 = *(const f32x4*)(dtb + cl0 + 4);
; #pragma unroll
;                 for (int ai = 0; ai < 2; ++ai)
; #pragma unroll
;                     for (int m = 0; m < 4; ++m) { const int row = row0 + ai * 128 + m * 16; const f32x4 v0 = acc[ai][0][m][0] + b0, v1 = acc[ai][0][m][1] + b1;
;                         float* d = DTA + (size_t)row * NH + cl0;
;                         *(f32x4*)d = (f32x4){softplusf_(v0[0]), softplusf_(v0[1]), softplusf_(v0[2]), softplusf_(v0[3])}; *(f32x4*)(d + 4) = (f32x4){softplusf_(v1[0]), softplusf_(v1[1]), softplusf_(v1[2]), softplusf_(v1[3])}; } }
	v_pk_fma_f32 v[160:161], v[158:159], v[160:161], s[8:9] op_sel_hi:[1,1,0]
	v_ldexp_f32 v155, v157, 1
	v_pk_mul_f32 v[156:157], v[156:157], v[158:159]
	v_cvt_f32_i32_e32 v159, v173
	v_cvt_f32_i32_e32 v158, v172
	v_pk_mul_f32 v[156:157], v[156:157], v[160:161]
	v_ldexp_f32 v163, v141, 1
	v_pk_add_f32 v[160:161], v[154:155], v[156:157]
	v_pk_mul_f32 v[164:165], v[158:159], s[36:37] op_sel_hi:[1,0]
	v_pk_add_f32 v[154:155], v[160:161], v[154:155] neg_lo:[0,1] neg_hi:[0,1]
	v_pk_fma_f32 v[166:167], v[158:159], s[36:37], v[164:165] op_sel_hi:[1,0,1] neg_lo:[0,0,1] neg_hi:[0,0,1]
	v_pk_add_f32 v[154:155], v[156:157], v[154:155] neg_lo:[0,1] neg_hi:[0,1]
	v_pk_fma_f32 v[158:159], v[158:159], s[10:11], v[166:167] op_sel_hi:[1,0,1]
	v_ldexp_f32 v140, v140, 1
	v_mov_b32_e32 v156, v164
	v_mov_b32_e32 v157, v155
	v_mov_b32_e32 v162, v158
	v_mov_b32_e32 v141, v163
	v_pk_add_f32 v[156:157], v[156:157], v[162:163]
	v_pk_add_f32 v[162:163], v[140:141], v[154:155]
	v_mov_b32_e32 v155, v161
	v_mov_b32_e32 v141, v163
	v_pk_add_f32 v[166:167], v[164:165], v[158:159]
	v_pk_add_f32 v[140:141], v[140:141], v[154:155]
	v_pk_add_f32 v[154:155], v[160:161], v[162:163]
	v_mov_b32_e32 v208, v160
	v_pk_add_f32 v[168:169], v[166:167], v[154:155]
	v_mov_b32_e32 v206, v154
	v_mov_b32_e32 v207, v169
	v_mov_b32_e32 v209, v167
	v_pk_add_f32 v[206:207], v[206:207], v[208:209] neg_lo:[0,1] neg_hi:[0,1]
	v_mov_b32_e32 v170, v168
	v_mov_b32_e32 v171, v167
	v_mov_b32_e32 v172, v166
	v_mov_b32_e32 v173, v165
	v_mov_b32_e32 v208, v166
	v_mov_b32_e32 v209, v169
	v_mov_b32_e32 v165, v207
	v_pk_add_f32 v[170:171], v[170:171], v[172:173] neg_lo:[0,1] neg_hi:[0,1]
	v_mov_b32_e32 v172, v154
	v_mov_b32_e32 v173, v159
	v_pk_add_f32 v[164:165], v[208:209], v[164:165] neg_lo:[0,1] neg_hi:[0,1]
	v_pk_add_f32 v[172:173], v[172:173], v[170:171] neg_lo:[0,1] neg_hi:[0,1]
	v_mov_b32_e32 v208, v164
	v_mov_b32_e32 v209, v171
	v_mov_b32_e32 v210, v168
	v_mov_b32_e32 v211, v155
	v_mov_b32_e32 v171, v161
	v_pk_add_f32 v[208:209], v[158:159], v[208:209] neg_lo:[0,1] neg_hi:[0,1]
	v_pk_add_f32 v[170:171], v[210:211], v[170:171] neg_lo:[0,1] neg_hi:[0,1]
	v_mov_b32_e32 v159, v167
	v_pk_add_f32 v[156:157], v[156:157], v[170:171] neg_lo:[0,1] neg_hi:[0,1]
	v_pk_add_f32 v[158:159], v[158:159], v[164:165] neg_lo:[0,1] neg_hi:[0,1]
	v_pk_add_f32 v[140:141], v[140:141], v[206:207] neg_lo:[0,1] neg_hi:[0,1]
	v_pk_add_f32 v[154:155], v[154:155], v[160:161] neg_lo:[0,1] neg_hi:[0,1]
	v_pk_add_f32 v[160:161], v[140:141], v[158:159]
	v_mov_b32_e32 v159, v173
	v_mov_b32_e32 v141, v157
	v_pk_add_f32 v[154:155], v[162:163], v[154:155] neg_lo:[0,1] neg_hi:[0,1]
	v_pk_add_f32 v[162:163], v[172:173], v[156:157]
	v_pk_add_f32 v[140:141], v[158:159], v[140:141]
	v_mov_b32_e32 v156, v160
	v_pk_add_f32 v[140:141], v[140:141], v[208:209] neg_lo:[0,1] neg_hi:[0,1]
	v_mov_b32_e32 v157, v163
	v_pk_add_f32 v[156:157], v[156:157], v[140:141] neg_lo:[0,1] neg_hi:[0,1]
	v_pk_add_f32 v[140:141], v[154:155], v[140:141] neg_lo:[0,1] neg_hi:[0,1]
	v_pk_add_f32 v[156:157], v[158:159], v[156:157] neg_lo:[0,1] neg_hi:[0,1]
	v_pk_add_f32 v[154:155], v[162:163], v[160:161]
	v_pk_add_f32 v[140:141], v[140:141], v[156:157]
	v_pk_add_f32 v[156:157], v[168:169], v[154:155]
	s_nop 0
	v_pk_add_f32 v[158:159], v[156:157], v[168:169] neg_lo:[0,1] neg_hi:[0,1]
	s_nop 0
	v_pk_add_f32 v[154:155], v[154:155], v[158:159] neg_lo:[0,1] neg_hi:[0,1]
	s_nop 0
	v_pk_add_f32 v[140:141], v[140:141], v[154:155]
	s_nop 0
	v_pk_add_f32 v[140:141], v[156:157], v[140:141]
	s_nop 0
	v_cndmask_b32_e32 v140, v252, v140, vcc
	v_cmp_neq_f32_e32 vcc, s3, v205
	s_nop 1
	v_cndmask_b32_e32 v141, v252, v141, vcc
	v_cmp_ngt_f32_e32 vcc, -1.0, v205
	s_nop 1
	v_cndmask_b32_e32 v141, v253, v141, vcc
	v_cmp_ngt_f32_e32 vcc, -1.0, v182
	s_nop 1
	v_cndmask_b32_e32 v140, v253, v140, vcc
	v_cmp_neq_f32_e32 vcc, -1.0, v182
	s_nop 1
	v_cndmask_b32_e32 v140, v244, v140, vcc
	v_cmp_neq_f32_e32 vcc, -1.0, v205
	s_nop 1
	v_cndmask_b32_e32 v141, v244, v141, vcc
	v_cmp_lt_f32_e64 vcc, |v182|, s4
	v_cndmask_b32_e64 v141, v141, v205, s[0:1]
	s_nop 0
	v_cndmask_b32_e32 v140, v140, v182, vcc
	v_pk_add_f32 v[140:141], v[152:153], v[140:141]
	global_store_dwordx4 v[146:147], v[138:141], off
	s_nop 1
	v_mul_f32_e64 v139, |v150|, s88
	v_exp_f32_e32 v182, v139
	v_max_f32_e32 v138, 0, v150
	v_add_f32_e32 v139, 1.0, v182
	v_add_f32_e32 v140, -1.0, v139
	v_sub_f32_e32 v141, v140, v139
	v_add_f32_e32 v141, 1.0, v141
	v_sub_f32_e32 v140, v182, v140
	v_add_f32_e32 v150, v140, v141
	v_frexp_mant_f32_e32 v140, v139
	v_cmp_gt_f32_e32 vcc, s2, v140
	v_cvt_f64_f32_e32 v[140:141], v139
	v_frexp_exp_i32_f64_e32 v140, v[140:141]
	v_subbrev_co_u32_e32 v168, vcc, 0, v140, vcc
	v_sub_u32_e32 v141, 0, v168
	v_ldexp_f32 v140, v139, v141
	v_ldexp_f32 v150, v150, v141
	v_mul_f32_e64 v141, |v151|, s88
	v_exp_f32_e32 v205, v141
	v_max_f32_e32 v139, 0, v151
	v_add_f32_e32 v141, 1.0, v205
	v_add_f32_e32 v151, -1.0, v141
	v_sub_f32_e32 v152, v151, v141
	v_add_f32_e32 v152, 1.0, v152
	v_sub_f32_e32 v151, v205, v151
	v_add_f32_e32 v151, v151, v152
	v_frexp_mant_f32_e32 v152, v141
	v_cmp_gt_f32_e32 vcc, s2, v152
	v_cvt_f64_f32_e32 v[152:153], v141
	v_frexp_exp_i32_f64_e32 v152, v[152:153]
	v_subbrev_co_u32_e32 v169, vcc, 0, v152, vcc
	v_sub_u32_e32 v152, 0, v169
	v_ldexp_f32 v141, v141, v152
	v_ldexp_f32 v151, v151, v152
	v_pk_add_f32 v[152:153], v[140:141], 1.0 op_sel_hi:[1,0]
	v_pk_add_f32 v[160:161], v[140:141], -1.0 op_sel_hi:[1,0]
	v_pk_add_f32 v[154:155], v[152:153], -1.0 op_sel_hi:[1,0]
	v_pk_add_f32 v[162:163], v[160:161], 1.0 op_sel_hi:[1,0]
	v_pk_add_f32 v[154:155], v[140:141], v[154:155] neg_lo:[0,1] neg_hi:[0,1]
; __device__ __forceinline__ float softplusf_(float x) { return fmaxf(x, 0.0f) + log1pf(__expf(-fabsf(x))); }
;     __device__ __forceinline__ void operator()(f32x4 (&acc)[2][2][4][2], const pg8::Unit& u, int wr, int wc, int fr, int fq) const {
;     ...
;             if (wc == 0) { const f32x4 b0 = *(const f32x4*)(dtb + cl0), b1 = *(const f32x4*)(dtb + cl0 + 4);
; #pragma unroll
;                 for (int ai = 0; ai < 2; ++ai)
; #pragma unroll
;                     for (int m = 0; m < 4; ++m) { const int row = row0 + ai * 128 + m * 16; const f32x4 v0 = acc[ai][0][m][0] + b0, v1 = acc[ai][0][m][1] + b1;
;                         float* d = DTA + (size_t)row * NH + cl0;
;                         *(f32x4*)d = (f32x4){softplusf_(v0[0]), softplusf_(v0[1]), softplusf_(v0[2]), softplusf_(v0[3])}; *(f32x4*)(d + 4) = (f32x4){softplusf_(v1[0]), softplusf_(v1[1]), softplusf_(v1[2]), softplusf_(v1[3])}; } }
	v_pk_add_f32 v[140:141], v[140:141], v[162:163] neg_lo:[0,1] neg_hi:[0,1]
	v_pk_add_f32 v[154:155], v[150:151], v[154:155]
	v_pk_add_f32 v[140:141], v[150:151], v[140:141]
	v_pk_add_f32 v[156:157], v[152:153], v[154:155]
	v_pk_add_f32 v[150:151], v[160:161], v[140:141]
	v_rcp_f32_e32 v158, v156
	v_rcp_f32_e32 v159, v157
	v_pk_add_f32 v[152:153], v[156:157], v[152:153] neg_lo:[0,1] neg_hi:[0,1]
	v_pk_add_f32 v[160:161], v[150:151], v[160:161] neg_lo:[0,1] neg_hi:[0,1]
	v_pk_add_f32 v[152:153], v[154:155], v[152:153] neg_lo:[0,1] neg_hi:[0,1]
	v_pk_mul_f32 v[154:155], v[150:151], v[158:159]
	v_pk_add_f32 v[140:141], v[140:141], v[160:161] neg_lo:[0,1] neg_hi:[0,1]
	v_pk_mul_f32 v[160:161], v[156:157], v[154:155]
	v_cmp_neq_f32_e32 vcc, s3, v182
	v_pk_fma_f32 v[162:163], v[154:155], v[156:157], v[160:161] neg_lo:[0,0,1] neg_hi:[0,0,1]
	v_cmp_lt_f32_e64 s[0:1], |v205|, s4
	v_pk_fma_f32 v[162:163], v[154:155], v[152:153], v[162:163]
	s_nop 0
	v_pk_add_f32 v[164:165], v[160:161], v[162:163]
	s_nop 0
	v_pk_add_f32 v[166:167], v[150:151], v[164:165] neg_lo:[0,1] neg_hi:[0,1]
	v_pk_add_f32 v[160:161], v[164:165], v[160:161] neg_lo:[0,1] neg_hi:[0,1]
	v_pk_add_f32 v[150:151], v[150:151], v[166:167] neg_lo:[0,1] neg_hi:[0,1]
	s_nop 0
	v_pk_add_f32 v[150:151], v[150:151], v[164:165] neg_lo:[0,1] neg_hi:[0,1]
	s_nop 0
	v_pk_add_f32 v[140:141], v[140:141], v[150:151]
	v_pk_add_f32 v[150:151], v[160:161], v[162:163] neg_lo:[0,1] neg_hi:[0,1]
	s_nop 0
	v_pk_add_f32 v[140:141], v[150:151], v[140:141]
	s_nop 0
	v_pk_add_f32 v[150:151], v[166:167], v[140:141]
	s_nop 0
	v_pk_mul_f32 v[160:161], v[158:159], v[150:151]
	s_nop 0
	v_pk_mul_f32 v[162:163], v[156:157], v[160:161]
	s_nop 0
	v_pk_fma_f32 v[156:157], v[160:161], v[156:157], v[162:163] neg_lo:[0,0,1] neg_hi:[0,0,1]
	s_nop 0
	v_pk_fma_f32 v[152:153], v[160:161], v[152:153], v[156:157]
	v_pk_add_f32 v[156:157], v[166:167], v[150:151] neg_lo:[0,1] neg_hi:[0,1]
	s_nop 0
	v_pk_add_f32 v[140:141], v[140:141], v[156:157]
	v_pk_add_f32 v[156:157], v[162:163], v[152:153]
	s_nop 0
	v_pk_add_f32 v[164:165], v[150:151], v[156:157] neg_lo:[0,1] neg_hi:[0,1]
	v_pk_add_f32 v[162:163], v[156:157], v[162:163] neg_lo:[0,1] neg_hi:[0,1]
	v_pk_add_f32 v[150:151], v[150:151], v[164:165] neg_lo:[0,1] neg_hi:[0,1]
	s_nop 0
	v_pk_add_f32 v[150:151], v[150:151], v[156:157] neg_lo:[0,1] neg_hi:[0,1]
	s_nop 0
	v_pk_add_f32 v[140:141], v[140:141], v[150:151]
	v_pk_add_f32 v[150:151], v[162:163], v[152:153] neg_lo:[0,1] neg_hi:[0,1]
	s_nop 0
	v_pk_add_f32 v[140:141], v[150:151], v[140:141]
	v_pk_add_f32 v[150:151], v[154:155], v[160:161]
	v_pk_add_f32 v[140:141], v[164:165], v[140:141]
	v_pk_add_f32 v[152:153], v[150:151], v[154:155] neg_lo:[0,1] neg_hi:[0,1]
	v_pk_mul_f32 v[140:141], v[158:159], v[140:141]
	v_pk_add_f32 v[152:153], v[160:161], v[152:153] neg_lo:[0,1] neg_hi:[0,1]
	s_nop 0
	v_pk_add_f32 v[140:141], v[152:153], v[140:141]
	s_nop 0
	v_pk_add_f32 v[152:153], v[150:151], v[140:141]
	s_nop 0
	v_pk_mul_f32 v[154:155], v[152:153], v[152:153]
	v_pk_add_f32 v[150:151], v[152:153], v[150:151] neg_lo:[0,1] neg_hi:[0,1]
	v_pk_fma_f32 v[156:157], v[154:155], s[6:7], v[142:143] op_sel_hi:[1,0,0]
	v_pk_add_f32 v[140:141], v[140:141], v[150:151] neg_lo:[0,1] neg_hi:[0,1]
	v_ldexp_f32 v150, v152, 1
	v_pk_fma_f32 v[156:157], v[154:155], v[156:157], s[8:9] op_sel_hi:[1,1,0]
	v_ldexp_f32 v151, v153, 1
	v_pk_mul_f32 v[152:153], v[152:153], v[154:155]
	v_cvt_f32_i32_e32 v155, v169
	v_cvt_f32_i32_e32 v154, v168
	v_pk_mul_f32 v[152:153], v[152:153], v[156:157]
	v_ldexp_f32 v159, v141, 1
	v_pk_add_f32 v[156:157], v[150:151], v[152:153]
	v_pk_mul_f32 v[160:161], v[154:155], s[36:37] op_sel_hi:[1,0]
	v_pk_add_f32 v[150:151], v[156:157], v[150:151] neg_lo:[0,1] neg_hi:[0,1]
	v_pk_fma_f32 v[162:163], v[154:155], s[36:37], v[160:161] op_sel_hi:[1,0,1] neg_lo:[0,0,1] neg_hi:[0,0,1]
	v_pk_add_f32 v[150:151], v[152:153], v[150:151] neg_lo:[0,1] neg_hi:[0,1]
	v_pk_fma_f32 v[154:155], v[154:155], s[10:11], v[162:163] op_sel_hi:[1,0,1]
	v_ldexp_f32 v140, v140, 1
	v_mov_b32_e32 v152, v160
	v_mov_b32_e32 v153, v151
	v_mov_b32_e32 v158, v154
	v_mov_b32_e32 v141, v159
	v_pk_add_f32 v[152:153], v[152:153], v[158:159]
	v_pk_add_f32 v[158:159], v[140:141], v[150:151]
	v_mov_b32_e32 v151, v157
	v_mov_b32_e32 v141, v159
	v_pk_add_f32 v[162:163], v[160:161], v[154:155]
	v_pk_add_f32 v[140:141], v[140:141], v[150:151]
	v_pk_add_f32 v[150:151], v[156:157], v[158:159]
	v_mov_b32_e32 v172, v156
	v_pk_add_f32 v[164:165], v[162:163], v[150:151]
	v_mov_b32_e32 v170, v150
	v_mov_b32_e32 v171, v165
	v_mov_b32_e32 v173, v163
	v_pk_add_f32 v[170:171], v[170:171], v[172:173] neg_lo:[0,1] neg_hi:[0,1]
	v_mov_b32_e32 v166, v164
	v_mov_b32_e32 v167, v163
	v_mov_b32_e32 v168, v162
	v_mov_b32_e32 v169, v161
	v_mov_b32_e32 v172, v162
	v_mov_b32_e32 v173, v165
	v_mov_b32_e32 v161, v171
	v_pk_add_f32 v[166:167], v[166:167], v[168:169] neg_lo:[0,1] neg_hi:[0,1]
	v_mov_b32_e32 v168, v150
	v_mov_b32_e32 v169, v155
	v_pk_add_f32 v[160:161], v[172:173], v[160:161] neg_lo:[0,1] neg_hi:[0,1]
	v_pk_add_f32 v[168:169], v[168:169], v[166:167] neg_lo:[0,1] neg_hi:[0,1]
	v_mov_b32_e32 v172, v160
	v_mov_b32_e32 v173, v167
	v_mov_b32_e32 v206, v164
	v_mov_b32_e32 v207, v151
	v_mov_b32_e32 v167, v157
	v_pk_add_f32 v[172:173], v[154:155], v[172:173] neg_lo:[0,1] neg_hi:[0,1]
	v_pk_add_f32 v[166:167], v[206:207], v[166:167] neg_lo:[0,1] neg_hi:[0,1]
	v_mov_b32_e32 v155, v163
	v_pk_add_f32 v[152:153], v[152:153], v[166:167] neg_lo:[0,1] neg_hi:[0,1]
	v_pk_add_f32 v[154:155], v[154:155], v[160:161] neg_lo:[0,1] neg_hi:[0,1]
	v_pk_add_f32 v[140:141], v[140:141], v[170:171] neg_lo:[0,1] neg_hi:[0,1]
; __device__ __forceinline__ float softplusf_(float x) { return fmaxf(x, 0.0f) + log1pf(__expf(-fabsf(x))); }
;     __device__ __forceinline__ void operator()(f32x4 (&acc)[2][2][4][2], const pg8::Unit& u, int wr, int wc, int fr, int fq) const {
;     ...
;             if (wc == 0) { const f32x4 b0 = *(const f32x4*)(dtb + cl0), b1 = *(const f32x4*)(dtb + cl0 + 4);
; #pragma unroll
;                 for (int ai = 0; ai < 2; ++ai)
; #pragma unroll
;                     for (int m = 0; m < 4; ++m) { const int row = row0 + ai * 128 + m * 16; const f32x4 v0 = acc[ai][0][m][0] + b0, v1 = acc[ai][0][m][1] + b1;
;                         float* d = DTA + (size_t)row * NH + cl0;
;                         *(f32x4*)d = (f32x4){softplusf_(v0[0]), softplusf_(v0[1]), softplusf_(v0[2]), softplusf_(v0[3])}; *(f32x4*)(d + 4) = (f32x4){softplusf_(v1[0]), softplusf_(v1[1]), softplusf_(v1[2]), softplusf_(v1[3])}; } }
	v_pk_add_f32 v[150:151], v[150:151], v[156:157] neg_lo:[0,1] neg_hi:[0,1]
	v_pk_add_f32 v[156:157], v[140:141], v[154:155]
	v_mov_b32_e32 v155, v169
	v_mov_b32_e32 v141, v153
	v_pk_add_f32 v[150:151], v[158:159], v[150:151] neg_lo:[0,1] neg_hi:[0,1]
	v_pk_add_f32 v[158:159], v[168:169], v[152:153]
	v_pk_add_f32 v[140:141], v[154:155], v[140:141]
	v_mov_b32_e32 v152, v156
	v_pk_add_f32 v[140:141], v[140:141], v[172:173] neg_lo:[0,1] neg_hi:[0,1]
	v_mov_b32_e32 v153, v159
	v_pk_add_f32 v[152:153], v[152:153], v[140:141] neg_lo:[0,1] neg_hi:[0,1]
	v_pk_add_f32 v[140:141], v[150:151], v[140:141] neg_lo:[0,1] neg_hi:[0,1]
	v_pk_add_f32 v[152:153], v[154:155], v[152:153] neg_lo:[0,1] neg_hi:[0,1]
	v_pk_add_f32 v[150:151], v[158:159], v[156:157]
	v_pk_add_f32 v[140:141], v[140:141], v[152:153]
	v_pk_add_f32 v[152:153], v[164:165], v[150:151]
	s_nop 0
	v_pk_add_f32 v[154:155], v[152:153], v[164:165] neg_lo:[0,1] neg_hi:[0,1]
	s_nop 0
	v_pk_add_f32 v[150:151], v[150:151], v[154:155] neg_lo:[0,1] neg_hi:[0,1]
	s_nop 0
	v_pk_add_f32 v[140:141], v[140:141], v[150:151]
	s_nop 0
	v_pk_add_f32 v[140:141], v[152:153], v[140:141]
	s_nop 0
	v_cndmask_b32_e32 v140, v252, v140, vcc
	v_cmp_neq_f32_e32 vcc, s3, v205
	s_nop 1
	v_cndmask_b32_e32 v141, v252, v141, vcc
	v_cmp_ngt_f32_e32 vcc, -1.0, v205
	s_nop 1
	v_cndmask_b32_e32 v141, v253, v141, vcc
	v_cmp_ngt_f32_e32 vcc, -1.0, v182
	s_nop 1
	v_cndmask_b32_e32 v140, v253, v140, vcc
	v_cmp_neq_f32_e32 vcc, -1.0, v182
	s_nop 1
	v_cndmask_b32_e32 v140, v244, v140, vcc
	v_cmp_neq_f32_e32 vcc, -1.0, v205
	s_nop 1
	v_cndmask_b32_e32 v141, v244, v141, vcc
	v_cmp_lt_f32_e64 vcc, |v182|, s4
	v_cndmask_b32_e64 v141, v141, v205, s[0:1]
	s_nop 0
	v_cndmask_b32_e32 v140, v140, v182, vcc
	v_pk_add_f32 v[138:139], v[138:139], v[140:141]
	v_mul_f32_e64 v141, |v148|, s88
	v_exp_f32_e32 v182, v141
	v_max_f32_e32 v140, 0, v148
	v_add_f32_e32 v141, 1.0, v182
	v_add_f32_e32 v148, -1.0, v141
	v_sub_f32_e32 v150, v148, v141
	v_add_f32_e32 v150, 1.0, v150
	v_sub_f32_e32 v148, v182, v148
	v_add_f32_e32 v152, v148, v150
	v_frexp_mant_f32_e32 v148, v141
	v_cvt_f64_f32_e32 v[150:151], v141
	v_cmp_gt_f32_e32 vcc, s2, v148
	v_frexp_exp_i32_f64_e32 v148, v[150:151]
	s_nop 0
	v_subbrev_co_u32_e32 v168, vcc, 0, v148, vcc
	v_sub_u32_e32 v150, 0, v168
	v_ldexp_f32 v148, v141, v150
	v_max_f32_e32 v141, 0, v149
	v_mul_f32_e64 v149, |v149|, s88
	v_exp_f32_e32 v205, v149
	v_ldexp_f32 v150, v152, v150
	v_add_f32_e32 v149, 1.0, v205
	v_add_f32_e32 v151, -1.0, v149
	v_sub_f32_e32 v152, v151, v149
	v_add_f32_e32 v152, 1.0, v152
	v_sub_f32_e32 v151, v205, v151
	v_add_f32_e32 v151, v151, v152
	v_frexp_mant_f32_e32 v152, v149
	v_cmp_gt_f32_e32 vcc, s2, v152
	v_cvt_f64_f32_e32 v[152:153], v149
	v_frexp_exp_i32_f64_e32 v152, v[152:153]
	v_subbrev_co_u32_e32 v169, vcc, 0, v152, vcc
	v_sub_u32_e32 v152, 0, v169
	v_ldexp_f32 v149, v149, v152
	v_ldexp_f32 v151, v151, v152
	v_pk_add_f32 v[152:153], v[148:149], 1.0 op_sel_hi:[1,0]
	v_pk_add_f32 v[160:161], v[148:149], -1.0 op_sel_hi:[1,0]
	v_pk_add_f32 v[154:155], v[152:153], -1.0 op_sel_hi:[1,0]
	v_pk_add_f32 v[162:163], v[160:161], 1.0 op_sel_hi:[1,0]
	v_pk_add_f32 v[154:155], v[148:149], v[154:155] neg_lo:[0,1] neg_hi:[0,1]
	v_pk_add_f32 v[148:149], v[148:149], v[162:163] neg_lo:[0,1] neg_hi:[0,1]
	v_pk_add_f32 v[154:155], v[150:151], v[154:155]
	v_pk_add_f32 v[148:149], v[150:151], v[148:149]
	v_pk_add_f32 v[156:157], v[152:153], v[154:155]
	v_pk_add_f32 v[150:151], v[160:161], v[148:149]
	v_rcp_f32_e32 v158, v156
	v_rcp_f32_e32 v159, v157
	v_pk_add_f32 v[152:153], v[156:157], v[152:153] neg_lo:[0,1] neg_hi:[0,1]
	v_pk_add_f32 v[160:161], v[150:151], v[160:161] neg_lo:[0,1] neg_hi:[0,1]
	v_pk_add_f32 v[152:153], v[154:155], v[152:153] neg_lo:[0,1] neg_hi:[0,1]
	v_pk_mul_f32 v[154:155], v[150:151], v[158:159]
	v_pk_add_f32 v[148:149], v[148:149], v[160:161] neg_lo:[0,1] neg_hi:[0,1]
	v_pk_mul_f32 v[160:161], v[156:157], v[154:155]
	v_cmp_neq_f32_e32 vcc, s3, v182
	v_pk_fma_f32 v[162:163], v[154:155], v[156:157], v[160:161] neg_lo:[0,0,1] neg_hi:[0,0,1]
	v_cmp_lt_f32_e64 s[0:1], |v205|, s4
	v_pk_fma_f32 v[162:163], v[154:155], v[152:153], v[162:163]
	s_nop 0
	v_pk_add_f32 v[164:165], v[160:161], v[162:163]
	s_nop 0
	v_pk_add_f32 v[166:167], v[150:151], v[164:165] neg_lo:[0,1] neg_hi:[0,1]
	v_pk_add_f32 v[160:161], v[164:165], v[160:161] neg_lo:[0,1] neg_hi:[0,1]
	v_pk_add_f32 v[150:151], v[150:151], v[166:167] neg_lo:[0,1] neg_hi:[0,1]
	s_nop 0
	v_pk_add_f32 v[150:151], v[150:151], v[164:165] neg_lo:[0,1] neg_hi:[0,1]
	s_nop 0
	v_pk_add_f32 v[148:149], v[148:149], v[150:151]
	v_pk_add_f32 v[150:151], v[160:161], v[162:163] neg_lo:[0,1] neg_hi:[0,1]
	s_nop 0
	v_pk_add_f32 v[148:149], v[150:151], v[148:149]
	s_nop 0
	v_pk_add_f32 v[150:151], v[166:167], v[148:149]
	s_nop 0
	v_pk_mul_f32 v[160:161], v[158:159], v[150:151]
	s_nop 0
	v_pk_mul_f32 v[162:163], v[156:157], v[160:161]
	s_nop 0
	v_pk_fma_f32 v[156:157], v[160:161], v[156:157], v[162:163] neg_lo:[0,0,1] neg_hi:[0,0,1]
	s_nop 0
	v_pk_fma_f32 v[152:153], v[160:161], v[152:153], v[156:157]
	v_pk_add_f32 v[156:157], v[166:167], v[150:151] neg_lo:[0,1] neg_hi:[0,1]
	s_nop 0
	v_pk_add_f32 v[148:149], v[148:149], v[156:157]
	v_pk_add_f32 v[156:157], v[162:163], v[152:153]
	s_nop 0
	v_pk_add_f32 v[164:165], v[150:151], v[156:157] neg_lo:[0,1] neg_hi:[0,1]
	v_pk_add_f32 v[162:163], v[156:157], v[162:163] neg_lo:[0,1] neg_hi:[0,1]
	v_pk_add_f32 v[150:151], v[150:151], v[164:165] neg_lo:[0,1] neg_hi:[0,1]
	s_nop 0
	v_pk_add_f32 v[150:151], v[150:151], v[156:157] neg_lo:[0,1] neg_hi:[0,1]
	s_nop 0
	v_pk_add_f32 v[148:149], v[148:149], v[150:151]
; __device__ __forceinline__ float softplusf_(float x) { return fmaxf(x, 0.0f) + log1pf(__expf(-fabsf(x))); }
;     __device__ __forceinline__ void operator()(f32x4 (&acc)[2][2][4][2], const pg8::Unit& u, int wr, int wc, int fr, int fq) const {
;     ...
;             if (wc == 0) { const f32x4 b0 = *(const f32x4*)(dtb + cl0), b1 = *(const f32x4*)(dtb + cl0 + 4);
; #pragma unroll
;                 for (int ai = 0; ai < 2; ++ai)
; #pragma unroll
;                     for (int m = 0; m < 4; ++m) { const int row = row0 + ai * 128 + m * 16; const f32x4 v0 = acc[ai][0][m][0] + b0, v1 = acc[ai][0][m][1] + b1;
;                         float* d = DTA + (size_t)row * NH + cl0;
;                         *(f32x4*)d = (f32x4){softplusf_(v0[0]), softplusf_(v0[1]), softplusf_(v0[2]), softplusf_(v0[3])}; *(f32x4*)(d + 4) = (f32x4){softplusf_(v1[0]), softplusf_(v1[1]), softplusf_(v1[2]), softplusf_(v1[3])}; } }
	v_pk_add_f32 v[150:151], v[162:163], v[152:153] neg_lo:[0,1] neg_hi:[0,1]
	s_nop 0
	v_pk_add_f32 v[148:149], v[150:151], v[148:149]
	v_pk_add_f32 v[150:151], v[154:155], v[160:161]
	v_pk_add_f32 v[148:149], v[164:165], v[148:149]
	v_pk_add_f32 v[152:153], v[150:151], v[154:155] neg_lo:[0,1] neg_hi:[0,1]
	v_pk_mul_f32 v[148:149], v[158:159], v[148:149]
	v_pk_add_f32 v[152:153], v[160:161], v[152:153] neg_lo:[0,1] neg_hi:[0,1]
	s_nop 0
	v_pk_add_f32 v[148:149], v[152:153], v[148:149]
	s_nop 0
	v_pk_add_f32 v[152:153], v[150:151], v[148:149]
	s_nop 0
	v_pk_mul_f32 v[154:155], v[152:153], v[152:153]
	v_pk_add_f32 v[150:151], v[152:153], v[150:151] neg_lo:[0,1] neg_hi:[0,1]
	v_pk_fma_f32 v[156:157], v[154:155], s[6:7], v[142:143] op_sel_hi:[1,0,0]
	v_pk_add_f32 v[148:149], v[148:149], v[150:151] neg_lo:[0,1] neg_hi:[0,1]
	v_ldexp_f32 v150, v152, 1
	v_pk_fma_f32 v[156:157], v[154:155], v[156:157], s[8:9] op_sel_hi:[1,1,0]
	v_ldexp_f32 v151, v153, 1
	v_pk_mul_f32 v[152:153], v[152:153], v[154:155]
	v_cvt_f32_i32_e32 v155, v169
	v_cvt_f32_i32_e32 v154, v168
	v_pk_mul_f32 v[152:153], v[152:153], v[156:157]
	v_ldexp_f32 v159, v149, 1
	v_pk_add_f32 v[156:157], v[150:151], v[152:153]
	v_pk_mul_f32 v[160:161], v[154:155], s[36:37] op_sel_hi:[1,0]
	v_pk_add_f32 v[150:151], v[156:157], v[150:151] neg_lo:[0,1] neg_hi:[0,1]
	v_pk_fma_f32 v[162:163], v[154:155], s[36:37], v[160:161] op_sel_hi:[1,0,1] neg_lo:[0,0,1] neg_hi:[0,0,1]
	v_pk_add_f32 v[150:151], v[152:153], v[150:151] neg_lo:[0,1] neg_hi:[0,1]
	v_pk_fma_f32 v[154:155], v[154:155], s[10:11], v[162:163] op_sel_hi:[1,0,1]
	v_ldexp_f32 v148, v148, 1
	v_mov_b32_e32 v152, v160
	v_mov_b32_e32 v153, v151
	v_mov_b32_e32 v158, v154
	v_mov_b32_e32 v149, v159
	v_pk_add_f32 v[152:153], v[152:153], v[158:159]
	v_pk_add_f32 v[158:159], v[148:149], v[150:151]
	v_mov_b32_e32 v151, v157
	v_mov_b32_e32 v149, v159
	v_pk_add_f32 v[162:163], v[160:161], v[154:155]
	v_pk_add_f32 v[148:149], v[148:149], v[150:151]
	v_pk_add_f32 v[150:151], v[156:157], v[158:159]
	v_mov_b32_e32 v172, v156
	v_pk_add_f32 v[164:165], v[162:163], v[150:151]
	v_mov_b32_e32 v170, v150
	v_mov_b32_e32 v171, v165
	v_mov_b32_e32 v173, v163
	v_pk_add_f32 v[170:171], v[170:171], v[172:173] neg_lo:[0,1] neg_hi:[0,1]
	v_mov_b32_e32 v166, v164
	v_mov_b32_e32 v167, v163
	v_mov_b32_e32 v168, v162
	v_mov_b32_e32 v169, v161
	v_mov_b32_e32 v172, v162
	v_mov_b32_e32 v173, v165
	v_mov_b32_e32 v161, v171
	v_pk_add_f32 v[166:167], v[166:167], v[168:169] neg_lo:[0,1] neg_hi:[0,1]
	v_mov_b32_e32 v168, v150
	v_mov_b32_e32 v169, v155
	v_pk_add_f32 v[160:161], v[172:173], v[160:161] neg_lo:[0,1] neg_hi:[0,1]
	v_pk_add_f32 v[168:169], v[168:169], v[166:167] neg_lo:[0,1] neg_hi:[0,1]
	v_mov_b32_e32 v172, v160
	v_mov_b32_e32 v173, v167
	v_mov_b32_e32 v206, v164
	v_mov_b32_e32 v207, v151
	v_mov_b32_e32 v167, v157
	v_pk_add_f32 v[172:173], v[154:155], v[172:173] neg_lo:[0,1] neg_hi:[0,1]
	v_pk_add_f32 v[166:167], v[206:207], v[166:167] neg_lo:[0,1] neg_hi:[0,1]
	v_mov_b32_e32 v155, v163
	v_pk_add_f32 v[152:153], v[152:153], v[166:167] neg_lo:[0,1] neg_hi:[0,1]
	v_pk_add_f32 v[154:155], v[154:155], v[160:161] neg_lo:[0,1] neg_hi:[0,1]
	v_pk_add_f32 v[148:149], v[148:149], v[170:171] neg_lo:[0,1] neg_hi:[0,1]
	v_pk_add_f32 v[150:151], v[150:151], v[156:157] neg_lo:[0,1] neg_hi:[0,1]
	v_pk_add_f32 v[156:157], v[148:149], v[154:155]
	v_mov_b32_e32 v155, v169
	v_mov_b32_e32 v149, v153
	v_pk_add_f32 v[150:151], v[158:159], v[150:151] neg_lo:[0,1] neg_hi:[0,1]
	v_pk_add_f32 v[158:159], v[168:169], v[152:153]
	v_pk_add_f32 v[148:149], v[154:155], v[148:149]
	v_mov_b32_e32 v152, v156
	v_pk_add_f32 v[148:149], v[148:149], v[172:173] neg_lo:[0,1] neg_hi:[0,1]
	v_mov_b32_e32 v153, v159
	v_pk_add_f32 v[152:153], v[152:153], v[148:149] neg_lo:[0,1] neg_hi:[0,1]
	v_pk_add_f32 v[148:149], v[150:151], v[148:149] neg_lo:[0,1] neg_hi:[0,1]
	v_pk_add_f32 v[152:153], v[154:155], v[152:153] neg_lo:[0,1] neg_hi:[0,1]
	v_pk_add_f32 v[150:151], v[158:159], v[156:157]
	v_pk_add_f32 v[148:149], v[148:149], v[152:153]
	v_pk_add_f32 v[152:153], v[164:165], v[150:151]
	s_nop 0
	v_pk_add_f32 v[154:155], v[152:153], v[164:165] neg_lo:[0,1] neg_hi:[0,1]
	s_nop 0
	v_pk_add_f32 v[150:151], v[150:151], v[154:155] neg_lo:[0,1] neg_hi:[0,1]
	s_nop 0
	v_pk_add_f32 v[148:149], v[148:149], v[150:151]
	v_pk_add_f32 v[150:151], v[90:91], v[130:131]
	v_pk_add_f32 v[148:149], v[152:153], v[148:149]
	v_pk_add_f32 v[152:153], v[94:95], v[134:135]
	v_cndmask_b32_e32 v148, v252, v148, vcc
	v_cmp_neq_f32_e32 vcc, s3, v205
	s_nop 1
	v_cndmask_b32_e32 v149, v252, v149, vcc
	v_cmp_ngt_f32_e32 vcc, -1.0, v205
	s_nop 1
	v_cndmask_b32_e32 v149, v253, v149, vcc
	v_cmp_ngt_f32_e32 vcc, -1.0, v182
	s_nop 1
	v_cndmask_b32_e32 v148, v253, v148, vcc
	v_cmp_neq_f32_e32 vcc, -1.0, v182
	s_nop 1
	v_cndmask_b32_e32 v148, v244, v148, vcc
	v_cmp_neq_f32_e32 vcc, -1.0, v205
	s_nop 1
	v_cndmask_b32_e32 v149, v244, v149, vcc
	v_cmp_lt_f32_e64 vcc, |v182|, s4
	v_cndmask_b32_e64 v149, v149, v205, s[0:1]
	s_nop 0
	v_cndmask_b32_e32 v148, v148, v182, vcc
	v_pk_add_f32 v[140:141], v[140:141], v[148:149]
	global_store_dwordx4 v[146:147], v[138:141], off offset:16
	v_pk_add_f32 v[148:149], v[92:93], v[132:133]
	s_nop 0
	v_lshlrev_b64 v[138:139], 7, v[198:199]
	v_lshl_add_u64 v[146:147], v[144:145], 0, v[138:139]
	v_mul_f32_e64 v139, |v152|, s88
	v_exp_f32_e32 v182, v139
	v_max_f32_e32 v138, 0, v152
	v_pk_add_f32 v[140:141], v[96:97], v[136:137]
	v_add_f32_e32 v139, 1.0, v182
	v_add_f32_e32 v152, -1.0, v139
	v_sub_f32_e32 v154, v152, v139
	v_add_f32_e32 v154, 1.0, v154
	v_sub_f32_e32 v152, v182, v152
	v_add_f32_e32 v156, v152, v154
; __device__ __forceinline__ float softplusf_(float x) { return fmaxf(x, 0.0f) + log1pf(__expf(-fabsf(x))); }
;     __device__ __forceinline__ void operator()(f32x4 (&acc)[2][2][4][2], const pg8::Unit& u, int wr, int wc, int fr, int fq) const {
;     ...
;                     for (int m = 0; m < 4; ++m) { const int row = row0 + ai * 128 + m * 16; const f32x4 v0 = acc[ai][0][m][0] + b0, v1 = acc[ai][0][m][1] + b1;
;                         float* d = DTA + (size_t)row * NH + cl0;
;                         *(f32x4*)d = (f32x4){softplusf_(v0[0]), softplusf_(v0[1]), softplusf_(v0[2]), softplusf_(v0[3])}; *(f32x4*)(d + 4) = (f32x4){softplusf_(v1[0]), softplusf_(v1[1]), softplusf_(v1[2]), softplusf_(v1[3])}; } }
	v_frexp_mant_f32_e32 v152, v139
	v_cvt_f64_f32_e32 v[154:155], v139
	v_cmp_gt_f32_e32 vcc, s2, v152
	v_frexp_exp_i32_f64_e32 v152, v[154:155]
	s_nop 0
	v_subbrev_co_u32_e32 v172, vcc, 0, v152, vcc
	v_sub_u32_e32 v154, 0, v172
	v_ldexp_f32 v152, v139, v154
	v_max_f32_e32 v139, 0, v153
	v_mul_f32_e64 v153, |v153|, s88
	v_exp_f32_e32 v205, v153
	v_ldexp_f32 v154, v156, v154
	v_add_f32_e32 v153, 1.0, v205
	v_add_f32_e32 v155, -1.0, v153
	v_sub_f32_e32 v156, v155, v153
	v_add_f32_e32 v156, 1.0, v156
	v_sub_f32_e32 v155, v205, v155
	v_add_f32_e32 v155, v155, v156
	v_frexp_mant_f32_e32 v156, v153
	v_cmp_gt_f32_e32 vcc, s2, v156
	v_cvt_f64_f32_e32 v[156:157], v153
	v_frexp_exp_i32_f64_e32 v156, v[156:157]
	v_subbrev_co_u32_e32 v173, vcc, 0, v156, vcc
	v_sub_u32_e32 v156, 0, v173
	v_ldexp_f32 v153, v153, v156
	v_ldexp_f32 v155, v155, v156
	v_pk_add_f32 v[156:157], v[152:153], 1.0 op_sel_hi:[1,0]
	v_pk_add_f32 v[164:165], v[152:153], -1.0 op_sel_hi:[1,0]
	v_pk_add_f32 v[158:159], v[156:157], -1.0 op_sel_hi:[1,0]
	v_pk_add_f32 v[166:167], v[164:165], 1.0 op_sel_hi:[1,0]
	v_pk_add_f32 v[158:159], v[152:153], v[158:159] neg_lo:[0,1] neg_hi:[0,1]
	v_pk_add_f32 v[152:153], v[152:153], v[166:167] neg_lo:[0,1] neg_hi:[0,1]
	v_pk_add_f32 v[158:159], v[154:155], v[158:159]
	v_pk_add_f32 v[152:153], v[154:155], v[152:153]
	v_pk_add_f32 v[160:161], v[156:157], v[158:159]
	v_pk_add_f32 v[154:155], v[164:165], v[152:153]
	v_rcp_f32_e32 v162, v160
	v_rcp_f32_e32 v163, v161
	v_pk_add_f32 v[156:157], v[160:161], v[156:157] neg_lo:[0,1] neg_hi:[0,1]
	v_pk_add_f32 v[164:165], v[154:155], v[164:165] neg_lo:[0,1] neg_hi:[0,1]
	v_pk_add_f32 v[156:157], v[158:159], v[156:157] neg_lo:[0,1] neg_hi:[0,1]
	v_pk_mul_f32 v[158:159], v[154:155], v[162:163]
	v_pk_add_f32 v[152:153], v[152:153], v[164:165] neg_lo:[0,1] neg_hi:[0,1]
	v_pk_mul_f32 v[164:165], v[160:161], v[158:159]
	v_cmp_neq_f32_e32 vcc, s3, v182
	v_pk_fma_f32 v[166:167], v[158:159], v[160:161], v[164:165] neg_lo:[0,0,1] neg_hi:[0,0,1]
	v_cmp_lt_f32_e64 s[0:1], |v205|, s4
	v_pk_fma_f32 v[166:167], v[158:159], v[156:157], v[166:167]
	s_nop 0
	v_pk_add_f32 v[168:169], v[164:165], v[166:167]
	s_nop 0
	v_pk_add_f32 v[170:171], v[154:155], v[168:169] neg_lo:[0,1] neg_hi:[0,1]
	v_pk_add_f32 v[164:165], v[168:169], v[164:165] neg_lo:[0,1] neg_hi:[0,1]
	v_pk_add_f32 v[154:155], v[154:155], v[170:171] neg_lo:[0,1] neg_hi:[0,1]
	s_nop 0
	v_pk_add_f32 v[154:155], v[154:155], v[168:169] neg_lo:[0,1] neg_hi:[0,1]
	s_nop 0
	v_pk_add_f32 v[152:153], v[152:153], v[154:155]
	v_pk_add_f32 v[154:155], v[164:165], v[166:167] neg_lo:[0,1] neg_hi:[0,1]
	s_nop 0
	v_pk_add_f32 v[152:153], v[154:155], v[152:153]
	s_nop 0
	v_pk_add_f32 v[154:155], v[170:171], v[152:153]
	s_nop 0
	v_pk_mul_f32 v[164:165], v[162:163], v[154:155]
	s_nop 0
	v_pk_mul_f32 v[166:167], v[160:161], v[164:165]
	s_nop 0
	v_pk_fma_f32 v[160:161], v[164:165], v[160:161], v[166:167] neg_lo:[0,0,1] neg_hi:[0,0,1]
	s_nop 0
	v_pk_fma_f32 v[156:157], v[164:165], v[156:157], v[160:161]
	v_pk_add_f32 v[160:161], v[170:171], v[154:155] neg_lo:[0,1] neg_hi:[0,1]
	s_nop 0
	v_pk_add_f32 v[152:153], v[152:153], v[160:161]
	v_pk_add_f32 v[160:161], v[166:167], v[156:157]
	s_nop 0
	v_pk_add_f32 v[168:169], v[154:155], v[160:161] neg_lo:[0,1] neg_hi:[0,1]
	v_pk_add_f32 v[166:167], v[160:161], v[166:167] neg_lo:[0,1] neg_hi:[0,1]
	v_pk_add_f32 v[154:155], v[154:155], v[168:169] neg_lo:[0,1] neg_hi:[0,1]
	s_nop 0
	v_pk_add_f32 v[154:155], v[154:155], v[160:161] neg_lo:[0,1] neg_hi:[0,1]
	s_nop 0
	v_pk_add_f32 v[152:153], v[152:153], v[154:155]
	v_pk_add_f32 v[154:155], v[166:167], v[156:157] neg_lo:[0,1] neg_hi:[0,1]
	s_nop 0
	v_pk_add_f32 v[152:153], v[154:155], v[152:153]
	v_pk_add_f32 v[154:155], v[158:159], v[164:165]
	v_pk_add_f32 v[152:153], v[168:169], v[152:153]
	v_pk_add_f32 v[156:157], v[154:155], v[158:159] neg_lo:[0,1] neg_hi:[0,1]
	v_pk_mul_f32 v[152:153], v[162:163], v[152:153]
	v_pk_add_f32 v[156:157], v[164:165], v[156:157] neg_lo:[0,1] neg_hi:[0,1]
	s_nop 0
	v_pk_add_f32 v[152:153], v[156:157], v[152:153]
	s_nop 0
	v_pk_add_f32 v[156:157], v[154:155], v[152:153]
	s_nop 0
	v_pk_mul_f32 v[158:159], v[156:157], v[156:157]
	v_pk_add_f32 v[154:155], v[156:157], v[154:155] neg_lo:[0,1] neg_hi:[0,1]
	v_pk_fma_f32 v[160:161], v[158:159], s[6:7], v[142:143] op_sel_hi:[1,0,0]
	v_pk_add_f32 v[152:153], v[152:153], v[154:155] neg_lo:[0,1] neg_hi:[0,1]
	v_ldexp_f32 v154, v156, 1
	v_pk_fma_f32 v[160:161], v[158:159], v[160:161], s[8:9] op_sel_hi:[1,1,0]
	v_ldexp_f32 v155, v157, 1
	v_pk_mul_f32 v[156:157], v[156:157], v[158:159]
	v_cvt_f32_i32_e32 v159, v173
	v_cvt_f32_i32_e32 v158, v172
	v_pk_mul_f32 v[156:157], v[156:157], v[160:161]
	v_ldexp_f32 v163, v153, 1
	v_pk_add_f32 v[160:161], v[154:155], v[156:157]
	v_pk_mul_f32 v[164:165], v[158:159], s[36:37] op_sel_hi:[1,0]
	v_pk_add_f32 v[154:155], v[160:161], v[154:155] neg_lo:[0,1] neg_hi:[0,1]
	v_pk_fma_f32 v[166:167], v[158:159], s[36:37], v[164:165] op_sel_hi:[1,0,1] neg_lo:[0,0,1] neg_hi:[0,0,1]
	v_pk_add_f32 v[154:155], v[156:157], v[154:155] neg_lo:[0,1] neg_hi:[0,1]
	v_pk_fma_f32 v[158:159], v[158:159], s[10:11], v[166:167] op_sel_hi:[1,0,1]
	v_ldexp_f32 v152, v152, 1
	v_mov_b32_e32 v156, v164
	v_mov_b32_e32 v157, v155
	v_mov_b32_e32 v162, v158
	v_mov_b32_e32 v153, v163
	v_pk_add_f32 v[156:157], v[156:157], v[162:163]
	v_pk_add_f32 v[162:163], v[152:153], v[154:155]
	v_mov_b32_e32 v155, v161
	v_mov_b32_e32 v153, v163
	v_pk_add_f32 v[166:167], v[164:165], v[158:159]
	v_pk_add_f32 v[152:153], v[152:153], v[154:155]
	v_pk_add_f32 v[154:155], v[160:161], v[162:163]
	v_mov_b32_e32 v208, v160
	v_pk_add_f32 v[168:169], v[166:167], v[154:155]
; __device__ __forceinline__ float softplusf_(float x) { return fmaxf(x, 0.0f) + log1pf(__expf(-fabsf(x))); }
;     __device__ __forceinline__ void operator()(f32x4 (&acc)[2][2][4][2], const pg8::Unit& u, int wr, int wc, int fr, int fq) const {
;     ...
;                     for (int m = 0; m < 4; ++m) { const int row = row0 + ai * 128 + m * 16; const f32x4 v0 = acc[ai][0][m][0] + b0, v1 = acc[ai][0][m][1] + b1;
;                         float* d = DTA + (size_t)row * NH + cl0;
;                         *(f32x4*)d = (f32x4){softplusf_(v0[0]), softplusf_(v0[1]), softplusf_(v0[2]), softplusf_(v0[3])}; *(f32x4*)(d + 4) = (f32x4){softplusf_(v1[0]), softplusf_(v1[1]), softplusf_(v1[2]), softplusf_(v1[3])}; } }
	v_mov_b32_e32 v206, v154
	v_mov_b32_e32 v207, v169
	v_mov_b32_e32 v209, v167
	v_pk_add_f32 v[206:207], v[206:207], v[208:209] neg_lo:[0,1] neg_hi:[0,1]
	v_mov_b32_e32 v170, v168
	v_mov_b32_e32 v171, v167
	v_mov_b32_e32 v172, v166
	v_mov_b32_e32 v173, v165
	v_mov_b32_e32 v208, v166
	v_mov_b32_e32 v209, v169
	v_mov_b32_e32 v165, v207
	v_pk_add_f32 v[170:171], v[170:171], v[172:173] neg_lo:[0,1] neg_hi:[0,1]
	v_mov_b32_e32 v172, v154
	v_mov_b32_e32 v173, v159
	v_pk_add_f32 v[164:165], v[208:209], v[164:165] neg_lo:[0,1] neg_hi:[0,1]
	v_pk_add_f32 v[172:173], v[172:173], v[170:171] neg_lo:[0,1] neg_hi:[0,1]
	v_mov_b32_e32 v208, v164
	v_mov_b32_e32 v209, v171
	v_mov_b32_e32 v210, v168
	v_mov_b32_e32 v211, v155
	v_mov_b32_e32 v171, v161
	v_pk_add_f32 v[208:209], v[158:159], v[208:209] neg_lo:[0,1] neg_hi:[0,1]
	v_pk_add_f32 v[170:171], v[210:211], v[170:171] neg_lo:[0,1] neg_hi:[0,1]
	v_mov_b32_e32 v159, v167
	v_pk_add_f32 v[156:157], v[156:157], v[170:171] neg_lo:[0,1] neg_hi:[0,1]
	v_pk_add_f32 v[158:159], v[158:159], v[164:165] neg_lo:[0,1] neg_hi:[0,1]
	v_pk_add_f32 v[152:153], v[152:153], v[206:207] neg_lo:[0,1] neg_hi:[0,1]
	v_pk_add_f32 v[154:155], v[154:155], v[160:161] neg_lo:[0,1] neg_hi:[0,1]
	v_pk_add_f32 v[160:161], v[152:153], v[158:159]
	v_mov_b32_e32 v159, v173
	v_mov_b32_e32 v153, v157
	v_pk_add_f32 v[154:155], v[162:163], v[154:155] neg_lo:[0,1] neg_hi:[0,1]
	v_pk_add_f32 v[162:163], v[172:173], v[156:157]
	v_pk_add_f32 v[152:153], v[158:159], v[152:153]
	v_mov_b32_e32 v156, v160
	v_pk_add_f32 v[152:153], v[152:153], v[208:209] neg_lo:[0,1] neg_hi:[0,1]
	v_mov_b32_e32 v157, v163
	v_pk_add_f32 v[156:157], v[156:157], v[152:153] neg_lo:[0,1] neg_hi:[0,1]
	v_pk_add_f32 v[152:153], v[154:155], v[152:153] neg_lo:[0,1] neg_hi:[0,1]
	v_pk_add_f32 v[156:157], v[158:159], v[156:157] neg_lo:[0,1] neg_hi:[0,1]
	v_pk_add_f32 v[154:155], v[162:163], v[160:161]
	v_pk_add_f32 v[152:153], v[152:153], v[156:157]
	v_pk_add_f32 v[156:157], v[168:169], v[154:155]
	s_nop 0
	v_pk_add_f32 v[158:159], v[156:157], v[168:169] neg_lo:[0,1] neg_hi:[0,1]
	s_nop 0
	v_pk_add_f32 v[154:155], v[154:155], v[158:159] neg_lo:[0,1] neg_hi:[0,1]
	s_nop 0
	v_pk_add_f32 v[152:153], v[152:153], v[154:155]
	s_nop 0
	v_pk_add_f32 v[152:153], v[156:157], v[152:153]
	s_nop 0
	v_cndmask_b32_e32 v152, v252, v152, vcc
	v_cmp_neq_f32_e32 vcc, s3, v205
	s_nop 1
	v_cndmask_b32_e32 v153, v252, v153, vcc
	v_cmp_ngt_f32_e32 vcc, -1.0, v205
	s_nop 1
	v_cndmask_b32_e32 v153, v253, v153, vcc
	v_cmp_ngt_f32_e32 vcc, -1.0, v182
	s_nop 1
	v_cndmask_b32_e32 v152, v253, v152, vcc
	v_cmp_neq_f32_e32 vcc, -1.0, v182
	s_nop 1
	v_cndmask_b32_e32 v152, v244, v152, vcc
	v_cmp_neq_f32_e32 vcc, -1.0, v205
	s_nop 1
	v_cndmask_b32_e32 v153, v244, v153, vcc
	v_cmp_lt_f32_e64 vcc, |v182|, s4
	v_cndmask_b32_e64 v153, v153, v205, s[0:1]
	s_nop 0
	v_cndmask_b32_e32 v152, v152, v182, vcc
	v_pk_add_f32 v[138:139], v[138:139], v[152:153]
	v_max_f32_e32 v152, 0, v140
	v_mul_f32_e64 v140, |v140|, s88
	v_exp_f32_e32 v182, v140
	s_nop 0
	v_add_f32_e32 v140, 1.0, v182
	v_add_f32_e32 v153, -1.0, v140
	v_sub_f32_e32 v154, v153, v140
	v_add_f32_e32 v154, 1.0, v154
	v_sub_f32_e32 v153, v182, v153
	v_add_f32_e32 v153, v153, v154
	v_frexp_mant_f32_e32 v154, v140
	v_cmp_gt_f32_e32 vcc, s2, v154
	v_cvt_f64_f32_e32 v[154:155], v140
	v_frexp_exp_i32_f64_e32 v154, v[154:155]
	v_subbrev_co_u32_e32 v172, vcc, 0, v154, vcc
	v_sub_u32_e32 v154, 0, v172
	v_ldexp_f32 v140, v140, v154
	v_ldexp_f32 v154, v153, v154
	v_max_f32_e32 v153, 0, v141
	v_mul_f32_e64 v141, |v141|, s88
	v_exp_f32_e32 v205, v141
	s_nop 0
	v_add_f32_e32 v141, 1.0, v205
	v_add_f32_e32 v155, -1.0, v141
	v_sub_f32_e32 v156, v155, v141
	v_add_f32_e32 v156, 1.0, v156
	v_sub_f32_e32 v155, v205, v155
	v_add_f32_e32 v155, v155, v156
	v_frexp_mant_f32_e32 v156, v141
	v_cmp_gt_f32_e32 vcc, s2, v156
	v_cvt_f64_f32_e32 v[156:157], v141
	v_frexp_exp_i32_f64_e32 v156, v[156:157]
	v_subbrev_co_u32_e32 v173, vcc, 0, v156, vcc
	v_sub_u32_e32 v156, 0, v173
	v_ldexp_f32 v141, v141, v156
	v_ldexp_f32 v155, v155, v156
	v_pk_add_f32 v[156:157], v[140:141], 1.0 op_sel_hi:[1,0]
	v_pk_add_f32 v[164:165], v[140:141], -1.0 op_sel_hi:[1,0]
	v_pk_add_f32 v[158:159], v[156:157], -1.0 op_sel_hi:[1,0]
	v_pk_add_f32 v[166:167], v[164:165], 1.0 op_sel_hi:[1,0]
	v_pk_add_f32 v[158:159], v[140:141], v[158:159] neg_lo:[0,1] neg_hi:[0,1]
	v_pk_add_f32 v[140:141], v[140:141], v[166:167] neg_lo:[0,1] neg_hi:[0,1]
	v_pk_add_f32 v[158:159], v[154:155], v[158:159]
	v_pk_add_f32 v[140:141], v[154:155], v[140:141]
	v_pk_add_f32 v[160:161], v[156:157], v[158:159]
	v_pk_add_f32 v[154:155], v[164:165], v[140:141]
	v_rcp_f32_e32 v162, v160
	v_rcp_f32_e32 v163, v161
	v_pk_add_f32 v[156:157], v[160:161], v[156:157] neg_lo:[0,1] neg_hi:[0,1]
	v_pk_add_f32 v[164:165], v[154:155], v[164:165] neg_lo:[0,1] neg_hi:[0,1]
	v_pk_add_f32 v[156:157], v[158:159], v[156:157] neg_lo:[0,1] neg_hi:[0,1]
	v_pk_mul_f32 v[158:159], v[154:155], v[162:163]
	v_pk_add_f32 v[140:141], v[140:141], v[164:165] neg_lo:[0,1] neg_hi:[0,1]
	v_pk_mul_f32 v[164:165], v[160:161], v[158:159]
	v_cmp_neq_f32_e32 vcc, s3, v182
	v_pk_fma_f32 v[166:167], v[158:159], v[160:161], v[164:165] neg_lo:[0,0,1] neg_hi:[0,0,1]
	v_cmp_lt_f32_e64 s[0:1], |v205|, s4
	v_pk_fma_f32 v[166:167], v[158:159], v[156:157], v[166:167]
	s_nop 0
	v_pk_add_f32 v[168:169], v[164:165], v[166:167]
	s_nop 0
	v_pk_add_f32 v[170:171], v[154:155], v[168:169] neg_lo:[0,1] neg_hi:[0,1]
	v_pk_add_f32 v[164:165], v[168:169], v[164:165] neg_lo:[0,1] neg_hi:[0,1]
	v_pk_add_f32 v[154:155], v[154:155], v[170:171] neg_lo:[0,1] neg_hi:[0,1]
	s_nop 0
; __device__ __forceinline__ float softplusf_(float x) { return fmaxf(x, 0.0f) + log1pf(__expf(-fabsf(x))); }
;     __device__ __forceinline__ void operator()(f32x4 (&acc)[2][2][4][2], const pg8::Unit& u, int wr, int wc, int fr, int fq) const {
;     ...
;                     for (int m = 0; m < 4; ++m) { const int row = row0 + ai * 128 + m * 16; const f32x4 v0 = acc[ai][0][m][0] + b0, v1 = acc[ai][0][m][1] + b1;
;                         float* d = DTA + (size_t)row * NH + cl0;
;                         *(f32x4*)d = (f32x4){softplusf_(v0[0]), softplusf_(v0[1]), softplusf_(v0[2]), softplusf_(v0[3])}; *(f32x4*)(d + 4) = (f32x4){softplusf_(v1[0]), softplusf_(v1[1]), softplusf_(v1[2]), softplusf_(v1[3])}; } }
	v_pk_add_f32 v[154:155], v[154:155], v[168:169] neg_lo:[0,1] neg_hi:[0,1]
	s_nop 0
	v_pk_add_f32 v[140:141], v[140:141], v[154:155]
	v_pk_add_f32 v[154:155], v[164:165], v[166:167] neg_lo:[0,1] neg_hi:[0,1]
	s_nop 0
	v_pk_add_f32 v[140:141], v[154:155], v[140:141]
	s_nop 0
	v_pk_add_f32 v[154:155], v[170:171], v[140:141]
	s_nop 0
	v_pk_mul_f32 v[164:165], v[162:163], v[154:155]
	s_nop 0
	v_pk_mul_f32 v[166:167], v[160:161], v[164:165]
	s_nop 0
	v_pk_fma_f32 v[160:161], v[164:165], v[160:161], v[166:167] neg_lo:[0,0,1] neg_hi:[0,0,1]
	s_nop 0
	v_pk_fma_f32 v[156:157], v[164:165], v[156:157], v[160:161]
	v_pk_add_f32 v[160:161], v[170:171], v[154:155] neg_lo:[0,1] neg_hi:[0,1]
	s_nop 0
	v_pk_add_f32 v[140:141], v[140:141], v[160:161]
	v_pk_add_f32 v[160:161], v[166:167], v[156:157]
	s_nop 0
	v_pk_add_f32 v[168:169], v[154:155], v[160:161] neg_lo:[0,1] neg_hi:[0,1]
	v_pk_add_f32 v[166:167], v[160:161], v[166:167] neg_lo:[0,1] neg_hi:[0,1]
	v_pk_add_f32 v[154:155], v[154:155], v[168:169] neg_lo:[0,1] neg_hi:[0,1]
	s_nop 0
	v_pk_add_f32 v[154:155], v[154:155], v[160:161] neg_lo:[0,1] neg_hi:[0,1]
	s_nop 0
	v_pk_add_f32 v[140:141], v[140:141], v[154:155]
	v_pk_add_f32 v[154:155], v[166:167], v[156:157] neg_lo:[0,1] neg_hi:[0,1]
	s_nop 0
	v_pk_add_f32 v[140:141], v[154:155], v[140:141]
	v_pk_add_f32 v[154:155], v[158:159], v[164:165]
	v_pk_add_f32 v[140:141], v[168:169], v[140:141]
	v_pk_add_f32 v[156:157], v[154:155], v[158:159] neg_lo:[0,1] neg_hi:[0,1]
	v_pk_mul_f32 v[140:141], v[162:163], v[140:141]
	v_pk_add_f32 v[156:157], v[164:165], v[156:157] neg_lo:[0,1] neg_hi:[0,1]
	s_nop 0
	v_pk_add_f32 v[140:141], v[156:157], v[140:141]
	s_nop 0
	v_pk_add_f32 v[156:157], v[154:155], v[140:141]
	s_nop 0
	v_pk_mul_f32 v[158:159], v[156:157], v[156:157]
	v_pk_add_f32 v[154:155], v[156:157], v[154:155] neg_lo:[0,1] neg_hi:[0,1]
	v_pk_fma_f32 v[160:161], v[158:159], s[6:7], v[142:143] op_sel_hi:[1,0,0]
	v_pk_add_f32 v[140:141], v[140:141], v[154:155] neg_lo:[0,1] neg_hi:[0,1]
	v_ldexp_f32 v154, v156, 1
	v_pk_fma_f32 v[160:161], v[158:159], v[160:161], s[8:9] op_sel_hi:[1,1,0]
	v_ldexp_f32 v155, v157, 1
	v_pk_mul_f32 v[156:157], v[156:157], v[158:159]
	v_cvt_f32_i32_e32 v159, v173
	v_cvt_f32_i32_e32 v158, v172
	v_pk_mul_f32 v[156:157], v[156:157], v[160:161]
	v_ldexp_f32 v163, v141, 1
	v_pk_add_f32 v[160:161], v[154:155], v[156:157]
	v_pk_mul_f32 v[164:165], v[158:159], s[36:37] op_sel_hi:[1,0]
	v_pk_add_f32 v[154:155], v[160:161], v[154:155] neg_lo:[0,1] neg_hi:[0,1]
	v_pk_fma_f32 v[166:167], v[158:159], s[36:37], v[164:165] op_sel_hi:[1,0,1] neg_lo:[0,0,1] neg_hi:[0,0,1]
	v_pk_add_f32 v[154:155], v[156:157], v[154:155] neg_lo:[0,1] neg_hi:[0,1]
	v_pk_fma_f32 v[158:159], v[158:159], s[10:11], v[166:167] op_sel_hi:[1,0,1]
	v_ldexp_f32 v140, v140, 1
	v_mov_b32_e32 v156, v164
	v_mov_b32_e32 v157, v155
	v_mov_b32_e32 v162, v158
	v_mov_b32_e32 v141, v163
	v_pk_add_f32 v[156:157], v[156:157], v[162:163]
	v_pk_add_f32 v[162:163], v[140:141], v[154:155]
	v_mov_b32_e32 v155, v161
	v_mov_b32_e32 v141, v163
	v_pk_add_f32 v[166:167], v[164:165], v[158:159]
	v_pk_add_f32 v[140:141], v[140:141], v[154:155]
	v_pk_add_f32 v[154:155], v[160:161], v[162:163]
	v_mov_b32_e32 v208, v160
	v_pk_add_f32 v[168:169], v[166:167], v[154:155]
	v_mov_b32_e32 v206, v154
	v_mov_b32_e32 v207, v169
	v_mov_b32_e32 v209, v167
	v_pk_add_f32 v[206:207], v[206:207], v[208:209] neg_lo:[0,1] neg_hi:[0,1]
	v_mov_b32_e32 v170, v168
	v_mov_b32_e32 v171, v167
	v_mov_b32_e32 v172, v166
	v_mov_b32_e32 v173, v165
	v_mov_b32_e32 v208, v166
	v_mov_b32_e32 v209, v169
	v_mov_b32_e32 v165, v207
	v_pk_add_f32 v[170:171], v[170:171], v[172:173] neg_lo:[0,1] neg_hi:[0,1]
	v_mov_b32_e32 v172, v154
	v_mov_b32_e32 v173, v159
	v_pk_add_f32 v[164:165], v[208:209], v[164:165] neg_lo:[0,1] neg_hi:[0,1]
	v_pk_add_f32 v[172:173], v[172:173], v[170:171] neg_lo:[0,1] neg_hi:[0,1]
	v_mov_b32_e32 v208, v164
	v_mov_b32_e32 v209, v171
	v_mov_b32_e32 v210, v168
	v_mov_b32_e32 v211, v155
	v_mov_b32_e32 v171, v161
	v_pk_add_f32 v[208:209], v[158:159], v[208:209] neg_lo:[0,1] neg_hi:[0,1]
	v_pk_add_f32 v[170:171], v[210:211], v[170:171] neg_lo:[0,1] neg_hi:[0,1]
	v_mov_b32_e32 v159, v167
	v_pk_add_f32 v[156:157], v[156:157], v[170:171] neg_lo:[0,1] neg_hi:[0,1]
	v_pk_add_f32 v[158:159], v[158:159], v[164:165] neg_lo:[0,1] neg_hi:[0,1]
	v_pk_add_f32 v[140:141], v[140:141], v[206:207] neg_lo:[0,1] neg_hi:[0,1]
	v_pk_add_f32 v[154:155], v[154:155], v[160:161] neg_lo:[0,1] neg_hi:[0,1]
	v_pk_add_f32 v[160:161], v[140:141], v[158:159]
	v_mov_b32_e32 v159, v173
	v_mov_b32_e32 v141, v157
	v_pk_add_f32 v[154:155], v[162:163], v[154:155] neg_lo:[0,1] neg_hi:[0,1]
	v_pk_add_f32 v[162:163], v[172:173], v[156:157]
	v_pk_add_f32 v[140:141], v[158:159], v[140:141]
	v_mov_b32_e32 v156, v160
	v_pk_add_f32 v[140:141], v[140:141], v[208:209] neg_lo:[0,1] neg_hi:[0,1]
	v_mov_b32_e32 v157, v163
	v_pk_add_f32 v[156:157], v[156:157], v[140:141] neg_lo:[0,1] neg_hi:[0,1]
	v_pk_add_f32 v[140:141], v[154:155], v[140:141] neg_lo:[0,1] neg_hi:[0,1]
	v_pk_add_f32 v[156:157], v[158:159], v[156:157] neg_lo:[0,1] neg_hi:[0,1]
	v_pk_add_f32 v[154:155], v[162:163], v[160:161]
	v_pk_add_f32 v[140:141], v[140:141], v[156:157]
	v_pk_add_f32 v[156:157], v[168:169], v[154:155]
	s_nop 0
	v_pk_add_f32 v[158:159], v[156:157], v[168:169] neg_lo:[0,1] neg_hi:[0,1]
	s_nop 0
	v_pk_add_f32 v[154:155], v[154:155], v[158:159] neg_lo:[0,1] neg_hi:[0,1]
	s_nop 0
	v_pk_add_f32 v[140:141], v[140:141], v[154:155]
	s_nop 0
	v_pk_add_f32 v[140:141], v[156:157], v[140:141]
	s_nop 0
	v_cndmask_b32_e32 v140, v252, v140, vcc
	v_cmp_neq_f32_e32 vcc, s3, v205
	s_nop 1
; __device__ __forceinline__ float softplusf_(float x) { return fmaxf(x, 0.0f) + log1pf(__expf(-fabsf(x))); }
;     __device__ __forceinline__ void operator()(f32x4 (&acc)[2][2][4][2], const pg8::Unit& u, int wr, int wc, int fr, int fq) const {
;     ...
;             if (wc == 0) { const f32x4 b0 = *(const f32x4*)(dtb + cl0), b1 = *(const f32x4*)(dtb + cl0 + 4);
; #pragma unroll
;                 for (int ai = 0; ai < 2; ++ai)
; #pragma unroll
;                     for (int m = 0; m < 4; ++m) { const int row = row0 + ai * 128 + m * 16; const f32x4 v0 = acc[ai][0][m][0] + b0, v1 = acc[ai][0][m][1] + b1;
;                         float* d = DTA + (size_t)row * NH + cl0;
;                         *(f32x4*)d = (f32x4){softplusf_(v0[0]), softplusf_(v0[1]), softplusf_(v0[2]), softplusf_(v0[3])}; *(f32x4*)(d + 4) = (f32x4){softplusf_(v1[0]), softplusf_(v1[1]), softplusf_(v1[2]), softplusf_(v1[3])}; } }
	v_cndmask_b32_e32 v141, v252, v141, vcc
	v_cmp_ngt_f32_e32 vcc, -1.0, v205
	s_nop 1
	v_cndmask_b32_e32 v141, v253, v141, vcc
	v_cmp_ngt_f32_e32 vcc, -1.0, v182
	s_nop 1
	v_cndmask_b32_e32 v140, v253, v140, vcc
	v_cmp_neq_f32_e32 vcc, -1.0, v182
	s_nop 1
	v_cndmask_b32_e32 v140, v244, v140, vcc
	v_cmp_neq_f32_e32 vcc, -1.0, v205
	s_nop 1
	v_cndmask_b32_e32 v141, v244, v141, vcc
	v_cmp_lt_f32_e64 vcc, |v182|, s4
	v_cndmask_b32_e64 v141, v141, v205, s[0:1]
	s_nop 0
	v_cndmask_b32_e32 v140, v140, v182, vcc
	v_pk_add_f32 v[140:141], v[152:153], v[140:141]
	global_store_dwordx4 v[146:147], v[138:141], off
	s_nop 1
	v_mul_f32_e64 v139, |v150|, s88
	v_exp_f32_e32 v182, v139
	v_max_f32_e32 v138, 0, v150
	v_add_f32_e32 v139, 1.0, v182
	v_add_f32_e32 v140, -1.0, v139
	v_sub_f32_e32 v141, v140, v139
	v_add_f32_e32 v141, 1.0, v141
	v_sub_f32_e32 v140, v182, v140
	v_add_f32_e32 v150, v140, v141
	v_frexp_mant_f32_e32 v140, v139
	v_cmp_gt_f32_e32 vcc, s2, v140
	v_cvt_f64_f32_e32 v[140:141], v139
	v_frexp_exp_i32_f64_e32 v140, v[140:141]
	v_subbrev_co_u32_e32 v168, vcc, 0, v140, vcc
	v_sub_u32_e32 v141, 0, v168
	v_ldexp_f32 v140, v139, v141
	v_ldexp_f32 v150, v150, v141
	v_mul_f32_e64 v141, |v151|, s88
	v_exp_f32_e32 v205, v141
	v_max_f32_e32 v139, 0, v151
	v_add_f32_e32 v141, 1.0, v205
	v_add_f32_e32 v151, -1.0, v141
	v_sub_f32_e32 v152, v151, v141
	v_add_f32_e32 v152, 1.0, v152
	v_sub_f32_e32 v151, v205, v151
	v_add_f32_e32 v151, v151, v152
	v_frexp_mant_f32_e32 v152, v141
	v_cmp_gt_f32_e32 vcc, s2, v152
	v_cvt_f64_f32_e32 v[152:153], v141
	v_frexp_exp_i32_f64_e32 v152, v[152:153]
	v_subbrev_co_u32_e32 v169, vcc, 0, v152, vcc
	v_sub_u32_e32 v152, 0, v169
	v_ldexp_f32 v141, v141, v152
	v_ldexp_f32 v151, v151, v152
	v_pk_add_f32 v[152:153], v[140:141], 1.0 op_sel_hi:[1,0]
	v_pk_add_f32 v[160:161], v[140:141], -1.0 op_sel_hi:[1,0]
	v_pk_add_f32 v[154:155], v[152:153], -1.0 op_sel_hi:[1,0]
	v_pk_add_f32 v[162:163], v[160:161], 1.0 op_sel_hi:[1,0]
	v_pk_add_f32 v[154:155], v[140:141], v[154:155] neg_lo:[0,1] neg_hi:[0,1]
	v_pk_add_f32 v[140:141], v[140:141], v[162:163] neg_lo:[0,1] neg_hi:[0,1]
	v_pk_add_f32 v[154:155], v[150:151], v[154:155]
	v_pk_add_f32 v[140:141], v[150:151], v[140:141]
	v_pk_add_f32 v[156:157], v[152:153], v[154:155]
	v_pk_add_f32 v[150:151], v[160:161], v[140:141]
	v_rcp_f32_e32 v158, v156
	v_rcp_f32_e32 v159, v157
	v_pk_add_f32 v[152:153], v[156:157], v[152:153] neg_lo:[0,1] neg_hi:[0,1]
	v_pk_add_f32 v[160:161], v[150:151], v[160:161] neg_lo:[0,1] neg_hi:[0,1]
	v_pk_add_f32 v[152:153], v[154:155], v[152:153] neg_lo:[0,1] neg_hi:[0,1]
	v_pk_mul_f32 v[154:155], v[150:151], v[158:159]
	v_pk_add_f32 v[140:141], v[140:141], v[160:161] neg_lo:[0,1] neg_hi:[0,1]
	v_pk_mul_f32 v[160:161], v[156:157], v[154:155]
	v_cmp_neq_f32_e32 vcc, s3, v182
	v_pk_fma_f32 v[162:163], v[154:155], v[156:157], v[160:161] neg_lo:[0,0,1] neg_hi:[0,0,1]
	v_cmp_lt_f32_e64 s[0:1], |v205|, s4
	v_pk_fma_f32 v[162:163], v[154:155], v[152:153], v[162:163]
	s_nop 0
	v_pk_add_f32 v[164:165], v[160:161], v[162:163]
	s_nop 0
	v_pk_add_f32 v[166:167], v[150:151], v[164:165] neg_lo:[0,1] neg_hi:[0,1]
	v_pk_add_f32 v[160:161], v[164:165], v[160:161] neg_lo:[0,1] neg_hi:[0,1]
	v_pk_add_f32 v[150:151], v[150:151], v[166:167] neg_lo:[0,1] neg_hi:[0,1]
	s_nop 0
	v_pk_add_f32 v[150:151], v[150:151], v[164:165] neg_lo:[0,1] neg_hi:[0,1]
	s_nop 0
	v_pk_add_f32 v[140:141], v[140:141], v[150:151]
	v_pk_add_f32 v[150:151], v[160:161], v[162:163] neg_lo:[0,1] neg_hi:[0,1]
	s_nop 0
	v_pk_add_f32 v[140:141], v[150:151], v[140:141]
	s_nop 0
	v_pk_add_f32 v[150:151], v[166:167], v[140:141]
	s_nop 0
	v_pk_mul_f32 v[160:161], v[158:159], v[150:151]
	s_nop 0
	v_pk_mul_f32 v[162:163], v[156:157], v[160:161]
	s_nop 0
	v_pk_fma_f32 v[156:157], v[160:161], v[156:157], v[162:163] neg_lo:[0,0,1] neg_hi:[0,0,1]
	s_nop 0
	v_pk_fma_f32 v[152:153], v[160:161], v[152:153], v[156:157]
	v_pk_add_f32 v[156:157], v[166:167], v[150:151] neg_lo:[0,1] neg_hi:[0,1]
	s_nop 0
	v_pk_add_f32 v[140:141], v[140:141], v[156:157]
	v_pk_add_f32 v[156:157], v[162:163], v[152:153]
	s_nop 0
	v_pk_add_f32 v[164:165], v[150:151], v[156:157] neg_lo:[0,1] neg_hi:[0,1]
	v_pk_add_f32 v[162:163], v[156:157], v[162:163] neg_lo:[0,1] neg_hi:[0,1]
	v_pk_add_f32 v[150:151], v[150:151], v[164:165] neg_lo:[0,1] neg_hi:[0,1]
	s_nop 0
	v_pk_add_f32 v[150:151], v[150:151], v[156:157] neg_lo:[0,1] neg_hi:[0,1]
	s_nop 0
	v_pk_add_f32 v[140:141], v[140:141], v[150:151]
	v_pk_add_f32 v[150:151], v[162:163], v[152:153] neg_lo:[0,1] neg_hi:[0,1]
	s_nop 0
	v_pk_add_f32 v[140:141], v[150:151], v[140:141]
	v_pk_add_f32 v[150:151], v[154:155], v[160:161]
	v_pk_add_f32 v[140:141], v[164:165], v[140:141]
	v_pk_add_f32 v[152:153], v[150:151], v[154:155] neg_lo:[0,1] neg_hi:[0,1]
	v_pk_mul_f32 v[140:141], v[158:159], v[140:141]
	v_pk_add_f32 v[152:153], v[160:161], v[152:153] neg_lo:[0,1] neg_hi:[0,1]
	s_nop 0
	v_pk_add_f32 v[140:141], v[152:153], v[140:141]
	s_nop 0
	v_pk_add_f32 v[152:153], v[150:151], v[140:141]
	s_nop 0
	v_pk_mul_f32 v[154:155], v[152:153], v[152:153]
	v_pk_add_f32 v[150:151], v[152:153], v[150:151] neg_lo:[0,1] neg_hi:[0,1]
	v_pk_fma_f32 v[156:157], v[154:155], s[6:7], v[142:143] op_sel_hi:[1,0,0]
	v_pk_add_f32 v[140:141], v[140:141], v[150:151] neg_lo:[0,1] neg_hi:[0,1]
	v_ldexp_f32 v150, v152, 1
	v_pk_fma_f32 v[156:157], v[154:155], v[156:157], s[8:9] op_sel_hi:[1,1,0]
	v_ldexp_f32 v151, v153, 1
	v_pk_mul_f32 v[152:153], v[152:153], v[154:155]
	v_cvt_f32_i32_e32 v155, v169
	v_cvt_f32_i32_e32 v154, v168
	v_pk_mul_f32 v[152:153], v[152:153], v[156:157]
	v_ldexp_f32 v159, v141, 1
	v_pk_add_f32 v[156:157], v[150:151], v[152:153]
; __device__ __forceinline__ float softplusf_(float x) { return fmaxf(x, 0.0f) + log1pf(__expf(-fabsf(x))); }
;     __device__ __forceinline__ void operator()(f32x4 (&acc)[2][2][4][2], const pg8::Unit& u, int wr, int wc, int fr, int fq) const {
;     ...
;                     for (int m = 0; m < 4; ++m) { const int row = row0 + ai * 128 + m * 16; const f32x4 v0 = acc[ai][0][m][0] + b0, v1 = acc[ai][0][m][1] + b1;
;                         float* d = DTA + (size_t)row * NH + cl0;
;                         *(f32x4*)d = (f32x4){softplusf_(v0[0]), softplusf_(v0[1]), softplusf_(v0[2]), softplusf_(v0[3])}; *(f32x4*)(d + 4) = (f32x4){softplusf_(v1[0]), softplusf_(v1[1]), softplusf_(v1[2]), softplusf_(v1[3])}; } }
	v_pk_mul_f32 v[160:161], v[154:155], s[36:37] op_sel_hi:[1,0]
	v_pk_add_f32 v[150:151], v[156:157], v[150:151] neg_lo:[0,1] neg_hi:[0,1]
	v_pk_fma_f32 v[162:163], v[154:155], s[36:37], v[160:161] op_sel_hi:[1,0,1] neg_lo:[0,0,1] neg_hi:[0,0,1]
	v_pk_add_f32 v[150:151], v[152:153], v[150:151] neg_lo:[0,1] neg_hi:[0,1]
	v_pk_fma_f32 v[154:155], v[154:155], s[10:11], v[162:163] op_sel_hi:[1,0,1]
	v_ldexp_f32 v140, v140, 1
	v_mov_b32_e32 v152, v160
	v_mov_b32_e32 v153, v151
	v_mov_b32_e32 v158, v154
	v_mov_b32_e32 v141, v159
	v_pk_add_f32 v[152:153], v[152:153], v[158:159]
	v_pk_add_f32 v[158:159], v[140:141], v[150:151]
	v_mov_b32_e32 v151, v157
	v_mov_b32_e32 v141, v159
	v_pk_add_f32 v[162:163], v[160:161], v[154:155]
	v_pk_add_f32 v[140:141], v[140:141], v[150:151]
	v_pk_add_f32 v[150:151], v[156:157], v[158:159]
	v_mov_b32_e32 v172, v156
	v_pk_add_f32 v[164:165], v[162:163], v[150:151]
	v_mov_b32_e32 v170, v150
	v_mov_b32_e32 v171, v165
	v_mov_b32_e32 v173, v163
	v_pk_add_f32 v[170:171], v[170:171], v[172:173] neg_lo:[0,1] neg_hi:[0,1]
	v_mov_b32_e32 v166, v164
	v_mov_b32_e32 v167, v163
	v_mov_b32_e32 v168, v162
	v_mov_b32_e32 v169, v161
	v_mov_b32_e32 v172, v162
	v_mov_b32_e32 v173, v165
	v_mov_b32_e32 v161, v171
	v_pk_add_f32 v[166:167], v[166:167], v[168:169] neg_lo:[0,1] neg_hi:[0,1]
	v_mov_b32_e32 v168, v150
	v_mov_b32_e32 v169, v155
	v_pk_add_f32 v[160:161], v[172:173], v[160:161] neg_lo:[0,1] neg_hi:[0,1]
	v_pk_add_f32 v[168:169], v[168:169], v[166:167] neg_lo:[0,1] neg_hi:[0,1]
	v_mov_b32_e32 v172, v160
	v_mov_b32_e32 v173, v167
	v_mov_b32_e32 v206, v164
	v_mov_b32_e32 v207, v151
	v_mov_b32_e32 v167, v157
	v_pk_add_f32 v[172:173], v[154:155], v[172:173] neg_lo:[0,1] neg_hi:[0,1]
	v_pk_add_f32 v[166:167], v[206:207], v[166:167] neg_lo:[0,1] neg_hi:[0,1]
	v_mov_b32_e32 v155, v163
	v_pk_add_f32 v[152:153], v[152:153], v[166:167] neg_lo:[0,1] neg_hi:[0,1]
	v_pk_add_f32 v[154:155], v[154:155], v[160:161] neg_lo:[0,1] neg_hi:[0,1]
	v_pk_add_f32 v[140:141], v[140:141], v[170:171] neg_lo:[0,1] neg_hi:[0,1]
	v_pk_add_f32 v[150:151], v[150:151], v[156:157] neg_lo:[0,1] neg_hi:[0,1]
	v_pk_add_f32 v[156:157], v[140:141], v[154:155]
	v_mov_b32_e32 v155, v169
	v_mov_b32_e32 v141, v153
	v_pk_add_f32 v[150:151], v[158:159], v[150:151] neg_lo:[0,1] neg_hi:[0,1]
	v_pk_add_f32 v[158:159], v[168:169], v[152:153]
	v_pk_add_f32 v[140:141], v[154:155], v[140:141]
	v_mov_b32_e32 v152, v156
	v_pk_add_f32 v[140:141], v[140:141], v[172:173] neg_lo:[0,1] neg_hi:[0,1]
	v_mov_b32_e32 v153, v159
	v_pk_add_f32 v[152:153], v[152:153], v[140:141] neg_lo:[0,1] neg_hi:[0,1]
	v_pk_add_f32 v[140:141], v[150:151], v[140:141] neg_lo:[0,1] neg_hi:[0,1]
	v_pk_add_f32 v[152:153], v[154:155], v[152:153] neg_lo:[0,1] neg_hi:[0,1]
	v_pk_add_f32 v[150:151], v[158:159], v[156:157]
	v_pk_add_f32 v[140:141], v[140:141], v[152:153]
	v_pk_add_f32 v[152:153], v[164:165], v[150:151]
	s_nop 0
	v_pk_add_f32 v[154:155], v[152:153], v[164:165] neg_lo:[0,1] neg_hi:[0,1]
	s_nop 0
	v_pk_add_f32 v[150:151], v[150:151], v[154:155] neg_lo:[0,1] neg_hi:[0,1]
	s_nop 0
	v_pk_add_f32 v[140:141], v[140:141], v[150:151]
	s_nop 0
	v_pk_add_f32 v[140:141], v[152:153], v[140:141]
	s_nop 0
	v_cndmask_b32_e32 v140, v252, v140, vcc
	v_cmp_neq_f32_e32 vcc, s3, v205
	s_nop 1
	v_cndmask_b32_e32 v141, v252, v141, vcc
	v_cmp_ngt_f32_e32 vcc, -1.0, v205
	s_nop 1
	v_cndmask_b32_e32 v141, v253, v141, vcc
	v_cmp_ngt_f32_e32 vcc, -1.0, v182
	s_nop 1
	v_cndmask_b32_e32 v140, v253, v140, vcc
	v_cmp_neq_f32_e32 vcc, -1.0, v182
	s_nop 1
	v_cndmask_b32_e32 v140, v244, v140, vcc
	v_cmp_neq_f32_e32 vcc, -1.0, v205
	s_nop 1
	v_cndmask_b32_e32 v141, v244, v141, vcc
	v_cmp_lt_f32_e64 vcc, |v182|, s4
	v_cndmask_b32_e64 v141, v141, v205, s[0:1]
	s_nop 0
	v_cndmask_b32_e32 v140, v140, v182, vcc
	v_pk_add_f32 v[138:139], v[138:139], v[140:141]
	v_mul_f32_e64 v141, |v148|, s88
	v_exp_f32_e32 v182, v141
	v_max_f32_e32 v140, 0, v148
	v_add_f32_e32 v141, 1.0, v182
	v_add_f32_e32 v148, -1.0, v141
	v_sub_f32_e32 v150, v148, v141
	v_add_f32_e32 v150, 1.0, v150
	v_sub_f32_e32 v148, v182, v148
	v_add_f32_e32 v152, v148, v150
	v_frexp_mant_f32_e32 v148, v141
	v_cvt_f64_f32_e32 v[150:151], v141
	v_cmp_gt_f32_e32 vcc, s2, v148
	v_frexp_exp_i32_f64_e32 v148, v[150:151]
	s_nop 0
	v_subbrev_co_u32_e32 v168, vcc, 0, v148, vcc
	v_sub_u32_e32 v150, 0, v168
	v_ldexp_f32 v148, v141, v150
	v_max_f32_e32 v141, 0, v149
	v_mul_f32_e64 v149, |v149|, s88
	v_exp_f32_e32 v205, v149
	v_ldexp_f32 v150, v152, v150
	v_add_f32_e32 v149, 1.0, v205
	v_add_f32_e32 v151, -1.0, v149
	v_sub_f32_e32 v152, v151, v149
	v_add_f32_e32 v152, 1.0, v152
	v_sub_f32_e32 v151, v205, v151
	v_add_f32_e32 v151, v151, v152
	v_frexp_mant_f32_e32 v152, v149
	v_cmp_gt_f32_e32 vcc, s2, v152
	v_cvt_f64_f32_e32 v[152:153], v149
	v_frexp_exp_i32_f64_e32 v152, v[152:153]
	v_subbrev_co_u32_e32 v169, vcc, 0, v152, vcc
	v_sub_u32_e32 v152, 0, v169
	v_ldexp_f32 v149, v149, v152
	v_ldexp_f32 v151, v151, v152
	v_pk_add_f32 v[152:153], v[148:149], 1.0 op_sel_hi:[1,0]
	v_pk_add_f32 v[160:161], v[148:149], -1.0 op_sel_hi:[1,0]
	v_pk_add_f32 v[154:155], v[152:153], -1.0 op_sel_hi:[1,0]
	v_pk_add_f32 v[162:163], v[160:161], 1.0 op_sel_hi:[1,0]
	v_pk_add_f32 v[154:155], v[148:149], v[154:155] neg_lo:[0,1] neg_hi:[0,1]
	v_pk_add_f32 v[148:149], v[148:149], v[162:163] neg_lo:[0,1] neg_hi:[0,1]
	v_pk_add_f32 v[154:155], v[150:151], v[154:155]
	v_pk_add_f32 v[148:149], v[150:151], v[148:149]
	v_pk_add_f32 v[156:157], v[152:153], v[154:155]
	v_pk_add_f32 v[150:151], v[160:161], v[148:149]
	v_rcp_f32_e32 v158, v156
	v_rcp_f32_e32 v159, v157
	v_pk_add_f32 v[152:153], v[156:157], v[152:153] neg_lo:[0,1] neg_hi:[0,1]
; __device__ __forceinline__ float softplusf_(float x) { return fmaxf(x, 0.0f) + log1pf(__expf(-fabsf(x))); }
;     __device__ __forceinline__ void operator()(f32x4 (&acc)[2][2][4][2], const pg8::Unit& u, int wr, int wc, int fr, int fq) const {
;     ...
;                     for (int m = 0; m < 4; ++m) { const int row = row0 + ai * 128 + m * 16; const f32x4 v0 = acc[ai][0][m][0] + b0, v1 = acc[ai][0][m][1] + b1;
;                         float* d = DTA + (size_t)row * NH + cl0;
;                         *(f32x4*)d = (f32x4){softplusf_(v0[0]), softplusf_(v0[1]), softplusf_(v0[2]), softplusf_(v0[3])}; *(f32x4*)(d + 4) = (f32x4){softplusf_(v1[0]), softplusf_(v1[1]), softplusf_(v1[2]), softplusf_(v1[3])}; } }
	v_pk_add_f32 v[160:161], v[150:151], v[160:161] neg_lo:[0,1] neg_hi:[0,1]
	v_pk_add_f32 v[152:153], v[154:155], v[152:153] neg_lo:[0,1] neg_hi:[0,1]
	v_pk_mul_f32 v[154:155], v[150:151], v[158:159]
	v_pk_add_f32 v[148:149], v[148:149], v[160:161] neg_lo:[0,1] neg_hi:[0,1]
	v_pk_mul_f32 v[160:161], v[156:157], v[154:155]
	v_cmp_neq_f32_e32 vcc, s3, v182
	v_pk_fma_f32 v[162:163], v[154:155], v[156:157], v[160:161] neg_lo:[0,0,1] neg_hi:[0,0,1]
	v_cmp_lt_f32_e64 s[0:1], |v205|, s4
	v_pk_fma_f32 v[162:163], v[154:155], v[152:153], v[162:163]
	s_nop 0
	v_pk_add_f32 v[164:165], v[160:161], v[162:163]
	s_nop 0
	v_pk_add_f32 v[166:167], v[150:151], v[164:165] neg_lo:[0,1] neg_hi:[0,1]
	v_pk_add_f32 v[160:161], v[164:165], v[160:161] neg_lo:[0,1] neg_hi:[0,1]
	v_pk_add_f32 v[150:151], v[150:151], v[166:167] neg_lo:[0,1] neg_hi:[0,1]
	s_nop 0
	v_pk_add_f32 v[150:151], v[150:151], v[164:165] neg_lo:[0,1] neg_hi:[0,1]
	s_nop 0
	v_pk_add_f32 v[148:149], v[148:149], v[150:151]
	v_pk_add_f32 v[150:151], v[160:161], v[162:163] neg_lo:[0,1] neg_hi:[0,1]
	s_nop 0
	v_pk_add_f32 v[148:149], v[150:151], v[148:149]
	s_nop 0
	v_pk_add_f32 v[150:151], v[166:167], v[148:149]
	s_nop 0
	v_pk_mul_f32 v[160:161], v[158:159], v[150:151]
	s_nop 0
	v_pk_mul_f32 v[162:163], v[156:157], v[160:161]
	s_nop 0
	v_pk_fma_f32 v[156:157], v[160:161], v[156:157], v[162:163] neg_lo:[0,0,1] neg_hi:[0,0,1]
	s_nop 0
	v_pk_fma_f32 v[152:153], v[160:161], v[152:153], v[156:157]
	v_pk_add_f32 v[156:157], v[166:167], v[150:151] neg_lo:[0,1] neg_hi:[0,1]
	s_nop 0
	v_pk_add_f32 v[148:149], v[148:149], v[156:157]
	v_pk_add_f32 v[156:157], v[162:163], v[152:153]
	s_nop 0
	v_pk_add_f32 v[164:165], v[150:151], v[156:157] neg_lo:[0,1] neg_hi:[0,1]
	v_pk_add_f32 v[162:163], v[156:157], v[162:163] neg_lo:[0,1] neg_hi:[0,1]
	v_pk_add_f32 v[150:151], v[150:151], v[164:165] neg_lo:[0,1] neg_hi:[0,1]
	s_nop 0
	v_pk_add_f32 v[150:151], v[150:151], v[156:157] neg_lo:[0,1] neg_hi:[0,1]
	s_nop 0
	v_pk_add_f32 v[148:149], v[148:149], v[150:151]
	v_pk_add_f32 v[150:151], v[162:163], v[152:153] neg_lo:[0,1] neg_hi:[0,1]
	s_nop 0
	v_pk_add_f32 v[148:149], v[150:151], v[148:149]
	v_pk_add_f32 v[150:151], v[154:155], v[160:161]
	v_pk_add_f32 v[148:149], v[164:165], v[148:149]
	v_pk_add_f32 v[152:153], v[150:151], v[154:155] neg_lo:[0,1] neg_hi:[0,1]
	v_pk_mul_f32 v[148:149], v[158:159], v[148:149]
	v_pk_add_f32 v[152:153], v[160:161], v[152:153] neg_lo:[0,1] neg_hi:[0,1]
	s_nop 0
	v_pk_add_f32 v[148:149], v[152:153], v[148:149]
	s_nop 0
	v_pk_add_f32 v[152:153], v[150:151], v[148:149]
	s_nop 0
	v_pk_mul_f32 v[154:155], v[152:153], v[152:153]
	v_pk_add_f32 v[150:151], v[152:153], v[150:151] neg_lo:[0,1] neg_hi:[0,1]
	v_pk_fma_f32 v[156:157], v[154:155], s[6:7], v[142:143] op_sel_hi:[1,0,0]
	v_pk_add_f32 v[148:149], v[148:149], v[150:151] neg_lo:[0,1] neg_hi:[0,1]
	v_ldexp_f32 v150, v152, 1
	v_pk_fma_f32 v[156:157], v[154:155], v[156:157], s[8:9] op_sel_hi:[1,1,0]
	v_ldexp_f32 v151, v153, 1
	v_pk_mul_f32 v[152:153], v[152:153], v[154:155]
	v_cvt_f32_i32_e32 v155, v169
	v_cvt_f32_i32_e32 v154, v168
	v_pk_mul_f32 v[152:153], v[152:153], v[156:157]
	v_ldexp_f32 v159, v149, 1
	v_pk_add_f32 v[156:157], v[150:151], v[152:153]
	v_pk_mul_f32 v[160:161], v[154:155], s[36:37] op_sel_hi:[1,0]
	v_pk_add_f32 v[150:151], v[156:157], v[150:151] neg_lo:[0,1] neg_hi:[0,1]
	v_pk_fma_f32 v[162:163], v[154:155], s[36:37], v[160:161] op_sel_hi:[1,0,1] neg_lo:[0,0,1] neg_hi:[0,0,1]
	v_pk_add_f32 v[150:151], v[152:153], v[150:151] neg_lo:[0,1] neg_hi:[0,1]
	v_pk_fma_f32 v[154:155], v[154:155], s[10:11], v[162:163] op_sel_hi:[1,0,1]
	v_ldexp_f32 v148, v148, 1
	v_mov_b32_e32 v152, v160
	v_mov_b32_e32 v153, v151
	v_mov_b32_e32 v158, v154
	v_mov_b32_e32 v149, v159
	v_pk_add_f32 v[152:153], v[152:153], v[158:159]
	v_pk_add_f32 v[158:159], v[148:149], v[150:151]
	v_mov_b32_e32 v151, v157
	v_mov_b32_e32 v149, v159
	v_pk_add_f32 v[162:163], v[160:161], v[154:155]
	v_pk_add_f32 v[148:149], v[148:149], v[150:151]
	v_pk_add_f32 v[150:151], v[156:157], v[158:159]
	v_mov_b32_e32 v172, v156
	v_pk_add_f32 v[164:165], v[162:163], v[150:151]
	v_mov_b32_e32 v170, v150
	v_mov_b32_e32 v171, v165
	v_mov_b32_e32 v173, v163
	v_pk_add_f32 v[170:171], v[170:171], v[172:173] neg_lo:[0,1] neg_hi:[0,1]
	v_mov_b32_e32 v166, v164
	v_mov_b32_e32 v167, v163
	v_mov_b32_e32 v168, v162
	v_mov_b32_e32 v169, v161
	v_mov_b32_e32 v172, v162
	v_mov_b32_e32 v173, v165
	v_mov_b32_e32 v161, v171
	v_pk_add_f32 v[166:167], v[166:167], v[168:169] neg_lo:[0,1] neg_hi:[0,1]
	v_mov_b32_e32 v168, v150
	v_mov_b32_e32 v169, v155
	v_pk_add_f32 v[160:161], v[172:173], v[160:161] neg_lo:[0,1] neg_hi:[0,1]
	v_pk_add_f32 v[168:169], v[168:169], v[166:167] neg_lo:[0,1] neg_hi:[0,1]
	v_mov_b32_e32 v172, v160
	v_mov_b32_e32 v173, v167
	v_mov_b32_e32 v206, v164
	v_mov_b32_e32 v207, v151
	v_mov_b32_e32 v167, v157
	v_pk_add_f32 v[172:173], v[154:155], v[172:173] neg_lo:[0,1] neg_hi:[0,1]
	v_pk_add_f32 v[166:167], v[206:207], v[166:167] neg_lo:[0,1] neg_hi:[0,1]
	v_mov_b32_e32 v155, v163
	v_pk_add_f32 v[152:153], v[152:153], v[166:167] neg_lo:[0,1] neg_hi:[0,1]
	v_pk_add_f32 v[154:155], v[154:155], v[160:161] neg_lo:[0,1] neg_hi:[0,1]
	v_pk_add_f32 v[148:149], v[148:149], v[170:171] neg_lo:[0,1] neg_hi:[0,1]
	v_pk_add_f32 v[150:151], v[150:151], v[156:157] neg_lo:[0,1] neg_hi:[0,1]
	v_pk_add_f32 v[156:157], v[148:149], v[154:155]
	v_mov_b32_e32 v155, v169
	v_mov_b32_e32 v149, v153
	v_pk_add_f32 v[150:151], v[158:159], v[150:151] neg_lo:[0,1] neg_hi:[0,1]
	v_pk_add_f32 v[158:159], v[168:169], v[152:153]
	v_pk_add_f32 v[148:149], v[154:155], v[148:149]
	v_mov_b32_e32 v152, v156
; __device__ __forceinline__ float softplusf_(float x) { return fmaxf(x, 0.0f) + log1pf(__expf(-fabsf(x))); }
;     __device__ __forceinline__ void operator()(f32x4 (&acc)[2][2][4][2], const pg8::Unit& u, int wr, int wc, int fr, int fq) const {
;     ...
;             if (wc == 0) { const f32x4 b0 = *(const f32x4*)(dtb + cl0), b1 = *(const f32x4*)(dtb + cl0 + 4);
; #pragma unroll
;                 for (int ai = 0; ai < 2; ++ai)
; #pragma unroll
;                     for (int m = 0; m < 4; ++m) { const int row = row0 + ai * 128 + m * 16; const f32x4 v0 = acc[ai][0][m][0] + b0, v1 = acc[ai][0][m][1] + b1;
;                         float* d = DTA + (size_t)row * NH + cl0;
;                         *(f32x4*)d = (f32x4){softplusf_(v0[0]), softplusf_(v0[1]), softplusf_(v0[2]), softplusf_(v0[3])}; *(f32x4*)(d + 4) = (f32x4){softplusf_(v1[0]), softplusf_(v1[1]), softplusf_(v1[2]), softplusf_(v1[3])}; } }
	v_pk_add_f32 v[148:149], v[148:149], v[172:173] neg_lo:[0,1] neg_hi:[0,1]
	v_mov_b32_e32 v153, v159
	v_pk_add_f32 v[152:153], v[152:153], v[148:149] neg_lo:[0,1] neg_hi:[0,1]
	v_pk_add_f32 v[148:149], v[150:151], v[148:149] neg_lo:[0,1] neg_hi:[0,1]
	v_pk_add_f32 v[152:153], v[154:155], v[152:153] neg_lo:[0,1] neg_hi:[0,1]
	v_pk_add_f32 v[150:151], v[158:159], v[156:157]
	v_pk_add_f32 v[148:149], v[148:149], v[152:153]
	v_pk_add_f32 v[152:153], v[164:165], v[150:151]
	s_nop 0
	v_pk_add_f32 v[154:155], v[152:153], v[164:165] neg_lo:[0,1] neg_hi:[0,1]
	s_nop 0
	v_pk_add_f32 v[150:151], v[150:151], v[154:155] neg_lo:[0,1] neg_hi:[0,1]
	s_nop 0
	v_pk_add_f32 v[148:149], v[148:149], v[150:151]
	v_pk_add_f32 v[150:151], v[74:75], v[130:131]
	v_pk_add_f32 v[148:149], v[152:153], v[148:149]
	v_pk_add_f32 v[152:153], v[78:79], v[134:135]
	v_cndmask_b32_e32 v148, v252, v148, vcc
	v_cmp_neq_f32_e32 vcc, s3, v205
	s_nop 1
	v_cndmask_b32_e32 v149, v252, v149, vcc
	v_cmp_ngt_f32_e32 vcc, -1.0, v205
	s_nop 1
	v_cndmask_b32_e32 v149, v253, v149, vcc
	v_cmp_ngt_f32_e32 vcc, -1.0, v182
	s_nop 1
	v_cndmask_b32_e32 v148, v253, v148, vcc
	v_cmp_neq_f32_e32 vcc, -1.0, v182
	s_nop 1
	v_cndmask_b32_e32 v148, v244, v148, vcc
	v_cmp_neq_f32_e32 vcc, -1.0, v205
	s_nop 1
	v_cndmask_b32_e32 v149, v244, v149, vcc
	v_cmp_lt_f32_e64 vcc, |v182|, s4
	v_cndmask_b32_e64 v149, v149, v205, s[0:1]
	s_nop 0
	v_cndmask_b32_e32 v148, v148, v182, vcc
	v_pk_add_f32 v[140:141], v[140:141], v[148:149]
	global_store_dwordx4 v[146:147], v[138:141], off offset:16
	v_pk_add_f32 v[148:149], v[76:77], v[132:133]
	s_nop 0
	v_lshlrev_b64 v[138:139], 7, v[196:197]
	v_lshl_add_u64 v[146:147], v[144:145], 0, v[138:139]
	v_mul_f32_e64 v139, |v152|, s88
	v_exp_f32_e32 v182, v139
	v_max_f32_e32 v138, 0, v152
	v_pk_add_f32 v[140:141], v[80:81], v[136:137]
	v_add_f32_e32 v139, 1.0, v182
	v_add_f32_e32 v152, -1.0, v139
	v_sub_f32_e32 v154, v152, v139
	v_add_f32_e32 v154, 1.0, v154
	v_sub_f32_e32 v152, v182, v152
	v_add_f32_e32 v156, v152, v154
	v_frexp_mant_f32_e32 v152, v139
	v_cvt_f64_f32_e32 v[154:155], v139
	v_cmp_gt_f32_e32 vcc, s2, v152
	v_frexp_exp_i32_f64_e32 v152, v[154:155]
	s_nop 0
	v_subbrev_co_u32_e32 v172, vcc, 0, v152, vcc
	v_sub_u32_e32 v154, 0, v172
	v_ldexp_f32 v152, v139, v154
	v_max_f32_e32 v139, 0, v153
	v_mul_f32_e64 v153, |v153|, s88
	v_exp_f32_e32 v205, v153
	v_ldexp_f32 v154, v156, v154
	v_add_f32_e32 v153, 1.0, v205
	v_add_f32_e32 v155, -1.0, v153
	v_sub_f32_e32 v156, v155, v153
	v_add_f32_e32 v156, 1.0, v156
	v_sub_f32_e32 v155, v205, v155
	v_add_f32_e32 v155, v155, v156
	v_frexp_mant_f32_e32 v156, v153
	v_cmp_gt_f32_e32 vcc, s2, v156
	v_cvt_f64_f32_e32 v[156:157], v153
	v_frexp_exp_i32_f64_e32 v156, v[156:157]
	v_subbrev_co_u32_e32 v173, vcc, 0, v156, vcc
	v_sub_u32_e32 v156, 0, v173
	v_ldexp_f32 v153, v153, v156
	v_ldexp_f32 v155, v155, v156
	v_pk_add_f32 v[156:157], v[152:153], 1.0 op_sel_hi:[1,0]
	v_pk_add_f32 v[164:165], v[152:153], -1.0 op_sel_hi:[1,0]
	v_pk_add_f32 v[158:159], v[156:157], -1.0 op_sel_hi:[1,0]
	v_pk_add_f32 v[166:167], v[164:165], 1.0 op_sel_hi:[1,0]
	v_pk_add_f32 v[158:159], v[152:153], v[158:159] neg_lo:[0,1] neg_hi:[0,1]
	v_pk_add_f32 v[152:153], v[152:153], v[166:167] neg_lo:[0,1] neg_hi:[0,1]
	v_pk_add_f32 v[158:159], v[154:155], v[158:159]
	v_pk_add_f32 v[152:153], v[154:155], v[152:153]
	v_pk_add_f32 v[160:161], v[156:157], v[158:159]
	v_pk_add_f32 v[154:155], v[164:165], v[152:153]
	v_rcp_f32_e32 v162, v160
	v_rcp_f32_e32 v163, v161
	v_pk_add_f32 v[156:157], v[160:161], v[156:157] neg_lo:[0,1] neg_hi:[0,1]
	v_pk_add_f32 v[164:165], v[154:155], v[164:165] neg_lo:[0,1] neg_hi:[0,1]
	v_pk_add_f32 v[156:157], v[158:159], v[156:157] neg_lo:[0,1] neg_hi:[0,1]
	v_pk_mul_f32 v[158:159], v[154:155], v[162:163]
	v_pk_add_f32 v[152:153], v[152:153], v[164:165] neg_lo:[0,1] neg_hi:[0,1]
	v_pk_mul_f32 v[164:165], v[160:161], v[158:159]
	v_cmp_neq_f32_e32 vcc, s3, v182
	v_pk_fma_f32 v[166:167], v[158:159], v[160:161], v[164:165] neg_lo:[0,0,1] neg_hi:[0,0,1]
	v_cmp_lt_f32_e64 s[0:1], |v205|, s4
	v_pk_fma_f32 v[166:167], v[158:159], v[156:157], v[166:167]
	s_nop 0
	v_pk_add_f32 v[168:169], v[164:165], v[166:167]
	s_nop 0
	v_pk_add_f32 v[170:171], v[154:155], v[168:169] neg_lo:[0,1] neg_hi:[0,1]
	v_pk_add_f32 v[164:165], v[168:169], v[164:165] neg_lo:[0,1] neg_hi:[0,1]
	v_pk_add_f32 v[154:155], v[154:155], v[170:171] neg_lo:[0,1] neg_hi:[0,1]
	s_nop 0
	v_pk_add_f32 v[154:155], v[154:155], v[168:169] neg_lo:[0,1] neg_hi:[0,1]
	s_nop 0
	v_pk_add_f32 v[152:153], v[152:153], v[154:155]
	v_pk_add_f32 v[154:155], v[164:165], v[166:167] neg_lo:[0,1] neg_hi:[0,1]
	s_nop 0
	v_pk_add_f32 v[152:153], v[154:155], v[152:153]
	s_nop 0
	v_pk_add_f32 v[154:155], v[170:171], v[152:153]
	s_nop 0
	v_pk_mul_f32 v[164:165], v[162:163], v[154:155]
	s_nop 0
	v_pk_mul_f32 v[166:167], v[160:161], v[164:165]
	s_nop 0
	v_pk_fma_f32 v[160:161], v[164:165], v[160:161], v[166:167] neg_lo:[0,0,1] neg_hi:[0,0,1]
	s_nop 0
	v_pk_fma_f32 v[156:157], v[164:165], v[156:157], v[160:161]
	v_pk_add_f32 v[160:161], v[170:171], v[154:155] neg_lo:[0,1] neg_hi:[0,1]
	s_nop 0
	v_pk_add_f32 v[152:153], v[152:153], v[160:161]
	v_pk_add_f32 v[160:161], v[166:167], v[156:157]
	s_nop 0
	v_pk_add_f32 v[168:169], v[154:155], v[160:161] neg_lo:[0,1] neg_hi:[0,1]
	v_pk_add_f32 v[166:167], v[160:161], v[166:167] neg_lo:[0,1] neg_hi:[0,1]
	v_pk_add_f32 v[154:155], v[154:155], v[168:169] neg_lo:[0,1] neg_hi:[0,1]
	s_nop 0
	v_pk_add_f32 v[154:155], v[154:155], v[160:161] neg_lo:[0,1] neg_hi:[0,1]
	s_nop 0
	v_pk_add_f32 v[152:153], v[152:153], v[154:155]
	v_pk_add_f32 v[154:155], v[166:167], v[156:157] neg_lo:[0,1] neg_hi:[0,1]
; __device__ __forceinline__ float softplusf_(float x) { return fmaxf(x, 0.0f) + log1pf(__expf(-fabsf(x))); }
;     __device__ __forceinline__ void operator()(f32x4 (&acc)[2][2][4][2], const pg8::Unit& u, int wr, int wc, int fr, int fq) const {
;     ...
;                     for (int m = 0; m < 4; ++m) { const int row = row0 + ai * 128 + m * 16; const f32x4 v0 = acc[ai][0][m][0] + b0, v1 = acc[ai][0][m][1] + b1;
;                         float* d = DTA + (size_t)row * NH + cl0;
;                         *(f32x4*)d = (f32x4){softplusf_(v0[0]), softplusf_(v0[1]), softplusf_(v0[2]), softplusf_(v0[3])}; *(f32x4*)(d + 4) = (f32x4){softplusf_(v1[0]), softplusf_(v1[1]), softplusf_(v1[2]), softplusf_(v1[3])}; } }
	s_nop 0
	v_pk_add_f32 v[152:153], v[154:155], v[152:153]
	v_pk_add_f32 v[154:155], v[158:159], v[164:165]
	v_pk_add_f32 v[152:153], v[168:169], v[152:153]
	v_pk_add_f32 v[156:157], v[154:155], v[158:159] neg_lo:[0,1] neg_hi:[0,1]
	v_pk_mul_f32 v[152:153], v[162:163], v[152:153]
	v_pk_add_f32 v[156:157], v[164:165], v[156:157] neg_lo:[0,1] neg_hi:[0,1]
	s_nop 0
	v_pk_add_f32 v[152:153], v[156:157], v[152:153]
	s_nop 0
	v_pk_add_f32 v[156:157], v[154:155], v[152:153]
	s_nop 0
	v_pk_mul_f32 v[158:159], v[156:157], v[156:157]
	v_pk_add_f32 v[154:155], v[156:157], v[154:155] neg_lo:[0,1] neg_hi:[0,1]
	v_pk_fma_f32 v[160:161], v[158:159], s[6:7], v[142:143] op_sel_hi:[1,0,0]
	v_pk_add_f32 v[152:153], v[152:153], v[154:155] neg_lo:[0,1] neg_hi:[0,1]
	v_ldexp_f32 v154, v156, 1
	v_pk_fma_f32 v[160:161], v[158:159], v[160:161], s[8:9] op_sel_hi:[1,1,0]
	v_ldexp_f32 v155, v157, 1
	v_pk_mul_f32 v[156:157], v[156:157], v[158:159]
	v_cvt_f32_i32_e32 v159, v173
	v_cvt_f32_i32_e32 v158, v172
	v_pk_mul_f32 v[156:157], v[156:157], v[160:161]
	v_ldexp_f32 v163, v153, 1
	v_pk_add_f32 v[160:161], v[154:155], v[156:157]
	v_pk_mul_f32 v[164:165], v[158:159], s[36:37] op_sel_hi:[1,0]
	v_pk_add_f32 v[154:155], v[160:161], v[154:155] neg_lo:[0,1] neg_hi:[0,1]
	v_pk_fma_f32 v[166:167], v[158:159], s[36:37], v[164:165] op_sel_hi:[1,0,1] neg_lo:[0,0,1] neg_hi:[0,0,1]
	v_pk_add_f32 v[154:155], v[156:157], v[154:155] neg_lo:[0,1] neg_hi:[0,1]
	v_pk_fma_f32 v[158:159], v[158:159], s[10:11], v[166:167] op_sel_hi:[1,0,1]
	v_ldexp_f32 v152, v152, 1
	v_mov_b32_e32 v156, v164
	v_mov_b32_e32 v157, v155
	v_mov_b32_e32 v162, v158
	v_mov_b32_e32 v153, v163
	v_pk_add_f32 v[156:157], v[156:157], v[162:163]
	v_pk_add_f32 v[162:163], v[152:153], v[154:155]
	v_mov_b32_e32 v155, v161
	v_mov_b32_e32 v153, v163
	v_pk_add_f32 v[166:167], v[164:165], v[158:159]
	v_pk_add_f32 v[152:153], v[152:153], v[154:155]
	v_pk_add_f32 v[154:155], v[160:161], v[162:163]
	v_mov_b32_e32 v208, v160
	v_pk_add_f32 v[168:169], v[166:167], v[154:155]
	v_mov_b32_e32 v206, v154
	v_mov_b32_e32 v207, v169
	v_mov_b32_e32 v209, v167
	v_pk_add_f32 v[206:207], v[206:207], v[208:209] neg_lo:[0,1] neg_hi:[0,1]
	v_mov_b32_e32 v170, v168
	v_mov_b32_e32 v171, v167
	v_mov_b32_e32 v172, v166
	v_mov_b32_e32 v173, v165
	v_mov_b32_e32 v208, v166
	v_mov_b32_e32 v209, v169
	v_mov_b32_e32 v165, v207
	v_pk_add_f32 v[170:171], v[170:171], v[172:173] neg_lo:[0,1] neg_hi:[0,1]
	v_mov_b32_e32 v172, v154
	v_mov_b32_e32 v173, v159
	v_pk_add_f32 v[164:165], v[208:209], v[164:165] neg_lo:[0,1] neg_hi:[0,1]
	v_pk_add_f32 v[172:173], v[172:173], v[170:171] neg_lo:[0,1] neg_hi:[0,1]
	v_mov_b32_e32 v208, v164
	v_mov_b32_e32 v209, v171
	v_mov_b32_e32 v210, v168
	v_mov_b32_e32 v211, v155
	v_mov_b32_e32 v171, v161
	v_pk_add_f32 v[208:209], v[158:159], v[208:209] neg_lo:[0,1] neg_hi:[0,1]
	v_pk_add_f32 v[170:171], v[210:211], v[170:171] neg_lo:[0,1] neg_hi:[0,1]
	v_mov_b32_e32 v159, v167
	v_pk_add_f32 v[156:157], v[156:157], v[170:171] neg_lo:[0,1] neg_hi:[0,1]
	v_pk_add_f32 v[158:159], v[158:159], v[164:165] neg_lo:[0,1] neg_hi:[0,1]
	v_pk_add_f32 v[152:153], v[152:153], v[206:207] neg_lo:[0,1] neg_hi:[0,1]
	v_pk_add_f32 v[154:155], v[154:155], v[160:161] neg_lo:[0,1] neg_hi:[0,1]
	v_pk_add_f32 v[160:161], v[152:153], v[158:159]
	v_mov_b32_e32 v159, v173
	v_mov_b32_e32 v153, v157
	v_pk_add_f32 v[154:155], v[162:163], v[154:155] neg_lo:[0,1] neg_hi:[0,1]
	v_pk_add_f32 v[162:163], v[172:173], v[156:157]
	v_pk_add_f32 v[152:153], v[158:159], v[152:153]
	v_mov_b32_e32 v156, v160
	v_pk_add_f32 v[152:153], v[152:153], v[208:209] neg_lo:[0,1] neg_hi:[0,1]
	v_mov_b32_e32 v157, v163
	v_pk_add_f32 v[156:157], v[156:157], v[152:153] neg_lo:[0,1] neg_hi:[0,1]
	v_pk_add_f32 v[152:153], v[154:155], v[152:153] neg_lo:[0,1] neg_hi:[0,1]
	v_pk_add_f32 v[156:157], v[158:159], v[156:157] neg_lo:[0,1] neg_hi:[0,1]
	v_pk_add_f32 v[154:155], v[162:163], v[160:161]
	v_pk_add_f32 v[152:153], v[152:153], v[156:157]
	v_pk_add_f32 v[156:157], v[168:169], v[154:155]
	s_nop 0
	v_pk_add_f32 v[158:159], v[156:157], v[168:169] neg_lo:[0,1] neg_hi:[0,1]
	s_nop 0
	v_pk_add_f32 v[154:155], v[154:155], v[158:159] neg_lo:[0,1] neg_hi:[0,1]
	s_nop 0
	v_pk_add_f32 v[152:153], v[152:153], v[154:155]
	s_nop 0
	v_pk_add_f32 v[152:153], v[156:157], v[152:153]
	s_nop 0
	v_cndmask_b32_e32 v152, v252, v152, vcc
	v_cmp_neq_f32_e32 vcc, s3, v205
	s_nop 1
	v_cndmask_b32_e32 v153, v252, v153, vcc
	v_cmp_ngt_f32_e32 vcc, -1.0, v205
	s_nop 1
	v_cndmask_b32_e32 v153, v253, v153, vcc
	v_cmp_ngt_f32_e32 vcc, -1.0, v182
	s_nop 1
	v_cndmask_b32_e32 v152, v253, v152, vcc
	v_cmp_neq_f32_e32 vcc, -1.0, v182
	s_nop 1
	v_cndmask_b32_e32 v152, v244, v152, vcc
	v_cmp_neq_f32_e32 vcc, -1.0, v205
	s_nop 1
	v_cndmask_b32_e32 v153, v244, v153, vcc
	v_cmp_lt_f32_e64 vcc, |v182|, s4
	v_cndmask_b32_e64 v153, v153, v205, s[0:1]
	s_nop 0
	v_cndmask_b32_e32 v152, v152, v182, vcc
	v_pk_add_f32 v[138:139], v[138:139], v[152:153]
	v_max_f32_e32 v152, 0, v140
	v_mul_f32_e64 v140, |v140|, s88
	v_exp_f32_e32 v182, v140
	s_nop 0
	v_add_f32_e32 v140, 1.0, v182
	v_add_f32_e32 v153, -1.0, v140
	v_sub_f32_e32 v154, v153, v140
	v_add_f32_e32 v154, 1.0, v154
	v_sub_f32_e32 v153, v182, v153
	v_add_f32_e32 v153, v153, v154
	v_frexp_mant_f32_e32 v154, v140
	v_cmp_gt_f32_e32 vcc, s2, v154
	v_cvt_f64_f32_e32 v[154:155], v140
	v_frexp_exp_i32_f64_e32 v154, v[154:155]
	v_subbrev_co_u32_e32 v172, vcc, 0, v154, vcc
	v_sub_u32_e32 v154, 0, v172
	v_ldexp_f32 v140, v140, v154
	v_ldexp_f32 v154, v153, v154
	v_max_f32_e32 v153, 0, v141
	v_mul_f32_e64 v141, |v141|, s88
	v_exp_f32_e32 v205, v141
	s_nop 0
	v_add_f32_e32 v141, 1.0, v205
; __device__ __forceinline__ float softplusf_(float x) { return fmaxf(x, 0.0f) + log1pf(__expf(-fabsf(x))); }
;     __device__ __forceinline__ void operator()(f32x4 (&acc)[2][2][4][2], const pg8::Unit& u, int wr, int wc, int fr, int fq) const {
;     ...
;                     for (int m = 0; m < 4; ++m) { const int row = row0 + ai * 128 + m * 16; const f32x4 v0 = acc[ai][0][m][0] + b0, v1 = acc[ai][0][m][1] + b1;
;                         float* d = DTA + (size_t)row * NH + cl0;
;                         *(f32x4*)d = (f32x4){softplusf_(v0[0]), softplusf_(v0[1]), softplusf_(v0[2]), softplusf_(v0[3])}; *(f32x4*)(d + 4) = (f32x4){softplusf_(v1[0]), softplusf_(v1[1]), softplusf_(v1[2]), softplusf_(v1[3])}; } }
	v_add_f32_e32 v155, -1.0, v141
	v_sub_f32_e32 v156, v155, v141
	v_add_f32_e32 v156, 1.0, v156
	v_sub_f32_e32 v155, v205, v155
	v_add_f32_e32 v155, v155, v156
	v_frexp_mant_f32_e32 v156, v141
	v_cmp_gt_f32_e32 vcc, s2, v156
	v_cvt_f64_f32_e32 v[156:157], v141
	v_frexp_exp_i32_f64_e32 v156, v[156:157]
	v_subbrev_co_u32_e32 v173, vcc, 0, v156, vcc
	v_sub_u32_e32 v156, 0, v173
	v_ldexp_f32 v141, v141, v156
	v_ldexp_f32 v155, v155, v156
	v_pk_add_f32 v[156:157], v[140:141], 1.0 op_sel_hi:[1,0]
	v_pk_add_f32 v[164:165], v[140:141], -1.0 op_sel_hi:[1,0]
	v_pk_add_f32 v[158:159], v[156:157], -1.0 op_sel_hi:[1,0]
	v_pk_add_f32 v[166:167], v[164:165], 1.0 op_sel_hi:[1,0]
	v_pk_add_f32 v[158:159], v[140:141], v[158:159] neg_lo:[0,1] neg_hi:[0,1]
	v_pk_add_f32 v[140:141], v[140:141], v[166:167] neg_lo:[0,1] neg_hi:[0,1]
	v_pk_add_f32 v[158:159], v[154:155], v[158:159]
	v_pk_add_f32 v[140:141], v[154:155], v[140:141]
	v_pk_add_f32 v[160:161], v[156:157], v[158:159]
	v_pk_add_f32 v[154:155], v[164:165], v[140:141]
	v_rcp_f32_e32 v162, v160
	v_rcp_f32_e32 v163, v161
	v_pk_add_f32 v[156:157], v[160:161], v[156:157] neg_lo:[0,1] neg_hi:[0,1]
	v_pk_add_f32 v[164:165], v[154:155], v[164:165] neg_lo:[0,1] neg_hi:[0,1]
	v_pk_add_f32 v[156:157], v[158:159], v[156:157] neg_lo:[0,1] neg_hi:[0,1]
	v_pk_mul_f32 v[158:159], v[154:155], v[162:163]
	v_pk_add_f32 v[140:141], v[140:141], v[164:165] neg_lo:[0,1] neg_hi:[0,1]
	v_pk_mul_f32 v[164:165], v[160:161], v[158:159]
	v_cmp_neq_f32_e32 vcc, s3, v182
	v_pk_fma_f32 v[166:167], v[158:159], v[160:161], v[164:165] neg_lo:[0,0,1] neg_hi:[0,0,1]
	v_cmp_lt_f32_e64 s[0:1], |v205|, s4
	v_pk_fma_f32 v[166:167], v[158:159], v[156:157], v[166:167]
	s_nop 0
	v_pk_add_f32 v[168:169], v[164:165], v[166:167]
	s_nop 0
	v_pk_add_f32 v[170:171], v[154:155], v[168:169] neg_lo:[0,1] neg_hi:[0,1]
	v_pk_add_f32 v[164:165], v[168:169], v[164:165] neg_lo:[0,1] neg_hi:[0,1]
	v_pk_add_f32 v[154:155], v[154:155], v[170:171] neg_lo:[0,1] neg_hi:[0,1]
	s_nop 0
	v_pk_add_f32 v[154:155], v[154:155], v[168:169] neg_lo:[0,1] neg_hi:[0,1]
	s_nop 0
	v_pk_add_f32 v[140:141], v[140:141], v[154:155]
	v_pk_add_f32 v[154:155], v[164:165], v[166:167] neg_lo:[0,1] neg_hi:[0,1]
	s_nop 0
	v_pk_add_f32 v[140:141], v[154:155], v[140:141]
	s_nop 0
	v_pk_add_f32 v[154:155], v[170:171], v[140:141]
	s_nop 0
	v_pk_mul_f32 v[164:165], v[162:163], v[154:155]
	s_nop 0
	v_pk_mul_f32 v[166:167], v[160:161], v[164:165]
	s_nop 0
	v_pk_fma_f32 v[160:161], v[164:165], v[160:161], v[166:167] neg_lo:[0,0,1] neg_hi:[0,0,1]
	s_nop 0
	v_pk_fma_f32 v[156:157], v[164:165], v[156:157], v[160:161]
	v_pk_add_f32 v[160:161], v[170:171], v[154:155] neg_lo:[0,1] neg_hi:[0,1]
	s_nop 0
	v_pk_add_f32 v[140:141], v[140:141], v[160:161]
	v_pk_add_f32 v[160:161], v[166:167], v[156:157]
	s_nop 0
	v_pk_add_f32 v[168:169], v[154:155], v[160:161] neg_lo:[0,1] neg_hi:[0,1]
	v_pk_add_f32 v[166:167], v[160:161], v[166:167] neg_lo:[0,1] neg_hi:[0,1]
	v_pk_add_f32 v[154:155], v[154:155], v[168:169] neg_lo:[0,1] neg_hi:[0,1]
	s_nop 0
	v_pk_add_f32 v[154:155], v[154:155], v[160:161] neg_lo:[0,1] neg_hi:[0,1]
	s_nop 0
	v_pk_add_f32 v[140:141], v[140:141], v[154:155]
	v_pk_add_f32 v[154:155], v[166:167], v[156:157] neg_lo:[0,1] neg_hi:[0,1]
	s_nop 0
	v_pk_add_f32 v[140:141], v[154:155], v[140:141]
	v_pk_add_f32 v[154:155], v[158:159], v[164:165]
	v_pk_add_f32 v[140:141], v[168:169], v[140:141]
	v_pk_add_f32 v[156:157], v[154:155], v[158:159] neg_lo:[0,1] neg_hi:[0,1]
	v_pk_mul_f32 v[140:141], v[162:163], v[140:141]
	v_pk_add_f32 v[156:157], v[164:165], v[156:157] neg_lo:[0,1] neg_hi:[0,1]
	s_nop 0
	v_pk_add_f32 v[140:141], v[156:157], v[140:141]
	s_nop 0
	v_pk_add_f32 v[156:157], v[154:155], v[140:141]
	s_nop 0
	v_pk_mul_f32 v[158:159], v[156:157], v[156:157]
	v_pk_add_f32 v[154:155], v[156:157], v[154:155] neg_lo:[0,1] neg_hi:[0,1]
	v_pk_fma_f32 v[160:161], v[158:159], s[6:7], v[142:143] op_sel_hi:[1,0,0]
	v_pk_add_f32 v[140:141], v[140:141], v[154:155] neg_lo:[0,1] neg_hi:[0,1]
	v_ldexp_f32 v154, v156, 1
	v_pk_fma_f32 v[160:161], v[158:159], v[160:161], s[8:9] op_sel_hi:[1,1,0]
	v_ldexp_f32 v155, v157, 1
	v_pk_mul_f32 v[156:157], v[156:157], v[158:159]
	v_cvt_f32_i32_e32 v159, v173
	v_cvt_f32_i32_e32 v158, v172
	v_pk_mul_f32 v[156:157], v[156:157], v[160:161]
	v_ldexp_f32 v163, v141, 1
	v_pk_add_f32 v[160:161], v[154:155], v[156:157]
	v_pk_mul_f32 v[164:165], v[158:159], s[36:37] op_sel_hi:[1,0]
	v_pk_add_f32 v[154:155], v[160:161], v[154:155] neg_lo:[0,1] neg_hi:[0,1]
	v_pk_fma_f32 v[166:167], v[158:159], s[36:37], v[164:165] op_sel_hi:[1,0,1] neg_lo:[0,0,1] neg_hi:[0,0,1]
	v_pk_add_f32 v[154:155], v[156:157], v[154:155] neg_lo:[0,1] neg_hi:[0,1]
	v_pk_fma_f32 v[158:159], v[158:159], s[10:11], v[166:167] op_sel_hi:[1,0,1]
	v_ldexp_f32 v140, v140, 1
	v_mov_b32_e32 v156, v164
	v_mov_b32_e32 v157, v155
	v_mov_b32_e32 v162, v158
	v_mov_b32_e32 v141, v163
	v_pk_add_f32 v[156:157], v[156:157], v[162:163]
	v_pk_add_f32 v[162:163], v[140:141], v[154:155]
	v_mov_b32_e32 v155, v161
	v_mov_b32_e32 v141, v163
	v_pk_add_f32 v[166:167], v[164:165], v[158:159]
	v_pk_add_f32 v[140:141], v[140:141], v[154:155]
	v_pk_add_f32 v[154:155], v[160:161], v[162:163]
	v_mov_b32_e32 v208, v160
	v_pk_add_f32 v[168:169], v[166:167], v[154:155]
	v_mov_b32_e32 v206, v154
	v_mov_b32_e32 v207, v169
	v_mov_b32_e32 v209, v167
	v_pk_add_f32 v[206:207], v[206:207], v[208:209] neg_lo:[0,1] neg_hi:[0,1]
	v_mov_b32_e32 v170, v168
	v_mov_b32_e32 v171, v167
	v_mov_b32_e32 v172, v166
	v_mov_b32_e32 v173, v165
	v_mov_b32_e32 v208, v166
	v_mov_b32_e32 v209, v169
	v_mov_b32_e32 v165, v207
	v_pk_add_f32 v[170:171], v[170:171], v[172:173] neg_lo:[0,1] neg_hi:[0,1]
; __device__ __forceinline__ float softplusf_(float x) { return fmaxf(x, 0.0f) + log1pf(__expf(-fabsf(x))); }
;     __device__ __forceinline__ void operator()(f32x4 (&acc)[2][2][4][2], const pg8::Unit& u, int wr, int wc, int fr, int fq) const {
;     ...
;             if (wc == 0) { const f32x4 b0 = *(const f32x4*)(dtb + cl0), b1 = *(const f32x4*)(dtb + cl0 + 4);
; #pragma unroll
;                 for (int ai = 0; ai < 2; ++ai)
; #pragma unroll
;                     for (int m = 0; m < 4; ++m) { const int row = row0 + ai * 128 + m * 16; const f32x4 v0 = acc[ai][0][m][0] + b0, v1 = acc[ai][0][m][1] + b1;
;                         float* d = DTA + (size_t)row * NH + cl0;
;                         *(f32x4*)d = (f32x4){softplusf_(v0[0]), softplusf_(v0[1]), softplusf_(v0[2]), softplusf_(v0[3])}; *(f32x4*)(d + 4) = (f32x4){softplusf_(v1[0]), softplusf_(v1[1]), softplusf_(v1[2]), softplusf_(v1[3])}; } }
	v_mov_b32_e32 v172, v154
	v_mov_b32_e32 v173, v159
	v_pk_add_f32 v[164:165], v[208:209], v[164:165] neg_lo:[0,1] neg_hi:[0,1]
	v_pk_add_f32 v[172:173], v[172:173], v[170:171] neg_lo:[0,1] neg_hi:[0,1]
	v_mov_b32_e32 v208, v164
	v_mov_b32_e32 v209, v171
	v_mov_b32_e32 v210, v168
	v_mov_b32_e32 v211, v155
	v_mov_b32_e32 v171, v161
	v_pk_add_f32 v[208:209], v[158:159], v[208:209] neg_lo:[0,1] neg_hi:[0,1]
	v_pk_add_f32 v[170:171], v[210:211], v[170:171] neg_lo:[0,1] neg_hi:[0,1]
	v_mov_b32_e32 v159, v167
	v_pk_add_f32 v[156:157], v[156:157], v[170:171] neg_lo:[0,1] neg_hi:[0,1]
	v_pk_add_f32 v[158:159], v[158:159], v[164:165] neg_lo:[0,1] neg_hi:[0,1]
	v_pk_add_f32 v[140:141], v[140:141], v[206:207] neg_lo:[0,1] neg_hi:[0,1]
	v_pk_add_f32 v[154:155], v[154:155], v[160:161] neg_lo:[0,1] neg_hi:[0,1]
	v_pk_add_f32 v[160:161], v[140:141], v[158:159]
	v_mov_b32_e32 v159, v173
	v_mov_b32_e32 v141, v157
	v_pk_add_f32 v[154:155], v[162:163], v[154:155] neg_lo:[0,1] neg_hi:[0,1]
	v_pk_add_f32 v[162:163], v[172:173], v[156:157]
	v_pk_add_f32 v[140:141], v[158:159], v[140:141]
	v_mov_b32_e32 v156, v160
	v_pk_add_f32 v[140:141], v[140:141], v[208:209] neg_lo:[0,1] neg_hi:[0,1]
	v_mov_b32_e32 v157, v163
	v_pk_add_f32 v[156:157], v[156:157], v[140:141] neg_lo:[0,1] neg_hi:[0,1]
	v_pk_add_f32 v[140:141], v[154:155], v[140:141] neg_lo:[0,1] neg_hi:[0,1]
	v_pk_add_f32 v[156:157], v[158:159], v[156:157] neg_lo:[0,1] neg_hi:[0,1]
	v_pk_add_f32 v[154:155], v[162:163], v[160:161]
	v_pk_add_f32 v[140:141], v[140:141], v[156:157]
	v_pk_add_f32 v[156:157], v[168:169], v[154:155]
	s_nop 0
	v_pk_add_f32 v[158:159], v[156:157], v[168:169] neg_lo:[0,1] neg_hi:[0,1]
	s_nop 0
	v_pk_add_f32 v[154:155], v[154:155], v[158:159] neg_lo:[0,1] neg_hi:[0,1]
	s_nop 0
	v_pk_add_f32 v[140:141], v[140:141], v[154:155]
	s_nop 0
	v_pk_add_f32 v[140:141], v[156:157], v[140:141]
	s_nop 0
	v_cndmask_b32_e32 v140, v252, v140, vcc
	v_cmp_neq_f32_e32 vcc, s3, v205
	s_nop 1
	v_cndmask_b32_e32 v141, v252, v141, vcc
	v_cmp_ngt_f32_e32 vcc, -1.0, v205
	s_nop 1
	v_cndmask_b32_e32 v141, v253, v141, vcc
	v_cmp_ngt_f32_e32 vcc, -1.0, v182
	s_nop 1
	v_cndmask_b32_e32 v140, v253, v140, vcc
	v_cmp_neq_f32_e32 vcc, -1.0, v182
	s_nop 1
	v_cndmask_b32_e32 v140, v244, v140, vcc
	v_cmp_neq_f32_e32 vcc, -1.0, v205
	s_nop 1
	v_cndmask_b32_e32 v141, v244, v141, vcc
	v_cmp_lt_f32_e64 vcc, |v182|, s4
	v_cndmask_b32_e64 v141, v141, v205, s[0:1]
	s_nop 0
	v_cndmask_b32_e32 v140, v140, v182, vcc
	v_pk_add_f32 v[140:141], v[152:153], v[140:141]
	global_store_dwordx4 v[146:147], v[138:141], off
	s_nop 1
	v_mul_f32_e64 v139, |v150|, s88
	v_exp_f32_e32 v182, v139
	v_max_f32_e32 v138, 0, v150
	v_add_f32_e32 v139, 1.0, v182
	v_add_f32_e32 v140, -1.0, v139
	v_sub_f32_e32 v141, v140, v139
	v_add_f32_e32 v141, 1.0, v141
	v_sub_f32_e32 v140, v182, v140
	v_add_f32_e32 v150, v140, v141
	v_frexp_mant_f32_e32 v140, v139
	v_cmp_gt_f32_e32 vcc, s2, v140
	v_cvt_f64_f32_e32 v[140:141], v139
	v_frexp_exp_i32_f64_e32 v140, v[140:141]
	v_subbrev_co_u32_e32 v168, vcc, 0, v140, vcc
	v_sub_u32_e32 v141, 0, v168
	v_ldexp_f32 v140, v139, v141
	v_ldexp_f32 v150, v150, v141
	v_mul_f32_e64 v141, |v151|, s88
	v_exp_f32_e32 v205, v141
	v_max_f32_e32 v139, 0, v151
	v_add_f32_e32 v141, 1.0, v205
	v_add_f32_e32 v151, -1.0, v141
	v_sub_f32_e32 v152, v151, v141
	v_add_f32_e32 v152, 1.0, v152
	v_sub_f32_e32 v151, v205, v151
	v_add_f32_e32 v151, v151, v152
	v_frexp_mant_f32_e32 v152, v141
	v_cmp_gt_f32_e32 vcc, s2, v152
	v_cvt_f64_f32_e32 v[152:153], v141
	v_frexp_exp_i32_f64_e32 v152, v[152:153]
	v_subbrev_co_u32_e32 v169, vcc, 0, v152, vcc
	v_sub_u32_e32 v152, 0, v169
	v_ldexp_f32 v141, v141, v152
	v_ldexp_f32 v151, v151, v152
	v_pk_add_f32 v[152:153], v[140:141], 1.0 op_sel_hi:[1,0]
	v_pk_add_f32 v[160:161], v[140:141], -1.0 op_sel_hi:[1,0]
	v_pk_add_f32 v[154:155], v[152:153], -1.0 op_sel_hi:[1,0]
	v_pk_add_f32 v[162:163], v[160:161], 1.0 op_sel_hi:[1,0]
	v_pk_add_f32 v[154:155], v[140:141], v[154:155] neg_lo:[0,1] neg_hi:[0,1]
	v_pk_add_f32 v[140:141], v[140:141], v[162:163] neg_lo:[0,1] neg_hi:[0,1]
	v_pk_add_f32 v[154:155], v[150:151], v[154:155]
	v_pk_add_f32 v[140:141], v[150:151], v[140:141]
	v_pk_add_f32 v[156:157], v[152:153], v[154:155]
	v_pk_add_f32 v[150:151], v[160:161], v[140:141]
	v_rcp_f32_e32 v158, v156
	v_rcp_f32_e32 v159, v157
	v_pk_add_f32 v[152:153], v[156:157], v[152:153] neg_lo:[0,1] neg_hi:[0,1]
	v_pk_add_f32 v[160:161], v[150:151], v[160:161] neg_lo:[0,1] neg_hi:[0,1]
	v_pk_add_f32 v[152:153], v[154:155], v[152:153] neg_lo:[0,1] neg_hi:[0,1]
	v_pk_mul_f32 v[154:155], v[150:151], v[158:159]
	v_pk_add_f32 v[140:141], v[140:141], v[160:161] neg_lo:[0,1] neg_hi:[0,1]
	v_pk_mul_f32 v[160:161], v[156:157], v[154:155]
	v_cmp_neq_f32_e32 vcc, s3, v182
	v_pk_fma_f32 v[162:163], v[154:155], v[156:157], v[160:161] neg_lo:[0,0,1] neg_hi:[0,0,1]
	v_cmp_lt_f32_e64 s[0:1], |v205|, s4
	v_pk_fma_f32 v[162:163], v[154:155], v[152:153], v[162:163]
	s_nop 0
	v_pk_add_f32 v[164:165], v[160:161], v[162:163]
	s_nop 0
	v_pk_add_f32 v[166:167], v[150:151], v[164:165] neg_lo:[0,1] neg_hi:[0,1]
	v_pk_add_f32 v[160:161], v[164:165], v[160:161] neg_lo:[0,1] neg_hi:[0,1]
	v_pk_add_f32 v[150:151], v[150:151], v[166:167] neg_lo:[0,1] neg_hi:[0,1]
	s_nop 0
	v_pk_add_f32 v[150:151], v[150:151], v[164:165] neg_lo:[0,1] neg_hi:[0,1]
	s_nop 0
	v_pk_add_f32 v[140:141], v[140:141], v[150:151]
	v_pk_add_f32 v[150:151], v[160:161], v[162:163] neg_lo:[0,1] neg_hi:[0,1]
	s_nop 0
	v_pk_add_f32 v[140:141], v[150:151], v[140:141]
	s_nop 0
	v_pk_add_f32 v[150:151], v[166:167], v[140:141]
	s_nop 0
	v_pk_mul_f32 v[160:161], v[158:159], v[150:151]
	s_nop 0
; __device__ __forceinline__ float softplusf_(float x) { return fmaxf(x, 0.0f) + log1pf(__expf(-fabsf(x))); }
;     __device__ __forceinline__ void operator()(f32x4 (&acc)[2][2][4][2], const pg8::Unit& u, int wr, int wc, int fr, int fq) const {
;     ...
;                     for (int m = 0; m < 4; ++m) { const int row = row0 + ai * 128 + m * 16; const f32x4 v0 = acc[ai][0][m][0] + b0, v1 = acc[ai][0][m][1] + b1;
;                         float* d = DTA + (size_t)row * NH + cl0;
;                         *(f32x4*)d = (f32x4){softplusf_(v0[0]), softplusf_(v0[1]), softplusf_(v0[2]), softplusf_(v0[3])}; *(f32x4*)(d + 4) = (f32x4){softplusf_(v1[0]), softplusf_(v1[1]), softplusf_(v1[2]), softplusf_(v1[3])}; } }
	v_pk_mul_f32 v[162:163], v[156:157], v[160:161]
	s_nop 0
	v_pk_fma_f32 v[156:157], v[160:161], v[156:157], v[162:163] neg_lo:[0,0,1] neg_hi:[0,0,1]
	s_nop 0
	v_pk_fma_f32 v[152:153], v[160:161], v[152:153], v[156:157]
	v_pk_add_f32 v[156:157], v[166:167], v[150:151] neg_lo:[0,1] neg_hi:[0,1]
	s_nop 0
	v_pk_add_f32 v[140:141], v[140:141], v[156:157]
	v_pk_add_f32 v[156:157], v[162:163], v[152:153]
	s_nop 0
	v_pk_add_f32 v[164:165], v[150:151], v[156:157] neg_lo:[0,1] neg_hi:[0,1]
	v_pk_add_f32 v[162:163], v[156:157], v[162:163] neg_lo:[0,1] neg_hi:[0,1]
	v_pk_add_f32 v[150:151], v[150:151], v[164:165] neg_lo:[0,1] neg_hi:[0,1]
	s_nop 0
	v_pk_add_f32 v[150:151], v[150:151], v[156:157] neg_lo:[0,1] neg_hi:[0,1]
	s_nop 0
	v_pk_add_f32 v[140:141], v[140:141], v[150:151]
	v_pk_add_f32 v[150:151], v[162:163], v[152:153] neg_lo:[0,1] neg_hi:[0,1]
	s_nop 0
	v_pk_add_f32 v[140:141], v[150:151], v[140:141]
	v_pk_add_f32 v[150:151], v[154:155], v[160:161]
	v_pk_add_f32 v[140:141], v[164:165], v[140:141]
	v_pk_add_f32 v[152:153], v[150:151], v[154:155] neg_lo:[0,1] neg_hi:[0,1]
	v_pk_mul_f32 v[140:141], v[158:159], v[140:141]
	v_pk_add_f32 v[152:153], v[160:161], v[152:153] neg_lo:[0,1] neg_hi:[0,1]
	s_nop 0
	v_pk_add_f32 v[140:141], v[152:153], v[140:141]
	s_nop 0
	v_pk_add_f32 v[152:153], v[150:151], v[140:141]
	s_nop 0
	v_pk_mul_f32 v[154:155], v[152:153], v[152:153]
	v_pk_add_f32 v[150:151], v[152:153], v[150:151] neg_lo:[0,1] neg_hi:[0,1]
	v_pk_fma_f32 v[156:157], v[154:155], s[6:7], v[142:143] op_sel_hi:[1,0,0]
	v_pk_add_f32 v[140:141], v[140:141], v[150:151] neg_lo:[0,1] neg_hi:[0,1]
	v_ldexp_f32 v150, v152, 1
	v_pk_fma_f32 v[156:157], v[154:155], v[156:157], s[8:9] op_sel_hi:[1,1,0]
	v_ldexp_f32 v151, v153, 1
	v_pk_mul_f32 v[152:153], v[152:153], v[154:155]
	v_cvt_f32_i32_e32 v155, v169
	v_cvt_f32_i32_e32 v154, v168
	v_pk_mul_f32 v[152:153], v[152:153], v[156:157]
	v_ldexp_f32 v159, v141, 1
	v_pk_add_f32 v[156:157], v[150:151], v[152:153]
	v_pk_mul_f32 v[160:161], v[154:155], s[36:37] op_sel_hi:[1,0]
	v_pk_add_f32 v[150:151], v[156:157], v[150:151] neg_lo:[0,1] neg_hi:[0,1]
	v_pk_fma_f32 v[162:163], v[154:155], s[36:37], v[160:161] op_sel_hi:[1,0,1] neg_lo:[0,0,1] neg_hi:[0,0,1]
	v_pk_add_f32 v[150:151], v[152:153], v[150:151] neg_lo:[0,1] neg_hi:[0,1]
	v_pk_fma_f32 v[154:155], v[154:155], s[10:11], v[162:163] op_sel_hi:[1,0,1]
	v_ldexp_f32 v140, v140, 1
	v_mov_b32_e32 v152, v160
	v_mov_b32_e32 v153, v151
	v_mov_b32_e32 v158, v154
	v_mov_b32_e32 v141, v159
	v_pk_add_f32 v[152:153], v[152:153], v[158:159]
	v_pk_add_f32 v[158:159], v[140:141], v[150:151]
	v_mov_b32_e32 v151, v157
	v_mov_b32_e32 v141, v159
	v_pk_add_f32 v[162:163], v[160:161], v[154:155]
	v_pk_add_f32 v[140:141], v[140:141], v[150:151]
	v_pk_add_f32 v[150:151], v[156:157], v[158:159]
	v_mov_b32_e32 v172, v156
	v_pk_add_f32 v[164:165], v[162:163], v[150:151]
	v_mov_b32_e32 v170, v150
	v_mov_b32_e32 v171, v165
	v_mov_b32_e32 v173, v163
	v_pk_add_f32 v[170:171], v[170:171], v[172:173] neg_lo:[0,1] neg_hi:[0,1]
	v_mov_b32_e32 v166, v164
	v_mov_b32_e32 v167, v163
	v_mov_b32_e32 v168, v162
	v_mov_b32_e32 v169, v161
	v_mov_b32_e32 v172, v162
	v_mov_b32_e32 v173, v165
	v_mov_b32_e32 v161, v171
	v_pk_add_f32 v[166:167], v[166:167], v[168:169] neg_lo:[0,1] neg_hi:[0,1]
	v_mov_b32_e32 v168, v150
	v_mov_b32_e32 v169, v155
	v_pk_add_f32 v[160:161], v[172:173], v[160:161] neg_lo:[0,1] neg_hi:[0,1]
	v_pk_add_f32 v[168:169], v[168:169], v[166:167] neg_lo:[0,1] neg_hi:[0,1]
	v_mov_b32_e32 v172, v160
	v_mov_b32_e32 v173, v167
	v_mov_b32_e32 v206, v164
	v_mov_b32_e32 v207, v151
	v_mov_b32_e32 v167, v157
	v_pk_add_f32 v[172:173], v[154:155], v[172:173] neg_lo:[0,1] neg_hi:[0,1]
	v_pk_add_f32 v[166:167], v[206:207], v[166:167] neg_lo:[0,1] neg_hi:[0,1]
	v_mov_b32_e32 v155, v163
	v_pk_add_f32 v[152:153], v[152:153], v[166:167] neg_lo:[0,1] neg_hi:[0,1]
	v_pk_add_f32 v[154:155], v[154:155], v[160:161] neg_lo:[0,1] neg_hi:[0,1]
	v_pk_add_f32 v[140:141], v[140:141], v[170:171] neg_lo:[0,1] neg_hi:[0,1]
	v_pk_add_f32 v[150:151], v[150:151], v[156:157] neg_lo:[0,1] neg_hi:[0,1]
	v_pk_add_f32 v[156:157], v[140:141], v[154:155]
	v_mov_b32_e32 v155, v169
	v_mov_b32_e32 v141, v153
	v_pk_add_f32 v[150:151], v[158:159], v[150:151] neg_lo:[0,1] neg_hi:[0,1]
	v_pk_add_f32 v[158:159], v[168:169], v[152:153]
	v_pk_add_f32 v[140:141], v[154:155], v[140:141]
	v_mov_b32_e32 v152, v156
	v_pk_add_f32 v[140:141], v[140:141], v[172:173] neg_lo:[0,1] neg_hi:[0,1]
	v_mov_b32_e32 v153, v159
	v_pk_add_f32 v[152:153], v[152:153], v[140:141] neg_lo:[0,1] neg_hi:[0,1]
	v_pk_add_f32 v[140:141], v[150:151], v[140:141] neg_lo:[0,1] neg_hi:[0,1]
	v_pk_add_f32 v[152:153], v[154:155], v[152:153] neg_lo:[0,1] neg_hi:[0,1]
	v_pk_add_f32 v[150:151], v[158:159], v[156:157]
	v_pk_add_f32 v[140:141], v[140:141], v[152:153]
	v_pk_add_f32 v[152:153], v[164:165], v[150:151]
	s_nop 0
	v_pk_add_f32 v[154:155], v[152:153], v[164:165] neg_lo:[0,1] neg_hi:[0,1]
	s_nop 0
	v_pk_add_f32 v[150:151], v[150:151], v[154:155] neg_lo:[0,1] neg_hi:[0,1]
	s_nop 0
	v_pk_add_f32 v[140:141], v[140:141], v[150:151]
	s_nop 0
	v_pk_add_f32 v[140:141], v[152:153], v[140:141]
	s_nop 0
	v_cndmask_b32_e32 v140, v252, v140, vcc
	v_cmp_neq_f32_e32 vcc, s3, v205
	s_nop 1
	v_cndmask_b32_e32 v141, v252, v141, vcc
	v_cmp_ngt_f32_e32 vcc, -1.0, v205
	s_nop 1
	v_cndmask_b32_e32 v141, v253, v141, vcc
	v_cmp_ngt_f32_e32 vcc, -1.0, v182
	s_nop 1
	v_cndmask_b32_e32 v140, v253, v140, vcc
	v_cmp_neq_f32_e32 vcc, -1.0, v182
	s_nop 1
	v_cndmask_b32_e32 v140, v244, v140, vcc
	v_cmp_neq_f32_e32 vcc, -1.0, v205
	s_nop 1
	v_cndmask_b32_e32 v141, v244, v141, vcc
	v_cmp_lt_f32_e64 vcc, |v182|, s4
; __device__ __forceinline__ float softplusf_(float x) { return fmaxf(x, 0.0f) + log1pf(__expf(-fabsf(x))); }
;     __device__ __forceinline__ void operator()(f32x4 (&acc)[2][2][4][2], const pg8::Unit& u, int wr, int wc, int fr, int fq) const {
;     ...
;                     for (int m = 0; m < 4; ++m) { const int row = row0 + ai * 128 + m * 16; const f32x4 v0 = acc[ai][0][m][0] + b0, v1 = acc[ai][0][m][1] + b1;
;                         float* d = DTA + (size_t)row * NH + cl0;
;                         *(f32x4*)d = (f32x4){softplusf_(v0[0]), softplusf_(v0[1]), softplusf_(v0[2]), softplusf_(v0[3])}; *(f32x4*)(d + 4) = (f32x4){softplusf_(v1[0]), softplusf_(v1[1]), softplusf_(v1[2]), softplusf_(v1[3])}; } }
	v_cndmask_b32_e64 v141, v141, v205, s[0:1]
	s_nop 0
	v_cndmask_b32_e32 v140, v140, v182, vcc
	v_pk_add_f32 v[138:139], v[138:139], v[140:141]
	v_mul_f32_e64 v141, |v148|, s88
	v_exp_f32_e32 v182, v141
	v_max_f32_e32 v140, 0, v148
	v_add_f32_e32 v141, 1.0, v182
	v_add_f32_e32 v148, -1.0, v141
	v_sub_f32_e32 v150, v148, v141
	v_add_f32_e32 v150, 1.0, v150
	v_sub_f32_e32 v148, v182, v148
	v_add_f32_e32 v152, v148, v150
	v_frexp_mant_f32_e32 v148, v141
	v_cvt_f64_f32_e32 v[150:151], v141
	v_cmp_gt_f32_e32 vcc, s2, v148
	v_frexp_exp_i32_f64_e32 v148, v[150:151]
	s_nop 0
	v_subbrev_co_u32_e32 v168, vcc, 0, v148, vcc
	v_sub_u32_e32 v150, 0, v168
	v_ldexp_f32 v148, v141, v150
	v_max_f32_e32 v141, 0, v149
	v_mul_f32_e64 v149, |v149|, s88
	v_exp_f32_e32 v205, v149
	v_ldexp_f32 v150, v152, v150
	v_add_f32_e32 v149, 1.0, v205
	v_add_f32_e32 v151, -1.0, v149
	v_sub_f32_e32 v152, v151, v149
	v_add_f32_e32 v152, 1.0, v152
	v_sub_f32_e32 v151, v205, v151
	v_add_f32_e32 v151, v151, v152
	v_frexp_mant_f32_e32 v152, v149
	v_cmp_gt_f32_e32 vcc, s2, v152
	v_cvt_f64_f32_e32 v[152:153], v149
	v_frexp_exp_i32_f64_e32 v152, v[152:153]
	v_subbrev_co_u32_e32 v169, vcc, 0, v152, vcc
	v_sub_u32_e32 v152, 0, v169
	v_ldexp_f32 v149, v149, v152
	v_ldexp_f32 v151, v151, v152
	v_pk_add_f32 v[152:153], v[148:149], 1.0 op_sel_hi:[1,0]
	v_pk_add_f32 v[160:161], v[148:149], -1.0 op_sel_hi:[1,0]
	v_pk_add_f32 v[154:155], v[152:153], -1.0 op_sel_hi:[1,0]
	v_pk_add_f32 v[162:163], v[160:161], 1.0 op_sel_hi:[1,0]
	v_pk_add_f32 v[154:155], v[148:149], v[154:155] neg_lo:[0,1] neg_hi:[0,1]
	v_pk_add_f32 v[148:149], v[148:149], v[162:163] neg_lo:[0,1] neg_hi:[0,1]
	v_pk_add_f32 v[154:155], v[150:151], v[154:155]
	v_pk_add_f32 v[148:149], v[150:151], v[148:149]
	v_pk_add_f32 v[156:157], v[152:153], v[154:155]
	v_pk_add_f32 v[150:151], v[160:161], v[148:149]
	v_rcp_f32_e32 v158, v156
	v_rcp_f32_e32 v159, v157
	v_pk_add_f32 v[152:153], v[156:157], v[152:153] neg_lo:[0,1] neg_hi:[0,1]
	v_pk_add_f32 v[160:161], v[150:151], v[160:161] neg_lo:[0,1] neg_hi:[0,1]
	v_pk_add_f32 v[152:153], v[154:155], v[152:153] neg_lo:[0,1] neg_hi:[0,1]
	v_pk_mul_f32 v[154:155], v[150:151], v[158:159]
	v_pk_add_f32 v[148:149], v[148:149], v[160:161] neg_lo:[0,1] neg_hi:[0,1]
	v_pk_mul_f32 v[160:161], v[156:157], v[154:155]
	v_cmp_neq_f32_e32 vcc, s3, v182
	v_pk_fma_f32 v[162:163], v[154:155], v[156:157], v[160:161] neg_lo:[0,0,1] neg_hi:[0,0,1]
	v_cmp_lt_f32_e64 s[0:1], |v205|, s4
	v_pk_fma_f32 v[162:163], v[154:155], v[152:153], v[162:163]
	s_nop 0
	v_pk_add_f32 v[164:165], v[160:161], v[162:163]
	s_nop 0
	v_pk_add_f32 v[166:167], v[150:151], v[164:165] neg_lo:[0,1] neg_hi:[0,1]
	v_pk_add_f32 v[160:161], v[164:165], v[160:161] neg_lo:[0,1] neg_hi:[0,1]
	v_pk_add_f32 v[150:151], v[150:151], v[166:167] neg_lo:[0,1] neg_hi:[0,1]
	s_nop 0
	v_pk_add_f32 v[150:151], v[150:151], v[164:165] neg_lo:[0,1] neg_hi:[0,1]
	s_nop 0
	v_pk_add_f32 v[148:149], v[148:149], v[150:151]
	v_pk_add_f32 v[150:151], v[160:161], v[162:163] neg_lo:[0,1] neg_hi:[0,1]
	s_nop 0
	v_pk_add_f32 v[148:149], v[150:151], v[148:149]
	s_nop 0
	v_pk_add_f32 v[150:151], v[166:167], v[148:149]
	s_nop 0
	v_pk_mul_f32 v[160:161], v[158:159], v[150:151]
	s_nop 0
	v_pk_mul_f32 v[162:163], v[156:157], v[160:161]
	s_nop 0
	v_pk_fma_f32 v[156:157], v[160:161], v[156:157], v[162:163] neg_lo:[0,0,1] neg_hi:[0,0,1]
	s_nop 0
	v_pk_fma_f32 v[152:153], v[160:161], v[152:153], v[156:157]
	v_pk_add_f32 v[156:157], v[166:167], v[150:151] neg_lo:[0,1] neg_hi:[0,1]
	s_nop 0
	v_pk_add_f32 v[148:149], v[148:149], v[156:157]
	v_pk_add_f32 v[156:157], v[162:163], v[152:153]
	s_nop 0
	v_pk_add_f32 v[164:165], v[150:151], v[156:157] neg_lo:[0,1] neg_hi:[0,1]
	v_pk_add_f32 v[162:163], v[156:157], v[162:163] neg_lo:[0,1] neg_hi:[0,1]
	v_pk_add_f32 v[150:151], v[150:151], v[164:165] neg_lo:[0,1] neg_hi:[0,1]
	s_nop 0
	v_pk_add_f32 v[150:151], v[150:151], v[156:157] neg_lo:[0,1] neg_hi:[0,1]
	s_nop 0
	v_pk_add_f32 v[148:149], v[148:149], v[150:151]
	v_pk_add_f32 v[150:151], v[162:163], v[152:153] neg_lo:[0,1] neg_hi:[0,1]
	s_nop 0
	v_pk_add_f32 v[148:149], v[150:151], v[148:149]
	v_pk_add_f32 v[150:151], v[154:155], v[160:161]
	v_pk_add_f32 v[148:149], v[164:165], v[148:149]
	v_pk_add_f32 v[152:153], v[150:151], v[154:155] neg_lo:[0,1] neg_hi:[0,1]
	v_pk_mul_f32 v[148:149], v[158:159], v[148:149]
	v_pk_add_f32 v[152:153], v[160:161], v[152:153] neg_lo:[0,1] neg_hi:[0,1]
	s_nop 0
	v_pk_add_f32 v[148:149], v[152:153], v[148:149]
	s_nop 0
	v_pk_add_f32 v[152:153], v[150:151], v[148:149]
	s_nop 0
	v_pk_mul_f32 v[154:155], v[152:153], v[152:153]
	v_pk_add_f32 v[150:151], v[152:153], v[150:151] neg_lo:[0,1] neg_hi:[0,1]
	v_pk_fma_f32 v[156:157], v[154:155], s[6:7], v[142:143] op_sel_hi:[1,0,0]
	v_pk_add_f32 v[148:149], v[148:149], v[150:151] neg_lo:[0,1] neg_hi:[0,1]
	v_ldexp_f32 v150, v152, 1
	v_pk_fma_f32 v[156:157], v[154:155], v[156:157], s[8:9] op_sel_hi:[1,1,0]
	v_ldexp_f32 v151, v153, 1
	v_pk_mul_f32 v[152:153], v[152:153], v[154:155]
	v_cvt_f32_i32_e32 v155, v169
	v_cvt_f32_i32_e32 v154, v168
	v_pk_mul_f32 v[152:153], v[152:153], v[156:157]
	v_ldexp_f32 v159, v149, 1
	v_pk_add_f32 v[156:157], v[150:151], v[152:153]
	v_pk_mul_f32 v[160:161], v[154:155], s[36:37] op_sel_hi:[1,0]
	v_pk_add_f32 v[150:151], v[156:157], v[150:151] neg_lo:[0,1] neg_hi:[0,1]
	v_pk_fma_f32 v[162:163], v[154:155], s[36:37], v[160:161] op_sel_hi:[1,0,1] neg_lo:[0,0,1] neg_hi:[0,0,1]
	v_pk_add_f32 v[150:151], v[152:153], v[150:151] neg_lo:[0,1] neg_hi:[0,1]
	v_pk_fma_f32 v[154:155], v[154:155], s[10:11], v[162:163] op_sel_hi:[1,0,1]
	v_ldexp_f32 v148, v148, 1
	v_mov_b32_e32 v152, v160
; __device__ __forceinline__ float softplusf_(float x) { return fmaxf(x, 0.0f) + log1pf(__expf(-fabsf(x))); }
;     __device__ __forceinline__ void operator()(f32x4 (&acc)[2][2][4][2], const pg8::Unit& u, int wr, int wc, int fr, int fq) const {
;     ...
;             if (wc == 0) { const f32x4 b0 = *(const f32x4*)(dtb + cl0), b1 = *(const f32x4*)(dtb + cl0 + 4);
; #pragma unroll
;                 for (int ai = 0; ai < 2; ++ai)
; #pragma unroll
;                     for (int m = 0; m < 4; ++m) { const int row = row0 + ai * 128 + m * 16; const f32x4 v0 = acc[ai][0][m][0] + b0, v1 = acc[ai][0][m][1] + b1;
;                         float* d = DTA + (size_t)row * NH + cl0;
;                         *(f32x4*)d = (f32x4){softplusf_(v0[0]), softplusf_(v0[1]), softplusf_(v0[2]), softplusf_(v0[3])}; *(f32x4*)(d + 4) = (f32x4){softplusf_(v1[0]), softplusf_(v1[1]), softplusf_(v1[2]), softplusf_(v1[3])}; } }
	v_mov_b32_e32 v153, v151
	v_mov_b32_e32 v158, v154
	v_mov_b32_e32 v149, v159
	v_pk_add_f32 v[152:153], v[152:153], v[158:159]
	v_pk_add_f32 v[158:159], v[148:149], v[150:151]
	v_mov_b32_e32 v151, v157
	v_mov_b32_e32 v149, v159
	v_pk_add_f32 v[162:163], v[160:161], v[154:155]
	v_pk_add_f32 v[148:149], v[148:149], v[150:151]
	v_pk_add_f32 v[150:151], v[156:157], v[158:159]
	v_mov_b32_e32 v172, v156
	v_pk_add_f32 v[164:165], v[162:163], v[150:151]
	v_mov_b32_e32 v170, v150
	v_mov_b32_e32 v171, v165
	v_mov_b32_e32 v173, v163
	v_pk_add_f32 v[170:171], v[170:171], v[172:173] neg_lo:[0,1] neg_hi:[0,1]
	v_mov_b32_e32 v166, v164
	v_mov_b32_e32 v167, v163
	v_mov_b32_e32 v168, v162
	v_mov_b32_e32 v169, v161
	v_mov_b32_e32 v172, v162
	v_mov_b32_e32 v173, v165
	v_mov_b32_e32 v161, v171
	v_pk_add_f32 v[166:167], v[166:167], v[168:169] neg_lo:[0,1] neg_hi:[0,1]
	v_mov_b32_e32 v168, v150
	v_mov_b32_e32 v169, v155
	v_pk_add_f32 v[160:161], v[172:173], v[160:161] neg_lo:[0,1] neg_hi:[0,1]
	v_pk_add_f32 v[168:169], v[168:169], v[166:167] neg_lo:[0,1] neg_hi:[0,1]
	v_mov_b32_e32 v172, v160
	v_mov_b32_e32 v173, v167
	v_mov_b32_e32 v206, v164
	v_mov_b32_e32 v207, v151
	v_mov_b32_e32 v167, v157
	v_pk_add_f32 v[172:173], v[154:155], v[172:173] neg_lo:[0,1] neg_hi:[0,1]
	v_pk_add_f32 v[166:167], v[206:207], v[166:167] neg_lo:[0,1] neg_hi:[0,1]
	v_mov_b32_e32 v155, v163
	v_pk_add_f32 v[152:153], v[152:153], v[166:167] neg_lo:[0,1] neg_hi:[0,1]
	v_pk_add_f32 v[154:155], v[154:155], v[160:161] neg_lo:[0,1] neg_hi:[0,1]
	v_pk_add_f32 v[148:149], v[148:149], v[170:171] neg_lo:[0,1] neg_hi:[0,1]
	v_pk_add_f32 v[150:151], v[150:151], v[156:157] neg_lo:[0,1] neg_hi:[0,1]
	v_pk_add_f32 v[156:157], v[148:149], v[154:155]
	v_mov_b32_e32 v155, v169
	v_mov_b32_e32 v149, v153
	v_pk_add_f32 v[150:151], v[158:159], v[150:151] neg_lo:[0,1] neg_hi:[0,1]
	v_pk_add_f32 v[158:159], v[168:169], v[152:153]
	v_pk_add_f32 v[148:149], v[154:155], v[148:149]
	v_mov_b32_e32 v152, v156
	v_pk_add_f32 v[148:149], v[148:149], v[172:173] neg_lo:[0,1] neg_hi:[0,1]
	v_mov_b32_e32 v153, v159
	v_pk_add_f32 v[152:153], v[152:153], v[148:149] neg_lo:[0,1] neg_hi:[0,1]
	v_pk_add_f32 v[148:149], v[150:151], v[148:149] neg_lo:[0,1] neg_hi:[0,1]
	v_pk_add_f32 v[152:153], v[154:155], v[152:153] neg_lo:[0,1] neg_hi:[0,1]
	v_pk_add_f32 v[150:151], v[158:159], v[156:157]
	v_pk_add_f32 v[148:149], v[148:149], v[152:153]
	v_pk_add_f32 v[152:153], v[164:165], v[150:151]
	s_nop 0
	v_pk_add_f32 v[154:155], v[152:153], v[164:165] neg_lo:[0,1] neg_hi:[0,1]
	s_nop 0
	v_pk_add_f32 v[150:151], v[150:151], v[154:155] neg_lo:[0,1] neg_hi:[0,1]
	s_nop 0
	v_pk_add_f32 v[148:149], v[148:149], v[150:151]
	v_pk_add_f32 v[150:151], v[58:59], v[130:131]
	v_pk_add_f32 v[148:149], v[152:153], v[148:149]
	v_pk_add_f32 v[152:153], v[62:63], v[134:135]
	v_cndmask_b32_e32 v148, v252, v148, vcc
	v_cmp_neq_f32_e32 vcc, s3, v205
	s_nop 1
	v_cndmask_b32_e32 v149, v252, v149, vcc
	v_cmp_ngt_f32_e32 vcc, -1.0, v205
	s_nop 1
	v_cndmask_b32_e32 v149, v253, v149, vcc
	v_cmp_ngt_f32_e32 vcc, -1.0, v182
	s_nop 1
	v_cndmask_b32_e32 v148, v253, v148, vcc
	v_cmp_neq_f32_e32 vcc, -1.0, v182
	s_nop 1
	v_cndmask_b32_e32 v148, v244, v148, vcc
	v_cmp_neq_f32_e32 vcc, -1.0, v205
	s_nop 1
	v_cndmask_b32_e32 v149, v244, v149, vcc
	v_cmp_lt_f32_e64 vcc, |v182|, s4
	v_cndmask_b32_e64 v149, v149, v205, s[0:1]
	s_nop 0
	v_cndmask_b32_e32 v148, v148, v182, vcc
	v_pk_add_f32 v[140:141], v[140:141], v[148:149]
	global_store_dwordx4 v[146:147], v[138:141], off offset:16
	v_pk_add_f32 v[148:149], v[60:61], v[132:133]
	s_nop 0
	v_lshlrev_b64 v[138:139], 7, v[194:195]
	v_lshl_add_u64 v[146:147], v[144:145], 0, v[138:139]
	v_mul_f32_e64 v139, |v152|, s88
	v_exp_f32_e32 v182, v139
	v_max_f32_e32 v138, 0, v152
	v_pk_add_f32 v[140:141], v[64:65], v[136:137]
	v_add_f32_e32 v139, 1.0, v182
	v_add_f32_e32 v152, -1.0, v139
	v_sub_f32_e32 v154, v152, v139
	v_add_f32_e32 v154, 1.0, v154
	v_sub_f32_e32 v152, v182, v152
	v_add_f32_e32 v156, v152, v154
	v_frexp_mant_f32_e32 v152, v139
	v_cvt_f64_f32_e32 v[154:155], v139
	v_cmp_gt_f32_e32 vcc, s2, v152
	v_frexp_exp_i32_f64_e32 v152, v[154:155]
	s_nop 0
	v_subbrev_co_u32_e32 v172, vcc, 0, v152, vcc
	v_sub_u32_e32 v154, 0, v172
	v_ldexp_f32 v152, v139, v154
	v_max_f32_e32 v139, 0, v153
	v_mul_f32_e64 v153, |v153|, s88
	v_exp_f32_e32 v205, v153
	v_ldexp_f32 v154, v156, v154
	v_add_f32_e32 v153, 1.0, v205
	v_add_f32_e32 v155, -1.0, v153
	v_sub_f32_e32 v156, v155, v153
	v_add_f32_e32 v156, 1.0, v156
	v_sub_f32_e32 v155, v205, v155
	v_add_f32_e32 v155, v155, v156
	v_frexp_mant_f32_e32 v156, v153
	v_cmp_gt_f32_e32 vcc, s2, v156
	v_cvt_f64_f32_e32 v[156:157], v153
	v_frexp_exp_i32_f64_e32 v156, v[156:157]
	v_subbrev_co_u32_e32 v173, vcc, 0, v156, vcc
	v_sub_u32_e32 v156, 0, v173
	v_ldexp_f32 v153, v153, v156
	v_ldexp_f32 v155, v155, v156
	v_pk_add_f32 v[156:157], v[152:153], 1.0 op_sel_hi:[1,0]
	v_pk_add_f32 v[164:165], v[152:153], -1.0 op_sel_hi:[1,0]
	v_pk_add_f32 v[158:159], v[156:157], -1.0 op_sel_hi:[1,0]
	v_pk_add_f32 v[166:167], v[164:165], 1.0 op_sel_hi:[1,0]
	v_pk_add_f32 v[158:159], v[152:153], v[158:159] neg_lo:[0,1] neg_hi:[0,1]
	v_pk_add_f32 v[152:153], v[152:153], v[166:167] neg_lo:[0,1] neg_hi:[0,1]
	v_pk_add_f32 v[158:159], v[154:155], v[158:159]
	v_pk_add_f32 v[152:153], v[154:155], v[152:153]
	v_pk_add_f32 v[160:161], v[156:157], v[158:159]
	v_pk_add_f32 v[154:155], v[164:165], v[152:153]
	v_rcp_f32_e32 v162, v160
	v_rcp_f32_e32 v163, v161
	v_pk_add_f32 v[156:157], v[160:161], v[156:157] neg_lo:[0,1] neg_hi:[0,1]
	v_pk_add_f32 v[164:165], v[154:155], v[164:165] neg_lo:[0,1] neg_hi:[0,1]
; __device__ __forceinline__ float softplusf_(float x) { return fmaxf(x, 0.0f) + log1pf(__expf(-fabsf(x))); }
;     __device__ __forceinline__ void operator()(f32x4 (&acc)[2][2][4][2], const pg8::Unit& u, int wr, int wc, int fr, int fq) const {
;     ...
;                     for (int m = 0; m < 4; ++m) { const int row = row0 + ai * 128 + m * 16; const f32x4 v0 = acc[ai][0][m][0] + b0, v1 = acc[ai][0][m][1] + b1;
;                         float* d = DTA + (size_t)row * NH + cl0;
;                         *(f32x4*)d = (f32x4){softplusf_(v0[0]), softplusf_(v0[1]), softplusf_(v0[2]), softplusf_(v0[3])}; *(f32x4*)(d + 4) = (f32x4){softplusf_(v1[0]), softplusf_(v1[1]), softplusf_(v1[2]), softplusf_(v1[3])}; } }
	v_pk_add_f32 v[156:157], v[158:159], v[156:157] neg_lo:[0,1] neg_hi:[0,1]
	v_pk_mul_f32 v[158:159], v[154:155], v[162:163]
	v_pk_add_f32 v[152:153], v[152:153], v[164:165] neg_lo:[0,1] neg_hi:[0,1]
	v_pk_mul_f32 v[164:165], v[160:161], v[158:159]
	v_cmp_neq_f32_e32 vcc, s3, v182
	v_pk_fma_f32 v[166:167], v[158:159], v[160:161], v[164:165] neg_lo:[0,0,1] neg_hi:[0,0,1]
	v_cmp_lt_f32_e64 s[0:1], |v205|, s4
	v_pk_fma_f32 v[166:167], v[158:159], v[156:157], v[166:167]
	s_nop 0
	v_pk_add_f32 v[168:169], v[164:165], v[166:167]
	s_nop 0
	v_pk_add_f32 v[170:171], v[154:155], v[168:169] neg_lo:[0,1] neg_hi:[0,1]
	v_pk_add_f32 v[164:165], v[168:169], v[164:165] neg_lo:[0,1] neg_hi:[0,1]
	v_pk_add_f32 v[154:155], v[154:155], v[170:171] neg_lo:[0,1] neg_hi:[0,1]
	s_nop 0
	v_pk_add_f32 v[154:155], v[154:155], v[168:169] neg_lo:[0,1] neg_hi:[0,1]
	s_nop 0
	v_pk_add_f32 v[152:153], v[152:153], v[154:155]
	v_pk_add_f32 v[154:155], v[164:165], v[166:167] neg_lo:[0,1] neg_hi:[0,1]
	s_nop 0
	v_pk_add_f32 v[152:153], v[154:155], v[152:153]
	s_nop 0
	v_pk_add_f32 v[154:155], v[170:171], v[152:153]
	s_nop 0
	v_pk_mul_f32 v[164:165], v[162:163], v[154:155]
	s_nop 0
	v_pk_mul_f32 v[166:167], v[160:161], v[164:165]
	s_nop 0
	v_pk_fma_f32 v[160:161], v[164:165], v[160:161], v[166:167] neg_lo:[0,0,1] neg_hi:[0,0,1]
	s_nop 0
	v_pk_fma_f32 v[156:157], v[164:165], v[156:157], v[160:161]
	v_pk_add_f32 v[160:161], v[170:171], v[154:155] neg_lo:[0,1] neg_hi:[0,1]
	s_nop 0
	v_pk_add_f32 v[152:153], v[152:153], v[160:161]
	v_pk_add_f32 v[160:161], v[166:167], v[156:157]
	s_nop 0
	v_pk_add_f32 v[168:169], v[154:155], v[160:161] neg_lo:[0,1] neg_hi:[0,1]
	v_pk_add_f32 v[166:167], v[160:161], v[166:167] neg_lo:[0,1] neg_hi:[0,1]
	v_pk_add_f32 v[154:155], v[154:155], v[168:169] neg_lo:[0,1] neg_hi:[0,1]
	s_nop 0
	v_pk_add_f32 v[154:155], v[154:155], v[160:161] neg_lo:[0,1] neg_hi:[0,1]
	s_nop 0
	v_pk_add_f32 v[152:153], v[152:153], v[154:155]
	v_pk_add_f32 v[154:155], v[166:167], v[156:157] neg_lo:[0,1] neg_hi:[0,1]
	s_nop 0
	v_pk_add_f32 v[152:153], v[154:155], v[152:153]
	v_pk_add_f32 v[154:155], v[158:159], v[164:165]
	v_pk_add_f32 v[152:153], v[168:169], v[152:153]
	v_pk_add_f32 v[156:157], v[154:155], v[158:159] neg_lo:[0,1] neg_hi:[0,1]
	v_pk_mul_f32 v[152:153], v[162:163], v[152:153]
	v_pk_add_f32 v[156:157], v[164:165], v[156:157] neg_lo:[0,1] neg_hi:[0,1]
	s_nop 0
	v_pk_add_f32 v[152:153], v[156:157], v[152:153]
	s_nop 0
	v_pk_add_f32 v[156:157], v[154:155], v[152:153]
	s_nop 0
	v_pk_mul_f32 v[158:159], v[156:157], v[156:157]
	v_pk_add_f32 v[154:155], v[156:157], v[154:155] neg_lo:[0,1] neg_hi:[0,1]
	v_pk_fma_f32 v[160:161], v[158:159], s[6:7], v[142:143] op_sel_hi:[1,0,0]
	v_pk_add_f32 v[152:153], v[152:153], v[154:155] neg_lo:[0,1] neg_hi:[0,1]
	v_ldexp_f32 v154, v156, 1
	v_pk_fma_f32 v[160:161], v[158:159], v[160:161], s[8:9] op_sel_hi:[1,1,0]
	v_ldexp_f32 v155, v157, 1
	v_pk_mul_f32 v[156:157], v[156:157], v[158:159]
	v_cvt_f32_i32_e32 v159, v173
	v_cvt_f32_i32_e32 v158, v172
	v_pk_mul_f32 v[156:157], v[156:157], v[160:161]
	v_ldexp_f32 v163, v153, 1
	v_pk_add_f32 v[160:161], v[154:155], v[156:157]
	v_pk_mul_f32 v[164:165], v[158:159], s[36:37] op_sel_hi:[1,0]
	v_pk_add_f32 v[154:155], v[160:161], v[154:155] neg_lo:[0,1] neg_hi:[0,1]
	v_pk_fma_f32 v[166:167], v[158:159], s[36:37], v[164:165] op_sel_hi:[1,0,1] neg_lo:[0,0,1] neg_hi:[0,0,1]
	v_pk_add_f32 v[154:155], v[156:157], v[154:155] neg_lo:[0,1] neg_hi:[0,1]
	v_pk_fma_f32 v[158:159], v[158:159], s[10:11], v[166:167] op_sel_hi:[1,0,1]
	v_ldexp_f32 v152, v152, 1
	v_mov_b32_e32 v156, v164
	v_mov_b32_e32 v157, v155
	v_mov_b32_e32 v162, v158
	v_mov_b32_e32 v153, v163
	v_pk_add_f32 v[156:157], v[156:157], v[162:163]
	v_pk_add_f32 v[162:163], v[152:153], v[154:155]
	v_mov_b32_e32 v155, v161
	v_mov_b32_e32 v153, v163
	v_pk_add_f32 v[166:167], v[164:165], v[158:159]
	v_pk_add_f32 v[152:153], v[152:153], v[154:155]
	v_pk_add_f32 v[154:155], v[160:161], v[162:163]
	v_mov_b32_e32 v208, v160
	v_pk_add_f32 v[168:169], v[166:167], v[154:155]
	v_mov_b32_e32 v206, v154
	v_mov_b32_e32 v207, v169
	v_mov_b32_e32 v209, v167
	v_pk_add_f32 v[206:207], v[206:207], v[208:209] neg_lo:[0,1] neg_hi:[0,1]
	v_mov_b32_e32 v170, v168
	v_mov_b32_e32 v171, v167
	v_mov_b32_e32 v172, v166
	v_mov_b32_e32 v173, v165
	v_mov_b32_e32 v208, v166
	v_mov_b32_e32 v209, v169
	v_mov_b32_e32 v165, v207
	v_pk_add_f32 v[170:171], v[170:171], v[172:173] neg_lo:[0,1] neg_hi:[0,1]
	v_mov_b32_e32 v172, v154
	v_mov_b32_e32 v173, v159
	v_pk_add_f32 v[164:165], v[208:209], v[164:165] neg_lo:[0,1] neg_hi:[0,1]
	v_pk_add_f32 v[172:173], v[172:173], v[170:171] neg_lo:[0,1] neg_hi:[0,1]
	v_mov_b32_e32 v208, v164
	v_mov_b32_e32 v209, v171
	v_mov_b32_e32 v210, v168
	v_mov_b32_e32 v211, v155
	v_mov_b32_e32 v171, v161
	v_pk_add_f32 v[208:209], v[158:159], v[208:209] neg_lo:[0,1] neg_hi:[0,1]
	v_pk_add_f32 v[170:171], v[210:211], v[170:171] neg_lo:[0,1] neg_hi:[0,1]
	v_mov_b32_e32 v159, v167
	v_pk_add_f32 v[156:157], v[156:157], v[170:171] neg_lo:[0,1] neg_hi:[0,1]
	v_pk_add_f32 v[158:159], v[158:159], v[164:165] neg_lo:[0,1] neg_hi:[0,1]
	v_pk_add_f32 v[152:153], v[152:153], v[206:207] neg_lo:[0,1] neg_hi:[0,1]
	v_pk_add_f32 v[154:155], v[154:155], v[160:161] neg_lo:[0,1] neg_hi:[0,1]
	v_pk_add_f32 v[160:161], v[152:153], v[158:159]
	v_mov_b32_e32 v159, v173
	v_mov_b32_e32 v153, v157
	v_pk_add_f32 v[154:155], v[162:163], v[154:155] neg_lo:[0,1] neg_hi:[0,1]
	v_pk_add_f32 v[162:163], v[172:173], v[156:157]
	v_pk_add_f32 v[152:153], v[158:159], v[152:153]
	v_mov_b32_e32 v156, v160
	v_pk_add_f32 v[152:153], v[152:153], v[208:209] neg_lo:[0,1] neg_hi:[0,1]
	v_mov_b32_e32 v157, v163
; __device__ __forceinline__ float softplusf_(float x) { return fmaxf(x, 0.0f) + log1pf(__expf(-fabsf(x))); }
;     __device__ __forceinline__ void operator()(f32x4 (&acc)[2][2][4][2], const pg8::Unit& u, int wr, int wc, int fr, int fq) const {
;     ...
;                     for (int m = 0; m < 4; ++m) { const int row = row0 + ai * 128 + m * 16; const f32x4 v0 = acc[ai][0][m][0] + b0, v1 = acc[ai][0][m][1] + b1;
;                         float* d = DTA + (size_t)row * NH + cl0;
;                         *(f32x4*)d = (f32x4){softplusf_(v0[0]), softplusf_(v0[1]), softplusf_(v0[2]), softplusf_(v0[3])}; *(f32x4*)(d + 4) = (f32x4){softplusf_(v1[0]), softplusf_(v1[1]), softplusf_(v1[2]), softplusf_(v1[3])}; } }
	v_pk_add_f32 v[156:157], v[156:157], v[152:153] neg_lo:[0,1] neg_hi:[0,1]
	v_pk_add_f32 v[152:153], v[154:155], v[152:153] neg_lo:[0,1] neg_hi:[0,1]
	v_pk_add_f32 v[156:157], v[158:159], v[156:157] neg_lo:[0,1] neg_hi:[0,1]
	v_pk_add_f32 v[154:155], v[162:163], v[160:161]
	v_pk_add_f32 v[152:153], v[152:153], v[156:157]
	v_pk_add_f32 v[156:157], v[168:169], v[154:155]
	s_nop 0
	v_pk_add_f32 v[158:159], v[156:157], v[168:169] neg_lo:[0,1] neg_hi:[0,1]
	s_nop 0
	v_pk_add_f32 v[154:155], v[154:155], v[158:159] neg_lo:[0,1] neg_hi:[0,1]
	s_nop 0
	v_pk_add_f32 v[152:153], v[152:153], v[154:155]
	s_nop 0
	v_pk_add_f32 v[152:153], v[156:157], v[152:153]
	s_nop 0
	v_cndmask_b32_e32 v152, v252, v152, vcc
	v_cmp_neq_f32_e32 vcc, s3, v205
	s_nop 1
	v_cndmask_b32_e32 v153, v252, v153, vcc
	v_cmp_ngt_f32_e32 vcc, -1.0, v205
	s_nop 1
	v_cndmask_b32_e32 v153, v253, v153, vcc
	v_cmp_ngt_f32_e32 vcc, -1.0, v182
	s_nop 1
	v_cndmask_b32_e32 v152, v253, v152, vcc
	v_cmp_neq_f32_e32 vcc, -1.0, v182
	s_nop 1
	v_cndmask_b32_e32 v152, v244, v152, vcc
	v_cmp_neq_f32_e32 vcc, -1.0, v205
	s_nop 1
	v_cndmask_b32_e32 v153, v244, v153, vcc
	v_cmp_lt_f32_e64 vcc, |v182|, s4
	v_cndmask_b32_e64 v153, v153, v205, s[0:1]
	s_nop 0
	v_cndmask_b32_e32 v152, v152, v182, vcc
	v_pk_add_f32 v[138:139], v[138:139], v[152:153]
	v_max_f32_e32 v152, 0, v140
	v_mul_f32_e64 v140, |v140|, s88
	v_exp_f32_e32 v182, v140
	s_nop 0
	v_add_f32_e32 v140, 1.0, v182
	v_add_f32_e32 v153, -1.0, v140
	v_sub_f32_e32 v154, v153, v140
	v_add_f32_e32 v154, 1.0, v154
	v_sub_f32_e32 v153, v182, v153
	v_add_f32_e32 v153, v153, v154
	v_frexp_mant_f32_e32 v154, v140
	v_cmp_gt_f32_e32 vcc, s2, v154
	v_cvt_f64_f32_e32 v[154:155], v140
	v_frexp_exp_i32_f64_e32 v154, v[154:155]
	v_subbrev_co_u32_e32 v172, vcc, 0, v154, vcc
	v_sub_u32_e32 v154, 0, v172
	v_ldexp_f32 v140, v140, v154
	v_ldexp_f32 v154, v153, v154
	v_max_f32_e32 v153, 0, v141
	v_mul_f32_e64 v141, |v141|, s88
	v_exp_f32_e32 v205, v141
	s_nop 0
	v_add_f32_e32 v141, 1.0, v205
	v_add_f32_e32 v155, -1.0, v141
	v_sub_f32_e32 v156, v155, v141
	v_add_f32_e32 v156, 1.0, v156
	v_sub_f32_e32 v155, v205, v155
	v_add_f32_e32 v155, v155, v156
	v_frexp_mant_f32_e32 v156, v141
	v_cmp_gt_f32_e32 vcc, s2, v156
	v_cvt_f64_f32_e32 v[156:157], v141
	v_frexp_exp_i32_f64_e32 v156, v[156:157]
	v_subbrev_co_u32_e32 v173, vcc, 0, v156, vcc
	v_sub_u32_e32 v156, 0, v173
	v_ldexp_f32 v141, v141, v156
	v_ldexp_f32 v155, v155, v156
	v_pk_add_f32 v[156:157], v[140:141], 1.0 op_sel_hi:[1,0]
	v_pk_add_f32 v[164:165], v[140:141], -1.0 op_sel_hi:[1,0]
	v_pk_add_f32 v[158:159], v[156:157], -1.0 op_sel_hi:[1,0]
	v_pk_add_f32 v[166:167], v[164:165], 1.0 op_sel_hi:[1,0]
	v_pk_add_f32 v[158:159], v[140:141], v[158:159] neg_lo:[0,1] neg_hi:[0,1]
	v_pk_add_f32 v[140:141], v[140:141], v[166:167] neg_lo:[0,1] neg_hi:[0,1]
	v_pk_add_f32 v[158:159], v[154:155], v[158:159]
	v_pk_add_f32 v[140:141], v[154:155], v[140:141]
	v_pk_add_f32 v[160:161], v[156:157], v[158:159]
	v_pk_add_f32 v[154:155], v[164:165], v[140:141]
	v_rcp_f32_e32 v162, v160
	v_rcp_f32_e32 v163, v161
	v_pk_add_f32 v[156:157], v[160:161], v[156:157] neg_lo:[0,1] neg_hi:[0,1]
	v_pk_add_f32 v[164:165], v[154:155], v[164:165] neg_lo:[0,1] neg_hi:[0,1]
	v_pk_add_f32 v[156:157], v[158:159], v[156:157] neg_lo:[0,1] neg_hi:[0,1]
	v_pk_mul_f32 v[158:159], v[154:155], v[162:163]
	v_pk_add_f32 v[140:141], v[140:141], v[164:165] neg_lo:[0,1] neg_hi:[0,1]
	v_pk_mul_f32 v[164:165], v[160:161], v[158:159]
	v_cmp_neq_f32_e32 vcc, s3, v182
	v_pk_fma_f32 v[166:167], v[158:159], v[160:161], v[164:165] neg_lo:[0,0,1] neg_hi:[0,0,1]
	v_cmp_lt_f32_e64 s[0:1], |v205|, s4
	v_pk_fma_f32 v[166:167], v[158:159], v[156:157], v[166:167]
	s_nop 0
	v_pk_add_f32 v[168:169], v[164:165], v[166:167]
	s_nop 0
	v_pk_add_f32 v[170:171], v[154:155], v[168:169] neg_lo:[0,1] neg_hi:[0,1]
	v_pk_add_f32 v[164:165], v[168:169], v[164:165] neg_lo:[0,1] neg_hi:[0,1]
	v_pk_add_f32 v[154:155], v[154:155], v[170:171] neg_lo:[0,1] neg_hi:[0,1]
	s_nop 0
	v_pk_add_f32 v[154:155], v[154:155], v[168:169] neg_lo:[0,1] neg_hi:[0,1]
	s_nop 0
	v_pk_add_f32 v[140:141], v[140:141], v[154:155]
	v_pk_add_f32 v[154:155], v[164:165], v[166:167] neg_lo:[0,1] neg_hi:[0,1]
	s_nop 0
	v_pk_add_f32 v[140:141], v[154:155], v[140:141]
	s_nop 0
	v_pk_add_f32 v[154:155], v[170:171], v[140:141]
	s_nop 0
	v_pk_mul_f32 v[164:165], v[162:163], v[154:155]
	s_nop 0
	v_pk_mul_f32 v[166:167], v[160:161], v[164:165]
	s_nop 0
	v_pk_fma_f32 v[160:161], v[164:165], v[160:161], v[166:167] neg_lo:[0,0,1] neg_hi:[0,0,1]
	s_nop 0
	v_pk_fma_f32 v[156:157], v[164:165], v[156:157], v[160:161]
	v_pk_add_f32 v[160:161], v[170:171], v[154:155] neg_lo:[0,1] neg_hi:[0,1]
	s_nop 0
	v_pk_add_f32 v[140:141], v[140:141], v[160:161]
	v_pk_add_f32 v[160:161], v[166:167], v[156:157]
	s_nop 0
	v_pk_add_f32 v[168:169], v[154:155], v[160:161] neg_lo:[0,1] neg_hi:[0,1]
	v_pk_add_f32 v[166:167], v[160:161], v[166:167] neg_lo:[0,1] neg_hi:[0,1]
	v_pk_add_f32 v[154:155], v[154:155], v[168:169] neg_lo:[0,1] neg_hi:[0,1]
	s_nop 0
	v_pk_add_f32 v[154:155], v[154:155], v[160:161] neg_lo:[0,1] neg_hi:[0,1]
	s_nop 0
	v_pk_add_f32 v[140:141], v[140:141], v[154:155]
	v_pk_add_f32 v[154:155], v[166:167], v[156:157] neg_lo:[0,1] neg_hi:[0,1]
	s_nop 0
	v_pk_add_f32 v[140:141], v[154:155], v[140:141]
	v_pk_add_f32 v[154:155], v[158:159], v[164:165]
	v_pk_add_f32 v[140:141], v[168:169], v[140:141]
	v_pk_add_f32 v[156:157], v[154:155], v[158:159] neg_lo:[0,1] neg_hi:[0,1]
	v_pk_mul_f32 v[140:141], v[162:163], v[140:141]
	v_pk_add_f32 v[156:157], v[164:165], v[156:157] neg_lo:[0,1] neg_hi:[0,1]
	s_nop 0
	v_pk_add_f32 v[140:141], v[156:157], v[140:141]
; __device__ __forceinline__ float softplusf_(float x) { return fmaxf(x, 0.0f) + log1pf(__expf(-fabsf(x))); }
;     __device__ __forceinline__ void operator()(f32x4 (&acc)[2][2][4][2], const pg8::Unit& u, int wr, int wc, int fr, int fq) const {
;     ...
;             if (wc == 0) { const f32x4 b0 = *(const f32x4*)(dtb + cl0), b1 = *(const f32x4*)(dtb + cl0 + 4);
; #pragma unroll
;                 for (int ai = 0; ai < 2; ++ai)
; #pragma unroll
;                     for (int m = 0; m < 4; ++m) { const int row = row0 + ai * 128 + m * 16; const f32x4 v0 = acc[ai][0][m][0] + b0, v1 = acc[ai][0][m][1] + b1;
;                         float* d = DTA + (size_t)row * NH + cl0;
;                         *(f32x4*)d = (f32x4){softplusf_(v0[0]), softplusf_(v0[1]), softplusf_(v0[2]), softplusf_(v0[3])}; *(f32x4*)(d + 4) = (f32x4){softplusf_(v1[0]), softplusf_(v1[1]), softplusf_(v1[2]), softplusf_(v1[3])}; } }
	s_nop 0
	v_pk_add_f32 v[156:157], v[154:155], v[140:141]
	s_nop 0
	v_pk_mul_f32 v[158:159], v[156:157], v[156:157]
	v_pk_add_f32 v[154:155], v[156:157], v[154:155] neg_lo:[0,1] neg_hi:[0,1]
	v_pk_fma_f32 v[160:161], v[158:159], s[6:7], v[142:143] op_sel_hi:[1,0,0]
	v_pk_add_f32 v[140:141], v[140:141], v[154:155] neg_lo:[0,1] neg_hi:[0,1]
	v_ldexp_f32 v154, v156, 1
	v_pk_fma_f32 v[160:161], v[158:159], v[160:161], s[8:9] op_sel_hi:[1,1,0]
	v_ldexp_f32 v155, v157, 1
	v_pk_mul_f32 v[156:157], v[156:157], v[158:159]
	v_cvt_f32_i32_e32 v159, v173
	v_cvt_f32_i32_e32 v158, v172
	v_pk_mul_f32 v[156:157], v[156:157], v[160:161]
	v_ldexp_f32 v163, v141, 1
	v_pk_add_f32 v[160:161], v[154:155], v[156:157]
	v_pk_mul_f32 v[164:165], v[158:159], s[36:37] op_sel_hi:[1,0]
	v_pk_add_f32 v[154:155], v[160:161], v[154:155] neg_lo:[0,1] neg_hi:[0,1]
	v_pk_fma_f32 v[166:167], v[158:159], s[36:37], v[164:165] op_sel_hi:[1,0,1] neg_lo:[0,0,1] neg_hi:[0,0,1]
	v_pk_add_f32 v[154:155], v[156:157], v[154:155] neg_lo:[0,1] neg_hi:[0,1]
	v_pk_fma_f32 v[158:159], v[158:159], s[10:11], v[166:167] op_sel_hi:[1,0,1]
	v_ldexp_f32 v140, v140, 1
	v_mov_b32_e32 v156, v164
	v_mov_b32_e32 v157, v155
	v_mov_b32_e32 v162, v158
	v_mov_b32_e32 v141, v163
	v_pk_add_f32 v[156:157], v[156:157], v[162:163]
	v_pk_add_f32 v[162:163], v[140:141], v[154:155]
	v_mov_b32_e32 v155, v161
	v_mov_b32_e32 v141, v163
	v_pk_add_f32 v[166:167], v[164:165], v[158:159]
	v_pk_add_f32 v[140:141], v[140:141], v[154:155]
	v_pk_add_f32 v[154:155], v[160:161], v[162:163]
	v_mov_b32_e32 v208, v160
	v_pk_add_f32 v[168:169], v[166:167], v[154:155]
	v_mov_b32_e32 v206, v154
	v_mov_b32_e32 v207, v169
	v_mov_b32_e32 v209, v167
	v_pk_add_f32 v[206:207], v[206:207], v[208:209] neg_lo:[0,1] neg_hi:[0,1]
	v_mov_b32_e32 v170, v168
	v_mov_b32_e32 v171, v167
	v_mov_b32_e32 v172, v166
	v_mov_b32_e32 v173, v165
	v_mov_b32_e32 v208, v166
	v_mov_b32_e32 v209, v169
	v_mov_b32_e32 v165, v207
	v_pk_add_f32 v[170:171], v[170:171], v[172:173] neg_lo:[0,1] neg_hi:[0,1]
	v_mov_b32_e32 v172, v154
	v_mov_b32_e32 v173, v159
	v_pk_add_f32 v[164:165], v[208:209], v[164:165] neg_lo:[0,1] neg_hi:[0,1]
	v_pk_add_f32 v[172:173], v[172:173], v[170:171] neg_lo:[0,1] neg_hi:[0,1]
	v_mov_b32_e32 v208, v164
	v_mov_b32_e32 v209, v171
	v_mov_b32_e32 v210, v168
	v_mov_b32_e32 v211, v155
	v_mov_b32_e32 v171, v161
	v_pk_add_f32 v[208:209], v[158:159], v[208:209] neg_lo:[0,1] neg_hi:[0,1]
	v_pk_add_f32 v[170:171], v[210:211], v[170:171] neg_lo:[0,1] neg_hi:[0,1]
	v_mov_b32_e32 v159, v167
	v_pk_add_f32 v[156:157], v[156:157], v[170:171] neg_lo:[0,1] neg_hi:[0,1]
	v_pk_add_f32 v[158:159], v[158:159], v[164:165] neg_lo:[0,1] neg_hi:[0,1]
	v_pk_add_f32 v[140:141], v[140:141], v[206:207] neg_lo:[0,1] neg_hi:[0,1]
	v_pk_add_f32 v[154:155], v[154:155], v[160:161] neg_lo:[0,1] neg_hi:[0,1]
	v_pk_add_f32 v[160:161], v[140:141], v[158:159]
	v_mov_b32_e32 v159, v173
	v_mov_b32_e32 v141, v157
	v_pk_add_f32 v[154:155], v[162:163], v[154:155] neg_lo:[0,1] neg_hi:[0,1]
	v_pk_add_f32 v[162:163], v[172:173], v[156:157]
	v_pk_add_f32 v[140:141], v[158:159], v[140:141]
	v_mov_b32_e32 v156, v160
	v_pk_add_f32 v[140:141], v[140:141], v[208:209] neg_lo:[0,1] neg_hi:[0,1]
	v_mov_b32_e32 v157, v163
	v_pk_add_f32 v[156:157], v[156:157], v[140:141] neg_lo:[0,1] neg_hi:[0,1]
	v_pk_add_f32 v[140:141], v[154:155], v[140:141] neg_lo:[0,1] neg_hi:[0,1]
	v_pk_add_f32 v[156:157], v[158:159], v[156:157] neg_lo:[0,1] neg_hi:[0,1]
	v_pk_add_f32 v[154:155], v[162:163], v[160:161]
	v_pk_add_f32 v[140:141], v[140:141], v[156:157]
	v_pk_add_f32 v[156:157], v[168:169], v[154:155]
	s_nop 0
	v_pk_add_f32 v[158:159], v[156:157], v[168:169] neg_lo:[0,1] neg_hi:[0,1]
	s_nop 0
	v_pk_add_f32 v[154:155], v[154:155], v[158:159] neg_lo:[0,1] neg_hi:[0,1]
	s_nop 0
	v_pk_add_f32 v[140:141], v[140:141], v[154:155]
	s_nop 0
	v_pk_add_f32 v[140:141], v[156:157], v[140:141]
	s_nop 0
	v_cndmask_b32_e32 v140, v252, v140, vcc
	v_cmp_neq_f32_e32 vcc, s3, v205
	s_nop 1
	v_cndmask_b32_e32 v141, v252, v141, vcc
	v_cmp_ngt_f32_e32 vcc, -1.0, v205
	s_nop 1
	v_cndmask_b32_e32 v141, v253, v141, vcc
	v_cmp_ngt_f32_e32 vcc, -1.0, v182
	s_nop 1
	v_cndmask_b32_e32 v140, v253, v140, vcc
	v_cmp_neq_f32_e32 vcc, -1.0, v182
	s_nop 1
	v_cndmask_b32_e32 v140, v244, v140, vcc
	v_cmp_neq_f32_e32 vcc, -1.0, v205
	s_nop 1
	v_cndmask_b32_e32 v141, v244, v141, vcc
	v_cmp_lt_f32_e64 vcc, |v182|, s4
	v_cndmask_b32_e64 v141, v141, v205, s[0:1]
	s_nop 0
	v_cndmask_b32_e32 v140, v140, v182, vcc
	v_pk_add_f32 v[140:141], v[152:153], v[140:141]
	global_store_dwordx4 v[146:147], v[138:141], off
	s_nop 1
	v_mul_f32_e64 v139, |v150|, s88
	v_exp_f32_e32 v182, v139
	v_max_f32_e32 v138, 0, v150
	v_add_f32_e32 v139, 1.0, v182
	v_add_f32_e32 v140, -1.0, v139
	v_sub_f32_e32 v141, v140, v139
	v_add_f32_e32 v141, 1.0, v141
	v_sub_f32_e32 v140, v182, v140
	v_add_f32_e32 v150, v140, v141
	v_frexp_mant_f32_e32 v140, v139
	v_cmp_gt_f32_e32 vcc, s2, v140
	v_cvt_f64_f32_e32 v[140:141], v139
	v_frexp_exp_i32_f64_e32 v140, v[140:141]
	v_subbrev_co_u32_e32 v168, vcc, 0, v140, vcc
	v_sub_u32_e32 v141, 0, v168
	v_ldexp_f32 v140, v139, v141
	v_ldexp_f32 v150, v150, v141
	v_mul_f32_e64 v141, |v151|, s88
	v_exp_f32_e32 v205, v141
	v_max_f32_e32 v139, 0, v151
	v_add_f32_e32 v141, 1.0, v205
	v_add_f32_e32 v151, -1.0, v141
	v_sub_f32_e32 v152, v151, v141
	v_add_f32_e32 v152, 1.0, v152
	v_sub_f32_e32 v151, v205, v151
	v_add_f32_e32 v151, v151, v152
	v_frexp_mant_f32_e32 v152, v141
	v_cmp_gt_f32_e32 vcc, s2, v152
	v_cvt_f64_f32_e32 v[152:153], v141
	v_frexp_exp_i32_f64_e32 v152, v[152:153]
	v_subbrev_co_u32_e32 v169, vcc, 0, v152, vcc
	v_sub_u32_e32 v152, 0, v169
; __device__ __forceinline__ float softplusf_(float x) { return fmaxf(x, 0.0f) + log1pf(__expf(-fabsf(x))); }
;     __device__ __forceinline__ void operator()(f32x4 (&acc)[2][2][4][2], const pg8::Unit& u, int wr, int wc, int fr, int fq) const {
;     ...
;                     for (int m = 0; m < 4; ++m) { const int row = row0 + ai * 128 + m * 16; const f32x4 v0 = acc[ai][0][m][0] + b0, v1 = acc[ai][0][m][1] + b1;
;                         float* d = DTA + (size_t)row * NH + cl0;
;                         *(f32x4*)d = (f32x4){softplusf_(v0[0]), softplusf_(v0[1]), softplusf_(v0[2]), softplusf_(v0[3])}; *(f32x4*)(d + 4) = (f32x4){softplusf_(v1[0]), softplusf_(v1[1]), softplusf_(v1[2]), softplusf_(v1[3])}; } }
	v_ldexp_f32 v141, v141, v152
	v_ldexp_f32 v151, v151, v152
	v_pk_add_f32 v[152:153], v[140:141], 1.0 op_sel_hi:[1,0]
	v_pk_add_f32 v[160:161], v[140:141], -1.0 op_sel_hi:[1,0]
	v_pk_add_f32 v[154:155], v[152:153], -1.0 op_sel_hi:[1,0]
	v_pk_add_f32 v[162:163], v[160:161], 1.0 op_sel_hi:[1,0]
	v_pk_add_f32 v[154:155], v[140:141], v[154:155] neg_lo:[0,1] neg_hi:[0,1]
	v_pk_add_f32 v[140:141], v[140:141], v[162:163] neg_lo:[0,1] neg_hi:[0,1]
	v_pk_add_f32 v[154:155], v[150:151], v[154:155]
	v_pk_add_f32 v[140:141], v[150:151], v[140:141]
	v_pk_add_f32 v[156:157], v[152:153], v[154:155]
	v_pk_add_f32 v[150:151], v[160:161], v[140:141]
	v_rcp_f32_e32 v158, v156
	v_rcp_f32_e32 v159, v157
	v_pk_add_f32 v[152:153], v[156:157], v[152:153] neg_lo:[0,1] neg_hi:[0,1]
	v_pk_add_f32 v[160:161], v[150:151], v[160:161] neg_lo:[0,1] neg_hi:[0,1]
	v_pk_add_f32 v[152:153], v[154:155], v[152:153] neg_lo:[0,1] neg_hi:[0,1]
	v_pk_mul_f32 v[154:155], v[150:151], v[158:159]
	v_pk_add_f32 v[140:141], v[140:141], v[160:161] neg_lo:[0,1] neg_hi:[0,1]
	v_pk_mul_f32 v[160:161], v[156:157], v[154:155]
	v_cmp_neq_f32_e32 vcc, s3, v182
	v_pk_fma_f32 v[162:163], v[154:155], v[156:157], v[160:161] neg_lo:[0,0,1] neg_hi:[0,0,1]
	v_cmp_lt_f32_e64 s[0:1], |v205|, s4
	v_pk_fma_f32 v[162:163], v[154:155], v[152:153], v[162:163]
	s_nop 0
	v_pk_add_f32 v[164:165], v[160:161], v[162:163]
	s_nop 0
	v_pk_add_f32 v[166:167], v[150:151], v[164:165] neg_lo:[0,1] neg_hi:[0,1]
	v_pk_add_f32 v[160:161], v[164:165], v[160:161] neg_lo:[0,1] neg_hi:[0,1]
	v_pk_add_f32 v[150:151], v[150:151], v[166:167] neg_lo:[0,1] neg_hi:[0,1]
	s_nop 0
	v_pk_add_f32 v[150:151], v[150:151], v[164:165] neg_lo:[0,1] neg_hi:[0,1]
	s_nop 0
	v_pk_add_f32 v[140:141], v[140:141], v[150:151]
	v_pk_add_f32 v[150:151], v[160:161], v[162:163] neg_lo:[0,1] neg_hi:[0,1]
	s_nop 0
	v_pk_add_f32 v[140:141], v[150:151], v[140:141]
	s_nop 0
	v_pk_add_f32 v[150:151], v[166:167], v[140:141]
	s_nop 0
	v_pk_mul_f32 v[160:161], v[158:159], v[150:151]
	s_nop 0
	v_pk_mul_f32 v[162:163], v[156:157], v[160:161]
	s_nop 0
	v_pk_fma_f32 v[156:157], v[160:161], v[156:157], v[162:163] neg_lo:[0,0,1] neg_hi:[0,0,1]
	s_nop 0
	v_pk_fma_f32 v[152:153], v[160:161], v[152:153], v[156:157]
	v_pk_add_f32 v[156:157], v[166:167], v[150:151] neg_lo:[0,1] neg_hi:[0,1]
	s_nop 0
	v_pk_add_f32 v[140:141], v[140:141], v[156:157]
	v_pk_add_f32 v[156:157], v[162:163], v[152:153]
	s_nop 0
	v_pk_add_f32 v[164:165], v[150:151], v[156:157] neg_lo:[0,1] neg_hi:[0,1]
	v_pk_add_f32 v[162:163], v[156:157], v[162:163] neg_lo:[0,1] neg_hi:[0,1]
	v_pk_add_f32 v[150:151], v[150:151], v[164:165] neg_lo:[0,1] neg_hi:[0,1]
	s_nop 0
	v_pk_add_f32 v[150:151], v[150:151], v[156:157] neg_lo:[0,1] neg_hi:[0,1]
	s_nop 0
	v_pk_add_f32 v[140:141], v[140:141], v[150:151]
	v_pk_add_f32 v[150:151], v[162:163], v[152:153] neg_lo:[0,1] neg_hi:[0,1]
	s_nop 0
	v_pk_add_f32 v[140:141], v[150:151], v[140:141]
	v_pk_add_f32 v[150:151], v[154:155], v[160:161]
	v_pk_add_f32 v[140:141], v[164:165], v[140:141]
	v_pk_add_f32 v[152:153], v[150:151], v[154:155] neg_lo:[0,1] neg_hi:[0,1]
	v_pk_mul_f32 v[140:141], v[158:159], v[140:141]
	v_pk_add_f32 v[152:153], v[160:161], v[152:153] neg_lo:[0,1] neg_hi:[0,1]
	s_nop 0
	v_pk_add_f32 v[140:141], v[152:153], v[140:141]
	s_nop 0
	v_pk_add_f32 v[152:153], v[150:151], v[140:141]
	s_nop 0
	v_pk_mul_f32 v[154:155], v[152:153], v[152:153]
	v_pk_add_f32 v[150:151], v[152:153], v[150:151] neg_lo:[0,1] neg_hi:[0,1]
	v_pk_fma_f32 v[156:157], v[154:155], s[6:7], v[142:143] op_sel_hi:[1,0,0]
	v_pk_add_f32 v[140:141], v[140:141], v[150:151] neg_lo:[0,1] neg_hi:[0,1]
	v_ldexp_f32 v150, v152, 1
	v_pk_fma_f32 v[156:157], v[154:155], v[156:157], s[8:9] op_sel_hi:[1,1,0]
	v_ldexp_f32 v151, v153, 1
	v_pk_mul_f32 v[152:153], v[152:153], v[154:155]
	v_cvt_f32_i32_e32 v155, v169
	v_cvt_f32_i32_e32 v154, v168
	v_pk_mul_f32 v[152:153], v[152:153], v[156:157]
	v_ldexp_f32 v159, v141, 1
	v_pk_add_f32 v[156:157], v[150:151], v[152:153]
	v_pk_mul_f32 v[160:161], v[154:155], s[36:37] op_sel_hi:[1,0]
	v_pk_add_f32 v[150:151], v[156:157], v[150:151] neg_lo:[0,1] neg_hi:[0,1]
	v_pk_fma_f32 v[162:163], v[154:155], s[36:37], v[160:161] op_sel_hi:[1,0,1] neg_lo:[0,0,1] neg_hi:[0,0,1]
	v_pk_add_f32 v[150:151], v[152:153], v[150:151] neg_lo:[0,1] neg_hi:[0,1]
	v_pk_fma_f32 v[154:155], v[154:155], s[10:11], v[162:163] op_sel_hi:[1,0,1]
	v_ldexp_f32 v140, v140, 1
	v_mov_b32_e32 v152, v160
	v_mov_b32_e32 v153, v151
	v_mov_b32_e32 v158, v154
	v_mov_b32_e32 v141, v159
	v_pk_add_f32 v[152:153], v[152:153], v[158:159]
	v_pk_add_f32 v[158:159], v[140:141], v[150:151]
	v_mov_b32_e32 v151, v157
	v_mov_b32_e32 v141, v159
	v_pk_add_f32 v[162:163], v[160:161], v[154:155]
	v_pk_add_f32 v[140:141], v[140:141], v[150:151]
	v_pk_add_f32 v[150:151], v[156:157], v[158:159]
	v_mov_b32_e32 v172, v156
	v_pk_add_f32 v[164:165], v[162:163], v[150:151]
	v_mov_b32_e32 v170, v150
	v_mov_b32_e32 v171, v165
	v_mov_b32_e32 v173, v163
	v_pk_add_f32 v[170:171], v[170:171], v[172:173] neg_lo:[0,1] neg_hi:[0,1]
	v_mov_b32_e32 v166, v164
	v_mov_b32_e32 v167, v163
	v_mov_b32_e32 v168, v162
	v_mov_b32_e32 v169, v161
	v_mov_b32_e32 v172, v162
	v_mov_b32_e32 v173, v165
	v_mov_b32_e32 v161, v171
	v_pk_add_f32 v[166:167], v[166:167], v[168:169] neg_lo:[0,1] neg_hi:[0,1]
	v_mov_b32_e32 v168, v150
	v_mov_b32_e32 v169, v155
	v_pk_add_f32 v[160:161], v[172:173], v[160:161] neg_lo:[0,1] neg_hi:[0,1]
	v_pk_add_f32 v[168:169], v[168:169], v[166:167] neg_lo:[0,1] neg_hi:[0,1]
	v_mov_b32_e32 v172, v160
	v_mov_b32_e32 v173, v167
	v_mov_b32_e32 v206, v164
	v_mov_b32_e32 v207, v151
	v_mov_b32_e32 v167, v157
; __device__ __forceinline__ float softplusf_(float x) { return fmaxf(x, 0.0f) + log1pf(__expf(-fabsf(x))); }
;     __device__ __forceinline__ void operator()(f32x4 (&acc)[2][2][4][2], const pg8::Unit& u, int wr, int wc, int fr, int fq) const {
;     ...
;                     for (int m = 0; m < 4; ++m) { const int row = row0 + ai * 128 + m * 16; const f32x4 v0 = acc[ai][0][m][0] + b0, v1 = acc[ai][0][m][1] + b1;
;                         float* d = DTA + (size_t)row * NH + cl0;
;                         *(f32x4*)d = (f32x4){softplusf_(v0[0]), softplusf_(v0[1]), softplusf_(v0[2]), softplusf_(v0[3])}; *(f32x4*)(d + 4) = (f32x4){softplusf_(v1[0]), softplusf_(v1[1]), softplusf_(v1[2]), softplusf_(v1[3])}; } }
	v_pk_add_f32 v[172:173], v[154:155], v[172:173] neg_lo:[0,1] neg_hi:[0,1]
	v_pk_add_f32 v[166:167], v[206:207], v[166:167] neg_lo:[0,1] neg_hi:[0,1]
	v_mov_b32_e32 v155, v163
	v_pk_add_f32 v[152:153], v[152:153], v[166:167] neg_lo:[0,1] neg_hi:[0,1]
	v_pk_add_f32 v[154:155], v[154:155], v[160:161] neg_lo:[0,1] neg_hi:[0,1]
	v_pk_add_f32 v[140:141], v[140:141], v[170:171] neg_lo:[0,1] neg_hi:[0,1]
	v_pk_add_f32 v[150:151], v[150:151], v[156:157] neg_lo:[0,1] neg_hi:[0,1]
	v_pk_add_f32 v[156:157], v[140:141], v[154:155]
	v_mov_b32_e32 v155, v169
	v_mov_b32_e32 v141, v153
	v_pk_add_f32 v[150:151], v[158:159], v[150:151] neg_lo:[0,1] neg_hi:[0,1]
	v_pk_add_f32 v[158:159], v[168:169], v[152:153]
	v_pk_add_f32 v[140:141], v[154:155], v[140:141]
	v_mov_b32_e32 v152, v156
	v_pk_add_f32 v[140:141], v[140:141], v[172:173] neg_lo:[0,1] neg_hi:[0,1]
	v_mov_b32_e32 v153, v159
	v_pk_add_f32 v[152:153], v[152:153], v[140:141] neg_lo:[0,1] neg_hi:[0,1]
	v_pk_add_f32 v[140:141], v[150:151], v[140:141] neg_lo:[0,1] neg_hi:[0,1]
	v_pk_add_f32 v[152:153], v[154:155], v[152:153] neg_lo:[0,1] neg_hi:[0,1]
	v_pk_add_f32 v[150:151], v[158:159], v[156:157]
	v_pk_add_f32 v[140:141], v[140:141], v[152:153]
	v_pk_add_f32 v[152:153], v[164:165], v[150:151]
	s_nop 0
	v_pk_add_f32 v[154:155], v[152:153], v[164:165] neg_lo:[0,1] neg_hi:[0,1]
	s_nop 0
	v_pk_add_f32 v[150:151], v[150:151], v[154:155] neg_lo:[0,1] neg_hi:[0,1]
	s_nop 0
	v_pk_add_f32 v[140:141], v[140:141], v[150:151]
	s_nop 0
	v_pk_add_f32 v[140:141], v[152:153], v[140:141]
	s_nop 0
	v_cndmask_b32_e32 v140, v252, v140, vcc
	v_cmp_neq_f32_e32 vcc, s3, v205
	s_nop 1
	v_cndmask_b32_e32 v141, v252, v141, vcc
	v_cmp_ngt_f32_e32 vcc, -1.0, v205
	s_nop 1
	v_cndmask_b32_e32 v141, v253, v141, vcc
	v_cmp_ngt_f32_e32 vcc, -1.0, v182
	s_nop 1
	v_cndmask_b32_e32 v140, v253, v140, vcc
	v_cmp_neq_f32_e32 vcc, -1.0, v182
	s_nop 1
	v_cndmask_b32_e32 v140, v244, v140, vcc
	v_cmp_neq_f32_e32 vcc, -1.0, v205
	s_nop 1
	v_cndmask_b32_e32 v141, v244, v141, vcc
	v_cmp_lt_f32_e64 vcc, |v182|, s4
	v_cndmask_b32_e64 v141, v141, v205, s[0:1]
	s_nop 0
	v_cndmask_b32_e32 v140, v140, v182, vcc
	v_pk_add_f32 v[138:139], v[138:139], v[140:141]
	v_mul_f32_e64 v141, |v148|, s88
	v_exp_f32_e32 v182, v141
	v_max_f32_e32 v140, 0, v148
	v_add_f32_e32 v141, 1.0, v182
	v_add_f32_e32 v148, -1.0, v141
	v_sub_f32_e32 v150, v148, v141
	v_add_f32_e32 v150, 1.0, v150
	v_sub_f32_e32 v148, v182, v148
	v_add_f32_e32 v152, v148, v150
	v_frexp_mant_f32_e32 v148, v141
	v_cvt_f64_f32_e32 v[150:151], v141
	v_cmp_gt_f32_e32 vcc, s2, v148
	v_frexp_exp_i32_f64_e32 v148, v[150:151]
	s_nop 0
	v_subbrev_co_u32_e32 v168, vcc, 0, v148, vcc
	v_sub_u32_e32 v150, 0, v168
	v_ldexp_f32 v148, v141, v150
	v_max_f32_e32 v141, 0, v149
	v_mul_f32_e64 v149, |v149|, s88
	v_exp_f32_e32 v205, v149
	v_ldexp_f32 v150, v152, v150
	v_add_f32_e32 v149, 1.0, v205
	v_add_f32_e32 v151, -1.0, v149
	v_sub_f32_e32 v152, v151, v149
	v_add_f32_e32 v152, 1.0, v152
	v_sub_f32_e32 v151, v205, v151
	v_add_f32_e32 v151, v151, v152
	v_frexp_mant_f32_e32 v152, v149
	v_cmp_gt_f32_e32 vcc, s2, v152
	v_cvt_f64_f32_e32 v[152:153], v149
	v_frexp_exp_i32_f64_e32 v152, v[152:153]
	v_subbrev_co_u32_e32 v169, vcc, 0, v152, vcc
	v_sub_u32_e32 v152, 0, v169
	v_ldexp_f32 v149, v149, v152
	v_ldexp_f32 v151, v151, v152
	v_pk_add_f32 v[152:153], v[148:149], 1.0 op_sel_hi:[1,0]
	v_pk_add_f32 v[160:161], v[148:149], -1.0 op_sel_hi:[1,0]
	v_pk_add_f32 v[154:155], v[152:153], -1.0 op_sel_hi:[1,0]
	v_pk_add_f32 v[162:163], v[160:161], 1.0 op_sel_hi:[1,0]
	v_pk_add_f32 v[154:155], v[148:149], v[154:155] neg_lo:[0,1] neg_hi:[0,1]
	v_pk_add_f32 v[148:149], v[148:149], v[162:163] neg_lo:[0,1] neg_hi:[0,1]
	v_pk_add_f32 v[154:155], v[150:151], v[154:155]
	v_pk_add_f32 v[148:149], v[150:151], v[148:149]
	v_pk_add_f32 v[156:157], v[152:153], v[154:155]
	v_pk_add_f32 v[150:151], v[160:161], v[148:149]
	v_rcp_f32_e32 v158, v156
	v_rcp_f32_e32 v159, v157
	v_pk_add_f32 v[152:153], v[156:157], v[152:153] neg_lo:[0,1] neg_hi:[0,1]
	v_pk_add_f32 v[160:161], v[150:151], v[160:161] neg_lo:[0,1] neg_hi:[0,1]
	v_pk_add_f32 v[152:153], v[154:155], v[152:153] neg_lo:[0,1] neg_hi:[0,1]
	v_pk_mul_f32 v[154:155], v[150:151], v[158:159]
	v_pk_add_f32 v[148:149], v[148:149], v[160:161] neg_lo:[0,1] neg_hi:[0,1]
	v_pk_mul_f32 v[160:161], v[156:157], v[154:155]
	v_cmp_neq_f32_e32 vcc, s3, v182
	v_pk_fma_f32 v[162:163], v[154:155], v[156:157], v[160:161] neg_lo:[0,0,1] neg_hi:[0,0,1]
	v_cmp_lt_f32_e64 s[0:1], |v205|, s4
	v_pk_fma_f32 v[162:163], v[154:155], v[152:153], v[162:163]
	s_nop 0
	v_pk_add_f32 v[164:165], v[160:161], v[162:163]
	s_nop 0
	v_pk_add_f32 v[166:167], v[150:151], v[164:165] neg_lo:[0,1] neg_hi:[0,1]
	v_pk_add_f32 v[160:161], v[164:165], v[160:161] neg_lo:[0,1] neg_hi:[0,1]
	v_pk_add_f32 v[150:151], v[150:151], v[166:167] neg_lo:[0,1] neg_hi:[0,1]
	s_nop 0
	v_pk_add_f32 v[150:151], v[150:151], v[164:165] neg_lo:[0,1] neg_hi:[0,1]
	s_nop 0
	v_pk_add_f32 v[148:149], v[148:149], v[150:151]
	v_pk_add_f32 v[150:151], v[160:161], v[162:163] neg_lo:[0,1] neg_hi:[0,1]
	s_nop 0
	v_pk_add_f32 v[148:149], v[150:151], v[148:149]
	s_nop 0
	v_pk_add_f32 v[150:151], v[166:167], v[148:149]
	s_nop 0
	v_pk_mul_f32 v[160:161], v[158:159], v[150:151]
	s_nop 0
	v_pk_mul_f32 v[162:163], v[156:157], v[160:161]
	s_nop 0
	v_pk_fma_f32 v[156:157], v[160:161], v[156:157], v[162:163] neg_lo:[0,0,1] neg_hi:[0,0,1]
	s_nop 0
	v_pk_fma_f32 v[152:153], v[160:161], v[152:153], v[156:157]
	v_pk_add_f32 v[156:157], v[166:167], v[150:151] neg_lo:[0,1] neg_hi:[0,1]
	s_nop 0
	v_pk_add_f32 v[148:149], v[148:149], v[156:157]
	v_pk_add_f32 v[156:157], v[162:163], v[152:153]
; __device__ __forceinline__ float softplusf_(float x) { return fmaxf(x, 0.0f) + log1pf(__expf(-fabsf(x))); }
;     __device__ __forceinline__ void operator()(f32x4 (&acc)[2][2][4][2], const pg8::Unit& u, int wr, int wc, int fr, int fq) const {
;     ...
;             if (wc == 0) { const f32x4 b0 = *(const f32x4*)(dtb + cl0), b1 = *(const f32x4*)(dtb + cl0 + 4);
; #pragma unroll
;                 for (int ai = 0; ai < 2; ++ai)
; #pragma unroll
;                     for (int m = 0; m < 4; ++m) { const int row = row0 + ai * 128 + m * 16; const f32x4 v0 = acc[ai][0][m][0] + b0, v1 = acc[ai][0][m][1] + b1;
;                         float* d = DTA + (size_t)row * NH + cl0;
;                         *(f32x4*)d = (f32x4){softplusf_(v0[0]), softplusf_(v0[1]), softplusf_(v0[2]), softplusf_(v0[3])}; *(f32x4*)(d + 4) = (f32x4){softplusf_(v1[0]), softplusf_(v1[1]), softplusf_(v1[2]), softplusf_(v1[3])}; } }
	s_nop 0
	v_pk_add_f32 v[164:165], v[150:151], v[156:157] neg_lo:[0,1] neg_hi:[0,1]
	v_pk_add_f32 v[162:163], v[156:157], v[162:163] neg_lo:[0,1] neg_hi:[0,1]
	v_pk_add_f32 v[150:151], v[150:151], v[164:165] neg_lo:[0,1] neg_hi:[0,1]
	s_nop 0
	v_pk_add_f32 v[150:151], v[150:151], v[156:157] neg_lo:[0,1] neg_hi:[0,1]
	s_nop 0
	v_pk_add_f32 v[148:149], v[148:149], v[150:151]
	v_pk_add_f32 v[150:151], v[162:163], v[152:153] neg_lo:[0,1] neg_hi:[0,1]
	s_nop 0
	v_pk_add_f32 v[148:149], v[150:151], v[148:149]
	v_pk_add_f32 v[150:151], v[154:155], v[160:161]
	v_pk_add_f32 v[148:149], v[164:165], v[148:149]
	v_pk_add_f32 v[152:153], v[150:151], v[154:155] neg_lo:[0,1] neg_hi:[0,1]
	v_pk_mul_f32 v[148:149], v[158:159], v[148:149]
	v_pk_add_f32 v[152:153], v[160:161], v[152:153] neg_lo:[0,1] neg_hi:[0,1]
	s_nop 0
	v_pk_add_f32 v[148:149], v[152:153], v[148:149]
	s_nop 0
	v_pk_add_f32 v[152:153], v[150:151], v[148:149]
	s_nop 0
	v_pk_mul_f32 v[154:155], v[152:153], v[152:153]
	v_pk_add_f32 v[150:151], v[152:153], v[150:151] neg_lo:[0,1] neg_hi:[0,1]
	v_pk_fma_f32 v[156:157], v[154:155], s[6:7], v[142:143] op_sel_hi:[1,0,0]
	v_pk_add_f32 v[148:149], v[148:149], v[150:151] neg_lo:[0,1] neg_hi:[0,1]
	v_ldexp_f32 v150, v152, 1
	v_pk_fma_f32 v[156:157], v[154:155], v[156:157], s[8:9] op_sel_hi:[1,1,0]
	v_ldexp_f32 v151, v153, 1
	v_pk_mul_f32 v[152:153], v[152:153], v[154:155]
	v_cvt_f32_i32_e32 v155, v169
	v_cvt_f32_i32_e32 v154, v168
	v_pk_mul_f32 v[152:153], v[152:153], v[156:157]
	v_ldexp_f32 v159, v149, 1
	v_pk_add_f32 v[156:157], v[150:151], v[152:153]
	v_pk_mul_f32 v[160:161], v[154:155], s[36:37] op_sel_hi:[1,0]
	v_pk_add_f32 v[150:151], v[156:157], v[150:151] neg_lo:[0,1] neg_hi:[0,1]
	v_pk_fma_f32 v[162:163], v[154:155], s[36:37], v[160:161] op_sel_hi:[1,0,1] neg_lo:[0,0,1] neg_hi:[0,0,1]
	v_pk_add_f32 v[150:151], v[152:153], v[150:151] neg_lo:[0,1] neg_hi:[0,1]
	v_pk_fma_f32 v[154:155], v[154:155], s[10:11], v[162:163] op_sel_hi:[1,0,1]
	v_ldexp_f32 v148, v148, 1
	v_mov_b32_e32 v152, v160
	v_mov_b32_e32 v153, v151
	v_mov_b32_e32 v158, v154
	v_mov_b32_e32 v149, v159
	v_pk_add_f32 v[152:153], v[152:153], v[158:159]
	v_pk_add_f32 v[158:159], v[148:149], v[150:151]
	v_mov_b32_e32 v151, v157
	v_mov_b32_e32 v149, v159
	v_pk_add_f32 v[162:163], v[160:161], v[154:155]
	v_pk_add_f32 v[148:149], v[148:149], v[150:151]
	v_pk_add_f32 v[150:151], v[156:157], v[158:159]
	v_mov_b32_e32 v172, v156
	v_pk_add_f32 v[164:165], v[162:163], v[150:151]
	v_mov_b32_e32 v170, v150
	v_mov_b32_e32 v171, v165
	v_mov_b32_e32 v173, v163
	v_pk_add_f32 v[170:171], v[170:171], v[172:173] neg_lo:[0,1] neg_hi:[0,1]
	v_mov_b32_e32 v166, v164
	v_mov_b32_e32 v167, v163
	v_mov_b32_e32 v168, v162
	v_mov_b32_e32 v169, v161
	v_mov_b32_e32 v172, v162
	v_mov_b32_e32 v173, v165
	v_mov_b32_e32 v161, v171
	v_pk_add_f32 v[166:167], v[166:167], v[168:169] neg_lo:[0,1] neg_hi:[0,1]
	v_mov_b32_e32 v168, v150
	v_mov_b32_e32 v169, v155
	v_pk_add_f32 v[160:161], v[172:173], v[160:161] neg_lo:[0,1] neg_hi:[0,1]
	v_pk_add_f32 v[168:169], v[168:169], v[166:167] neg_lo:[0,1] neg_hi:[0,1]
	v_mov_b32_e32 v172, v160
	v_mov_b32_e32 v173, v167
	v_mov_b32_e32 v206, v164
	v_mov_b32_e32 v207, v151
	v_mov_b32_e32 v167, v157
	v_pk_add_f32 v[172:173], v[154:155], v[172:173] neg_lo:[0,1] neg_hi:[0,1]
	v_pk_add_f32 v[166:167], v[206:207], v[166:167] neg_lo:[0,1] neg_hi:[0,1]
	v_mov_b32_e32 v155, v163
	v_pk_add_f32 v[152:153], v[152:153], v[166:167] neg_lo:[0,1] neg_hi:[0,1]
	v_pk_add_f32 v[154:155], v[154:155], v[160:161] neg_lo:[0,1] neg_hi:[0,1]
	v_pk_add_f32 v[148:149], v[148:149], v[170:171] neg_lo:[0,1] neg_hi:[0,1]
	v_pk_add_f32 v[150:151], v[150:151], v[156:157] neg_lo:[0,1] neg_hi:[0,1]
	v_pk_add_f32 v[156:157], v[148:149], v[154:155]
	v_mov_b32_e32 v155, v169
	v_mov_b32_e32 v149, v153
	v_pk_add_f32 v[150:151], v[158:159], v[150:151] neg_lo:[0,1] neg_hi:[0,1]
	v_pk_add_f32 v[158:159], v[168:169], v[152:153]
	v_pk_add_f32 v[148:149], v[154:155], v[148:149]
	v_mov_b32_e32 v152, v156
	v_pk_add_f32 v[148:149], v[148:149], v[172:173] neg_lo:[0,1] neg_hi:[0,1]
	v_mov_b32_e32 v153, v159
	v_pk_add_f32 v[152:153], v[152:153], v[148:149] neg_lo:[0,1] neg_hi:[0,1]
	v_pk_add_f32 v[148:149], v[150:151], v[148:149] neg_lo:[0,1] neg_hi:[0,1]
	v_pk_add_f32 v[152:153], v[154:155], v[152:153] neg_lo:[0,1] neg_hi:[0,1]
	v_pk_add_f32 v[150:151], v[158:159], v[156:157]
	v_pk_add_f32 v[148:149], v[148:149], v[152:153]
	v_pk_add_f32 v[152:153], v[164:165], v[150:151]
	s_nop 0
	v_pk_add_f32 v[154:155], v[152:153], v[164:165] neg_lo:[0,1] neg_hi:[0,1]
	s_nop 0
	v_pk_add_f32 v[150:151], v[150:151], v[154:155] neg_lo:[0,1] neg_hi:[0,1]
	s_nop 0
	v_pk_add_f32 v[148:149], v[148:149], v[150:151]
	v_pk_add_f32 v[150:151], v[42:43], v[130:131]
	v_pk_add_f32 v[148:149], v[152:153], v[148:149]
	v_pk_add_f32 v[152:153], v[46:47], v[134:135]
	v_cndmask_b32_e32 v148, v252, v148, vcc
	v_cmp_neq_f32_e32 vcc, s3, v205
	s_nop 1
	v_cndmask_b32_e32 v149, v252, v149, vcc
	v_cmp_ngt_f32_e32 vcc, -1.0, v205
	s_nop 1
	v_cndmask_b32_e32 v149, v253, v149, vcc
	v_cmp_ngt_f32_e32 vcc, -1.0, v182
	s_nop 1
	v_cndmask_b32_e32 v148, v253, v148, vcc
	v_cmp_neq_f32_e32 vcc, -1.0, v182
	s_nop 1
	v_cndmask_b32_e32 v148, v244, v148, vcc
	v_cmp_neq_f32_e32 vcc, -1.0, v205
	s_nop 1
	v_cndmask_b32_e32 v149, v244, v149, vcc
	v_cmp_lt_f32_e64 vcc, |v182|, s4
	v_cndmask_b32_e64 v149, v149, v205, s[0:1]
	s_nop 0
	v_cndmask_b32_e32 v148, v148, v182, vcc
	v_pk_add_f32 v[140:141], v[140:141], v[148:149]
	global_store_dwordx4 v[146:147], v[138:141], off offset:16
	v_pk_add_f32 v[148:149], v[44:45], v[132:133]
	s_nop 0
	v_lshlrev_b64 v[138:139], 7, v[192:193]
; __device__ __forceinline__ float softplusf_(float x) { return fmaxf(x, 0.0f) + log1pf(__expf(-fabsf(x))); }
;     __device__ __forceinline__ void operator()(f32x4 (&acc)[2][2][4][2], const pg8::Unit& u, int wr, int wc, int fr, int fq) const {
;     ...
;                     for (int m = 0; m < 4; ++m) { const int row = row0 + ai * 128 + m * 16; const f32x4 v0 = acc[ai][0][m][0] + b0, v1 = acc[ai][0][m][1] + b1;
;                         float* d = DTA + (size_t)row * NH + cl0;
;                         *(f32x4*)d = (f32x4){softplusf_(v0[0]), softplusf_(v0[1]), softplusf_(v0[2]), softplusf_(v0[3])}; *(f32x4*)(d + 4) = (f32x4){softplusf_(v1[0]), softplusf_(v1[1]), softplusf_(v1[2]), softplusf_(v1[3])}; } }
	v_lshl_add_u64 v[146:147], v[144:145], 0, v[138:139]
	v_mul_f32_e64 v139, |v152|, s88
	v_exp_f32_e32 v182, v139
	v_max_f32_e32 v138, 0, v152
	v_pk_add_f32 v[140:141], v[48:49], v[136:137]
	v_add_f32_e32 v139, 1.0, v182
	v_add_f32_e32 v152, -1.0, v139
	v_sub_f32_e32 v154, v152, v139
	v_add_f32_e32 v154, 1.0, v154
	v_sub_f32_e32 v152, v182, v152
	v_add_f32_e32 v156, v152, v154
	v_frexp_mant_f32_e32 v152, v139
	v_cvt_f64_f32_e32 v[154:155], v139
	v_cmp_gt_f32_e32 vcc, s2, v152
	v_frexp_exp_i32_f64_e32 v152, v[154:155]
	s_nop 0
	v_subbrev_co_u32_e32 v172, vcc, 0, v152, vcc
	v_sub_u32_e32 v154, 0, v172
	v_ldexp_f32 v152, v139, v154
	v_max_f32_e32 v139, 0, v153
	v_mul_f32_e64 v153, |v153|, s88
	v_exp_f32_e32 v205, v153
	v_ldexp_f32 v154, v156, v154
	v_add_f32_e32 v153, 1.0, v205
	v_add_f32_e32 v155, -1.0, v153
	v_sub_f32_e32 v156, v155, v153
	v_add_f32_e32 v156, 1.0, v156
	v_sub_f32_e32 v155, v205, v155
	v_add_f32_e32 v155, v155, v156
	v_frexp_mant_f32_e32 v156, v153
	v_cmp_gt_f32_e32 vcc, s2, v156
	v_cvt_f64_f32_e32 v[156:157], v153
	v_frexp_exp_i32_f64_e32 v156, v[156:157]
	v_subbrev_co_u32_e32 v173, vcc, 0, v156, vcc
	v_sub_u32_e32 v156, 0, v173
	v_ldexp_f32 v153, v153, v156
	v_ldexp_f32 v155, v155, v156
	v_pk_add_f32 v[156:157], v[152:153], 1.0 op_sel_hi:[1,0]
	v_pk_add_f32 v[164:165], v[152:153], -1.0 op_sel_hi:[1,0]
	v_pk_add_f32 v[158:159], v[156:157], -1.0 op_sel_hi:[1,0]
	v_pk_add_f32 v[166:167], v[164:165], 1.0 op_sel_hi:[1,0]
	v_pk_add_f32 v[158:159], v[152:153], v[158:159] neg_lo:[0,1] neg_hi:[0,1]
	v_pk_add_f32 v[152:153], v[152:153], v[166:167] neg_lo:[0,1] neg_hi:[0,1]
	v_pk_add_f32 v[158:159], v[154:155], v[158:159]
	v_pk_add_f32 v[152:153], v[154:155], v[152:153]
	v_pk_add_f32 v[160:161], v[156:157], v[158:159]
	v_pk_add_f32 v[154:155], v[164:165], v[152:153]
	v_rcp_f32_e32 v162, v160
	v_rcp_f32_e32 v163, v161
	v_pk_add_f32 v[156:157], v[160:161], v[156:157] neg_lo:[0,1] neg_hi:[0,1]
	v_pk_add_f32 v[164:165], v[154:155], v[164:165] neg_lo:[0,1] neg_hi:[0,1]
	v_pk_add_f32 v[156:157], v[158:159], v[156:157] neg_lo:[0,1] neg_hi:[0,1]
	v_pk_mul_f32 v[158:159], v[154:155], v[162:163]
	v_pk_add_f32 v[152:153], v[152:153], v[164:165] neg_lo:[0,1] neg_hi:[0,1]
	v_pk_mul_f32 v[164:165], v[160:161], v[158:159]
	v_cmp_neq_f32_e32 vcc, s3, v182
	v_pk_fma_f32 v[166:167], v[158:159], v[160:161], v[164:165] neg_lo:[0,0,1] neg_hi:[0,0,1]
	v_cmp_lt_f32_e64 s[0:1], |v205|, s4
	v_pk_fma_f32 v[166:167], v[158:159], v[156:157], v[166:167]
	s_nop 0
	v_pk_add_f32 v[168:169], v[164:165], v[166:167]
	s_nop 0
	v_pk_add_f32 v[170:171], v[154:155], v[168:169] neg_lo:[0,1] neg_hi:[0,1]
	v_pk_add_f32 v[164:165], v[168:169], v[164:165] neg_lo:[0,1] neg_hi:[0,1]
	v_pk_add_f32 v[154:155], v[154:155], v[170:171] neg_lo:[0,1] neg_hi:[0,1]
	s_nop 0
	v_pk_add_f32 v[154:155], v[154:155], v[168:169] neg_lo:[0,1] neg_hi:[0,1]
	s_nop 0
	v_pk_add_f32 v[152:153], v[152:153], v[154:155]
	v_pk_add_f32 v[154:155], v[164:165], v[166:167] neg_lo:[0,1] neg_hi:[0,1]
	s_nop 0
	v_pk_add_f32 v[152:153], v[154:155], v[152:153]
	s_nop 0
	v_pk_add_f32 v[154:155], v[170:171], v[152:153]
	s_nop 0
	v_pk_mul_f32 v[164:165], v[162:163], v[154:155]
	s_nop 0
	v_pk_mul_f32 v[166:167], v[160:161], v[164:165]
	s_nop 0
	v_pk_fma_f32 v[160:161], v[164:165], v[160:161], v[166:167] neg_lo:[0,0,1] neg_hi:[0,0,1]
	s_nop 0
	v_pk_fma_f32 v[156:157], v[164:165], v[156:157], v[160:161]
	v_pk_add_f32 v[160:161], v[170:171], v[154:155] neg_lo:[0,1] neg_hi:[0,1]
	s_nop 0
	v_pk_add_f32 v[152:153], v[152:153], v[160:161]
	v_pk_add_f32 v[160:161], v[166:167], v[156:157]
	s_nop 0
	v_pk_add_f32 v[168:169], v[154:155], v[160:161] neg_lo:[0,1] neg_hi:[0,1]
	v_pk_add_f32 v[166:167], v[160:161], v[166:167] neg_lo:[0,1] neg_hi:[0,1]
	v_pk_add_f32 v[154:155], v[154:155], v[168:169] neg_lo:[0,1] neg_hi:[0,1]
	s_nop 0
	v_pk_add_f32 v[154:155], v[154:155], v[160:161] neg_lo:[0,1] neg_hi:[0,1]
	s_nop 0
	v_pk_add_f32 v[152:153], v[152:153], v[154:155]
	v_pk_add_f32 v[154:155], v[166:167], v[156:157] neg_lo:[0,1] neg_hi:[0,1]
	s_nop 0
	v_pk_add_f32 v[152:153], v[154:155], v[152:153]
	v_pk_add_f32 v[154:155], v[158:159], v[164:165]
	v_pk_add_f32 v[152:153], v[168:169], v[152:153]
	v_pk_add_f32 v[156:157], v[154:155], v[158:159] neg_lo:[0,1] neg_hi:[0,1]
	v_pk_mul_f32 v[152:153], v[162:163], v[152:153]
	v_pk_add_f32 v[156:157], v[164:165], v[156:157] neg_lo:[0,1] neg_hi:[0,1]
	s_nop 0
	v_pk_add_f32 v[152:153], v[156:157], v[152:153]
	s_nop 0
	v_pk_add_f32 v[156:157], v[154:155], v[152:153]
	s_nop 0
	v_pk_mul_f32 v[158:159], v[156:157], v[156:157]
	v_pk_add_f32 v[154:155], v[156:157], v[154:155] neg_lo:[0,1] neg_hi:[0,1]
	v_pk_fma_f32 v[160:161], v[158:159], s[6:7], v[142:143] op_sel_hi:[1,0,0]
	v_pk_add_f32 v[152:153], v[152:153], v[154:155] neg_lo:[0,1] neg_hi:[0,1]
	v_ldexp_f32 v154, v156, 1
	v_pk_fma_f32 v[160:161], v[158:159], v[160:161], s[8:9] op_sel_hi:[1,1,0]
	v_ldexp_f32 v155, v157, 1
	v_pk_mul_f32 v[156:157], v[156:157], v[158:159]
	v_cvt_f32_i32_e32 v159, v173
	v_cvt_f32_i32_e32 v158, v172
	v_pk_mul_f32 v[156:157], v[156:157], v[160:161]
	v_ldexp_f32 v163, v153, 1
	v_pk_add_f32 v[160:161], v[154:155], v[156:157]
	v_pk_mul_f32 v[164:165], v[158:159], s[36:37] op_sel_hi:[1,0]
	v_pk_add_f32 v[154:155], v[160:161], v[154:155] neg_lo:[0,1] neg_hi:[0,1]
	v_pk_fma_f32 v[166:167], v[158:159], s[36:37], v[164:165] op_sel_hi:[1,0,1] neg_lo:[0,0,1] neg_hi:[0,0,1]
	v_pk_add_f32 v[154:155], v[156:157], v[154:155] neg_lo:[0,1] neg_hi:[0,1]
	v_pk_fma_f32 v[158:159], v[158:159], s[10:11], v[166:167] op_sel_hi:[1,0,1]
	v_ldexp_f32 v152, v152, 1
	v_mov_b32_e32 v156, v164
	v_mov_b32_e32 v157, v155
	v_mov_b32_e32 v162, v158
; __device__ __forceinline__ float softplusf_(float x) { return fmaxf(x, 0.0f) + log1pf(__expf(-fabsf(x))); }
;     __device__ __forceinline__ void operator()(f32x4 (&acc)[2][2][4][2], const pg8::Unit& u, int wr, int wc, int fr, int fq) const {
;     ...
;                     for (int m = 0; m < 4; ++m) { const int row = row0 + ai * 128 + m * 16; const f32x4 v0 = acc[ai][0][m][0] + b0, v1 = acc[ai][0][m][1] + b1;
;                         float* d = DTA + (size_t)row * NH + cl0;
;                         *(f32x4*)d = (f32x4){softplusf_(v0[0]), softplusf_(v0[1]), softplusf_(v0[2]), softplusf_(v0[3])}; *(f32x4*)(d + 4) = (f32x4){softplusf_(v1[0]), softplusf_(v1[1]), softplusf_(v1[2]), softplusf_(v1[3])}; } }
	v_mov_b32_e32 v153, v163
	v_pk_add_f32 v[156:157], v[156:157], v[162:163]
	v_pk_add_f32 v[162:163], v[152:153], v[154:155]
	v_mov_b32_e32 v155, v161
	v_mov_b32_e32 v153, v163
	v_pk_add_f32 v[166:167], v[164:165], v[158:159]
	v_pk_add_f32 v[152:153], v[152:153], v[154:155]
	v_pk_add_f32 v[154:155], v[160:161], v[162:163]
	v_mov_b32_e32 v208, v160
	v_pk_add_f32 v[168:169], v[166:167], v[154:155]
	v_mov_b32_e32 v206, v154
	v_mov_b32_e32 v207, v169
	v_mov_b32_e32 v209, v167
	v_pk_add_f32 v[206:207], v[206:207], v[208:209] neg_lo:[0,1] neg_hi:[0,1]
	v_mov_b32_e32 v170, v168
	v_mov_b32_e32 v171, v167
	v_mov_b32_e32 v172, v166
	v_mov_b32_e32 v173, v165
	v_mov_b32_e32 v208, v166
	v_mov_b32_e32 v209, v169
	v_mov_b32_e32 v165, v207
	v_pk_add_f32 v[170:171], v[170:171], v[172:173] neg_lo:[0,1] neg_hi:[0,1]
	v_mov_b32_e32 v172, v154
	v_mov_b32_e32 v173, v159
	v_pk_add_f32 v[164:165], v[208:209], v[164:165] neg_lo:[0,1] neg_hi:[0,1]
	v_pk_add_f32 v[172:173], v[172:173], v[170:171] neg_lo:[0,1] neg_hi:[0,1]
	v_mov_b32_e32 v208, v164
	v_mov_b32_e32 v209, v171
	v_mov_b32_e32 v210, v168
	v_mov_b32_e32 v211, v155
	v_mov_b32_e32 v171, v161
	v_pk_add_f32 v[208:209], v[158:159], v[208:209] neg_lo:[0,1] neg_hi:[0,1]
	v_pk_add_f32 v[170:171], v[210:211], v[170:171] neg_lo:[0,1] neg_hi:[0,1]
	v_mov_b32_e32 v159, v167
	v_pk_add_f32 v[156:157], v[156:157], v[170:171] neg_lo:[0,1] neg_hi:[0,1]
	v_pk_add_f32 v[158:159], v[158:159], v[164:165] neg_lo:[0,1] neg_hi:[0,1]
	v_pk_add_f32 v[152:153], v[152:153], v[206:207] neg_lo:[0,1] neg_hi:[0,1]
	v_pk_add_f32 v[154:155], v[154:155], v[160:161] neg_lo:[0,1] neg_hi:[0,1]
	v_pk_add_f32 v[160:161], v[152:153], v[158:159]
	v_mov_b32_e32 v159, v173
	v_mov_b32_e32 v153, v157
	v_pk_add_f32 v[154:155], v[162:163], v[154:155] neg_lo:[0,1] neg_hi:[0,1]
	v_pk_add_f32 v[162:163], v[172:173], v[156:157]
	v_pk_add_f32 v[152:153], v[158:159], v[152:153]
	v_mov_b32_e32 v156, v160
	v_pk_add_f32 v[152:153], v[152:153], v[208:209] neg_lo:[0,1] neg_hi:[0,1]
	v_mov_b32_e32 v157, v163
	v_pk_add_f32 v[156:157], v[156:157], v[152:153] neg_lo:[0,1] neg_hi:[0,1]
	v_pk_add_f32 v[152:153], v[154:155], v[152:153] neg_lo:[0,1] neg_hi:[0,1]
	v_pk_add_f32 v[156:157], v[158:159], v[156:157] neg_lo:[0,1] neg_hi:[0,1]
	v_pk_add_f32 v[154:155], v[162:163], v[160:161]
	v_pk_add_f32 v[152:153], v[152:153], v[156:157]
	v_pk_add_f32 v[156:157], v[168:169], v[154:155]
	s_nop 0
	v_pk_add_f32 v[158:159], v[156:157], v[168:169] neg_lo:[0,1] neg_hi:[0,1]
	s_nop 0
	v_pk_add_f32 v[154:155], v[154:155], v[158:159] neg_lo:[0,1] neg_hi:[0,1]
	s_nop 0
	v_pk_add_f32 v[152:153], v[152:153], v[154:155]
	s_nop 0
	v_pk_add_f32 v[152:153], v[156:157], v[152:153]
	s_nop 0
	v_cndmask_b32_e32 v152, v252, v152, vcc
	v_cmp_neq_f32_e32 vcc, s3, v205
	s_nop 1
	v_cndmask_b32_e32 v153, v252, v153, vcc
	v_cmp_ngt_f32_e32 vcc, -1.0, v205
	s_nop 1
	v_cndmask_b32_e32 v153, v253, v153, vcc
	v_cmp_ngt_f32_e32 vcc, -1.0, v182
	s_nop 1
	v_cndmask_b32_e32 v152, v253, v152, vcc
	v_cmp_neq_f32_e32 vcc, -1.0, v182
	s_nop 1
	v_cndmask_b32_e32 v152, v244, v152, vcc
	v_cmp_neq_f32_e32 vcc, -1.0, v205
	s_nop 1
	v_cndmask_b32_e32 v153, v244, v153, vcc
	v_cmp_lt_f32_e64 vcc, |v182|, s4
	v_cndmask_b32_e64 v153, v153, v205, s[0:1]
	s_nop 0
	v_cndmask_b32_e32 v152, v152, v182, vcc
	v_pk_add_f32 v[138:139], v[138:139], v[152:153]
	v_max_f32_e32 v152, 0, v140
	v_mul_f32_e64 v140, |v140|, s88
	v_exp_f32_e32 v182, v140
	s_nop 0
	v_add_f32_e32 v140, 1.0, v182
	v_add_f32_e32 v153, -1.0, v140
	v_sub_f32_e32 v154, v153, v140
	v_add_f32_e32 v154, 1.0, v154
	v_sub_f32_e32 v153, v182, v153
	v_add_f32_e32 v153, v153, v154
	v_frexp_mant_f32_e32 v154, v140
	v_cmp_gt_f32_e32 vcc, s2, v154
	v_cvt_f64_f32_e32 v[154:155], v140
	v_frexp_exp_i32_f64_e32 v154, v[154:155]
	v_subbrev_co_u32_e32 v172, vcc, 0, v154, vcc
	v_sub_u32_e32 v154, 0, v172
	v_ldexp_f32 v140, v140, v154
	v_ldexp_f32 v154, v153, v154
	v_max_f32_e32 v153, 0, v141
	v_mul_f32_e64 v141, |v141|, s88
	v_exp_f32_e32 v205, v141
	s_nop 0
	v_add_f32_e32 v141, 1.0, v205
	v_add_f32_e32 v155, -1.0, v141
	v_sub_f32_e32 v156, v155, v141
	v_add_f32_e32 v156, 1.0, v156
	v_sub_f32_e32 v155, v205, v155
	v_add_f32_e32 v155, v155, v156
	v_frexp_mant_f32_e32 v156, v141
	v_cmp_gt_f32_e32 vcc, s2, v156
	v_cvt_f64_f32_e32 v[156:157], v141
	v_frexp_exp_i32_f64_e32 v156, v[156:157]
	v_subbrev_co_u32_e32 v173, vcc, 0, v156, vcc
	v_sub_u32_e32 v156, 0, v173
	v_ldexp_f32 v141, v141, v156
	v_ldexp_f32 v155, v155, v156
	v_pk_add_f32 v[156:157], v[140:141], 1.0 op_sel_hi:[1,0]
	v_pk_add_f32 v[164:165], v[140:141], -1.0 op_sel_hi:[1,0]
	v_pk_add_f32 v[158:159], v[156:157], -1.0 op_sel_hi:[1,0]
	v_pk_add_f32 v[166:167], v[164:165], 1.0 op_sel_hi:[1,0]
	v_pk_add_f32 v[158:159], v[140:141], v[158:159] neg_lo:[0,1] neg_hi:[0,1]
	v_pk_add_f32 v[140:141], v[140:141], v[166:167] neg_lo:[0,1] neg_hi:[0,1]
	v_pk_add_f32 v[158:159], v[154:155], v[158:159]
	v_pk_add_f32 v[140:141], v[154:155], v[140:141]
	v_pk_add_f32 v[160:161], v[156:157], v[158:159]
	v_pk_add_f32 v[154:155], v[164:165], v[140:141]
	v_rcp_f32_e32 v162, v160
	v_rcp_f32_e32 v163, v161
	v_pk_add_f32 v[156:157], v[160:161], v[156:157] neg_lo:[0,1] neg_hi:[0,1]
	v_pk_add_f32 v[164:165], v[154:155], v[164:165] neg_lo:[0,1] neg_hi:[0,1]
	v_pk_add_f32 v[156:157], v[158:159], v[156:157] neg_lo:[0,1] neg_hi:[0,1]
	v_pk_mul_f32 v[158:159], v[154:155], v[162:163]
	v_pk_add_f32 v[140:141], v[140:141], v[164:165] neg_lo:[0,1] neg_hi:[0,1]
	v_pk_mul_f32 v[164:165], v[160:161], v[158:159]
	v_cmp_neq_f32_e32 vcc, s3, v182
	v_pk_fma_f32 v[166:167], v[158:159], v[160:161], v[164:165] neg_lo:[0,0,1] neg_hi:[0,0,1]
	v_cmp_lt_f32_e64 s[0:1], |v205|, s4
; __device__ __forceinline__ float softplusf_(float x) { return fmaxf(x, 0.0f) + log1pf(__expf(-fabsf(x))); }
;     __device__ __forceinline__ void operator()(f32x4 (&acc)[2][2][4][2], const pg8::Unit& u, int wr, int wc, int fr, int fq) const {
;     ...
;             if (wc == 0) { const f32x4 b0 = *(const f32x4*)(dtb + cl0), b1 = *(const f32x4*)(dtb + cl0 + 4);
; #pragma unroll
;                 for (int ai = 0; ai < 2; ++ai)
; #pragma unroll
;                     for (int m = 0; m < 4; ++m) { const int row = row0 + ai * 128 + m * 16; const f32x4 v0 = acc[ai][0][m][0] + b0, v1 = acc[ai][0][m][1] + b1;
;                         float* d = DTA + (size_t)row * NH + cl0;
;                         *(f32x4*)d = (f32x4){softplusf_(v0[0]), softplusf_(v0[1]), softplusf_(v0[2]), softplusf_(v0[3])}; *(f32x4*)(d + 4) = (f32x4){softplusf_(v1[0]), softplusf_(v1[1]), softplusf_(v1[2]), softplusf_(v1[3])}; } }
	v_pk_fma_f32 v[166:167], v[158:159], v[156:157], v[166:167]
	s_nop 0
	v_pk_add_f32 v[168:169], v[164:165], v[166:167]
	s_nop 0
	v_pk_add_f32 v[170:171], v[154:155], v[168:169] neg_lo:[0,1] neg_hi:[0,1]
	v_pk_add_f32 v[164:165], v[168:169], v[164:165] neg_lo:[0,1] neg_hi:[0,1]
	v_pk_add_f32 v[154:155], v[154:155], v[170:171] neg_lo:[0,1] neg_hi:[0,1]
	s_nop 0
	v_pk_add_f32 v[154:155], v[154:155], v[168:169] neg_lo:[0,1] neg_hi:[0,1]
	s_nop 0
	v_pk_add_f32 v[140:141], v[140:141], v[154:155]
	v_pk_add_f32 v[154:155], v[164:165], v[166:167] neg_lo:[0,1] neg_hi:[0,1]
	s_nop 0
	v_pk_add_f32 v[140:141], v[154:155], v[140:141]
	s_nop 0
	v_pk_add_f32 v[154:155], v[170:171], v[140:141]
	s_nop 0
	v_pk_mul_f32 v[164:165], v[162:163], v[154:155]
	s_nop 0
	v_pk_mul_f32 v[166:167], v[160:161], v[164:165]
	s_nop 0
	v_pk_fma_f32 v[160:161], v[164:165], v[160:161], v[166:167] neg_lo:[0,0,1] neg_hi:[0,0,1]
	s_nop 0
	v_pk_fma_f32 v[156:157], v[164:165], v[156:157], v[160:161]
	v_pk_add_f32 v[160:161], v[170:171], v[154:155] neg_lo:[0,1] neg_hi:[0,1]
	s_nop 0
	v_pk_add_f32 v[140:141], v[140:141], v[160:161]
	v_pk_add_f32 v[160:161], v[166:167], v[156:157]
	s_nop 0
	v_pk_add_f32 v[168:169], v[154:155], v[160:161] neg_lo:[0,1] neg_hi:[0,1]
	v_pk_add_f32 v[166:167], v[160:161], v[166:167] neg_lo:[0,1] neg_hi:[0,1]
	v_pk_add_f32 v[154:155], v[154:155], v[168:169] neg_lo:[0,1] neg_hi:[0,1]
	s_nop 0
	v_pk_add_f32 v[154:155], v[154:155], v[160:161] neg_lo:[0,1] neg_hi:[0,1]
	s_nop 0
	v_pk_add_f32 v[140:141], v[140:141], v[154:155]
	v_pk_add_f32 v[154:155], v[166:167], v[156:157] neg_lo:[0,1] neg_hi:[0,1]
	s_nop 0
	v_pk_add_f32 v[140:141], v[154:155], v[140:141]
	v_pk_add_f32 v[154:155], v[158:159], v[164:165]
	v_pk_add_f32 v[140:141], v[168:169], v[140:141]
	v_pk_add_f32 v[156:157], v[154:155], v[158:159] neg_lo:[0,1] neg_hi:[0,1]
	v_pk_mul_f32 v[140:141], v[162:163], v[140:141]
	v_pk_add_f32 v[156:157], v[164:165], v[156:157] neg_lo:[0,1] neg_hi:[0,1]
	s_nop 0
	v_pk_add_f32 v[140:141], v[156:157], v[140:141]
	s_nop 0
	v_pk_add_f32 v[156:157], v[154:155], v[140:141]
	s_nop 0
	v_pk_mul_f32 v[158:159], v[156:157], v[156:157]
	v_pk_add_f32 v[154:155], v[156:157], v[154:155] neg_lo:[0,1] neg_hi:[0,1]
	v_pk_fma_f32 v[160:161], v[158:159], s[6:7], v[142:143] op_sel_hi:[1,0,0]
	v_pk_add_f32 v[140:141], v[140:141], v[154:155] neg_lo:[0,1] neg_hi:[0,1]
	v_ldexp_f32 v154, v156, 1
	v_pk_fma_f32 v[160:161], v[158:159], v[160:161], s[8:9] op_sel_hi:[1,1,0]
	v_ldexp_f32 v155, v157, 1
	v_pk_mul_f32 v[156:157], v[156:157], v[158:159]
	v_cvt_f32_i32_e32 v159, v173
	v_cvt_f32_i32_e32 v158, v172
	v_pk_mul_f32 v[156:157], v[156:157], v[160:161]
	v_ldexp_f32 v163, v141, 1
	v_pk_add_f32 v[160:161], v[154:155], v[156:157]
	v_pk_mul_f32 v[164:165], v[158:159], s[36:37] op_sel_hi:[1,0]
	v_pk_add_f32 v[154:155], v[160:161], v[154:155] neg_lo:[0,1] neg_hi:[0,1]
	v_pk_fma_f32 v[166:167], v[158:159], s[36:37], v[164:165] op_sel_hi:[1,0,1] neg_lo:[0,0,1] neg_hi:[0,0,1]
	v_pk_add_f32 v[154:155], v[156:157], v[154:155] neg_lo:[0,1] neg_hi:[0,1]
	v_pk_fma_f32 v[158:159], v[158:159], s[10:11], v[166:167] op_sel_hi:[1,0,1]
	v_ldexp_f32 v140, v140, 1
	v_mov_b32_e32 v156, v164
	v_mov_b32_e32 v157, v155
	v_mov_b32_e32 v162, v158
	v_mov_b32_e32 v141, v163
	v_pk_add_f32 v[156:157], v[156:157], v[162:163]
	v_pk_add_f32 v[162:163], v[140:141], v[154:155]
	v_mov_b32_e32 v155, v161
	v_mov_b32_e32 v141, v163
	v_pk_add_f32 v[166:167], v[164:165], v[158:159]
	v_pk_add_f32 v[140:141], v[140:141], v[154:155]
	v_pk_add_f32 v[154:155], v[160:161], v[162:163]
	v_mov_b32_e32 v208, v160
	v_pk_add_f32 v[168:169], v[166:167], v[154:155]
	v_mov_b32_e32 v206, v154
	v_mov_b32_e32 v207, v169
	v_mov_b32_e32 v209, v167
	v_pk_add_f32 v[206:207], v[206:207], v[208:209] neg_lo:[0,1] neg_hi:[0,1]
	v_mov_b32_e32 v170, v168
	v_mov_b32_e32 v171, v167
	v_mov_b32_e32 v172, v166
	v_mov_b32_e32 v173, v165
	v_mov_b32_e32 v208, v166
	v_mov_b32_e32 v209, v169
	v_mov_b32_e32 v165, v207
	v_pk_add_f32 v[170:171], v[170:171], v[172:173] neg_lo:[0,1] neg_hi:[0,1]
	v_mov_b32_e32 v172, v154
	v_mov_b32_e32 v173, v159
	v_pk_add_f32 v[164:165], v[208:209], v[164:165] neg_lo:[0,1] neg_hi:[0,1]
	v_pk_add_f32 v[172:173], v[172:173], v[170:171] neg_lo:[0,1] neg_hi:[0,1]
	v_mov_b32_e32 v208, v164
	v_mov_b32_e32 v209, v171
	v_mov_b32_e32 v210, v168
	v_mov_b32_e32 v211, v155
	v_mov_b32_e32 v171, v161
	v_pk_add_f32 v[208:209], v[158:159], v[208:209] neg_lo:[0,1] neg_hi:[0,1]
	v_pk_add_f32 v[170:171], v[210:211], v[170:171] neg_lo:[0,1] neg_hi:[0,1]
	v_mov_b32_e32 v159, v167
	v_pk_add_f32 v[156:157], v[156:157], v[170:171] neg_lo:[0,1] neg_hi:[0,1]
	v_pk_add_f32 v[158:159], v[158:159], v[164:165] neg_lo:[0,1] neg_hi:[0,1]
	v_pk_add_f32 v[140:141], v[140:141], v[206:207] neg_lo:[0,1] neg_hi:[0,1]
	v_pk_add_f32 v[154:155], v[154:155], v[160:161] neg_lo:[0,1] neg_hi:[0,1]
	v_pk_add_f32 v[160:161], v[140:141], v[158:159]
	v_mov_b32_e32 v159, v173
	v_mov_b32_e32 v141, v157
	v_pk_add_f32 v[154:155], v[162:163], v[154:155] neg_lo:[0,1] neg_hi:[0,1]
	v_pk_add_f32 v[162:163], v[172:173], v[156:157]
	v_pk_add_f32 v[140:141], v[158:159], v[140:141]
	v_mov_b32_e32 v156, v160
	v_pk_add_f32 v[140:141], v[140:141], v[208:209] neg_lo:[0,1] neg_hi:[0,1]
	v_mov_b32_e32 v157, v163
	v_pk_add_f32 v[156:157], v[156:157], v[140:141] neg_lo:[0,1] neg_hi:[0,1]
	v_pk_add_f32 v[140:141], v[154:155], v[140:141] neg_lo:[0,1] neg_hi:[0,1]
	v_pk_add_f32 v[156:157], v[158:159], v[156:157] neg_lo:[0,1] neg_hi:[0,1]
	v_pk_add_f32 v[154:155], v[162:163], v[160:161]
	v_pk_add_f32 v[140:141], v[140:141], v[156:157]
	v_pk_add_f32 v[156:157], v[168:169], v[154:155]
	s_nop 0
; __device__ __forceinline__ float softplusf_(float x) { return fmaxf(x, 0.0f) + log1pf(__expf(-fabsf(x))); }
;     __device__ __forceinline__ void operator()(f32x4 (&acc)[2][2][4][2], const pg8::Unit& u, int wr, int wc, int fr, int fq) const {
;     ...
;             if (wc == 0) { const f32x4 b0 = *(const f32x4*)(dtb + cl0), b1 = *(const f32x4*)(dtb + cl0 + 4);
; #pragma unroll
;                 for (int ai = 0; ai < 2; ++ai)
; #pragma unroll
;                     for (int m = 0; m < 4; ++m) { const int row = row0 + ai * 128 + m * 16; const f32x4 v0 = acc[ai][0][m][0] + b0, v1 = acc[ai][0][m][1] + b1;
;                         float* d = DTA + (size_t)row * NH + cl0;
;                         *(f32x4*)d = (f32x4){softplusf_(v0[0]), softplusf_(v0[1]), softplusf_(v0[2]), softplusf_(v0[3])}; *(f32x4*)(d + 4) = (f32x4){softplusf_(v1[0]), softplusf_(v1[1]), softplusf_(v1[2]), softplusf_(v1[3])}; } }
	v_pk_add_f32 v[158:159], v[156:157], v[168:169] neg_lo:[0,1] neg_hi:[0,1]
	s_nop 0
	v_pk_add_f32 v[154:155], v[154:155], v[158:159] neg_lo:[0,1] neg_hi:[0,1]
	s_nop 0
	v_pk_add_f32 v[140:141], v[140:141], v[154:155]
	s_nop 0
	v_pk_add_f32 v[140:141], v[156:157], v[140:141]
	s_nop 0
	v_cndmask_b32_e32 v140, v252, v140, vcc
	v_cmp_neq_f32_e32 vcc, s3, v205
	s_nop 1
	v_cndmask_b32_e32 v141, v252, v141, vcc
	v_cmp_ngt_f32_e32 vcc, -1.0, v205
	s_nop 1
	v_cndmask_b32_e32 v141, v253, v141, vcc
	v_cmp_ngt_f32_e32 vcc, -1.0, v182
	s_nop 1
	v_cndmask_b32_e32 v140, v253, v140, vcc
	v_cmp_neq_f32_e32 vcc, -1.0, v182
	s_nop 1
	v_cndmask_b32_e32 v140, v244, v140, vcc
	v_cmp_neq_f32_e32 vcc, -1.0, v205
	s_nop 1
	v_cndmask_b32_e32 v141, v244, v141, vcc
	v_cmp_lt_f32_e64 vcc, |v182|, s4
	v_cndmask_b32_e64 v141, v141, v205, s[0:1]
	s_nop 0
	v_cndmask_b32_e32 v140, v140, v182, vcc
	v_pk_add_f32 v[140:141], v[152:153], v[140:141]
	global_store_dwordx4 v[146:147], v[138:141], off
	s_nop 1
	v_mul_f32_e64 v139, |v150|, s88
	v_exp_f32_e32 v182, v139
	v_max_f32_e32 v138, 0, v150
	v_add_f32_e32 v139, 1.0, v182
	v_add_f32_e32 v140, -1.0, v139
	v_sub_f32_e32 v141, v140, v139
	v_add_f32_e32 v141, 1.0, v141
	v_sub_f32_e32 v140, v182, v140
	v_add_f32_e32 v150, v140, v141
	v_frexp_mant_f32_e32 v140, v139
	v_cmp_gt_f32_e32 vcc, s2, v140
	v_cvt_f64_f32_e32 v[140:141], v139
	v_frexp_exp_i32_f64_e32 v140, v[140:141]
	v_subbrev_co_u32_e32 v168, vcc, 0, v140, vcc
	v_sub_u32_e32 v141, 0, v168
	v_ldexp_f32 v140, v139, v141
	v_ldexp_f32 v150, v150, v141
	v_mul_f32_e64 v141, |v151|, s88
	v_exp_f32_e32 v205, v141
	v_max_f32_e32 v139, 0, v151
	v_add_f32_e32 v141, 1.0, v205
	v_add_f32_e32 v151, -1.0, v141
	v_sub_f32_e32 v152, v151, v141
	v_add_f32_e32 v152, 1.0, v152
	v_sub_f32_e32 v151, v205, v151
	v_add_f32_e32 v151, v151, v152
	v_frexp_mant_f32_e32 v152, v141
	v_cmp_gt_f32_e32 vcc, s2, v152
	v_cvt_f64_f32_e32 v[152:153], v141
	v_frexp_exp_i32_f64_e32 v152, v[152:153]
	v_subbrev_co_u32_e32 v169, vcc, 0, v152, vcc
	v_sub_u32_e32 v152, 0, v169
	v_ldexp_f32 v141, v141, v152
	v_ldexp_f32 v151, v151, v152
	v_pk_add_f32 v[152:153], v[140:141], 1.0 op_sel_hi:[1,0]
	v_pk_add_f32 v[160:161], v[140:141], -1.0 op_sel_hi:[1,0]
	v_pk_add_f32 v[154:155], v[152:153], -1.0 op_sel_hi:[1,0]
	v_pk_add_f32 v[162:163], v[160:161], 1.0 op_sel_hi:[1,0]
	v_pk_add_f32 v[154:155], v[140:141], v[154:155] neg_lo:[0,1] neg_hi:[0,1]
	v_pk_add_f32 v[140:141], v[140:141], v[162:163] neg_lo:[0,1] neg_hi:[0,1]
	v_pk_add_f32 v[154:155], v[150:151], v[154:155]
	v_pk_add_f32 v[140:141], v[150:151], v[140:141]
	v_pk_add_f32 v[156:157], v[152:153], v[154:155]
	v_pk_add_f32 v[150:151], v[160:161], v[140:141]
	v_rcp_f32_e32 v158, v156
	v_rcp_f32_e32 v159, v157
	v_pk_add_f32 v[152:153], v[156:157], v[152:153] neg_lo:[0,1] neg_hi:[0,1]
	v_pk_add_f32 v[160:161], v[150:151], v[160:161] neg_lo:[0,1] neg_hi:[0,1]
	v_pk_add_f32 v[152:153], v[154:155], v[152:153] neg_lo:[0,1] neg_hi:[0,1]
	v_pk_mul_f32 v[154:155], v[150:151], v[158:159]
	v_pk_add_f32 v[140:141], v[140:141], v[160:161] neg_lo:[0,1] neg_hi:[0,1]
	v_pk_mul_f32 v[160:161], v[156:157], v[154:155]
	v_cmp_neq_f32_e32 vcc, s3, v182
	v_pk_fma_f32 v[162:163], v[154:155], v[156:157], v[160:161] neg_lo:[0,0,1] neg_hi:[0,0,1]
	v_cmp_lt_f32_e64 s[0:1], |v205|, s4
	v_pk_fma_f32 v[162:163], v[154:155], v[152:153], v[162:163]
	s_nop 0
	v_pk_add_f32 v[164:165], v[160:161], v[162:163]
	s_nop 0
	v_pk_add_f32 v[166:167], v[150:151], v[164:165] neg_lo:[0,1] neg_hi:[0,1]
	v_pk_add_f32 v[160:161], v[164:165], v[160:161] neg_lo:[0,1] neg_hi:[0,1]
	v_pk_add_f32 v[150:151], v[150:151], v[166:167] neg_lo:[0,1] neg_hi:[0,1]
	s_nop 0
	v_pk_add_f32 v[150:151], v[150:151], v[164:165] neg_lo:[0,1] neg_hi:[0,1]
	s_nop 0
	v_pk_add_f32 v[140:141], v[140:141], v[150:151]
	v_pk_add_f32 v[150:151], v[160:161], v[162:163] neg_lo:[0,1] neg_hi:[0,1]
	s_nop 0
	v_pk_add_f32 v[140:141], v[150:151], v[140:141]
	s_nop 0
	v_pk_add_f32 v[150:151], v[166:167], v[140:141]
	s_nop 0
	v_pk_mul_f32 v[160:161], v[158:159], v[150:151]
	s_nop 0
	v_pk_mul_f32 v[162:163], v[156:157], v[160:161]
	s_nop 0
	v_pk_fma_f32 v[156:157], v[160:161], v[156:157], v[162:163] neg_lo:[0,0,1] neg_hi:[0,0,1]
	s_nop 0
	v_pk_fma_f32 v[152:153], v[160:161], v[152:153], v[156:157]
	v_pk_add_f32 v[156:157], v[166:167], v[150:151] neg_lo:[0,1] neg_hi:[0,1]
	s_nop 0
	v_pk_add_f32 v[140:141], v[140:141], v[156:157]
	v_pk_add_f32 v[156:157], v[162:163], v[152:153]
	s_nop 0
	v_pk_add_f32 v[164:165], v[150:151], v[156:157] neg_lo:[0,1] neg_hi:[0,1]
	v_pk_add_f32 v[162:163], v[156:157], v[162:163] neg_lo:[0,1] neg_hi:[0,1]
	v_pk_add_f32 v[150:151], v[150:151], v[164:165] neg_lo:[0,1] neg_hi:[0,1]
	s_nop 0
	v_pk_add_f32 v[150:151], v[150:151], v[156:157] neg_lo:[0,1] neg_hi:[0,1]
	s_nop 0
	v_pk_add_f32 v[140:141], v[140:141], v[150:151]
	v_pk_add_f32 v[150:151], v[162:163], v[152:153] neg_lo:[0,1] neg_hi:[0,1]
	s_nop 0
	v_pk_add_f32 v[140:141], v[150:151], v[140:141]
	v_pk_add_f32 v[150:151], v[154:155], v[160:161]
	v_pk_add_f32 v[140:141], v[164:165], v[140:141]
	v_pk_add_f32 v[152:153], v[150:151], v[154:155] neg_lo:[0,1] neg_hi:[0,1]
	v_pk_mul_f32 v[140:141], v[158:159], v[140:141]
	v_pk_add_f32 v[152:153], v[160:161], v[152:153] neg_lo:[0,1] neg_hi:[0,1]
	s_nop 0
	v_pk_add_f32 v[140:141], v[152:153], v[140:141]
	s_nop 0
	v_pk_add_f32 v[152:153], v[150:151], v[140:141]
	s_nop 0
	v_pk_mul_f32 v[154:155], v[152:153], v[152:153]
	v_pk_add_f32 v[150:151], v[152:153], v[150:151] neg_lo:[0,1] neg_hi:[0,1]
	v_pk_fma_f32 v[156:157], v[154:155], s[6:7], v[142:143] op_sel_hi:[1,0,0]
	v_pk_add_f32 v[140:141], v[140:141], v[150:151] neg_lo:[0,1] neg_hi:[0,1]
; __device__ __forceinline__ float softplusf_(float x) { return fmaxf(x, 0.0f) + log1pf(__expf(-fabsf(x))); }
;     __device__ __forceinline__ void operator()(f32x4 (&acc)[2][2][4][2], const pg8::Unit& u, int wr, int wc, int fr, int fq) const {
;     ...
;             if (wc == 0) { const f32x4 b0 = *(const f32x4*)(dtb + cl0), b1 = *(const f32x4*)(dtb + cl0 + 4);
; #pragma unroll
;                 for (int ai = 0; ai < 2; ++ai)
; #pragma unroll
;                     for (int m = 0; m < 4; ++m) { const int row = row0 + ai * 128 + m * 16; const f32x4 v0 = acc[ai][0][m][0] + b0, v1 = acc[ai][0][m][1] + b1;
;                         float* d = DTA + (size_t)row * NH + cl0;
;                         *(f32x4*)d = (f32x4){softplusf_(v0[0]), softplusf_(v0[1]), softplusf_(v0[2]), softplusf_(v0[3])}; *(f32x4*)(d + 4) = (f32x4){softplusf_(v1[0]), softplusf_(v1[1]), softplusf_(v1[2]), softplusf_(v1[3])}; } }
	v_ldexp_f32 v150, v152, 1
	v_pk_fma_f32 v[156:157], v[154:155], v[156:157], s[8:9] op_sel_hi:[1,1,0]
	v_ldexp_f32 v151, v153, 1
	v_pk_mul_f32 v[152:153], v[152:153], v[154:155]
	v_cvt_f32_i32_e32 v155, v169
	v_cvt_f32_i32_e32 v154, v168
	v_pk_mul_f32 v[152:153], v[152:153], v[156:157]
	v_ldexp_f32 v159, v141, 1
	v_pk_add_f32 v[156:157], v[150:151], v[152:153]
	v_pk_mul_f32 v[160:161], v[154:155], s[36:37] op_sel_hi:[1,0]
	v_pk_add_f32 v[150:151], v[156:157], v[150:151] neg_lo:[0,1] neg_hi:[0,1]
	v_pk_fma_f32 v[162:163], v[154:155], s[36:37], v[160:161] op_sel_hi:[1,0,1] neg_lo:[0,0,1] neg_hi:[0,0,1]
	v_pk_add_f32 v[150:151], v[152:153], v[150:151] neg_lo:[0,1] neg_hi:[0,1]
	v_pk_fma_f32 v[154:155], v[154:155], s[10:11], v[162:163] op_sel_hi:[1,0,1]
	v_ldexp_f32 v140, v140, 1
	v_mov_b32_e32 v152, v160
	v_mov_b32_e32 v153, v151
	v_mov_b32_e32 v158, v154
	v_mov_b32_e32 v141, v159
	v_pk_add_f32 v[152:153], v[152:153], v[158:159]
	v_pk_add_f32 v[158:159], v[140:141], v[150:151]
	v_mov_b32_e32 v151, v157
	v_mov_b32_e32 v141, v159
	v_pk_add_f32 v[162:163], v[160:161], v[154:155]
	v_pk_add_f32 v[140:141], v[140:141], v[150:151]
	v_pk_add_f32 v[150:151], v[156:157], v[158:159]
	v_mov_b32_e32 v172, v156
	v_pk_add_f32 v[164:165], v[162:163], v[150:151]
	v_mov_b32_e32 v170, v150
	v_mov_b32_e32 v171, v165
	v_mov_b32_e32 v173, v163
	v_pk_add_f32 v[170:171], v[170:171], v[172:173] neg_lo:[0,1] neg_hi:[0,1]
	v_mov_b32_e32 v166, v164
	v_mov_b32_e32 v167, v163
	v_mov_b32_e32 v168, v162
	v_mov_b32_e32 v169, v161
	v_mov_b32_e32 v172, v162
	v_mov_b32_e32 v173, v165
	v_mov_b32_e32 v161, v171
	v_pk_add_f32 v[166:167], v[166:167], v[168:169] neg_lo:[0,1] neg_hi:[0,1]
	v_mov_b32_e32 v168, v150
	v_mov_b32_e32 v169, v155
	v_pk_add_f32 v[160:161], v[172:173], v[160:161] neg_lo:[0,1] neg_hi:[0,1]
	v_pk_add_f32 v[168:169], v[168:169], v[166:167] neg_lo:[0,1] neg_hi:[0,1]
	v_mov_b32_e32 v172, v160
	v_mov_b32_e32 v173, v167
	v_mov_b32_e32 v206, v164
	v_mov_b32_e32 v207, v151
	v_mov_b32_e32 v167, v157
	v_pk_add_f32 v[172:173], v[154:155], v[172:173] neg_lo:[0,1] neg_hi:[0,1]
	v_pk_add_f32 v[166:167], v[206:207], v[166:167] neg_lo:[0,1] neg_hi:[0,1]
	v_mov_b32_e32 v155, v163
	v_pk_add_f32 v[152:153], v[152:153], v[166:167] neg_lo:[0,1] neg_hi:[0,1]
	v_pk_add_f32 v[154:155], v[154:155], v[160:161] neg_lo:[0,1] neg_hi:[0,1]
	v_pk_add_f32 v[140:141], v[140:141], v[170:171] neg_lo:[0,1] neg_hi:[0,1]
	v_pk_add_f32 v[150:151], v[150:151], v[156:157] neg_lo:[0,1] neg_hi:[0,1]
	v_pk_add_f32 v[156:157], v[140:141], v[154:155]
	v_mov_b32_e32 v155, v169
	v_mov_b32_e32 v141, v153
	v_pk_add_f32 v[150:151], v[158:159], v[150:151] neg_lo:[0,1] neg_hi:[0,1]
	v_pk_add_f32 v[158:159], v[168:169], v[152:153]
	v_pk_add_f32 v[140:141], v[154:155], v[140:141]
	v_mov_b32_e32 v152, v156
	v_pk_add_f32 v[140:141], v[140:141], v[172:173] neg_lo:[0,1] neg_hi:[0,1]
	v_mov_b32_e32 v153, v159
	v_pk_add_f32 v[152:153], v[152:153], v[140:141] neg_lo:[0,1] neg_hi:[0,1]
	v_pk_add_f32 v[140:141], v[150:151], v[140:141] neg_lo:[0,1] neg_hi:[0,1]
	v_pk_add_f32 v[152:153], v[154:155], v[152:153] neg_lo:[0,1] neg_hi:[0,1]
	v_pk_add_f32 v[150:151], v[158:159], v[156:157]
	v_pk_add_f32 v[140:141], v[140:141], v[152:153]
	v_pk_add_f32 v[152:153], v[164:165], v[150:151]
	s_nop 0
	v_pk_add_f32 v[154:155], v[152:153], v[164:165] neg_lo:[0,1] neg_hi:[0,1]
	s_nop 0
	v_pk_add_f32 v[150:151], v[150:151], v[154:155] neg_lo:[0,1] neg_hi:[0,1]
	s_nop 0
	v_pk_add_f32 v[140:141], v[140:141], v[150:151]
	s_nop 0
	v_pk_add_f32 v[140:141], v[152:153], v[140:141]
	s_nop 0
	v_cndmask_b32_e32 v140, v252, v140, vcc
	v_cmp_neq_f32_e32 vcc, s3, v205
	s_nop 1
	v_cndmask_b32_e32 v141, v252, v141, vcc
	v_cmp_ngt_f32_e32 vcc, -1.0, v205
	s_nop 1
	v_cndmask_b32_e32 v141, v253, v141, vcc
	v_cmp_ngt_f32_e32 vcc, -1.0, v182
	s_nop 1
	v_cndmask_b32_e32 v140, v253, v140, vcc
	v_cmp_neq_f32_e32 vcc, -1.0, v182
	s_nop 1
	v_cndmask_b32_e32 v140, v244, v140, vcc
	v_cmp_neq_f32_e32 vcc, -1.0, v205
	s_nop 1
	v_cndmask_b32_e32 v141, v244, v141, vcc
	v_cmp_lt_f32_e64 vcc, |v182|, s4
	v_cndmask_b32_e64 v141, v141, v205, s[0:1]
	s_nop 0
	v_cndmask_b32_e32 v140, v140, v182, vcc
	v_pk_add_f32 v[138:139], v[138:139], v[140:141]
	v_mul_f32_e64 v141, |v148|, s88
	v_exp_f32_e32 v182, v141
	v_max_f32_e32 v140, 0, v148
	v_add_f32_e32 v141, 1.0, v182
	v_add_f32_e32 v148, -1.0, v141
	v_sub_f32_e32 v150, v148, v141
	v_add_f32_e32 v150, 1.0, v150
	v_sub_f32_e32 v148, v182, v148
	v_add_f32_e32 v152, v148, v150
	v_frexp_mant_f32_e32 v148, v141
	v_cvt_f64_f32_e32 v[150:151], v141
	v_cmp_gt_f32_e32 vcc, s2, v148
	v_frexp_exp_i32_f64_e32 v148, v[150:151]
	s_nop 0
	v_subbrev_co_u32_e32 v168, vcc, 0, v148, vcc
	v_sub_u32_e32 v150, 0, v168
	v_ldexp_f32 v148, v141, v150
	v_max_f32_e32 v141, 0, v149
	v_mul_f32_e64 v149, |v149|, s88
	v_exp_f32_e32 v205, v149
	v_ldexp_f32 v150, v152, v150
	v_add_f32_e32 v149, 1.0, v205
	v_add_f32_e32 v151, -1.0, v149
	v_sub_f32_e32 v152, v151, v149
	v_add_f32_e32 v152, 1.0, v152
	v_sub_f32_e32 v151, v205, v151
	v_add_f32_e32 v151, v151, v152
	v_frexp_mant_f32_e32 v152, v149
	v_cmp_gt_f32_e32 vcc, s2, v152
	v_cvt_f64_f32_e32 v[152:153], v149
	v_frexp_exp_i32_f64_e32 v152, v[152:153]
	v_subbrev_co_u32_e32 v169, vcc, 0, v152, vcc
	v_sub_u32_e32 v152, 0, v169
	v_ldexp_f32 v149, v149, v152
	v_ldexp_f32 v151, v151, v152
	v_pk_add_f32 v[152:153], v[148:149], 1.0 op_sel_hi:[1,0]
	v_pk_add_f32 v[160:161], v[148:149], -1.0 op_sel_hi:[1,0]
	v_pk_add_f32 v[154:155], v[152:153], -1.0 op_sel_hi:[1,0]
	v_pk_add_f32 v[162:163], v[160:161], 1.0 op_sel_hi:[1,0]
	v_pk_add_f32 v[154:155], v[148:149], v[154:155] neg_lo:[0,1] neg_hi:[0,1]
; __device__ __forceinline__ float softplusf_(float x) { return fmaxf(x, 0.0f) + log1pf(__expf(-fabsf(x))); }
;     __device__ __forceinline__ void operator()(f32x4 (&acc)[2][2][4][2], const pg8::Unit& u, int wr, int wc, int fr, int fq) const {
;     ...
;             if (wc == 0) { const f32x4 b0 = *(const f32x4*)(dtb + cl0), b1 = *(const f32x4*)(dtb + cl0 + 4);
; #pragma unroll
;                 for (int ai = 0; ai < 2; ++ai)
; #pragma unroll
;                     for (int m = 0; m < 4; ++m) { const int row = row0 + ai * 128 + m * 16; const f32x4 v0 = acc[ai][0][m][0] + b0, v1 = acc[ai][0][m][1] + b1;
;                         float* d = DTA + (size_t)row * NH + cl0;
;                         *(f32x4*)d = (f32x4){softplusf_(v0[0]), softplusf_(v0[1]), softplusf_(v0[2]), softplusf_(v0[3])}; *(f32x4*)(d + 4) = (f32x4){softplusf_(v1[0]), softplusf_(v1[1]), softplusf_(v1[2]), softplusf_(v1[3])}; } }
	v_pk_add_f32 v[148:149], v[148:149], v[162:163] neg_lo:[0,1] neg_hi:[0,1]
	v_pk_add_f32 v[154:155], v[150:151], v[154:155]
	v_pk_add_f32 v[148:149], v[150:151], v[148:149]
	v_pk_add_f32 v[156:157], v[152:153], v[154:155]
	v_pk_add_f32 v[150:151], v[160:161], v[148:149]
	v_rcp_f32_e32 v158, v156
	v_rcp_f32_e32 v159, v157
	v_pk_add_f32 v[152:153], v[156:157], v[152:153] neg_lo:[0,1] neg_hi:[0,1]
	v_pk_add_f32 v[160:161], v[150:151], v[160:161] neg_lo:[0,1] neg_hi:[0,1]
	v_pk_add_f32 v[152:153], v[154:155], v[152:153] neg_lo:[0,1] neg_hi:[0,1]
	v_pk_mul_f32 v[154:155], v[150:151], v[158:159]
	v_pk_add_f32 v[148:149], v[148:149], v[160:161] neg_lo:[0,1] neg_hi:[0,1]
	v_pk_mul_f32 v[160:161], v[156:157], v[154:155]
	v_cmp_neq_f32_e32 vcc, s3, v182
	v_pk_fma_f32 v[162:163], v[154:155], v[156:157], v[160:161] neg_lo:[0,0,1] neg_hi:[0,0,1]
	v_cmp_lt_f32_e64 s[0:1], |v205|, s4
	v_pk_fma_f32 v[162:163], v[154:155], v[152:153], v[162:163]
	s_nop 0
	v_pk_add_f32 v[164:165], v[160:161], v[162:163]
	s_nop 0
	v_pk_add_f32 v[166:167], v[150:151], v[164:165] neg_lo:[0,1] neg_hi:[0,1]
	v_pk_add_f32 v[160:161], v[164:165], v[160:161] neg_lo:[0,1] neg_hi:[0,1]
	v_pk_add_f32 v[150:151], v[150:151], v[166:167] neg_lo:[0,1] neg_hi:[0,1]
	s_nop 0
	v_pk_add_f32 v[150:151], v[150:151], v[164:165] neg_lo:[0,1] neg_hi:[0,1]
	s_nop 0
	v_pk_add_f32 v[148:149], v[148:149], v[150:151]
	v_pk_add_f32 v[150:151], v[160:161], v[162:163] neg_lo:[0,1] neg_hi:[0,1]
	s_nop 0
	v_pk_add_f32 v[148:149], v[150:151], v[148:149]
	s_nop 0
	v_pk_add_f32 v[150:151], v[166:167], v[148:149]
	s_nop 0
	v_pk_mul_f32 v[160:161], v[158:159], v[150:151]
	s_nop 0
	v_pk_mul_f32 v[162:163], v[156:157], v[160:161]
	s_nop 0
	v_pk_fma_f32 v[156:157], v[160:161], v[156:157], v[162:163] neg_lo:[0,0,1] neg_hi:[0,0,1]
	s_nop 0
	v_pk_fma_f32 v[152:153], v[160:161], v[152:153], v[156:157]
	v_pk_add_f32 v[156:157], v[166:167], v[150:151] neg_lo:[0,1] neg_hi:[0,1]
	s_nop 0
	v_pk_add_f32 v[148:149], v[148:149], v[156:157]
	v_pk_add_f32 v[156:157], v[162:163], v[152:153]
	s_nop 0
	v_pk_add_f32 v[164:165], v[150:151], v[156:157] neg_lo:[0,1] neg_hi:[0,1]
	v_pk_add_f32 v[162:163], v[156:157], v[162:163] neg_lo:[0,1] neg_hi:[0,1]
	v_pk_add_f32 v[150:151], v[150:151], v[164:165] neg_lo:[0,1] neg_hi:[0,1]
	s_nop 0
	v_pk_add_f32 v[150:151], v[150:151], v[156:157] neg_lo:[0,1] neg_hi:[0,1]
	s_nop 0
	v_pk_add_f32 v[148:149], v[148:149], v[150:151]
	v_pk_add_f32 v[150:151], v[162:163], v[152:153] neg_lo:[0,1] neg_hi:[0,1]
	s_nop 0
	v_pk_add_f32 v[148:149], v[150:151], v[148:149]
	v_pk_add_f32 v[150:151], v[154:155], v[160:161]
	v_pk_add_f32 v[148:149], v[164:165], v[148:149]
	v_pk_add_f32 v[152:153], v[150:151], v[154:155] neg_lo:[0,1] neg_hi:[0,1]
	v_pk_mul_f32 v[148:149], v[158:159], v[148:149]
	v_pk_add_f32 v[152:153], v[160:161], v[152:153] neg_lo:[0,1] neg_hi:[0,1]
	s_nop 0
	v_pk_add_f32 v[148:149], v[152:153], v[148:149]
	s_nop 0
	v_pk_add_f32 v[152:153], v[150:151], v[148:149]
	s_nop 0
	v_pk_mul_f32 v[154:155], v[152:153], v[152:153]
	v_pk_add_f32 v[150:151], v[152:153], v[150:151] neg_lo:[0,1] neg_hi:[0,1]
	v_pk_fma_f32 v[156:157], v[154:155], s[6:7], v[142:143] op_sel_hi:[1,0,0]
	v_pk_add_f32 v[148:149], v[148:149], v[150:151] neg_lo:[0,1] neg_hi:[0,1]
	v_ldexp_f32 v150, v152, 1
	v_pk_fma_f32 v[156:157], v[154:155], v[156:157], s[8:9] op_sel_hi:[1,1,0]
	v_ldexp_f32 v151, v153, 1
	v_pk_mul_f32 v[152:153], v[152:153], v[154:155]
	v_cvt_f32_i32_e32 v155, v169
	v_cvt_f32_i32_e32 v154, v168
	v_pk_mul_f32 v[152:153], v[152:153], v[156:157]
	v_ldexp_f32 v159, v149, 1
	v_pk_add_f32 v[156:157], v[150:151], v[152:153]
	v_pk_mul_f32 v[160:161], v[154:155], s[36:37] op_sel_hi:[1,0]
	v_pk_add_f32 v[150:151], v[156:157], v[150:151] neg_lo:[0,1] neg_hi:[0,1]
	v_pk_fma_f32 v[162:163], v[154:155], s[36:37], v[160:161] op_sel_hi:[1,0,1] neg_lo:[0,0,1] neg_hi:[0,0,1]
	v_pk_add_f32 v[150:151], v[152:153], v[150:151] neg_lo:[0,1] neg_hi:[0,1]
	v_pk_fma_f32 v[154:155], v[154:155], s[10:11], v[162:163] op_sel_hi:[1,0,1]
	v_ldexp_f32 v148, v148, 1
	v_mov_b32_e32 v152, v160
	v_mov_b32_e32 v153, v151
	v_mov_b32_e32 v158, v154
	v_mov_b32_e32 v149, v159
	v_pk_add_f32 v[152:153], v[152:153], v[158:159]
	v_pk_add_f32 v[158:159], v[148:149], v[150:151]
	v_mov_b32_e32 v151, v157
	v_mov_b32_e32 v149, v159
	v_pk_add_f32 v[162:163], v[160:161], v[154:155]
	v_pk_add_f32 v[148:149], v[148:149], v[150:151]
	v_pk_add_f32 v[150:151], v[156:157], v[158:159]
	v_mov_b32_e32 v172, v156
	v_pk_add_f32 v[164:165], v[162:163], v[150:151]
	v_mov_b32_e32 v170, v150
	v_mov_b32_e32 v171, v165
	v_mov_b32_e32 v173, v163
	v_pk_add_f32 v[170:171], v[170:171], v[172:173] neg_lo:[0,1] neg_hi:[0,1]
	v_mov_b32_e32 v166, v164
	v_mov_b32_e32 v167, v163
	v_mov_b32_e32 v168, v162
	v_mov_b32_e32 v169, v161
	v_mov_b32_e32 v172, v162
	v_mov_b32_e32 v173, v165
	v_mov_b32_e32 v161, v171
	v_pk_add_f32 v[166:167], v[166:167], v[168:169] neg_lo:[0,1] neg_hi:[0,1]
	v_mov_b32_e32 v168, v150
	v_mov_b32_e32 v169, v155
	v_pk_add_f32 v[160:161], v[172:173], v[160:161] neg_lo:[0,1] neg_hi:[0,1]
	v_pk_add_f32 v[168:169], v[168:169], v[166:167] neg_lo:[0,1] neg_hi:[0,1]
	v_mov_b32_e32 v172, v160
	v_mov_b32_e32 v173, v167
	v_mov_b32_e32 v206, v164
	v_mov_b32_e32 v207, v151
	v_mov_b32_e32 v167, v157
	v_pk_add_f32 v[172:173], v[154:155], v[172:173] neg_lo:[0,1] neg_hi:[0,1]
	v_pk_add_f32 v[166:167], v[206:207], v[166:167] neg_lo:[0,1] neg_hi:[0,1]
	v_mov_b32_e32 v155, v163
	v_pk_add_f32 v[152:153], v[152:153], v[166:167] neg_lo:[0,1] neg_hi:[0,1]
	v_pk_add_f32 v[154:155], v[154:155], v[160:161] neg_lo:[0,1] neg_hi:[0,1]
	v_pk_add_f32 v[148:149], v[148:149], v[170:171] neg_lo:[0,1] neg_hi:[0,1]
; __device__ __forceinline__ float softplusf_(float x) { return fmaxf(x, 0.0f) + log1pf(__expf(-fabsf(x))); }
;     __device__ __forceinline__ void operator()(f32x4 (&acc)[2][2][4][2], const pg8::Unit& u, int wr, int wc, int fr, int fq) const {
;     ...
;             if (wc == 0) { const f32x4 b0 = *(const f32x4*)(dtb + cl0), b1 = *(const f32x4*)(dtb + cl0 + 4);
; #pragma unroll
;                 for (int ai = 0; ai < 2; ++ai)
; #pragma unroll
;                     for (int m = 0; m < 4; ++m) { const int row = row0 + ai * 128 + m * 16; const f32x4 v0 = acc[ai][0][m][0] + b0, v1 = acc[ai][0][m][1] + b1;
;                         float* d = DTA + (size_t)row * NH + cl0;
;                         *(f32x4*)d = (f32x4){softplusf_(v0[0]), softplusf_(v0[1]), softplusf_(v0[2]), softplusf_(v0[3])}; *(f32x4*)(d + 4) = (f32x4){softplusf_(v1[0]), softplusf_(v1[1]), softplusf_(v1[2]), softplusf_(v1[3])}; } }
	v_pk_add_f32 v[150:151], v[150:151], v[156:157] neg_lo:[0,1] neg_hi:[0,1]
	v_pk_add_f32 v[156:157], v[148:149], v[154:155]
	v_mov_b32_e32 v155, v169
	v_mov_b32_e32 v149, v153
	v_pk_add_f32 v[150:151], v[158:159], v[150:151] neg_lo:[0,1] neg_hi:[0,1]
	v_pk_add_f32 v[158:159], v[168:169], v[152:153]
	v_pk_add_f32 v[148:149], v[154:155], v[148:149]
	v_mov_b32_e32 v152, v156
	v_pk_add_f32 v[148:149], v[148:149], v[172:173] neg_lo:[0,1] neg_hi:[0,1]
	v_mov_b32_e32 v153, v159
	v_pk_add_f32 v[152:153], v[152:153], v[148:149] neg_lo:[0,1] neg_hi:[0,1]
	v_pk_add_f32 v[148:149], v[150:151], v[148:149] neg_lo:[0,1] neg_hi:[0,1]
	v_pk_add_f32 v[152:153], v[154:155], v[152:153] neg_lo:[0,1] neg_hi:[0,1]
	v_pk_add_f32 v[150:151], v[158:159], v[156:157]
	v_pk_add_f32 v[148:149], v[148:149], v[152:153]
	v_pk_add_f32 v[152:153], v[164:165], v[150:151]
	s_nop 0
	v_pk_add_f32 v[154:155], v[152:153], v[164:165] neg_lo:[0,1] neg_hi:[0,1]
	s_nop 0
	v_pk_add_f32 v[150:151], v[150:151], v[154:155] neg_lo:[0,1] neg_hi:[0,1]
	s_nop 0
	v_pk_add_f32 v[148:149], v[148:149], v[150:151]
	v_pk_add_f32 v[150:151], v[30:31], v[130:131]
	v_pk_add_f32 v[148:149], v[152:153], v[148:149]
	v_pk_add_f32 v[152:153], v[26:27], v[134:135]
	v_cndmask_b32_e32 v148, v252, v148, vcc
	v_cmp_neq_f32_e32 vcc, s3, v205
	s_nop 1
	v_cndmask_b32_e32 v149, v252, v149, vcc
	v_cmp_ngt_f32_e32 vcc, -1.0, v205
	s_nop 1
	v_cndmask_b32_e32 v149, v253, v149, vcc
	v_cmp_ngt_f32_e32 vcc, -1.0, v182
	s_nop 1
	v_cndmask_b32_e32 v148, v253, v148, vcc
	v_cmp_neq_f32_e32 vcc, -1.0, v182
	s_nop 1
	v_cndmask_b32_e32 v148, v244, v148, vcc
	v_cmp_neq_f32_e32 vcc, -1.0, v205
	s_nop 1
	v_cndmask_b32_e32 v149, v244, v149, vcc
	v_cmp_lt_f32_e64 vcc, |v182|, s4
	v_cndmask_b32_e64 v149, v149, v205, s[0:1]
	s_nop 0
	v_cndmask_b32_e32 v148, v148, v182, vcc
	v_pk_add_f32 v[140:141], v[140:141], v[148:149]
	global_store_dwordx4 v[146:147], v[138:141], off offset:16
	v_pk_add_f32 v[148:149], v[32:33], v[132:133]
	s_nop 0
	v_lshlrev_b64 v[138:139], 7, v[190:191]
	v_lshl_add_u64 v[146:147], v[144:145], 0, v[138:139]
	v_mul_f32_e64 v139, |v152|, s88
	v_exp_f32_e32 v182, v139
	v_max_f32_e32 v138, 0, v152
	v_pk_add_f32 v[140:141], v[28:29], v[136:137]
	v_add_f32_e32 v139, 1.0, v182
	v_add_f32_e32 v152, -1.0, v139
	v_sub_f32_e32 v154, v152, v139
	v_add_f32_e32 v154, 1.0, v154
	v_sub_f32_e32 v152, v182, v152
	v_add_f32_e32 v156, v152, v154
	v_frexp_mant_f32_e32 v152, v139
	v_cvt_f64_f32_e32 v[154:155], v139
	v_cmp_gt_f32_e32 vcc, s2, v152
	v_frexp_exp_i32_f64_e32 v152, v[154:155]
	s_nop 0
	v_subbrev_co_u32_e32 v172, vcc, 0, v152, vcc
	v_sub_u32_e32 v154, 0, v172
	v_ldexp_f32 v152, v139, v154
	v_max_f32_e32 v139, 0, v153
	v_mul_f32_e64 v153, |v153|, s88
	v_exp_f32_e32 v205, v153
	v_ldexp_f32 v154, v156, v154
	v_add_f32_e32 v153, 1.0, v205
	v_add_f32_e32 v155, -1.0, v153
	v_sub_f32_e32 v156, v155, v153
	v_add_f32_e32 v156, 1.0, v156
	v_sub_f32_e32 v155, v205, v155
	v_add_f32_e32 v155, v155, v156
	v_frexp_mant_f32_e32 v156, v153
	v_cmp_gt_f32_e32 vcc, s2, v156
	v_cvt_f64_f32_e32 v[156:157], v153
	v_frexp_exp_i32_f64_e32 v156, v[156:157]
	v_subbrev_co_u32_e32 v173, vcc, 0, v156, vcc
	v_sub_u32_e32 v156, 0, v173
	v_ldexp_f32 v153, v153, v156
	v_ldexp_f32 v155, v155, v156
	v_pk_add_f32 v[156:157], v[152:153], 1.0 op_sel_hi:[1,0]
	v_pk_add_f32 v[164:165], v[152:153], -1.0 op_sel_hi:[1,0]
	v_pk_add_f32 v[158:159], v[156:157], -1.0 op_sel_hi:[1,0]
	v_pk_add_f32 v[166:167], v[164:165], 1.0 op_sel_hi:[1,0]
	v_pk_add_f32 v[158:159], v[152:153], v[158:159] neg_lo:[0,1] neg_hi:[0,1]
	v_pk_add_f32 v[152:153], v[152:153], v[166:167] neg_lo:[0,1] neg_hi:[0,1]
	v_pk_add_f32 v[158:159], v[154:155], v[158:159]
	v_pk_add_f32 v[152:153], v[154:155], v[152:153]
	v_pk_add_f32 v[160:161], v[156:157], v[158:159]
	v_pk_add_f32 v[154:155], v[164:165], v[152:153]
	v_rcp_f32_e32 v162, v160
	v_rcp_f32_e32 v163, v161
	v_pk_add_f32 v[156:157], v[160:161], v[156:157] neg_lo:[0,1] neg_hi:[0,1]
	v_pk_add_f32 v[164:165], v[154:155], v[164:165] neg_lo:[0,1] neg_hi:[0,1]
	v_pk_add_f32 v[156:157], v[158:159], v[156:157] neg_lo:[0,1] neg_hi:[0,1]
	v_pk_mul_f32 v[158:159], v[154:155], v[162:163]
	v_pk_add_f32 v[152:153], v[152:153], v[164:165] neg_lo:[0,1] neg_hi:[0,1]
	v_pk_mul_f32 v[164:165], v[160:161], v[158:159]
	v_cmp_neq_f32_e32 vcc, s3, v182
	v_pk_fma_f32 v[166:167], v[158:159], v[160:161], v[164:165] neg_lo:[0,0,1] neg_hi:[0,0,1]
	v_cmp_lt_f32_e64 s[0:1], |v205|, s4
	v_pk_fma_f32 v[166:167], v[158:159], v[156:157], v[166:167]
	s_nop 0
	v_pk_add_f32 v[168:169], v[164:165], v[166:167]
	s_nop 0
	v_pk_add_f32 v[170:171], v[154:155], v[168:169] neg_lo:[0,1] neg_hi:[0,1]
	v_pk_add_f32 v[164:165], v[168:169], v[164:165] neg_lo:[0,1] neg_hi:[0,1]
	v_pk_add_f32 v[154:155], v[154:155], v[170:171] neg_lo:[0,1] neg_hi:[0,1]
	s_nop 0
	v_pk_add_f32 v[154:155], v[154:155], v[168:169] neg_lo:[0,1] neg_hi:[0,1]
	s_nop 0
	v_pk_add_f32 v[152:153], v[152:153], v[154:155]
	v_pk_add_f32 v[154:155], v[164:165], v[166:167] neg_lo:[0,1] neg_hi:[0,1]
	s_nop 0
	v_pk_add_f32 v[152:153], v[154:155], v[152:153]
	s_nop 0
	v_pk_add_f32 v[154:155], v[170:171], v[152:153]
	s_nop 0
	v_pk_mul_f32 v[164:165], v[162:163], v[154:155]
	s_nop 0
	v_pk_mul_f32 v[166:167], v[160:161], v[164:165]
	s_nop 0
	v_pk_fma_f32 v[160:161], v[164:165], v[160:161], v[166:167] neg_lo:[0,0,1] neg_hi:[0,0,1]
	s_nop 0
	v_pk_fma_f32 v[156:157], v[164:165], v[156:157], v[160:161]
	v_pk_add_f32 v[160:161], v[170:171], v[154:155] neg_lo:[0,1] neg_hi:[0,1]
	s_nop 0
	v_pk_add_f32 v[152:153], v[152:153], v[160:161]
	v_pk_add_f32 v[160:161], v[166:167], v[156:157]
	s_nop 0
	v_pk_add_f32 v[168:169], v[154:155], v[160:161] neg_lo:[0,1] neg_hi:[0,1]
; __device__ __forceinline__ float softplusf_(float x) { return fmaxf(x, 0.0f) + log1pf(__expf(-fabsf(x))); }
;     __device__ __forceinline__ void operator()(f32x4 (&acc)[2][2][4][2], const pg8::Unit& u, int wr, int wc, int fr, int fq) const {
;     ...
;             if (wc == 0) { const f32x4 b0 = *(const f32x4*)(dtb + cl0), b1 = *(const f32x4*)(dtb + cl0 + 4);
; #pragma unroll
;                 for (int ai = 0; ai < 2; ++ai)
; #pragma unroll
;                     for (int m = 0; m < 4; ++m) { const int row = row0 + ai * 128 + m * 16; const f32x4 v0 = acc[ai][0][m][0] + b0, v1 = acc[ai][0][m][1] + b1;
;                         float* d = DTA + (size_t)row * NH + cl0;
;                         *(f32x4*)d = (f32x4){softplusf_(v0[0]), softplusf_(v0[1]), softplusf_(v0[2]), softplusf_(v0[3])}; *(f32x4*)(d + 4) = (f32x4){softplusf_(v1[0]), softplusf_(v1[1]), softplusf_(v1[2]), softplusf_(v1[3])}; } }
	v_pk_add_f32 v[166:167], v[160:161], v[166:167] neg_lo:[0,1] neg_hi:[0,1]
	v_pk_add_f32 v[154:155], v[154:155], v[168:169] neg_lo:[0,1] neg_hi:[0,1]
	s_nop 0
	v_pk_add_f32 v[154:155], v[154:155], v[160:161] neg_lo:[0,1] neg_hi:[0,1]
	s_nop 0
	v_pk_add_f32 v[152:153], v[152:153], v[154:155]
	v_pk_add_f32 v[154:155], v[166:167], v[156:157] neg_lo:[0,1] neg_hi:[0,1]
	s_nop 0
	v_pk_add_f32 v[152:153], v[154:155], v[152:153]
	v_pk_add_f32 v[154:155], v[158:159], v[164:165]
	v_pk_add_f32 v[152:153], v[168:169], v[152:153]
	v_pk_add_f32 v[156:157], v[154:155], v[158:159] neg_lo:[0,1] neg_hi:[0,1]
	v_pk_mul_f32 v[152:153], v[162:163], v[152:153]
	v_pk_add_f32 v[156:157], v[164:165], v[156:157] neg_lo:[0,1] neg_hi:[0,1]
	s_nop 0
	v_pk_add_f32 v[152:153], v[156:157], v[152:153]
	s_nop 0
	v_pk_add_f32 v[156:157], v[154:155], v[152:153]
	s_nop 0
	v_pk_mul_f32 v[158:159], v[156:157], v[156:157]
	v_pk_add_f32 v[154:155], v[156:157], v[154:155] neg_lo:[0,1] neg_hi:[0,1]
	v_pk_fma_f32 v[160:161], v[158:159], s[6:7], v[142:143] op_sel_hi:[1,0,0]
	v_pk_add_f32 v[152:153], v[152:153], v[154:155] neg_lo:[0,1] neg_hi:[0,1]
	v_ldexp_f32 v154, v156, 1
	v_pk_fma_f32 v[160:161], v[158:159], v[160:161], s[8:9] op_sel_hi:[1,1,0]
	v_ldexp_f32 v155, v157, 1
	v_pk_mul_f32 v[156:157], v[156:157], v[158:159]
	v_cvt_f32_i32_e32 v159, v173
	v_cvt_f32_i32_e32 v158, v172
	v_pk_mul_f32 v[156:157], v[156:157], v[160:161]
	v_ldexp_f32 v163, v153, 1
	v_pk_add_f32 v[160:161], v[154:155], v[156:157]
	v_pk_mul_f32 v[164:165], v[158:159], s[36:37] op_sel_hi:[1,0]
	v_pk_add_f32 v[154:155], v[160:161], v[154:155] neg_lo:[0,1] neg_hi:[0,1]
	v_pk_fma_f32 v[166:167], v[158:159], s[36:37], v[164:165] op_sel_hi:[1,0,1] neg_lo:[0,0,1] neg_hi:[0,0,1]
	v_pk_add_f32 v[154:155], v[156:157], v[154:155] neg_lo:[0,1] neg_hi:[0,1]
	v_pk_fma_f32 v[158:159], v[158:159], s[10:11], v[166:167] op_sel_hi:[1,0,1]
	v_ldexp_f32 v152, v152, 1
	v_mov_b32_e32 v156, v164
	v_mov_b32_e32 v157, v155
	v_mov_b32_e32 v162, v158
	v_mov_b32_e32 v153, v163
	v_pk_add_f32 v[156:157], v[156:157], v[162:163]
	v_pk_add_f32 v[162:163], v[152:153], v[154:155]
	v_mov_b32_e32 v155, v161
	v_mov_b32_e32 v153, v163
	v_pk_add_f32 v[166:167], v[164:165], v[158:159]
	v_pk_add_f32 v[152:153], v[152:153], v[154:155]
	v_pk_add_f32 v[154:155], v[160:161], v[162:163]
	v_mov_b32_e32 v208, v160
	v_pk_add_f32 v[168:169], v[166:167], v[154:155]
	v_mov_b32_e32 v206, v154
	v_mov_b32_e32 v207, v169
	v_mov_b32_e32 v209, v167
	v_pk_add_f32 v[206:207], v[206:207], v[208:209] neg_lo:[0,1] neg_hi:[0,1]
	v_mov_b32_e32 v170, v168
	v_mov_b32_e32 v171, v167
	v_mov_b32_e32 v172, v166
	v_mov_b32_e32 v173, v165
	v_mov_b32_e32 v208, v166
	v_mov_b32_e32 v209, v169
	v_mov_b32_e32 v165, v207
	v_pk_add_f32 v[170:171], v[170:171], v[172:173] neg_lo:[0,1] neg_hi:[0,1]
	v_mov_b32_e32 v172, v154
	v_mov_b32_e32 v173, v159
	v_pk_add_f32 v[164:165], v[208:209], v[164:165] neg_lo:[0,1] neg_hi:[0,1]
	v_pk_add_f32 v[172:173], v[172:173], v[170:171] neg_lo:[0,1] neg_hi:[0,1]
	v_mov_b32_e32 v208, v164
	v_mov_b32_e32 v209, v171
	v_mov_b32_e32 v210, v168
	v_mov_b32_e32 v211, v155
	v_mov_b32_e32 v171, v161
	v_pk_add_f32 v[208:209], v[158:159], v[208:209] neg_lo:[0,1] neg_hi:[0,1]
	v_pk_add_f32 v[170:171], v[210:211], v[170:171] neg_lo:[0,1] neg_hi:[0,1]
	v_mov_b32_e32 v159, v167
	v_pk_add_f32 v[156:157], v[156:157], v[170:171] neg_lo:[0,1] neg_hi:[0,1]
	v_pk_add_f32 v[158:159], v[158:159], v[164:165] neg_lo:[0,1] neg_hi:[0,1]
	v_pk_add_f32 v[152:153], v[152:153], v[206:207] neg_lo:[0,1] neg_hi:[0,1]
	v_pk_add_f32 v[154:155], v[154:155], v[160:161] neg_lo:[0,1] neg_hi:[0,1]
	v_pk_add_f32 v[160:161], v[152:153], v[158:159]
	v_mov_b32_e32 v159, v173
	v_mov_b32_e32 v153, v157
	v_pk_add_f32 v[154:155], v[162:163], v[154:155] neg_lo:[0,1] neg_hi:[0,1]
	v_pk_add_f32 v[162:163], v[172:173], v[156:157]
	v_pk_add_f32 v[152:153], v[158:159], v[152:153]
	v_mov_b32_e32 v156, v160
	v_pk_add_f32 v[152:153], v[152:153], v[208:209] neg_lo:[0,1] neg_hi:[0,1]
	v_mov_b32_e32 v157, v163
	v_pk_add_f32 v[156:157], v[156:157], v[152:153] neg_lo:[0,1] neg_hi:[0,1]
	v_pk_add_f32 v[152:153], v[154:155], v[152:153] neg_lo:[0,1] neg_hi:[0,1]
	v_pk_add_f32 v[156:157], v[158:159], v[156:157] neg_lo:[0,1] neg_hi:[0,1]
	v_pk_add_f32 v[154:155], v[162:163], v[160:161]
	v_pk_add_f32 v[152:153], v[152:153], v[156:157]
	v_pk_add_f32 v[156:157], v[168:169], v[154:155]
	s_nop 0
	v_pk_add_f32 v[158:159], v[156:157], v[168:169] neg_lo:[0,1] neg_hi:[0,1]
	s_nop 0
	v_pk_add_f32 v[154:155], v[154:155], v[158:159] neg_lo:[0,1] neg_hi:[0,1]
	s_nop 0
	v_pk_add_f32 v[152:153], v[152:153], v[154:155]
	s_nop 0
	v_pk_add_f32 v[152:153], v[156:157], v[152:153]
	s_nop 0
	v_cndmask_b32_e32 v152, v252, v152, vcc
	v_cmp_neq_f32_e32 vcc, s3, v205
	s_nop 1
	v_cndmask_b32_e32 v153, v252, v153, vcc
	v_cmp_ngt_f32_e32 vcc, -1.0, v205
	s_nop 1
	v_cndmask_b32_e32 v153, v253, v153, vcc
	v_cmp_ngt_f32_e32 vcc, -1.0, v182
	s_nop 1
	v_cndmask_b32_e32 v152, v253, v152, vcc
	v_cmp_neq_f32_e32 vcc, -1.0, v182
	s_nop 1
	v_cndmask_b32_e32 v152, v244, v152, vcc
	v_cmp_neq_f32_e32 vcc, -1.0, v205
	s_nop 1
	v_cndmask_b32_e32 v153, v244, v153, vcc
	v_cmp_lt_f32_e64 vcc, |v182|, s4
	v_cndmask_b32_e64 v153, v153, v205, s[0:1]
	s_nop 0
	v_cndmask_b32_e32 v152, v152, v182, vcc
	v_pk_add_f32 v[138:139], v[138:139], v[152:153]
	v_max_f32_e32 v152, 0, v140
	v_mul_f32_e64 v140, |v140|, s88
	v_exp_f32_e32 v182, v140
	s_nop 0
	v_add_f32_e32 v140, 1.0, v182
	v_add_f32_e32 v153, -1.0, v140
	v_sub_f32_e32 v154, v153, v140
	v_add_f32_e32 v154, 1.0, v154
	v_sub_f32_e32 v153, v182, v153
	v_add_f32_e32 v153, v153, v154
	v_frexp_mant_f32_e32 v154, v140
; __device__ __forceinline__ float softplusf_(float x) { return fmaxf(x, 0.0f) + log1pf(__expf(-fabsf(x))); }
;     __device__ __forceinline__ void operator()(f32x4 (&acc)[2][2][4][2], const pg8::Unit& u, int wr, int wc, int fr, int fq) const {
;     ...
;             if (wc == 0) { const f32x4 b0 = *(const f32x4*)(dtb + cl0), b1 = *(const f32x4*)(dtb + cl0 + 4);
; #pragma unroll
;                 for (int ai = 0; ai < 2; ++ai)
; #pragma unroll
;                     for (int m = 0; m < 4; ++m) { const int row = row0 + ai * 128 + m * 16; const f32x4 v0 = acc[ai][0][m][0] + b0, v1 = acc[ai][0][m][1] + b1;
;                         float* d = DTA + (size_t)row * NH + cl0;
;                         *(f32x4*)d = (f32x4){softplusf_(v0[0]), softplusf_(v0[1]), softplusf_(v0[2]), softplusf_(v0[3])}; *(f32x4*)(d + 4) = (f32x4){softplusf_(v1[0]), softplusf_(v1[1]), softplusf_(v1[2]), softplusf_(v1[3])}; } }
	v_cmp_gt_f32_e32 vcc, s2, v154
	v_cvt_f64_f32_e32 v[154:155], v140
	v_frexp_exp_i32_f64_e32 v154, v[154:155]
	v_subbrev_co_u32_e32 v172, vcc, 0, v154, vcc
	v_sub_u32_e32 v154, 0, v172
	v_ldexp_f32 v140, v140, v154
	v_ldexp_f32 v154, v153, v154
	v_max_f32_e32 v153, 0, v141
	v_mul_f32_e64 v141, |v141|, s88
	v_exp_f32_e32 v205, v141
	s_nop 0
	v_add_f32_e32 v141, 1.0, v205
	v_add_f32_e32 v155, -1.0, v141
	v_sub_f32_e32 v156, v155, v141
	v_add_f32_e32 v156, 1.0, v156
	v_sub_f32_e32 v155, v205, v155
	v_add_f32_e32 v155, v155, v156
	v_frexp_mant_f32_e32 v156, v141
	v_cmp_gt_f32_e32 vcc, s2, v156
	v_cvt_f64_f32_e32 v[156:157], v141
	v_frexp_exp_i32_f64_e32 v156, v[156:157]
	v_subbrev_co_u32_e32 v173, vcc, 0, v156, vcc
	v_sub_u32_e32 v156, 0, v173
	v_ldexp_f32 v141, v141, v156
	v_ldexp_f32 v155, v155, v156
	v_pk_add_f32 v[156:157], v[140:141], 1.0 op_sel_hi:[1,0]
	v_pk_add_f32 v[164:165], v[140:141], -1.0 op_sel_hi:[1,0]
	v_pk_add_f32 v[158:159], v[156:157], -1.0 op_sel_hi:[1,0]
	v_pk_add_f32 v[166:167], v[164:165], 1.0 op_sel_hi:[1,0]
	v_pk_add_f32 v[158:159], v[140:141], v[158:159] neg_lo:[0,1] neg_hi:[0,1]
	v_pk_add_f32 v[140:141], v[140:141], v[166:167] neg_lo:[0,1] neg_hi:[0,1]
	v_pk_add_f32 v[158:159], v[154:155], v[158:159]
	v_pk_add_f32 v[140:141], v[154:155], v[140:141]
	v_pk_add_f32 v[160:161], v[156:157], v[158:159]
	v_pk_add_f32 v[154:155], v[164:165], v[140:141]
	v_rcp_f32_e32 v162, v160
	v_rcp_f32_e32 v163, v161
	v_pk_add_f32 v[156:157], v[160:161], v[156:157] neg_lo:[0,1] neg_hi:[0,1]
	v_pk_add_f32 v[164:165], v[154:155], v[164:165] neg_lo:[0,1] neg_hi:[0,1]
	v_pk_add_f32 v[156:157], v[158:159], v[156:157] neg_lo:[0,1] neg_hi:[0,1]
	v_pk_mul_f32 v[158:159], v[154:155], v[162:163]
	v_pk_add_f32 v[140:141], v[140:141], v[164:165] neg_lo:[0,1] neg_hi:[0,1]
	v_pk_mul_f32 v[164:165], v[160:161], v[158:159]
	v_cmp_neq_f32_e32 vcc, s3, v182
	v_pk_fma_f32 v[166:167], v[158:159], v[160:161], v[164:165] neg_lo:[0,0,1] neg_hi:[0,0,1]
	v_cmp_lt_f32_e64 s[0:1], |v205|, s4
	v_pk_fma_f32 v[166:167], v[158:159], v[156:157], v[166:167]
	s_nop 0
	v_pk_add_f32 v[168:169], v[164:165], v[166:167]
	s_nop 0
	v_pk_add_f32 v[170:171], v[154:155], v[168:169] neg_lo:[0,1] neg_hi:[0,1]
	v_pk_add_f32 v[164:165], v[168:169], v[164:165] neg_lo:[0,1] neg_hi:[0,1]
	v_pk_add_f32 v[154:155], v[154:155], v[170:171] neg_lo:[0,1] neg_hi:[0,1]
	s_nop 0
	v_pk_add_f32 v[154:155], v[154:155], v[168:169] neg_lo:[0,1] neg_hi:[0,1]
	s_nop 0
	v_pk_add_f32 v[140:141], v[140:141], v[154:155]
	v_pk_add_f32 v[154:155], v[164:165], v[166:167] neg_lo:[0,1] neg_hi:[0,1]
	s_nop 0
	v_pk_add_f32 v[140:141], v[154:155], v[140:141]
	s_nop 0
	v_pk_add_f32 v[154:155], v[170:171], v[140:141]
	s_nop 0
	v_pk_mul_f32 v[164:165], v[162:163], v[154:155]
	s_nop 0
	v_pk_mul_f32 v[166:167], v[160:161], v[164:165]
	s_nop 0
	v_pk_fma_f32 v[160:161], v[164:165], v[160:161], v[166:167] neg_lo:[0,0,1] neg_hi:[0,0,1]
	s_nop 0
	v_pk_fma_f32 v[156:157], v[164:165], v[156:157], v[160:161]
	v_pk_add_f32 v[160:161], v[170:171], v[154:155] neg_lo:[0,1] neg_hi:[0,1]
	s_nop 0
	v_pk_add_f32 v[140:141], v[140:141], v[160:161]
	v_pk_add_f32 v[160:161], v[166:167], v[156:157]
	s_nop 0
	v_pk_add_f32 v[168:169], v[154:155], v[160:161] neg_lo:[0,1] neg_hi:[0,1]
	v_pk_add_f32 v[166:167], v[160:161], v[166:167] neg_lo:[0,1] neg_hi:[0,1]
	v_pk_add_f32 v[154:155], v[154:155], v[168:169] neg_lo:[0,1] neg_hi:[0,1]
	s_nop 0
	v_pk_add_f32 v[154:155], v[154:155], v[160:161] neg_lo:[0,1] neg_hi:[0,1]
	s_nop 0
	v_pk_add_f32 v[140:141], v[140:141], v[154:155]
	v_pk_add_f32 v[154:155], v[166:167], v[156:157] neg_lo:[0,1] neg_hi:[0,1]
	s_nop 0
	v_pk_add_f32 v[140:141], v[154:155], v[140:141]
	v_pk_add_f32 v[154:155], v[158:159], v[164:165]
	v_pk_add_f32 v[140:141], v[168:169], v[140:141]
	v_pk_add_f32 v[156:157], v[154:155], v[158:159] neg_lo:[0,1] neg_hi:[0,1]
	v_pk_mul_f32 v[140:141], v[162:163], v[140:141]
	v_pk_add_f32 v[156:157], v[164:165], v[156:157] neg_lo:[0,1] neg_hi:[0,1]
	s_nop 0
	v_pk_add_f32 v[140:141], v[156:157], v[140:141]
	s_nop 0
	v_pk_add_f32 v[156:157], v[154:155], v[140:141]
	s_nop 0
	v_pk_mul_f32 v[158:159], v[156:157], v[156:157]
	v_pk_add_f32 v[154:155], v[156:157], v[154:155] neg_lo:[0,1] neg_hi:[0,1]
	v_pk_fma_f32 v[160:161], v[158:159], s[6:7], v[142:143] op_sel_hi:[1,0,0]
	v_pk_add_f32 v[140:141], v[140:141], v[154:155] neg_lo:[0,1] neg_hi:[0,1]
	v_ldexp_f32 v154, v156, 1
	v_pk_fma_f32 v[160:161], v[158:159], v[160:161], s[8:9] op_sel_hi:[1,1,0]
	v_ldexp_f32 v155, v157, 1
	v_pk_mul_f32 v[156:157], v[156:157], v[158:159]
	v_cvt_f32_i32_e32 v159, v173
	v_cvt_f32_i32_e32 v158, v172
	v_pk_mul_f32 v[156:157], v[156:157], v[160:161]
	v_ldexp_f32 v163, v141, 1
	v_pk_add_f32 v[160:161], v[154:155], v[156:157]
	v_pk_mul_f32 v[164:165], v[158:159], s[36:37] op_sel_hi:[1,0]
	v_pk_add_f32 v[154:155], v[160:161], v[154:155] neg_lo:[0,1] neg_hi:[0,1]
	v_pk_fma_f32 v[166:167], v[158:159], s[36:37], v[164:165] op_sel_hi:[1,0,1] neg_lo:[0,0,1] neg_hi:[0,0,1]
	v_pk_add_f32 v[154:155], v[156:157], v[154:155] neg_lo:[0,1] neg_hi:[0,1]
	v_pk_fma_f32 v[158:159], v[158:159], s[10:11], v[166:167] op_sel_hi:[1,0,1]
	v_ldexp_f32 v140, v140, 1
	v_mov_b32_e32 v156, v164
	v_mov_b32_e32 v157, v155
	v_mov_b32_e32 v162, v158
	v_mov_b32_e32 v141, v163
	v_pk_add_f32 v[156:157], v[156:157], v[162:163]
	v_pk_add_f32 v[162:163], v[140:141], v[154:155]
	v_mov_b32_e32 v155, v161
	v_mov_b32_e32 v141, v163
	v_pk_add_f32 v[166:167], v[164:165], v[158:159]
	v_pk_add_f32 v[140:141], v[140:141], v[154:155]
	v_pk_add_f32 v[154:155], v[160:161], v[162:163]
	v_mov_b32_e32 v208, v160
	v_pk_add_f32 v[168:169], v[166:167], v[154:155]
	v_mov_b32_e32 v206, v154
; __device__ __forceinline__ float softplusf_(float x) { return fmaxf(x, 0.0f) + log1pf(__expf(-fabsf(x))); }
;     __device__ __forceinline__ void operator()(f32x4 (&acc)[2][2][4][2], const pg8::Unit& u, int wr, int wc, int fr, int fq) const {
;     ...
;             if (wc == 0) { const f32x4 b0 = *(const f32x4*)(dtb + cl0), b1 = *(const f32x4*)(dtb + cl0 + 4);
; #pragma unroll
;                 for (int ai = 0; ai < 2; ++ai)
; #pragma unroll
;                     for (int m = 0; m < 4; ++m) { const int row = row0 + ai * 128 + m * 16; const f32x4 v0 = acc[ai][0][m][0] + b0, v1 = acc[ai][0][m][1] + b1;
;                         float* d = DTA + (size_t)row * NH + cl0;
;                         *(f32x4*)d = (f32x4){softplusf_(v0[0]), softplusf_(v0[1]), softplusf_(v0[2]), softplusf_(v0[3])}; *(f32x4*)(d + 4) = (f32x4){softplusf_(v1[0]), softplusf_(v1[1]), softplusf_(v1[2]), softplusf_(v1[3])}; } }
	v_mov_b32_e32 v207, v169
	v_mov_b32_e32 v209, v167
	v_pk_add_f32 v[206:207], v[206:207], v[208:209] neg_lo:[0,1] neg_hi:[0,1]
	v_mov_b32_e32 v170, v168
	v_mov_b32_e32 v171, v167
	v_mov_b32_e32 v172, v166
	v_mov_b32_e32 v173, v165
	v_mov_b32_e32 v208, v166
	v_mov_b32_e32 v209, v169
	v_mov_b32_e32 v165, v207
	v_pk_add_f32 v[170:171], v[170:171], v[172:173] neg_lo:[0,1] neg_hi:[0,1]
	v_mov_b32_e32 v172, v154
	v_mov_b32_e32 v173, v159
	v_pk_add_f32 v[164:165], v[208:209], v[164:165] neg_lo:[0,1] neg_hi:[0,1]
	v_pk_add_f32 v[172:173], v[172:173], v[170:171] neg_lo:[0,1] neg_hi:[0,1]
	v_mov_b32_e32 v208, v164
	v_mov_b32_e32 v209, v171
	v_mov_b32_e32 v210, v168
	v_mov_b32_e32 v211, v155
	v_mov_b32_e32 v171, v161
	v_pk_add_f32 v[208:209], v[158:159], v[208:209] neg_lo:[0,1] neg_hi:[0,1]
	v_pk_add_f32 v[170:171], v[210:211], v[170:171] neg_lo:[0,1] neg_hi:[0,1]
	v_mov_b32_e32 v159, v167
	v_pk_add_f32 v[156:157], v[156:157], v[170:171] neg_lo:[0,1] neg_hi:[0,1]
	v_pk_add_f32 v[158:159], v[158:159], v[164:165] neg_lo:[0,1] neg_hi:[0,1]
	v_pk_add_f32 v[140:141], v[140:141], v[206:207] neg_lo:[0,1] neg_hi:[0,1]
	v_pk_add_f32 v[154:155], v[154:155], v[160:161] neg_lo:[0,1] neg_hi:[0,1]
	v_pk_add_f32 v[160:161], v[140:141], v[158:159]
	v_mov_b32_e32 v159, v173
	v_mov_b32_e32 v141, v157
	v_pk_add_f32 v[154:155], v[162:163], v[154:155] neg_lo:[0,1] neg_hi:[0,1]
	v_pk_add_f32 v[162:163], v[172:173], v[156:157]
	v_pk_add_f32 v[140:141], v[158:159], v[140:141]
	v_mov_b32_e32 v156, v160
	v_pk_add_f32 v[140:141], v[140:141], v[208:209] neg_lo:[0,1] neg_hi:[0,1]
	v_mov_b32_e32 v157, v163
	v_pk_add_f32 v[156:157], v[156:157], v[140:141] neg_lo:[0,1] neg_hi:[0,1]
	v_pk_add_f32 v[140:141], v[154:155], v[140:141] neg_lo:[0,1] neg_hi:[0,1]
	v_pk_add_f32 v[156:157], v[158:159], v[156:157] neg_lo:[0,1] neg_hi:[0,1]
	v_pk_add_f32 v[154:155], v[162:163], v[160:161]
	v_pk_add_f32 v[140:141], v[140:141], v[156:157]
	v_pk_add_f32 v[156:157], v[168:169], v[154:155]
	s_nop 0
	v_pk_add_f32 v[158:159], v[156:157], v[168:169] neg_lo:[0,1] neg_hi:[0,1]
	s_nop 0
	v_pk_add_f32 v[154:155], v[154:155], v[158:159] neg_lo:[0,1] neg_hi:[0,1]
	s_nop 0
	v_pk_add_f32 v[140:141], v[140:141], v[154:155]
	s_nop 0
	v_pk_add_f32 v[140:141], v[156:157], v[140:141]
	s_nop 0
	v_cndmask_b32_e32 v140, v252, v140, vcc
	v_cmp_neq_f32_e32 vcc, s3, v205
	s_nop 1
	v_cndmask_b32_e32 v141, v252, v141, vcc
	v_cmp_ngt_f32_e32 vcc, -1.0, v205
	s_nop 1
	v_cndmask_b32_e32 v141, v253, v141, vcc
	v_cmp_ngt_f32_e32 vcc, -1.0, v182
	s_nop 1
	v_cndmask_b32_e32 v140, v253, v140, vcc
	v_cmp_neq_f32_e32 vcc, -1.0, v182
	s_nop 1
	v_cndmask_b32_e32 v140, v244, v140, vcc
	v_cmp_neq_f32_e32 vcc, -1.0, v205
	s_nop 1
	v_cndmask_b32_e32 v141, v244, v141, vcc
	v_cmp_lt_f32_e64 vcc, |v182|, s4
	v_cndmask_b32_e64 v141, v141, v205, s[0:1]
	s_nop 0
	v_cndmask_b32_e32 v140, v140, v182, vcc
	v_pk_add_f32 v[140:141], v[152:153], v[140:141]
	global_store_dwordx4 v[146:147], v[138:141], off
	s_nop 1
	v_mul_f32_e64 v139, |v150|, s88
	v_exp_f32_e32 v182, v139
	v_max_f32_e32 v138, 0, v150
	v_add_f32_e32 v139, 1.0, v182
	v_add_f32_e32 v140, -1.0, v139
	v_sub_f32_e32 v141, v140, v139
	v_add_f32_e32 v141, 1.0, v141
	v_sub_f32_e32 v140, v182, v140
	v_add_f32_e32 v150, v140, v141
	v_frexp_mant_f32_e32 v140, v139
	v_cmp_gt_f32_e32 vcc, s2, v140
	v_cvt_f64_f32_e32 v[140:141], v139
	v_frexp_exp_i32_f64_e32 v140, v[140:141]
	v_subbrev_co_u32_e32 v168, vcc, 0, v140, vcc
	v_sub_u32_e32 v141, 0, v168
	v_ldexp_f32 v140, v139, v141
	v_ldexp_f32 v150, v150, v141
	v_mul_f32_e64 v141, |v151|, s88
	v_exp_f32_e32 v205, v141
	v_max_f32_e32 v139, 0, v151
	v_add_f32_e32 v141, 1.0, v205
	v_add_f32_e32 v151, -1.0, v141
	v_sub_f32_e32 v152, v151, v141
	v_add_f32_e32 v152, 1.0, v152
	v_sub_f32_e32 v151, v205, v151
	v_add_f32_e32 v151, v151, v152
	v_frexp_mant_f32_e32 v152, v141
	v_cmp_gt_f32_e32 vcc, s2, v152
	v_cvt_f64_f32_e32 v[152:153], v141
	v_frexp_exp_i32_f64_e32 v152, v[152:153]
	v_subbrev_co_u32_e32 v169, vcc, 0, v152, vcc
	v_sub_u32_e32 v152, 0, v169
	v_ldexp_f32 v141, v141, v152
	v_ldexp_f32 v151, v151, v152
	v_pk_add_f32 v[152:153], v[140:141], 1.0 op_sel_hi:[1,0]
	v_pk_add_f32 v[160:161], v[140:141], -1.0 op_sel_hi:[1,0]
	v_pk_add_f32 v[154:155], v[152:153], -1.0 op_sel_hi:[1,0]
	v_pk_add_f32 v[162:163], v[160:161], 1.0 op_sel_hi:[1,0]
	v_pk_add_f32 v[154:155], v[140:141], v[154:155] neg_lo:[0,1] neg_hi:[0,1]
	v_pk_add_f32 v[140:141], v[140:141], v[162:163] neg_lo:[0,1] neg_hi:[0,1]
	v_pk_add_f32 v[154:155], v[150:151], v[154:155]
	v_pk_add_f32 v[140:141], v[150:151], v[140:141]
	v_pk_add_f32 v[156:157], v[152:153], v[154:155]
	v_pk_add_f32 v[150:151], v[160:161], v[140:141]
	v_rcp_f32_e32 v158, v156
	v_rcp_f32_e32 v159, v157
	v_pk_add_f32 v[152:153], v[156:157], v[152:153] neg_lo:[0,1] neg_hi:[0,1]
	v_pk_add_f32 v[160:161], v[150:151], v[160:161] neg_lo:[0,1] neg_hi:[0,1]
	v_pk_add_f32 v[152:153], v[154:155], v[152:153] neg_lo:[0,1] neg_hi:[0,1]
	v_pk_mul_f32 v[154:155], v[150:151], v[158:159]
	v_pk_add_f32 v[140:141], v[140:141], v[160:161] neg_lo:[0,1] neg_hi:[0,1]
	v_pk_mul_f32 v[160:161], v[156:157], v[154:155]
	v_cmp_neq_f32_e32 vcc, s3, v182
	v_pk_fma_f32 v[162:163], v[154:155], v[156:157], v[160:161] neg_lo:[0,0,1] neg_hi:[0,0,1]
	v_cmp_lt_f32_e64 s[0:1], |v205|, s4
	v_pk_fma_f32 v[162:163], v[154:155], v[152:153], v[162:163]
	s_nop 0
	v_pk_add_f32 v[164:165], v[160:161], v[162:163]
	s_nop 0
	v_pk_add_f32 v[166:167], v[150:151], v[164:165] neg_lo:[0,1] neg_hi:[0,1]
	v_pk_add_f32 v[160:161], v[164:165], v[160:161] neg_lo:[0,1] neg_hi:[0,1]
	v_pk_add_f32 v[150:151], v[150:151], v[166:167] neg_lo:[0,1] neg_hi:[0,1]
	s_nop 0
; __device__ __forceinline__ float softplusf_(float x) { return fmaxf(x, 0.0f) + log1pf(__expf(-fabsf(x))); }
;     __device__ __forceinline__ void operator()(f32x4 (&acc)[2][2][4][2], const pg8::Unit& u, int wr, int wc, int fr, int fq) const {
;     ...
;             if (wc == 0) { const f32x4 b0 = *(const f32x4*)(dtb + cl0), b1 = *(const f32x4*)(dtb + cl0 + 4);
; #pragma unroll
;                 for (int ai = 0; ai < 2; ++ai)
; #pragma unroll
;                     for (int m = 0; m < 4; ++m) { const int row = row0 + ai * 128 + m * 16; const f32x4 v0 = acc[ai][0][m][0] + b0, v1 = acc[ai][0][m][1] + b1;
;                         float* d = DTA + (size_t)row * NH + cl0;
;                         *(f32x4*)d = (f32x4){softplusf_(v0[0]), softplusf_(v0[1]), softplusf_(v0[2]), softplusf_(v0[3])}; *(f32x4*)(d + 4) = (f32x4){softplusf_(v1[0]), softplusf_(v1[1]), softplusf_(v1[2]), softplusf_(v1[3])}; } }
	v_pk_add_f32 v[150:151], v[150:151], v[164:165] neg_lo:[0,1] neg_hi:[0,1]
	s_nop 0
	v_pk_add_f32 v[140:141], v[140:141], v[150:151]
	v_pk_add_f32 v[150:151], v[160:161], v[162:163] neg_lo:[0,1] neg_hi:[0,1]
	s_nop 0
	v_pk_add_f32 v[140:141], v[150:151], v[140:141]
	s_nop 0
	v_pk_add_f32 v[150:151], v[166:167], v[140:141]
	s_nop 0
	v_pk_mul_f32 v[160:161], v[158:159], v[150:151]
	s_nop 0
	v_pk_mul_f32 v[162:163], v[156:157], v[160:161]
	s_nop 0
	v_pk_fma_f32 v[156:157], v[160:161], v[156:157], v[162:163] neg_lo:[0,0,1] neg_hi:[0,0,1]
	s_nop 0
	v_pk_fma_f32 v[152:153], v[160:161], v[152:153], v[156:157]
	v_pk_add_f32 v[156:157], v[166:167], v[150:151] neg_lo:[0,1] neg_hi:[0,1]
	s_nop 0
	v_pk_add_f32 v[140:141], v[140:141], v[156:157]
	v_pk_add_f32 v[156:157], v[162:163], v[152:153]
	s_nop 0
	v_pk_add_f32 v[164:165], v[150:151], v[156:157] neg_lo:[0,1] neg_hi:[0,1]
	v_pk_add_f32 v[162:163], v[156:157], v[162:163] neg_lo:[0,1] neg_hi:[0,1]
	v_pk_add_f32 v[150:151], v[150:151], v[164:165] neg_lo:[0,1] neg_hi:[0,1]
	s_nop 0
	v_pk_add_f32 v[150:151], v[150:151], v[156:157] neg_lo:[0,1] neg_hi:[0,1]
	s_nop 0
	v_pk_add_f32 v[140:141], v[140:141], v[150:151]
	v_pk_add_f32 v[150:151], v[162:163], v[152:153] neg_lo:[0,1] neg_hi:[0,1]
	s_nop 0
	v_pk_add_f32 v[140:141], v[150:151], v[140:141]
	v_pk_add_f32 v[150:151], v[154:155], v[160:161]
	v_pk_add_f32 v[140:141], v[164:165], v[140:141]
	v_pk_add_f32 v[152:153], v[150:151], v[154:155] neg_lo:[0,1] neg_hi:[0,1]
	v_pk_mul_f32 v[140:141], v[158:159], v[140:141]
	v_pk_add_f32 v[152:153], v[160:161], v[152:153] neg_lo:[0,1] neg_hi:[0,1]
	s_nop 0
	v_pk_add_f32 v[140:141], v[152:153], v[140:141]
	s_nop 0
	v_pk_add_f32 v[152:153], v[150:151], v[140:141]
	s_nop 0
	v_pk_mul_f32 v[154:155], v[152:153], v[152:153]
	v_pk_add_f32 v[150:151], v[152:153], v[150:151] neg_lo:[0,1] neg_hi:[0,1]
	v_pk_fma_f32 v[156:157], v[154:155], s[6:7], v[142:143] op_sel_hi:[1,0,0]
	v_pk_add_f32 v[140:141], v[140:141], v[150:151] neg_lo:[0,1] neg_hi:[0,1]
	v_ldexp_f32 v150, v152, 1
	v_pk_fma_f32 v[156:157], v[154:155], v[156:157], s[8:9] op_sel_hi:[1,1,0]
	v_ldexp_f32 v151, v153, 1
	v_pk_mul_f32 v[152:153], v[152:153], v[154:155]
	v_cvt_f32_i32_e32 v155, v169
	v_cvt_f32_i32_e32 v154, v168
	v_pk_mul_f32 v[152:153], v[152:153], v[156:157]
	v_ldexp_f32 v159, v141, 1
	v_pk_add_f32 v[156:157], v[150:151], v[152:153]
	v_pk_mul_f32 v[160:161], v[154:155], s[36:37] op_sel_hi:[1,0]
	v_pk_add_f32 v[150:151], v[156:157], v[150:151] neg_lo:[0,1] neg_hi:[0,1]
	v_pk_fma_f32 v[162:163], v[154:155], s[36:37], v[160:161] op_sel_hi:[1,0,1] neg_lo:[0,0,1] neg_hi:[0,0,1]
	v_pk_add_f32 v[150:151], v[152:153], v[150:151] neg_lo:[0,1] neg_hi:[0,1]
	v_pk_fma_f32 v[154:155], v[154:155], s[10:11], v[162:163] op_sel_hi:[1,0,1]
	v_ldexp_f32 v140, v140, 1
	v_mov_b32_e32 v152, v160
	v_mov_b32_e32 v153, v151
	v_mov_b32_e32 v158, v154
	v_mov_b32_e32 v141, v159
	v_pk_add_f32 v[152:153], v[152:153], v[158:159]
	v_pk_add_f32 v[158:159], v[140:141], v[150:151]
	v_mov_b32_e32 v151, v157
	v_mov_b32_e32 v141, v159
	v_pk_add_f32 v[162:163], v[160:161], v[154:155]
	v_pk_add_f32 v[140:141], v[140:141], v[150:151]
	v_pk_add_f32 v[150:151], v[156:157], v[158:159]
	v_mov_b32_e32 v172, v156
	v_pk_add_f32 v[164:165], v[162:163], v[150:151]
	v_mov_b32_e32 v170, v150
	v_mov_b32_e32 v171, v165
	v_mov_b32_e32 v173, v163
	v_pk_add_f32 v[170:171], v[170:171], v[172:173] neg_lo:[0,1] neg_hi:[0,1]
	v_mov_b32_e32 v166, v164
	v_mov_b32_e32 v167, v163
	v_mov_b32_e32 v168, v162
	v_mov_b32_e32 v169, v161
	v_mov_b32_e32 v172, v162
	v_mov_b32_e32 v173, v165
	v_mov_b32_e32 v161, v171
	v_pk_add_f32 v[166:167], v[166:167], v[168:169] neg_lo:[0,1] neg_hi:[0,1]
	v_mov_b32_e32 v168, v150
	v_mov_b32_e32 v169, v155
	v_pk_add_f32 v[160:161], v[172:173], v[160:161] neg_lo:[0,1] neg_hi:[0,1]
	v_pk_add_f32 v[168:169], v[168:169], v[166:167] neg_lo:[0,1] neg_hi:[0,1]
	v_mov_b32_e32 v172, v160
	v_mov_b32_e32 v173, v167
	v_mov_b32_e32 v206, v164
	v_mov_b32_e32 v207, v151
	v_mov_b32_e32 v167, v157
	v_pk_add_f32 v[172:173], v[154:155], v[172:173] neg_lo:[0,1] neg_hi:[0,1]
	v_pk_add_f32 v[166:167], v[206:207], v[166:167] neg_lo:[0,1] neg_hi:[0,1]
	v_mov_b32_e32 v155, v163
	v_pk_add_f32 v[152:153], v[152:153], v[166:167] neg_lo:[0,1] neg_hi:[0,1]
	v_pk_add_f32 v[154:155], v[154:155], v[160:161] neg_lo:[0,1] neg_hi:[0,1]
	v_pk_add_f32 v[140:141], v[140:141], v[170:171] neg_lo:[0,1] neg_hi:[0,1]
	v_pk_add_f32 v[150:151], v[150:151], v[156:157] neg_lo:[0,1] neg_hi:[0,1]
	v_pk_add_f32 v[156:157], v[140:141], v[154:155]
	v_mov_b32_e32 v155, v169
	v_mov_b32_e32 v141, v153
	v_pk_add_f32 v[150:151], v[158:159], v[150:151] neg_lo:[0,1] neg_hi:[0,1]
	v_pk_add_f32 v[158:159], v[168:169], v[152:153]
	v_pk_add_f32 v[140:141], v[154:155], v[140:141]
	v_mov_b32_e32 v152, v156
	v_pk_add_f32 v[140:141], v[140:141], v[172:173] neg_lo:[0,1] neg_hi:[0,1]
	v_mov_b32_e32 v153, v159
	v_pk_add_f32 v[152:153], v[152:153], v[140:141] neg_lo:[0,1] neg_hi:[0,1]
	v_pk_add_f32 v[140:141], v[150:151], v[140:141] neg_lo:[0,1] neg_hi:[0,1]
	v_pk_add_f32 v[152:153], v[154:155], v[152:153] neg_lo:[0,1] neg_hi:[0,1]
	v_pk_add_f32 v[150:151], v[158:159], v[156:157]
	v_pk_add_f32 v[140:141], v[140:141], v[152:153]
	v_pk_add_f32 v[152:153], v[164:165], v[150:151]
	s_nop 0
	v_pk_add_f32 v[154:155], v[152:153], v[164:165] neg_lo:[0,1] neg_hi:[0,1]
	s_nop 0
	v_pk_add_f32 v[150:151], v[150:151], v[154:155] neg_lo:[0,1] neg_hi:[0,1]
	s_nop 0
	v_pk_add_f32 v[140:141], v[140:141], v[150:151]
	s_nop 0
	v_pk_add_f32 v[140:141], v[152:153], v[140:141]
	s_nop 0
	v_cndmask_b32_e32 v140, v252, v140, vcc
	v_cmp_neq_f32_e32 vcc, s3, v205
	s_nop 1
; __device__ __forceinline__ float softplusf_(float x) { return fmaxf(x, 0.0f) + log1pf(__expf(-fabsf(x))); }
;     __device__ __forceinline__ void operator()(f32x4 (&acc)[2][2][4][2], const pg8::Unit& u, int wr, int wc, int fr, int fq) const {
;     ...
;             if (wc == 0) { const f32x4 b0 = *(const f32x4*)(dtb + cl0), b1 = *(const f32x4*)(dtb + cl0 + 4);
; #pragma unroll
;                 for (int ai = 0; ai < 2; ++ai)
; #pragma unroll
;                     for (int m = 0; m < 4; ++m) { const int row = row0 + ai * 128 + m * 16; const f32x4 v0 = acc[ai][0][m][0] + b0, v1 = acc[ai][0][m][1] + b1;
;                         float* d = DTA + (size_t)row * NH + cl0;
;                         *(f32x4*)d = (f32x4){softplusf_(v0[0]), softplusf_(v0[1]), softplusf_(v0[2]), softplusf_(v0[3])}; *(f32x4*)(d + 4) = (f32x4){softplusf_(v1[0]), softplusf_(v1[1]), softplusf_(v1[2]), softplusf_(v1[3])}; } }
	v_cndmask_b32_e32 v141, v252, v141, vcc
	v_cmp_ngt_f32_e32 vcc, -1.0, v205
	s_nop 1
	v_cndmask_b32_e32 v141, v253, v141, vcc
	v_cmp_ngt_f32_e32 vcc, -1.0, v182
	s_nop 1
	v_cndmask_b32_e32 v140, v253, v140, vcc
	v_cmp_neq_f32_e32 vcc, -1.0, v182
	s_nop 1
	v_cndmask_b32_e32 v140, v244, v140, vcc
	v_cmp_neq_f32_e32 vcc, -1.0, v205
	s_nop 1
	v_cndmask_b32_e32 v141, v244, v141, vcc
	v_cmp_lt_f32_e64 vcc, |v182|, s4
	v_cndmask_b32_e64 v141, v141, v205, s[0:1]
	s_nop 0
	v_cndmask_b32_e32 v140, v140, v182, vcc
	v_pk_add_f32 v[138:139], v[138:139], v[140:141]
	v_mul_f32_e64 v141, |v148|, s88
	v_exp_f32_e32 v182, v141
	v_max_f32_e32 v140, 0, v148
	v_add_f32_e32 v141, 1.0, v182
	v_add_f32_e32 v148, -1.0, v141
	v_sub_f32_e32 v150, v148, v141
	v_add_f32_e32 v150, 1.0, v150
	v_sub_f32_e32 v148, v182, v148
	v_add_f32_e32 v152, v148, v150
	v_frexp_mant_f32_e32 v148, v141
	v_cvt_f64_f32_e32 v[150:151], v141
	v_cmp_gt_f32_e32 vcc, s2, v148
	v_frexp_exp_i32_f64_e32 v148, v[150:151]
	s_nop 0
	v_subbrev_co_u32_e32 v168, vcc, 0, v148, vcc
	v_sub_u32_e32 v150, 0, v168
	v_ldexp_f32 v148, v141, v150
	v_max_f32_e32 v141, 0, v149
	v_mul_f32_e64 v149, |v149|, s88
	v_exp_f32_e32 v205, v149
	v_ldexp_f32 v150, v152, v150
	v_add_f32_e32 v149, 1.0, v205
	v_add_f32_e32 v151, -1.0, v149
	v_sub_f32_e32 v152, v151, v149
	v_add_f32_e32 v152, 1.0, v152
	v_sub_f32_e32 v151, v205, v151
	v_add_f32_e32 v151, v151, v152
	v_frexp_mant_f32_e32 v152, v149
	v_cmp_gt_f32_e32 vcc, s2, v152
	v_cvt_f64_f32_e32 v[152:153], v149
	v_frexp_exp_i32_f64_e32 v152, v[152:153]
	v_subbrev_co_u32_e32 v169, vcc, 0, v152, vcc
	v_sub_u32_e32 v152, 0, v169
	v_ldexp_f32 v149, v149, v152
	v_ldexp_f32 v151, v151, v152
	v_pk_add_f32 v[152:153], v[148:149], 1.0 op_sel_hi:[1,0]
	v_pk_add_f32 v[160:161], v[148:149], -1.0 op_sel_hi:[1,0]
	v_pk_add_f32 v[154:155], v[152:153], -1.0 op_sel_hi:[1,0]
	v_pk_add_f32 v[162:163], v[160:161], 1.0 op_sel_hi:[1,0]
	v_pk_add_f32 v[154:155], v[148:149], v[154:155] neg_lo:[0,1] neg_hi:[0,1]
	v_pk_add_f32 v[148:149], v[148:149], v[162:163] neg_lo:[0,1] neg_hi:[0,1]
	v_pk_add_f32 v[154:155], v[150:151], v[154:155]
	v_pk_add_f32 v[148:149], v[150:151], v[148:149]
	v_pk_add_f32 v[156:157], v[152:153], v[154:155]
	v_pk_add_f32 v[150:151], v[160:161], v[148:149]
	v_rcp_f32_e32 v158, v156
	v_rcp_f32_e32 v159, v157
	v_pk_add_f32 v[152:153], v[156:157], v[152:153] neg_lo:[0,1] neg_hi:[0,1]
	v_pk_add_f32 v[160:161], v[150:151], v[160:161] neg_lo:[0,1] neg_hi:[0,1]
	v_pk_add_f32 v[152:153], v[154:155], v[152:153] neg_lo:[0,1] neg_hi:[0,1]
	v_pk_mul_f32 v[154:155], v[150:151], v[158:159]
	v_pk_add_f32 v[148:149], v[148:149], v[160:161] neg_lo:[0,1] neg_hi:[0,1]
	v_pk_mul_f32 v[160:161], v[156:157], v[154:155]
	v_cmp_neq_f32_e32 vcc, s3, v182
	v_pk_fma_f32 v[162:163], v[154:155], v[156:157], v[160:161] neg_lo:[0,0,1] neg_hi:[0,0,1]
	v_cmp_lt_f32_e64 s[0:1], |v205|, s4
	v_pk_fma_f32 v[162:163], v[154:155], v[152:153], v[162:163]
	s_nop 0
	v_pk_add_f32 v[164:165], v[160:161], v[162:163]
	s_nop 0
	v_pk_add_f32 v[166:167], v[150:151], v[164:165] neg_lo:[0,1] neg_hi:[0,1]
	v_pk_add_f32 v[160:161], v[164:165], v[160:161] neg_lo:[0,1] neg_hi:[0,1]
	v_pk_add_f32 v[150:151], v[150:151], v[166:167] neg_lo:[0,1] neg_hi:[0,1]
	s_nop 0
	v_pk_add_f32 v[150:151], v[150:151], v[164:165] neg_lo:[0,1] neg_hi:[0,1]
	s_nop 0
	v_pk_add_f32 v[148:149], v[148:149], v[150:151]
	v_pk_add_f32 v[150:151], v[160:161], v[162:163] neg_lo:[0,1] neg_hi:[0,1]
	s_nop 0
	v_pk_add_f32 v[148:149], v[150:151], v[148:149]
	s_nop 0
	v_pk_add_f32 v[150:151], v[166:167], v[148:149]
	s_nop 0
	v_pk_mul_f32 v[160:161], v[158:159], v[150:151]
	s_nop 0
	v_pk_mul_f32 v[162:163], v[156:157], v[160:161]
	s_nop 0
	v_pk_fma_f32 v[156:157], v[160:161], v[156:157], v[162:163] neg_lo:[0,0,1] neg_hi:[0,0,1]
	s_nop 0
	v_pk_fma_f32 v[152:153], v[160:161], v[152:153], v[156:157]
	v_pk_add_f32 v[156:157], v[166:167], v[150:151] neg_lo:[0,1] neg_hi:[0,1]
	s_nop 0
	v_pk_add_f32 v[148:149], v[148:149], v[156:157]
	v_pk_add_f32 v[156:157], v[162:163], v[152:153]
	s_nop 0
	v_pk_add_f32 v[164:165], v[150:151], v[156:157] neg_lo:[0,1] neg_hi:[0,1]
	v_pk_add_f32 v[162:163], v[156:157], v[162:163] neg_lo:[0,1] neg_hi:[0,1]
	v_pk_add_f32 v[150:151], v[150:151], v[164:165] neg_lo:[0,1] neg_hi:[0,1]
	s_nop 0
	v_pk_add_f32 v[150:151], v[150:151], v[156:157] neg_lo:[0,1] neg_hi:[0,1]
	s_nop 0
	v_pk_add_f32 v[148:149], v[148:149], v[150:151]
	v_pk_add_f32 v[150:151], v[162:163], v[152:153] neg_lo:[0,1] neg_hi:[0,1]
	s_nop 0
	v_pk_add_f32 v[148:149], v[150:151], v[148:149]
	v_pk_add_f32 v[150:151], v[154:155], v[160:161]
	v_pk_add_f32 v[148:149], v[164:165], v[148:149]
	v_pk_add_f32 v[152:153], v[150:151], v[154:155] neg_lo:[0,1] neg_hi:[0,1]
	v_pk_mul_f32 v[148:149], v[158:159], v[148:149]
	v_pk_add_f32 v[152:153], v[160:161], v[152:153] neg_lo:[0,1] neg_hi:[0,1]
	s_nop 0
	v_pk_add_f32 v[148:149], v[152:153], v[148:149]
	s_nop 0
	v_pk_add_f32 v[152:153], v[150:151], v[148:149]
	s_nop 0
	v_pk_mul_f32 v[154:155], v[152:153], v[152:153]
	v_pk_add_f32 v[150:151], v[152:153], v[150:151] neg_lo:[0,1] neg_hi:[0,1]
	v_pk_fma_f32 v[156:157], v[154:155], s[6:7], v[142:143] op_sel_hi:[1,0,0]
	v_pk_add_f32 v[148:149], v[148:149], v[150:151] neg_lo:[0,1] neg_hi:[0,1]
	v_ldexp_f32 v150, v152, 1
	v_pk_fma_f32 v[156:157], v[154:155], v[156:157], s[8:9] op_sel_hi:[1,1,0]
	v_ldexp_f32 v151, v153, 1
	v_pk_mul_f32 v[152:153], v[152:153], v[154:155]
	v_cvt_f32_i32_e32 v155, v169
	v_cvt_f32_i32_e32 v154, v168
	v_pk_mul_f32 v[152:153], v[152:153], v[156:157]
	v_ldexp_f32 v159, v149, 1
	v_pk_add_f32 v[156:157], v[150:151], v[152:153]
	v_pk_mul_f32 v[160:161], v[154:155], s[36:37] op_sel_hi:[1,0]
; __device__ __forceinline__ float softplusf_(float x) { return fmaxf(x, 0.0f) + log1pf(__expf(-fabsf(x))); }
;     __device__ __forceinline__ void operator()(f32x4 (&acc)[2][2][4][2], const pg8::Unit& u, int wr, int wc, int fr, int fq) const {
;     ...
;             if (wc == 0) { const f32x4 b0 = *(const f32x4*)(dtb + cl0), b1 = *(const f32x4*)(dtb + cl0 + 4);
; #pragma unroll
;                 for (int ai = 0; ai < 2; ++ai)
; #pragma unroll
;                     for (int m = 0; m < 4; ++m) { const int row = row0 + ai * 128 + m * 16; const f32x4 v0 = acc[ai][0][m][0] + b0, v1 = acc[ai][0][m][1] + b1;
;                         float* d = DTA + (size_t)row * NH + cl0;
;                         *(f32x4*)d = (f32x4){softplusf_(v0[0]), softplusf_(v0[1]), softplusf_(v0[2]), softplusf_(v0[3])}; *(f32x4*)(d + 4) = (f32x4){softplusf_(v1[0]), softplusf_(v1[1]), softplusf_(v1[2]), softplusf_(v1[3])}; } }
	v_pk_add_f32 v[150:151], v[156:157], v[150:151] neg_lo:[0,1] neg_hi:[0,1]
	v_pk_fma_f32 v[162:163], v[154:155], s[36:37], v[160:161] op_sel_hi:[1,0,1] neg_lo:[0,0,1] neg_hi:[0,0,1]
	v_pk_add_f32 v[150:151], v[152:153], v[150:151] neg_lo:[0,1] neg_hi:[0,1]
	v_pk_fma_f32 v[154:155], v[154:155], s[10:11], v[162:163] op_sel_hi:[1,0,1]
	v_ldexp_f32 v148, v148, 1
	v_mov_b32_e32 v152, v160
	v_mov_b32_e32 v153, v151
	v_mov_b32_e32 v158, v154
	v_mov_b32_e32 v149, v159
	v_pk_add_f32 v[152:153], v[152:153], v[158:159]
	v_pk_add_f32 v[158:159], v[148:149], v[150:151]
	v_mov_b32_e32 v151, v157
	v_mov_b32_e32 v149, v159
	v_pk_add_f32 v[162:163], v[160:161], v[154:155]
	v_pk_add_f32 v[148:149], v[148:149], v[150:151]
	v_pk_add_f32 v[150:151], v[156:157], v[158:159]
	v_mov_b32_e32 v172, v156
	v_pk_add_f32 v[164:165], v[162:163], v[150:151]
	v_mov_b32_e32 v170, v150
	v_mov_b32_e32 v171, v165
	v_mov_b32_e32 v173, v163
	v_pk_add_f32 v[170:171], v[170:171], v[172:173] neg_lo:[0,1] neg_hi:[0,1]
	v_mov_b32_e32 v166, v164
	v_mov_b32_e32 v167, v163
	v_mov_b32_e32 v168, v162
	v_mov_b32_e32 v169, v161
	v_mov_b32_e32 v172, v162
	v_mov_b32_e32 v173, v165
	v_mov_b32_e32 v161, v171
	v_pk_add_f32 v[166:167], v[166:167], v[168:169] neg_lo:[0,1] neg_hi:[0,1]
	v_mov_b32_e32 v168, v150
	v_mov_b32_e32 v169, v155
	v_pk_add_f32 v[160:161], v[172:173], v[160:161] neg_lo:[0,1] neg_hi:[0,1]
	v_pk_add_f32 v[168:169], v[168:169], v[166:167] neg_lo:[0,1] neg_hi:[0,1]
	v_mov_b32_e32 v172, v160
	v_mov_b32_e32 v173, v167
	v_mov_b32_e32 v206, v164
	v_mov_b32_e32 v207, v151
	v_mov_b32_e32 v167, v157
	v_pk_add_f32 v[172:173], v[154:155], v[172:173] neg_lo:[0,1] neg_hi:[0,1]
	v_pk_add_f32 v[166:167], v[206:207], v[166:167] neg_lo:[0,1] neg_hi:[0,1]
	v_mov_b32_e32 v155, v163
	v_pk_add_f32 v[152:153], v[152:153], v[166:167] neg_lo:[0,1] neg_hi:[0,1]
	v_pk_add_f32 v[154:155], v[154:155], v[160:161] neg_lo:[0,1] neg_hi:[0,1]
	v_pk_add_f32 v[148:149], v[148:149], v[170:171] neg_lo:[0,1] neg_hi:[0,1]
	v_pk_add_f32 v[150:151], v[150:151], v[156:157] neg_lo:[0,1] neg_hi:[0,1]
	v_pk_add_f32 v[156:157], v[148:149], v[154:155]
	v_mov_b32_e32 v155, v169
	v_mov_b32_e32 v149, v153
	v_pk_add_f32 v[150:151], v[158:159], v[150:151] neg_lo:[0,1] neg_hi:[0,1]
	v_pk_add_f32 v[158:159], v[168:169], v[152:153]
	v_pk_add_f32 v[148:149], v[154:155], v[148:149]
	v_mov_b32_e32 v152, v156
	v_pk_add_f32 v[148:149], v[148:149], v[172:173] neg_lo:[0,1] neg_hi:[0,1]
	v_mov_b32_e32 v153, v159
	v_pk_add_f32 v[152:153], v[152:153], v[148:149] neg_lo:[0,1] neg_hi:[0,1]
	v_pk_add_f32 v[148:149], v[150:151], v[148:149] neg_lo:[0,1] neg_hi:[0,1]
	v_pk_add_f32 v[152:153], v[154:155], v[152:153] neg_lo:[0,1] neg_hi:[0,1]
	v_pk_add_f32 v[150:151], v[158:159], v[156:157]
	v_pk_add_f32 v[148:149], v[148:149], v[152:153]
	v_pk_add_f32 v[152:153], v[164:165], v[150:151]
	s_nop 0
	v_pk_add_f32 v[154:155], v[152:153], v[164:165] neg_lo:[0,1] neg_hi:[0,1]
	s_nop 0
	v_pk_add_f32 v[150:151], v[150:151], v[154:155] neg_lo:[0,1] neg_hi:[0,1]
	s_nop 0
	v_pk_add_f32 v[148:149], v[148:149], v[150:151]
	s_nop 0
	v_pk_add_f32 v[148:149], v[152:153], v[148:149]
	s_nop 0
	v_cndmask_b32_e32 v148, v252, v148, vcc
	v_cmp_neq_f32_e32 vcc, s3, v205
	s_nop 1
	v_cndmask_b32_e32 v149, v252, v149, vcc
	v_cmp_ngt_f32_e32 vcc, -1.0, v205
	s_nop 1
	v_cndmask_b32_e32 v149, v253, v149, vcc
	v_cmp_ngt_f32_e32 vcc, -1.0, v182
	s_nop 1
	v_cndmask_b32_e32 v148, v253, v148, vcc
	v_cmp_neq_f32_e32 vcc, -1.0, v182
	s_nop 1
	v_cndmask_b32_e32 v148, v244, v148, vcc
	v_cmp_neq_f32_e32 vcc, -1.0, v205
	s_nop 1
	v_cndmask_b32_e32 v149, v244, v149, vcc
	v_cmp_lt_f32_e64 vcc, |v182|, s4
	v_cndmask_b32_e64 v149, v149, v205, s[0:1]
	s_nop 0
	v_cndmask_b32_e32 v148, v148, v182, vcc
	v_pk_add_f32 v[140:141], v[140:141], v[148:149]
	global_store_dwordx4 v[146:147], v[138:141], off offset:16
	v_pk_add_f32 v[146:147], v[14:15], v[134:135]
	s_nop 0
	v_pk_add_f32 v[138:139], v[10:11], v[130:131]
	v_lshlrev_b64 v[130:131], 7, v[188:189]
	v_lshl_add_u64 v[134:135], v[144:145], 0, v[130:131]
	v_mul_f32_e64 v131, |v146|, s88
	v_exp_f32_e32 v170, v131
	v_pk_add_f32 v[140:141], v[16:17], v[136:137]
	v_pk_add_f32 v[136:137], v[12:13], v[132:133]
	v_max_f32_e32 v130, 0, v146
	v_add_f32_e32 v131, 1.0, v170
	v_add_f32_e32 v132, -1.0, v131
	v_sub_f32_e32 v133, v132, v131
	v_add_f32_e32 v133, 1.0, v133
	v_sub_f32_e32 v132, v170, v132
	v_add_f32_e32 v144, v132, v133
	v_frexp_mant_f32_e32 v132, v131
	v_cmp_gt_f32_e32 vcc, s2, v132
	v_cvt_f64_f32_e32 v[132:133], v131
	v_frexp_exp_i32_f64_e32 v132, v[132:133]
	v_subbrev_co_u32_e32 v162, vcc, 0, v132, vcc
	v_sub_u32_e32 v133, 0, v162
	v_ldexp_f32 v132, v131, v133
	v_ldexp_f32 v144, v144, v133
	v_mul_f32_e64 v133, |v147|, s88
	v_exp_f32_e32 v171, v133
	v_max_f32_e32 v131, 0, v147
	v_add_f32_e32 v133, 1.0, v171
	v_add_f32_e32 v145, -1.0, v133
	v_sub_f32_e32 v146, v145, v133
	v_add_f32_e32 v146, 1.0, v146
	v_sub_f32_e32 v145, v171, v145
	v_add_f32_e32 v145, v145, v146
	v_frexp_mant_f32_e32 v146, v133
	v_cmp_gt_f32_e32 vcc, s2, v146
	v_cvt_f64_f32_e32 v[146:147], v133
	v_frexp_exp_i32_f64_e32 v146, v[146:147]
	v_subbrev_co_u32_e32 v163, vcc, 0, v146, vcc
	v_sub_u32_e32 v146, 0, v163
	v_ldexp_f32 v133, v133, v146
	v_ldexp_f32 v145, v145, v146
	v_pk_add_f32 v[146:147], v[132:133], 1.0 op_sel_hi:[1,0]
	v_pk_add_f32 v[154:155], v[132:133], -1.0 op_sel_hi:[1,0]
	v_pk_add_f32 v[148:149], v[146:147], -1.0 op_sel_hi:[1,0]
	v_pk_add_f32 v[156:157], v[154:155], 1.0 op_sel_hi:[1,0]
	v_pk_add_f32 v[148:149], v[132:133], v[148:149] neg_lo:[0,1] neg_hi:[0,1]
	v_pk_add_f32 v[132:133], v[132:133], v[156:157] neg_lo:[0,1] neg_hi:[0,1]
	v_pk_add_f32 v[148:149], v[144:145], v[148:149]
; __device__ __forceinline__ float softplusf_(float x) { return fmaxf(x, 0.0f) + log1pf(__expf(-fabsf(x))); }
;     __device__ __forceinline__ void operator()(f32x4 (&acc)[2][2][4][2], const pg8::Unit& u, int wr, int wc, int fr, int fq) const {
;     ...
;             if (wc == 0) { const f32x4 b0 = *(const f32x4*)(dtb + cl0), b1 = *(const f32x4*)(dtb + cl0 + 4);
; #pragma unroll
;                 for (int ai = 0; ai < 2; ++ai)
; #pragma unroll
;                     for (int m = 0; m < 4; ++m) { const int row = row0 + ai * 128 + m * 16; const f32x4 v0 = acc[ai][0][m][0] + b0, v1 = acc[ai][0][m][1] + b1;
;                         float* d = DTA + (size_t)row * NH + cl0;
;                         *(f32x4*)d = (f32x4){softplusf_(v0[0]), softplusf_(v0[1]), softplusf_(v0[2]), softplusf_(v0[3])}; *(f32x4*)(d + 4) = (f32x4){softplusf_(v1[0]), softplusf_(v1[1]), softplusf_(v1[2]), softplusf_(v1[3])}; } }
	v_pk_add_f32 v[132:133], v[144:145], v[132:133]
	v_pk_add_f32 v[150:151], v[146:147], v[148:149]
	v_pk_add_f32 v[144:145], v[154:155], v[132:133]
	v_rcp_f32_e32 v152, v150
	v_rcp_f32_e32 v153, v151
	v_pk_add_f32 v[146:147], v[150:151], v[146:147] neg_lo:[0,1] neg_hi:[0,1]
	v_pk_add_f32 v[154:155], v[144:145], v[154:155] neg_lo:[0,1] neg_hi:[0,1]
	v_pk_add_f32 v[146:147], v[148:149], v[146:147] neg_lo:[0,1] neg_hi:[0,1]
	v_pk_mul_f32 v[148:149], v[144:145], v[152:153]
	v_pk_add_f32 v[132:133], v[132:133], v[154:155] neg_lo:[0,1] neg_hi:[0,1]
	v_pk_mul_f32 v[154:155], v[150:151], v[148:149]
	v_cmp_neq_f32_e32 vcc, s3, v170
	v_pk_fma_f32 v[156:157], v[148:149], v[150:151], v[154:155] neg_lo:[0,0,1] neg_hi:[0,0,1]
	v_cmp_lt_f32_e64 s[0:1], |v171|, s4
	v_pk_fma_f32 v[156:157], v[148:149], v[146:147], v[156:157]
	s_nop 0
	v_pk_add_f32 v[158:159], v[154:155], v[156:157]
	s_nop 0
	v_pk_add_f32 v[160:161], v[144:145], v[158:159] neg_lo:[0,1] neg_hi:[0,1]
	v_pk_add_f32 v[154:155], v[158:159], v[154:155] neg_lo:[0,1] neg_hi:[0,1]
	v_pk_add_f32 v[144:145], v[144:145], v[160:161] neg_lo:[0,1] neg_hi:[0,1]
	s_nop 0
	v_pk_add_f32 v[144:145], v[144:145], v[158:159] neg_lo:[0,1] neg_hi:[0,1]
	s_nop 0
	v_pk_add_f32 v[132:133], v[132:133], v[144:145]
	v_pk_add_f32 v[144:145], v[154:155], v[156:157] neg_lo:[0,1] neg_hi:[0,1]
	s_nop 0
	v_pk_add_f32 v[132:133], v[144:145], v[132:133]
	s_nop 0
	v_pk_add_f32 v[144:145], v[160:161], v[132:133]
	s_nop 0
	v_pk_mul_f32 v[154:155], v[152:153], v[144:145]
	s_nop 0
	v_pk_mul_f32 v[156:157], v[150:151], v[154:155]
	s_nop 0
	v_pk_fma_f32 v[150:151], v[154:155], v[150:151], v[156:157] neg_lo:[0,0,1] neg_hi:[0,0,1]
	s_nop 0
	v_pk_fma_f32 v[146:147], v[154:155], v[146:147], v[150:151]
	v_pk_add_f32 v[150:151], v[160:161], v[144:145] neg_lo:[0,1] neg_hi:[0,1]
	s_nop 0
	v_pk_add_f32 v[132:133], v[132:133], v[150:151]
	v_pk_add_f32 v[150:151], v[156:157], v[146:147]
	s_nop 0
	v_pk_add_f32 v[158:159], v[144:145], v[150:151] neg_lo:[0,1] neg_hi:[0,1]
	v_pk_add_f32 v[156:157], v[150:151], v[156:157] neg_lo:[0,1] neg_hi:[0,1]
	v_pk_add_f32 v[144:145], v[144:145], v[158:159] neg_lo:[0,1] neg_hi:[0,1]
	s_nop 0
	v_pk_add_f32 v[144:145], v[144:145], v[150:151] neg_lo:[0,1] neg_hi:[0,1]
	s_nop 0
	v_pk_add_f32 v[132:133], v[132:133], v[144:145]
	v_pk_add_f32 v[144:145], v[156:157], v[146:147] neg_lo:[0,1] neg_hi:[0,1]
	s_nop 0
	v_pk_add_f32 v[132:133], v[144:145], v[132:133]
	v_pk_add_f32 v[144:145], v[148:149], v[154:155]
	v_pk_add_f32 v[132:133], v[158:159], v[132:133]
	v_pk_add_f32 v[146:147], v[144:145], v[148:149] neg_lo:[0,1] neg_hi:[0,1]
	v_pk_mul_f32 v[132:133], v[152:153], v[132:133]
	v_pk_add_f32 v[146:147], v[154:155], v[146:147] neg_lo:[0,1] neg_hi:[0,1]
	s_nop 0
	v_pk_add_f32 v[132:133], v[146:147], v[132:133]
	s_nop 0
	v_pk_add_f32 v[146:147], v[144:145], v[132:133]
	s_nop 0
	v_pk_mul_f32 v[148:149], v[146:147], v[146:147]
	v_pk_add_f32 v[144:145], v[146:147], v[144:145] neg_lo:[0,1] neg_hi:[0,1]
	v_pk_fma_f32 v[150:151], v[148:149], s[6:7], v[142:143] op_sel_hi:[1,0,0]
	v_pk_add_f32 v[132:133], v[132:133], v[144:145] neg_lo:[0,1] neg_hi:[0,1]
	v_ldexp_f32 v144, v146, 1
	v_pk_fma_f32 v[150:151], v[148:149], v[150:151], s[8:9] op_sel_hi:[1,1,0]
	v_ldexp_f32 v145, v147, 1
	v_pk_mul_f32 v[146:147], v[146:147], v[148:149]
	v_cvt_f32_i32_e32 v149, v163
	v_cvt_f32_i32_e32 v148, v162
	v_pk_mul_f32 v[146:147], v[146:147], v[150:151]
	v_ldexp_f32 v153, v133, 1
	v_pk_add_f32 v[150:151], v[144:145], v[146:147]
	v_pk_mul_f32 v[154:155], v[148:149], s[36:37] op_sel_hi:[1,0]
	v_pk_add_f32 v[144:145], v[150:151], v[144:145] neg_lo:[0,1] neg_hi:[0,1]
	v_pk_fma_f32 v[156:157], v[148:149], s[36:37], v[154:155] op_sel_hi:[1,0,1] neg_lo:[0,0,1] neg_hi:[0,0,1]
	v_pk_add_f32 v[144:145], v[146:147], v[144:145] neg_lo:[0,1] neg_hi:[0,1]
	v_pk_fma_f32 v[148:149], v[148:149], s[10:11], v[156:157] op_sel_hi:[1,0,1]
	v_ldexp_f32 v132, v132, 1
	v_mov_b32_e32 v146, v154
	v_mov_b32_e32 v147, v145
	v_mov_b32_e32 v152, v148
	v_mov_b32_e32 v133, v153
	v_pk_add_f32 v[146:147], v[146:147], v[152:153]
	v_pk_add_f32 v[152:153], v[132:133], v[144:145]
	v_mov_b32_e32 v145, v151
	v_mov_b32_e32 v133, v153
	v_pk_add_f32 v[156:157], v[154:155], v[148:149]
	v_pk_add_f32 v[132:133], v[132:133], v[144:145]
	v_pk_add_f32 v[144:145], v[150:151], v[152:153]
	v_mov_b32_e32 v166, v150
	v_pk_add_f32 v[158:159], v[156:157], v[144:145]
	v_mov_b32_e32 v164, v144
	v_mov_b32_e32 v165, v159
	v_mov_b32_e32 v167, v157
	v_pk_add_f32 v[164:165], v[164:165], v[166:167] neg_lo:[0,1] neg_hi:[0,1]
	v_mov_b32_e32 v160, v158
	v_mov_b32_e32 v161, v157
	v_mov_b32_e32 v162, v156
	v_mov_b32_e32 v163, v155
	v_mov_b32_e32 v166, v156
	v_mov_b32_e32 v167, v159
	v_mov_b32_e32 v155, v165
	v_pk_add_f32 v[160:161], v[160:161], v[162:163] neg_lo:[0,1] neg_hi:[0,1]
	v_mov_b32_e32 v162, v144
	v_mov_b32_e32 v163, v149
	v_pk_add_f32 v[154:155], v[166:167], v[154:155] neg_lo:[0,1] neg_hi:[0,1]
	v_pk_add_f32 v[162:163], v[162:163], v[160:161] neg_lo:[0,1] neg_hi:[0,1]
	v_mov_b32_e32 v166, v154
	v_mov_b32_e32 v167, v161
	v_mov_b32_e32 v168, v158
	v_mov_b32_e32 v169, v145
	v_mov_b32_e32 v161, v151
	v_pk_add_f32 v[166:167], v[148:149], v[166:167] neg_lo:[0,1] neg_hi:[0,1]
	v_pk_add_f32 v[160:161], v[168:169], v[160:161] neg_lo:[0,1] neg_hi:[0,1]
	v_mov_b32_e32 v149, v157
	v_pk_add_f32 v[146:147], v[146:147], v[160:161] neg_lo:[0,1] neg_hi:[0,1]
	v_pk_add_f32 v[148:149], v[148:149], v[154:155] neg_lo:[0,1] neg_hi:[0,1]
	v_pk_add_f32 v[132:133], v[132:133], v[164:165] neg_lo:[0,1] neg_hi:[0,1]
	v_pk_add_f32 v[144:145], v[144:145], v[150:151] neg_lo:[0,1] neg_hi:[0,1]
	v_pk_add_f32 v[150:151], v[132:133], v[148:149]
; __device__ __forceinline__ float softplusf_(float x) { return fmaxf(x, 0.0f) + log1pf(__expf(-fabsf(x))); }
;     __device__ __forceinline__ void operator()(f32x4 (&acc)[2][2][4][2], const pg8::Unit& u, int wr, int wc, int fr, int fq) const {
;     ...
;             if (wc == 0) { const f32x4 b0 = *(const f32x4*)(dtb + cl0), b1 = *(const f32x4*)(dtb + cl0 + 4);
; #pragma unroll
;                 for (int ai = 0; ai < 2; ++ai)
; #pragma unroll
;                     for (int m = 0; m < 4; ++m) { const int row = row0 + ai * 128 + m * 16; const f32x4 v0 = acc[ai][0][m][0] + b0, v1 = acc[ai][0][m][1] + b1;
;                         float* d = DTA + (size_t)row * NH + cl0;
;                         *(f32x4*)d = (f32x4){softplusf_(v0[0]), softplusf_(v0[1]), softplusf_(v0[2]), softplusf_(v0[3])}; *(f32x4*)(d + 4) = (f32x4){softplusf_(v1[0]), softplusf_(v1[1]), softplusf_(v1[2]), softplusf_(v1[3])}; } }
	v_mov_b32_e32 v149, v163
	v_mov_b32_e32 v133, v147
	v_pk_add_f32 v[144:145], v[152:153], v[144:145] neg_lo:[0,1] neg_hi:[0,1]
	v_pk_add_f32 v[152:153], v[162:163], v[146:147]
	v_pk_add_f32 v[132:133], v[148:149], v[132:133]
	v_mov_b32_e32 v146, v150
	v_pk_add_f32 v[132:133], v[132:133], v[166:167] neg_lo:[0,1] neg_hi:[0,1]
	v_mov_b32_e32 v147, v153
	v_pk_add_f32 v[146:147], v[146:147], v[132:133] neg_lo:[0,1] neg_hi:[0,1]
	v_pk_add_f32 v[132:133], v[144:145], v[132:133] neg_lo:[0,1] neg_hi:[0,1]
	v_pk_add_f32 v[146:147], v[148:149], v[146:147] neg_lo:[0,1] neg_hi:[0,1]
	v_pk_add_f32 v[144:145], v[152:153], v[150:151]
	v_pk_add_f32 v[132:133], v[132:133], v[146:147]
	v_pk_add_f32 v[146:147], v[158:159], v[144:145]
	s_nop 0
	v_pk_add_f32 v[148:149], v[146:147], v[158:159] neg_lo:[0,1] neg_hi:[0,1]
	s_nop 0
	v_pk_add_f32 v[144:145], v[144:145], v[148:149] neg_lo:[0,1] neg_hi:[0,1]
	s_nop 0
	v_pk_add_f32 v[132:133], v[132:133], v[144:145]
	s_nop 0
	v_pk_add_f32 v[132:133], v[146:147], v[132:133]
	s_nop 0
	v_cndmask_b32_e32 v132, v252, v132, vcc
	v_cmp_neq_f32_e32 vcc, s3, v171
	s_nop 1
	v_cndmask_b32_e32 v133, v252, v133, vcc
	v_cmp_ngt_f32_e32 vcc, -1.0, v171
	s_nop 1
	v_cndmask_b32_e32 v133, v253, v133, vcc
	v_cmp_ngt_f32_e32 vcc, -1.0, v170
	s_nop 1
	v_cndmask_b32_e32 v132, v253, v132, vcc
	v_cmp_neq_f32_e32 vcc, -1.0, v170
	s_nop 1
	v_cndmask_b32_e32 v132, v244, v132, vcc
	v_cmp_neq_f32_e32 vcc, -1.0, v171
	s_nop 1
	v_cndmask_b32_e32 v133, v244, v133, vcc
	v_cmp_lt_f32_e64 vcc, |v170|, s4
	v_cndmask_b32_e64 v133, v133, v171, s[0:1]
	s_nop 0
	v_cndmask_b32_e32 v132, v132, v170, vcc
	v_pk_add_f32 v[130:131], v[130:131], v[132:133]
	v_mul_f32_e64 v133, |v140|, s88
	v_exp_f32_e32 v170, v133
	v_max_f32_e32 v132, 0, v140
	v_add_f32_e32 v133, 1.0, v170
	v_add_f32_e32 v140, -1.0, v133
	v_sub_f32_e32 v144, v140, v133
	v_add_f32_e32 v144, 1.0, v144
	v_sub_f32_e32 v140, v170, v140
	v_add_f32_e32 v146, v140, v144
	v_frexp_mant_f32_e32 v140, v133
	v_cvt_f64_f32_e32 v[144:145], v133
	v_cmp_gt_f32_e32 vcc, s2, v140
	v_frexp_exp_i32_f64_e32 v140, v[144:145]
	s_nop 0
	v_subbrev_co_u32_e32 v162, vcc, 0, v140, vcc
	v_sub_u32_e32 v144, 0, v162
	v_ldexp_f32 v140, v133, v144
	v_max_f32_e32 v133, 0, v141
	v_mul_f32_e64 v141, |v141|, s88
	v_exp_f32_e32 v171, v141
	v_ldexp_f32 v144, v146, v144
	v_add_f32_e32 v141, 1.0, v171
	v_add_f32_e32 v145, -1.0, v141
	v_sub_f32_e32 v146, v145, v141
	v_add_f32_e32 v146, 1.0, v146
	v_sub_f32_e32 v145, v171, v145
	v_add_f32_e32 v145, v145, v146
	v_frexp_mant_f32_e32 v146, v141
	v_cmp_gt_f32_e32 vcc, s2, v146
	v_cvt_f64_f32_e32 v[146:147], v141
	v_frexp_exp_i32_f64_e32 v146, v[146:147]
	v_subbrev_co_u32_e32 v163, vcc, 0, v146, vcc
	v_sub_u32_e32 v146, 0, v163
	v_ldexp_f32 v141, v141, v146
	v_ldexp_f32 v145, v145, v146
	v_pk_add_f32 v[146:147], v[140:141], 1.0 op_sel_hi:[1,0]
	v_pk_add_f32 v[154:155], v[140:141], -1.0 op_sel_hi:[1,0]
	v_pk_add_f32 v[148:149], v[146:147], -1.0 op_sel_hi:[1,0]
	v_pk_add_f32 v[156:157], v[154:155], 1.0 op_sel_hi:[1,0]
	v_pk_add_f32 v[148:149], v[140:141], v[148:149] neg_lo:[0,1] neg_hi:[0,1]
	v_pk_add_f32 v[140:141], v[140:141], v[156:157] neg_lo:[0,1] neg_hi:[0,1]
	v_pk_add_f32 v[148:149], v[144:145], v[148:149]
	v_pk_add_f32 v[140:141], v[144:145], v[140:141]
	v_pk_add_f32 v[150:151], v[146:147], v[148:149]
	v_pk_add_f32 v[144:145], v[154:155], v[140:141]
	v_rcp_f32_e32 v152, v150
	v_rcp_f32_e32 v153, v151
	v_pk_add_f32 v[146:147], v[150:151], v[146:147] neg_lo:[0,1] neg_hi:[0,1]
	v_pk_add_f32 v[154:155], v[144:145], v[154:155] neg_lo:[0,1] neg_hi:[0,1]
	v_pk_add_f32 v[146:147], v[148:149], v[146:147] neg_lo:[0,1] neg_hi:[0,1]
	v_pk_mul_f32 v[148:149], v[144:145], v[152:153]
	v_pk_add_f32 v[140:141], v[140:141], v[154:155] neg_lo:[0,1] neg_hi:[0,1]
	v_pk_mul_f32 v[154:155], v[150:151], v[148:149]
	v_cmp_neq_f32_e32 vcc, s3, v170
	v_pk_fma_f32 v[156:157], v[148:149], v[150:151], v[154:155] neg_lo:[0,0,1] neg_hi:[0,0,1]
	v_cmp_lt_f32_e64 s[0:1], |v171|, s4
	v_pk_fma_f32 v[156:157], v[148:149], v[146:147], v[156:157]
	s_nop 0
	v_pk_add_f32 v[158:159], v[154:155], v[156:157]
	s_nop 0
	v_pk_add_f32 v[160:161], v[144:145], v[158:159] neg_lo:[0,1] neg_hi:[0,1]
	v_pk_add_f32 v[154:155], v[158:159], v[154:155] neg_lo:[0,1] neg_hi:[0,1]
	v_pk_add_f32 v[144:145], v[144:145], v[160:161] neg_lo:[0,1] neg_hi:[0,1]
	s_nop 0
	v_pk_add_f32 v[144:145], v[144:145], v[158:159] neg_lo:[0,1] neg_hi:[0,1]
	s_nop 0
	v_pk_add_f32 v[140:141], v[140:141], v[144:145]
	v_pk_add_f32 v[144:145], v[154:155], v[156:157] neg_lo:[0,1] neg_hi:[0,1]
	s_nop 0
	v_pk_add_f32 v[140:141], v[144:145], v[140:141]
	s_nop 0
	v_pk_add_f32 v[144:145], v[160:161], v[140:141]
	s_nop 0
	v_pk_mul_f32 v[154:155], v[152:153], v[144:145]
	s_nop 0
	v_pk_mul_f32 v[156:157], v[150:151], v[154:155]
	s_nop 0
	v_pk_fma_f32 v[150:151], v[154:155], v[150:151], v[156:157] neg_lo:[0,0,1] neg_hi:[0,0,1]
	s_nop 0
	v_pk_fma_f32 v[146:147], v[154:155], v[146:147], v[150:151]
	v_pk_add_f32 v[150:151], v[160:161], v[144:145] neg_lo:[0,1] neg_hi:[0,1]
	s_nop 0
	v_pk_add_f32 v[140:141], v[140:141], v[150:151]
	v_pk_add_f32 v[150:151], v[156:157], v[146:147]
	s_nop 0
	v_pk_add_f32 v[158:159], v[144:145], v[150:151] neg_lo:[0,1] neg_hi:[0,1]
	v_pk_add_f32 v[156:157], v[150:151], v[156:157] neg_lo:[0,1] neg_hi:[0,1]
	v_pk_add_f32 v[144:145], v[144:145], v[158:159] neg_lo:[0,1] neg_hi:[0,1]
	s_nop 0
	v_pk_add_f32 v[144:145], v[144:145], v[150:151] neg_lo:[0,1] neg_hi:[0,1]
	s_nop 0
	v_pk_add_f32 v[140:141], v[140:141], v[144:145]
	v_pk_add_f32 v[144:145], v[156:157], v[146:147] neg_lo:[0,1] neg_hi:[0,1]
	s_nop 0
	v_pk_add_f32 v[140:141], v[144:145], v[140:141]
; __device__ __forceinline__ float softplusf_(float x) { return fmaxf(x, 0.0f) + log1pf(__expf(-fabsf(x))); }
;     __device__ __forceinline__ void operator()(f32x4 (&acc)[2][2][4][2], const pg8::Unit& u, int wr, int wc, int fr, int fq) const {
;     ...
;             if (wc == 0) { const f32x4 b0 = *(const f32x4*)(dtb + cl0), b1 = *(const f32x4*)(dtb + cl0 + 4);
; #pragma unroll
;                 for (int ai = 0; ai < 2; ++ai)
; #pragma unroll
;                     for (int m = 0; m < 4; ++m) { const int row = row0 + ai * 128 + m * 16; const f32x4 v0 = acc[ai][0][m][0] + b0, v1 = acc[ai][0][m][1] + b1;
;                         float* d = DTA + (size_t)row * NH + cl0;
;                         *(f32x4*)d = (f32x4){softplusf_(v0[0]), softplusf_(v0[1]), softplusf_(v0[2]), softplusf_(v0[3])}; *(f32x4*)(d + 4) = (f32x4){softplusf_(v1[0]), softplusf_(v1[1]), softplusf_(v1[2]), softplusf_(v1[3])}; } }
	v_pk_add_f32 v[144:145], v[148:149], v[154:155]
	v_pk_add_f32 v[140:141], v[158:159], v[140:141]
	v_pk_add_f32 v[146:147], v[144:145], v[148:149] neg_lo:[0,1] neg_hi:[0,1]
	v_pk_mul_f32 v[140:141], v[152:153], v[140:141]
	v_pk_add_f32 v[146:147], v[154:155], v[146:147] neg_lo:[0,1] neg_hi:[0,1]
	s_nop 0
	v_pk_add_f32 v[140:141], v[146:147], v[140:141]
	s_nop 0
	v_pk_add_f32 v[146:147], v[144:145], v[140:141]
	s_nop 0
	v_pk_mul_f32 v[148:149], v[146:147], v[146:147]
	v_pk_add_f32 v[144:145], v[146:147], v[144:145] neg_lo:[0,1] neg_hi:[0,1]
	v_pk_fma_f32 v[150:151], v[148:149], s[6:7], v[142:143] op_sel_hi:[1,0,0]
	v_pk_add_f32 v[140:141], v[140:141], v[144:145] neg_lo:[0,1] neg_hi:[0,1]
	v_ldexp_f32 v144, v146, 1
	v_pk_fma_f32 v[150:151], v[148:149], v[150:151], s[8:9] op_sel_hi:[1,1,0]
	v_ldexp_f32 v145, v147, 1
	v_pk_mul_f32 v[146:147], v[146:147], v[148:149]
	v_cvt_f32_i32_e32 v149, v163
	v_cvt_f32_i32_e32 v148, v162
	v_pk_mul_f32 v[146:147], v[146:147], v[150:151]
	v_ldexp_f32 v153, v141, 1
	v_pk_add_f32 v[150:151], v[144:145], v[146:147]
	v_pk_mul_f32 v[154:155], v[148:149], s[36:37] op_sel_hi:[1,0]
	v_pk_add_f32 v[144:145], v[150:151], v[144:145] neg_lo:[0,1] neg_hi:[0,1]
	v_pk_fma_f32 v[156:157], v[148:149], s[36:37], v[154:155] op_sel_hi:[1,0,1] neg_lo:[0,0,1] neg_hi:[0,0,1]
	v_pk_add_f32 v[144:145], v[146:147], v[144:145] neg_lo:[0,1] neg_hi:[0,1]
	v_pk_fma_f32 v[148:149], v[148:149], s[10:11], v[156:157] op_sel_hi:[1,0,1]
	v_ldexp_f32 v140, v140, 1
	v_mov_b32_e32 v146, v154
	v_mov_b32_e32 v147, v145
	v_mov_b32_e32 v152, v148
	v_mov_b32_e32 v141, v153
	v_pk_add_f32 v[146:147], v[146:147], v[152:153]
	v_pk_add_f32 v[152:153], v[140:141], v[144:145]
	v_mov_b32_e32 v145, v151
	v_mov_b32_e32 v141, v153
	v_pk_add_f32 v[156:157], v[154:155], v[148:149]
	v_pk_add_f32 v[140:141], v[140:141], v[144:145]
	v_pk_add_f32 v[144:145], v[150:151], v[152:153]
	v_mov_b32_e32 v166, v150
	v_pk_add_f32 v[158:159], v[156:157], v[144:145]
	v_mov_b32_e32 v164, v144
	v_mov_b32_e32 v165, v159
	v_mov_b32_e32 v167, v157
	v_pk_add_f32 v[164:165], v[164:165], v[166:167] neg_lo:[0,1] neg_hi:[0,1]
	v_mov_b32_e32 v160, v158
	v_mov_b32_e32 v161, v157
	v_mov_b32_e32 v162, v156
	v_mov_b32_e32 v163, v155
	v_mov_b32_e32 v166, v156
	v_mov_b32_e32 v167, v159
	v_mov_b32_e32 v155, v165
	v_pk_add_f32 v[160:161], v[160:161], v[162:163] neg_lo:[0,1] neg_hi:[0,1]
	v_mov_b32_e32 v162, v144
	v_mov_b32_e32 v163, v149
	v_pk_add_f32 v[154:155], v[166:167], v[154:155] neg_lo:[0,1] neg_hi:[0,1]
	v_pk_add_f32 v[162:163], v[162:163], v[160:161] neg_lo:[0,1] neg_hi:[0,1]
	v_mov_b32_e32 v166, v154
	v_mov_b32_e32 v167, v161
	v_mov_b32_e32 v168, v158
	v_mov_b32_e32 v169, v145
	v_mov_b32_e32 v161, v151
	v_pk_add_f32 v[166:167], v[148:149], v[166:167] neg_lo:[0,1] neg_hi:[0,1]
	v_pk_add_f32 v[160:161], v[168:169], v[160:161] neg_lo:[0,1] neg_hi:[0,1]
	v_mov_b32_e32 v149, v157
	v_pk_add_f32 v[146:147], v[146:147], v[160:161] neg_lo:[0,1] neg_hi:[0,1]
	v_pk_add_f32 v[148:149], v[148:149], v[154:155] neg_lo:[0,1] neg_hi:[0,1]
	v_pk_add_f32 v[140:141], v[140:141], v[164:165] neg_lo:[0,1] neg_hi:[0,1]
	v_pk_add_f32 v[144:145], v[144:145], v[150:151] neg_lo:[0,1] neg_hi:[0,1]
	v_pk_add_f32 v[150:151], v[140:141], v[148:149]
	v_mov_b32_e32 v149, v163
	v_mov_b32_e32 v141, v147
	v_pk_add_f32 v[144:145], v[152:153], v[144:145] neg_lo:[0,1] neg_hi:[0,1]
	v_pk_add_f32 v[152:153], v[162:163], v[146:147]
	v_pk_add_f32 v[140:141], v[148:149], v[140:141]
	v_mov_b32_e32 v146, v150
	v_pk_add_f32 v[140:141], v[140:141], v[166:167] neg_lo:[0,1] neg_hi:[0,1]
	v_mov_b32_e32 v147, v153
	v_pk_add_f32 v[146:147], v[146:147], v[140:141] neg_lo:[0,1] neg_hi:[0,1]
	v_pk_add_f32 v[140:141], v[144:145], v[140:141] neg_lo:[0,1] neg_hi:[0,1]
	v_pk_add_f32 v[146:147], v[148:149], v[146:147] neg_lo:[0,1] neg_hi:[0,1]
	v_pk_add_f32 v[144:145], v[152:153], v[150:151]
	v_pk_add_f32 v[140:141], v[140:141], v[146:147]
	v_pk_add_f32 v[146:147], v[158:159], v[144:145]
	s_nop 0
	v_pk_add_f32 v[148:149], v[146:147], v[158:159] neg_lo:[0,1] neg_hi:[0,1]
	s_nop 0
	v_pk_add_f32 v[144:145], v[144:145], v[148:149] neg_lo:[0,1] neg_hi:[0,1]
	s_nop 0
	v_pk_add_f32 v[140:141], v[140:141], v[144:145]
	s_nop 0
	v_pk_add_f32 v[140:141], v[146:147], v[140:141]
	s_nop 0
	v_cndmask_b32_e32 v140, v252, v140, vcc
	v_cmp_neq_f32_e32 vcc, s3, v171
	s_nop 1
	v_cndmask_b32_e32 v141, v252, v141, vcc
	v_cmp_ngt_f32_e32 vcc, -1.0, v171
	s_nop 1
	v_cndmask_b32_e32 v141, v253, v141, vcc
	v_cmp_ngt_f32_e32 vcc, -1.0, v170
	s_nop 1
	v_cndmask_b32_e32 v140, v253, v140, vcc
	v_cmp_neq_f32_e32 vcc, -1.0, v170
	s_nop 1
	v_cndmask_b32_e32 v140, v244, v140, vcc
	v_cmp_neq_f32_e32 vcc, -1.0, v171
	s_nop 1
	v_cndmask_b32_e32 v141, v244, v141, vcc
	v_cmp_lt_f32_e64 vcc, |v170|, s4
	v_cndmask_b32_e64 v141, v141, v171, s[0:1]
	s_nop 0
	v_cndmask_b32_e32 v140, v140, v170, vcc
	v_pk_add_f32 v[132:133], v[132:133], v[140:141]
	global_store_dwordx4 v[134:135], v[130:133], off
	s_nop 1
	v_mul_f32_e64 v131, |v138|, s88
	v_exp_f32_e32 v166, v131
	v_max_f32_e32 v130, 0, v138
	v_add_f32_e32 v131, 1.0, v166
	v_add_f32_e32 v132, -1.0, v131
	v_sub_f32_e32 v133, v132, v131
	v_add_f32_e32 v133, 1.0, v133
	v_sub_f32_e32 v132, v166, v132
	v_add_f32_e32 v138, v132, v133
	v_frexp_mant_f32_e32 v132, v131
	v_cmp_gt_f32_e32 vcc, s2, v132
	v_cvt_f64_f32_e32 v[132:133], v131
	v_frexp_exp_i32_f64_e32 v132, v[132:133]
	v_subbrev_co_u32_e32 v158, vcc, 0, v132, vcc
	v_sub_u32_e32 v133, 0, v158
	v_ldexp_f32 v132, v131, v133
	v_ldexp_f32 v138, v138, v133
	v_mul_f32_e64 v133, |v139|, s88
	v_exp_f32_e32 v167, v133
	v_max_f32_e32 v131, 0, v139
	v_add_f32_e32 v133, 1.0, v167
	v_add_f32_e32 v139, -1.0, v133
; __device__ __forceinline__ float softplusf_(float x) { return fmaxf(x, 0.0f) + log1pf(__expf(-fabsf(x))); }
;     __device__ __forceinline__ void operator()(f32x4 (&acc)[2][2][4][2], const pg8::Unit& u, int wr, int wc, int fr, int fq) const {
;     ...
;             if (wc == 0) { const f32x4 b0 = *(const f32x4*)(dtb + cl0), b1 = *(const f32x4*)(dtb + cl0 + 4);
; #pragma unroll
;                 for (int ai = 0; ai < 2; ++ai)
; #pragma unroll
;                     for (int m = 0; m < 4; ++m) { const int row = row0 + ai * 128 + m * 16; const f32x4 v0 = acc[ai][0][m][0] + b0, v1 = acc[ai][0][m][1] + b1;
;                         float* d = DTA + (size_t)row * NH + cl0;
;                         *(f32x4*)d = (f32x4){softplusf_(v0[0]), softplusf_(v0[1]), softplusf_(v0[2]), softplusf_(v0[3])}; *(f32x4*)(d + 4) = (f32x4){softplusf_(v1[0]), softplusf_(v1[1]), softplusf_(v1[2]), softplusf_(v1[3])}; } }
	v_sub_f32_e32 v140, v139, v133
	v_add_f32_e32 v140, 1.0, v140
	v_sub_f32_e32 v139, v167, v139
	v_add_f32_e32 v139, v139, v140
	v_frexp_mant_f32_e32 v140, v133
	v_cmp_gt_f32_e32 vcc, s2, v140
	v_cvt_f64_f32_e32 v[140:141], v133
	v_frexp_exp_i32_f64_e32 v140, v[140:141]
	v_subbrev_co_u32_e32 v159, vcc, 0, v140, vcc
	v_sub_u32_e32 v140, 0, v159
	v_ldexp_f32 v133, v133, v140
	v_ldexp_f32 v139, v139, v140
	v_pk_add_f32 v[140:141], v[132:133], 1.0 op_sel_hi:[1,0]
	v_pk_add_f32 v[150:151], v[132:133], -1.0 op_sel_hi:[1,0]
	v_pk_add_f32 v[144:145], v[140:141], -1.0 op_sel_hi:[1,0]
	v_pk_add_f32 v[152:153], v[150:151], 1.0 op_sel_hi:[1,0]
	v_pk_add_f32 v[144:145], v[132:133], v[144:145] neg_lo:[0,1] neg_hi:[0,1]
	v_pk_add_f32 v[132:133], v[132:133], v[152:153] neg_lo:[0,1] neg_hi:[0,1]
	v_pk_add_f32 v[144:145], v[138:139], v[144:145]
	v_pk_add_f32 v[132:133], v[138:139], v[132:133]
	v_pk_add_f32 v[146:147], v[140:141], v[144:145]
	v_pk_add_f32 v[138:139], v[150:151], v[132:133]
	v_rcp_f32_e32 v148, v146
	v_rcp_f32_e32 v149, v147
	v_pk_add_f32 v[140:141], v[146:147], v[140:141] neg_lo:[0,1] neg_hi:[0,1]
	v_pk_add_f32 v[150:151], v[138:139], v[150:151] neg_lo:[0,1] neg_hi:[0,1]
	v_pk_add_f32 v[140:141], v[144:145], v[140:141] neg_lo:[0,1] neg_hi:[0,1]
	v_pk_mul_f32 v[144:145], v[138:139], v[148:149]
	v_pk_add_f32 v[132:133], v[132:133], v[150:151] neg_lo:[0,1] neg_hi:[0,1]
	v_pk_mul_f32 v[150:151], v[146:147], v[144:145]
	v_cmp_neq_f32_e32 vcc, s3, v166
	v_pk_fma_f32 v[152:153], v[144:145], v[146:147], v[150:151] neg_lo:[0,0,1] neg_hi:[0,0,1]
	v_cmp_lt_f32_e64 s[0:1], |v167|, s4
	v_pk_fma_f32 v[152:153], v[144:145], v[140:141], v[152:153]
	s_nop 0
	v_pk_add_f32 v[154:155], v[150:151], v[152:153]
	s_nop 0
	v_pk_add_f32 v[156:157], v[138:139], v[154:155] neg_lo:[0,1] neg_hi:[0,1]
	v_pk_add_f32 v[150:151], v[154:155], v[150:151] neg_lo:[0,1] neg_hi:[0,1]
	v_pk_add_f32 v[138:139], v[138:139], v[156:157] neg_lo:[0,1] neg_hi:[0,1]
	s_nop 0
	v_pk_add_f32 v[138:139], v[138:139], v[154:155] neg_lo:[0,1] neg_hi:[0,1]
	s_nop 0
	v_pk_add_f32 v[132:133], v[132:133], v[138:139]
	v_pk_add_f32 v[138:139], v[150:151], v[152:153] neg_lo:[0,1] neg_hi:[0,1]
	s_nop 0
	v_pk_add_f32 v[132:133], v[138:139], v[132:133]
	s_nop 0
	v_pk_add_f32 v[138:139], v[156:157], v[132:133]
	s_nop 0
	v_pk_mul_f32 v[150:151], v[148:149], v[138:139]
	s_nop 0
	v_pk_mul_f32 v[152:153], v[146:147], v[150:151]
	s_nop 0
	v_pk_fma_f32 v[146:147], v[150:151], v[146:147], v[152:153] neg_lo:[0,0,1] neg_hi:[0,0,1]
	s_nop 0
	v_pk_fma_f32 v[140:141], v[150:151], v[140:141], v[146:147]
	v_pk_add_f32 v[146:147], v[156:157], v[138:139] neg_lo:[0,1] neg_hi:[0,1]
	s_nop 0
	v_pk_add_f32 v[132:133], v[132:133], v[146:147]
	v_pk_add_f32 v[146:147], v[152:153], v[140:141]
	s_nop 0
	v_pk_add_f32 v[154:155], v[138:139], v[146:147] neg_lo:[0,1] neg_hi:[0,1]
	v_pk_add_f32 v[152:153], v[146:147], v[152:153] neg_lo:[0,1] neg_hi:[0,1]
	v_pk_add_f32 v[138:139], v[138:139], v[154:155] neg_lo:[0,1] neg_hi:[0,1]
	s_nop 0
	v_pk_add_f32 v[138:139], v[138:139], v[146:147] neg_lo:[0,1] neg_hi:[0,1]
	s_nop 0
	v_pk_add_f32 v[132:133], v[132:133], v[138:139]
	v_pk_add_f32 v[138:139], v[152:153], v[140:141] neg_lo:[0,1] neg_hi:[0,1]
	s_nop 0
	v_pk_add_f32 v[132:133], v[138:139], v[132:133]
	v_pk_add_f32 v[138:139], v[144:145], v[150:151]
	v_pk_add_f32 v[132:133], v[154:155], v[132:133]
	v_pk_add_f32 v[140:141], v[138:139], v[144:145] neg_lo:[0,1] neg_hi:[0,1]
	v_pk_mul_f32 v[132:133], v[148:149], v[132:133]
	v_pk_add_f32 v[140:141], v[150:151], v[140:141] neg_lo:[0,1] neg_hi:[0,1]
	s_nop 0
	v_pk_add_f32 v[132:133], v[140:141], v[132:133]
	s_nop 0
	v_pk_add_f32 v[140:141], v[138:139], v[132:133]
	s_nop 0
	v_pk_mul_f32 v[144:145], v[140:141], v[140:141]
	v_pk_add_f32 v[138:139], v[140:141], v[138:139] neg_lo:[0,1] neg_hi:[0,1]
	v_pk_fma_f32 v[146:147], v[144:145], s[6:7], v[142:143] op_sel_hi:[1,0,0]
	v_pk_add_f32 v[132:133], v[132:133], v[138:139] neg_lo:[0,1] neg_hi:[0,1]
	v_ldexp_f32 v138, v140, 1
	v_pk_fma_f32 v[146:147], v[144:145], v[146:147], s[8:9] op_sel_hi:[1,1,0]
	v_ldexp_f32 v139, v141, 1
	v_pk_mul_f32 v[140:141], v[140:141], v[144:145]
	v_cvt_f32_i32_e32 v145, v159
	v_cvt_f32_i32_e32 v144, v158
	v_pk_mul_f32 v[140:141], v[140:141], v[146:147]
	v_ldexp_f32 v149, v133, 1
	v_pk_add_f32 v[146:147], v[138:139], v[140:141]
	v_pk_mul_f32 v[150:151], v[144:145], s[36:37] op_sel_hi:[1,0]
	v_pk_add_f32 v[138:139], v[146:147], v[138:139] neg_lo:[0,1] neg_hi:[0,1]
	v_pk_fma_f32 v[152:153], v[144:145], s[36:37], v[150:151] op_sel_hi:[1,0,1] neg_lo:[0,0,1] neg_hi:[0,0,1]
	v_pk_add_f32 v[138:139], v[140:141], v[138:139] neg_lo:[0,1] neg_hi:[0,1]
	v_pk_fma_f32 v[144:145], v[144:145], s[10:11], v[152:153] op_sel_hi:[1,0,1]
	v_ldexp_f32 v132, v132, 1
	v_mov_b32_e32 v140, v150
	v_mov_b32_e32 v141, v139
	v_mov_b32_e32 v148, v144
	v_mov_b32_e32 v133, v149
	v_pk_add_f32 v[140:141], v[140:141], v[148:149]
	v_pk_add_f32 v[148:149], v[132:133], v[138:139]
	v_mov_b32_e32 v139, v147
	v_mov_b32_e32 v133, v149
	v_pk_add_f32 v[152:153], v[150:151], v[144:145]
	v_pk_add_f32 v[132:133], v[132:133], v[138:139]
	v_pk_add_f32 v[138:139], v[146:147], v[148:149]
	v_mov_b32_e32 v162, v146
	v_pk_add_f32 v[154:155], v[152:153], v[138:139]
	v_mov_b32_e32 v160, v138
	v_mov_b32_e32 v161, v155
	v_mov_b32_e32 v163, v153
	v_pk_add_f32 v[160:161], v[160:161], v[162:163] neg_lo:[0,1] neg_hi:[0,1]
	v_mov_b32_e32 v156, v154
	v_mov_b32_e32 v157, v153
	v_mov_b32_e32 v158, v152
	v_mov_b32_e32 v159, v151
	v_mov_b32_e32 v162, v152
	v_mov_b32_e32 v163, v155
	v_mov_b32_e32 v151, v161
	v_pk_add_f32 v[156:157], v[156:157], v[158:159] neg_lo:[0,1] neg_hi:[0,1]
; __device__ __forceinline__ float softplusf_(float x) { return fmaxf(x, 0.0f) + log1pf(__expf(-fabsf(x))); }
;     __device__ __forceinline__ void operator()(f32x4 (&acc)[2][2][4][2], const pg8::Unit& u, int wr, int wc, int fr, int fq) const {
;     ...
;             if (wc == 0) { const f32x4 b0 = *(const f32x4*)(dtb + cl0), b1 = *(const f32x4*)(dtb + cl0 + 4);
; #pragma unroll
;                 for (int ai = 0; ai < 2; ++ai)
; #pragma unroll
;                     for (int m = 0; m < 4; ++m) { const int row = row0 + ai * 128 + m * 16; const f32x4 v0 = acc[ai][0][m][0] + b0, v1 = acc[ai][0][m][1] + b1;
;                         float* d = DTA + (size_t)row * NH + cl0;
;                         *(f32x4*)d = (f32x4){softplusf_(v0[0]), softplusf_(v0[1]), softplusf_(v0[2]), softplusf_(v0[3])}; *(f32x4*)(d + 4) = (f32x4){softplusf_(v1[0]), softplusf_(v1[1]), softplusf_(v1[2]), softplusf_(v1[3])}; } }
	v_mov_b32_e32 v158, v138
	v_mov_b32_e32 v159, v145
	v_pk_add_f32 v[150:151], v[162:163], v[150:151] neg_lo:[0,1] neg_hi:[0,1]
	v_pk_add_f32 v[158:159], v[158:159], v[156:157] neg_lo:[0,1] neg_hi:[0,1]
	v_mov_b32_e32 v162, v150
	v_mov_b32_e32 v163, v157
	v_mov_b32_e32 v164, v154
	v_mov_b32_e32 v165, v139
	v_mov_b32_e32 v157, v147
	v_pk_add_f32 v[162:163], v[144:145], v[162:163] neg_lo:[0,1] neg_hi:[0,1]
	v_pk_add_f32 v[156:157], v[164:165], v[156:157] neg_lo:[0,1] neg_hi:[0,1]
	v_mov_b32_e32 v145, v153
	v_pk_add_f32 v[140:141], v[140:141], v[156:157] neg_lo:[0,1] neg_hi:[0,1]
	v_pk_add_f32 v[144:145], v[144:145], v[150:151] neg_lo:[0,1] neg_hi:[0,1]
	v_pk_add_f32 v[132:133], v[132:133], v[160:161] neg_lo:[0,1] neg_hi:[0,1]
	v_pk_add_f32 v[138:139], v[138:139], v[146:147] neg_lo:[0,1] neg_hi:[0,1]
	v_pk_add_f32 v[146:147], v[132:133], v[144:145]
	v_mov_b32_e32 v145, v159
	v_mov_b32_e32 v133, v141
	v_pk_add_f32 v[138:139], v[148:149], v[138:139] neg_lo:[0,1] neg_hi:[0,1]
	v_pk_add_f32 v[148:149], v[158:159], v[140:141]
	v_pk_add_f32 v[132:133], v[144:145], v[132:133]
	v_mov_b32_e32 v140, v146
	v_pk_add_f32 v[132:133], v[132:133], v[162:163] neg_lo:[0,1] neg_hi:[0,1]
	v_mov_b32_e32 v141, v149
	v_pk_add_f32 v[140:141], v[140:141], v[132:133] neg_lo:[0,1] neg_hi:[0,1]
	v_pk_add_f32 v[132:133], v[138:139], v[132:133] neg_lo:[0,1] neg_hi:[0,1]
	v_pk_add_f32 v[140:141], v[144:145], v[140:141] neg_lo:[0,1] neg_hi:[0,1]
	v_pk_add_f32 v[138:139], v[148:149], v[146:147]
	v_pk_add_f32 v[132:133], v[132:133], v[140:141]
	v_pk_add_f32 v[140:141], v[154:155], v[138:139]
	s_nop 0
	v_pk_add_f32 v[144:145], v[140:141], v[154:155] neg_lo:[0,1] neg_hi:[0,1]
	s_nop 0
	v_pk_add_f32 v[138:139], v[138:139], v[144:145] neg_lo:[0,1] neg_hi:[0,1]
	s_nop 0
	v_pk_add_f32 v[132:133], v[132:133], v[138:139]
	s_nop 0
	v_pk_add_f32 v[132:133], v[140:141], v[132:133]
	s_nop 0
	v_cndmask_b32_e32 v132, v252, v132, vcc
	v_cmp_neq_f32_e32 vcc, s3, v167
	s_nop 1
	v_cndmask_b32_e32 v133, v252, v133, vcc
	v_cmp_ngt_f32_e32 vcc, -1.0, v167
	s_nop 1
	v_cndmask_b32_e32 v133, v253, v133, vcc
	v_cmp_ngt_f32_e32 vcc, -1.0, v166
	s_nop 1
	v_cndmask_b32_e32 v132, v253, v132, vcc
	v_cmp_neq_f32_e32 vcc, -1.0, v166
	s_nop 1
	v_cndmask_b32_e32 v132, v244, v132, vcc
	v_cmp_neq_f32_e32 vcc, -1.0, v167
	s_nop 1
	v_cndmask_b32_e32 v133, v244, v133, vcc
	v_cmp_lt_f32_e64 vcc, |v166|, s4
	v_cndmask_b32_e64 v133, v133, v167, s[0:1]
	s_nop 0
	v_cndmask_b32_e32 v132, v132, v166, vcc
	v_pk_add_f32 v[130:131], v[130:131], v[132:133]
	v_mul_f32_e64 v133, |v136|, s88
	v_exp_f32_e32 v164, v133
	v_max_f32_e32 v132, 0, v136
	v_add_f32_e32 v133, 1.0, v164
	v_add_f32_e32 v136, -1.0, v133
	v_sub_f32_e32 v138, v136, v133
	v_add_f32_e32 v138, 1.0, v138
	v_sub_f32_e32 v136, v164, v136
	v_add_f32_e32 v140, v136, v138
	v_frexp_mant_f32_e32 v136, v133
	v_cvt_f64_f32_e32 v[138:139], v133
	v_cmp_gt_f32_e32 vcc, s2, v136
	v_frexp_exp_i32_f64_e32 v136, v[138:139]
	s_nop 0
	v_subbrev_co_u32_e32 v158, vcc, 0, v136, vcc
	v_sub_u32_e32 v138, 0, v158
	v_ldexp_f32 v136, v133, v138
	v_max_f32_e32 v133, 0, v137
	v_mul_f32_e64 v137, |v137|, s88
	v_exp_f32_e32 v165, v137
	v_ldexp_f32 v138, v140, v138
	v_add_f32_e32 v137, 1.0, v165
	v_add_f32_e32 v139, -1.0, v137
	v_sub_f32_e32 v140, v139, v137
	v_add_f32_e32 v140, 1.0, v140
	v_sub_f32_e32 v139, v165, v139
	v_add_f32_e32 v139, v139, v140
	v_frexp_mant_f32_e32 v140, v137
	v_cmp_gt_f32_e32 vcc, s2, v140
	v_cvt_f64_f32_e32 v[140:141], v137
	v_frexp_exp_i32_f64_e32 v140, v[140:141]
	v_subbrev_co_u32_e32 v159, vcc, 0, v140, vcc
	v_sub_u32_e32 v140, 0, v159
	v_ldexp_f32 v137, v137, v140
	v_ldexp_f32 v139, v139, v140
	v_pk_add_f32 v[140:141], v[136:137], 1.0 op_sel_hi:[1,0]
	v_pk_add_f32 v[150:151], v[136:137], -1.0 op_sel_hi:[1,0]
	v_pk_add_f32 v[144:145], v[140:141], -1.0 op_sel_hi:[1,0]
	v_pk_add_f32 v[152:153], v[150:151], 1.0 op_sel_hi:[1,0]
	v_pk_add_f32 v[144:145], v[136:137], v[144:145] neg_lo:[0,1] neg_hi:[0,1]
	v_pk_add_f32 v[136:137], v[136:137], v[152:153] neg_lo:[0,1] neg_hi:[0,1]
	v_pk_add_f32 v[144:145], v[138:139], v[144:145]
	v_pk_add_f32 v[136:137], v[138:139], v[136:137]
	v_pk_add_f32 v[146:147], v[140:141], v[144:145]
	v_pk_add_f32 v[138:139], v[150:151], v[136:137]
	v_rcp_f32_e32 v148, v146
	v_rcp_f32_e32 v149, v147
	v_pk_add_f32 v[140:141], v[146:147], v[140:141] neg_lo:[0,1] neg_hi:[0,1]
	v_pk_add_f32 v[150:151], v[138:139], v[150:151] neg_lo:[0,1] neg_hi:[0,1]
	v_pk_add_f32 v[140:141], v[144:145], v[140:141] neg_lo:[0,1] neg_hi:[0,1]
	v_pk_mul_f32 v[144:145], v[138:139], v[148:149]
	v_pk_add_f32 v[136:137], v[136:137], v[150:151] neg_lo:[0,1] neg_hi:[0,1]
	v_pk_mul_f32 v[150:151], v[146:147], v[144:145]
	v_cmp_neq_f32_e32 vcc, s3, v164
	v_pk_fma_f32 v[152:153], v[144:145], v[146:147], v[150:151] neg_lo:[0,0,1] neg_hi:[0,0,1]
	v_cmp_lt_f32_e64 s[0:1], |v165|, s4
	v_pk_fma_f32 v[152:153], v[144:145], v[140:141], v[152:153]
	s_nop 0
	v_pk_add_f32 v[154:155], v[150:151], v[152:153]
	s_nop 0
	v_pk_add_f32 v[156:157], v[138:139], v[154:155] neg_lo:[0,1] neg_hi:[0,1]
	v_pk_add_f32 v[150:151], v[154:155], v[150:151] neg_lo:[0,1] neg_hi:[0,1]
	v_pk_add_f32 v[138:139], v[138:139], v[156:157] neg_lo:[0,1] neg_hi:[0,1]
	s_nop 0
	v_pk_add_f32 v[138:139], v[138:139], v[154:155] neg_lo:[0,1] neg_hi:[0,1]
	s_nop 0
	v_pk_add_f32 v[136:137], v[136:137], v[138:139]
	v_pk_add_f32 v[138:139], v[150:151], v[152:153] neg_lo:[0,1] neg_hi:[0,1]
	s_nop 0
	v_pk_add_f32 v[136:137], v[138:139], v[136:137]
	s_nop 0
	v_pk_add_f32 v[138:139], v[156:157], v[136:137]
	s_nop 0
	v_pk_mul_f32 v[150:151], v[148:149], v[138:139]
	s_nop 0
	v_pk_mul_f32 v[152:153], v[146:147], v[150:151]
	s_nop 0
; __device__ __forceinline__ float softplusf_(float x) { return fmaxf(x, 0.0f) + log1pf(__expf(-fabsf(x))); }
;     __device__ __forceinline__ void operator()(f32x4 (&acc)[2][2][4][2], const pg8::Unit& u, int wr, int wc, int fr, int fq) const {
;     ...
;             if (wc == 0) { const f32x4 b0 = *(const f32x4*)(dtb + cl0), b1 = *(const f32x4*)(dtb + cl0 + 4);
; #pragma unroll
;                 for (int ai = 0; ai < 2; ++ai)
; #pragma unroll
;                     for (int m = 0; m < 4; ++m) { const int row = row0 + ai * 128 + m * 16; const f32x4 v0 = acc[ai][0][m][0] + b0, v1 = acc[ai][0][m][1] + b1;
;                         float* d = DTA + (size_t)row * NH + cl0;
;                         *(f32x4*)d = (f32x4){softplusf_(v0[0]), softplusf_(v0[1]), softplusf_(v0[2]), softplusf_(v0[3])}; *(f32x4*)(d + 4) = (f32x4){softplusf_(v1[0]), softplusf_(v1[1]), softplusf_(v1[2]), softplusf_(v1[3])}; } }
	v_pk_fma_f32 v[146:147], v[150:151], v[146:147], v[152:153] neg_lo:[0,0,1] neg_hi:[0,0,1]
	s_nop 0
	v_pk_fma_f32 v[140:141], v[150:151], v[140:141], v[146:147]
	v_pk_add_f32 v[146:147], v[156:157], v[138:139] neg_lo:[0,1] neg_hi:[0,1]
	s_nop 0
	v_pk_add_f32 v[136:137], v[136:137], v[146:147]
	v_pk_add_f32 v[146:147], v[152:153], v[140:141]
	s_nop 0
	v_pk_add_f32 v[154:155], v[138:139], v[146:147] neg_lo:[0,1] neg_hi:[0,1]
	v_pk_add_f32 v[152:153], v[146:147], v[152:153] neg_lo:[0,1] neg_hi:[0,1]
	v_pk_add_f32 v[138:139], v[138:139], v[154:155] neg_lo:[0,1] neg_hi:[0,1]
	s_nop 0
	v_pk_add_f32 v[138:139], v[138:139], v[146:147] neg_lo:[0,1] neg_hi:[0,1]
	s_nop 0
	v_pk_add_f32 v[136:137], v[136:137], v[138:139]
	v_pk_add_f32 v[138:139], v[152:153], v[140:141] neg_lo:[0,1] neg_hi:[0,1]
	s_nop 0
	v_pk_add_f32 v[136:137], v[138:139], v[136:137]
	v_pk_add_f32 v[138:139], v[144:145], v[150:151]
	v_pk_add_f32 v[136:137], v[154:155], v[136:137]
	v_pk_add_f32 v[140:141], v[138:139], v[144:145] neg_lo:[0,1] neg_hi:[0,1]
	v_pk_mul_f32 v[136:137], v[148:149], v[136:137]
	v_pk_add_f32 v[140:141], v[150:151], v[140:141] neg_lo:[0,1] neg_hi:[0,1]
	s_nop 0
	v_pk_add_f32 v[136:137], v[140:141], v[136:137]
	s_nop 0
	v_pk_add_f32 v[140:141], v[138:139], v[136:137]
	s_nop 0
	v_pk_mul_f32 v[144:145], v[140:141], v[140:141]
	v_pk_add_f32 v[138:139], v[140:141], v[138:139] neg_lo:[0,1] neg_hi:[0,1]
	v_pk_fma_f32 v[142:143], v[144:145], s[6:7], v[142:143] op_sel_hi:[1,0,0]
	v_pk_add_f32 v[136:137], v[136:137], v[138:139] neg_lo:[0,1] neg_hi:[0,1]
	v_ldexp_f32 v138, v140, 1
	v_pk_fma_f32 v[142:143], v[144:145], v[142:143], s[8:9] op_sel_hi:[1,1,0]
	v_ldexp_f32 v139, v141, 1
	v_pk_mul_f32 v[140:141], v[140:141], v[144:145]
	v_cvt_f32_i32_e32 v145, v159
	v_cvt_f32_i32_e32 v144, v158
	v_pk_mul_f32 v[140:141], v[140:141], v[142:143]
	v_ldexp_f32 v147, v137, 1
	v_pk_add_f32 v[142:143], v[138:139], v[140:141]
	v_pk_mul_f32 v[148:149], v[144:145], s[36:37] op_sel_hi:[1,0]
	v_pk_add_f32 v[138:139], v[142:143], v[138:139] neg_lo:[0,1] neg_hi:[0,1]
	v_pk_fma_f32 v[150:151], v[144:145], s[36:37], v[148:149] op_sel_hi:[1,0,1] neg_lo:[0,0,1] neg_hi:[0,0,1]
	v_pk_add_f32 v[138:139], v[140:141], v[138:139] neg_lo:[0,1] neg_hi:[0,1]
	v_pk_fma_f32 v[144:145], v[144:145], s[10:11], v[150:151] op_sel_hi:[1,0,1]
	v_ldexp_f32 v136, v136, 1
	v_mov_b32_e32 v140, v148
	v_mov_b32_e32 v141, v139
	v_mov_b32_e32 v146, v144
	v_mov_b32_e32 v137, v147
	v_pk_add_f32 v[140:141], v[140:141], v[146:147]
	v_pk_add_f32 v[146:147], v[136:137], v[138:139]
	v_mov_b32_e32 v139, v143
	v_mov_b32_e32 v137, v147
	v_pk_add_f32 v[150:151], v[148:149], v[144:145]
	v_pk_add_f32 v[136:137], v[136:137], v[138:139]
	v_pk_add_f32 v[138:139], v[142:143], v[146:147]
	v_mov_b32_e32 v160, v142
	v_pk_add_f32 v[152:153], v[150:151], v[138:139]
	v_mov_b32_e32 v158, v138
	v_mov_b32_e32 v159, v153
	v_mov_b32_e32 v161, v151
	v_pk_add_f32 v[158:159], v[158:159], v[160:161] neg_lo:[0,1] neg_hi:[0,1]
	v_mov_b32_e32 v154, v152
	v_mov_b32_e32 v155, v151
	v_mov_b32_e32 v156, v150
	v_mov_b32_e32 v157, v149
	v_mov_b32_e32 v160, v150
	v_mov_b32_e32 v161, v153
	v_mov_b32_e32 v149, v159
	v_pk_add_f32 v[154:155], v[154:155], v[156:157] neg_lo:[0,1] neg_hi:[0,1]
	v_mov_b32_e32 v156, v138
	v_mov_b32_e32 v157, v145
	v_pk_add_f32 v[148:149], v[160:161], v[148:149] neg_lo:[0,1] neg_hi:[0,1]
	v_pk_add_f32 v[156:157], v[156:157], v[154:155] neg_lo:[0,1] neg_hi:[0,1]
	v_mov_b32_e32 v160, v148
	v_mov_b32_e32 v161, v155
	v_mov_b32_e32 v162, v152
	v_mov_b32_e32 v163, v139
	v_mov_b32_e32 v155, v143
	v_pk_add_f32 v[160:161], v[144:145], v[160:161] neg_lo:[0,1] neg_hi:[0,1]
	v_pk_add_f32 v[154:155], v[162:163], v[154:155] neg_lo:[0,1] neg_hi:[0,1]
	v_mov_b32_e32 v145, v151
	v_pk_add_f32 v[138:139], v[138:139], v[142:143] neg_lo:[0,1] neg_hi:[0,1]
	v_pk_add_f32 v[140:141], v[140:141], v[154:155] neg_lo:[0,1] neg_hi:[0,1]
	v_pk_add_f32 v[142:143], v[144:145], v[148:149] neg_lo:[0,1] neg_hi:[0,1]
	v_pk_add_f32 v[136:137], v[136:137], v[158:159] neg_lo:[0,1] neg_hi:[0,1]
	v_pk_add_f32 v[138:139], v[146:147], v[138:139] neg_lo:[0,1] neg_hi:[0,1]
	v_pk_add_f32 v[144:145], v[136:137], v[142:143]
	v_mov_b32_e32 v143, v157
	v_mov_b32_e32 v137, v141
	v_pk_add_f32 v[146:147], v[156:157], v[140:141]
	v_pk_add_f32 v[136:137], v[142:143], v[136:137]
	v_mov_b32_e32 v140, v144
	v_pk_add_f32 v[136:137], v[136:137], v[160:161] neg_lo:[0,1] neg_hi:[0,1]
	v_mov_b32_e32 v141, v147
	v_pk_add_f32 v[140:141], v[140:141], v[136:137] neg_lo:[0,1] neg_hi:[0,1]
	v_pk_add_f32 v[136:137], v[138:139], v[136:137] neg_lo:[0,1] neg_hi:[0,1]
	v_pk_add_f32 v[140:141], v[142:143], v[140:141] neg_lo:[0,1] neg_hi:[0,1]
	v_pk_add_f32 v[138:139], v[146:147], v[144:145]
	v_pk_add_f32 v[136:137], v[136:137], v[140:141]
	v_pk_add_f32 v[140:141], v[152:153], v[138:139]
	s_nop 0
	v_pk_add_f32 v[142:143], v[140:141], v[152:153] neg_lo:[0,1] neg_hi:[0,1]
	s_nop 0
	v_pk_add_f32 v[138:139], v[138:139], v[142:143] neg_lo:[0,1] neg_hi:[0,1]
	s_nop 0
	v_pk_add_f32 v[136:137], v[136:137], v[138:139]
	s_nop 0
	v_pk_add_f32 v[136:137], v[140:141], v[136:137]
	s_nop 0
	v_cndmask_b32_e32 v136, v252, v136, vcc
	v_cmp_neq_f32_e32 vcc, s3, v165
	s_nop 1
	v_cndmask_b32_e32 v137, v252, v137, vcc
	v_cmp_ngt_f32_e32 vcc, -1.0, v165
	s_nop 1
	v_cndmask_b32_e32 v137, v253, v137, vcc
	v_cmp_ngt_f32_e32 vcc, -1.0, v164
	s_nop 1
	v_cndmask_b32_e32 v136, v253, v136, vcc
	v_cmp_neq_f32_e32 vcc, -1.0, v164
	s_nop 1
	v_cndmask_b32_e32 v136, v244, v136, vcc
	v_cmp_neq_f32_e32 vcc, -1.0, v165
	s_nop 1
	v_cndmask_b32_e32 v137, v244, v137, vcc
	v_cmp_lt_f32_e64 vcc, |v164|, s4
	v_cndmask_b32_e64 v137, v137, v165, s[0:1]
	s_nop 0
	v_cndmask_b32_e32 v136, v136, v164, vcc
	v_pk_add_f32 v[132:133], v[132:133], v[136:137]
	global_store_dwordx4 v[134:135], v[130:133], off offset:16
	s_cbranch_execnz .LBB0_199
	s_branch .LBB0_1727
